# v58 + priority 1 held through the post-barrier global-load and fragment-read issue (prio 0 just before first waitcnt/MFMA)
# speedup vs baseline: 1.0008x; 1.0008x over previous
.LBB0_257:
	v_ashrrev_i32_e32 v3, 31, v2
	v_lshlrev_b64 v[2:3], 11, v[2:3]
	v_lshl_add_u64 v[70:71], v[86:87], 0, v[2:3]
	v_or_b32_e32 v2, s56, v154
	v_ashrrev_i32_e32 v3, 31, v2
	v_lshlrev_b64 v[2:3], 11, v[2:3]
	v_lshl_add_u64 v[72:73], v[84:85], 0, v[2:3]
	v_add_u32_e32 v2, s56, v155
	v_ashrrev_i32_e32 v3, 31, v2
	v_lshlrev_b64 v[2:3], 11, v[2:3]
	v_lshl_add_u64 v[74:75], v[84:85], 0, v[2:3]
	v_add_u32_e32 v2, s56, v156
	v_ashrrev_i32_e32 v3, 31, v2
	v_lshlrev_b64 v[2:3], 11, v[2:3]
	v_lshl_add_u64 v[76:77], v[84:85], 0, v[2:3]
	v_add_u32_e32 v2, s56, v157
	v_ashrrev_i32_e32 v3, 31, v2
	v_ashrrev_i32_e32 v9, 31, v8
	v_ashrrev_i32_e32 v5, 31, v4
	v_lshlrev_b64 v[2:3], 11, v[2:3]
	v_ashrrev_i32_e32 v7, 31, v6
	v_lshlrev_b64 v[8:9], 11, v[8:9]
	v_lshlrev_b64 v[4:5], 11, v[4:5]
	v_lshl_add_u64 v[78:79], v[84:85], 0, v[2:3]
	v_lshlrev_b64 v[2:3], 11, v[6:7]
	v_lshl_add_u64 v[66:67], v[86:87], 0, v[8:9]
	v_lshl_add_u64 v[68:69], v[86:87], 0, v[4:5]
	v_lshl_add_u64 v[80:81], v[86:87], 0, v[2:3]
	global_load_dwordx4 v[2:5], v[70:71], off
	global_load_dwordx4 v[6:9], v[68:69], off
	global_load_dwordx4 v[10:13], v[66:67], off
	global_load_dwordx4 v[14:17], v[80:81], off
	global_load_dwordx4 v[18:21], v[72:73], off
	global_load_dwordx4 v[22:25], v[74:75], off
	global_load_dwordx4 v[26:29], v[76:77], off
	global_load_dwordx4 v[30:33], v[78:79], off
	global_load_dwordx4 v[122:125], v[70:71], off offset:128
	global_load_dwordx4 v[126:129], v[68:69], off offset:128
	global_load_dwordx4 v[136:139], v[66:67], off offset:128
	global_load_dwordx4 v[140:143], v[80:81], off offset:128
	global_load_dwordx4 v[144:147], v[72:73], off offset:128
	global_load_dwordx4 v[148:151], v[74:75], off offset:128
	global_load_dwordx4 v[172:175], v[76:77], off offset:128
	global_load_dwordx4 v[176:179], v[78:79], off offset:128
	s_waitcnt vmcnt(15)
	ds_write_b128 v165, v[2:5] offset:36864
	s_waitcnt vmcnt(14)
	ds_write_b128 v165, v[6:9] offset:41472
	s_waitcnt vmcnt(13)
	ds_write_b128 v165, v[10:13] offset:46080
	s_waitcnt vmcnt(12)
	ds_write_b128 v165, v[14:17] offset:50688
	s_waitcnt vmcnt(11)
	ds_write_b128 v165, v[18:21]
	s_waitcnt vmcnt(10)
	ds_write_b128 v165, v[22:25] offset:4608
	s_waitcnt vmcnt(9)
	ds_write_b128 v165, v[26:29] offset:9216
	s_waitcnt vmcnt(8)
	ds_write_b128 v165, v[30:33] offset:13824
	s_waitcnt lgkmcnt(0)
	s_barrier
	global_load_dwordx4 v[180:183], v[74:75], off offset:256
	global_load_dwordx4 v[184:187], v[76:77], off offset:256
	global_load_dwordx4 v[188:191], v[72:73], off offset:256
	global_load_dwordx4 v[192:195], v[70:71], off offset:256
	global_load_dwordx4 v[196:199], v[68:69], off offset:256
	global_load_dwordx4 v[200:203], v[66:67], off offset:256
	global_load_dwordx4 v[204:207], v[78:79], off offset:256
	global_load_dwordx4 v[208:211], v[80:81], off offset:256
	v_and_b32_e32 v246, 15, v1
	v_add_u32_e32 v246, 4, v246
	v_bfe_u32 v246, v246, 3, 1
	v_bfe_u32 v249, v1, 4, 2
	v_xor_b32_e32 v246, v246, v249
	v_bfe_u32 v249, v1, 5, 1
	v_sub_u32_e32 v246, v246, v249
	v_lshlrev_b32_e32 v246, 4, v246
	v_bfe_u32 v249, v1, 4, 1
	v_mul_u32_u24_e32 v249, 0x900, v249
	v_sub_u32_e32 v246, v246, v249
	v_add_u32_e32 v244, v246, v162
	v_add_u32_e32 v245, v246, v164
	ds_read_b128 v[228:231], v245 offset:36864
	ds_read_b128 v[212:215], v244
	ds_read_b128 v[236:239], v245 offset:39168
	ds_read_b128 v[240:243], v245 offset:41472
	ds_read_b128 v[252:255], v245 offset:43776
	ds_read_b128 v[216:219], v244 offset:2304
	ds_read_b128 v[220:223], v244 offset:4608
	ds_read_b128 v[224:227], v244 offset:6912
	s_waitcnt lgkmcnt(6)
	v_mfma_f32_16x16x32_bf16 v[50:53], v[212:215], v[228:231], 0
	s_waitcnt lgkmcnt(5)
	v_mfma_f32_16x16x32_bf16 v[54:57], v[212:215], v[236:239], 0
	s_waitcnt lgkmcnt(4)
	v_mfma_f32_16x16x32_bf16 v[34:37], v[212:215], v[240:243], 0
	s_waitcnt lgkmcnt(3)
	v_mfma_f32_16x16x32_bf16 v[38:41], v[212:215], v[252:255], 0
	ds_read_b128 v[212:215], v244 offset:64
	s_waitcnt lgkmcnt(3)
	v_mfma_f32_16x16x32_bf16 v[58:61], v[216:219], v[228:231], 0
	v_mfma_f32_16x16x32_bf16 v[62:65], v[216:219], v[236:239], 0
	v_mfma_f32_16x16x32_bf16 v[42:45], v[216:219], v[240:243], 0
	v_mfma_f32_16x16x32_bf16 v[46:49], v[216:219], v[252:255], 0
	ds_read_b128 v[216:219], v244 offset:2368
	s_setprio 1
	s_waitcnt vmcnt(11)
	ds_write_b128 v165, v[144:147] offset:18432
	s_waitcnt vmcnt(10)
	ds_write_b128 v165, v[148:151] offset:23040
	s_waitcnt lgkmcnt(5)
	v_mfma_f32_16x16x32_bf16 v[18:21], v[220:223], v[228:231], 0
	v_mfma_f32_16x16x32_bf16 v[22:25], v[220:223], v[236:239], 0
	v_mfma_f32_16x16x32_bf16 v[2:5], v[220:223], v[240:243], 0
	v_mfma_f32_16x16x32_bf16 v[6:9], v[220:223], v[252:255], 0
	ds_read_b128 v[220:223], v244 offset:4672
	s_waitcnt vmcnt(9)
	ds_write_b128 v165, v[172:175] offset:27648
	s_waitcnt vmcnt(8)
	ds_write_b128 v165, v[176:179] offset:32256
	s_waitcnt lgkmcnt(7)
	v_mfma_f32_16x16x32_bf16 v[26:29], v[224:227], v[228:231], 0
	ds_read_b128 v[228:231], v245 offset:36928
	v_mfma_f32_16x16x32_bf16 v[30:33], v[224:227], v[236:239], 0
	ds_read_b128 v[236:239], v245 offset:39232
	v_mfma_f32_16x16x32_bf16 v[10:13], v[224:227], v[240:243], 0
	ds_read_b128 v[240:243], v245 offset:41536
	v_mfma_f32_16x16x32_bf16 v[14:17], v[224:227], v[252:255], 0
	ds_read_b128 v[252:255], v245 offset:43840
	ds_read_b128 v[224:227], v244 offset:6976
	s_waitcnt lgkmcnt(4)
	v_mfma_f32_16x16x32_bf16 v[50:53], v[212:215], v[228:231], v[50:53]
	s_waitcnt lgkmcnt(3)
	v_mfma_f32_16x16x32_bf16 v[54:57], v[212:215], v[236:239], v[54:57]
	s_waitcnt lgkmcnt(2)
	v_mfma_f32_16x16x32_bf16 v[34:37], v[212:215], v[240:243], v[34:37]
	s_waitcnt lgkmcnt(1)
	v_mfma_f32_16x16x32_bf16 v[38:41], v[212:215], v[252:255], v[38:41]
	ds_write_b128 v165, v[122:125] offset:55296
	ds_write_b128 v165, v[126:129] offset:59904
	v_mfma_f32_16x16x32_bf16 v[58:61], v[216:219], v[228:231], v[58:61]
	v_mfma_f32_16x16x32_bf16 v[62:65], v[216:219], v[236:239], v[62:65]
	v_mfma_f32_16x16x32_bf16 v[42:45], v[216:219], v[240:243], v[42:45]
	v_mfma_f32_16x16x32_bf16 v[46:49], v[216:219], v[252:255], v[46:49]
	ds_write_b128 v165, v[136:139] offset:64512
	ds_write_b128 v166, v[140:143] offset:32256
	v_mfma_f32_16x16x32_bf16 v[18:21], v[220:223], v[228:231], v[18:21]
	v_mfma_f32_16x16x32_bf16 v[22:25], v[220:223], v[236:239], v[22:25]
	v_mfma_f32_16x16x32_bf16 v[2:5], v[220:223], v[240:243], v[2:5]
	v_mfma_f32_16x16x32_bf16 v[6:9], v[220:223], v[252:255], v[6:9]
	s_waitcnt lgkmcnt(4)
	v_mfma_f32_16x16x32_bf16 v[26:29], v[224:227], v[228:231], v[26:29]
	v_mfma_f32_16x16x32_bf16 v[30:33], v[224:227], v[236:239], v[30:33]
	v_mfma_f32_16x16x32_bf16 v[10:13], v[224:227], v[240:243], v[10:13]
	v_mfma_f32_16x16x32_bf16 v[14:17], v[224:227], v[252:255], v[14:17]
	s_waitcnt lgkmcnt(0)
	s_barrier
	global_load_dwordx4 v[122:125], v[72:73], off offset:384
	global_load_dwordx4 v[126:129], v[74:75], off offset:384
	global_load_dwordx4 v[136:139], v[76:77], off offset:384
	global_load_dwordx4 v[140:143], v[78:79], off offset:384
	global_load_dwordx4 v[144:147], v[70:71], off offset:384
	global_load_dwordx4 v[148:151], v[68:69], off offset:384
	global_load_dwordx4 v[172:175], v[66:67], off offset:384
	global_load_dwordx4 v[176:179], v[80:81], off offset:384
	ds_read_b128 v[228:231], v245 offset:55296
	ds_read_b128 v[212:215], v244 offset:18432
	ds_read_b128 v[236:239], v245 offset:57600
	ds_read_b128 v[240:243], v245 offset:59904
	ds_read_b128 v[252:255], v245 offset:62208
	ds_read_b128 v[216:219], v244 offset:20736
	ds_read_b128 v[220:223], v244 offset:23040
	ds_read_b128 v[224:227], v244 offset:25344
	s_setprio 0
	s_waitcnt lgkmcnt(6)
	v_mfma_f32_16x16x32_bf16 v[50:53], v[212:215], v[228:231], v[50:53]
	s_waitcnt lgkmcnt(5)
	v_mfma_f32_16x16x32_bf16 v[54:57], v[212:215], v[236:239], v[54:57]
	s_waitcnt lgkmcnt(4)
	v_mfma_f32_16x16x32_bf16 v[34:37], v[212:215], v[240:243], v[34:37]
	s_waitcnt lgkmcnt(3)
	v_mfma_f32_16x16x32_bf16 v[38:41], v[212:215], v[252:255], v[38:41]
	ds_read_b128 v[212:215], v244 offset:18496
	s_waitcnt lgkmcnt(3)
	v_mfma_f32_16x16x32_bf16 v[58:61], v[216:219], v[228:231], v[58:61]
	v_mfma_f32_16x16x32_bf16 v[62:65], v[216:219], v[236:239], v[62:65]
	v_mfma_f32_16x16x32_bf16 v[42:45], v[216:219], v[240:243], v[42:45]
	v_mfma_f32_16x16x32_bf16 v[46:49], v[216:219], v[252:255], v[46:49]
	ds_read_b128 v[216:219], v244 offset:20800
	s_setprio 1
	s_waitcnt vmcnt(13)
	ds_write_b128 v165, v[188:191]
	ds_write_b128 v165, v[180:183] offset:4608
	s_waitcnt lgkmcnt(5)
	v_mfma_f32_16x16x32_bf16 v[18:21], v[220:223], v[228:231], v[18:21]
	v_mfma_f32_16x16x32_bf16 v[22:25], v[220:223], v[236:239], v[22:25]
	v_mfma_f32_16x16x32_bf16 v[2:5], v[220:223], v[240:243], v[2:5]
	v_mfma_f32_16x16x32_bf16 v[6:9], v[220:223], v[252:255], v[6:9]
	ds_read_b128 v[220:223], v244 offset:23104
	ds_write_b128 v165, v[184:187] offset:9216
	s_waitcnt vmcnt(9)
	ds_write_b128 v165, v[204:207] offset:13824
	s_waitcnt lgkmcnt(7)
	v_mfma_f32_16x16x32_bf16 v[26:29], v[224:227], v[228:231], v[26:29]
	ds_read_b128 v[228:231], v245 offset:55360
	v_mfma_f32_16x16x32_bf16 v[30:33], v[224:227], v[236:239], v[30:33]
	ds_read_b128 v[236:239], v245 offset:57664
	v_mfma_f32_16x16x32_bf16 v[10:13], v[224:227], v[240:243], v[10:13]
	ds_read_b128 v[240:243], v245 offset:59968
	v_mfma_f32_16x16x32_bf16 v[14:17], v[224:227], v[252:255], v[14:17]
	ds_read_b128 v[252:255], v245 offset:62272
	ds_read_b128 v[224:227], v244 offset:25408
	s_waitcnt lgkmcnt(4)
	v_mfma_f32_16x16x32_bf16 v[50:53], v[212:215], v[228:231], v[50:53]
	s_waitcnt lgkmcnt(3)
	v_mfma_f32_16x16x32_bf16 v[54:57], v[212:215], v[236:239], v[54:57]
	s_waitcnt lgkmcnt(2)
	v_mfma_f32_16x16x32_bf16 v[34:37], v[212:215], v[240:243], v[34:37]
	s_waitcnt lgkmcnt(1)
	v_mfma_f32_16x16x32_bf16 v[38:41], v[212:215], v[252:255], v[38:41]
	ds_write_b128 v165, v[192:195] offset:36864
	ds_write_b128 v165, v[196:199] offset:41472
	v_mfma_f32_16x16x32_bf16 v[58:61], v[216:219], v[228:231], v[58:61]
	v_mfma_f32_16x16x32_bf16 v[62:65], v[216:219], v[236:239], v[62:65]
	v_mfma_f32_16x16x32_bf16 v[42:45], v[216:219], v[240:243], v[42:45]
	v_mfma_f32_16x16x32_bf16 v[46:49], v[216:219], v[252:255], v[46:49]
	ds_write_b128 v165, v[200:203] offset:46080
	s_waitcnt vmcnt(8)
	ds_write_b128 v165, v[208:211] offset:50688
	v_mfma_f32_16x16x32_bf16 v[18:21], v[220:223], v[228:231], v[18:21]
	v_mfma_f32_16x16x32_bf16 v[22:25], v[220:223], v[236:239], v[22:25]
	v_mfma_f32_16x16x32_bf16 v[2:5], v[220:223], v[240:243], v[2:5]
	v_mfma_f32_16x16x32_bf16 v[6:9], v[220:223], v[252:255], v[6:9]
	s_waitcnt lgkmcnt(4)
	v_mfma_f32_16x16x32_bf16 v[26:29], v[224:227], v[228:231], v[26:29]
	v_mfma_f32_16x16x32_bf16 v[30:33], v[224:227], v[236:239], v[30:33]
	v_mfma_f32_16x16x32_bf16 v[10:13], v[224:227], v[240:243], v[10:13]
	v_mfma_f32_16x16x32_bf16 v[14:17], v[224:227], v[252:255], v[14:17]
	s_waitcnt lgkmcnt(0)
	s_barrier
	global_load_dwordx4 v[180:183], v[72:73], off offset:512
	global_load_dwordx4 v[184:187], v[74:75], off offset:512
	global_load_dwordx4 v[188:191], v[76:77], off offset:512
	global_load_dwordx4 v[192:195], v[78:79], off offset:512
	global_load_dwordx4 v[196:199], v[70:71], off offset:512
	global_load_dwordx4 v[200:203], v[68:69], off offset:512
	global_load_dwordx4 v[204:207], v[66:67], off offset:512
	global_load_dwordx4 v[208:211], v[80:81], off offset:512
	ds_read_b128 v[228:231], v245 offset:36864
	ds_read_b128 v[212:215], v244
	ds_read_b128 v[236:239], v245 offset:39168
	ds_read_b128 v[240:243], v245 offset:41472
	ds_read_b128 v[252:255], v245 offset:43776
	ds_read_b128 v[216:219], v244 offset:2304
	ds_read_b128 v[220:223], v244 offset:4608
	ds_read_b128 v[224:227], v244 offset:6912
	s_setprio 0
	s_waitcnt lgkmcnt(6)
	v_mfma_f32_16x16x32_bf16 v[50:53], v[212:215], v[228:231], v[50:53]
	s_waitcnt lgkmcnt(5)
	v_mfma_f32_16x16x32_bf16 v[54:57], v[212:215], v[236:239], v[54:57]
	s_waitcnt lgkmcnt(4)
	v_mfma_f32_16x16x32_bf16 v[34:37], v[212:215], v[240:243], v[34:37]
	s_waitcnt lgkmcnt(3)
	v_mfma_f32_16x16x32_bf16 v[38:41], v[212:215], v[252:255], v[38:41]
	ds_read_b128 v[212:215], v244 offset:64
	s_waitcnt lgkmcnt(3)
	v_mfma_f32_16x16x32_bf16 v[58:61], v[216:219], v[228:231], v[58:61]
	v_mfma_f32_16x16x32_bf16 v[62:65], v[216:219], v[236:239], v[62:65]
	v_mfma_f32_16x16x32_bf16 v[42:45], v[216:219], v[240:243], v[42:45]
	v_mfma_f32_16x16x32_bf16 v[46:49], v[216:219], v[252:255], v[46:49]
	ds_read_b128 v[216:219], v244 offset:2368
	s_setprio 1
	s_waitcnt vmcnt(15)
	ds_write_b128 v165, v[122:125] offset:18432
	s_waitcnt vmcnt(14)
	ds_write_b128 v165, v[126:129] offset:23040
	s_waitcnt lgkmcnt(5)
	v_mfma_f32_16x16x32_bf16 v[18:21], v[220:223], v[228:231], v[18:21]
	v_mfma_f32_16x16x32_bf16 v[22:25], v[220:223], v[236:239], v[22:25]
	v_mfma_f32_16x16x32_bf16 v[2:5], v[220:223], v[240:243], v[2:5]
	v_mfma_f32_16x16x32_bf16 v[6:9], v[220:223], v[252:255], v[6:9]
	ds_read_b128 v[220:223], v244 offset:4672
	s_waitcnt vmcnt(13)
	ds_write_b128 v165, v[136:139] offset:27648
	s_waitcnt vmcnt(12)
	ds_write_b128 v165, v[140:143] offset:32256
	s_waitcnt lgkmcnt(7)
	v_mfma_f32_16x16x32_bf16 v[26:29], v[224:227], v[228:231], v[26:29]
	ds_read_b128 v[228:231], v245 offset:36928
	v_mfma_f32_16x16x32_bf16 v[30:33], v[224:227], v[236:239], v[30:33]
	ds_read_b128 v[236:239], v245 offset:39232
	v_mfma_f32_16x16x32_bf16 v[10:13], v[224:227], v[240:243], v[10:13]
	ds_read_b128 v[240:243], v245 offset:41536
	v_mfma_f32_16x16x32_bf16 v[14:17], v[224:227], v[252:255], v[14:17]
	ds_read_b128 v[252:255], v245 offset:43840
	ds_read_b128 v[224:227], v244 offset:6976
	s_waitcnt lgkmcnt(4)
	v_mfma_f32_16x16x32_bf16 v[50:53], v[212:215], v[228:231], v[50:53]
	s_waitcnt lgkmcnt(3)
	v_mfma_f32_16x16x32_bf16 v[54:57], v[212:215], v[236:239], v[54:57]
	s_waitcnt lgkmcnt(2)
	v_mfma_f32_16x16x32_bf16 v[34:37], v[212:215], v[240:243], v[34:37]
	s_waitcnt lgkmcnt(1)
	v_mfma_f32_16x16x32_bf16 v[38:41], v[212:215], v[252:255], v[38:41]
	s_waitcnt vmcnt(11)
	ds_write_b128 v165, v[144:147] offset:55296
	s_waitcnt vmcnt(10)
	ds_write_b128 v165, v[148:151] offset:59904
	v_mfma_f32_16x16x32_bf16 v[58:61], v[216:219], v[228:231], v[58:61]
	v_mfma_f32_16x16x32_bf16 v[62:65], v[216:219], v[236:239], v[62:65]
	v_mfma_f32_16x16x32_bf16 v[42:45], v[216:219], v[240:243], v[42:45]
	v_mfma_f32_16x16x32_bf16 v[46:49], v[216:219], v[252:255], v[46:49]
	s_waitcnt vmcnt(9)
	ds_write_b128 v165, v[172:175] offset:64512
	s_waitcnt vmcnt(8)
	ds_write_b128 v166, v[176:179] offset:32256
	v_mfma_f32_16x16x32_bf16 v[18:21], v[220:223], v[228:231], v[18:21]
	v_mfma_f32_16x16x32_bf16 v[22:25], v[220:223], v[236:239], v[22:25]
	v_mfma_f32_16x16x32_bf16 v[2:5], v[220:223], v[240:243], v[2:5]
	v_mfma_f32_16x16x32_bf16 v[6:9], v[220:223], v[252:255], v[6:9]
	s_waitcnt lgkmcnt(4)
	v_mfma_f32_16x16x32_bf16 v[26:29], v[224:227], v[228:231], v[26:29]
	v_mfma_f32_16x16x32_bf16 v[30:33], v[224:227], v[236:239], v[30:33]
	v_mfma_f32_16x16x32_bf16 v[10:13], v[224:227], v[240:243], v[10:13]
	v_mfma_f32_16x16x32_bf16 v[14:17], v[224:227], v[252:255], v[14:17]
	s_waitcnt lgkmcnt(0)
	s_barrier
	global_load_dwordx4 v[122:125], v[72:73], off offset:640
	global_load_dwordx4 v[126:129], v[74:75], off offset:640
	global_load_dwordx4 v[136:139], v[76:77], off offset:640
	global_load_dwordx4 v[140:143], v[78:79], off offset:640
	global_load_dwordx4 v[144:147], v[70:71], off offset:640
	global_load_dwordx4 v[148:151], v[68:69], off offset:640
	global_load_dwordx4 v[172:175], v[66:67], off offset:640
	global_load_dwordx4 v[176:179], v[80:81], off offset:640
	ds_read_b128 v[228:231], v245 offset:55296
	ds_read_b128 v[212:215], v244 offset:18432
	ds_read_b128 v[236:239], v245 offset:57600
	ds_read_b128 v[240:243], v245 offset:59904
	ds_read_b128 v[252:255], v245 offset:62208
	ds_read_b128 v[216:219], v244 offset:20736
	ds_read_b128 v[220:223], v244 offset:23040
	ds_read_b128 v[224:227], v244 offset:25344
	s_setprio 0
	s_waitcnt lgkmcnt(6)
	v_mfma_f32_16x16x32_bf16 v[50:53], v[212:215], v[228:231], v[50:53]
	s_waitcnt lgkmcnt(5)
	v_mfma_f32_16x16x32_bf16 v[54:57], v[212:215], v[236:239], v[54:57]
	s_waitcnt lgkmcnt(4)
	v_mfma_f32_16x16x32_bf16 v[34:37], v[212:215], v[240:243], v[34:37]
	s_waitcnt lgkmcnt(3)
	v_mfma_f32_16x16x32_bf16 v[38:41], v[212:215], v[252:255], v[38:41]
	ds_read_b128 v[212:215], v244 offset:18496
	s_waitcnt lgkmcnt(3)
	v_mfma_f32_16x16x32_bf16 v[58:61], v[216:219], v[228:231], v[58:61]
	v_mfma_f32_16x16x32_bf16 v[62:65], v[216:219], v[236:239], v[62:65]
	v_mfma_f32_16x16x32_bf16 v[42:45], v[216:219], v[240:243], v[42:45]
	v_mfma_f32_16x16x32_bf16 v[46:49], v[216:219], v[252:255], v[46:49]
	ds_read_b128 v[216:219], v244 offset:20800
	s_setprio 1
	s_waitcnt vmcnt(15)
	ds_write_b128 v165, v[180:183]
	s_waitcnt vmcnt(14)
	ds_write_b128 v165, v[184:187] offset:4608
	s_waitcnt lgkmcnt(5)
	v_mfma_f32_16x16x32_bf16 v[18:21], v[220:223], v[228:231], v[18:21]
	v_mfma_f32_16x16x32_bf16 v[22:25], v[220:223], v[236:239], v[22:25]
	v_mfma_f32_16x16x32_bf16 v[2:5], v[220:223], v[240:243], v[2:5]
	v_mfma_f32_16x16x32_bf16 v[6:9], v[220:223], v[252:255], v[6:9]
	ds_read_b128 v[220:223], v244 offset:23104
	s_waitcnt vmcnt(13)
	ds_write_b128 v165, v[188:191] offset:9216
	s_waitcnt vmcnt(12)
	ds_write_b128 v165, v[192:195] offset:13824
	s_waitcnt lgkmcnt(7)
	v_mfma_f32_16x16x32_bf16 v[26:29], v[224:227], v[228:231], v[26:29]
	ds_read_b128 v[228:231], v245 offset:55360
	v_mfma_f32_16x16x32_bf16 v[30:33], v[224:227], v[236:239], v[30:33]
	ds_read_b128 v[236:239], v245 offset:57664
	v_mfma_f32_16x16x32_bf16 v[10:13], v[224:227], v[240:243], v[10:13]
	ds_read_b128 v[240:243], v245 offset:59968
	v_mfma_f32_16x16x32_bf16 v[14:17], v[224:227], v[252:255], v[14:17]
	ds_read_b128 v[252:255], v245 offset:62272
	ds_read_b128 v[224:227], v244 offset:25408
	s_waitcnt lgkmcnt(4)
	v_mfma_f32_16x16x32_bf16 v[50:53], v[212:215], v[228:231], v[50:53]
	s_waitcnt lgkmcnt(3)
	v_mfma_f32_16x16x32_bf16 v[54:57], v[212:215], v[236:239], v[54:57]
	s_waitcnt lgkmcnt(2)
	v_mfma_f32_16x16x32_bf16 v[34:37], v[212:215], v[240:243], v[34:37]
	s_waitcnt lgkmcnt(1)
	v_mfma_f32_16x16x32_bf16 v[38:41], v[212:215], v[252:255], v[38:41]
	s_waitcnt vmcnt(11)
	ds_write_b128 v165, v[196:199] offset:36864
	s_waitcnt vmcnt(10)
	ds_write_b128 v165, v[200:203] offset:41472
	v_mfma_f32_16x16x32_bf16 v[58:61], v[216:219], v[228:231], v[58:61]
	v_mfma_f32_16x16x32_bf16 v[62:65], v[216:219], v[236:239], v[62:65]
	v_mfma_f32_16x16x32_bf16 v[42:45], v[216:219], v[240:243], v[42:45]
	v_mfma_f32_16x16x32_bf16 v[46:49], v[216:219], v[252:255], v[46:49]
	s_waitcnt vmcnt(9)
	ds_write_b128 v165, v[204:207] offset:46080
	s_waitcnt vmcnt(8)
	ds_write_b128 v165, v[208:211] offset:50688
	v_mfma_f32_16x16x32_bf16 v[18:21], v[220:223], v[228:231], v[18:21]
	v_mfma_f32_16x16x32_bf16 v[22:25], v[220:223], v[236:239], v[22:25]
	v_mfma_f32_16x16x32_bf16 v[2:5], v[220:223], v[240:243], v[2:5]
	v_mfma_f32_16x16x32_bf16 v[6:9], v[220:223], v[252:255], v[6:9]
	s_waitcnt lgkmcnt(4)
	v_mfma_f32_16x16x32_bf16 v[26:29], v[224:227], v[228:231], v[26:29]
	v_mfma_f32_16x16x32_bf16 v[30:33], v[224:227], v[236:239], v[30:33]
	v_mfma_f32_16x16x32_bf16 v[10:13], v[224:227], v[240:243], v[10:13]
	v_mfma_f32_16x16x32_bf16 v[14:17], v[224:227], v[252:255], v[14:17]
	s_waitcnt lgkmcnt(0)
	s_barrier
	global_load_dwordx4 v[180:183], v[72:73], off offset:768
	global_load_dwordx4 v[184:187], v[74:75], off offset:768
	global_load_dwordx4 v[188:191], v[76:77], off offset:768
	global_load_dwordx4 v[192:195], v[78:79], off offset:768
	global_load_dwordx4 v[196:199], v[70:71], off offset:768
	global_load_dwordx4 v[200:203], v[68:69], off offset:768
	global_load_dwordx4 v[204:207], v[66:67], off offset:768
	global_load_dwordx4 v[208:211], v[80:81], off offset:768
	ds_read_b128 v[228:231], v245 offset:36864
	ds_read_b128 v[212:215], v244
	ds_read_b128 v[236:239], v245 offset:39168
	ds_read_b128 v[240:243], v245 offset:41472
	ds_read_b128 v[252:255], v245 offset:43776
	ds_read_b128 v[216:219], v244 offset:2304
	ds_read_b128 v[220:223], v244 offset:4608
	ds_read_b128 v[224:227], v244 offset:6912
	s_setprio 0
	s_waitcnt lgkmcnt(6)
	v_mfma_f32_16x16x32_bf16 v[50:53], v[212:215], v[228:231], v[50:53]
	s_waitcnt lgkmcnt(5)
	v_mfma_f32_16x16x32_bf16 v[54:57], v[212:215], v[236:239], v[54:57]
	s_waitcnt lgkmcnt(4)
	v_mfma_f32_16x16x32_bf16 v[34:37], v[212:215], v[240:243], v[34:37]
	s_waitcnt lgkmcnt(3)
	v_mfma_f32_16x16x32_bf16 v[38:41], v[212:215], v[252:255], v[38:41]
	ds_read_b128 v[212:215], v244 offset:64
	s_waitcnt lgkmcnt(3)
	v_mfma_f32_16x16x32_bf16 v[58:61], v[216:219], v[228:231], v[58:61]
	v_mfma_f32_16x16x32_bf16 v[62:65], v[216:219], v[236:239], v[62:65]
	v_mfma_f32_16x16x32_bf16 v[42:45], v[216:219], v[240:243], v[42:45]
	v_mfma_f32_16x16x32_bf16 v[46:49], v[216:219], v[252:255], v[46:49]
	ds_read_b128 v[216:219], v244 offset:2368
	s_setprio 1
	s_waitcnt vmcnt(15)
	ds_write_b128 v165, v[122:125] offset:18432
	s_waitcnt vmcnt(14)
	ds_write_b128 v165, v[126:129] offset:23040
	s_waitcnt lgkmcnt(5)
	v_mfma_f32_16x16x32_bf16 v[18:21], v[220:223], v[228:231], v[18:21]
	v_mfma_f32_16x16x32_bf16 v[22:25], v[220:223], v[236:239], v[22:25]
	v_mfma_f32_16x16x32_bf16 v[2:5], v[220:223], v[240:243], v[2:5]
	v_mfma_f32_16x16x32_bf16 v[6:9], v[220:223], v[252:255], v[6:9]
	ds_read_b128 v[220:223], v244 offset:4672
	s_waitcnt vmcnt(13)
	ds_write_b128 v165, v[136:139] offset:27648
	s_waitcnt vmcnt(12)
	ds_write_b128 v165, v[140:143] offset:32256
	s_waitcnt lgkmcnt(7)
	v_mfma_f32_16x16x32_bf16 v[26:29], v[224:227], v[228:231], v[26:29]
	ds_read_b128 v[228:231], v245 offset:36928
	v_mfma_f32_16x16x32_bf16 v[30:33], v[224:227], v[236:239], v[30:33]
	ds_read_b128 v[236:239], v245 offset:39232
	v_mfma_f32_16x16x32_bf16 v[10:13], v[224:227], v[240:243], v[10:13]
	ds_read_b128 v[240:243], v245 offset:41536
	v_mfma_f32_16x16x32_bf16 v[14:17], v[224:227], v[252:255], v[14:17]
	ds_read_b128 v[252:255], v245 offset:43840
	ds_read_b128 v[224:227], v244 offset:6976
	s_waitcnt lgkmcnt(4)
	v_mfma_f32_16x16x32_bf16 v[50:53], v[212:215], v[228:231], v[50:53]
	s_waitcnt lgkmcnt(3)
	v_mfma_f32_16x16x32_bf16 v[54:57], v[212:215], v[236:239], v[54:57]
	s_waitcnt lgkmcnt(2)
	v_mfma_f32_16x16x32_bf16 v[34:37], v[212:215], v[240:243], v[34:37]
	s_waitcnt lgkmcnt(1)
	v_mfma_f32_16x16x32_bf16 v[38:41], v[212:215], v[252:255], v[38:41]
	s_waitcnt vmcnt(11)
	ds_write_b128 v165, v[144:147] offset:55296
	s_waitcnt vmcnt(10)
	ds_write_b128 v165, v[148:151] offset:59904
	v_mfma_f32_16x16x32_bf16 v[58:61], v[216:219], v[228:231], v[58:61]
	v_mfma_f32_16x16x32_bf16 v[62:65], v[216:219], v[236:239], v[62:65]
	v_mfma_f32_16x16x32_bf16 v[42:45], v[216:219], v[240:243], v[42:45]
	v_mfma_f32_16x16x32_bf16 v[46:49], v[216:219], v[252:255], v[46:49]
	s_waitcnt vmcnt(9)
	ds_write_b128 v165, v[172:175] offset:64512
	s_waitcnt vmcnt(8)
	ds_write_b128 v166, v[176:179] offset:32256
	v_mfma_f32_16x16x32_bf16 v[18:21], v[220:223], v[228:231], v[18:21]
	v_mfma_f32_16x16x32_bf16 v[22:25], v[220:223], v[236:239], v[22:25]
	v_mfma_f32_16x16x32_bf16 v[2:5], v[220:223], v[240:243], v[2:5]
	v_mfma_f32_16x16x32_bf16 v[6:9], v[220:223], v[252:255], v[6:9]
	s_waitcnt lgkmcnt(4)
	v_mfma_f32_16x16x32_bf16 v[26:29], v[224:227], v[228:231], v[26:29]
	v_mfma_f32_16x16x32_bf16 v[30:33], v[224:227], v[236:239], v[30:33]
	v_mfma_f32_16x16x32_bf16 v[10:13], v[224:227], v[240:243], v[10:13]
	v_mfma_f32_16x16x32_bf16 v[14:17], v[224:227], v[252:255], v[14:17]
	s_waitcnt lgkmcnt(0)
	s_barrier
	global_load_dwordx4 v[122:125], v[72:73], off offset:896
	global_load_dwordx4 v[126:129], v[74:75], off offset:896
	global_load_dwordx4 v[136:139], v[76:77], off offset:896
	global_load_dwordx4 v[140:143], v[78:79], off offset:896
	global_load_dwordx4 v[144:147], v[70:71], off offset:896
	global_load_dwordx4 v[148:151], v[68:69], off offset:896
	global_load_dwordx4 v[172:175], v[66:67], off offset:896
	global_load_dwordx4 v[176:179], v[80:81], off offset:896
	ds_read_b128 v[228:231], v245 offset:55296
	ds_read_b128 v[212:215], v244 offset:18432
	ds_read_b128 v[236:239], v245 offset:57600
	ds_read_b128 v[240:243], v245 offset:59904
	ds_read_b128 v[252:255], v245 offset:62208
	ds_read_b128 v[216:219], v244 offset:20736
	ds_read_b128 v[220:223], v244 offset:23040
	ds_read_b128 v[224:227], v244 offset:25344
	s_setprio 0
	s_waitcnt lgkmcnt(6)
	v_mfma_f32_16x16x32_bf16 v[50:53], v[212:215], v[228:231], v[50:53]
	s_waitcnt lgkmcnt(5)
	v_mfma_f32_16x16x32_bf16 v[54:57], v[212:215], v[236:239], v[54:57]
	s_waitcnt lgkmcnt(4)
	v_mfma_f32_16x16x32_bf16 v[34:37], v[212:215], v[240:243], v[34:37]
	s_waitcnt lgkmcnt(3)
	v_mfma_f32_16x16x32_bf16 v[38:41], v[212:215], v[252:255], v[38:41]
	ds_read_b128 v[212:215], v244 offset:18496
	s_waitcnt lgkmcnt(3)
	v_mfma_f32_16x16x32_bf16 v[58:61], v[216:219], v[228:231], v[58:61]
	v_mfma_f32_16x16x32_bf16 v[62:65], v[216:219], v[236:239], v[62:65]
	v_mfma_f32_16x16x32_bf16 v[42:45], v[216:219], v[240:243], v[42:45]
	v_mfma_f32_16x16x32_bf16 v[46:49], v[216:219], v[252:255], v[46:49]
	ds_read_b128 v[216:219], v244 offset:20800
	s_setprio 1
	s_waitcnt vmcnt(15)
	ds_write_b128 v165, v[180:183]
	s_waitcnt vmcnt(14)
	ds_write_b128 v165, v[184:187] offset:4608
	s_waitcnt lgkmcnt(5)
	v_mfma_f32_16x16x32_bf16 v[18:21], v[220:223], v[228:231], v[18:21]
	v_mfma_f32_16x16x32_bf16 v[22:25], v[220:223], v[236:239], v[22:25]
	v_mfma_f32_16x16x32_bf16 v[2:5], v[220:223], v[240:243], v[2:5]
	v_mfma_f32_16x16x32_bf16 v[6:9], v[220:223], v[252:255], v[6:9]
	ds_read_b128 v[220:223], v244 offset:23104
	s_waitcnt vmcnt(13)
	ds_write_b128 v165, v[188:191] offset:9216
	s_waitcnt vmcnt(12)
	ds_write_b128 v165, v[192:195] offset:13824
	s_waitcnt lgkmcnt(7)
	v_mfma_f32_16x16x32_bf16 v[26:29], v[224:227], v[228:231], v[26:29]
	ds_read_b128 v[228:231], v245 offset:55360
	v_mfma_f32_16x16x32_bf16 v[30:33], v[224:227], v[236:239], v[30:33]
	ds_read_b128 v[236:239], v245 offset:57664
	v_mfma_f32_16x16x32_bf16 v[10:13], v[224:227], v[240:243], v[10:13]
	ds_read_b128 v[240:243], v245 offset:59968
	v_mfma_f32_16x16x32_bf16 v[14:17], v[224:227], v[252:255], v[14:17]
	ds_read_b128 v[252:255], v245 offset:62272
	ds_read_b128 v[224:227], v244 offset:25408
	s_waitcnt lgkmcnt(4)
	v_mfma_f32_16x16x32_bf16 v[50:53], v[212:215], v[228:231], v[50:53]
	s_waitcnt lgkmcnt(3)
	v_mfma_f32_16x16x32_bf16 v[54:57], v[212:215], v[236:239], v[54:57]
	s_waitcnt lgkmcnt(2)
	v_mfma_f32_16x16x32_bf16 v[34:37], v[212:215], v[240:243], v[34:37]
	s_waitcnt lgkmcnt(1)
	v_mfma_f32_16x16x32_bf16 v[38:41], v[212:215], v[252:255], v[38:41]
	s_waitcnt vmcnt(11)
	ds_write_b128 v165, v[196:199] offset:36864
	s_waitcnt vmcnt(10)
	ds_write_b128 v165, v[200:203] offset:41472
	v_mfma_f32_16x16x32_bf16 v[58:61], v[216:219], v[228:231], v[58:61]
	v_mfma_f32_16x16x32_bf16 v[62:65], v[216:219], v[236:239], v[62:65]
	v_mfma_f32_16x16x32_bf16 v[42:45], v[216:219], v[240:243], v[42:45]
	v_mfma_f32_16x16x32_bf16 v[46:49], v[216:219], v[252:255], v[46:49]
	s_waitcnt vmcnt(9)
	ds_write_b128 v165, v[204:207] offset:46080
	s_waitcnt vmcnt(8)
	ds_write_b128 v165, v[208:211] offset:50688
	v_mfma_f32_16x16x32_bf16 v[18:21], v[220:223], v[228:231], v[18:21]
	v_mfma_f32_16x16x32_bf16 v[22:25], v[220:223], v[236:239], v[22:25]
	v_mfma_f32_16x16x32_bf16 v[2:5], v[220:223], v[240:243], v[2:5]
	v_mfma_f32_16x16x32_bf16 v[6:9], v[220:223], v[252:255], v[6:9]
	s_waitcnt lgkmcnt(4)
	v_mfma_f32_16x16x32_bf16 v[26:29], v[224:227], v[228:231], v[26:29]
	v_mfma_f32_16x16x32_bf16 v[30:33], v[224:227], v[236:239], v[30:33]
	v_mfma_f32_16x16x32_bf16 v[10:13], v[224:227], v[240:243], v[10:13]
	v_mfma_f32_16x16x32_bf16 v[14:17], v[224:227], v[252:255], v[14:17]
	s_waitcnt lgkmcnt(0)
	s_barrier
	global_load_dwordx4 v[180:183], v[72:73], off offset:1024
	global_load_dwordx4 v[184:187], v[74:75], off offset:1024
	global_load_dwordx4 v[188:191], v[76:77], off offset:1024
	global_load_dwordx4 v[192:195], v[78:79], off offset:1024
	global_load_dwordx4 v[196:199], v[70:71], off offset:1024
	global_load_dwordx4 v[200:203], v[68:69], off offset:1024
	global_load_dwordx4 v[204:207], v[66:67], off offset:1024
	global_load_dwordx4 v[208:211], v[80:81], off offset:1024
	ds_read_b128 v[228:231], v245 offset:36864
	ds_read_b128 v[212:215], v244
	ds_read_b128 v[236:239], v245 offset:39168
	ds_read_b128 v[240:243], v245 offset:41472
	ds_read_b128 v[252:255], v245 offset:43776
	ds_read_b128 v[216:219], v244 offset:2304
	ds_read_b128 v[220:223], v244 offset:4608
	ds_read_b128 v[224:227], v244 offset:6912
	s_setprio 0
	s_waitcnt lgkmcnt(6)
	v_mfma_f32_16x16x32_bf16 v[50:53], v[212:215], v[228:231], v[50:53]
	s_waitcnt lgkmcnt(5)
	v_mfma_f32_16x16x32_bf16 v[54:57], v[212:215], v[236:239], v[54:57]
	s_waitcnt lgkmcnt(4)
	v_mfma_f32_16x16x32_bf16 v[34:37], v[212:215], v[240:243], v[34:37]
	s_waitcnt lgkmcnt(3)
	v_mfma_f32_16x16x32_bf16 v[38:41], v[212:215], v[252:255], v[38:41]
	ds_read_b128 v[212:215], v244 offset:64
	s_waitcnt lgkmcnt(3)
	v_mfma_f32_16x16x32_bf16 v[58:61], v[216:219], v[228:231], v[58:61]
	v_mfma_f32_16x16x32_bf16 v[62:65], v[216:219], v[236:239], v[62:65]
	v_mfma_f32_16x16x32_bf16 v[42:45], v[216:219], v[240:243], v[42:45]
	v_mfma_f32_16x16x32_bf16 v[46:49], v[216:219], v[252:255], v[46:49]
	ds_read_b128 v[216:219], v244 offset:2368
	s_setprio 1
	s_waitcnt vmcnt(15)
	ds_write_b128 v165, v[122:125] offset:18432
	s_waitcnt vmcnt(14)
	ds_write_b128 v165, v[126:129] offset:23040
	s_waitcnt lgkmcnt(5)
	v_mfma_f32_16x16x32_bf16 v[18:21], v[220:223], v[228:231], v[18:21]
	v_mfma_f32_16x16x32_bf16 v[22:25], v[220:223], v[236:239], v[22:25]
	v_mfma_f32_16x16x32_bf16 v[2:5], v[220:223], v[240:243], v[2:5]
	v_mfma_f32_16x16x32_bf16 v[6:9], v[220:223], v[252:255], v[6:9]
	ds_read_b128 v[220:223], v244 offset:4672
	s_waitcnt vmcnt(13)
	ds_write_b128 v165, v[136:139] offset:27648
	s_waitcnt vmcnt(12)
	ds_write_b128 v165, v[140:143] offset:32256
	s_waitcnt lgkmcnt(7)
	v_mfma_f32_16x16x32_bf16 v[26:29], v[224:227], v[228:231], v[26:29]
	ds_read_b128 v[228:231], v245 offset:36928
	v_mfma_f32_16x16x32_bf16 v[30:33], v[224:227], v[236:239], v[30:33]
	ds_read_b128 v[236:239], v245 offset:39232
	v_mfma_f32_16x16x32_bf16 v[10:13], v[224:227], v[240:243], v[10:13]
	ds_read_b128 v[240:243], v245 offset:41536
	v_mfma_f32_16x16x32_bf16 v[14:17], v[224:227], v[252:255], v[14:17]
	ds_read_b128 v[252:255], v245 offset:43840
	ds_read_b128 v[224:227], v244 offset:6976
	s_waitcnt lgkmcnt(4)
	v_mfma_f32_16x16x32_bf16 v[50:53], v[212:215], v[228:231], v[50:53]
	s_waitcnt lgkmcnt(3)
	v_mfma_f32_16x16x32_bf16 v[54:57], v[212:215], v[236:239], v[54:57]
	s_waitcnt lgkmcnt(2)
	v_mfma_f32_16x16x32_bf16 v[34:37], v[212:215], v[240:243], v[34:37]
	s_waitcnt lgkmcnt(1)
	v_mfma_f32_16x16x32_bf16 v[38:41], v[212:215], v[252:255], v[38:41]
	s_waitcnt vmcnt(11)
	ds_write_b128 v165, v[144:147] offset:55296
	s_waitcnt vmcnt(10)
	ds_write_b128 v165, v[148:151] offset:59904
	v_mfma_f32_16x16x32_bf16 v[58:61], v[216:219], v[228:231], v[58:61]
	v_mfma_f32_16x16x32_bf16 v[62:65], v[216:219], v[236:239], v[62:65]
	v_mfma_f32_16x16x32_bf16 v[42:45], v[216:219], v[240:243], v[42:45]
	v_mfma_f32_16x16x32_bf16 v[46:49], v[216:219], v[252:255], v[46:49]
	s_waitcnt vmcnt(9)
	ds_write_b128 v165, v[172:175] offset:64512
	s_waitcnt vmcnt(8)
	ds_write_b128 v166, v[176:179] offset:32256
	v_mfma_f32_16x16x32_bf16 v[18:21], v[220:223], v[228:231], v[18:21]
	v_mfma_f32_16x16x32_bf16 v[22:25], v[220:223], v[236:239], v[22:25]
	v_mfma_f32_16x16x32_bf16 v[2:5], v[220:223], v[240:243], v[2:5]
	v_mfma_f32_16x16x32_bf16 v[6:9], v[220:223], v[252:255], v[6:9]
	s_waitcnt lgkmcnt(4)
	v_mfma_f32_16x16x32_bf16 v[26:29], v[224:227], v[228:231], v[26:29]
	v_mfma_f32_16x16x32_bf16 v[30:33], v[224:227], v[236:239], v[30:33]
	v_mfma_f32_16x16x32_bf16 v[10:13], v[224:227], v[240:243], v[10:13]
	v_mfma_f32_16x16x32_bf16 v[14:17], v[224:227], v[252:255], v[14:17]
	s_waitcnt lgkmcnt(0)
	s_barrier
	global_load_dwordx4 v[122:125], v[72:73], off offset:1152
	global_load_dwordx4 v[126:129], v[74:75], off offset:1152
	global_load_dwordx4 v[136:139], v[76:77], off offset:1152
	global_load_dwordx4 v[140:143], v[78:79], off offset:1152
	global_load_dwordx4 v[144:147], v[70:71], off offset:1152
	global_load_dwordx4 v[148:151], v[68:69], off offset:1152
	global_load_dwordx4 v[172:175], v[66:67], off offset:1152
	global_load_dwordx4 v[176:179], v[80:81], off offset:1152
	ds_read_b128 v[228:231], v245 offset:55296
	ds_read_b128 v[212:215], v244 offset:18432
	ds_read_b128 v[236:239], v245 offset:57600
	ds_read_b128 v[240:243], v245 offset:59904
	ds_read_b128 v[252:255], v245 offset:62208
	ds_read_b128 v[216:219], v244 offset:20736
	ds_read_b128 v[220:223], v244 offset:23040
	ds_read_b128 v[224:227], v244 offset:25344
	s_setprio 0
	s_waitcnt lgkmcnt(6)
	v_mfma_f32_16x16x32_bf16 v[50:53], v[212:215], v[228:231], v[50:53]
	s_waitcnt lgkmcnt(5)
	v_mfma_f32_16x16x32_bf16 v[54:57], v[212:215], v[236:239], v[54:57]
	s_waitcnt lgkmcnt(4)
	v_mfma_f32_16x16x32_bf16 v[34:37], v[212:215], v[240:243], v[34:37]
	s_waitcnt lgkmcnt(3)
	v_mfma_f32_16x16x32_bf16 v[38:41], v[212:215], v[252:255], v[38:41]
	ds_read_b128 v[212:215], v244 offset:18496
	s_waitcnt lgkmcnt(3)
	v_mfma_f32_16x16x32_bf16 v[58:61], v[216:219], v[228:231], v[58:61]
	v_mfma_f32_16x16x32_bf16 v[62:65], v[216:219], v[236:239], v[62:65]
	v_mfma_f32_16x16x32_bf16 v[42:45], v[216:219], v[240:243], v[42:45]
	v_mfma_f32_16x16x32_bf16 v[46:49], v[216:219], v[252:255], v[46:49]
	ds_read_b128 v[216:219], v244 offset:20800
	s_setprio 1
	s_waitcnt vmcnt(15)
	ds_write_b128 v165, v[180:183]
	s_waitcnt vmcnt(14)
	ds_write_b128 v165, v[184:187] offset:4608
	s_waitcnt lgkmcnt(5)
	v_mfma_f32_16x16x32_bf16 v[18:21], v[220:223], v[228:231], v[18:21]
	v_mfma_f32_16x16x32_bf16 v[22:25], v[220:223], v[236:239], v[22:25]
	v_mfma_f32_16x16x32_bf16 v[2:5], v[220:223], v[240:243], v[2:5]
	v_mfma_f32_16x16x32_bf16 v[6:9], v[220:223], v[252:255], v[6:9]
	ds_read_b128 v[220:223], v244 offset:23104
	s_waitcnt vmcnt(13)
	ds_write_b128 v165, v[188:191] offset:9216
	s_waitcnt vmcnt(12)
	ds_write_b128 v165, v[192:195] offset:13824
	s_waitcnt lgkmcnt(7)
	v_mfma_f32_16x16x32_bf16 v[26:29], v[224:227], v[228:231], v[26:29]
	ds_read_b128 v[228:231], v245 offset:55360
	v_mfma_f32_16x16x32_bf16 v[30:33], v[224:227], v[236:239], v[30:33]
	ds_read_b128 v[236:239], v245 offset:57664
	v_mfma_f32_16x16x32_bf16 v[10:13], v[224:227], v[240:243], v[10:13]
	ds_read_b128 v[240:243], v245 offset:59968
	v_mfma_f32_16x16x32_bf16 v[14:17], v[224:227], v[252:255], v[14:17]
	ds_read_b128 v[252:255], v245 offset:62272
	ds_read_b128 v[224:227], v244 offset:25408
	s_waitcnt lgkmcnt(4)
	v_mfma_f32_16x16x32_bf16 v[50:53], v[212:215], v[228:231], v[50:53]
	s_waitcnt lgkmcnt(3)
	v_mfma_f32_16x16x32_bf16 v[54:57], v[212:215], v[236:239], v[54:57]
	s_waitcnt lgkmcnt(2)
	v_mfma_f32_16x16x32_bf16 v[34:37], v[212:215], v[240:243], v[34:37]
	s_waitcnt lgkmcnt(1)
	v_mfma_f32_16x16x32_bf16 v[38:41], v[212:215], v[252:255], v[38:41]
	s_waitcnt vmcnt(11)
	ds_write_b128 v165, v[196:199] offset:36864
	s_waitcnt vmcnt(10)
	ds_write_b128 v165, v[200:203] offset:41472
	v_mfma_f32_16x16x32_bf16 v[58:61], v[216:219], v[228:231], v[58:61]
	v_mfma_f32_16x16x32_bf16 v[62:65], v[216:219], v[236:239], v[62:65]
	v_mfma_f32_16x16x32_bf16 v[42:45], v[216:219], v[240:243], v[42:45]
	v_mfma_f32_16x16x32_bf16 v[46:49], v[216:219], v[252:255], v[46:49]
	s_waitcnt vmcnt(9)
	ds_write_b128 v165, v[204:207] offset:46080
	s_waitcnt vmcnt(8)
	ds_write_b128 v165, v[208:211] offset:50688
	v_mfma_f32_16x16x32_bf16 v[18:21], v[220:223], v[228:231], v[18:21]
	v_mfma_f32_16x16x32_bf16 v[22:25], v[220:223], v[236:239], v[22:25]
	v_mfma_f32_16x16x32_bf16 v[2:5], v[220:223], v[240:243], v[2:5]
	v_mfma_f32_16x16x32_bf16 v[6:9], v[220:223], v[252:255], v[6:9]
	s_waitcnt lgkmcnt(4)
	v_mfma_f32_16x16x32_bf16 v[26:29], v[224:227], v[228:231], v[26:29]
	v_mfma_f32_16x16x32_bf16 v[30:33], v[224:227], v[236:239], v[30:33]
	v_mfma_f32_16x16x32_bf16 v[10:13], v[224:227], v[240:243], v[10:13]
	v_mfma_f32_16x16x32_bf16 v[14:17], v[224:227], v[252:255], v[14:17]
	s_waitcnt lgkmcnt(0)
	s_barrier
	global_load_dwordx4 v[180:183], v[72:73], off offset:1280
	global_load_dwordx4 v[184:187], v[74:75], off offset:1280
	global_load_dwordx4 v[188:191], v[76:77], off offset:1280
	global_load_dwordx4 v[192:195], v[78:79], off offset:1280
	global_load_dwordx4 v[196:199], v[70:71], off offset:1280
	global_load_dwordx4 v[200:203], v[68:69], off offset:1280
	global_load_dwordx4 v[204:207], v[66:67], off offset:1280
	global_load_dwordx4 v[208:211], v[80:81], off offset:1280
	ds_read_b128 v[228:231], v245 offset:36864
	ds_read_b128 v[212:215], v244
	ds_read_b128 v[236:239], v245 offset:39168
	ds_read_b128 v[240:243], v245 offset:41472
	ds_read_b128 v[252:255], v245 offset:43776
	ds_read_b128 v[216:219], v244 offset:2304
	ds_read_b128 v[220:223], v244 offset:4608
	ds_read_b128 v[224:227], v244 offset:6912
	s_setprio 0
	s_waitcnt lgkmcnt(6)
	v_mfma_f32_16x16x32_bf16 v[50:53], v[212:215], v[228:231], v[50:53]
	s_waitcnt lgkmcnt(5)
	v_mfma_f32_16x16x32_bf16 v[54:57], v[212:215], v[236:239], v[54:57]
	s_waitcnt lgkmcnt(4)
	v_mfma_f32_16x16x32_bf16 v[34:37], v[212:215], v[240:243], v[34:37]
	s_waitcnt lgkmcnt(3)
	v_mfma_f32_16x16x32_bf16 v[38:41], v[212:215], v[252:255], v[38:41]
	ds_read_b128 v[212:215], v244 offset:64
	s_waitcnt lgkmcnt(3)
	v_mfma_f32_16x16x32_bf16 v[58:61], v[216:219], v[228:231], v[58:61]
	v_mfma_f32_16x16x32_bf16 v[62:65], v[216:219], v[236:239], v[62:65]
	v_mfma_f32_16x16x32_bf16 v[42:45], v[216:219], v[240:243], v[42:45]
	v_mfma_f32_16x16x32_bf16 v[46:49], v[216:219], v[252:255], v[46:49]
	ds_read_b128 v[216:219], v244 offset:2368
	s_setprio 1
	s_waitcnt vmcnt(15)
	ds_write_b128 v165, v[122:125] offset:18432
	s_waitcnt vmcnt(14)
	ds_write_b128 v165, v[126:129] offset:23040
	s_waitcnt lgkmcnt(5)
	v_mfma_f32_16x16x32_bf16 v[18:21], v[220:223], v[228:231], v[18:21]
	v_mfma_f32_16x16x32_bf16 v[22:25], v[220:223], v[236:239], v[22:25]
	v_mfma_f32_16x16x32_bf16 v[2:5], v[220:223], v[240:243], v[2:5]
	v_mfma_f32_16x16x32_bf16 v[6:9], v[220:223], v[252:255], v[6:9]
	ds_read_b128 v[220:223], v244 offset:4672
	s_waitcnt vmcnt(13)
	ds_write_b128 v165, v[136:139] offset:27648
	s_waitcnt vmcnt(12)
	ds_write_b128 v165, v[140:143] offset:32256
	s_waitcnt lgkmcnt(7)
	v_mfma_f32_16x16x32_bf16 v[26:29], v[224:227], v[228:231], v[26:29]
	ds_read_b128 v[228:231], v245 offset:36928
	v_mfma_f32_16x16x32_bf16 v[30:33], v[224:227], v[236:239], v[30:33]
	ds_read_b128 v[236:239], v245 offset:39232
	v_mfma_f32_16x16x32_bf16 v[10:13], v[224:227], v[240:243], v[10:13]
	ds_read_b128 v[240:243], v245 offset:41536
	v_mfma_f32_16x16x32_bf16 v[14:17], v[224:227], v[252:255], v[14:17]
	ds_read_b128 v[252:255], v245 offset:43840
	ds_read_b128 v[224:227], v244 offset:6976
	s_waitcnt lgkmcnt(4)
	v_mfma_f32_16x16x32_bf16 v[50:53], v[212:215], v[228:231], v[50:53]
	s_waitcnt lgkmcnt(3)
	v_mfma_f32_16x16x32_bf16 v[54:57], v[212:215], v[236:239], v[54:57]
	s_waitcnt lgkmcnt(2)
	v_mfma_f32_16x16x32_bf16 v[34:37], v[212:215], v[240:243], v[34:37]
	s_waitcnt lgkmcnt(1)
	v_mfma_f32_16x16x32_bf16 v[38:41], v[212:215], v[252:255], v[38:41]
	s_waitcnt vmcnt(11)
	ds_write_b128 v165, v[144:147] offset:55296
	s_waitcnt vmcnt(10)
	ds_write_b128 v165, v[148:151] offset:59904
	v_mfma_f32_16x16x32_bf16 v[58:61], v[216:219], v[228:231], v[58:61]
	v_mfma_f32_16x16x32_bf16 v[62:65], v[216:219], v[236:239], v[62:65]
	v_mfma_f32_16x16x32_bf16 v[42:45], v[216:219], v[240:243], v[42:45]
	v_mfma_f32_16x16x32_bf16 v[46:49], v[216:219], v[252:255], v[46:49]
	s_waitcnt vmcnt(9)
	ds_write_b128 v165, v[172:175] offset:64512
	s_waitcnt vmcnt(8)
	ds_write_b128 v166, v[176:179] offset:32256
	v_mfma_f32_16x16x32_bf16 v[18:21], v[220:223], v[228:231], v[18:21]
	v_mfma_f32_16x16x32_bf16 v[22:25], v[220:223], v[236:239], v[22:25]
	v_mfma_f32_16x16x32_bf16 v[2:5], v[220:223], v[240:243], v[2:5]
	v_mfma_f32_16x16x32_bf16 v[6:9], v[220:223], v[252:255], v[6:9]
	s_waitcnt lgkmcnt(4)
	v_mfma_f32_16x16x32_bf16 v[26:29], v[224:227], v[228:231], v[26:29]
	v_mfma_f32_16x16x32_bf16 v[30:33], v[224:227], v[236:239], v[30:33]
	v_mfma_f32_16x16x32_bf16 v[10:13], v[224:227], v[240:243], v[10:13]
	v_mfma_f32_16x16x32_bf16 v[14:17], v[224:227], v[252:255], v[14:17]
	s_waitcnt lgkmcnt(0)
	s_barrier
	global_load_dwordx4 v[122:125], v[72:73], off offset:1408
	global_load_dwordx4 v[126:129], v[74:75], off offset:1408
	global_load_dwordx4 v[136:139], v[76:77], off offset:1408
	global_load_dwordx4 v[140:143], v[78:79], off offset:1408
	global_load_dwordx4 v[144:147], v[70:71], off offset:1408
	global_load_dwordx4 v[148:151], v[68:69], off offset:1408
	global_load_dwordx4 v[172:175], v[66:67], off offset:1408
	global_load_dwordx4 v[176:179], v[80:81], off offset:1408
	ds_read_b128 v[228:231], v245 offset:55296
	ds_read_b128 v[212:215], v244 offset:18432
	ds_read_b128 v[236:239], v245 offset:57600
	ds_read_b128 v[240:243], v245 offset:59904
	ds_read_b128 v[252:255], v245 offset:62208
	ds_read_b128 v[216:219], v244 offset:20736
	ds_read_b128 v[220:223], v244 offset:23040
	ds_read_b128 v[224:227], v244 offset:25344
	s_setprio 0
	s_waitcnt lgkmcnt(6)
	v_mfma_f32_16x16x32_bf16 v[50:53], v[212:215], v[228:231], v[50:53]
	s_waitcnt lgkmcnt(5)
	v_mfma_f32_16x16x32_bf16 v[54:57], v[212:215], v[236:239], v[54:57]
	s_waitcnt lgkmcnt(4)
	v_mfma_f32_16x16x32_bf16 v[34:37], v[212:215], v[240:243], v[34:37]
	s_waitcnt lgkmcnt(3)
	v_mfma_f32_16x16x32_bf16 v[38:41], v[212:215], v[252:255], v[38:41]
	ds_read_b128 v[212:215], v244 offset:18496
	s_waitcnt lgkmcnt(3)
	v_mfma_f32_16x16x32_bf16 v[58:61], v[216:219], v[228:231], v[58:61]
	v_mfma_f32_16x16x32_bf16 v[62:65], v[216:219], v[236:239], v[62:65]
	v_mfma_f32_16x16x32_bf16 v[42:45], v[216:219], v[240:243], v[42:45]
	v_mfma_f32_16x16x32_bf16 v[46:49], v[216:219], v[252:255], v[46:49]
	ds_read_b128 v[216:219], v244 offset:20800
	s_setprio 1
	s_waitcnt vmcnt(15)
	ds_write_b128 v165, v[180:183]
	s_waitcnt vmcnt(14)
	ds_write_b128 v165, v[184:187] offset:4608
	s_waitcnt lgkmcnt(5)
	v_mfma_f32_16x16x32_bf16 v[18:21], v[220:223], v[228:231], v[18:21]
	v_mfma_f32_16x16x32_bf16 v[22:25], v[220:223], v[236:239], v[22:25]
	v_mfma_f32_16x16x32_bf16 v[2:5], v[220:223], v[240:243], v[2:5]
	v_mfma_f32_16x16x32_bf16 v[6:9], v[220:223], v[252:255], v[6:9]
	ds_read_b128 v[220:223], v244 offset:23104
	s_waitcnt vmcnt(13)
	ds_write_b128 v165, v[188:191] offset:9216
	s_waitcnt vmcnt(12)
	ds_write_b128 v165, v[192:195] offset:13824
	s_waitcnt lgkmcnt(7)
	v_mfma_f32_16x16x32_bf16 v[26:29], v[224:227], v[228:231], v[26:29]
	ds_read_b128 v[228:231], v245 offset:55360
	v_mfma_f32_16x16x32_bf16 v[30:33], v[224:227], v[236:239], v[30:33]
	ds_read_b128 v[236:239], v245 offset:57664
	v_mfma_f32_16x16x32_bf16 v[10:13], v[224:227], v[240:243], v[10:13]
	ds_read_b128 v[240:243], v245 offset:59968
	v_mfma_f32_16x16x32_bf16 v[14:17], v[224:227], v[252:255], v[14:17]
	ds_read_b128 v[252:255], v245 offset:62272
	ds_read_b128 v[224:227], v244 offset:25408
	s_waitcnt lgkmcnt(4)
	v_mfma_f32_16x16x32_bf16 v[50:53], v[212:215], v[228:231], v[50:53]
	s_waitcnt lgkmcnt(3)
	v_mfma_f32_16x16x32_bf16 v[54:57], v[212:215], v[236:239], v[54:57]
	s_waitcnt lgkmcnt(2)
	v_mfma_f32_16x16x32_bf16 v[34:37], v[212:215], v[240:243], v[34:37]
	s_waitcnt lgkmcnt(1)
	v_mfma_f32_16x16x32_bf16 v[38:41], v[212:215], v[252:255], v[38:41]
	s_waitcnt vmcnt(11)
	ds_write_b128 v165, v[196:199] offset:36864
	s_waitcnt vmcnt(10)
	ds_write_b128 v165, v[200:203] offset:41472
	v_mfma_f32_16x16x32_bf16 v[58:61], v[216:219], v[228:231], v[58:61]
	v_mfma_f32_16x16x32_bf16 v[62:65], v[216:219], v[236:239], v[62:65]
	v_mfma_f32_16x16x32_bf16 v[42:45], v[216:219], v[240:243], v[42:45]
	v_mfma_f32_16x16x32_bf16 v[46:49], v[216:219], v[252:255], v[46:49]
	s_waitcnt vmcnt(9)
	ds_write_b128 v165, v[204:207] offset:46080
	s_waitcnt vmcnt(8)
	ds_write_b128 v165, v[208:211] offset:50688
	v_mfma_f32_16x16x32_bf16 v[18:21], v[220:223], v[228:231], v[18:21]
	v_mfma_f32_16x16x32_bf16 v[22:25], v[220:223], v[236:239], v[22:25]
	v_mfma_f32_16x16x32_bf16 v[2:5], v[220:223], v[240:243], v[2:5]
	v_mfma_f32_16x16x32_bf16 v[6:9], v[220:223], v[252:255], v[6:9]
	s_waitcnt lgkmcnt(4)
	v_mfma_f32_16x16x32_bf16 v[26:29], v[224:227], v[228:231], v[26:29]
	v_mfma_f32_16x16x32_bf16 v[30:33], v[224:227], v[236:239], v[30:33]
	v_mfma_f32_16x16x32_bf16 v[10:13], v[224:227], v[240:243], v[10:13]
	v_mfma_f32_16x16x32_bf16 v[14:17], v[224:227], v[252:255], v[14:17]
	s_waitcnt lgkmcnt(0)
	s_barrier
	global_load_dwordx4 v[180:183], v[72:73], off offset:1536
	global_load_dwordx4 v[184:187], v[74:75], off offset:1536
	global_load_dwordx4 v[188:191], v[76:77], off offset:1536
	global_load_dwordx4 v[192:195], v[78:79], off offset:1536
	global_load_dwordx4 v[196:199], v[70:71], off offset:1536
	global_load_dwordx4 v[200:203], v[68:69], off offset:1536
	global_load_dwordx4 v[204:207], v[66:67], off offset:1536
	global_load_dwordx4 v[208:211], v[80:81], off offset:1536
	ds_read_b128 v[228:231], v245 offset:36864
	ds_read_b128 v[212:215], v244
	ds_read_b128 v[236:239], v245 offset:39168
	ds_read_b128 v[240:243], v245 offset:41472
	ds_read_b128 v[252:255], v245 offset:43776
	ds_read_b128 v[216:219], v244 offset:2304
	ds_read_b128 v[220:223], v244 offset:4608
	ds_read_b128 v[224:227], v244 offset:6912
	s_setprio 0
	s_waitcnt lgkmcnt(6)
	v_mfma_f32_16x16x32_bf16 v[50:53], v[212:215], v[228:231], v[50:53]
	s_waitcnt lgkmcnt(5)
	v_mfma_f32_16x16x32_bf16 v[54:57], v[212:215], v[236:239], v[54:57]
	s_waitcnt lgkmcnt(4)
	v_mfma_f32_16x16x32_bf16 v[34:37], v[212:215], v[240:243], v[34:37]
	s_waitcnt lgkmcnt(3)
	v_mfma_f32_16x16x32_bf16 v[38:41], v[212:215], v[252:255], v[38:41]
	ds_read_b128 v[212:215], v244 offset:64
	s_waitcnt lgkmcnt(3)
	v_mfma_f32_16x16x32_bf16 v[58:61], v[216:219], v[228:231], v[58:61]
	v_mfma_f32_16x16x32_bf16 v[62:65], v[216:219], v[236:239], v[62:65]
	v_mfma_f32_16x16x32_bf16 v[42:45], v[216:219], v[240:243], v[42:45]
	v_mfma_f32_16x16x32_bf16 v[46:49], v[216:219], v[252:255], v[46:49]
	ds_read_b128 v[216:219], v244 offset:2368
	s_setprio 1
	s_waitcnt vmcnt(15)
	ds_write_b128 v165, v[122:125] offset:18432
	s_waitcnt vmcnt(14)
	ds_write_b128 v165, v[126:129] offset:23040
	s_waitcnt lgkmcnt(5)
	v_mfma_f32_16x16x32_bf16 v[18:21], v[220:223], v[228:231], v[18:21]
	v_mfma_f32_16x16x32_bf16 v[22:25], v[220:223], v[236:239], v[22:25]
	v_mfma_f32_16x16x32_bf16 v[2:5], v[220:223], v[240:243], v[2:5]
	v_mfma_f32_16x16x32_bf16 v[6:9], v[220:223], v[252:255], v[6:9]
	ds_read_b128 v[220:223], v244 offset:4672
	s_waitcnt vmcnt(13)
	ds_write_b128 v165, v[136:139] offset:27648
	s_waitcnt vmcnt(12)
	ds_write_b128 v165, v[140:143] offset:32256
	s_waitcnt lgkmcnt(7)
	v_mfma_f32_16x16x32_bf16 v[26:29], v[224:227], v[228:231], v[26:29]
	ds_read_b128 v[228:231], v245 offset:36928
	v_mfma_f32_16x16x32_bf16 v[30:33], v[224:227], v[236:239], v[30:33]
	ds_read_b128 v[236:239], v245 offset:39232
	v_mfma_f32_16x16x32_bf16 v[10:13], v[224:227], v[240:243], v[10:13]
	ds_read_b128 v[240:243], v245 offset:41536
	v_mfma_f32_16x16x32_bf16 v[14:17], v[224:227], v[252:255], v[14:17]
	ds_read_b128 v[252:255], v245 offset:43840
	ds_read_b128 v[224:227], v244 offset:6976
	s_waitcnt lgkmcnt(4)
	v_mfma_f32_16x16x32_bf16 v[50:53], v[212:215], v[228:231], v[50:53]
	s_waitcnt lgkmcnt(3)
	v_mfma_f32_16x16x32_bf16 v[54:57], v[212:215], v[236:239], v[54:57]
	s_waitcnt lgkmcnt(2)
	v_mfma_f32_16x16x32_bf16 v[34:37], v[212:215], v[240:243], v[34:37]
	s_waitcnt lgkmcnt(1)
	v_mfma_f32_16x16x32_bf16 v[38:41], v[212:215], v[252:255], v[38:41]
	s_waitcnt vmcnt(11)
	ds_write_b128 v165, v[144:147] offset:55296
	s_waitcnt vmcnt(10)
	ds_write_b128 v165, v[148:151] offset:59904
	v_mfma_f32_16x16x32_bf16 v[58:61], v[216:219], v[228:231], v[58:61]
	v_mfma_f32_16x16x32_bf16 v[62:65], v[216:219], v[236:239], v[62:65]
	v_mfma_f32_16x16x32_bf16 v[42:45], v[216:219], v[240:243], v[42:45]
	v_mfma_f32_16x16x32_bf16 v[46:49], v[216:219], v[252:255], v[46:49]
	s_waitcnt vmcnt(9)
	ds_write_b128 v165, v[172:175] offset:64512
	s_waitcnt vmcnt(8)
	ds_write_b128 v166, v[176:179] offset:32256
	v_mfma_f32_16x16x32_bf16 v[18:21], v[220:223], v[228:231], v[18:21]
	v_mfma_f32_16x16x32_bf16 v[22:25], v[220:223], v[236:239], v[22:25]
	v_mfma_f32_16x16x32_bf16 v[2:5], v[220:223], v[240:243], v[2:5]
	v_mfma_f32_16x16x32_bf16 v[6:9], v[220:223], v[252:255], v[6:9]
	s_waitcnt lgkmcnt(4)
	v_mfma_f32_16x16x32_bf16 v[26:29], v[224:227], v[228:231], v[26:29]
	v_mfma_f32_16x16x32_bf16 v[30:33], v[224:227], v[236:239], v[30:33]
	v_mfma_f32_16x16x32_bf16 v[10:13], v[224:227], v[240:243], v[10:13]
	v_mfma_f32_16x16x32_bf16 v[14:17], v[224:227], v[252:255], v[14:17]
	s_waitcnt lgkmcnt(0)
	s_barrier
	global_load_dwordx4 v[122:125], v[72:73], off offset:1664
	global_load_dwordx4 v[126:129], v[74:75], off offset:1664
	global_load_dwordx4 v[136:139], v[76:77], off offset:1664
	global_load_dwordx4 v[140:143], v[78:79], off offset:1664
	global_load_dwordx4 v[144:147], v[70:71], off offset:1664
	global_load_dwordx4 v[148:151], v[68:69], off offset:1664
	global_load_dwordx4 v[172:175], v[66:67], off offset:1664
	global_load_dwordx4 v[176:179], v[80:81], off offset:1664
	ds_read_b128 v[228:231], v245 offset:55296
	ds_read_b128 v[212:215], v244 offset:18432
	ds_read_b128 v[236:239], v245 offset:57600
	ds_read_b128 v[240:243], v245 offset:59904
	ds_read_b128 v[252:255], v245 offset:62208
	ds_read_b128 v[216:219], v244 offset:20736
	ds_read_b128 v[220:223], v244 offset:23040
	ds_read_b128 v[224:227], v244 offset:25344
	s_setprio 0
	s_waitcnt lgkmcnt(6)
	v_mfma_f32_16x16x32_bf16 v[50:53], v[212:215], v[228:231], v[50:53]
	s_waitcnt lgkmcnt(5)
	v_mfma_f32_16x16x32_bf16 v[54:57], v[212:215], v[236:239], v[54:57]
	s_waitcnt lgkmcnt(4)
	v_mfma_f32_16x16x32_bf16 v[34:37], v[212:215], v[240:243], v[34:37]
	s_waitcnt lgkmcnt(3)
	v_mfma_f32_16x16x32_bf16 v[38:41], v[212:215], v[252:255], v[38:41]
	ds_read_b128 v[212:215], v244 offset:18496
	s_waitcnt lgkmcnt(3)
	v_mfma_f32_16x16x32_bf16 v[58:61], v[216:219], v[228:231], v[58:61]
	v_mfma_f32_16x16x32_bf16 v[62:65], v[216:219], v[236:239], v[62:65]
	v_mfma_f32_16x16x32_bf16 v[42:45], v[216:219], v[240:243], v[42:45]
	v_mfma_f32_16x16x32_bf16 v[46:49], v[216:219], v[252:255], v[46:49]
	ds_read_b128 v[216:219], v244 offset:20800
	s_setprio 1
	s_waitcnt vmcnt(15)
	ds_write_b128 v165, v[180:183]
	s_waitcnt vmcnt(14)
	ds_write_b128 v165, v[184:187] offset:4608
	s_waitcnt lgkmcnt(5)
	v_mfma_f32_16x16x32_bf16 v[18:21], v[220:223], v[228:231], v[18:21]
	v_mfma_f32_16x16x32_bf16 v[22:25], v[220:223], v[236:239], v[22:25]
	v_mfma_f32_16x16x32_bf16 v[2:5], v[220:223], v[240:243], v[2:5]
	v_mfma_f32_16x16x32_bf16 v[6:9], v[220:223], v[252:255], v[6:9]
	ds_read_b128 v[220:223], v244 offset:23104
	s_waitcnt vmcnt(13)
	ds_write_b128 v165, v[188:191] offset:9216
	s_waitcnt vmcnt(12)
	ds_write_b128 v165, v[192:195] offset:13824
	s_waitcnt lgkmcnt(7)
	v_mfma_f32_16x16x32_bf16 v[26:29], v[224:227], v[228:231], v[26:29]
	ds_read_b128 v[228:231], v245 offset:55360
	v_mfma_f32_16x16x32_bf16 v[30:33], v[224:227], v[236:239], v[30:33]
	ds_read_b128 v[236:239], v245 offset:57664
	v_mfma_f32_16x16x32_bf16 v[10:13], v[224:227], v[240:243], v[10:13]
	ds_read_b128 v[240:243], v245 offset:59968
	v_mfma_f32_16x16x32_bf16 v[14:17], v[224:227], v[252:255], v[14:17]
	ds_read_b128 v[252:255], v245 offset:62272
	ds_read_b128 v[224:227], v244 offset:25408
	s_waitcnt lgkmcnt(4)
	v_mfma_f32_16x16x32_bf16 v[50:53], v[212:215], v[228:231], v[50:53]
	s_waitcnt lgkmcnt(3)
	v_mfma_f32_16x16x32_bf16 v[54:57], v[212:215], v[236:239], v[54:57]
	s_waitcnt lgkmcnt(2)
	v_mfma_f32_16x16x32_bf16 v[34:37], v[212:215], v[240:243], v[34:37]
	s_waitcnt lgkmcnt(1)
	v_mfma_f32_16x16x32_bf16 v[38:41], v[212:215], v[252:255], v[38:41]
	s_waitcnt vmcnt(11)
	ds_write_b128 v165, v[196:199] offset:36864
	s_waitcnt vmcnt(10)
	ds_write_b128 v165, v[200:203] offset:41472
	v_mfma_f32_16x16x32_bf16 v[58:61], v[216:219], v[228:231], v[58:61]
	v_mfma_f32_16x16x32_bf16 v[62:65], v[216:219], v[236:239], v[62:65]
	v_mfma_f32_16x16x32_bf16 v[42:45], v[216:219], v[240:243], v[42:45]
	v_mfma_f32_16x16x32_bf16 v[46:49], v[216:219], v[252:255], v[46:49]
	s_waitcnt vmcnt(9)
	ds_write_b128 v165, v[204:207] offset:46080
	s_waitcnt vmcnt(8)
	ds_write_b128 v165, v[208:211] offset:50688
	v_mfma_f32_16x16x32_bf16 v[18:21], v[220:223], v[228:231], v[18:21]
	v_mfma_f32_16x16x32_bf16 v[22:25], v[220:223], v[236:239], v[22:25]
	v_mfma_f32_16x16x32_bf16 v[2:5], v[220:223], v[240:243], v[2:5]
	v_mfma_f32_16x16x32_bf16 v[6:9], v[220:223], v[252:255], v[6:9]
	s_waitcnt lgkmcnt(4)
	v_mfma_f32_16x16x32_bf16 v[26:29], v[224:227], v[228:231], v[26:29]
	v_mfma_f32_16x16x32_bf16 v[30:33], v[224:227], v[236:239], v[30:33]
	v_mfma_f32_16x16x32_bf16 v[10:13], v[224:227], v[240:243], v[10:13]
	v_mfma_f32_16x16x32_bf16 v[14:17], v[224:227], v[252:255], v[14:17]
	s_waitcnt lgkmcnt(0)
	s_barrier
	global_load_dwordx4 v[180:183], v[72:73], off offset:1792
	global_load_dwordx4 v[184:187], v[74:75], off offset:1792
	global_load_dwordx4 v[188:191], v[76:77], off offset:1792
	global_load_dwordx4 v[192:195], v[78:79], off offset:1792
	global_load_dwordx4 v[196:199], v[70:71], off offset:1792
	global_load_dwordx4 v[200:203], v[68:69], off offset:1792
	global_load_dwordx4 v[204:207], v[66:67], off offset:1792
	global_load_dwordx4 v[208:211], v[80:81], off offset:1792
	ds_read_b128 v[228:231], v245 offset:36864
	ds_read_b128 v[212:215], v244
	ds_read_b128 v[236:239], v245 offset:39168
	ds_read_b128 v[240:243], v245 offset:41472
	ds_read_b128 v[252:255], v245 offset:43776
	ds_read_b128 v[216:219], v244 offset:2304
	ds_read_b128 v[220:223], v244 offset:4608
	ds_read_b128 v[224:227], v244 offset:6912
	s_setprio 0
	s_waitcnt lgkmcnt(6)
	v_mfma_f32_16x16x32_bf16 v[50:53], v[212:215], v[228:231], v[50:53]
	s_waitcnt lgkmcnt(5)
	v_mfma_f32_16x16x32_bf16 v[54:57], v[212:215], v[236:239], v[54:57]
	s_waitcnt lgkmcnt(4)
	v_mfma_f32_16x16x32_bf16 v[34:37], v[212:215], v[240:243], v[34:37]
	s_waitcnt lgkmcnt(3)
	v_mfma_f32_16x16x32_bf16 v[38:41], v[212:215], v[252:255], v[38:41]
	ds_read_b128 v[212:215], v244 offset:64
	s_waitcnt lgkmcnt(3)
	v_mfma_f32_16x16x32_bf16 v[58:61], v[216:219], v[228:231], v[58:61]
	v_mfma_f32_16x16x32_bf16 v[62:65], v[216:219], v[236:239], v[62:65]
	v_mfma_f32_16x16x32_bf16 v[42:45], v[216:219], v[240:243], v[42:45]
	v_mfma_f32_16x16x32_bf16 v[46:49], v[216:219], v[252:255], v[46:49]
	ds_read_b128 v[216:219], v244 offset:2368
	s_setprio 1
	s_waitcnt vmcnt(15)
	ds_write_b128 v165, v[122:125] offset:18432
	s_waitcnt vmcnt(14)
	ds_write_b128 v165, v[126:129] offset:23040
	s_waitcnt lgkmcnt(5)
	v_mfma_f32_16x16x32_bf16 v[18:21], v[220:223], v[228:231], v[18:21]
	v_mfma_f32_16x16x32_bf16 v[22:25], v[220:223], v[236:239], v[22:25]
	v_mfma_f32_16x16x32_bf16 v[2:5], v[220:223], v[240:243], v[2:5]
	v_mfma_f32_16x16x32_bf16 v[6:9], v[220:223], v[252:255], v[6:9]
	ds_read_b128 v[220:223], v244 offset:4672
	s_waitcnt vmcnt(13)
	ds_write_b128 v165, v[136:139] offset:27648
	s_waitcnt vmcnt(12)
	ds_write_b128 v165, v[140:143] offset:32256
	s_waitcnt lgkmcnt(7)
	v_mfma_f32_16x16x32_bf16 v[26:29], v[224:227], v[228:231], v[26:29]
	ds_read_b128 v[228:231], v245 offset:36928
	v_mfma_f32_16x16x32_bf16 v[30:33], v[224:227], v[236:239], v[30:33]
	ds_read_b128 v[236:239], v245 offset:39232
	v_mfma_f32_16x16x32_bf16 v[10:13], v[224:227], v[240:243], v[10:13]
	ds_read_b128 v[240:243], v245 offset:41536
	v_mfma_f32_16x16x32_bf16 v[14:17], v[224:227], v[252:255], v[14:17]
	ds_read_b128 v[252:255], v245 offset:43840
	ds_read_b128 v[224:227], v244 offset:6976
	s_waitcnt lgkmcnt(4)
	v_mfma_f32_16x16x32_bf16 v[50:53], v[212:215], v[228:231], v[50:53]
	s_waitcnt lgkmcnt(3)
	v_mfma_f32_16x16x32_bf16 v[54:57], v[212:215], v[236:239], v[54:57]
	s_waitcnt lgkmcnt(2)
	v_mfma_f32_16x16x32_bf16 v[34:37], v[212:215], v[240:243], v[34:37]
	s_waitcnt lgkmcnt(1)
	v_mfma_f32_16x16x32_bf16 v[38:41], v[212:215], v[252:255], v[38:41]
	s_waitcnt vmcnt(11)
	ds_write_b128 v165, v[144:147] offset:55296
	s_waitcnt vmcnt(10)
	ds_write_b128 v165, v[148:151] offset:59904
	v_mfma_f32_16x16x32_bf16 v[58:61], v[216:219], v[228:231], v[58:61]
	v_mfma_f32_16x16x32_bf16 v[62:65], v[216:219], v[236:239], v[62:65]
	v_mfma_f32_16x16x32_bf16 v[42:45], v[216:219], v[240:243], v[42:45]
	v_mfma_f32_16x16x32_bf16 v[46:49], v[216:219], v[252:255], v[46:49]
	s_waitcnt vmcnt(9)
	ds_write_b128 v165, v[172:175] offset:64512
	s_waitcnt vmcnt(8)
	ds_write_b128 v166, v[176:179] offset:32256
	v_mfma_f32_16x16x32_bf16 v[18:21], v[220:223], v[228:231], v[18:21]
	v_mfma_f32_16x16x32_bf16 v[22:25], v[220:223], v[236:239], v[22:25]
	v_mfma_f32_16x16x32_bf16 v[2:5], v[220:223], v[240:243], v[2:5]
	v_mfma_f32_16x16x32_bf16 v[6:9], v[220:223], v[252:255], v[6:9]
	s_waitcnt lgkmcnt(4)
	v_mfma_f32_16x16x32_bf16 v[26:29], v[224:227], v[228:231], v[26:29]
	v_mfma_f32_16x16x32_bf16 v[30:33], v[224:227], v[236:239], v[30:33]
	v_mfma_f32_16x16x32_bf16 v[10:13], v[224:227], v[240:243], v[10:13]
	v_mfma_f32_16x16x32_bf16 v[14:17], v[224:227], v[252:255], v[14:17]
	s_waitcnt lgkmcnt(0)
	s_barrier
	global_load_dwordx4 v[122:125], v[72:73], off offset:1920
	s_nop 0
	global_load_dwordx4 v[72:75], v[74:75], off offset:1920
	s_nop 0
	global_load_dwordx4 v[126:129], v[76:77], off offset:1920
	s_nop 0
	global_load_dwordx4 v[76:79], v[78:79], off offset:1920
	s_nop 0
	global_load_dwordx4 v[136:139], v[70:71], off offset:1920
	s_nop 0
	global_load_dwordx4 v[68:71], v[68:69], off offset:1920
	s_nop 0
	global_load_dwordx4 v[140:143], v[66:67], off offset:1920
	global_load_dwordx4 v[144:147], v[80:81], off offset:1920
	ds_read_b128 v[228:231], v245 offset:55296
	ds_read_b128 v[212:215], v244 offset:18432
	ds_read_b128 v[236:239], v245 offset:57600
	ds_read_b128 v[240:243], v245 offset:59904
	ds_read_b128 v[252:255], v245 offset:62208
	ds_read_b128 v[216:219], v244 offset:20736
	ds_read_b128 v[220:223], v244 offset:23040
	ds_read_b128 v[224:227], v244 offset:25344
	s_setprio 0
	s_waitcnt lgkmcnt(6)
	v_mfma_f32_16x16x32_bf16 v[50:53], v[212:215], v[228:231], v[50:53]
	s_waitcnt lgkmcnt(5)
	v_mfma_f32_16x16x32_bf16 v[54:57], v[212:215], v[236:239], v[54:57]
	s_waitcnt lgkmcnt(4)
	v_mfma_f32_16x16x32_bf16 v[34:37], v[212:215], v[240:243], v[34:37]
	s_waitcnt lgkmcnt(3)
	v_mfma_f32_16x16x32_bf16 v[38:41], v[212:215], v[252:255], v[38:41]
	ds_read_b128 v[212:215], v244 offset:18496
	s_waitcnt lgkmcnt(3)
	v_mfma_f32_16x16x32_bf16 v[58:61], v[216:219], v[228:231], v[58:61]
	v_mfma_f32_16x16x32_bf16 v[62:65], v[216:219], v[236:239], v[62:65]
	v_mfma_f32_16x16x32_bf16 v[42:45], v[216:219], v[240:243], v[42:45]
	v_mfma_f32_16x16x32_bf16 v[46:49], v[216:219], v[252:255], v[46:49]
	ds_read_b128 v[216:219], v244 offset:20800
	s_setprio 1
	s_waitcnt vmcnt(15)
	ds_write_b128 v165, v[180:183]
	s_waitcnt vmcnt(14)
	ds_write_b128 v165, v[184:187] offset:4608
	s_waitcnt lgkmcnt(5)
	v_mfma_f32_16x16x32_bf16 v[18:21], v[220:223], v[228:231], v[18:21]
	v_mfma_f32_16x16x32_bf16 v[22:25], v[220:223], v[236:239], v[22:25]
	v_mfma_f32_16x16x32_bf16 v[2:5], v[220:223], v[240:243], v[2:5]
	v_mfma_f32_16x16x32_bf16 v[6:9], v[220:223], v[252:255], v[6:9]
	ds_read_b128 v[220:223], v244 offset:23104
	s_waitcnt vmcnt(13)
	ds_write_b128 v165, v[188:191] offset:9216
	s_waitcnt vmcnt(12)
	ds_write_b128 v165, v[192:195] offset:13824
	s_waitcnt lgkmcnt(7)
	v_mfma_f32_16x16x32_bf16 v[26:29], v[224:227], v[228:231], v[26:29]
	ds_read_b128 v[228:231], v245 offset:55360
	v_mfma_f32_16x16x32_bf16 v[30:33], v[224:227], v[236:239], v[30:33]
	ds_read_b128 v[236:239], v245 offset:57664
	v_mfma_f32_16x16x32_bf16 v[10:13], v[224:227], v[240:243], v[10:13]
	ds_read_b128 v[240:243], v245 offset:59968
	v_mfma_f32_16x16x32_bf16 v[14:17], v[224:227], v[252:255], v[14:17]
	ds_read_b128 v[252:255], v245 offset:62272
	ds_read_b128 v[224:227], v244 offset:25408
	s_waitcnt lgkmcnt(4)
	v_mfma_f32_16x16x32_bf16 v[50:53], v[212:215], v[228:231], v[50:53]
	s_waitcnt lgkmcnt(3)
	v_mfma_f32_16x16x32_bf16 v[54:57], v[212:215], v[236:239], v[54:57]
	s_waitcnt lgkmcnt(2)
	v_mfma_f32_16x16x32_bf16 v[34:37], v[212:215], v[240:243], v[34:37]
	s_waitcnt lgkmcnt(1)
	v_mfma_f32_16x16x32_bf16 v[38:41], v[212:215], v[252:255], v[38:41]
	s_waitcnt vmcnt(11)
	ds_write_b128 v165, v[196:199] offset:36864
	s_waitcnt vmcnt(10)
	ds_write_b128 v165, v[200:203] offset:41472
	v_mfma_f32_16x16x32_bf16 v[58:61], v[216:219], v[228:231], v[58:61]
	v_mfma_f32_16x16x32_bf16 v[62:65], v[216:219], v[236:239], v[62:65]
	v_mfma_f32_16x16x32_bf16 v[42:45], v[216:219], v[240:243], v[42:45]
	v_mfma_f32_16x16x32_bf16 v[46:49], v[216:219], v[252:255], v[46:49]
	s_waitcnt vmcnt(9)
	ds_write_b128 v165, v[204:207] offset:46080
	s_waitcnt vmcnt(8)
	ds_write_b128 v165, v[208:211] offset:50688
	v_mfma_f32_16x16x32_bf16 v[18:21], v[220:223], v[228:231], v[18:21]
	v_mfma_f32_16x16x32_bf16 v[22:25], v[220:223], v[236:239], v[22:25]
	v_mfma_f32_16x16x32_bf16 v[2:5], v[220:223], v[240:243], v[2:5]
	v_mfma_f32_16x16x32_bf16 v[6:9], v[220:223], v[252:255], v[6:9]
	s_waitcnt lgkmcnt(4)
	v_mfma_f32_16x16x32_bf16 v[26:29], v[224:227], v[228:231], v[26:29]
	v_mfma_f32_16x16x32_bf16 v[30:33], v[224:227], v[236:239], v[30:33]
	v_mfma_f32_16x16x32_bf16 v[10:13], v[224:227], v[240:243], v[10:13]
	v_mfma_f32_16x16x32_bf16 v[14:17], v[224:227], v[252:255], v[14:17]
	s_waitcnt lgkmcnt(0)
	s_barrier
	ds_read_b128 v[228:231], v245 offset:36864
	ds_read_b128 v[212:215], v244
	ds_read_b128 v[236:239], v245 offset:39168
	ds_read_b128 v[240:243], v245 offset:41472
	ds_read_b128 v[252:255], v245 offset:43776
	ds_read_b128 v[216:219], v244 offset:2304
	ds_read_b128 v[220:223], v244 offset:4608
	ds_read_b128 v[224:227], v244 offset:6912
	s_setprio 0
	s_waitcnt lgkmcnt(6)
	v_mfma_f32_16x16x32_bf16 v[50:53], v[212:215], v[228:231], v[50:53]
	s_waitcnt lgkmcnt(5)
	v_mfma_f32_16x16x32_bf16 v[54:57], v[212:215], v[236:239], v[54:57]
	s_waitcnt lgkmcnt(4)
	v_mfma_f32_16x16x32_bf16 v[34:37], v[212:215], v[240:243], v[34:37]
	s_waitcnt lgkmcnt(3)
	v_mfma_f32_16x16x32_bf16 v[38:41], v[212:215], v[252:255], v[38:41]
	ds_read_b128 v[212:215], v244 offset:64
	s_waitcnt lgkmcnt(3)
	v_mfma_f32_16x16x32_bf16 v[58:61], v[216:219], v[228:231], v[58:61]
	v_mfma_f32_16x16x32_bf16 v[62:65], v[216:219], v[236:239], v[62:65]
	v_mfma_f32_16x16x32_bf16 v[42:45], v[216:219], v[240:243], v[42:45]
	v_mfma_f32_16x16x32_bf16 v[46:49], v[216:219], v[252:255], v[46:49]
	ds_read_b128 v[216:219], v244 offset:2368
	s_setprio 1
	s_waitcnt vmcnt(7)
	ds_write_b128 v165, v[122:125] offset:18432
	s_waitcnt vmcnt(6)
	ds_write_b128 v165, v[72:75] offset:23040
	s_waitcnt lgkmcnt(5)
	v_mfma_f32_16x16x32_bf16 v[18:21], v[220:223], v[228:231], v[18:21]
	v_mfma_f32_16x16x32_bf16 v[22:25], v[220:223], v[236:239], v[22:25]
	v_mfma_f32_16x16x32_bf16 v[2:5], v[220:223], v[240:243], v[2:5]
	v_mfma_f32_16x16x32_bf16 v[6:9], v[220:223], v[252:255], v[6:9]
	ds_read_b128 v[220:223], v244 offset:4672
	s_waitcnt vmcnt(5)
	ds_write_b128 v165, v[126:129] offset:27648
	s_waitcnt vmcnt(4)
	ds_write_b128 v165, v[76:79] offset:32256
	s_waitcnt lgkmcnt(7)
	v_mfma_f32_16x16x32_bf16 v[26:29], v[224:227], v[228:231], v[26:29]
	ds_read_b128 v[228:231], v245 offset:36928
	v_mfma_f32_16x16x32_bf16 v[30:33], v[224:227], v[236:239], v[30:33]
	ds_read_b128 v[236:239], v245 offset:39232
	v_mfma_f32_16x16x32_bf16 v[10:13], v[224:227], v[240:243], v[10:13]
	ds_read_b128 v[240:243], v245 offset:41536
	v_mfma_f32_16x16x32_bf16 v[14:17], v[224:227], v[252:255], v[14:17]
	ds_read_b128 v[252:255], v245 offset:43840
	ds_read_b128 v[224:227], v244 offset:6976
	s_waitcnt lgkmcnt(4)
	v_mfma_f32_16x16x32_bf16 v[50:53], v[212:215], v[228:231], v[50:53]
	s_waitcnt lgkmcnt(3)
	v_mfma_f32_16x16x32_bf16 v[54:57], v[212:215], v[236:239], v[54:57]
	s_waitcnt lgkmcnt(2)
	v_mfma_f32_16x16x32_bf16 v[34:37], v[212:215], v[240:243], v[34:37]
	s_waitcnt lgkmcnt(1)
	v_mfma_f32_16x16x32_bf16 v[38:41], v[212:215], v[252:255], v[38:41]
	s_waitcnt vmcnt(3)
	ds_write_b128 v165, v[136:139] offset:55296
	s_waitcnt vmcnt(2)
	ds_write_b128 v165, v[68:71] offset:59904
	v_mfma_f32_16x16x32_bf16 v[58:61], v[216:219], v[228:231], v[58:61]
	v_mfma_f32_16x16x32_bf16 v[62:65], v[216:219], v[236:239], v[62:65]
	v_mfma_f32_16x16x32_bf16 v[42:45], v[216:219], v[240:243], v[42:45]
	v_mfma_f32_16x16x32_bf16 v[46:49], v[216:219], v[252:255], v[46:49]
	s_waitcnt vmcnt(1)
	ds_write_b128 v165, v[140:143] offset:64512
	s_waitcnt vmcnt(0)
	ds_write_b128 v166, v[144:147] offset:32256
	v_mfma_f32_16x16x32_bf16 v[18:21], v[220:223], v[228:231], v[18:21]
	v_mfma_f32_16x16x32_bf16 v[22:25], v[220:223], v[236:239], v[22:25]
	v_mfma_f32_16x16x32_bf16 v[2:5], v[220:223], v[240:243], v[2:5]
	v_mfma_f32_16x16x32_bf16 v[6:9], v[220:223], v[252:255], v[6:9]
	s_waitcnt lgkmcnt(4)
	v_mfma_f32_16x16x32_bf16 v[26:29], v[224:227], v[228:231], v[26:29]
	v_mfma_f32_16x16x32_bf16 v[30:33], v[224:227], v[236:239], v[30:33]
	v_mfma_f32_16x16x32_bf16 v[10:13], v[224:227], v[240:243], v[10:13]
	v_mfma_f32_16x16x32_bf16 v[14:17], v[224:227], v[252:255], v[14:17]
	s_waitcnt lgkmcnt(0)
	s_barrier
	ds_read_b128 v[228:231], v245 offset:55296
	ds_read_b128 v[212:215], v244 offset:18432
	ds_read_b128 v[236:239], v245 offset:57600
	ds_read_b128 v[240:243], v245 offset:59904
	ds_read_b128 v[252:255], v245 offset:62208
	ds_read_b128 v[216:219], v244 offset:20736
	ds_read_b128 v[220:223], v244 offset:23040
	ds_read_b128 v[224:227], v244 offset:25344
	s_setprio 0
	s_waitcnt lgkmcnt(6)
	v_mfma_f32_16x16x32_bf16 v[50:53], v[212:215], v[228:231], v[50:53]
	s_waitcnt lgkmcnt(5)
	v_mfma_f32_16x16x32_bf16 v[54:57], v[212:215], v[236:239], v[54:57]
	s_waitcnt lgkmcnt(4)
	v_mfma_f32_16x16x32_bf16 v[34:37], v[212:215], v[240:243], v[34:37]
	s_waitcnt lgkmcnt(3)
	v_mfma_f32_16x16x32_bf16 v[38:41], v[212:215], v[252:255], v[38:41]
	ds_read_b128 v[212:215], v244 offset:18496
	s_waitcnt lgkmcnt(3)
	v_mfma_f32_16x16x32_bf16 v[58:61], v[216:219], v[228:231], v[58:61]
	v_mfma_f32_16x16x32_bf16 v[62:65], v[216:219], v[236:239], v[62:65]
	v_mfma_f32_16x16x32_bf16 v[42:45], v[216:219], v[240:243], v[42:45]
	v_mfma_f32_16x16x32_bf16 v[46:49], v[216:219], v[252:255], v[46:49]
	ds_read_b128 v[216:219], v244 offset:20800
	s_waitcnt lgkmcnt(3)
	v_mfma_f32_16x16x32_bf16 v[18:21], v[220:223], v[228:231], v[18:21]
	v_mfma_f32_16x16x32_bf16 v[22:25], v[220:223], v[236:239], v[22:25]
	v_mfma_f32_16x16x32_bf16 v[2:5], v[220:223], v[240:243], v[2:5]
	v_mfma_f32_16x16x32_bf16 v[6:9], v[220:223], v[252:255], v[6:9]
	ds_read_b128 v[220:223], v244 offset:23104
	s_waitcnt lgkmcnt(3)
	v_mfma_f32_16x16x32_bf16 v[26:29], v[224:227], v[228:231], v[26:29]
	ds_read_b128 v[228:231], v245 offset:55360
	v_mfma_f32_16x16x32_bf16 v[30:33], v[224:227], v[236:239], v[30:33]
	ds_read_b128 v[236:239], v245 offset:57664
	v_mfma_f32_16x16x32_bf16 v[10:13], v[224:227], v[240:243], v[10:13]
	ds_read_b128 v[240:243], v245 offset:59968
	v_mfma_f32_16x16x32_bf16 v[14:17], v[224:227], v[252:255], v[14:17]
	ds_read_b128 v[252:255], v245 offset:62272
	ds_read_b128 v[224:227], v244 offset:25408
	s_waitcnt lgkmcnt(4)
	v_mfma_f32_16x16x32_bf16 v[50:53], v[212:215], v[228:231], v[50:53]
	s_waitcnt lgkmcnt(3)
	v_mfma_f32_16x16x32_bf16 v[54:57], v[212:215], v[236:239], v[54:57]
	s_waitcnt lgkmcnt(2)
	v_mfma_f32_16x16x32_bf16 v[34:37], v[212:215], v[240:243], v[34:37]
	s_waitcnt lgkmcnt(1)
	v_mfma_f32_16x16x32_bf16 v[38:41], v[212:215], v[252:255], v[38:41]
	v_mfma_f32_16x16x32_bf16 v[58:61], v[216:219], v[228:231], v[58:61]
	v_mfma_f32_16x16x32_bf16 v[62:65], v[216:219], v[236:239], v[62:65]
	v_mfma_f32_16x16x32_bf16 v[42:45], v[216:219], v[240:243], v[42:45]
	v_mfma_f32_16x16x32_bf16 v[46:49], v[216:219], v[252:255], v[46:49]
	v_mfma_f32_16x16x32_bf16 v[18:21], v[220:223], v[228:231], v[18:21]
	v_mfma_f32_16x16x32_bf16 v[22:25], v[220:223], v[236:239], v[22:25]
	v_mfma_f32_16x16x32_bf16 v[2:5], v[220:223], v[240:243], v[2:5]
	v_mfma_f32_16x16x32_bf16 v[6:9], v[220:223], v[252:255], v[6:9]
	s_waitcnt lgkmcnt(0)
	v_mfma_f32_16x16x32_bf16 v[26:29], v[224:227], v[228:231], v[26:29]
	v_mfma_f32_16x16x32_bf16 v[30:33], v[224:227], v[236:239], v[30:33]
	v_mfma_f32_16x16x32_bf16 v[10:13], v[224:227], v[240:243], v[10:13]
	v_mfma_f32_16x16x32_bf16 v[14:17], v[224:227], v[252:255], v[14:17]
	s_mov_b64 s[2:3], 0
	s_waitcnt lgkmcnt(0)
	s_barrier
	s_nop 7
	v_permlane16_swap_b32_e32 v50, v54
	v_permlane16_swap_b32_e32 v51, v55
	v_permlane16_swap_b32_e32 v52, v56
	v_permlane16_swap_b32_e32 v53, v57
	v_permlane16_swap_b32_e32 v58, v62
	v_permlane16_swap_b32_e32 v59, v63
	v_permlane16_swap_b32_e32 v60, v64
	v_permlane16_swap_b32_e32 v61, v65
	v_permlane16_swap_b32_e32 v34, v38
	v_permlane16_swap_b32_e32 v35, v39
	v_permlane16_swap_b32_e32 v36, v40
	v_permlane16_swap_b32_e32 v37, v41
	v_permlane16_swap_b32_e32 v42, v46
	v_permlane16_swap_b32_e32 v43, v47
	v_permlane16_swap_b32_e32 v44, v48
	v_permlane16_swap_b32_e32 v45, v49
	v_permlane16_swap_b32_e32 v18, v22
	v_permlane16_swap_b32_e32 v19, v23
	v_permlane16_swap_b32_e32 v20, v24
	v_permlane16_swap_b32_e32 v21, v25
	v_permlane16_swap_b32_e32 v26, v30
	v_permlane16_swap_b32_e32 v27, v31
	v_permlane16_swap_b32_e32 v28, v32
	v_permlane16_swap_b32_e32 v29, v33
	v_permlane16_swap_b32_e32 v2, v6
	v_permlane16_swap_b32_e32 v3, v7
	v_permlane16_swap_b32_e32 v4, v8
	v_permlane16_swap_b32_e32 v5, v9
	v_permlane16_swap_b32_e32 v10, v14
	v_permlane16_swap_b32_e32 v11, v15
	v_permlane16_swap_b32_e32 v12, v16
	v_permlane16_swap_b32_e32 v13, v17
	v_permlane32_swap_b32_e32 v50, v54
	v_permlane32_swap_b32_e32 v51, v55
	v_permlane32_swap_b32_e32 v52, v56
	v_permlane32_swap_b32_e32 v53, v57
	v_permlane32_swap_b32_e32 v58, v62
	v_permlane32_swap_b32_e32 v59, v63
	v_permlane32_swap_b32_e32 v60, v64
	v_permlane32_swap_b32_e32 v61, v65
	v_permlane32_swap_b32_e32 v34, v38
	v_permlane32_swap_b32_e32 v35, v39
	v_permlane32_swap_b32_e32 v36, v40
	v_permlane32_swap_b32_e32 v37, v41
	v_permlane32_swap_b32_e32 v42, v46
	v_permlane32_swap_b32_e32 v43, v47
	v_permlane32_swap_b32_e32 v44, v48
	v_permlane32_swap_b32_e32 v45, v49
	v_permlane32_swap_b32_e32 v18, v22
	v_permlane32_swap_b32_e32 v19, v23
	v_permlane32_swap_b32_e32 v20, v24
	v_permlane32_swap_b32_e32 v21, v25
	v_permlane32_swap_b32_e32 v26, v30
	v_permlane32_swap_b32_e32 v27, v31
	v_permlane32_swap_b32_e32 v28, v32
	v_permlane32_swap_b32_e32 v29, v33
	v_permlane32_swap_b32_e32 v2, v6
	v_permlane32_swap_b32_e32 v3, v7
	v_permlane32_swap_b32_e32 v4, v8
	v_permlane32_swap_b32_e32 v5, v9
	v_permlane32_swap_b32_e32 v10, v14
	v_permlane32_swap_b32_e32 v11, v15
	v_permlane32_swap_b32_e32 v12, v16
	v_permlane32_swap_b32_e32 v13, v17

.LBB0_275:
	v_ashrrev_i32_e32 v3, 31, v2
	v_lshlrev_b64 v[2:3], 11, v[2:3]
	v_ashrrev_i32_e32 v9, 31, v8
	v_lshl_add_u64 v[70:71], v[86:87], 0, v[2:3]
	v_lshlrev_b64 v[2:3], 11, v[8:9]
	v_lshl_add_u64 v[72:73], v[86:87], 0, v[2:3]
	v_or_b32_e32 v2, s56, v154
	v_ashrrev_i32_e32 v3, 31, v2
	v_lshlrev_b64 v[2:3], 11, v[2:3]
	v_lshl_add_u64 v[74:75], v[84:85], 0, v[2:3]
	v_add_u32_e32 v2, s56, v155
	v_ashrrev_i32_e32 v3, 31, v2
	v_lshlrev_b64 v[2:3], 11, v[2:3]
	v_lshl_add_u64 v[76:77], v[84:85], 0, v[2:3]
	v_add_u32_e32 v2, s56, v156
	v_ashrrev_i32_e32 v3, 31, v2
	v_lshlrev_b64 v[2:3], 11, v[2:3]
	v_lshl_add_u64 v[78:79], v[84:85], 0, v[2:3]
	v_add_u32_e32 v2, s56, v157
	v_ashrrev_i32_e32 v7, 31, v6
	v_ashrrev_i32_e32 v5, 31, v4
	v_ashrrev_i32_e32 v3, 31, v2
	v_lshlrev_b64 v[6:7], 11, v[6:7]
	v_lshlrev_b64 v[4:5], 11, v[4:5]
	v_lshlrev_b64 v[2:3], 11, v[2:3]
	v_lshl_add_u64 v[66:67], v[86:87], 0, v[6:7]
	v_lshl_add_u64 v[68:69], v[86:87], 0, v[4:5]
	v_lshl_add_u64 v[80:81], v[84:85], 0, v[2:3]
	global_load_dwordx4 v[2:5], v[70:71], off
	global_load_dwordx4 v[6:9], v[68:69], off
	global_load_dwordx4 v[10:13], v[66:67], off
	global_load_dwordx4 v[14:17], v[72:73], off
	global_load_dwordx4 v[18:21], v[74:75], off
	global_load_dwordx4 v[22:25], v[76:77], off
	global_load_dwordx4 v[26:29], v[78:79], off
	global_load_dwordx4 v[30:33], v[80:81], off
	global_load_dwordx4 v[122:125], v[70:71], off offset:128
	global_load_dwordx4 v[126:129], v[68:69], off offset:128
	global_load_dwordx4 v[136:139], v[66:67], off offset:128
	global_load_dwordx4 v[140:143], v[72:73], off offset:128
	global_load_dwordx4 v[144:147], v[74:75], off offset:128
	global_load_dwordx4 v[148:151], v[76:77], off offset:128
	global_load_dwordx4 v[172:175], v[78:79], off offset:128
	global_load_dwordx4 v[176:179], v[80:81], off offset:128
	s_waitcnt vmcnt(15)
	ds_write_b128 v165, v[2:5]
	s_waitcnt vmcnt(14)
	ds_write_b128 v165, v[6:9] offset:4608
	s_waitcnt vmcnt(13)
	ds_write_b128 v165, v[10:13] offset:9216
	s_waitcnt vmcnt(12)
	ds_write_b128 v165, v[14:17] offset:13824
	s_waitcnt vmcnt(11)
	ds_write_b128 v165, v[18:21] offset:36864
	s_waitcnt vmcnt(10)
	ds_write_b128 v165, v[22:25] offset:41472
	s_waitcnt vmcnt(9)
	ds_write_b128 v165, v[26:29] offset:46080
	s_waitcnt vmcnt(8)
	ds_write_b128 v165, v[30:33] offset:50688
	s_waitcnt lgkmcnt(0)
	s_barrier
	global_load_dwordx4 v[180:183], v[68:69], off offset:256
	global_load_dwordx4 v[184:187], v[66:67], off offset:256
	global_load_dwordx4 v[188:191], v[70:71], off offset:256
	global_load_dwordx4 v[192:195], v[72:73], off offset:256
	global_load_dwordx4 v[196:199], v[74:75], off offset:256
	global_load_dwordx4 v[200:203], v[76:77], off offset:256
	global_load_dwordx4 v[204:207], v[78:79], off offset:256
	global_load_dwordx4 v[208:211], v[80:81], off offset:256
	v_and_b32_e32 v246, 15, v1
	v_add_u32_e32 v246, 4, v246
	v_bfe_u32 v246, v246, 3, 1
	v_bfe_u32 v249, v1, 4, 2
	v_xor_b32_e32 v246, v246, v249
	v_bfe_u32 v249, v1, 5, 1
	v_sub_u32_e32 v246, v246, v249
	v_lshlrev_b32_e32 v246, 4, v246
	v_bfe_u32 v249, v1, 4, 1
	v_mul_u32_u24_e32 v249, 0x900, v249
	v_sub_u32_e32 v246, v246, v249
	v_add_u32_e32 v244, v246, v162
	v_add_u32_e32 v245, v246, v164
	ds_read_b128 v[228:231], v245 offset:36864
	ds_read_b128 v[212:215], v244
	ds_read_b128 v[236:239], v245 offset:39168
	ds_read_b128 v[240:243], v245 offset:41472
	ds_read_b128 v[252:255], v245 offset:43776
	ds_read_b128 v[216:219], v244 offset:2304
	ds_read_b128 v[220:223], v244 offset:4608
	ds_read_b128 v[224:227], v244 offset:6912
	s_waitcnt lgkmcnt(6)
	v_mfma_f32_16x16x32_bf16 v[50:53], v[212:215], v[228:231], 0
	s_waitcnt lgkmcnt(5)
	v_mfma_f32_16x16x32_bf16 v[54:57], v[212:215], v[236:239], 0
	s_waitcnt lgkmcnt(4)
	v_mfma_f32_16x16x32_bf16 v[34:37], v[212:215], v[240:243], 0
	s_waitcnt lgkmcnt(3)
	v_mfma_f32_16x16x32_bf16 v[38:41], v[212:215], v[252:255], 0
	ds_read_b128 v[212:215], v244 offset:64
	s_waitcnt lgkmcnt(3)
	v_mfma_f32_16x16x32_bf16 v[58:61], v[216:219], v[228:231], 0
	v_mfma_f32_16x16x32_bf16 v[62:65], v[216:219], v[236:239], 0
	v_mfma_f32_16x16x32_bf16 v[42:45], v[216:219], v[240:243], 0
	v_mfma_f32_16x16x32_bf16 v[46:49], v[216:219], v[252:255], 0
	ds_read_b128 v[216:219], v244 offset:2368
	s_setprio 1
	s_waitcnt vmcnt(15)
	ds_write_b128 v165, v[122:125] offset:18432
	s_waitcnt vmcnt(14)
	ds_write_b128 v165, v[126:129] offset:23040
	s_waitcnt lgkmcnt(5)
	v_mfma_f32_16x16x32_bf16 v[18:21], v[220:223], v[228:231], 0
	v_mfma_f32_16x16x32_bf16 v[22:25], v[220:223], v[236:239], 0
	v_mfma_f32_16x16x32_bf16 v[2:5], v[220:223], v[240:243], 0
	v_mfma_f32_16x16x32_bf16 v[6:9], v[220:223], v[252:255], 0
	ds_read_b128 v[220:223], v244 offset:4672
	s_waitcnt vmcnt(13)
	ds_write_b128 v165, v[136:139] offset:27648
	s_waitcnt vmcnt(12)
	ds_write_b128 v165, v[140:143] offset:32256
	s_waitcnt lgkmcnt(7)
	v_mfma_f32_16x16x32_bf16 v[26:29], v[224:227], v[228:231], 0
	ds_read_b128 v[228:231], v245 offset:36928
	v_mfma_f32_16x16x32_bf16 v[30:33], v[224:227], v[236:239], 0
	ds_read_b128 v[236:239], v245 offset:39232
	v_mfma_f32_16x16x32_bf16 v[10:13], v[224:227], v[240:243], 0
	ds_read_b128 v[240:243], v245 offset:41536
	v_mfma_f32_16x16x32_bf16 v[14:17], v[224:227], v[252:255], 0
	ds_read_b128 v[252:255], v245 offset:43840
	ds_read_b128 v[224:227], v244 offset:6976
	s_waitcnt lgkmcnt(4)
	v_mfma_f32_16x16x32_bf16 v[50:53], v[212:215], v[228:231], v[50:53]
	s_waitcnt lgkmcnt(3)
	v_mfma_f32_16x16x32_bf16 v[54:57], v[212:215], v[236:239], v[54:57]
	s_waitcnt lgkmcnt(2)
	v_mfma_f32_16x16x32_bf16 v[34:37], v[212:215], v[240:243], v[34:37]
	s_waitcnt lgkmcnt(1)
	v_mfma_f32_16x16x32_bf16 v[38:41], v[212:215], v[252:255], v[38:41]
	s_waitcnt vmcnt(11)
	ds_write_b128 v165, v[144:147] offset:55296
	s_waitcnt vmcnt(10)
	ds_write_b128 v165, v[148:151] offset:59904
	v_mfma_f32_16x16x32_bf16 v[58:61], v[216:219], v[228:231], v[58:61]
	v_mfma_f32_16x16x32_bf16 v[62:65], v[216:219], v[236:239], v[62:65]
	v_mfma_f32_16x16x32_bf16 v[42:45], v[216:219], v[240:243], v[42:45]
	v_mfma_f32_16x16x32_bf16 v[46:49], v[216:219], v[252:255], v[46:49]
	s_waitcnt vmcnt(9)
	ds_write_b128 v165, v[172:175] offset:64512
	s_waitcnt vmcnt(8)
	ds_write_b128 v166, v[176:179] offset:32256
	v_mfma_f32_16x16x32_bf16 v[18:21], v[220:223], v[228:231], v[18:21]
	v_mfma_f32_16x16x32_bf16 v[22:25], v[220:223], v[236:239], v[22:25]
	v_mfma_f32_16x16x32_bf16 v[2:5], v[220:223], v[240:243], v[2:5]
	v_mfma_f32_16x16x32_bf16 v[6:9], v[220:223], v[252:255], v[6:9]
	s_waitcnt lgkmcnt(4)
	v_mfma_f32_16x16x32_bf16 v[26:29], v[224:227], v[228:231], v[26:29]
	v_mfma_f32_16x16x32_bf16 v[30:33], v[224:227], v[236:239], v[30:33]
	v_mfma_f32_16x16x32_bf16 v[10:13], v[224:227], v[240:243], v[10:13]
	v_mfma_f32_16x16x32_bf16 v[14:17], v[224:227], v[252:255], v[14:17]
	s_waitcnt lgkmcnt(0)
	s_barrier
	global_load_dwordx4 v[122:125], v[70:71], off offset:384
	global_load_dwordx4 v[126:129], v[68:69], off offset:384
	global_load_dwordx4 v[136:139], v[66:67], off offset:384
	global_load_dwordx4 v[140:143], v[72:73], off offset:384
	global_load_dwordx4 v[144:147], v[74:75], off offset:384
	global_load_dwordx4 v[148:151], v[76:77], off offset:384
	global_load_dwordx4 v[172:175], v[78:79], off offset:384
	global_load_dwordx4 v[176:179], v[80:81], off offset:384
	ds_read_b128 v[228:231], v245 offset:55296
	ds_read_b128 v[212:215], v244 offset:18432
	ds_read_b128 v[236:239], v245 offset:57600
	ds_read_b128 v[240:243], v245 offset:59904
	ds_read_b128 v[252:255], v245 offset:62208
	ds_read_b128 v[216:219], v244 offset:20736
	ds_read_b128 v[220:223], v244 offset:23040
	ds_read_b128 v[224:227], v244 offset:25344
	s_setprio 0
	s_waitcnt lgkmcnt(6)
	v_mfma_f32_16x16x32_bf16 v[50:53], v[212:215], v[228:231], v[50:53]
	s_waitcnt lgkmcnt(5)
	v_mfma_f32_16x16x32_bf16 v[54:57], v[212:215], v[236:239], v[54:57]
	s_waitcnt lgkmcnt(4)
	v_mfma_f32_16x16x32_bf16 v[34:37], v[212:215], v[240:243], v[34:37]
	s_waitcnt lgkmcnt(3)
	v_mfma_f32_16x16x32_bf16 v[38:41], v[212:215], v[252:255], v[38:41]
	ds_read_b128 v[212:215], v244 offset:18496
	s_waitcnt lgkmcnt(3)
	v_mfma_f32_16x16x32_bf16 v[58:61], v[216:219], v[228:231], v[58:61]
	v_mfma_f32_16x16x32_bf16 v[62:65], v[216:219], v[236:239], v[62:65]
	v_mfma_f32_16x16x32_bf16 v[42:45], v[216:219], v[240:243], v[42:45]
	v_mfma_f32_16x16x32_bf16 v[46:49], v[216:219], v[252:255], v[46:49]
	ds_read_b128 v[216:219], v244 offset:20800
	s_setprio 1
	s_waitcnt vmcnt(13)
	ds_write_b128 v165, v[188:191]
	ds_write_b128 v165, v[180:183] offset:4608
	s_waitcnt lgkmcnt(5)
	v_mfma_f32_16x16x32_bf16 v[18:21], v[220:223], v[228:231], v[18:21]
	v_mfma_f32_16x16x32_bf16 v[22:25], v[220:223], v[236:239], v[22:25]
	v_mfma_f32_16x16x32_bf16 v[2:5], v[220:223], v[240:243], v[2:5]
	v_mfma_f32_16x16x32_bf16 v[6:9], v[220:223], v[252:255], v[6:9]
	ds_read_b128 v[220:223], v244 offset:23104
	ds_write_b128 v165, v[184:187] offset:9216
	s_waitcnt vmcnt(12)
	ds_write_b128 v165, v[192:195] offset:13824
	s_waitcnt lgkmcnt(7)
	v_mfma_f32_16x16x32_bf16 v[26:29], v[224:227], v[228:231], v[26:29]
	ds_read_b128 v[228:231], v245 offset:55360
	v_mfma_f32_16x16x32_bf16 v[30:33], v[224:227], v[236:239], v[30:33]
	ds_read_b128 v[236:239], v245 offset:57664
	v_mfma_f32_16x16x32_bf16 v[10:13], v[224:227], v[240:243], v[10:13]
	ds_read_b128 v[240:243], v245 offset:59968
	v_mfma_f32_16x16x32_bf16 v[14:17], v[224:227], v[252:255], v[14:17]
	ds_read_b128 v[252:255], v245 offset:62272
	ds_read_b128 v[224:227], v244 offset:25408
	s_waitcnt lgkmcnt(4)
	v_mfma_f32_16x16x32_bf16 v[50:53], v[212:215], v[228:231], v[50:53]
	s_waitcnt lgkmcnt(3)
	v_mfma_f32_16x16x32_bf16 v[54:57], v[212:215], v[236:239], v[54:57]
	s_waitcnt lgkmcnt(2)
	v_mfma_f32_16x16x32_bf16 v[34:37], v[212:215], v[240:243], v[34:37]
	s_waitcnt lgkmcnt(1)
	v_mfma_f32_16x16x32_bf16 v[38:41], v[212:215], v[252:255], v[38:41]
	s_waitcnt vmcnt(11)
	ds_write_b128 v165, v[196:199] offset:36864
	s_waitcnt vmcnt(10)
	ds_write_b128 v165, v[200:203] offset:41472
	v_mfma_f32_16x16x32_bf16 v[58:61], v[216:219], v[228:231], v[58:61]
	v_mfma_f32_16x16x32_bf16 v[62:65], v[216:219], v[236:239], v[62:65]
	v_mfma_f32_16x16x32_bf16 v[42:45], v[216:219], v[240:243], v[42:45]
	v_mfma_f32_16x16x32_bf16 v[46:49], v[216:219], v[252:255], v[46:49]
	s_waitcnt vmcnt(9)
	ds_write_b128 v165, v[204:207] offset:46080
	s_waitcnt vmcnt(8)
	ds_write_b128 v165, v[208:211] offset:50688
	v_mfma_f32_16x16x32_bf16 v[18:21], v[220:223], v[228:231], v[18:21]
	v_mfma_f32_16x16x32_bf16 v[22:25], v[220:223], v[236:239], v[22:25]
	v_mfma_f32_16x16x32_bf16 v[2:5], v[220:223], v[240:243], v[2:5]
	v_mfma_f32_16x16x32_bf16 v[6:9], v[220:223], v[252:255], v[6:9]
	s_waitcnt lgkmcnt(4)
	v_mfma_f32_16x16x32_bf16 v[26:29], v[224:227], v[228:231], v[26:29]
	v_mfma_f32_16x16x32_bf16 v[30:33], v[224:227], v[236:239], v[30:33]
	v_mfma_f32_16x16x32_bf16 v[10:13], v[224:227], v[240:243], v[10:13]
	v_mfma_f32_16x16x32_bf16 v[14:17], v[224:227], v[252:255], v[14:17]
	s_waitcnt lgkmcnt(0)
	s_barrier
	global_load_dwordx4 v[180:183], v[70:71], off offset:512
	global_load_dwordx4 v[184:187], v[68:69], off offset:512
	global_load_dwordx4 v[188:191], v[66:67], off offset:512
	global_load_dwordx4 v[192:195], v[72:73], off offset:512
	global_load_dwordx4 v[196:199], v[74:75], off offset:512
	global_load_dwordx4 v[200:203], v[76:77], off offset:512
	global_load_dwordx4 v[204:207], v[78:79], off offset:512
	global_load_dwordx4 v[208:211], v[80:81], off offset:512
	ds_read_b128 v[228:231], v245 offset:36864
	ds_read_b128 v[212:215], v244
	ds_read_b128 v[236:239], v245 offset:39168
	ds_read_b128 v[240:243], v245 offset:41472
	ds_read_b128 v[252:255], v245 offset:43776
	ds_read_b128 v[216:219], v244 offset:2304
	ds_read_b128 v[220:223], v244 offset:4608
	ds_read_b128 v[224:227], v244 offset:6912
	s_setprio 0
	s_waitcnt lgkmcnt(6)
	v_mfma_f32_16x16x32_bf16 v[50:53], v[212:215], v[228:231], v[50:53]
	s_waitcnt lgkmcnt(5)
	v_mfma_f32_16x16x32_bf16 v[54:57], v[212:215], v[236:239], v[54:57]
	s_waitcnt lgkmcnt(4)
	v_mfma_f32_16x16x32_bf16 v[34:37], v[212:215], v[240:243], v[34:37]
	s_waitcnt lgkmcnt(3)
	v_mfma_f32_16x16x32_bf16 v[38:41], v[212:215], v[252:255], v[38:41]
	ds_read_b128 v[212:215], v244 offset:64
	s_waitcnt lgkmcnt(3)
	v_mfma_f32_16x16x32_bf16 v[58:61], v[216:219], v[228:231], v[58:61]
	v_mfma_f32_16x16x32_bf16 v[62:65], v[216:219], v[236:239], v[62:65]
	v_mfma_f32_16x16x32_bf16 v[42:45], v[216:219], v[240:243], v[42:45]
	v_mfma_f32_16x16x32_bf16 v[46:49], v[216:219], v[252:255], v[46:49]
	ds_read_b128 v[216:219], v244 offset:2368
	s_setprio 1
	s_waitcnt vmcnt(15)
	ds_write_b128 v165, v[122:125] offset:18432
	s_waitcnt vmcnt(14)
	ds_write_b128 v165, v[126:129] offset:23040
	s_waitcnt lgkmcnt(5)
	v_mfma_f32_16x16x32_bf16 v[18:21], v[220:223], v[228:231], v[18:21]
	v_mfma_f32_16x16x32_bf16 v[22:25], v[220:223], v[236:239], v[22:25]
	v_mfma_f32_16x16x32_bf16 v[2:5], v[220:223], v[240:243], v[2:5]
	v_mfma_f32_16x16x32_bf16 v[6:9], v[220:223], v[252:255], v[6:9]
	ds_read_b128 v[220:223], v244 offset:4672
	s_waitcnt vmcnt(13)
	ds_write_b128 v165, v[136:139] offset:27648
	s_waitcnt vmcnt(12)
	ds_write_b128 v165, v[140:143] offset:32256
	s_waitcnt lgkmcnt(7)
	v_mfma_f32_16x16x32_bf16 v[26:29], v[224:227], v[228:231], v[26:29]
	ds_read_b128 v[228:231], v245 offset:36928
	v_mfma_f32_16x16x32_bf16 v[30:33], v[224:227], v[236:239], v[30:33]
	ds_read_b128 v[236:239], v245 offset:39232
	v_mfma_f32_16x16x32_bf16 v[10:13], v[224:227], v[240:243], v[10:13]
	ds_read_b128 v[240:243], v245 offset:41536
	v_mfma_f32_16x16x32_bf16 v[14:17], v[224:227], v[252:255], v[14:17]
	ds_read_b128 v[252:255], v245 offset:43840
	ds_read_b128 v[224:227], v244 offset:6976
	s_waitcnt lgkmcnt(4)
	v_mfma_f32_16x16x32_bf16 v[50:53], v[212:215], v[228:231], v[50:53]
	s_waitcnt lgkmcnt(3)
	v_mfma_f32_16x16x32_bf16 v[54:57], v[212:215], v[236:239], v[54:57]
	s_waitcnt lgkmcnt(2)
	v_mfma_f32_16x16x32_bf16 v[34:37], v[212:215], v[240:243], v[34:37]
	s_waitcnt lgkmcnt(1)
	v_mfma_f32_16x16x32_bf16 v[38:41], v[212:215], v[252:255], v[38:41]
	s_waitcnt vmcnt(11)
	ds_write_b128 v165, v[144:147] offset:55296
	s_waitcnt vmcnt(10)
	ds_write_b128 v165, v[148:151] offset:59904
	v_mfma_f32_16x16x32_bf16 v[58:61], v[216:219], v[228:231], v[58:61]
	v_mfma_f32_16x16x32_bf16 v[62:65], v[216:219], v[236:239], v[62:65]
	v_mfma_f32_16x16x32_bf16 v[42:45], v[216:219], v[240:243], v[42:45]
	v_mfma_f32_16x16x32_bf16 v[46:49], v[216:219], v[252:255], v[46:49]
	s_waitcnt vmcnt(9)
	ds_write_b128 v165, v[172:175] offset:64512
	s_waitcnt vmcnt(8)
	ds_write_b128 v166, v[176:179] offset:32256
	v_mfma_f32_16x16x32_bf16 v[18:21], v[220:223], v[228:231], v[18:21]
	v_mfma_f32_16x16x32_bf16 v[22:25], v[220:223], v[236:239], v[22:25]
	v_mfma_f32_16x16x32_bf16 v[2:5], v[220:223], v[240:243], v[2:5]
	v_mfma_f32_16x16x32_bf16 v[6:9], v[220:223], v[252:255], v[6:9]
	s_waitcnt lgkmcnt(4)
	v_mfma_f32_16x16x32_bf16 v[26:29], v[224:227], v[228:231], v[26:29]
	v_mfma_f32_16x16x32_bf16 v[30:33], v[224:227], v[236:239], v[30:33]
	v_mfma_f32_16x16x32_bf16 v[10:13], v[224:227], v[240:243], v[10:13]
	v_mfma_f32_16x16x32_bf16 v[14:17], v[224:227], v[252:255], v[14:17]
	s_waitcnt lgkmcnt(0)
	s_barrier
	global_load_dwordx4 v[122:125], v[70:71], off offset:640
	global_load_dwordx4 v[126:129], v[68:69], off offset:640
	global_load_dwordx4 v[136:139], v[66:67], off offset:640
	global_load_dwordx4 v[140:143], v[72:73], off offset:640
	global_load_dwordx4 v[144:147], v[74:75], off offset:640
	global_load_dwordx4 v[148:151], v[76:77], off offset:640
	global_load_dwordx4 v[172:175], v[78:79], off offset:640
	global_load_dwordx4 v[176:179], v[80:81], off offset:640
	ds_read_b128 v[228:231], v245 offset:55296
	ds_read_b128 v[212:215], v244 offset:18432
	ds_read_b128 v[236:239], v245 offset:57600
	ds_read_b128 v[240:243], v245 offset:59904
	ds_read_b128 v[252:255], v245 offset:62208
	ds_read_b128 v[216:219], v244 offset:20736
	ds_read_b128 v[220:223], v244 offset:23040
	ds_read_b128 v[224:227], v244 offset:25344
	s_setprio 0
	s_waitcnt lgkmcnt(6)
	v_mfma_f32_16x16x32_bf16 v[50:53], v[212:215], v[228:231], v[50:53]
	s_waitcnt lgkmcnt(5)
	v_mfma_f32_16x16x32_bf16 v[54:57], v[212:215], v[236:239], v[54:57]
	s_waitcnt lgkmcnt(4)
	v_mfma_f32_16x16x32_bf16 v[34:37], v[212:215], v[240:243], v[34:37]
	s_waitcnt lgkmcnt(3)
	v_mfma_f32_16x16x32_bf16 v[38:41], v[212:215], v[252:255], v[38:41]
	ds_read_b128 v[212:215], v244 offset:18496
	s_waitcnt lgkmcnt(3)
	v_mfma_f32_16x16x32_bf16 v[58:61], v[216:219], v[228:231], v[58:61]
	v_mfma_f32_16x16x32_bf16 v[62:65], v[216:219], v[236:239], v[62:65]
	v_mfma_f32_16x16x32_bf16 v[42:45], v[216:219], v[240:243], v[42:45]
	v_mfma_f32_16x16x32_bf16 v[46:49], v[216:219], v[252:255], v[46:49]
	ds_read_b128 v[216:219], v244 offset:20800
	s_setprio 1
	s_waitcnt vmcnt(15)
	ds_write_b128 v165, v[180:183]
	s_waitcnt vmcnt(14)
	ds_write_b128 v165, v[184:187] offset:4608
	s_waitcnt lgkmcnt(5)
	v_mfma_f32_16x16x32_bf16 v[18:21], v[220:223], v[228:231], v[18:21]
	v_mfma_f32_16x16x32_bf16 v[22:25], v[220:223], v[236:239], v[22:25]
	v_mfma_f32_16x16x32_bf16 v[2:5], v[220:223], v[240:243], v[2:5]
	v_mfma_f32_16x16x32_bf16 v[6:9], v[220:223], v[252:255], v[6:9]
	ds_read_b128 v[220:223], v244 offset:23104
	s_waitcnt vmcnt(13)
	ds_write_b128 v165, v[188:191] offset:9216
	s_waitcnt vmcnt(12)
	ds_write_b128 v165, v[192:195] offset:13824
	s_waitcnt lgkmcnt(7)
	v_mfma_f32_16x16x32_bf16 v[26:29], v[224:227], v[228:231], v[26:29]
	ds_read_b128 v[228:231], v245 offset:55360
	v_mfma_f32_16x16x32_bf16 v[30:33], v[224:227], v[236:239], v[30:33]
	ds_read_b128 v[236:239], v245 offset:57664
	v_mfma_f32_16x16x32_bf16 v[10:13], v[224:227], v[240:243], v[10:13]
	ds_read_b128 v[240:243], v245 offset:59968
	v_mfma_f32_16x16x32_bf16 v[14:17], v[224:227], v[252:255], v[14:17]
	ds_read_b128 v[252:255], v245 offset:62272
	ds_read_b128 v[224:227], v244 offset:25408
	s_waitcnt lgkmcnt(4)
	v_mfma_f32_16x16x32_bf16 v[50:53], v[212:215], v[228:231], v[50:53]
	s_waitcnt lgkmcnt(3)
	v_mfma_f32_16x16x32_bf16 v[54:57], v[212:215], v[236:239], v[54:57]
	s_waitcnt lgkmcnt(2)
	v_mfma_f32_16x16x32_bf16 v[34:37], v[212:215], v[240:243], v[34:37]
	s_waitcnt lgkmcnt(1)
	v_mfma_f32_16x16x32_bf16 v[38:41], v[212:215], v[252:255], v[38:41]
	s_waitcnt vmcnt(11)
	ds_write_b128 v165, v[196:199] offset:36864
	s_waitcnt vmcnt(10)
	ds_write_b128 v165, v[200:203] offset:41472
	v_mfma_f32_16x16x32_bf16 v[58:61], v[216:219], v[228:231], v[58:61]
	v_mfma_f32_16x16x32_bf16 v[62:65], v[216:219], v[236:239], v[62:65]
	v_mfma_f32_16x16x32_bf16 v[42:45], v[216:219], v[240:243], v[42:45]
	v_mfma_f32_16x16x32_bf16 v[46:49], v[216:219], v[252:255], v[46:49]
	s_waitcnt vmcnt(9)
	ds_write_b128 v165, v[204:207] offset:46080
	s_waitcnt vmcnt(8)
	ds_write_b128 v165, v[208:211] offset:50688
	v_mfma_f32_16x16x32_bf16 v[18:21], v[220:223], v[228:231], v[18:21]
	v_mfma_f32_16x16x32_bf16 v[22:25], v[220:223], v[236:239], v[22:25]
	v_mfma_f32_16x16x32_bf16 v[2:5], v[220:223], v[240:243], v[2:5]
	v_mfma_f32_16x16x32_bf16 v[6:9], v[220:223], v[252:255], v[6:9]
	s_waitcnt lgkmcnt(4)
	v_mfma_f32_16x16x32_bf16 v[26:29], v[224:227], v[228:231], v[26:29]
	v_mfma_f32_16x16x32_bf16 v[30:33], v[224:227], v[236:239], v[30:33]
	v_mfma_f32_16x16x32_bf16 v[10:13], v[224:227], v[240:243], v[10:13]
	v_mfma_f32_16x16x32_bf16 v[14:17], v[224:227], v[252:255], v[14:17]
	s_waitcnt lgkmcnt(0)
	s_barrier
	global_load_dwordx4 v[180:183], v[70:71], off offset:768
	global_load_dwordx4 v[184:187], v[68:69], off offset:768
	global_load_dwordx4 v[188:191], v[66:67], off offset:768
	global_load_dwordx4 v[192:195], v[72:73], off offset:768
	global_load_dwordx4 v[196:199], v[74:75], off offset:768
	global_load_dwordx4 v[200:203], v[76:77], off offset:768
	global_load_dwordx4 v[204:207], v[78:79], off offset:768
	global_load_dwordx4 v[208:211], v[80:81], off offset:768
	ds_read_b128 v[228:231], v245 offset:36864
	ds_read_b128 v[212:215], v244
	ds_read_b128 v[236:239], v245 offset:39168
	ds_read_b128 v[240:243], v245 offset:41472
	ds_read_b128 v[252:255], v245 offset:43776
	ds_read_b128 v[216:219], v244 offset:2304
	ds_read_b128 v[220:223], v244 offset:4608
	ds_read_b128 v[224:227], v244 offset:6912
	s_setprio 0
	s_waitcnt lgkmcnt(6)
	v_mfma_f32_16x16x32_bf16 v[50:53], v[212:215], v[228:231], v[50:53]
	s_waitcnt lgkmcnt(5)
	v_mfma_f32_16x16x32_bf16 v[54:57], v[212:215], v[236:239], v[54:57]
	s_waitcnt lgkmcnt(4)
	v_mfma_f32_16x16x32_bf16 v[34:37], v[212:215], v[240:243], v[34:37]
	s_waitcnt lgkmcnt(3)
	v_mfma_f32_16x16x32_bf16 v[38:41], v[212:215], v[252:255], v[38:41]
	ds_read_b128 v[212:215], v244 offset:64
	s_waitcnt lgkmcnt(3)
	v_mfma_f32_16x16x32_bf16 v[58:61], v[216:219], v[228:231], v[58:61]
	v_mfma_f32_16x16x32_bf16 v[62:65], v[216:219], v[236:239], v[62:65]
	v_mfma_f32_16x16x32_bf16 v[42:45], v[216:219], v[240:243], v[42:45]
	v_mfma_f32_16x16x32_bf16 v[46:49], v[216:219], v[252:255], v[46:49]
	ds_read_b128 v[216:219], v244 offset:2368
	s_setprio 1
	s_waitcnt vmcnt(15)
	ds_write_b128 v165, v[122:125] offset:18432
	s_waitcnt vmcnt(14)
	ds_write_b128 v165, v[126:129] offset:23040
	s_waitcnt lgkmcnt(5)
	v_mfma_f32_16x16x32_bf16 v[18:21], v[220:223], v[228:231], v[18:21]
	v_mfma_f32_16x16x32_bf16 v[22:25], v[220:223], v[236:239], v[22:25]
	v_mfma_f32_16x16x32_bf16 v[2:5], v[220:223], v[240:243], v[2:5]
	v_mfma_f32_16x16x32_bf16 v[6:9], v[220:223], v[252:255], v[6:9]
	ds_read_b128 v[220:223], v244 offset:4672
	s_waitcnt vmcnt(13)
	ds_write_b128 v165, v[136:139] offset:27648
	s_waitcnt vmcnt(12)
	ds_write_b128 v165, v[140:143] offset:32256
	s_waitcnt lgkmcnt(7)
	v_mfma_f32_16x16x32_bf16 v[26:29], v[224:227], v[228:231], v[26:29]
	ds_read_b128 v[228:231], v245 offset:36928
	v_mfma_f32_16x16x32_bf16 v[30:33], v[224:227], v[236:239], v[30:33]
	ds_read_b128 v[236:239], v245 offset:39232
	v_mfma_f32_16x16x32_bf16 v[10:13], v[224:227], v[240:243], v[10:13]
	ds_read_b128 v[240:243], v245 offset:41536
	v_mfma_f32_16x16x32_bf16 v[14:17], v[224:227], v[252:255], v[14:17]
	ds_read_b128 v[252:255], v245 offset:43840
	ds_read_b128 v[224:227], v244 offset:6976
	s_waitcnt lgkmcnt(4)
	v_mfma_f32_16x16x32_bf16 v[50:53], v[212:215], v[228:231], v[50:53]
	s_waitcnt lgkmcnt(3)
	v_mfma_f32_16x16x32_bf16 v[54:57], v[212:215], v[236:239], v[54:57]
	s_waitcnt lgkmcnt(2)
	v_mfma_f32_16x16x32_bf16 v[34:37], v[212:215], v[240:243], v[34:37]
	s_waitcnt lgkmcnt(1)
	v_mfma_f32_16x16x32_bf16 v[38:41], v[212:215], v[252:255], v[38:41]
	s_waitcnt vmcnt(11)
	ds_write_b128 v165, v[144:147] offset:55296
	s_waitcnt vmcnt(10)
	ds_write_b128 v165, v[148:151] offset:59904
	v_mfma_f32_16x16x32_bf16 v[58:61], v[216:219], v[228:231], v[58:61]
	v_mfma_f32_16x16x32_bf16 v[62:65], v[216:219], v[236:239], v[62:65]
	v_mfma_f32_16x16x32_bf16 v[42:45], v[216:219], v[240:243], v[42:45]
	v_mfma_f32_16x16x32_bf16 v[46:49], v[216:219], v[252:255], v[46:49]
	s_waitcnt vmcnt(9)
	ds_write_b128 v165, v[172:175] offset:64512
	s_waitcnt vmcnt(8)
	ds_write_b128 v166, v[176:179] offset:32256
	v_mfma_f32_16x16x32_bf16 v[18:21], v[220:223], v[228:231], v[18:21]
	v_mfma_f32_16x16x32_bf16 v[22:25], v[220:223], v[236:239], v[22:25]
	v_mfma_f32_16x16x32_bf16 v[2:5], v[220:223], v[240:243], v[2:5]
	v_mfma_f32_16x16x32_bf16 v[6:9], v[220:223], v[252:255], v[6:9]
	s_waitcnt lgkmcnt(4)
	v_mfma_f32_16x16x32_bf16 v[26:29], v[224:227], v[228:231], v[26:29]
	v_mfma_f32_16x16x32_bf16 v[30:33], v[224:227], v[236:239], v[30:33]
	v_mfma_f32_16x16x32_bf16 v[10:13], v[224:227], v[240:243], v[10:13]
	v_mfma_f32_16x16x32_bf16 v[14:17], v[224:227], v[252:255], v[14:17]
	s_waitcnt lgkmcnt(0)
	s_barrier
	global_load_dwordx4 v[122:125], v[70:71], off offset:896
	global_load_dwordx4 v[126:129], v[68:69], off offset:896
	global_load_dwordx4 v[136:139], v[66:67], off offset:896
	global_load_dwordx4 v[140:143], v[72:73], off offset:896
	global_load_dwordx4 v[144:147], v[74:75], off offset:896
	global_load_dwordx4 v[148:151], v[76:77], off offset:896
	global_load_dwordx4 v[172:175], v[78:79], off offset:896
	global_load_dwordx4 v[176:179], v[80:81], off offset:896
	ds_read_b128 v[228:231], v245 offset:55296
	ds_read_b128 v[212:215], v244 offset:18432
	ds_read_b128 v[236:239], v245 offset:57600
	ds_read_b128 v[240:243], v245 offset:59904
	ds_read_b128 v[252:255], v245 offset:62208
	ds_read_b128 v[216:219], v244 offset:20736
	ds_read_b128 v[220:223], v244 offset:23040
	ds_read_b128 v[224:227], v244 offset:25344
	s_setprio 0
	s_waitcnt lgkmcnt(6)
	v_mfma_f32_16x16x32_bf16 v[50:53], v[212:215], v[228:231], v[50:53]
	s_waitcnt lgkmcnt(5)
	v_mfma_f32_16x16x32_bf16 v[54:57], v[212:215], v[236:239], v[54:57]
	s_waitcnt lgkmcnt(4)
	v_mfma_f32_16x16x32_bf16 v[34:37], v[212:215], v[240:243], v[34:37]
	s_waitcnt lgkmcnt(3)
	v_mfma_f32_16x16x32_bf16 v[38:41], v[212:215], v[252:255], v[38:41]
	ds_read_b128 v[212:215], v244 offset:18496
	s_waitcnt lgkmcnt(3)
	v_mfma_f32_16x16x32_bf16 v[58:61], v[216:219], v[228:231], v[58:61]
	v_mfma_f32_16x16x32_bf16 v[62:65], v[216:219], v[236:239], v[62:65]
	v_mfma_f32_16x16x32_bf16 v[42:45], v[216:219], v[240:243], v[42:45]
	v_mfma_f32_16x16x32_bf16 v[46:49], v[216:219], v[252:255], v[46:49]
	ds_read_b128 v[216:219], v244 offset:20800
	s_setprio 1
	s_waitcnt vmcnt(15)
	ds_write_b128 v165, v[180:183]
	s_waitcnt vmcnt(14)
	ds_write_b128 v165, v[184:187] offset:4608
	s_waitcnt lgkmcnt(5)
	v_mfma_f32_16x16x32_bf16 v[18:21], v[220:223], v[228:231], v[18:21]
	v_mfma_f32_16x16x32_bf16 v[22:25], v[220:223], v[236:239], v[22:25]
	v_mfma_f32_16x16x32_bf16 v[2:5], v[220:223], v[240:243], v[2:5]
	v_mfma_f32_16x16x32_bf16 v[6:9], v[220:223], v[252:255], v[6:9]
	ds_read_b128 v[220:223], v244 offset:23104
	s_waitcnt vmcnt(13)
	ds_write_b128 v165, v[188:191] offset:9216
	s_waitcnt vmcnt(12)
	ds_write_b128 v165, v[192:195] offset:13824
	s_waitcnt lgkmcnt(7)
	v_mfma_f32_16x16x32_bf16 v[26:29], v[224:227], v[228:231], v[26:29]
	ds_read_b128 v[228:231], v245 offset:55360
	v_mfma_f32_16x16x32_bf16 v[30:33], v[224:227], v[236:239], v[30:33]
	ds_read_b128 v[236:239], v245 offset:57664
	v_mfma_f32_16x16x32_bf16 v[10:13], v[224:227], v[240:243], v[10:13]
	ds_read_b128 v[240:243], v245 offset:59968
	v_mfma_f32_16x16x32_bf16 v[14:17], v[224:227], v[252:255], v[14:17]
	ds_read_b128 v[252:255], v245 offset:62272
	ds_read_b128 v[224:227], v244 offset:25408
	s_waitcnt lgkmcnt(4)
	v_mfma_f32_16x16x32_bf16 v[50:53], v[212:215], v[228:231], v[50:53]
	s_waitcnt lgkmcnt(3)
	v_mfma_f32_16x16x32_bf16 v[54:57], v[212:215], v[236:239], v[54:57]
	s_waitcnt lgkmcnt(2)
	v_mfma_f32_16x16x32_bf16 v[34:37], v[212:215], v[240:243], v[34:37]
	s_waitcnt lgkmcnt(1)
	v_mfma_f32_16x16x32_bf16 v[38:41], v[212:215], v[252:255], v[38:41]
	s_waitcnt vmcnt(11)
	ds_write_b128 v165, v[196:199] offset:36864
	s_waitcnt vmcnt(10)
	ds_write_b128 v165, v[200:203] offset:41472
	v_mfma_f32_16x16x32_bf16 v[58:61], v[216:219], v[228:231], v[58:61]
	v_mfma_f32_16x16x32_bf16 v[62:65], v[216:219], v[236:239], v[62:65]
	v_mfma_f32_16x16x32_bf16 v[42:45], v[216:219], v[240:243], v[42:45]
	v_mfma_f32_16x16x32_bf16 v[46:49], v[216:219], v[252:255], v[46:49]
	s_waitcnt vmcnt(9)
	ds_write_b128 v165, v[204:207] offset:46080
	s_waitcnt vmcnt(8)
	ds_write_b128 v165, v[208:211] offset:50688
	v_mfma_f32_16x16x32_bf16 v[18:21], v[220:223], v[228:231], v[18:21]
	v_mfma_f32_16x16x32_bf16 v[22:25], v[220:223], v[236:239], v[22:25]
	v_mfma_f32_16x16x32_bf16 v[2:5], v[220:223], v[240:243], v[2:5]
	v_mfma_f32_16x16x32_bf16 v[6:9], v[220:223], v[252:255], v[6:9]
	s_waitcnt lgkmcnt(4)
	v_mfma_f32_16x16x32_bf16 v[26:29], v[224:227], v[228:231], v[26:29]
	v_mfma_f32_16x16x32_bf16 v[30:33], v[224:227], v[236:239], v[30:33]
	v_mfma_f32_16x16x32_bf16 v[10:13], v[224:227], v[240:243], v[10:13]
	v_mfma_f32_16x16x32_bf16 v[14:17], v[224:227], v[252:255], v[14:17]
	s_waitcnt lgkmcnt(0)
	s_barrier
	global_load_dwordx4 v[180:183], v[70:71], off offset:1024
	global_load_dwordx4 v[184:187], v[68:69], off offset:1024
	global_load_dwordx4 v[188:191], v[66:67], off offset:1024
	global_load_dwordx4 v[192:195], v[72:73], off offset:1024
	global_load_dwordx4 v[196:199], v[74:75], off offset:1024
	global_load_dwordx4 v[200:203], v[76:77], off offset:1024
	global_load_dwordx4 v[204:207], v[78:79], off offset:1024
	global_load_dwordx4 v[208:211], v[80:81], off offset:1024
	ds_read_b128 v[228:231], v245 offset:36864
	ds_read_b128 v[212:215], v244
	ds_read_b128 v[236:239], v245 offset:39168
	ds_read_b128 v[240:243], v245 offset:41472
	ds_read_b128 v[252:255], v245 offset:43776
	ds_read_b128 v[216:219], v244 offset:2304
	ds_read_b128 v[220:223], v244 offset:4608
	ds_read_b128 v[224:227], v244 offset:6912
	s_setprio 0
	s_waitcnt lgkmcnt(6)
	v_mfma_f32_16x16x32_bf16 v[50:53], v[212:215], v[228:231], v[50:53]
	s_waitcnt lgkmcnt(5)
	v_mfma_f32_16x16x32_bf16 v[54:57], v[212:215], v[236:239], v[54:57]
	s_waitcnt lgkmcnt(4)
	v_mfma_f32_16x16x32_bf16 v[34:37], v[212:215], v[240:243], v[34:37]
	s_waitcnt lgkmcnt(3)
	v_mfma_f32_16x16x32_bf16 v[38:41], v[212:215], v[252:255], v[38:41]
	ds_read_b128 v[212:215], v244 offset:64
	s_waitcnt lgkmcnt(3)
	v_mfma_f32_16x16x32_bf16 v[58:61], v[216:219], v[228:231], v[58:61]
	v_mfma_f32_16x16x32_bf16 v[62:65], v[216:219], v[236:239], v[62:65]
	v_mfma_f32_16x16x32_bf16 v[42:45], v[216:219], v[240:243], v[42:45]
	v_mfma_f32_16x16x32_bf16 v[46:49], v[216:219], v[252:255], v[46:49]
	ds_read_b128 v[216:219], v244 offset:2368
	s_setprio 1
	s_waitcnt vmcnt(15)
	ds_write_b128 v165, v[122:125] offset:18432
	s_waitcnt vmcnt(14)
	ds_write_b128 v165, v[126:129] offset:23040
	s_waitcnt lgkmcnt(5)
	v_mfma_f32_16x16x32_bf16 v[18:21], v[220:223], v[228:231], v[18:21]
	v_mfma_f32_16x16x32_bf16 v[22:25], v[220:223], v[236:239], v[22:25]
	v_mfma_f32_16x16x32_bf16 v[2:5], v[220:223], v[240:243], v[2:5]
	v_mfma_f32_16x16x32_bf16 v[6:9], v[220:223], v[252:255], v[6:9]
	ds_read_b128 v[220:223], v244 offset:4672
	s_waitcnt vmcnt(13)
	ds_write_b128 v165, v[136:139] offset:27648
	s_waitcnt vmcnt(12)
	ds_write_b128 v165, v[140:143] offset:32256
	s_waitcnt lgkmcnt(7)
	v_mfma_f32_16x16x32_bf16 v[26:29], v[224:227], v[228:231], v[26:29]
	ds_read_b128 v[228:231], v245 offset:36928
	v_mfma_f32_16x16x32_bf16 v[30:33], v[224:227], v[236:239], v[30:33]
	ds_read_b128 v[236:239], v245 offset:39232
	v_mfma_f32_16x16x32_bf16 v[10:13], v[224:227], v[240:243], v[10:13]
	ds_read_b128 v[240:243], v245 offset:41536
	v_mfma_f32_16x16x32_bf16 v[14:17], v[224:227], v[252:255], v[14:17]
	ds_read_b128 v[252:255], v245 offset:43840
	ds_read_b128 v[224:227], v244 offset:6976
	s_waitcnt lgkmcnt(4)
	v_mfma_f32_16x16x32_bf16 v[50:53], v[212:215], v[228:231], v[50:53]
	s_waitcnt lgkmcnt(3)
	v_mfma_f32_16x16x32_bf16 v[54:57], v[212:215], v[236:239], v[54:57]
	s_waitcnt lgkmcnt(2)
	v_mfma_f32_16x16x32_bf16 v[34:37], v[212:215], v[240:243], v[34:37]
	s_waitcnt lgkmcnt(1)
	v_mfma_f32_16x16x32_bf16 v[38:41], v[212:215], v[252:255], v[38:41]
	s_waitcnt vmcnt(11)
	ds_write_b128 v165, v[144:147] offset:55296
	s_waitcnt vmcnt(10)
	ds_write_b128 v165, v[148:151] offset:59904
	v_mfma_f32_16x16x32_bf16 v[58:61], v[216:219], v[228:231], v[58:61]
	v_mfma_f32_16x16x32_bf16 v[62:65], v[216:219], v[236:239], v[62:65]
	v_mfma_f32_16x16x32_bf16 v[42:45], v[216:219], v[240:243], v[42:45]
	v_mfma_f32_16x16x32_bf16 v[46:49], v[216:219], v[252:255], v[46:49]
	s_waitcnt vmcnt(9)
	ds_write_b128 v165, v[172:175] offset:64512
	s_waitcnt vmcnt(8)
	ds_write_b128 v166, v[176:179] offset:32256
	v_mfma_f32_16x16x32_bf16 v[18:21], v[220:223], v[228:231], v[18:21]
	v_mfma_f32_16x16x32_bf16 v[22:25], v[220:223], v[236:239], v[22:25]
	v_mfma_f32_16x16x32_bf16 v[2:5], v[220:223], v[240:243], v[2:5]
	v_mfma_f32_16x16x32_bf16 v[6:9], v[220:223], v[252:255], v[6:9]
	s_waitcnt lgkmcnt(4)
	v_mfma_f32_16x16x32_bf16 v[26:29], v[224:227], v[228:231], v[26:29]
	v_mfma_f32_16x16x32_bf16 v[30:33], v[224:227], v[236:239], v[30:33]
	v_mfma_f32_16x16x32_bf16 v[10:13], v[224:227], v[240:243], v[10:13]
	v_mfma_f32_16x16x32_bf16 v[14:17], v[224:227], v[252:255], v[14:17]
	s_waitcnt lgkmcnt(0)
	s_barrier
	global_load_dwordx4 v[122:125], v[70:71], off offset:1152
	global_load_dwordx4 v[126:129], v[68:69], off offset:1152
	global_load_dwordx4 v[136:139], v[66:67], off offset:1152
	global_load_dwordx4 v[140:143], v[72:73], off offset:1152
	global_load_dwordx4 v[144:147], v[74:75], off offset:1152
	global_load_dwordx4 v[148:151], v[76:77], off offset:1152
	global_load_dwordx4 v[172:175], v[78:79], off offset:1152
	global_load_dwordx4 v[176:179], v[80:81], off offset:1152
	ds_read_b128 v[228:231], v245 offset:55296
	ds_read_b128 v[212:215], v244 offset:18432
	ds_read_b128 v[236:239], v245 offset:57600
	ds_read_b128 v[240:243], v245 offset:59904
	ds_read_b128 v[252:255], v245 offset:62208
	ds_read_b128 v[216:219], v244 offset:20736
	ds_read_b128 v[220:223], v244 offset:23040
	ds_read_b128 v[224:227], v244 offset:25344
	s_setprio 0
	s_waitcnt lgkmcnt(6)
	v_mfma_f32_16x16x32_bf16 v[50:53], v[212:215], v[228:231], v[50:53]
	s_waitcnt lgkmcnt(5)
	v_mfma_f32_16x16x32_bf16 v[54:57], v[212:215], v[236:239], v[54:57]
	s_waitcnt lgkmcnt(4)
	v_mfma_f32_16x16x32_bf16 v[34:37], v[212:215], v[240:243], v[34:37]
	s_waitcnt lgkmcnt(3)
	v_mfma_f32_16x16x32_bf16 v[38:41], v[212:215], v[252:255], v[38:41]
	ds_read_b128 v[212:215], v244 offset:18496
	s_waitcnt lgkmcnt(3)
	v_mfma_f32_16x16x32_bf16 v[58:61], v[216:219], v[228:231], v[58:61]
	v_mfma_f32_16x16x32_bf16 v[62:65], v[216:219], v[236:239], v[62:65]
	v_mfma_f32_16x16x32_bf16 v[42:45], v[216:219], v[240:243], v[42:45]
	v_mfma_f32_16x16x32_bf16 v[46:49], v[216:219], v[252:255], v[46:49]
	ds_read_b128 v[216:219], v244 offset:20800
	s_setprio 1
	s_waitcnt vmcnt(15)
	ds_write_b128 v165, v[180:183]
	s_waitcnt vmcnt(14)
	ds_write_b128 v165, v[184:187] offset:4608
	s_waitcnt lgkmcnt(5)
	v_mfma_f32_16x16x32_bf16 v[18:21], v[220:223], v[228:231], v[18:21]
	v_mfma_f32_16x16x32_bf16 v[22:25], v[220:223], v[236:239], v[22:25]
	v_mfma_f32_16x16x32_bf16 v[2:5], v[220:223], v[240:243], v[2:5]
	v_mfma_f32_16x16x32_bf16 v[6:9], v[220:223], v[252:255], v[6:9]
	ds_read_b128 v[220:223], v244 offset:23104
	s_waitcnt vmcnt(13)
	ds_write_b128 v165, v[188:191] offset:9216
	s_waitcnt vmcnt(12)
	ds_write_b128 v165, v[192:195] offset:13824
	s_waitcnt lgkmcnt(7)
	v_mfma_f32_16x16x32_bf16 v[26:29], v[224:227], v[228:231], v[26:29]
	ds_read_b128 v[228:231], v245 offset:55360
	v_mfma_f32_16x16x32_bf16 v[30:33], v[224:227], v[236:239], v[30:33]
	ds_read_b128 v[236:239], v245 offset:57664
	v_mfma_f32_16x16x32_bf16 v[10:13], v[224:227], v[240:243], v[10:13]
	ds_read_b128 v[240:243], v245 offset:59968
	v_mfma_f32_16x16x32_bf16 v[14:17], v[224:227], v[252:255], v[14:17]
	ds_read_b128 v[252:255], v245 offset:62272
	ds_read_b128 v[224:227], v244 offset:25408
	s_waitcnt lgkmcnt(4)
	v_mfma_f32_16x16x32_bf16 v[50:53], v[212:215], v[228:231], v[50:53]
	s_waitcnt lgkmcnt(3)
	v_mfma_f32_16x16x32_bf16 v[54:57], v[212:215], v[236:239], v[54:57]
	s_waitcnt lgkmcnt(2)
	v_mfma_f32_16x16x32_bf16 v[34:37], v[212:215], v[240:243], v[34:37]
	s_waitcnt lgkmcnt(1)
	v_mfma_f32_16x16x32_bf16 v[38:41], v[212:215], v[252:255], v[38:41]
	s_waitcnt vmcnt(11)
	ds_write_b128 v165, v[196:199] offset:36864
	s_waitcnt vmcnt(10)
	ds_write_b128 v165, v[200:203] offset:41472
	v_mfma_f32_16x16x32_bf16 v[58:61], v[216:219], v[228:231], v[58:61]
	v_mfma_f32_16x16x32_bf16 v[62:65], v[216:219], v[236:239], v[62:65]
	v_mfma_f32_16x16x32_bf16 v[42:45], v[216:219], v[240:243], v[42:45]
	v_mfma_f32_16x16x32_bf16 v[46:49], v[216:219], v[252:255], v[46:49]
	s_waitcnt vmcnt(9)
	ds_write_b128 v165, v[204:207] offset:46080
	s_waitcnt vmcnt(8)
	ds_write_b128 v165, v[208:211] offset:50688
	v_mfma_f32_16x16x32_bf16 v[18:21], v[220:223], v[228:231], v[18:21]
	v_mfma_f32_16x16x32_bf16 v[22:25], v[220:223], v[236:239], v[22:25]
	v_mfma_f32_16x16x32_bf16 v[2:5], v[220:223], v[240:243], v[2:5]
	v_mfma_f32_16x16x32_bf16 v[6:9], v[220:223], v[252:255], v[6:9]
	s_waitcnt lgkmcnt(4)
	v_mfma_f32_16x16x32_bf16 v[26:29], v[224:227], v[228:231], v[26:29]
	v_mfma_f32_16x16x32_bf16 v[30:33], v[224:227], v[236:239], v[30:33]
	v_mfma_f32_16x16x32_bf16 v[10:13], v[224:227], v[240:243], v[10:13]
	v_mfma_f32_16x16x32_bf16 v[14:17], v[224:227], v[252:255], v[14:17]
	s_waitcnt lgkmcnt(0)
	s_barrier
	global_load_dwordx4 v[180:183], v[70:71], off offset:1280
	global_load_dwordx4 v[184:187], v[68:69], off offset:1280
	global_load_dwordx4 v[188:191], v[66:67], off offset:1280
	global_load_dwordx4 v[192:195], v[72:73], off offset:1280
	global_load_dwordx4 v[196:199], v[74:75], off offset:1280
	global_load_dwordx4 v[200:203], v[76:77], off offset:1280
	global_load_dwordx4 v[204:207], v[78:79], off offset:1280
	global_load_dwordx4 v[208:211], v[80:81], off offset:1280
	ds_read_b128 v[228:231], v245 offset:36864
	ds_read_b128 v[212:215], v244
	ds_read_b128 v[236:239], v245 offset:39168
	ds_read_b128 v[240:243], v245 offset:41472
	ds_read_b128 v[252:255], v245 offset:43776
	ds_read_b128 v[216:219], v244 offset:2304
	ds_read_b128 v[220:223], v244 offset:4608
	ds_read_b128 v[224:227], v244 offset:6912
	s_setprio 0
	s_waitcnt lgkmcnt(6)
	v_mfma_f32_16x16x32_bf16 v[50:53], v[212:215], v[228:231], v[50:53]
	s_waitcnt lgkmcnt(5)
	v_mfma_f32_16x16x32_bf16 v[54:57], v[212:215], v[236:239], v[54:57]
	s_waitcnt lgkmcnt(4)
	v_mfma_f32_16x16x32_bf16 v[34:37], v[212:215], v[240:243], v[34:37]
	s_waitcnt lgkmcnt(3)
	v_mfma_f32_16x16x32_bf16 v[38:41], v[212:215], v[252:255], v[38:41]
	ds_read_b128 v[212:215], v244 offset:64
	s_waitcnt lgkmcnt(3)
	v_mfma_f32_16x16x32_bf16 v[58:61], v[216:219], v[228:231], v[58:61]
	v_mfma_f32_16x16x32_bf16 v[62:65], v[216:219], v[236:239], v[62:65]
	v_mfma_f32_16x16x32_bf16 v[42:45], v[216:219], v[240:243], v[42:45]
	v_mfma_f32_16x16x32_bf16 v[46:49], v[216:219], v[252:255], v[46:49]
	ds_read_b128 v[216:219], v244 offset:2368
	s_setprio 1
	s_waitcnt vmcnt(15)
	ds_write_b128 v165, v[122:125] offset:18432
	s_waitcnt vmcnt(14)
	ds_write_b128 v165, v[126:129] offset:23040
	s_waitcnt lgkmcnt(5)
	v_mfma_f32_16x16x32_bf16 v[18:21], v[220:223], v[228:231], v[18:21]
	v_mfma_f32_16x16x32_bf16 v[22:25], v[220:223], v[236:239], v[22:25]
	v_mfma_f32_16x16x32_bf16 v[2:5], v[220:223], v[240:243], v[2:5]
	v_mfma_f32_16x16x32_bf16 v[6:9], v[220:223], v[252:255], v[6:9]
	ds_read_b128 v[220:223], v244 offset:4672
	s_waitcnt vmcnt(13)
	ds_write_b128 v165, v[136:139] offset:27648
	s_waitcnt vmcnt(12)
	ds_write_b128 v165, v[140:143] offset:32256
	s_waitcnt lgkmcnt(7)
	v_mfma_f32_16x16x32_bf16 v[26:29], v[224:227], v[228:231], v[26:29]
	ds_read_b128 v[228:231], v245 offset:36928
	v_mfma_f32_16x16x32_bf16 v[30:33], v[224:227], v[236:239], v[30:33]
	ds_read_b128 v[236:239], v245 offset:39232
	v_mfma_f32_16x16x32_bf16 v[10:13], v[224:227], v[240:243], v[10:13]
	ds_read_b128 v[240:243], v245 offset:41536
	v_mfma_f32_16x16x32_bf16 v[14:17], v[224:227], v[252:255], v[14:17]
	ds_read_b128 v[252:255], v245 offset:43840
	ds_read_b128 v[224:227], v244 offset:6976
	s_waitcnt lgkmcnt(4)
	v_mfma_f32_16x16x32_bf16 v[50:53], v[212:215], v[228:231], v[50:53]
	s_waitcnt lgkmcnt(3)
	v_mfma_f32_16x16x32_bf16 v[54:57], v[212:215], v[236:239], v[54:57]
	s_waitcnt lgkmcnt(2)
	v_mfma_f32_16x16x32_bf16 v[34:37], v[212:215], v[240:243], v[34:37]
	s_waitcnt lgkmcnt(1)
	v_mfma_f32_16x16x32_bf16 v[38:41], v[212:215], v[252:255], v[38:41]
	s_waitcnt vmcnt(11)
	ds_write_b128 v165, v[144:147] offset:55296
	s_waitcnt vmcnt(10)
	ds_write_b128 v165, v[148:151] offset:59904
	v_mfma_f32_16x16x32_bf16 v[58:61], v[216:219], v[228:231], v[58:61]
	v_mfma_f32_16x16x32_bf16 v[62:65], v[216:219], v[236:239], v[62:65]
	v_mfma_f32_16x16x32_bf16 v[42:45], v[216:219], v[240:243], v[42:45]
	v_mfma_f32_16x16x32_bf16 v[46:49], v[216:219], v[252:255], v[46:49]
	s_waitcnt vmcnt(9)
	ds_write_b128 v165, v[172:175] offset:64512
	s_waitcnt vmcnt(8)
	ds_write_b128 v166, v[176:179] offset:32256
	v_mfma_f32_16x16x32_bf16 v[18:21], v[220:223], v[228:231], v[18:21]
	v_mfma_f32_16x16x32_bf16 v[22:25], v[220:223], v[236:239], v[22:25]
	v_mfma_f32_16x16x32_bf16 v[2:5], v[220:223], v[240:243], v[2:5]
	v_mfma_f32_16x16x32_bf16 v[6:9], v[220:223], v[252:255], v[6:9]
	s_waitcnt lgkmcnt(4)
	v_mfma_f32_16x16x32_bf16 v[26:29], v[224:227], v[228:231], v[26:29]
	v_mfma_f32_16x16x32_bf16 v[30:33], v[224:227], v[236:239], v[30:33]
	v_mfma_f32_16x16x32_bf16 v[10:13], v[224:227], v[240:243], v[10:13]
	v_mfma_f32_16x16x32_bf16 v[14:17], v[224:227], v[252:255], v[14:17]
	s_waitcnt lgkmcnt(0)
	s_barrier
	global_load_dwordx4 v[122:125], v[70:71], off offset:1408
	global_load_dwordx4 v[126:129], v[68:69], off offset:1408
	global_load_dwordx4 v[136:139], v[66:67], off offset:1408
	global_load_dwordx4 v[140:143], v[72:73], off offset:1408
	global_load_dwordx4 v[144:147], v[74:75], off offset:1408
	global_load_dwordx4 v[148:151], v[76:77], off offset:1408
	global_load_dwordx4 v[172:175], v[78:79], off offset:1408
	global_load_dwordx4 v[176:179], v[80:81], off offset:1408
	ds_read_b128 v[228:231], v245 offset:55296
	ds_read_b128 v[212:215], v244 offset:18432
	ds_read_b128 v[236:239], v245 offset:57600
	ds_read_b128 v[240:243], v245 offset:59904
	ds_read_b128 v[252:255], v245 offset:62208
	ds_read_b128 v[216:219], v244 offset:20736
	ds_read_b128 v[220:223], v244 offset:23040
	ds_read_b128 v[224:227], v244 offset:25344
	s_setprio 0
	s_waitcnt lgkmcnt(6)
	v_mfma_f32_16x16x32_bf16 v[50:53], v[212:215], v[228:231], v[50:53]
	s_waitcnt lgkmcnt(5)
	v_mfma_f32_16x16x32_bf16 v[54:57], v[212:215], v[236:239], v[54:57]
	s_waitcnt lgkmcnt(4)
	v_mfma_f32_16x16x32_bf16 v[34:37], v[212:215], v[240:243], v[34:37]
	s_waitcnt lgkmcnt(3)
	v_mfma_f32_16x16x32_bf16 v[38:41], v[212:215], v[252:255], v[38:41]
	ds_read_b128 v[212:215], v244 offset:18496
	s_waitcnt lgkmcnt(3)
	v_mfma_f32_16x16x32_bf16 v[58:61], v[216:219], v[228:231], v[58:61]
	v_mfma_f32_16x16x32_bf16 v[62:65], v[216:219], v[236:239], v[62:65]
	v_mfma_f32_16x16x32_bf16 v[42:45], v[216:219], v[240:243], v[42:45]
	v_mfma_f32_16x16x32_bf16 v[46:49], v[216:219], v[252:255], v[46:49]
	ds_read_b128 v[216:219], v244 offset:20800
	s_setprio 1
	s_waitcnt vmcnt(15)
	ds_write_b128 v165, v[180:183]
	s_waitcnt vmcnt(14)
	ds_write_b128 v165, v[184:187] offset:4608
	s_waitcnt lgkmcnt(5)
	v_mfma_f32_16x16x32_bf16 v[18:21], v[220:223], v[228:231], v[18:21]
	v_mfma_f32_16x16x32_bf16 v[22:25], v[220:223], v[236:239], v[22:25]
	v_mfma_f32_16x16x32_bf16 v[2:5], v[220:223], v[240:243], v[2:5]
	v_mfma_f32_16x16x32_bf16 v[6:9], v[220:223], v[252:255], v[6:9]
	ds_read_b128 v[220:223], v244 offset:23104
	s_waitcnt vmcnt(13)
	ds_write_b128 v165, v[188:191] offset:9216
	s_waitcnt vmcnt(12)
	ds_write_b128 v165, v[192:195] offset:13824
	s_waitcnt lgkmcnt(7)
	v_mfma_f32_16x16x32_bf16 v[26:29], v[224:227], v[228:231], v[26:29]
	ds_read_b128 v[228:231], v245 offset:55360
	v_mfma_f32_16x16x32_bf16 v[30:33], v[224:227], v[236:239], v[30:33]
	ds_read_b128 v[236:239], v245 offset:57664
	v_mfma_f32_16x16x32_bf16 v[10:13], v[224:227], v[240:243], v[10:13]
	ds_read_b128 v[240:243], v245 offset:59968
	v_mfma_f32_16x16x32_bf16 v[14:17], v[224:227], v[252:255], v[14:17]
	ds_read_b128 v[252:255], v245 offset:62272
	ds_read_b128 v[224:227], v244 offset:25408
	s_waitcnt lgkmcnt(4)
	v_mfma_f32_16x16x32_bf16 v[50:53], v[212:215], v[228:231], v[50:53]
	s_waitcnt lgkmcnt(3)
	v_mfma_f32_16x16x32_bf16 v[54:57], v[212:215], v[236:239], v[54:57]
	s_waitcnt lgkmcnt(2)
	v_mfma_f32_16x16x32_bf16 v[34:37], v[212:215], v[240:243], v[34:37]
	s_waitcnt lgkmcnt(1)
	v_mfma_f32_16x16x32_bf16 v[38:41], v[212:215], v[252:255], v[38:41]
	s_waitcnt vmcnt(11)
	ds_write_b128 v165, v[196:199] offset:36864
	s_waitcnt vmcnt(10)
	ds_write_b128 v165, v[200:203] offset:41472
	v_mfma_f32_16x16x32_bf16 v[58:61], v[216:219], v[228:231], v[58:61]
	v_mfma_f32_16x16x32_bf16 v[62:65], v[216:219], v[236:239], v[62:65]
	v_mfma_f32_16x16x32_bf16 v[42:45], v[216:219], v[240:243], v[42:45]
	v_mfma_f32_16x16x32_bf16 v[46:49], v[216:219], v[252:255], v[46:49]
	s_waitcnt vmcnt(9)
	ds_write_b128 v165, v[204:207] offset:46080
	s_waitcnt vmcnt(8)
	ds_write_b128 v165, v[208:211] offset:50688
	v_mfma_f32_16x16x32_bf16 v[18:21], v[220:223], v[228:231], v[18:21]
	v_mfma_f32_16x16x32_bf16 v[22:25], v[220:223], v[236:239], v[22:25]
	v_mfma_f32_16x16x32_bf16 v[2:5], v[220:223], v[240:243], v[2:5]
	v_mfma_f32_16x16x32_bf16 v[6:9], v[220:223], v[252:255], v[6:9]
	s_waitcnt lgkmcnt(4)
	v_mfma_f32_16x16x32_bf16 v[26:29], v[224:227], v[228:231], v[26:29]
	v_mfma_f32_16x16x32_bf16 v[30:33], v[224:227], v[236:239], v[30:33]
	v_mfma_f32_16x16x32_bf16 v[10:13], v[224:227], v[240:243], v[10:13]
	v_mfma_f32_16x16x32_bf16 v[14:17], v[224:227], v[252:255], v[14:17]
	s_waitcnt lgkmcnt(0)
	s_barrier
	global_load_dwordx4 v[180:183], v[70:71], off offset:1536
	global_load_dwordx4 v[184:187], v[68:69], off offset:1536
	global_load_dwordx4 v[188:191], v[66:67], off offset:1536
	global_load_dwordx4 v[192:195], v[72:73], off offset:1536
	global_load_dwordx4 v[196:199], v[74:75], off offset:1536
	global_load_dwordx4 v[200:203], v[76:77], off offset:1536
	global_load_dwordx4 v[204:207], v[78:79], off offset:1536
	global_load_dwordx4 v[208:211], v[80:81], off offset:1536
	ds_read_b128 v[228:231], v245 offset:36864
	ds_read_b128 v[212:215], v244
	ds_read_b128 v[236:239], v245 offset:39168
	ds_read_b128 v[240:243], v245 offset:41472
	ds_read_b128 v[252:255], v245 offset:43776
	ds_read_b128 v[216:219], v244 offset:2304
	ds_read_b128 v[220:223], v244 offset:4608
	ds_read_b128 v[224:227], v244 offset:6912
	s_setprio 0
	s_waitcnt lgkmcnt(6)
	v_mfma_f32_16x16x32_bf16 v[50:53], v[212:215], v[228:231], v[50:53]
	s_waitcnt lgkmcnt(5)
	v_mfma_f32_16x16x32_bf16 v[54:57], v[212:215], v[236:239], v[54:57]
	s_waitcnt lgkmcnt(4)
	v_mfma_f32_16x16x32_bf16 v[34:37], v[212:215], v[240:243], v[34:37]
	s_waitcnt lgkmcnt(3)
	v_mfma_f32_16x16x32_bf16 v[38:41], v[212:215], v[252:255], v[38:41]
	ds_read_b128 v[212:215], v244 offset:64
	s_waitcnt lgkmcnt(3)
	v_mfma_f32_16x16x32_bf16 v[58:61], v[216:219], v[228:231], v[58:61]
	v_mfma_f32_16x16x32_bf16 v[62:65], v[216:219], v[236:239], v[62:65]
	v_mfma_f32_16x16x32_bf16 v[42:45], v[216:219], v[240:243], v[42:45]
	v_mfma_f32_16x16x32_bf16 v[46:49], v[216:219], v[252:255], v[46:49]
	ds_read_b128 v[216:219], v244 offset:2368
	s_setprio 1
	s_waitcnt vmcnt(15)
	ds_write_b128 v165, v[122:125] offset:18432
	s_waitcnt vmcnt(14)
	ds_write_b128 v165, v[126:129] offset:23040
	s_waitcnt lgkmcnt(5)
	v_mfma_f32_16x16x32_bf16 v[18:21], v[220:223], v[228:231], v[18:21]
	v_mfma_f32_16x16x32_bf16 v[22:25], v[220:223], v[236:239], v[22:25]
	v_mfma_f32_16x16x32_bf16 v[2:5], v[220:223], v[240:243], v[2:5]
	v_mfma_f32_16x16x32_bf16 v[6:9], v[220:223], v[252:255], v[6:9]
	ds_read_b128 v[220:223], v244 offset:4672
	s_waitcnt vmcnt(13)
	ds_write_b128 v165, v[136:139] offset:27648
	s_waitcnt vmcnt(12)
	ds_write_b128 v165, v[140:143] offset:32256
	s_waitcnt lgkmcnt(7)
	v_mfma_f32_16x16x32_bf16 v[26:29], v[224:227], v[228:231], v[26:29]
	ds_read_b128 v[228:231], v245 offset:36928
	v_mfma_f32_16x16x32_bf16 v[30:33], v[224:227], v[236:239], v[30:33]
	ds_read_b128 v[236:239], v245 offset:39232
	v_mfma_f32_16x16x32_bf16 v[10:13], v[224:227], v[240:243], v[10:13]
	ds_read_b128 v[240:243], v245 offset:41536
	v_mfma_f32_16x16x32_bf16 v[14:17], v[224:227], v[252:255], v[14:17]
	ds_read_b128 v[252:255], v245 offset:43840
	ds_read_b128 v[224:227], v244 offset:6976
	s_waitcnt lgkmcnt(4)
	v_mfma_f32_16x16x32_bf16 v[50:53], v[212:215], v[228:231], v[50:53]
	s_waitcnt lgkmcnt(3)
	v_mfma_f32_16x16x32_bf16 v[54:57], v[212:215], v[236:239], v[54:57]
	s_waitcnt lgkmcnt(2)
	v_mfma_f32_16x16x32_bf16 v[34:37], v[212:215], v[240:243], v[34:37]
	s_waitcnt lgkmcnt(1)
	v_mfma_f32_16x16x32_bf16 v[38:41], v[212:215], v[252:255], v[38:41]
	s_waitcnt vmcnt(11)
	ds_write_b128 v165, v[144:147] offset:55296
	s_waitcnt vmcnt(10)
	ds_write_b128 v165, v[148:151] offset:59904
	v_mfma_f32_16x16x32_bf16 v[58:61], v[216:219], v[228:231], v[58:61]
	v_mfma_f32_16x16x32_bf16 v[62:65], v[216:219], v[236:239], v[62:65]
	v_mfma_f32_16x16x32_bf16 v[42:45], v[216:219], v[240:243], v[42:45]
	v_mfma_f32_16x16x32_bf16 v[46:49], v[216:219], v[252:255], v[46:49]
	s_waitcnt vmcnt(9)
	ds_write_b128 v165, v[172:175] offset:64512
	s_waitcnt vmcnt(8)
	ds_write_b128 v166, v[176:179] offset:32256
	v_mfma_f32_16x16x32_bf16 v[18:21], v[220:223], v[228:231], v[18:21]
	v_mfma_f32_16x16x32_bf16 v[22:25], v[220:223], v[236:239], v[22:25]
	v_mfma_f32_16x16x32_bf16 v[2:5], v[220:223], v[240:243], v[2:5]
	v_mfma_f32_16x16x32_bf16 v[6:9], v[220:223], v[252:255], v[6:9]
	s_waitcnt lgkmcnt(4)
	v_mfma_f32_16x16x32_bf16 v[26:29], v[224:227], v[228:231], v[26:29]
	v_mfma_f32_16x16x32_bf16 v[30:33], v[224:227], v[236:239], v[30:33]
	v_mfma_f32_16x16x32_bf16 v[10:13], v[224:227], v[240:243], v[10:13]
	v_mfma_f32_16x16x32_bf16 v[14:17], v[224:227], v[252:255], v[14:17]
	s_waitcnt lgkmcnt(0)
	s_barrier
	global_load_dwordx4 v[122:125], v[70:71], off offset:1664
	global_load_dwordx4 v[126:129], v[68:69], off offset:1664
	global_load_dwordx4 v[136:139], v[66:67], off offset:1664
	global_load_dwordx4 v[140:143], v[72:73], off offset:1664
	global_load_dwordx4 v[144:147], v[74:75], off offset:1664
	global_load_dwordx4 v[148:151], v[76:77], off offset:1664
	global_load_dwordx4 v[172:175], v[78:79], off offset:1664
	global_load_dwordx4 v[176:179], v[80:81], off offset:1664
	ds_read_b128 v[228:231], v245 offset:55296
	ds_read_b128 v[212:215], v244 offset:18432
	ds_read_b128 v[236:239], v245 offset:57600
	ds_read_b128 v[240:243], v245 offset:59904
	ds_read_b128 v[252:255], v245 offset:62208
	ds_read_b128 v[216:219], v244 offset:20736
	ds_read_b128 v[220:223], v244 offset:23040
	ds_read_b128 v[224:227], v244 offset:25344
	s_setprio 0
	s_waitcnt lgkmcnt(6)
	v_mfma_f32_16x16x32_bf16 v[50:53], v[212:215], v[228:231], v[50:53]
	s_waitcnt lgkmcnt(5)
	v_mfma_f32_16x16x32_bf16 v[54:57], v[212:215], v[236:239], v[54:57]
	s_waitcnt lgkmcnt(4)
	v_mfma_f32_16x16x32_bf16 v[34:37], v[212:215], v[240:243], v[34:37]
	s_waitcnt lgkmcnt(3)
	v_mfma_f32_16x16x32_bf16 v[38:41], v[212:215], v[252:255], v[38:41]
	ds_read_b128 v[212:215], v244 offset:18496
	s_waitcnt lgkmcnt(3)
	v_mfma_f32_16x16x32_bf16 v[58:61], v[216:219], v[228:231], v[58:61]
	v_mfma_f32_16x16x32_bf16 v[62:65], v[216:219], v[236:239], v[62:65]
	v_mfma_f32_16x16x32_bf16 v[42:45], v[216:219], v[240:243], v[42:45]
	v_mfma_f32_16x16x32_bf16 v[46:49], v[216:219], v[252:255], v[46:49]
	ds_read_b128 v[216:219], v244 offset:20800
	s_setprio 1
	s_waitcnt vmcnt(15)
	ds_write_b128 v165, v[180:183]
	s_waitcnt vmcnt(14)
	ds_write_b128 v165, v[184:187] offset:4608
	s_waitcnt lgkmcnt(5)
	v_mfma_f32_16x16x32_bf16 v[18:21], v[220:223], v[228:231], v[18:21]
	v_mfma_f32_16x16x32_bf16 v[22:25], v[220:223], v[236:239], v[22:25]
	v_mfma_f32_16x16x32_bf16 v[2:5], v[220:223], v[240:243], v[2:5]
	v_mfma_f32_16x16x32_bf16 v[6:9], v[220:223], v[252:255], v[6:9]
	ds_read_b128 v[220:223], v244 offset:23104
	s_waitcnt vmcnt(13)
	ds_write_b128 v165, v[188:191] offset:9216
	s_waitcnt vmcnt(12)
	ds_write_b128 v165, v[192:195] offset:13824
	s_waitcnt lgkmcnt(7)
	v_mfma_f32_16x16x32_bf16 v[26:29], v[224:227], v[228:231], v[26:29]
	ds_read_b128 v[228:231], v245 offset:55360
	v_mfma_f32_16x16x32_bf16 v[30:33], v[224:227], v[236:239], v[30:33]
	ds_read_b128 v[236:239], v245 offset:57664
	v_mfma_f32_16x16x32_bf16 v[10:13], v[224:227], v[240:243], v[10:13]
	ds_read_b128 v[240:243], v245 offset:59968
	v_mfma_f32_16x16x32_bf16 v[14:17], v[224:227], v[252:255], v[14:17]
	ds_read_b128 v[252:255], v245 offset:62272
	ds_read_b128 v[224:227], v244 offset:25408
	s_waitcnt lgkmcnt(4)
	v_mfma_f32_16x16x32_bf16 v[50:53], v[212:215], v[228:231], v[50:53]
	s_waitcnt lgkmcnt(3)
	v_mfma_f32_16x16x32_bf16 v[54:57], v[212:215], v[236:239], v[54:57]
	s_waitcnt lgkmcnt(2)
	v_mfma_f32_16x16x32_bf16 v[34:37], v[212:215], v[240:243], v[34:37]
	s_waitcnt lgkmcnt(1)
	v_mfma_f32_16x16x32_bf16 v[38:41], v[212:215], v[252:255], v[38:41]
	s_waitcnt vmcnt(11)
	ds_write_b128 v165, v[196:199] offset:36864
	s_waitcnt vmcnt(10)
	ds_write_b128 v165, v[200:203] offset:41472
	v_mfma_f32_16x16x32_bf16 v[58:61], v[216:219], v[228:231], v[58:61]
	v_mfma_f32_16x16x32_bf16 v[62:65], v[216:219], v[236:239], v[62:65]
	v_mfma_f32_16x16x32_bf16 v[42:45], v[216:219], v[240:243], v[42:45]
	v_mfma_f32_16x16x32_bf16 v[46:49], v[216:219], v[252:255], v[46:49]
	s_waitcnt vmcnt(9)
	ds_write_b128 v165, v[204:207] offset:46080
	s_waitcnt vmcnt(8)
	ds_write_b128 v165, v[208:211] offset:50688
	v_mfma_f32_16x16x32_bf16 v[18:21], v[220:223], v[228:231], v[18:21]
	v_mfma_f32_16x16x32_bf16 v[22:25], v[220:223], v[236:239], v[22:25]
	v_mfma_f32_16x16x32_bf16 v[2:5], v[220:223], v[240:243], v[2:5]
	v_mfma_f32_16x16x32_bf16 v[6:9], v[220:223], v[252:255], v[6:9]
	s_waitcnt lgkmcnt(4)
	v_mfma_f32_16x16x32_bf16 v[26:29], v[224:227], v[228:231], v[26:29]
	v_mfma_f32_16x16x32_bf16 v[30:33], v[224:227], v[236:239], v[30:33]
	v_mfma_f32_16x16x32_bf16 v[10:13], v[224:227], v[240:243], v[10:13]
	v_mfma_f32_16x16x32_bf16 v[14:17], v[224:227], v[252:255], v[14:17]
	s_waitcnt lgkmcnt(0)
	s_barrier
	global_load_dwordx4 v[180:183], v[70:71], off offset:1792
	global_load_dwordx4 v[184:187], v[68:69], off offset:1792
	global_load_dwordx4 v[188:191], v[66:67], off offset:1792
	global_load_dwordx4 v[192:195], v[72:73], off offset:1792
	global_load_dwordx4 v[196:199], v[74:75], off offset:1792
	global_load_dwordx4 v[200:203], v[76:77], off offset:1792
	global_load_dwordx4 v[204:207], v[78:79], off offset:1792
	global_load_dwordx4 v[208:211], v[80:81], off offset:1792
	ds_read_b128 v[228:231], v245 offset:36864
	ds_read_b128 v[212:215], v244
	ds_read_b128 v[236:239], v245 offset:39168
	ds_read_b128 v[240:243], v245 offset:41472
	ds_read_b128 v[252:255], v245 offset:43776
	ds_read_b128 v[216:219], v244 offset:2304
	ds_read_b128 v[220:223], v244 offset:4608
	ds_read_b128 v[224:227], v244 offset:6912
	s_setprio 0
	s_waitcnt lgkmcnt(6)
	v_mfma_f32_16x16x32_bf16 v[50:53], v[212:215], v[228:231], v[50:53]
	s_waitcnt lgkmcnt(5)
	v_mfma_f32_16x16x32_bf16 v[54:57], v[212:215], v[236:239], v[54:57]
	s_waitcnt lgkmcnt(4)
	v_mfma_f32_16x16x32_bf16 v[34:37], v[212:215], v[240:243], v[34:37]
	s_waitcnt lgkmcnt(3)
	v_mfma_f32_16x16x32_bf16 v[38:41], v[212:215], v[252:255], v[38:41]
	ds_read_b128 v[212:215], v244 offset:64
	s_waitcnt lgkmcnt(3)
	v_mfma_f32_16x16x32_bf16 v[58:61], v[216:219], v[228:231], v[58:61]
	v_mfma_f32_16x16x32_bf16 v[62:65], v[216:219], v[236:239], v[62:65]
	v_mfma_f32_16x16x32_bf16 v[42:45], v[216:219], v[240:243], v[42:45]
	v_mfma_f32_16x16x32_bf16 v[46:49], v[216:219], v[252:255], v[46:49]
	ds_read_b128 v[216:219], v244 offset:2368
	s_setprio 1
	s_waitcnt vmcnt(15)
	ds_write_b128 v165, v[122:125] offset:18432
	s_waitcnt vmcnt(14)
	ds_write_b128 v165, v[126:129] offset:23040
	s_waitcnt lgkmcnt(5)
	v_mfma_f32_16x16x32_bf16 v[18:21], v[220:223], v[228:231], v[18:21]
	v_mfma_f32_16x16x32_bf16 v[22:25], v[220:223], v[236:239], v[22:25]
	v_mfma_f32_16x16x32_bf16 v[2:5], v[220:223], v[240:243], v[2:5]
	v_mfma_f32_16x16x32_bf16 v[6:9], v[220:223], v[252:255], v[6:9]
	ds_read_b128 v[220:223], v244 offset:4672
	s_waitcnt vmcnt(13)
	ds_write_b128 v165, v[136:139] offset:27648
	s_waitcnt vmcnt(12)
	ds_write_b128 v165, v[140:143] offset:32256
	s_waitcnt lgkmcnt(7)
	v_mfma_f32_16x16x32_bf16 v[26:29], v[224:227], v[228:231], v[26:29]
	ds_read_b128 v[228:231], v245 offset:36928
	v_mfma_f32_16x16x32_bf16 v[30:33], v[224:227], v[236:239], v[30:33]
	ds_read_b128 v[236:239], v245 offset:39232
	v_mfma_f32_16x16x32_bf16 v[10:13], v[224:227], v[240:243], v[10:13]
	ds_read_b128 v[240:243], v245 offset:41536
	v_mfma_f32_16x16x32_bf16 v[14:17], v[224:227], v[252:255], v[14:17]
	ds_read_b128 v[252:255], v245 offset:43840
	ds_read_b128 v[224:227], v244 offset:6976
	s_waitcnt lgkmcnt(4)
	v_mfma_f32_16x16x32_bf16 v[50:53], v[212:215], v[228:231], v[50:53]
	s_waitcnt lgkmcnt(3)
	v_mfma_f32_16x16x32_bf16 v[54:57], v[212:215], v[236:239], v[54:57]
	s_waitcnt lgkmcnt(2)
	v_mfma_f32_16x16x32_bf16 v[34:37], v[212:215], v[240:243], v[34:37]
	s_waitcnt lgkmcnt(1)
	v_mfma_f32_16x16x32_bf16 v[38:41], v[212:215], v[252:255], v[38:41]
	s_waitcnt vmcnt(11)
	ds_write_b128 v165, v[144:147] offset:55296
	s_waitcnt vmcnt(10)
	ds_write_b128 v165, v[148:151] offset:59904
	v_mfma_f32_16x16x32_bf16 v[58:61], v[216:219], v[228:231], v[58:61]
	v_mfma_f32_16x16x32_bf16 v[62:65], v[216:219], v[236:239], v[62:65]
	v_mfma_f32_16x16x32_bf16 v[42:45], v[216:219], v[240:243], v[42:45]
	v_mfma_f32_16x16x32_bf16 v[46:49], v[216:219], v[252:255], v[46:49]
	s_waitcnt vmcnt(9)
	ds_write_b128 v165, v[172:175] offset:64512
	s_waitcnt vmcnt(8)
	ds_write_b128 v166, v[176:179] offset:32256
	v_mfma_f32_16x16x32_bf16 v[18:21], v[220:223], v[228:231], v[18:21]
	v_mfma_f32_16x16x32_bf16 v[22:25], v[220:223], v[236:239], v[22:25]
	v_mfma_f32_16x16x32_bf16 v[2:5], v[220:223], v[240:243], v[2:5]
	v_mfma_f32_16x16x32_bf16 v[6:9], v[220:223], v[252:255], v[6:9]
	s_waitcnt lgkmcnt(4)
	v_mfma_f32_16x16x32_bf16 v[26:29], v[224:227], v[228:231], v[26:29]
	v_mfma_f32_16x16x32_bf16 v[30:33], v[224:227], v[236:239], v[30:33]
	v_mfma_f32_16x16x32_bf16 v[10:13], v[224:227], v[240:243], v[10:13]
	v_mfma_f32_16x16x32_bf16 v[14:17], v[224:227], v[252:255], v[14:17]
	s_waitcnt lgkmcnt(0)
	s_barrier
	global_load_dwordx4 v[122:125], v[70:71], off offset:1920
	s_nop 0
	global_load_dwordx4 v[68:71], v[68:69], off offset:1920
	s_nop 0
	global_load_dwordx4 v[126:129], v[66:67], off offset:1920
	global_load_dwordx4 v[136:139], v[72:73], off offset:1920
	s_nop 0
	global_load_dwordx4 v[72:75], v[74:75], off offset:1920
	s_nop 0
	global_load_dwordx4 v[140:143], v[76:77], off offset:1920
	s_nop 0
	global_load_dwordx4 v[76:79], v[78:79], off offset:1920
	s_nop 0
	global_load_dwordx4 v[144:147], v[80:81], off offset:1920
	ds_read_b128 v[228:231], v245 offset:55296
	ds_read_b128 v[212:215], v244 offset:18432
	ds_read_b128 v[236:239], v245 offset:57600
	ds_read_b128 v[240:243], v245 offset:59904
	ds_read_b128 v[252:255], v245 offset:62208
	ds_read_b128 v[216:219], v244 offset:20736
	ds_read_b128 v[220:223], v244 offset:23040
	ds_read_b128 v[224:227], v244 offset:25344
	s_setprio 0
	s_waitcnt lgkmcnt(6)
	v_mfma_f32_16x16x32_bf16 v[50:53], v[212:215], v[228:231], v[50:53]
	s_waitcnt lgkmcnt(5)
	v_mfma_f32_16x16x32_bf16 v[54:57], v[212:215], v[236:239], v[54:57]
	s_waitcnt lgkmcnt(4)
	v_mfma_f32_16x16x32_bf16 v[34:37], v[212:215], v[240:243], v[34:37]
	s_waitcnt lgkmcnt(3)
	v_mfma_f32_16x16x32_bf16 v[38:41], v[212:215], v[252:255], v[38:41]
	ds_read_b128 v[212:215], v244 offset:18496
	s_waitcnt lgkmcnt(3)
	v_mfma_f32_16x16x32_bf16 v[58:61], v[216:219], v[228:231], v[58:61]
	v_mfma_f32_16x16x32_bf16 v[62:65], v[216:219], v[236:239], v[62:65]
	v_mfma_f32_16x16x32_bf16 v[42:45], v[216:219], v[240:243], v[42:45]
	v_mfma_f32_16x16x32_bf16 v[46:49], v[216:219], v[252:255], v[46:49]
	ds_read_b128 v[216:219], v244 offset:20800
	s_setprio 1
	s_waitcnt vmcnt(15)
	ds_write_b128 v165, v[180:183]
	s_waitcnt vmcnt(14)
	ds_write_b128 v165, v[184:187] offset:4608
	s_waitcnt lgkmcnt(5)
	v_mfma_f32_16x16x32_bf16 v[18:21], v[220:223], v[228:231], v[18:21]
	v_mfma_f32_16x16x32_bf16 v[22:25], v[220:223], v[236:239], v[22:25]
	v_mfma_f32_16x16x32_bf16 v[2:5], v[220:223], v[240:243], v[2:5]
	v_mfma_f32_16x16x32_bf16 v[6:9], v[220:223], v[252:255], v[6:9]
	ds_read_b128 v[220:223], v244 offset:23104
	s_waitcnt vmcnt(13)
	ds_write_b128 v165, v[188:191] offset:9216
	s_waitcnt vmcnt(12)
	ds_write_b128 v165, v[192:195] offset:13824
	s_waitcnt lgkmcnt(7)
	v_mfma_f32_16x16x32_bf16 v[26:29], v[224:227], v[228:231], v[26:29]
	ds_read_b128 v[228:231], v245 offset:55360
	v_mfma_f32_16x16x32_bf16 v[30:33], v[224:227], v[236:239], v[30:33]
	ds_read_b128 v[236:239], v245 offset:57664
	v_mfma_f32_16x16x32_bf16 v[10:13], v[224:227], v[240:243], v[10:13]
	ds_read_b128 v[240:243], v245 offset:59968
	v_mfma_f32_16x16x32_bf16 v[14:17], v[224:227], v[252:255], v[14:17]
	ds_read_b128 v[252:255], v245 offset:62272
	ds_read_b128 v[224:227], v244 offset:25408
	s_waitcnt lgkmcnt(4)
	v_mfma_f32_16x16x32_bf16 v[50:53], v[212:215], v[228:231], v[50:53]
	s_waitcnt lgkmcnt(3)
	v_mfma_f32_16x16x32_bf16 v[54:57], v[212:215], v[236:239], v[54:57]
	s_waitcnt lgkmcnt(2)
	v_mfma_f32_16x16x32_bf16 v[34:37], v[212:215], v[240:243], v[34:37]
	s_waitcnt lgkmcnt(1)
	v_mfma_f32_16x16x32_bf16 v[38:41], v[212:215], v[252:255], v[38:41]
	s_waitcnt vmcnt(11)
	ds_write_b128 v165, v[196:199] offset:36864
	s_waitcnt vmcnt(10)
	ds_write_b128 v165, v[200:203] offset:41472
	v_mfma_f32_16x16x32_bf16 v[58:61], v[216:219], v[228:231], v[58:61]
	v_mfma_f32_16x16x32_bf16 v[62:65], v[216:219], v[236:239], v[62:65]
	v_mfma_f32_16x16x32_bf16 v[42:45], v[216:219], v[240:243], v[42:45]
	v_mfma_f32_16x16x32_bf16 v[46:49], v[216:219], v[252:255], v[46:49]
	s_waitcnt vmcnt(9)
	ds_write_b128 v165, v[204:207] offset:46080
	s_waitcnt vmcnt(8)
	ds_write_b128 v165, v[208:211] offset:50688
	v_mfma_f32_16x16x32_bf16 v[18:21], v[220:223], v[228:231], v[18:21]
	v_mfma_f32_16x16x32_bf16 v[22:25], v[220:223], v[236:239], v[22:25]
	v_mfma_f32_16x16x32_bf16 v[2:5], v[220:223], v[240:243], v[2:5]
	v_mfma_f32_16x16x32_bf16 v[6:9], v[220:223], v[252:255], v[6:9]
	s_waitcnt lgkmcnt(4)
	v_mfma_f32_16x16x32_bf16 v[26:29], v[224:227], v[228:231], v[26:29]
	v_mfma_f32_16x16x32_bf16 v[30:33], v[224:227], v[236:239], v[30:33]
	v_mfma_f32_16x16x32_bf16 v[10:13], v[224:227], v[240:243], v[10:13]
	v_mfma_f32_16x16x32_bf16 v[14:17], v[224:227], v[252:255], v[14:17]
	s_waitcnt lgkmcnt(0)
	s_barrier
	ds_read_b128 v[228:231], v245 offset:36864
	ds_read_b128 v[212:215], v244
	ds_read_b128 v[236:239], v245 offset:39168
	ds_read_b128 v[240:243], v245 offset:41472
	ds_read_b128 v[252:255], v245 offset:43776
	ds_read_b128 v[216:219], v244 offset:2304
	ds_read_b128 v[220:223], v244 offset:4608
	ds_read_b128 v[224:227], v244 offset:6912
	s_setprio 0
	s_waitcnt lgkmcnt(6)
	v_mfma_f32_16x16x32_bf16 v[50:53], v[212:215], v[228:231], v[50:53]
	s_waitcnt lgkmcnt(5)
	v_mfma_f32_16x16x32_bf16 v[54:57], v[212:215], v[236:239], v[54:57]
	s_waitcnt lgkmcnt(4)
	v_mfma_f32_16x16x32_bf16 v[34:37], v[212:215], v[240:243], v[34:37]
	s_waitcnt lgkmcnt(3)
	v_mfma_f32_16x16x32_bf16 v[38:41], v[212:215], v[252:255], v[38:41]
	ds_read_b128 v[212:215], v244 offset:64
	s_waitcnt lgkmcnt(3)
	v_mfma_f32_16x16x32_bf16 v[58:61], v[216:219], v[228:231], v[58:61]
	v_mfma_f32_16x16x32_bf16 v[62:65], v[216:219], v[236:239], v[62:65]
	v_mfma_f32_16x16x32_bf16 v[42:45], v[216:219], v[240:243], v[42:45]
	v_mfma_f32_16x16x32_bf16 v[46:49], v[216:219], v[252:255], v[46:49]
	ds_read_b128 v[216:219], v244 offset:2368
	s_setprio 1
	s_waitcnt vmcnt(7)
	ds_write_b128 v165, v[122:125] offset:18432
	s_waitcnt vmcnt(6)
	ds_write_b128 v165, v[68:71] offset:23040
	s_waitcnt lgkmcnt(5)
	v_mfma_f32_16x16x32_bf16 v[18:21], v[220:223], v[228:231], v[18:21]
	v_mfma_f32_16x16x32_bf16 v[22:25], v[220:223], v[236:239], v[22:25]
	v_mfma_f32_16x16x32_bf16 v[2:5], v[220:223], v[240:243], v[2:5]
	v_mfma_f32_16x16x32_bf16 v[6:9], v[220:223], v[252:255], v[6:9]
	ds_read_b128 v[220:223], v244 offset:4672
	s_waitcnt vmcnt(5)
	ds_write_b128 v165, v[126:129] offset:27648
	s_waitcnt vmcnt(4)
	ds_write_b128 v165, v[136:139] offset:32256
	s_waitcnt lgkmcnt(7)
	v_mfma_f32_16x16x32_bf16 v[26:29], v[224:227], v[228:231], v[26:29]
	ds_read_b128 v[228:231], v245 offset:36928
	v_mfma_f32_16x16x32_bf16 v[30:33], v[224:227], v[236:239], v[30:33]
	ds_read_b128 v[236:239], v245 offset:39232
	v_mfma_f32_16x16x32_bf16 v[10:13], v[224:227], v[240:243], v[10:13]
	ds_read_b128 v[240:243], v245 offset:41536
	v_mfma_f32_16x16x32_bf16 v[14:17], v[224:227], v[252:255], v[14:17]
	ds_read_b128 v[252:255], v245 offset:43840
	ds_read_b128 v[224:227], v244 offset:6976
	s_waitcnt lgkmcnt(4)
	v_mfma_f32_16x16x32_bf16 v[50:53], v[212:215], v[228:231], v[50:53]
	s_waitcnt lgkmcnt(3)
	v_mfma_f32_16x16x32_bf16 v[54:57], v[212:215], v[236:239], v[54:57]
	s_waitcnt lgkmcnt(2)
	v_mfma_f32_16x16x32_bf16 v[34:37], v[212:215], v[240:243], v[34:37]
	s_waitcnt lgkmcnt(1)
	v_mfma_f32_16x16x32_bf16 v[38:41], v[212:215], v[252:255], v[38:41]
	s_waitcnt vmcnt(3)
	ds_write_b128 v165, v[72:75] offset:55296
	s_waitcnt vmcnt(2)
	ds_write_b128 v165, v[140:143] offset:59904
	v_mfma_f32_16x16x32_bf16 v[58:61], v[216:219], v[228:231], v[58:61]
	v_mfma_f32_16x16x32_bf16 v[62:65], v[216:219], v[236:239], v[62:65]
	v_mfma_f32_16x16x32_bf16 v[42:45], v[216:219], v[240:243], v[42:45]
	v_mfma_f32_16x16x32_bf16 v[46:49], v[216:219], v[252:255], v[46:49]
	s_waitcnt vmcnt(1)
	ds_write_b128 v165, v[76:79] offset:64512
	s_waitcnt vmcnt(0)
	ds_write_b128 v166, v[144:147] offset:32256
	v_mfma_f32_16x16x32_bf16 v[18:21], v[220:223], v[228:231], v[18:21]
	v_mfma_f32_16x16x32_bf16 v[22:25], v[220:223], v[236:239], v[22:25]
	v_mfma_f32_16x16x32_bf16 v[2:5], v[220:223], v[240:243], v[2:5]
	v_mfma_f32_16x16x32_bf16 v[6:9], v[220:223], v[252:255], v[6:9]
	s_waitcnt lgkmcnt(4)
	v_mfma_f32_16x16x32_bf16 v[26:29], v[224:227], v[228:231], v[26:29]
	v_mfma_f32_16x16x32_bf16 v[30:33], v[224:227], v[236:239], v[30:33]
	v_mfma_f32_16x16x32_bf16 v[10:13], v[224:227], v[240:243], v[10:13]
	v_mfma_f32_16x16x32_bf16 v[14:17], v[224:227], v[252:255], v[14:17]
	s_waitcnt lgkmcnt(0)
	s_barrier
	ds_read_b128 v[228:231], v245 offset:55296
	ds_read_b128 v[212:215], v244 offset:18432
	ds_read_b128 v[236:239], v245 offset:57600
	ds_read_b128 v[240:243], v245 offset:59904
	ds_read_b128 v[252:255], v245 offset:62208
	ds_read_b128 v[216:219], v244 offset:20736
	ds_read_b128 v[220:223], v244 offset:23040
	ds_read_b128 v[224:227], v244 offset:25344
	s_setprio 0
	s_waitcnt lgkmcnt(6)
	v_mfma_f32_16x16x32_bf16 v[50:53], v[212:215], v[228:231], v[50:53]
	s_waitcnt lgkmcnt(5)
	v_mfma_f32_16x16x32_bf16 v[54:57], v[212:215], v[236:239], v[54:57]
	s_waitcnt lgkmcnt(4)
	v_mfma_f32_16x16x32_bf16 v[34:37], v[212:215], v[240:243], v[34:37]
	s_waitcnt lgkmcnt(3)
	v_mfma_f32_16x16x32_bf16 v[38:41], v[212:215], v[252:255], v[38:41]
	ds_read_b128 v[212:215], v244 offset:18496
	s_waitcnt lgkmcnt(3)
	v_mfma_f32_16x16x32_bf16 v[58:61], v[216:219], v[228:231], v[58:61]
	v_mfma_f32_16x16x32_bf16 v[62:65], v[216:219], v[236:239], v[62:65]
	v_mfma_f32_16x16x32_bf16 v[42:45], v[216:219], v[240:243], v[42:45]
	v_mfma_f32_16x16x32_bf16 v[46:49], v[216:219], v[252:255], v[46:49]
	ds_read_b128 v[216:219], v244 offset:20800
	s_waitcnt lgkmcnt(3)
	v_mfma_f32_16x16x32_bf16 v[18:21], v[220:223], v[228:231], v[18:21]
	v_mfma_f32_16x16x32_bf16 v[22:25], v[220:223], v[236:239], v[22:25]
	v_mfma_f32_16x16x32_bf16 v[2:5], v[220:223], v[240:243], v[2:5]
	v_mfma_f32_16x16x32_bf16 v[6:9], v[220:223], v[252:255], v[6:9]
	ds_read_b128 v[220:223], v244 offset:23104
	s_waitcnt lgkmcnt(3)
	v_mfma_f32_16x16x32_bf16 v[26:29], v[224:227], v[228:231], v[26:29]
	ds_read_b128 v[228:231], v245 offset:55360
	v_mfma_f32_16x16x32_bf16 v[30:33], v[224:227], v[236:239], v[30:33]
	ds_read_b128 v[236:239], v245 offset:57664
	v_mfma_f32_16x16x32_bf16 v[10:13], v[224:227], v[240:243], v[10:13]
	ds_read_b128 v[240:243], v245 offset:59968
	v_mfma_f32_16x16x32_bf16 v[14:17], v[224:227], v[252:255], v[14:17]
	ds_read_b128 v[252:255], v245 offset:62272
	ds_read_b128 v[224:227], v244 offset:25408
	s_waitcnt lgkmcnt(4)
	v_mfma_f32_16x16x32_bf16 v[50:53], v[212:215], v[228:231], v[50:53]
	s_waitcnt lgkmcnt(3)
	v_mfma_f32_16x16x32_bf16 v[54:57], v[212:215], v[236:239], v[54:57]
	s_waitcnt lgkmcnt(2)
	v_mfma_f32_16x16x32_bf16 v[34:37], v[212:215], v[240:243], v[34:37]
	s_waitcnt lgkmcnt(1)
	v_mfma_f32_16x16x32_bf16 v[38:41], v[212:215], v[252:255], v[38:41]
	v_mfma_f32_16x16x32_bf16 v[58:61], v[216:219], v[228:231], v[58:61]
	v_mfma_f32_16x16x32_bf16 v[62:65], v[216:219], v[236:239], v[62:65]
	v_mfma_f32_16x16x32_bf16 v[42:45], v[216:219], v[240:243], v[42:45]
	v_mfma_f32_16x16x32_bf16 v[46:49], v[216:219], v[252:255], v[46:49]
	v_mfma_f32_16x16x32_bf16 v[18:21], v[220:223], v[228:231], v[18:21]
	v_mfma_f32_16x16x32_bf16 v[22:25], v[220:223], v[236:239], v[22:25]
	v_mfma_f32_16x16x32_bf16 v[2:5], v[220:223], v[240:243], v[2:5]
	v_mfma_f32_16x16x32_bf16 v[6:9], v[220:223], v[252:255], v[6:9]
	s_waitcnt lgkmcnt(0)
	v_mfma_f32_16x16x32_bf16 v[26:29], v[224:227], v[228:231], v[26:29]
	v_mfma_f32_16x16x32_bf16 v[30:33], v[224:227], v[236:239], v[30:33]
	v_mfma_f32_16x16x32_bf16 v[10:13], v[224:227], v[240:243], v[10:13]
	v_mfma_f32_16x16x32_bf16 v[14:17], v[224:227], v[252:255], v[14:17]
	s_waitcnt lgkmcnt(0)
	s_barrier
	s_nop 7
	v_permlane16_swap_b32_e32 v50, v54
	v_permlane16_swap_b32_e32 v51, v55
	v_permlane16_swap_b32_e32 v52, v56
	v_permlane16_swap_b32_e32 v53, v57
	v_permlane16_swap_b32_e32 v58, v62
	v_permlane16_swap_b32_e32 v59, v63
	v_permlane16_swap_b32_e32 v60, v64
	v_permlane16_swap_b32_e32 v61, v65
	v_permlane16_swap_b32_e32 v34, v38
	v_permlane16_swap_b32_e32 v35, v39
	v_permlane16_swap_b32_e32 v36, v40
	v_permlane16_swap_b32_e32 v37, v41
	v_permlane16_swap_b32_e32 v42, v46
	v_permlane16_swap_b32_e32 v43, v47
	v_permlane16_swap_b32_e32 v44, v48
	v_permlane16_swap_b32_e32 v45, v49
	v_permlane16_swap_b32_e32 v18, v22
	v_permlane16_swap_b32_e32 v19, v23
	v_permlane16_swap_b32_e32 v20, v24
	v_permlane16_swap_b32_e32 v21, v25
	v_permlane16_swap_b32_e32 v26, v30
	v_permlane16_swap_b32_e32 v27, v31
	v_permlane16_swap_b32_e32 v28, v32
	v_permlane16_swap_b32_e32 v29, v33
	v_permlane16_swap_b32_e32 v2, v6
	v_permlane16_swap_b32_e32 v3, v7
	v_permlane16_swap_b32_e32 v4, v8
	v_permlane16_swap_b32_e32 v5, v9
	v_permlane16_swap_b32_e32 v10, v14
	v_permlane16_swap_b32_e32 v11, v15
	v_permlane16_swap_b32_e32 v12, v16
	v_permlane16_swap_b32_e32 v13, v17
	v_permlane32_swap_b32_e32 v50, v54
	v_permlane32_swap_b32_e32 v51, v55
	v_permlane32_swap_b32_e32 v52, v56
	v_permlane32_swap_b32_e32 v53, v57
	v_permlane32_swap_b32_e32 v58, v62
	v_permlane32_swap_b32_e32 v59, v63
	v_permlane32_swap_b32_e32 v60, v64
	v_permlane32_swap_b32_e32 v61, v65
	v_permlane32_swap_b32_e32 v34, v38
	v_permlane32_swap_b32_e32 v35, v39
	v_permlane32_swap_b32_e32 v36, v40
	v_permlane32_swap_b32_e32 v37, v41
	v_permlane32_swap_b32_e32 v42, v46
	v_permlane32_swap_b32_e32 v43, v47
	v_permlane32_swap_b32_e32 v44, v48
	v_permlane32_swap_b32_e32 v45, v49
	v_permlane32_swap_b32_e32 v18, v22
	v_permlane32_swap_b32_e32 v19, v23
	v_permlane32_swap_b32_e32 v20, v24
	v_permlane32_swap_b32_e32 v21, v25
	v_permlane32_swap_b32_e32 v26, v30
	v_permlane32_swap_b32_e32 v27, v31
	v_permlane32_swap_b32_e32 v28, v32
	v_permlane32_swap_b32_e32 v29, v33
	v_permlane32_swap_b32_e32 v2, v6
	v_permlane32_swap_b32_e32 v3, v7
	v_permlane32_swap_b32_e32 v4, v8
	v_permlane32_swap_b32_e32 v5, v9
	v_permlane32_swap_b32_e32 v10, v14
	v_permlane32_swap_b32_e32 v11, v15
	v_permlane32_swap_b32_e32 v12, v16
	v_permlane32_swap_b32_e32 v13, v17

.LBB0_749:
	s_and_b32 s3, s2, 0xffff
	s_mul_i32 s3, s3, 0xaaab
	s_lshr_b32 s3, s3, 18
	s_mul_i32 s10, s3, 6
	s_sub_i32 s2, s2, s10
	s_and_b32 s2, s2, 0xffff
	s_add_i32 s2, s6, s2
	s_lshl_b32 s10, s2, 7
	v_or_b32_e32 v2, s10, v91
	v_lshlrev_b32_e32 v66, 11, v2
	v_lshl_add_u64 v[74:75], v[68:69], 0, v[66:67]
	v_add_lshl_u32 v66, s10, v92, 11
	s_add_i32 s3, s8, s3
	v_lshl_add_u64 v[76:77], v[68:69], 0, v[66:67]
	v_add_lshl_u32 v66, s10, v93, 11
	s_lshl_b32 s11, s3, 7
	v_lshl_add_u64 v[78:79], v[68:69], 0, v[66:67]
	v_add_lshl_u32 v66, s10, v94, 11
	v_lshl_add_u64 v[80:81], v[68:69], 0, v[66:67]
	v_or_b32_e32 v66, s11, v91
	v_lshlrev_b64 v[2:3], 11, v[66:67]
	v_add_u32_e32 v66, s11, v92
	v_lshl_add_u64 v[82:83], v[70:71], 0, v[2:3]
	v_lshlrev_b64 v[2:3], 11, v[66:67]
	v_add_u32_e32 v66, s11, v93
	v_lshl_add_u64 v[84:85], v[70:71], 0, v[2:3]
	v_lshlrev_b64 v[2:3], 11, v[66:67]
	v_add_u32_e32 v66, s11, v94
	v_lshl_add_u64 v[86:87], v[70:71], 0, v[2:3]
	v_lshlrev_b64 v[2:3], 11, v[66:67]
	v_lshl_add_u64 v[88:89], v[70:71], 0, v[2:3]
	global_load_dwordx4 v[2:5], v[74:75], off
	global_load_dwordx4 v[6:9], v[76:77], off
	global_load_dwordx4 v[10:13], v[78:79], off
	global_load_dwordx4 v[14:17], v[80:81], off
	global_load_dwordx4 v[18:21], v[82:83], off
	global_load_dwordx4 v[22:25], v[84:85], off
	global_load_dwordx4 v[26:29], v[86:87], off
	global_load_dwordx4 v[30:33], v[88:89], off
	global_load_dwordx4 v[102:105], v[74:75], off offset:128
	global_load_dwordx4 v[106:109], v[76:77], off offset:128
	global_load_dwordx4 v[110:113], v[78:79], off offset:128
	global_load_dwordx4 v[114:117], v[80:81], off offset:128
	global_load_dwordx4 v[118:121], v[82:83], off offset:128
	global_load_dwordx4 v[122:125], v[84:85], off offset:128
	global_load_dwordx4 v[126:129], v[86:87], off offset:128
	global_load_dwordx4 v[136:139], v[88:89], off offset:128
	s_waitcnt vmcnt(15)
	ds_write_b128 v98, v[2:5]
	s_waitcnt vmcnt(14)
	ds_write_b128 v98, v[6:9] offset:4608
	s_waitcnt vmcnt(13)
	ds_write_b128 v98, v[10:13] offset:9216
	s_waitcnt vmcnt(12)
	ds_write_b128 v98, v[14:17] offset:13824
	s_waitcnt vmcnt(11)
	ds_write_b128 v98, v[18:21] offset:36864
	s_waitcnt vmcnt(10)
	ds_write_b128 v98, v[22:25] offset:41472
	s_waitcnt vmcnt(9)
	ds_write_b128 v98, v[26:29] offset:46080
	s_waitcnt vmcnt(8)
	ds_write_b128 v98, v[30:33] offset:50688
	s_waitcnt lgkmcnt(0)
	s_barrier
	global_load_dwordx4 v[140:143], v[74:75], off offset:256
	global_load_dwordx4 v[144:147], v[76:77], off offset:256
	global_load_dwordx4 v[148:151], v[78:79], off offset:256
	global_load_dwordx4 v[152:155], v[80:81], off offset:256
	global_load_dwordx4 v[156:159], v[82:83], off offset:256
	global_load_dwordx4 v[160:163], v[84:85], off offset:256
	global_load_dwordx4 v[164:167], v[86:87], off offset:256
	global_load_dwordx4 v[168:171], v[88:89], off offset:256
	v_and_b32_e32 v246, 15, v1
	v_add_u32_e32 v246, 4, v246
	v_bfe_u32 v246, v246, 3, 1
	v_bfe_u32 v249, v1, 4, 2
	v_xor_b32_e32 v246, v246, v249
	v_bfe_u32 v249, v1, 5, 1
	v_sub_u32_e32 v246, v246, v249
	v_lshlrev_b32_e32 v246, 4, v246
	v_bfe_u32 v249, v1, 4, 1
	v_mul_u32_u24_e32 v249, 0x900, v249
	v_sub_u32_e32 v246, v246, v249
	v_add_u32_e32 v244, v246, v96
	v_add_u32_e32 v245, v246, v97
	ds_read_b128 v[212:215], v245 offset:36864
	ds_read_b128 v[196:199], v244
	ds_read_b128 v[216:219], v245 offset:39168
	ds_read_b128 v[220:223], v245 offset:41472
	ds_read_b128 v[224:227], v245 offset:43776
	ds_read_b128 v[200:203], v244 offset:2304
	ds_read_b128 v[204:207], v244 offset:4608
	ds_read_b128 v[208:211], v244 offset:6912
	s_waitcnt lgkmcnt(6)
	v_mfma_f32_16x16x32_bf16 v[50:53], v[196:199], v[212:215], 0
	ds_read_b128 v[228:231], v245 offset:36928
	s_waitcnt lgkmcnt(6)
	v_mfma_f32_16x16x32_bf16 v[54:57], v[196:199], v[216:219], 0
	ds_read_b128 v[232:235], v245 offset:39232
	s_waitcnt lgkmcnt(6)
	v_mfma_f32_16x16x32_bf16 v[18:21], v[196:199], v[220:223], 0
	ds_read_b128 v[236:239], v245 offset:41536
	s_waitcnt lgkmcnt(6)
	v_mfma_f32_16x16x32_bf16 v[22:25], v[196:199], v[224:227], 0
	ds_read_b128 v[240:243], v245 offset:43840
	ds_read_b128 v[196:199], v244 offset:64
	s_waitcnt lgkmcnt(7)
	v_mfma_f32_16x16x32_bf16 v[58:61], v[200:203], v[212:215], 0
	v_mfma_f32_16x16x32_bf16 v[62:65], v[200:203], v[216:219], 0
	v_mfma_f32_16x16x32_bf16 v[26:29], v[200:203], v[220:223], 0
	v_mfma_f32_16x16x32_bf16 v[30:33], v[200:203], v[224:227], 0
	ds_read_b128 v[200:203], v244 offset:2368
	s_waitcnt lgkmcnt(7)
	v_mfma_f32_16x16x32_bf16 v[34:37], v[204:207], v[212:215], 0
	v_mfma_f32_16x16x32_bf16 v[38:41], v[204:207], v[216:219], 0
	v_mfma_f32_16x16x32_bf16 v[2:5], v[204:207], v[220:223], 0
	v_mfma_f32_16x16x32_bf16 v[6:9], v[204:207], v[224:227], 0
	ds_read_b128 v[204:207], v244 offset:4672
	s_setprio 1
	s_waitcnt vmcnt(15)
	ds_write_b128 v98, v[102:105] offset:18432
	s_waitcnt vmcnt(14)
	ds_write_b128 v98, v[106:109] offset:23040
	s_waitcnt lgkmcnt(9)
	v_mfma_f32_16x16x32_bf16 v[42:45], v[208:211], v[212:215], 0
	v_mfma_f32_16x16x32_bf16 v[46:49], v[208:211], v[216:219], 0
	v_mfma_f32_16x16x32_bf16 v[10:13], v[208:211], v[220:223], 0
	v_mfma_f32_16x16x32_bf16 v[14:17], v[208:211], v[224:227], 0
	ds_read_b128 v[208:211], v244 offset:6976
	s_waitcnt vmcnt(13)
	ds_write_b128 v98, v[110:113] offset:27648
	s_waitcnt vmcnt(12)
	ds_write_b128 v98, v[114:117] offset:32256
	s_waitcnt lgkmcnt(7)
	v_mfma_f32_16x16x32_bf16 v[50:53], v[196:199], v[228:231], v[50:53]
	v_mfma_f32_16x16x32_bf16 v[54:57], v[196:199], v[232:235], v[54:57]
	v_mfma_f32_16x16x32_bf16 v[18:21], v[196:199], v[236:239], v[18:21]
	v_mfma_f32_16x16x32_bf16 v[22:25], v[196:199], v[240:243], v[22:25]
	s_waitcnt vmcnt(11)
	ds_write_b128 v98, v[118:121] offset:55296
	s_waitcnt vmcnt(10)
	ds_write_b128 v98, v[122:125] offset:59904
	s_waitcnt lgkmcnt(8)
	v_mfma_f32_16x16x32_bf16 v[58:61], v[200:203], v[228:231], v[58:61]
	v_mfma_f32_16x16x32_bf16 v[62:65], v[200:203], v[232:235], v[62:65]
	v_mfma_f32_16x16x32_bf16 v[26:29], v[200:203], v[236:239], v[26:29]
	v_mfma_f32_16x16x32_bf16 v[30:33], v[200:203], v[240:243], v[30:33]
	s_waitcnt vmcnt(9)
	ds_write_b128 v98, v[126:129] offset:64512
	s_waitcnt vmcnt(8)
	ds_write_b128 v99, v[136:139] offset:32256
	s_waitcnt lgkmcnt(0)
	s_barrier
	ds_read_b128 v[212:215], v245 offset:55296
	ds_read_b128 v[196:199], v244 offset:18432
	ds_read_b128 v[216:219], v245 offset:57600
	ds_read_b128 v[220:223], v245 offset:59904
	ds_read_b128 v[224:227], v245 offset:62208
	ds_read_b128 v[200:203], v244 offset:20736
	s_setprio 0
	v_mfma_f32_16x16x32_bf16 v[34:37], v[204:207], v[228:231], v[34:37]
	v_mfma_f32_16x16x32_bf16 v[38:41], v[204:207], v[232:235], v[38:41]
	v_mfma_f32_16x16x32_bf16 v[2:5], v[204:207], v[236:239], v[2:5]
	v_mfma_f32_16x16x32_bf16 v[6:9], v[204:207], v[240:243], v[6:9]
	ds_read_b128 v[204:207], v244 offset:23040
	v_mfma_f32_16x16x32_bf16 v[42:45], v[208:211], v[228:231], v[42:45]
	v_mfma_f32_16x16x32_bf16 v[46:49], v[208:211], v[232:235], v[46:49]
	v_mfma_f32_16x16x32_bf16 v[10:13], v[208:211], v[236:239], v[10:13]
	v_mfma_f32_16x16x32_bf16 v[14:17], v[208:211], v[240:243], v[14:17]
	ds_read_b128 v[208:211], v244 offset:25344
	global_load_dwordx4 v[102:105], v[74:75], off offset:384
	global_load_dwordx4 v[106:109], v[76:77], off offset:384
	global_load_dwordx4 v[110:113], v[78:79], off offset:384
	global_load_dwordx4 v[114:117], v[80:81], off offset:384
	global_load_dwordx4 v[118:121], v[82:83], off offset:384
	global_load_dwordx4 v[122:125], v[84:85], off offset:384
	global_load_dwordx4 v[126:129], v[86:87], off offset:384
	global_load_dwordx4 v[136:139], v[88:89], off offset:384
	s_waitcnt lgkmcnt(6)
	v_mfma_f32_16x16x32_bf16 v[50:53], v[196:199], v[212:215], v[50:53]
	ds_read_b128 v[228:231], v245 offset:55360
	s_waitcnt lgkmcnt(6)
	v_mfma_f32_16x16x32_bf16 v[54:57], v[196:199], v[216:219], v[54:57]
	ds_read_b128 v[232:235], v245 offset:57664
	s_waitcnt lgkmcnt(6)
	v_mfma_f32_16x16x32_bf16 v[18:21], v[196:199], v[220:223], v[18:21]
	ds_read_b128 v[236:239], v245 offset:59968
	s_waitcnt lgkmcnt(6)
	v_mfma_f32_16x16x32_bf16 v[22:25], v[196:199], v[224:227], v[22:25]
	ds_read_b128 v[240:243], v245 offset:62272
	ds_read_b128 v[196:199], v244 offset:18496
	s_waitcnt lgkmcnt(7)
	v_mfma_f32_16x16x32_bf16 v[58:61], v[200:203], v[212:215], v[58:61]
	v_mfma_f32_16x16x32_bf16 v[62:65], v[200:203], v[216:219], v[62:65]
	v_mfma_f32_16x16x32_bf16 v[26:29], v[200:203], v[220:223], v[26:29]
	v_mfma_f32_16x16x32_bf16 v[30:33], v[200:203], v[224:227], v[30:33]
	ds_read_b128 v[200:203], v244 offset:20800
	s_waitcnt lgkmcnt(7)
	v_mfma_f32_16x16x32_bf16 v[34:37], v[204:207], v[212:215], v[34:37]
	v_mfma_f32_16x16x32_bf16 v[38:41], v[204:207], v[216:219], v[38:41]
	v_mfma_f32_16x16x32_bf16 v[2:5], v[204:207], v[220:223], v[2:5]
	v_mfma_f32_16x16x32_bf16 v[6:9], v[204:207], v[224:227], v[6:9]
	ds_read_b128 v[204:207], v244 offset:23104
	s_setprio 1
	s_waitcnt vmcnt(15)
	ds_write_b128 v98, v[140:143]
	s_waitcnt vmcnt(14)
	ds_write_b128 v98, v[144:147] offset:4608
	s_waitcnt lgkmcnt(9)
	v_mfma_f32_16x16x32_bf16 v[42:45], v[208:211], v[212:215], v[42:45]
	v_mfma_f32_16x16x32_bf16 v[46:49], v[208:211], v[216:219], v[46:49]
	v_mfma_f32_16x16x32_bf16 v[10:13], v[208:211], v[220:223], v[10:13]
	v_mfma_f32_16x16x32_bf16 v[14:17], v[208:211], v[224:227], v[14:17]
	ds_read_b128 v[208:211], v244 offset:25408
	s_waitcnt vmcnt(13)
	ds_write_b128 v98, v[148:151] offset:9216
	s_waitcnt vmcnt(12)
	ds_write_b128 v98, v[152:155] offset:13824
	s_waitcnt lgkmcnt(7)
	v_mfma_f32_16x16x32_bf16 v[50:53], v[196:199], v[228:231], v[50:53]
	v_mfma_f32_16x16x32_bf16 v[54:57], v[196:199], v[232:235], v[54:57]
	v_mfma_f32_16x16x32_bf16 v[18:21], v[196:199], v[236:239], v[18:21]
	v_mfma_f32_16x16x32_bf16 v[22:25], v[196:199], v[240:243], v[22:25]
	s_waitcnt vmcnt(11)
	ds_write_b128 v98, v[156:159] offset:36864
	s_waitcnt vmcnt(10)
	ds_write_b128 v98, v[160:163] offset:41472
	s_waitcnt lgkmcnt(8)
	v_mfma_f32_16x16x32_bf16 v[58:61], v[200:203], v[228:231], v[58:61]
	v_mfma_f32_16x16x32_bf16 v[62:65], v[200:203], v[232:235], v[62:65]
	v_mfma_f32_16x16x32_bf16 v[26:29], v[200:203], v[236:239], v[26:29]
	v_mfma_f32_16x16x32_bf16 v[30:33], v[200:203], v[240:243], v[30:33]
	s_waitcnt vmcnt(9)
	ds_write_b128 v98, v[164:167] offset:46080
	s_waitcnt vmcnt(8)
	ds_write_b128 v98, v[168:171] offset:50688
	s_waitcnt lgkmcnt(0)
	s_barrier
	ds_read_b128 v[212:215], v245 offset:36864
	ds_read_b128 v[196:199], v244
	ds_read_b128 v[216:219], v245 offset:39168
	ds_read_b128 v[220:223], v245 offset:41472
	ds_read_b128 v[224:227], v245 offset:43776
	ds_read_b128 v[200:203], v244 offset:2304
	s_setprio 0
	v_mfma_f32_16x16x32_bf16 v[34:37], v[204:207], v[228:231], v[34:37]
	v_mfma_f32_16x16x32_bf16 v[38:41], v[204:207], v[232:235], v[38:41]
	v_mfma_f32_16x16x32_bf16 v[2:5], v[204:207], v[236:239], v[2:5]
	v_mfma_f32_16x16x32_bf16 v[6:9], v[204:207], v[240:243], v[6:9]
	ds_read_b128 v[204:207], v244 offset:4608
	v_mfma_f32_16x16x32_bf16 v[42:45], v[208:211], v[228:231], v[42:45]
	v_mfma_f32_16x16x32_bf16 v[46:49], v[208:211], v[232:235], v[46:49]
	v_mfma_f32_16x16x32_bf16 v[10:13], v[208:211], v[236:239], v[10:13]
	v_mfma_f32_16x16x32_bf16 v[14:17], v[208:211], v[240:243], v[14:17]
	ds_read_b128 v[208:211], v244 offset:6912
	global_load_dwordx4 v[140:143], v[74:75], off offset:512
	global_load_dwordx4 v[144:147], v[76:77], off offset:512
	global_load_dwordx4 v[148:151], v[78:79], off offset:512
	global_load_dwordx4 v[152:155], v[80:81], off offset:512
	global_load_dwordx4 v[156:159], v[82:83], off offset:512
	global_load_dwordx4 v[160:163], v[84:85], off offset:512
	global_load_dwordx4 v[164:167], v[86:87], off offset:512
	global_load_dwordx4 v[168:171], v[88:89], off offset:512
	s_waitcnt lgkmcnt(6)
	v_mfma_f32_16x16x32_bf16 v[50:53], v[196:199], v[212:215], v[50:53]
	ds_read_b128 v[228:231], v245 offset:36928
	s_waitcnt lgkmcnt(6)
	v_mfma_f32_16x16x32_bf16 v[54:57], v[196:199], v[216:219], v[54:57]
	ds_read_b128 v[232:235], v245 offset:39232
	s_waitcnt lgkmcnt(6)
	v_mfma_f32_16x16x32_bf16 v[18:21], v[196:199], v[220:223], v[18:21]
	ds_read_b128 v[236:239], v245 offset:41536
	s_waitcnt lgkmcnt(6)
	v_mfma_f32_16x16x32_bf16 v[22:25], v[196:199], v[224:227], v[22:25]
	ds_read_b128 v[240:243], v245 offset:43840
	ds_read_b128 v[196:199], v244 offset:64
	s_waitcnt lgkmcnt(7)
	v_mfma_f32_16x16x32_bf16 v[58:61], v[200:203], v[212:215], v[58:61]
	v_mfma_f32_16x16x32_bf16 v[62:65], v[200:203], v[216:219], v[62:65]
	v_mfma_f32_16x16x32_bf16 v[26:29], v[200:203], v[220:223], v[26:29]
	v_mfma_f32_16x16x32_bf16 v[30:33], v[200:203], v[224:227], v[30:33]
	ds_read_b128 v[200:203], v244 offset:2368
	s_waitcnt lgkmcnt(7)
	v_mfma_f32_16x16x32_bf16 v[34:37], v[204:207], v[212:215], v[34:37]
	v_mfma_f32_16x16x32_bf16 v[38:41], v[204:207], v[216:219], v[38:41]
	v_mfma_f32_16x16x32_bf16 v[2:5], v[204:207], v[220:223], v[2:5]
	v_mfma_f32_16x16x32_bf16 v[6:9], v[204:207], v[224:227], v[6:9]
	ds_read_b128 v[204:207], v244 offset:4672
	s_setprio 1
	s_waitcnt vmcnt(15)
	ds_write_b128 v98, v[102:105] offset:18432
	s_waitcnt vmcnt(14)
	ds_write_b128 v98, v[106:109] offset:23040
	s_waitcnt lgkmcnt(9)
	v_mfma_f32_16x16x32_bf16 v[42:45], v[208:211], v[212:215], v[42:45]
	v_mfma_f32_16x16x32_bf16 v[46:49], v[208:211], v[216:219], v[46:49]
	v_mfma_f32_16x16x32_bf16 v[10:13], v[208:211], v[220:223], v[10:13]
	v_mfma_f32_16x16x32_bf16 v[14:17], v[208:211], v[224:227], v[14:17]
	ds_read_b128 v[208:211], v244 offset:6976
	s_waitcnt vmcnt(13)
	ds_write_b128 v98, v[110:113] offset:27648
	s_waitcnt vmcnt(12)
	ds_write_b128 v98, v[114:117] offset:32256
	s_waitcnt lgkmcnt(7)
	v_mfma_f32_16x16x32_bf16 v[50:53], v[196:199], v[228:231], v[50:53]
	v_mfma_f32_16x16x32_bf16 v[54:57], v[196:199], v[232:235], v[54:57]
	v_mfma_f32_16x16x32_bf16 v[18:21], v[196:199], v[236:239], v[18:21]
	v_mfma_f32_16x16x32_bf16 v[22:25], v[196:199], v[240:243], v[22:25]
	s_waitcnt vmcnt(11)
	ds_write_b128 v98, v[118:121] offset:55296
	s_waitcnt vmcnt(10)
	ds_write_b128 v98, v[122:125] offset:59904
	s_waitcnt lgkmcnt(8)
	v_mfma_f32_16x16x32_bf16 v[58:61], v[200:203], v[228:231], v[58:61]
	v_mfma_f32_16x16x32_bf16 v[62:65], v[200:203], v[232:235], v[62:65]
	v_mfma_f32_16x16x32_bf16 v[26:29], v[200:203], v[236:239], v[26:29]
	v_mfma_f32_16x16x32_bf16 v[30:33], v[200:203], v[240:243], v[30:33]
	s_waitcnt vmcnt(9)
	ds_write_b128 v98, v[126:129] offset:64512
	s_waitcnt vmcnt(8)
	ds_write_b128 v99, v[136:139] offset:32256
	s_waitcnt lgkmcnt(0)
	s_barrier
	ds_read_b128 v[212:215], v245 offset:55296
	ds_read_b128 v[196:199], v244 offset:18432
	ds_read_b128 v[216:219], v245 offset:57600
	ds_read_b128 v[220:223], v245 offset:59904
	ds_read_b128 v[224:227], v245 offset:62208
	ds_read_b128 v[200:203], v244 offset:20736
	s_setprio 0
	v_mfma_f32_16x16x32_bf16 v[34:37], v[204:207], v[228:231], v[34:37]
	v_mfma_f32_16x16x32_bf16 v[38:41], v[204:207], v[232:235], v[38:41]
	v_mfma_f32_16x16x32_bf16 v[2:5], v[204:207], v[236:239], v[2:5]
	v_mfma_f32_16x16x32_bf16 v[6:9], v[204:207], v[240:243], v[6:9]
	ds_read_b128 v[204:207], v244 offset:23040
	v_mfma_f32_16x16x32_bf16 v[42:45], v[208:211], v[228:231], v[42:45]
	v_mfma_f32_16x16x32_bf16 v[46:49], v[208:211], v[232:235], v[46:49]
	v_mfma_f32_16x16x32_bf16 v[10:13], v[208:211], v[236:239], v[10:13]
	v_mfma_f32_16x16x32_bf16 v[14:17], v[208:211], v[240:243], v[14:17]
	ds_read_b128 v[208:211], v244 offset:25344
	global_load_dwordx4 v[102:105], v[74:75], off offset:640
	global_load_dwordx4 v[106:109], v[76:77], off offset:640
	global_load_dwordx4 v[110:113], v[78:79], off offset:640
	global_load_dwordx4 v[114:117], v[80:81], off offset:640
	global_load_dwordx4 v[118:121], v[82:83], off offset:640
	global_load_dwordx4 v[122:125], v[84:85], off offset:640
	global_load_dwordx4 v[126:129], v[86:87], off offset:640
	global_load_dwordx4 v[136:139], v[88:89], off offset:640
	s_waitcnt lgkmcnt(6)
	v_mfma_f32_16x16x32_bf16 v[50:53], v[196:199], v[212:215], v[50:53]
	ds_read_b128 v[228:231], v245 offset:55360
	s_waitcnt lgkmcnt(6)
	v_mfma_f32_16x16x32_bf16 v[54:57], v[196:199], v[216:219], v[54:57]
	ds_read_b128 v[232:235], v245 offset:57664
	s_waitcnt lgkmcnt(6)
	v_mfma_f32_16x16x32_bf16 v[18:21], v[196:199], v[220:223], v[18:21]
	ds_read_b128 v[236:239], v245 offset:59968
	s_waitcnt lgkmcnt(6)
	v_mfma_f32_16x16x32_bf16 v[22:25], v[196:199], v[224:227], v[22:25]
	ds_read_b128 v[240:243], v245 offset:62272
	ds_read_b128 v[196:199], v244 offset:18496
	s_waitcnt lgkmcnt(7)
	v_mfma_f32_16x16x32_bf16 v[58:61], v[200:203], v[212:215], v[58:61]
	v_mfma_f32_16x16x32_bf16 v[62:65], v[200:203], v[216:219], v[62:65]
	v_mfma_f32_16x16x32_bf16 v[26:29], v[200:203], v[220:223], v[26:29]
	v_mfma_f32_16x16x32_bf16 v[30:33], v[200:203], v[224:227], v[30:33]
	ds_read_b128 v[200:203], v244 offset:20800
	s_waitcnt lgkmcnt(7)
	v_mfma_f32_16x16x32_bf16 v[34:37], v[204:207], v[212:215], v[34:37]
	v_mfma_f32_16x16x32_bf16 v[38:41], v[204:207], v[216:219], v[38:41]
	v_mfma_f32_16x16x32_bf16 v[2:5], v[204:207], v[220:223], v[2:5]
	v_mfma_f32_16x16x32_bf16 v[6:9], v[204:207], v[224:227], v[6:9]
	ds_read_b128 v[204:207], v244 offset:23104
	s_setprio 1
	s_waitcnt vmcnt(15)
	ds_write_b128 v98, v[140:143]
	s_waitcnt vmcnt(14)
	ds_write_b128 v98, v[144:147] offset:4608
	s_waitcnt lgkmcnt(9)
	v_mfma_f32_16x16x32_bf16 v[42:45], v[208:211], v[212:215], v[42:45]
	v_mfma_f32_16x16x32_bf16 v[46:49], v[208:211], v[216:219], v[46:49]
	v_mfma_f32_16x16x32_bf16 v[10:13], v[208:211], v[220:223], v[10:13]
	v_mfma_f32_16x16x32_bf16 v[14:17], v[208:211], v[224:227], v[14:17]
	ds_read_b128 v[208:211], v244 offset:25408
	s_waitcnt vmcnt(13)
	ds_write_b128 v98, v[148:151] offset:9216
	s_waitcnt vmcnt(12)
	ds_write_b128 v98, v[152:155] offset:13824
	s_waitcnt lgkmcnt(7)
	v_mfma_f32_16x16x32_bf16 v[50:53], v[196:199], v[228:231], v[50:53]
	v_mfma_f32_16x16x32_bf16 v[54:57], v[196:199], v[232:235], v[54:57]
	v_mfma_f32_16x16x32_bf16 v[18:21], v[196:199], v[236:239], v[18:21]
	v_mfma_f32_16x16x32_bf16 v[22:25], v[196:199], v[240:243], v[22:25]
	s_waitcnt vmcnt(11)
	ds_write_b128 v98, v[156:159] offset:36864
	s_waitcnt vmcnt(10)
	ds_write_b128 v98, v[160:163] offset:41472
	s_waitcnt lgkmcnt(8)
	v_mfma_f32_16x16x32_bf16 v[58:61], v[200:203], v[228:231], v[58:61]
	v_mfma_f32_16x16x32_bf16 v[62:65], v[200:203], v[232:235], v[62:65]
	v_mfma_f32_16x16x32_bf16 v[26:29], v[200:203], v[236:239], v[26:29]
	v_mfma_f32_16x16x32_bf16 v[30:33], v[200:203], v[240:243], v[30:33]
	s_waitcnt vmcnt(9)
	ds_write_b128 v98, v[164:167] offset:46080
	s_waitcnt vmcnt(8)
	ds_write_b128 v98, v[168:171] offset:50688
	s_waitcnt lgkmcnt(0)
	s_barrier
	ds_read_b128 v[212:215], v245 offset:36864
	ds_read_b128 v[196:199], v244
	ds_read_b128 v[216:219], v245 offset:39168
	ds_read_b128 v[220:223], v245 offset:41472
	ds_read_b128 v[224:227], v245 offset:43776
	ds_read_b128 v[200:203], v244 offset:2304
	s_setprio 0
	v_mfma_f32_16x16x32_bf16 v[34:37], v[204:207], v[228:231], v[34:37]
	v_mfma_f32_16x16x32_bf16 v[38:41], v[204:207], v[232:235], v[38:41]
	v_mfma_f32_16x16x32_bf16 v[2:5], v[204:207], v[236:239], v[2:5]
	v_mfma_f32_16x16x32_bf16 v[6:9], v[204:207], v[240:243], v[6:9]
	ds_read_b128 v[204:207], v244 offset:4608
	v_mfma_f32_16x16x32_bf16 v[42:45], v[208:211], v[228:231], v[42:45]
	v_mfma_f32_16x16x32_bf16 v[46:49], v[208:211], v[232:235], v[46:49]
	v_mfma_f32_16x16x32_bf16 v[10:13], v[208:211], v[236:239], v[10:13]
	v_mfma_f32_16x16x32_bf16 v[14:17], v[208:211], v[240:243], v[14:17]
	ds_read_b128 v[208:211], v244 offset:6912
	global_load_dwordx4 v[140:143], v[74:75], off offset:768
	global_load_dwordx4 v[144:147], v[76:77], off offset:768
	global_load_dwordx4 v[148:151], v[78:79], off offset:768
	global_load_dwordx4 v[152:155], v[80:81], off offset:768
	global_load_dwordx4 v[156:159], v[82:83], off offset:768
	global_load_dwordx4 v[160:163], v[84:85], off offset:768
	global_load_dwordx4 v[164:167], v[86:87], off offset:768
	global_load_dwordx4 v[168:171], v[88:89], off offset:768
	s_waitcnt lgkmcnt(6)
	v_mfma_f32_16x16x32_bf16 v[50:53], v[196:199], v[212:215], v[50:53]
	ds_read_b128 v[228:231], v245 offset:36928
	s_waitcnt lgkmcnt(6)
	v_mfma_f32_16x16x32_bf16 v[54:57], v[196:199], v[216:219], v[54:57]
	ds_read_b128 v[232:235], v245 offset:39232
	s_waitcnt lgkmcnt(6)
	v_mfma_f32_16x16x32_bf16 v[18:21], v[196:199], v[220:223], v[18:21]
	ds_read_b128 v[236:239], v245 offset:41536
	s_waitcnt lgkmcnt(6)
	v_mfma_f32_16x16x32_bf16 v[22:25], v[196:199], v[224:227], v[22:25]
	ds_read_b128 v[240:243], v245 offset:43840
	ds_read_b128 v[196:199], v244 offset:64
	s_waitcnt lgkmcnt(7)
	v_mfma_f32_16x16x32_bf16 v[58:61], v[200:203], v[212:215], v[58:61]
	v_mfma_f32_16x16x32_bf16 v[62:65], v[200:203], v[216:219], v[62:65]
	v_mfma_f32_16x16x32_bf16 v[26:29], v[200:203], v[220:223], v[26:29]
	v_mfma_f32_16x16x32_bf16 v[30:33], v[200:203], v[224:227], v[30:33]
	ds_read_b128 v[200:203], v244 offset:2368
	s_waitcnt lgkmcnt(7)
	v_mfma_f32_16x16x32_bf16 v[34:37], v[204:207], v[212:215], v[34:37]
	v_mfma_f32_16x16x32_bf16 v[38:41], v[204:207], v[216:219], v[38:41]
	v_mfma_f32_16x16x32_bf16 v[2:5], v[204:207], v[220:223], v[2:5]
	v_mfma_f32_16x16x32_bf16 v[6:9], v[204:207], v[224:227], v[6:9]
	ds_read_b128 v[204:207], v244 offset:4672
	s_setprio 1
	s_waitcnt vmcnt(15)
	ds_write_b128 v98, v[102:105] offset:18432
	s_waitcnt vmcnt(14)
	ds_write_b128 v98, v[106:109] offset:23040
	s_waitcnt lgkmcnt(9)
	v_mfma_f32_16x16x32_bf16 v[42:45], v[208:211], v[212:215], v[42:45]
	v_mfma_f32_16x16x32_bf16 v[46:49], v[208:211], v[216:219], v[46:49]
	v_mfma_f32_16x16x32_bf16 v[10:13], v[208:211], v[220:223], v[10:13]
	v_mfma_f32_16x16x32_bf16 v[14:17], v[208:211], v[224:227], v[14:17]
	ds_read_b128 v[208:211], v244 offset:6976
	s_waitcnt vmcnt(13)
	ds_write_b128 v98, v[110:113] offset:27648
	s_waitcnt vmcnt(12)
	ds_write_b128 v98, v[114:117] offset:32256
	s_waitcnt lgkmcnt(7)
	v_mfma_f32_16x16x32_bf16 v[50:53], v[196:199], v[228:231], v[50:53]
	v_mfma_f32_16x16x32_bf16 v[54:57], v[196:199], v[232:235], v[54:57]
	v_mfma_f32_16x16x32_bf16 v[18:21], v[196:199], v[236:239], v[18:21]
	v_mfma_f32_16x16x32_bf16 v[22:25], v[196:199], v[240:243], v[22:25]
	s_waitcnt vmcnt(11)
	ds_write_b128 v98, v[118:121] offset:55296
	s_waitcnt vmcnt(10)
	ds_write_b128 v98, v[122:125] offset:59904
	s_waitcnt lgkmcnt(8)
	v_mfma_f32_16x16x32_bf16 v[58:61], v[200:203], v[228:231], v[58:61]
	v_mfma_f32_16x16x32_bf16 v[62:65], v[200:203], v[232:235], v[62:65]
	v_mfma_f32_16x16x32_bf16 v[26:29], v[200:203], v[236:239], v[26:29]
	v_mfma_f32_16x16x32_bf16 v[30:33], v[200:203], v[240:243], v[30:33]
	s_waitcnt vmcnt(9)
	ds_write_b128 v98, v[126:129] offset:64512
	s_waitcnt vmcnt(8)
	ds_write_b128 v99, v[136:139] offset:32256
	s_waitcnt lgkmcnt(0)
	s_barrier
	ds_read_b128 v[212:215], v245 offset:55296
	ds_read_b128 v[196:199], v244 offset:18432
	ds_read_b128 v[216:219], v245 offset:57600
	ds_read_b128 v[220:223], v245 offset:59904
	ds_read_b128 v[224:227], v245 offset:62208
	ds_read_b128 v[200:203], v244 offset:20736
	s_setprio 0
	v_mfma_f32_16x16x32_bf16 v[34:37], v[204:207], v[228:231], v[34:37]
	v_mfma_f32_16x16x32_bf16 v[38:41], v[204:207], v[232:235], v[38:41]
	v_mfma_f32_16x16x32_bf16 v[2:5], v[204:207], v[236:239], v[2:5]
	v_mfma_f32_16x16x32_bf16 v[6:9], v[204:207], v[240:243], v[6:9]
	ds_read_b128 v[204:207], v244 offset:23040
	v_mfma_f32_16x16x32_bf16 v[42:45], v[208:211], v[228:231], v[42:45]
	v_mfma_f32_16x16x32_bf16 v[46:49], v[208:211], v[232:235], v[46:49]
	v_mfma_f32_16x16x32_bf16 v[10:13], v[208:211], v[236:239], v[10:13]
	v_mfma_f32_16x16x32_bf16 v[14:17], v[208:211], v[240:243], v[14:17]
	ds_read_b128 v[208:211], v244 offset:25344
	global_load_dwordx4 v[102:105], v[74:75], off offset:896
	global_load_dwordx4 v[106:109], v[76:77], off offset:896
	global_load_dwordx4 v[110:113], v[78:79], off offset:896
	global_load_dwordx4 v[114:117], v[80:81], off offset:896
	global_load_dwordx4 v[118:121], v[82:83], off offset:896
	global_load_dwordx4 v[122:125], v[84:85], off offset:896
	global_load_dwordx4 v[126:129], v[86:87], off offset:896
	global_load_dwordx4 v[136:139], v[88:89], off offset:896
	s_waitcnt lgkmcnt(6)
	v_mfma_f32_16x16x32_bf16 v[50:53], v[196:199], v[212:215], v[50:53]
	ds_read_b128 v[228:231], v245 offset:55360
	s_waitcnt lgkmcnt(6)
	v_mfma_f32_16x16x32_bf16 v[54:57], v[196:199], v[216:219], v[54:57]
	ds_read_b128 v[232:235], v245 offset:57664
	s_waitcnt lgkmcnt(6)
	v_mfma_f32_16x16x32_bf16 v[18:21], v[196:199], v[220:223], v[18:21]
	ds_read_b128 v[236:239], v245 offset:59968
	s_waitcnt lgkmcnt(6)
	v_mfma_f32_16x16x32_bf16 v[22:25], v[196:199], v[224:227], v[22:25]
	ds_read_b128 v[240:243], v245 offset:62272
	ds_read_b128 v[196:199], v244 offset:18496
	s_waitcnt lgkmcnt(7)
	v_mfma_f32_16x16x32_bf16 v[58:61], v[200:203], v[212:215], v[58:61]
	v_mfma_f32_16x16x32_bf16 v[62:65], v[200:203], v[216:219], v[62:65]
	v_mfma_f32_16x16x32_bf16 v[26:29], v[200:203], v[220:223], v[26:29]
	v_mfma_f32_16x16x32_bf16 v[30:33], v[200:203], v[224:227], v[30:33]
	ds_read_b128 v[200:203], v244 offset:20800
	s_waitcnt lgkmcnt(7)
	v_mfma_f32_16x16x32_bf16 v[34:37], v[204:207], v[212:215], v[34:37]
	v_mfma_f32_16x16x32_bf16 v[38:41], v[204:207], v[216:219], v[38:41]
	v_mfma_f32_16x16x32_bf16 v[2:5], v[204:207], v[220:223], v[2:5]
	v_mfma_f32_16x16x32_bf16 v[6:9], v[204:207], v[224:227], v[6:9]
	ds_read_b128 v[204:207], v244 offset:23104
	s_setprio 1
	s_waitcnt vmcnt(15)
	ds_write_b128 v98, v[140:143]
	s_waitcnt vmcnt(14)
	ds_write_b128 v98, v[144:147] offset:4608
	s_waitcnt lgkmcnt(9)
	v_mfma_f32_16x16x32_bf16 v[42:45], v[208:211], v[212:215], v[42:45]
	v_mfma_f32_16x16x32_bf16 v[46:49], v[208:211], v[216:219], v[46:49]
	v_mfma_f32_16x16x32_bf16 v[10:13], v[208:211], v[220:223], v[10:13]
	v_mfma_f32_16x16x32_bf16 v[14:17], v[208:211], v[224:227], v[14:17]
	ds_read_b128 v[208:211], v244 offset:25408
	s_waitcnt vmcnt(13)
	ds_write_b128 v98, v[148:151] offset:9216
	s_waitcnt vmcnt(12)
	ds_write_b128 v98, v[152:155] offset:13824
	s_waitcnt lgkmcnt(7)
	v_mfma_f32_16x16x32_bf16 v[50:53], v[196:199], v[228:231], v[50:53]
	v_mfma_f32_16x16x32_bf16 v[54:57], v[196:199], v[232:235], v[54:57]
	v_mfma_f32_16x16x32_bf16 v[18:21], v[196:199], v[236:239], v[18:21]
	v_mfma_f32_16x16x32_bf16 v[22:25], v[196:199], v[240:243], v[22:25]
	s_waitcnt vmcnt(11)
	ds_write_b128 v98, v[156:159] offset:36864
	s_waitcnt vmcnt(10)
	ds_write_b128 v98, v[160:163] offset:41472
	s_waitcnt lgkmcnt(8)
	v_mfma_f32_16x16x32_bf16 v[58:61], v[200:203], v[228:231], v[58:61]
	v_mfma_f32_16x16x32_bf16 v[62:65], v[200:203], v[232:235], v[62:65]
	v_mfma_f32_16x16x32_bf16 v[26:29], v[200:203], v[236:239], v[26:29]
	v_mfma_f32_16x16x32_bf16 v[30:33], v[200:203], v[240:243], v[30:33]
	s_waitcnt vmcnt(9)
	ds_write_b128 v98, v[164:167] offset:46080
	s_waitcnt vmcnt(8)
	ds_write_b128 v98, v[168:171] offset:50688
	s_waitcnt lgkmcnt(0)
	s_barrier
	ds_read_b128 v[212:215], v245 offset:36864
	ds_read_b128 v[196:199], v244
	ds_read_b128 v[216:219], v245 offset:39168
	ds_read_b128 v[220:223], v245 offset:41472
	ds_read_b128 v[224:227], v245 offset:43776
	ds_read_b128 v[200:203], v244 offset:2304
	s_setprio 0
	v_mfma_f32_16x16x32_bf16 v[34:37], v[204:207], v[228:231], v[34:37]
	v_mfma_f32_16x16x32_bf16 v[38:41], v[204:207], v[232:235], v[38:41]
	v_mfma_f32_16x16x32_bf16 v[2:5], v[204:207], v[236:239], v[2:5]
	v_mfma_f32_16x16x32_bf16 v[6:9], v[204:207], v[240:243], v[6:9]
	ds_read_b128 v[204:207], v244 offset:4608
	v_mfma_f32_16x16x32_bf16 v[42:45], v[208:211], v[228:231], v[42:45]
	v_mfma_f32_16x16x32_bf16 v[46:49], v[208:211], v[232:235], v[46:49]
	v_mfma_f32_16x16x32_bf16 v[10:13], v[208:211], v[236:239], v[10:13]
	v_mfma_f32_16x16x32_bf16 v[14:17], v[208:211], v[240:243], v[14:17]
	ds_read_b128 v[208:211], v244 offset:6912
	global_load_dwordx4 v[140:143], v[74:75], off offset:1024
	global_load_dwordx4 v[144:147], v[76:77], off offset:1024
	global_load_dwordx4 v[148:151], v[78:79], off offset:1024
	global_load_dwordx4 v[152:155], v[80:81], off offset:1024
	global_load_dwordx4 v[156:159], v[82:83], off offset:1024
	global_load_dwordx4 v[160:163], v[84:85], off offset:1024
	global_load_dwordx4 v[164:167], v[86:87], off offset:1024
	global_load_dwordx4 v[168:171], v[88:89], off offset:1024
	s_waitcnt lgkmcnt(6)
	v_mfma_f32_16x16x32_bf16 v[50:53], v[196:199], v[212:215], v[50:53]
	ds_read_b128 v[228:231], v245 offset:36928
	s_waitcnt lgkmcnt(6)
	v_mfma_f32_16x16x32_bf16 v[54:57], v[196:199], v[216:219], v[54:57]
	ds_read_b128 v[232:235], v245 offset:39232
	s_waitcnt lgkmcnt(6)
	v_mfma_f32_16x16x32_bf16 v[18:21], v[196:199], v[220:223], v[18:21]
	ds_read_b128 v[236:239], v245 offset:41536
	s_waitcnt lgkmcnt(6)
	v_mfma_f32_16x16x32_bf16 v[22:25], v[196:199], v[224:227], v[22:25]
	ds_read_b128 v[240:243], v245 offset:43840
	ds_read_b128 v[196:199], v244 offset:64
	s_waitcnt lgkmcnt(7)
	v_mfma_f32_16x16x32_bf16 v[58:61], v[200:203], v[212:215], v[58:61]
	v_mfma_f32_16x16x32_bf16 v[62:65], v[200:203], v[216:219], v[62:65]
	v_mfma_f32_16x16x32_bf16 v[26:29], v[200:203], v[220:223], v[26:29]
	v_mfma_f32_16x16x32_bf16 v[30:33], v[200:203], v[224:227], v[30:33]
	ds_read_b128 v[200:203], v244 offset:2368
	s_waitcnt lgkmcnt(7)
	v_mfma_f32_16x16x32_bf16 v[34:37], v[204:207], v[212:215], v[34:37]
	v_mfma_f32_16x16x32_bf16 v[38:41], v[204:207], v[216:219], v[38:41]
	v_mfma_f32_16x16x32_bf16 v[2:5], v[204:207], v[220:223], v[2:5]
	v_mfma_f32_16x16x32_bf16 v[6:9], v[204:207], v[224:227], v[6:9]
	ds_read_b128 v[204:207], v244 offset:4672
	s_setprio 1
	s_waitcnt vmcnt(15)
	ds_write_b128 v98, v[102:105] offset:18432
	s_waitcnt vmcnt(14)
	ds_write_b128 v98, v[106:109] offset:23040
	s_waitcnt lgkmcnt(9)
	v_mfma_f32_16x16x32_bf16 v[42:45], v[208:211], v[212:215], v[42:45]
	v_mfma_f32_16x16x32_bf16 v[46:49], v[208:211], v[216:219], v[46:49]
	v_mfma_f32_16x16x32_bf16 v[10:13], v[208:211], v[220:223], v[10:13]
	v_mfma_f32_16x16x32_bf16 v[14:17], v[208:211], v[224:227], v[14:17]
	ds_read_b128 v[208:211], v244 offset:6976
	s_waitcnt vmcnt(13)
	ds_write_b128 v98, v[110:113] offset:27648
	s_waitcnt vmcnt(12)
	ds_write_b128 v98, v[114:117] offset:32256
	s_waitcnt lgkmcnt(7)
	v_mfma_f32_16x16x32_bf16 v[50:53], v[196:199], v[228:231], v[50:53]
	v_mfma_f32_16x16x32_bf16 v[54:57], v[196:199], v[232:235], v[54:57]
	v_mfma_f32_16x16x32_bf16 v[18:21], v[196:199], v[236:239], v[18:21]
	v_mfma_f32_16x16x32_bf16 v[22:25], v[196:199], v[240:243], v[22:25]
	s_waitcnt vmcnt(11)
	ds_write_b128 v98, v[118:121] offset:55296
	s_waitcnt vmcnt(10)
	ds_write_b128 v98, v[122:125] offset:59904
	s_waitcnt lgkmcnt(8)
	v_mfma_f32_16x16x32_bf16 v[58:61], v[200:203], v[228:231], v[58:61]
	v_mfma_f32_16x16x32_bf16 v[62:65], v[200:203], v[232:235], v[62:65]
	v_mfma_f32_16x16x32_bf16 v[26:29], v[200:203], v[236:239], v[26:29]
	v_mfma_f32_16x16x32_bf16 v[30:33], v[200:203], v[240:243], v[30:33]
	s_waitcnt vmcnt(9)
	ds_write_b128 v98, v[126:129] offset:64512
	s_waitcnt vmcnt(8)
	ds_write_b128 v99, v[136:139] offset:32256
	s_waitcnt lgkmcnt(0)
	s_barrier
	ds_read_b128 v[212:215], v245 offset:55296
	ds_read_b128 v[196:199], v244 offset:18432
	ds_read_b128 v[216:219], v245 offset:57600
	ds_read_b128 v[220:223], v245 offset:59904
	ds_read_b128 v[224:227], v245 offset:62208
	ds_read_b128 v[200:203], v244 offset:20736
	s_setprio 0
	v_mfma_f32_16x16x32_bf16 v[34:37], v[204:207], v[228:231], v[34:37]
	v_mfma_f32_16x16x32_bf16 v[38:41], v[204:207], v[232:235], v[38:41]
	v_mfma_f32_16x16x32_bf16 v[2:5], v[204:207], v[236:239], v[2:5]
	v_mfma_f32_16x16x32_bf16 v[6:9], v[204:207], v[240:243], v[6:9]
	ds_read_b128 v[204:207], v244 offset:23040
	v_mfma_f32_16x16x32_bf16 v[42:45], v[208:211], v[228:231], v[42:45]
	v_mfma_f32_16x16x32_bf16 v[46:49], v[208:211], v[232:235], v[46:49]
	v_mfma_f32_16x16x32_bf16 v[10:13], v[208:211], v[236:239], v[10:13]
	v_mfma_f32_16x16x32_bf16 v[14:17], v[208:211], v[240:243], v[14:17]
	ds_read_b128 v[208:211], v244 offset:25344
	global_load_dwordx4 v[102:105], v[74:75], off offset:1152
	global_load_dwordx4 v[106:109], v[76:77], off offset:1152
	global_load_dwordx4 v[110:113], v[78:79], off offset:1152
	global_load_dwordx4 v[114:117], v[80:81], off offset:1152
	global_load_dwordx4 v[118:121], v[82:83], off offset:1152
	global_load_dwordx4 v[122:125], v[84:85], off offset:1152
	global_load_dwordx4 v[126:129], v[86:87], off offset:1152
	global_load_dwordx4 v[136:139], v[88:89], off offset:1152
	s_waitcnt lgkmcnt(6)
	v_mfma_f32_16x16x32_bf16 v[50:53], v[196:199], v[212:215], v[50:53]
	ds_read_b128 v[228:231], v245 offset:55360
	s_waitcnt lgkmcnt(6)
	v_mfma_f32_16x16x32_bf16 v[54:57], v[196:199], v[216:219], v[54:57]
	ds_read_b128 v[232:235], v245 offset:57664
	s_waitcnt lgkmcnt(6)
	v_mfma_f32_16x16x32_bf16 v[18:21], v[196:199], v[220:223], v[18:21]
	ds_read_b128 v[236:239], v245 offset:59968
	s_waitcnt lgkmcnt(6)
	v_mfma_f32_16x16x32_bf16 v[22:25], v[196:199], v[224:227], v[22:25]
	ds_read_b128 v[240:243], v245 offset:62272
	ds_read_b128 v[196:199], v244 offset:18496
	s_waitcnt lgkmcnt(7)
	v_mfma_f32_16x16x32_bf16 v[58:61], v[200:203], v[212:215], v[58:61]
	v_mfma_f32_16x16x32_bf16 v[62:65], v[200:203], v[216:219], v[62:65]
	v_mfma_f32_16x16x32_bf16 v[26:29], v[200:203], v[220:223], v[26:29]
	v_mfma_f32_16x16x32_bf16 v[30:33], v[200:203], v[224:227], v[30:33]
	ds_read_b128 v[200:203], v244 offset:20800
	s_waitcnt lgkmcnt(7)
	v_mfma_f32_16x16x32_bf16 v[34:37], v[204:207], v[212:215], v[34:37]
	v_mfma_f32_16x16x32_bf16 v[38:41], v[204:207], v[216:219], v[38:41]
	v_mfma_f32_16x16x32_bf16 v[2:5], v[204:207], v[220:223], v[2:5]
	v_mfma_f32_16x16x32_bf16 v[6:9], v[204:207], v[224:227], v[6:9]
	ds_read_b128 v[204:207], v244 offset:23104
	s_setprio 1
	s_waitcnt vmcnt(15)
	ds_write_b128 v98, v[140:143]
	s_waitcnt vmcnt(14)
	ds_write_b128 v98, v[144:147] offset:4608
	s_waitcnt lgkmcnt(9)
	v_mfma_f32_16x16x32_bf16 v[42:45], v[208:211], v[212:215], v[42:45]
	v_mfma_f32_16x16x32_bf16 v[46:49], v[208:211], v[216:219], v[46:49]
	v_mfma_f32_16x16x32_bf16 v[10:13], v[208:211], v[220:223], v[10:13]
	v_mfma_f32_16x16x32_bf16 v[14:17], v[208:211], v[224:227], v[14:17]
	ds_read_b128 v[208:211], v244 offset:25408
	s_waitcnt vmcnt(13)
	ds_write_b128 v98, v[148:151] offset:9216
	s_waitcnt vmcnt(12)
	ds_write_b128 v98, v[152:155] offset:13824
	s_waitcnt lgkmcnt(7)
	v_mfma_f32_16x16x32_bf16 v[50:53], v[196:199], v[228:231], v[50:53]
	v_mfma_f32_16x16x32_bf16 v[54:57], v[196:199], v[232:235], v[54:57]
	v_mfma_f32_16x16x32_bf16 v[18:21], v[196:199], v[236:239], v[18:21]
	v_mfma_f32_16x16x32_bf16 v[22:25], v[196:199], v[240:243], v[22:25]
	s_waitcnt vmcnt(11)
	ds_write_b128 v98, v[156:159] offset:36864
	s_waitcnt vmcnt(10)
	ds_write_b128 v98, v[160:163] offset:41472
	s_waitcnt lgkmcnt(8)
	v_mfma_f32_16x16x32_bf16 v[58:61], v[200:203], v[228:231], v[58:61]
	v_mfma_f32_16x16x32_bf16 v[62:65], v[200:203], v[232:235], v[62:65]
	v_mfma_f32_16x16x32_bf16 v[26:29], v[200:203], v[236:239], v[26:29]
	v_mfma_f32_16x16x32_bf16 v[30:33], v[200:203], v[240:243], v[30:33]
	s_waitcnt vmcnt(9)
	ds_write_b128 v98, v[164:167] offset:46080
	s_waitcnt vmcnt(8)
	ds_write_b128 v98, v[168:171] offset:50688
	s_waitcnt lgkmcnt(0)
	s_barrier
	ds_read_b128 v[212:215], v245 offset:36864
	ds_read_b128 v[196:199], v244
	ds_read_b128 v[216:219], v245 offset:39168
	ds_read_b128 v[220:223], v245 offset:41472
	ds_read_b128 v[224:227], v245 offset:43776
	ds_read_b128 v[200:203], v244 offset:2304
	s_setprio 0
	v_mfma_f32_16x16x32_bf16 v[34:37], v[204:207], v[228:231], v[34:37]
	v_mfma_f32_16x16x32_bf16 v[38:41], v[204:207], v[232:235], v[38:41]
	v_mfma_f32_16x16x32_bf16 v[2:5], v[204:207], v[236:239], v[2:5]
	v_mfma_f32_16x16x32_bf16 v[6:9], v[204:207], v[240:243], v[6:9]
	ds_read_b128 v[204:207], v244 offset:4608
	v_mfma_f32_16x16x32_bf16 v[42:45], v[208:211], v[228:231], v[42:45]
	v_mfma_f32_16x16x32_bf16 v[46:49], v[208:211], v[232:235], v[46:49]
	v_mfma_f32_16x16x32_bf16 v[10:13], v[208:211], v[236:239], v[10:13]
	v_mfma_f32_16x16x32_bf16 v[14:17], v[208:211], v[240:243], v[14:17]
	ds_read_b128 v[208:211], v244 offset:6912
	global_load_dwordx4 v[140:143], v[74:75], off offset:1280
	global_load_dwordx4 v[144:147], v[76:77], off offset:1280
	global_load_dwordx4 v[148:151], v[78:79], off offset:1280
	global_load_dwordx4 v[152:155], v[80:81], off offset:1280
	global_load_dwordx4 v[156:159], v[82:83], off offset:1280
	global_load_dwordx4 v[160:163], v[84:85], off offset:1280
	global_load_dwordx4 v[164:167], v[86:87], off offset:1280
	global_load_dwordx4 v[168:171], v[88:89], off offset:1280
	s_waitcnt lgkmcnt(6)
	v_mfma_f32_16x16x32_bf16 v[50:53], v[196:199], v[212:215], v[50:53]
	ds_read_b128 v[228:231], v245 offset:36928
	s_waitcnt lgkmcnt(6)
	v_mfma_f32_16x16x32_bf16 v[54:57], v[196:199], v[216:219], v[54:57]
	ds_read_b128 v[232:235], v245 offset:39232
	s_waitcnt lgkmcnt(6)
	v_mfma_f32_16x16x32_bf16 v[18:21], v[196:199], v[220:223], v[18:21]
	ds_read_b128 v[236:239], v245 offset:41536
	s_waitcnt lgkmcnt(6)
	v_mfma_f32_16x16x32_bf16 v[22:25], v[196:199], v[224:227], v[22:25]
	ds_read_b128 v[240:243], v245 offset:43840
	ds_read_b128 v[196:199], v244 offset:64
	s_waitcnt lgkmcnt(7)
	v_mfma_f32_16x16x32_bf16 v[58:61], v[200:203], v[212:215], v[58:61]
	v_mfma_f32_16x16x32_bf16 v[62:65], v[200:203], v[216:219], v[62:65]
	v_mfma_f32_16x16x32_bf16 v[26:29], v[200:203], v[220:223], v[26:29]
	v_mfma_f32_16x16x32_bf16 v[30:33], v[200:203], v[224:227], v[30:33]
	ds_read_b128 v[200:203], v244 offset:2368
	s_waitcnt lgkmcnt(7)
	v_mfma_f32_16x16x32_bf16 v[34:37], v[204:207], v[212:215], v[34:37]
	v_mfma_f32_16x16x32_bf16 v[38:41], v[204:207], v[216:219], v[38:41]
	v_mfma_f32_16x16x32_bf16 v[2:5], v[204:207], v[220:223], v[2:5]
	v_mfma_f32_16x16x32_bf16 v[6:9], v[204:207], v[224:227], v[6:9]
	ds_read_b128 v[204:207], v244 offset:4672
	s_setprio 1
	s_waitcnt vmcnt(15)
	ds_write_b128 v98, v[102:105] offset:18432
	s_waitcnt vmcnt(14)
	ds_write_b128 v98, v[106:109] offset:23040
	s_waitcnt lgkmcnt(9)
	v_mfma_f32_16x16x32_bf16 v[42:45], v[208:211], v[212:215], v[42:45]
	v_mfma_f32_16x16x32_bf16 v[46:49], v[208:211], v[216:219], v[46:49]
	v_mfma_f32_16x16x32_bf16 v[10:13], v[208:211], v[220:223], v[10:13]
	v_mfma_f32_16x16x32_bf16 v[14:17], v[208:211], v[224:227], v[14:17]
	ds_read_b128 v[208:211], v244 offset:6976
	s_waitcnt vmcnt(13)
	ds_write_b128 v98, v[110:113] offset:27648
	s_waitcnt vmcnt(12)
	ds_write_b128 v98, v[114:117] offset:32256
	s_waitcnt lgkmcnt(7)
	v_mfma_f32_16x16x32_bf16 v[50:53], v[196:199], v[228:231], v[50:53]
	v_mfma_f32_16x16x32_bf16 v[54:57], v[196:199], v[232:235], v[54:57]
	v_mfma_f32_16x16x32_bf16 v[18:21], v[196:199], v[236:239], v[18:21]
	v_mfma_f32_16x16x32_bf16 v[22:25], v[196:199], v[240:243], v[22:25]
	s_waitcnt vmcnt(11)
	ds_write_b128 v98, v[118:121] offset:55296
	s_waitcnt vmcnt(10)
	ds_write_b128 v98, v[122:125] offset:59904
	s_waitcnt lgkmcnt(8)
	v_mfma_f32_16x16x32_bf16 v[58:61], v[200:203], v[228:231], v[58:61]
	v_mfma_f32_16x16x32_bf16 v[62:65], v[200:203], v[232:235], v[62:65]
	v_mfma_f32_16x16x32_bf16 v[26:29], v[200:203], v[236:239], v[26:29]
	v_mfma_f32_16x16x32_bf16 v[30:33], v[200:203], v[240:243], v[30:33]
	s_waitcnt vmcnt(9)
	ds_write_b128 v98, v[126:129] offset:64512
	s_waitcnt vmcnt(8)
	ds_write_b128 v99, v[136:139] offset:32256
	s_waitcnt lgkmcnt(0)
	s_barrier
	ds_read_b128 v[212:215], v245 offset:55296
	ds_read_b128 v[196:199], v244 offset:18432
	ds_read_b128 v[216:219], v245 offset:57600
	ds_read_b128 v[220:223], v245 offset:59904
	ds_read_b128 v[224:227], v245 offset:62208
	ds_read_b128 v[200:203], v244 offset:20736
	s_setprio 0
	v_mfma_f32_16x16x32_bf16 v[34:37], v[204:207], v[228:231], v[34:37]
	v_mfma_f32_16x16x32_bf16 v[38:41], v[204:207], v[232:235], v[38:41]
	v_mfma_f32_16x16x32_bf16 v[2:5], v[204:207], v[236:239], v[2:5]
	v_mfma_f32_16x16x32_bf16 v[6:9], v[204:207], v[240:243], v[6:9]
	ds_read_b128 v[204:207], v244 offset:23040
	v_mfma_f32_16x16x32_bf16 v[42:45], v[208:211], v[228:231], v[42:45]
	v_mfma_f32_16x16x32_bf16 v[46:49], v[208:211], v[232:235], v[46:49]
	v_mfma_f32_16x16x32_bf16 v[10:13], v[208:211], v[236:239], v[10:13]
	v_mfma_f32_16x16x32_bf16 v[14:17], v[208:211], v[240:243], v[14:17]
	ds_read_b128 v[208:211], v244 offset:25344
	global_load_dwordx4 v[102:105], v[74:75], off offset:1408
	global_load_dwordx4 v[106:109], v[76:77], off offset:1408
	global_load_dwordx4 v[110:113], v[78:79], off offset:1408
	global_load_dwordx4 v[114:117], v[80:81], off offset:1408
	global_load_dwordx4 v[118:121], v[82:83], off offset:1408
	global_load_dwordx4 v[122:125], v[84:85], off offset:1408
	global_load_dwordx4 v[126:129], v[86:87], off offset:1408
	global_load_dwordx4 v[136:139], v[88:89], off offset:1408
	s_waitcnt lgkmcnt(6)
	v_mfma_f32_16x16x32_bf16 v[50:53], v[196:199], v[212:215], v[50:53]
	ds_read_b128 v[228:231], v245 offset:55360
	s_waitcnt lgkmcnt(6)
	v_mfma_f32_16x16x32_bf16 v[54:57], v[196:199], v[216:219], v[54:57]
	ds_read_b128 v[232:235], v245 offset:57664
	s_waitcnt lgkmcnt(6)
	v_mfma_f32_16x16x32_bf16 v[18:21], v[196:199], v[220:223], v[18:21]
	ds_read_b128 v[236:239], v245 offset:59968
	s_waitcnt lgkmcnt(6)
	v_mfma_f32_16x16x32_bf16 v[22:25], v[196:199], v[224:227], v[22:25]
	ds_read_b128 v[240:243], v245 offset:62272
	ds_read_b128 v[196:199], v244 offset:18496
	s_waitcnt lgkmcnt(7)
	v_mfma_f32_16x16x32_bf16 v[58:61], v[200:203], v[212:215], v[58:61]
	v_mfma_f32_16x16x32_bf16 v[62:65], v[200:203], v[216:219], v[62:65]
	v_mfma_f32_16x16x32_bf16 v[26:29], v[200:203], v[220:223], v[26:29]
	v_mfma_f32_16x16x32_bf16 v[30:33], v[200:203], v[224:227], v[30:33]
	ds_read_b128 v[200:203], v244 offset:20800
	s_waitcnt lgkmcnt(7)
	v_mfma_f32_16x16x32_bf16 v[34:37], v[204:207], v[212:215], v[34:37]
	v_mfma_f32_16x16x32_bf16 v[38:41], v[204:207], v[216:219], v[38:41]
	v_mfma_f32_16x16x32_bf16 v[2:5], v[204:207], v[220:223], v[2:5]
	v_mfma_f32_16x16x32_bf16 v[6:9], v[204:207], v[224:227], v[6:9]
	ds_read_b128 v[204:207], v244 offset:23104
	s_setprio 1
	s_waitcnt vmcnt(15)
	ds_write_b128 v98, v[140:143]
	s_waitcnt vmcnt(14)
	ds_write_b128 v98, v[144:147] offset:4608
	s_waitcnt lgkmcnt(9)
	v_mfma_f32_16x16x32_bf16 v[42:45], v[208:211], v[212:215], v[42:45]
	v_mfma_f32_16x16x32_bf16 v[46:49], v[208:211], v[216:219], v[46:49]
	v_mfma_f32_16x16x32_bf16 v[10:13], v[208:211], v[220:223], v[10:13]
	v_mfma_f32_16x16x32_bf16 v[14:17], v[208:211], v[224:227], v[14:17]
	ds_read_b128 v[208:211], v244 offset:25408
	s_waitcnt vmcnt(13)
	ds_write_b128 v98, v[148:151] offset:9216
	s_waitcnt vmcnt(12)
	ds_write_b128 v98, v[152:155] offset:13824
	s_waitcnt lgkmcnt(7)
	v_mfma_f32_16x16x32_bf16 v[50:53], v[196:199], v[228:231], v[50:53]
	v_mfma_f32_16x16x32_bf16 v[54:57], v[196:199], v[232:235], v[54:57]
	v_mfma_f32_16x16x32_bf16 v[18:21], v[196:199], v[236:239], v[18:21]
	v_mfma_f32_16x16x32_bf16 v[22:25], v[196:199], v[240:243], v[22:25]
	s_waitcnt vmcnt(11)
	ds_write_b128 v98, v[156:159] offset:36864
	s_waitcnt vmcnt(10)
	ds_write_b128 v98, v[160:163] offset:41472
	s_waitcnt lgkmcnt(8)
	v_mfma_f32_16x16x32_bf16 v[58:61], v[200:203], v[228:231], v[58:61]
	v_mfma_f32_16x16x32_bf16 v[62:65], v[200:203], v[232:235], v[62:65]
	v_mfma_f32_16x16x32_bf16 v[26:29], v[200:203], v[236:239], v[26:29]
	v_mfma_f32_16x16x32_bf16 v[30:33], v[200:203], v[240:243], v[30:33]
	s_waitcnt vmcnt(9)
	ds_write_b128 v98, v[164:167] offset:46080
	s_waitcnt vmcnt(8)
	ds_write_b128 v98, v[168:171] offset:50688
	s_waitcnt lgkmcnt(0)
	s_barrier
	ds_read_b128 v[212:215], v245 offset:36864
	ds_read_b128 v[196:199], v244
	ds_read_b128 v[216:219], v245 offset:39168
	ds_read_b128 v[220:223], v245 offset:41472
	ds_read_b128 v[224:227], v245 offset:43776
	ds_read_b128 v[200:203], v244 offset:2304
	s_setprio 0
	v_mfma_f32_16x16x32_bf16 v[34:37], v[204:207], v[228:231], v[34:37]
	v_mfma_f32_16x16x32_bf16 v[38:41], v[204:207], v[232:235], v[38:41]
	v_mfma_f32_16x16x32_bf16 v[2:5], v[204:207], v[236:239], v[2:5]
	v_mfma_f32_16x16x32_bf16 v[6:9], v[204:207], v[240:243], v[6:9]
	ds_read_b128 v[204:207], v244 offset:4608
	v_mfma_f32_16x16x32_bf16 v[42:45], v[208:211], v[228:231], v[42:45]
	v_mfma_f32_16x16x32_bf16 v[46:49], v[208:211], v[232:235], v[46:49]
	v_mfma_f32_16x16x32_bf16 v[10:13], v[208:211], v[236:239], v[10:13]
	v_mfma_f32_16x16x32_bf16 v[14:17], v[208:211], v[240:243], v[14:17]
	ds_read_b128 v[208:211], v244 offset:6912
	global_load_dwordx4 v[140:143], v[74:75], off offset:1536
	global_load_dwordx4 v[144:147], v[76:77], off offset:1536
	global_load_dwordx4 v[148:151], v[78:79], off offset:1536
	global_load_dwordx4 v[152:155], v[80:81], off offset:1536
	global_load_dwordx4 v[156:159], v[82:83], off offset:1536
	global_load_dwordx4 v[160:163], v[84:85], off offset:1536
	global_load_dwordx4 v[164:167], v[86:87], off offset:1536
	global_load_dwordx4 v[168:171], v[88:89], off offset:1536
	s_waitcnt lgkmcnt(6)
	v_mfma_f32_16x16x32_bf16 v[50:53], v[196:199], v[212:215], v[50:53]
	ds_read_b128 v[228:231], v245 offset:36928
	s_waitcnt lgkmcnt(6)
	v_mfma_f32_16x16x32_bf16 v[54:57], v[196:199], v[216:219], v[54:57]
	ds_read_b128 v[232:235], v245 offset:39232
	s_waitcnt lgkmcnt(6)
	v_mfma_f32_16x16x32_bf16 v[18:21], v[196:199], v[220:223], v[18:21]
	ds_read_b128 v[236:239], v245 offset:41536
	s_waitcnt lgkmcnt(6)
	v_mfma_f32_16x16x32_bf16 v[22:25], v[196:199], v[224:227], v[22:25]
	ds_read_b128 v[240:243], v245 offset:43840
	ds_read_b128 v[196:199], v244 offset:64
	s_waitcnt lgkmcnt(7)
	v_mfma_f32_16x16x32_bf16 v[58:61], v[200:203], v[212:215], v[58:61]
	v_mfma_f32_16x16x32_bf16 v[62:65], v[200:203], v[216:219], v[62:65]
	v_mfma_f32_16x16x32_bf16 v[26:29], v[200:203], v[220:223], v[26:29]
	v_mfma_f32_16x16x32_bf16 v[30:33], v[200:203], v[224:227], v[30:33]
	ds_read_b128 v[200:203], v244 offset:2368
	s_waitcnt lgkmcnt(7)
	v_mfma_f32_16x16x32_bf16 v[34:37], v[204:207], v[212:215], v[34:37]
	v_mfma_f32_16x16x32_bf16 v[38:41], v[204:207], v[216:219], v[38:41]
	v_mfma_f32_16x16x32_bf16 v[2:5], v[204:207], v[220:223], v[2:5]
	v_mfma_f32_16x16x32_bf16 v[6:9], v[204:207], v[224:227], v[6:9]
	ds_read_b128 v[204:207], v244 offset:4672
	s_setprio 1
	s_waitcnt vmcnt(15)
	ds_write_b128 v98, v[102:105] offset:18432
	s_waitcnt vmcnt(14)
	ds_write_b128 v98, v[106:109] offset:23040
	s_waitcnt lgkmcnt(9)
	v_mfma_f32_16x16x32_bf16 v[42:45], v[208:211], v[212:215], v[42:45]
	v_mfma_f32_16x16x32_bf16 v[46:49], v[208:211], v[216:219], v[46:49]
	v_mfma_f32_16x16x32_bf16 v[10:13], v[208:211], v[220:223], v[10:13]
	v_mfma_f32_16x16x32_bf16 v[14:17], v[208:211], v[224:227], v[14:17]
	ds_read_b128 v[208:211], v244 offset:6976
	s_waitcnt vmcnt(13)
	ds_write_b128 v98, v[110:113] offset:27648
	s_waitcnt vmcnt(12)
	ds_write_b128 v98, v[114:117] offset:32256
	s_waitcnt lgkmcnt(7)
	v_mfma_f32_16x16x32_bf16 v[50:53], v[196:199], v[228:231], v[50:53]
	v_mfma_f32_16x16x32_bf16 v[54:57], v[196:199], v[232:235], v[54:57]
	v_mfma_f32_16x16x32_bf16 v[18:21], v[196:199], v[236:239], v[18:21]
	v_mfma_f32_16x16x32_bf16 v[22:25], v[196:199], v[240:243], v[22:25]
	s_waitcnt vmcnt(11)
	ds_write_b128 v98, v[118:121] offset:55296
	s_waitcnt vmcnt(10)
	ds_write_b128 v98, v[122:125] offset:59904
	s_waitcnt lgkmcnt(8)
	v_mfma_f32_16x16x32_bf16 v[58:61], v[200:203], v[228:231], v[58:61]
	v_mfma_f32_16x16x32_bf16 v[62:65], v[200:203], v[232:235], v[62:65]
	v_mfma_f32_16x16x32_bf16 v[26:29], v[200:203], v[236:239], v[26:29]
	v_mfma_f32_16x16x32_bf16 v[30:33], v[200:203], v[240:243], v[30:33]
	s_waitcnt vmcnt(9)
	ds_write_b128 v98, v[126:129] offset:64512
	s_waitcnt vmcnt(8)
	ds_write_b128 v99, v[136:139] offset:32256
	s_waitcnt lgkmcnt(0)
	s_barrier
	ds_read_b128 v[212:215], v245 offset:55296
	ds_read_b128 v[196:199], v244 offset:18432
	ds_read_b128 v[216:219], v245 offset:57600
	ds_read_b128 v[220:223], v245 offset:59904
	ds_read_b128 v[224:227], v245 offset:62208
	ds_read_b128 v[200:203], v244 offset:20736
	s_setprio 0
	v_mfma_f32_16x16x32_bf16 v[34:37], v[204:207], v[228:231], v[34:37]
	v_mfma_f32_16x16x32_bf16 v[38:41], v[204:207], v[232:235], v[38:41]
	v_mfma_f32_16x16x32_bf16 v[2:5], v[204:207], v[236:239], v[2:5]
	v_mfma_f32_16x16x32_bf16 v[6:9], v[204:207], v[240:243], v[6:9]
	ds_read_b128 v[204:207], v244 offset:23040
	v_mfma_f32_16x16x32_bf16 v[42:45], v[208:211], v[228:231], v[42:45]
	v_mfma_f32_16x16x32_bf16 v[46:49], v[208:211], v[232:235], v[46:49]
	v_mfma_f32_16x16x32_bf16 v[10:13], v[208:211], v[236:239], v[10:13]
	v_mfma_f32_16x16x32_bf16 v[14:17], v[208:211], v[240:243], v[14:17]
	ds_read_b128 v[208:211], v244 offset:25344
	global_load_dwordx4 v[102:105], v[74:75], off offset:1664
	global_load_dwordx4 v[106:109], v[76:77], off offset:1664
	global_load_dwordx4 v[110:113], v[78:79], off offset:1664
	global_load_dwordx4 v[114:117], v[80:81], off offset:1664
	global_load_dwordx4 v[118:121], v[82:83], off offset:1664
	global_load_dwordx4 v[122:125], v[84:85], off offset:1664
	global_load_dwordx4 v[126:129], v[86:87], off offset:1664
	global_load_dwordx4 v[136:139], v[88:89], off offset:1664
	s_waitcnt lgkmcnt(6)
	v_mfma_f32_16x16x32_bf16 v[50:53], v[196:199], v[212:215], v[50:53]
	ds_read_b128 v[228:231], v245 offset:55360
	s_waitcnt lgkmcnt(6)
	v_mfma_f32_16x16x32_bf16 v[54:57], v[196:199], v[216:219], v[54:57]
	ds_read_b128 v[232:235], v245 offset:57664
	s_waitcnt lgkmcnt(6)
	v_mfma_f32_16x16x32_bf16 v[18:21], v[196:199], v[220:223], v[18:21]
	ds_read_b128 v[236:239], v245 offset:59968
	s_waitcnt lgkmcnt(6)
	v_mfma_f32_16x16x32_bf16 v[22:25], v[196:199], v[224:227], v[22:25]
	ds_read_b128 v[240:243], v245 offset:62272
	ds_read_b128 v[196:199], v244 offset:18496
	s_waitcnt lgkmcnt(7)
	v_mfma_f32_16x16x32_bf16 v[58:61], v[200:203], v[212:215], v[58:61]
	v_mfma_f32_16x16x32_bf16 v[62:65], v[200:203], v[216:219], v[62:65]
	v_mfma_f32_16x16x32_bf16 v[26:29], v[200:203], v[220:223], v[26:29]
	v_mfma_f32_16x16x32_bf16 v[30:33], v[200:203], v[224:227], v[30:33]
	ds_read_b128 v[200:203], v244 offset:20800
	s_waitcnt lgkmcnt(7)
	v_mfma_f32_16x16x32_bf16 v[34:37], v[204:207], v[212:215], v[34:37]
	v_mfma_f32_16x16x32_bf16 v[38:41], v[204:207], v[216:219], v[38:41]
	v_mfma_f32_16x16x32_bf16 v[2:5], v[204:207], v[220:223], v[2:5]
	v_mfma_f32_16x16x32_bf16 v[6:9], v[204:207], v[224:227], v[6:9]
	ds_read_b128 v[204:207], v244 offset:23104
	s_setprio 1
	s_waitcnt vmcnt(15)
	ds_write_b128 v98, v[140:143]
	s_waitcnt vmcnt(14)
	ds_write_b128 v98, v[144:147] offset:4608
	s_waitcnt lgkmcnt(9)
	v_mfma_f32_16x16x32_bf16 v[42:45], v[208:211], v[212:215], v[42:45]
	v_mfma_f32_16x16x32_bf16 v[46:49], v[208:211], v[216:219], v[46:49]
	v_mfma_f32_16x16x32_bf16 v[10:13], v[208:211], v[220:223], v[10:13]
	v_mfma_f32_16x16x32_bf16 v[14:17], v[208:211], v[224:227], v[14:17]
	ds_read_b128 v[208:211], v244 offset:25408
	s_waitcnt vmcnt(13)
	ds_write_b128 v98, v[148:151] offset:9216
	s_waitcnt vmcnt(12)
	ds_write_b128 v98, v[152:155] offset:13824
	s_waitcnt lgkmcnt(7)
	v_mfma_f32_16x16x32_bf16 v[50:53], v[196:199], v[228:231], v[50:53]
	v_mfma_f32_16x16x32_bf16 v[54:57], v[196:199], v[232:235], v[54:57]
	v_mfma_f32_16x16x32_bf16 v[18:21], v[196:199], v[236:239], v[18:21]
	v_mfma_f32_16x16x32_bf16 v[22:25], v[196:199], v[240:243], v[22:25]
	s_waitcnt vmcnt(11)
	ds_write_b128 v98, v[156:159] offset:36864
	s_waitcnt vmcnt(10)
	ds_write_b128 v98, v[160:163] offset:41472
	s_waitcnt lgkmcnt(8)
	v_mfma_f32_16x16x32_bf16 v[58:61], v[200:203], v[228:231], v[58:61]
	v_mfma_f32_16x16x32_bf16 v[62:65], v[200:203], v[232:235], v[62:65]
	v_mfma_f32_16x16x32_bf16 v[26:29], v[200:203], v[236:239], v[26:29]
	v_mfma_f32_16x16x32_bf16 v[30:33], v[200:203], v[240:243], v[30:33]
	s_waitcnt vmcnt(9)
	ds_write_b128 v98, v[164:167] offset:46080
	s_waitcnt vmcnt(8)
	ds_write_b128 v98, v[168:171] offset:50688
	s_waitcnt lgkmcnt(0)
	s_barrier
	ds_read_b128 v[212:215], v245 offset:36864
	ds_read_b128 v[196:199], v244
	ds_read_b128 v[216:219], v245 offset:39168
	ds_read_b128 v[220:223], v245 offset:41472
	ds_read_b128 v[224:227], v245 offset:43776
	ds_read_b128 v[200:203], v244 offset:2304
	s_setprio 0
	v_mfma_f32_16x16x32_bf16 v[34:37], v[204:207], v[228:231], v[34:37]
	v_mfma_f32_16x16x32_bf16 v[38:41], v[204:207], v[232:235], v[38:41]
	v_mfma_f32_16x16x32_bf16 v[2:5], v[204:207], v[236:239], v[2:5]
	v_mfma_f32_16x16x32_bf16 v[6:9], v[204:207], v[240:243], v[6:9]
	ds_read_b128 v[204:207], v244 offset:4608
	v_mfma_f32_16x16x32_bf16 v[42:45], v[208:211], v[228:231], v[42:45]
	v_mfma_f32_16x16x32_bf16 v[46:49], v[208:211], v[232:235], v[46:49]
	v_mfma_f32_16x16x32_bf16 v[10:13], v[208:211], v[236:239], v[10:13]
	v_mfma_f32_16x16x32_bf16 v[14:17], v[208:211], v[240:243], v[14:17]
	ds_read_b128 v[208:211], v244 offset:6912
	global_load_dwordx4 v[140:143], v[74:75], off offset:1792
	global_load_dwordx4 v[144:147], v[76:77], off offset:1792
	global_load_dwordx4 v[148:151], v[78:79], off offset:1792
	global_load_dwordx4 v[152:155], v[80:81], off offset:1792
	global_load_dwordx4 v[156:159], v[82:83], off offset:1792
	global_load_dwordx4 v[160:163], v[84:85], off offset:1792
	global_load_dwordx4 v[164:167], v[86:87], off offset:1792
	global_load_dwordx4 v[168:171], v[88:89], off offset:1792
	s_waitcnt lgkmcnt(6)
	v_mfma_f32_16x16x32_bf16 v[50:53], v[196:199], v[212:215], v[50:53]
	ds_read_b128 v[228:231], v245 offset:36928
	s_waitcnt lgkmcnt(6)
	v_mfma_f32_16x16x32_bf16 v[54:57], v[196:199], v[216:219], v[54:57]
	ds_read_b128 v[232:235], v245 offset:39232
	s_waitcnt lgkmcnt(6)
	v_mfma_f32_16x16x32_bf16 v[18:21], v[196:199], v[220:223], v[18:21]
	ds_read_b128 v[236:239], v245 offset:41536
	s_waitcnt lgkmcnt(6)
	v_mfma_f32_16x16x32_bf16 v[22:25], v[196:199], v[224:227], v[22:25]
	ds_read_b128 v[240:243], v245 offset:43840
	ds_read_b128 v[196:199], v244 offset:64
	s_waitcnt lgkmcnt(7)
	v_mfma_f32_16x16x32_bf16 v[58:61], v[200:203], v[212:215], v[58:61]
	v_mfma_f32_16x16x32_bf16 v[62:65], v[200:203], v[216:219], v[62:65]
	v_mfma_f32_16x16x32_bf16 v[26:29], v[200:203], v[220:223], v[26:29]
	v_mfma_f32_16x16x32_bf16 v[30:33], v[200:203], v[224:227], v[30:33]
	ds_read_b128 v[200:203], v244 offset:2368
	s_waitcnt lgkmcnt(7)
	v_mfma_f32_16x16x32_bf16 v[34:37], v[204:207], v[212:215], v[34:37]
	v_mfma_f32_16x16x32_bf16 v[38:41], v[204:207], v[216:219], v[38:41]
	v_mfma_f32_16x16x32_bf16 v[2:5], v[204:207], v[220:223], v[2:5]
	v_mfma_f32_16x16x32_bf16 v[6:9], v[204:207], v[224:227], v[6:9]
	ds_read_b128 v[204:207], v244 offset:4672
	s_setprio 1
	s_waitcnt vmcnt(15)
	ds_write_b128 v98, v[102:105] offset:18432
	s_waitcnt vmcnt(14)
	ds_write_b128 v98, v[106:109] offset:23040
	s_waitcnt lgkmcnt(9)
	v_mfma_f32_16x16x32_bf16 v[42:45], v[208:211], v[212:215], v[42:45]
	v_mfma_f32_16x16x32_bf16 v[46:49], v[208:211], v[216:219], v[46:49]
	v_mfma_f32_16x16x32_bf16 v[10:13], v[208:211], v[220:223], v[10:13]
	v_mfma_f32_16x16x32_bf16 v[14:17], v[208:211], v[224:227], v[14:17]
	ds_read_b128 v[208:211], v244 offset:6976
	s_waitcnt vmcnt(13)
	ds_write_b128 v98, v[110:113] offset:27648
	s_waitcnt vmcnt(12)
	ds_write_b128 v98, v[114:117] offset:32256
	s_waitcnt lgkmcnt(7)
	v_mfma_f32_16x16x32_bf16 v[50:53], v[196:199], v[228:231], v[50:53]
	v_mfma_f32_16x16x32_bf16 v[54:57], v[196:199], v[232:235], v[54:57]
	v_mfma_f32_16x16x32_bf16 v[18:21], v[196:199], v[236:239], v[18:21]
	v_mfma_f32_16x16x32_bf16 v[22:25], v[196:199], v[240:243], v[22:25]
	s_waitcnt vmcnt(11)
	ds_write_b128 v98, v[118:121] offset:55296
	s_waitcnt vmcnt(10)
	ds_write_b128 v98, v[122:125] offset:59904
	s_waitcnt lgkmcnt(8)
	v_mfma_f32_16x16x32_bf16 v[58:61], v[200:203], v[228:231], v[58:61]
	v_mfma_f32_16x16x32_bf16 v[62:65], v[200:203], v[232:235], v[62:65]
	v_mfma_f32_16x16x32_bf16 v[26:29], v[200:203], v[236:239], v[26:29]
	v_mfma_f32_16x16x32_bf16 v[30:33], v[200:203], v[240:243], v[30:33]
	s_waitcnt vmcnt(9)
	ds_write_b128 v98, v[126:129] offset:64512
	s_waitcnt vmcnt(8)
	ds_write_b128 v99, v[136:139] offset:32256
	s_waitcnt lgkmcnt(0)
	s_barrier
	ds_read_b128 v[212:215], v245 offset:55296
	ds_read_b128 v[196:199], v244 offset:18432
	ds_read_b128 v[216:219], v245 offset:57600
	ds_read_b128 v[220:223], v245 offset:59904
	ds_read_b128 v[224:227], v245 offset:62208
	ds_read_b128 v[200:203], v244 offset:20736
	s_setprio 0
	v_mfma_f32_16x16x32_bf16 v[34:37], v[204:207], v[228:231], v[34:37]
	v_mfma_f32_16x16x32_bf16 v[38:41], v[204:207], v[232:235], v[38:41]
	v_mfma_f32_16x16x32_bf16 v[2:5], v[204:207], v[236:239], v[2:5]
	v_mfma_f32_16x16x32_bf16 v[6:9], v[204:207], v[240:243], v[6:9]
	ds_read_b128 v[204:207], v244 offset:23040
	v_mfma_f32_16x16x32_bf16 v[42:45], v[208:211], v[228:231], v[42:45]
	v_mfma_f32_16x16x32_bf16 v[46:49], v[208:211], v[232:235], v[46:49]
	v_mfma_f32_16x16x32_bf16 v[10:13], v[208:211], v[236:239], v[10:13]
	v_mfma_f32_16x16x32_bf16 v[14:17], v[208:211], v[240:243], v[14:17]
	ds_read_b128 v[208:211], v244 offset:25344
	global_load_dwordx4 v[102:105], v[74:75], off offset:1920
	s_nop 0
	global_load_dwordx4 v[74:77], v[76:77], off offset:1920
	s_nop 0
	global_load_dwordx4 v[106:109], v[78:79], off offset:1920
	s_nop 0
	global_load_dwordx4 v[78:81], v[80:81], off offset:1920
	s_nop 0
	global_load_dwordx4 v[110:113], v[82:83], off offset:1920
	s_nop 0
	global_load_dwordx4 v[82:85], v[84:85], off offset:1920
	s_nop 0
	global_load_dwordx4 v[114:117], v[86:87], off offset:1920
	s_nop 0
	global_load_dwordx4 v[86:89], v[88:89], off offset:1920
	s_waitcnt lgkmcnt(6)
	v_mfma_f32_16x16x32_bf16 v[50:53], v[196:199], v[212:215], v[50:53]
	ds_read_b128 v[228:231], v245 offset:55360
	s_waitcnt lgkmcnt(6)
	v_mfma_f32_16x16x32_bf16 v[54:57], v[196:199], v[216:219], v[54:57]
	ds_read_b128 v[232:235], v245 offset:57664
	s_waitcnt lgkmcnt(6)
	v_mfma_f32_16x16x32_bf16 v[18:21], v[196:199], v[220:223], v[18:21]
	ds_read_b128 v[236:239], v245 offset:59968
	s_waitcnt lgkmcnt(6)
	v_mfma_f32_16x16x32_bf16 v[22:25], v[196:199], v[224:227], v[22:25]
	ds_read_b128 v[240:243], v245 offset:62272
	ds_read_b128 v[196:199], v244 offset:18496
	s_waitcnt lgkmcnt(7)
	v_mfma_f32_16x16x32_bf16 v[58:61], v[200:203], v[212:215], v[58:61]
	v_mfma_f32_16x16x32_bf16 v[62:65], v[200:203], v[216:219], v[62:65]
	v_mfma_f32_16x16x32_bf16 v[26:29], v[200:203], v[220:223], v[26:29]
	v_mfma_f32_16x16x32_bf16 v[30:33], v[200:203], v[224:227], v[30:33]
	ds_read_b128 v[200:203], v244 offset:20800
	s_waitcnt lgkmcnt(7)
	v_mfma_f32_16x16x32_bf16 v[34:37], v[204:207], v[212:215], v[34:37]
	v_mfma_f32_16x16x32_bf16 v[38:41], v[204:207], v[216:219], v[38:41]
	v_mfma_f32_16x16x32_bf16 v[2:5], v[204:207], v[220:223], v[2:5]
	v_mfma_f32_16x16x32_bf16 v[6:9], v[204:207], v[224:227], v[6:9]
	ds_read_b128 v[204:207], v244 offset:23104
	s_setprio 1
	s_waitcnt vmcnt(15)
	ds_write_b128 v98, v[140:143]
	s_waitcnt vmcnt(14)
	ds_write_b128 v98, v[144:147] offset:4608
	s_waitcnt lgkmcnt(9)
	v_mfma_f32_16x16x32_bf16 v[42:45], v[208:211], v[212:215], v[42:45]
	v_mfma_f32_16x16x32_bf16 v[46:49], v[208:211], v[216:219], v[46:49]
	v_mfma_f32_16x16x32_bf16 v[10:13], v[208:211], v[220:223], v[10:13]
	v_mfma_f32_16x16x32_bf16 v[14:17], v[208:211], v[224:227], v[14:17]
	ds_read_b128 v[208:211], v244 offset:25408
	s_waitcnt vmcnt(13)
	ds_write_b128 v98, v[148:151] offset:9216
	s_waitcnt vmcnt(12)
	ds_write_b128 v98, v[152:155] offset:13824
	s_waitcnt lgkmcnt(7)
	v_mfma_f32_16x16x32_bf16 v[50:53], v[196:199], v[228:231], v[50:53]
	v_mfma_f32_16x16x32_bf16 v[54:57], v[196:199], v[232:235], v[54:57]
	v_mfma_f32_16x16x32_bf16 v[18:21], v[196:199], v[236:239], v[18:21]
	v_mfma_f32_16x16x32_bf16 v[22:25], v[196:199], v[240:243], v[22:25]
	s_waitcnt vmcnt(11)
	ds_write_b128 v98, v[156:159] offset:36864
	s_waitcnt vmcnt(10)
	ds_write_b128 v98, v[160:163] offset:41472
	s_waitcnt lgkmcnt(8)
	v_mfma_f32_16x16x32_bf16 v[58:61], v[200:203], v[228:231], v[58:61]
	v_mfma_f32_16x16x32_bf16 v[62:65], v[200:203], v[232:235], v[62:65]
	v_mfma_f32_16x16x32_bf16 v[26:29], v[200:203], v[236:239], v[26:29]
	v_mfma_f32_16x16x32_bf16 v[30:33], v[200:203], v[240:243], v[30:33]
	s_waitcnt vmcnt(9)
	ds_write_b128 v98, v[164:167] offset:46080
	s_waitcnt vmcnt(8)
	ds_write_b128 v98, v[168:171] offset:50688
	s_waitcnt lgkmcnt(0)
	s_barrier
	ds_read_b128 v[212:215], v245 offset:36864
	ds_read_b128 v[196:199], v244
	ds_read_b128 v[216:219], v245 offset:39168
	ds_read_b128 v[220:223], v245 offset:41472
	ds_read_b128 v[224:227], v245 offset:43776
	ds_read_b128 v[200:203], v244 offset:2304
	s_setprio 0
	v_mfma_f32_16x16x32_bf16 v[34:37], v[204:207], v[228:231], v[34:37]
	v_mfma_f32_16x16x32_bf16 v[38:41], v[204:207], v[232:235], v[38:41]
	v_mfma_f32_16x16x32_bf16 v[2:5], v[204:207], v[236:239], v[2:5]
	v_mfma_f32_16x16x32_bf16 v[6:9], v[204:207], v[240:243], v[6:9]
	ds_read_b128 v[204:207], v244 offset:4608
	v_mfma_f32_16x16x32_bf16 v[42:45], v[208:211], v[228:231], v[42:45]
	v_mfma_f32_16x16x32_bf16 v[46:49], v[208:211], v[232:235], v[46:49]
	v_mfma_f32_16x16x32_bf16 v[10:13], v[208:211], v[236:239], v[10:13]
	v_mfma_f32_16x16x32_bf16 v[14:17], v[208:211], v[240:243], v[14:17]
	ds_read_b128 v[208:211], v244 offset:6912
	s_waitcnt lgkmcnt(6)
	v_mfma_f32_16x16x32_bf16 v[50:53], v[196:199], v[212:215], v[50:53]
	ds_read_b128 v[228:231], v245 offset:36928
	s_waitcnt lgkmcnt(6)
	v_mfma_f32_16x16x32_bf16 v[54:57], v[196:199], v[216:219], v[54:57]
	ds_read_b128 v[232:235], v245 offset:39232
	s_waitcnt lgkmcnt(6)
	v_mfma_f32_16x16x32_bf16 v[18:21], v[196:199], v[220:223], v[18:21]
	ds_read_b128 v[236:239], v245 offset:41536
	s_waitcnt lgkmcnt(6)
	v_mfma_f32_16x16x32_bf16 v[22:25], v[196:199], v[224:227], v[22:25]
	ds_read_b128 v[240:243], v245 offset:43840
	ds_read_b128 v[196:199], v244 offset:64
	s_waitcnt lgkmcnt(7)
	v_mfma_f32_16x16x32_bf16 v[58:61], v[200:203], v[212:215], v[58:61]
	v_mfma_f32_16x16x32_bf16 v[62:65], v[200:203], v[216:219], v[62:65]
	v_mfma_f32_16x16x32_bf16 v[26:29], v[200:203], v[220:223], v[26:29]
	v_mfma_f32_16x16x32_bf16 v[30:33], v[200:203], v[224:227], v[30:33]
	ds_read_b128 v[200:203], v244 offset:2368
	s_waitcnt lgkmcnt(7)
	v_mfma_f32_16x16x32_bf16 v[34:37], v[204:207], v[212:215], v[34:37]
	v_mfma_f32_16x16x32_bf16 v[38:41], v[204:207], v[216:219], v[38:41]
	v_mfma_f32_16x16x32_bf16 v[2:5], v[204:207], v[220:223], v[2:5]
	v_mfma_f32_16x16x32_bf16 v[6:9], v[204:207], v[224:227], v[6:9]
	ds_read_b128 v[204:207], v244 offset:4672
	s_setprio 1
	s_waitcnt vmcnt(7)
	ds_write_b128 v98, v[102:105] offset:18432
	s_waitcnt vmcnt(6)
	ds_write_b128 v98, v[74:77] offset:23040
	s_waitcnt lgkmcnt(9)
	v_mfma_f32_16x16x32_bf16 v[42:45], v[208:211], v[212:215], v[42:45]
	v_mfma_f32_16x16x32_bf16 v[46:49], v[208:211], v[216:219], v[46:49]
	v_mfma_f32_16x16x32_bf16 v[10:13], v[208:211], v[220:223], v[10:13]
	v_mfma_f32_16x16x32_bf16 v[14:17], v[208:211], v[224:227], v[14:17]
	ds_read_b128 v[208:211], v244 offset:6976
	s_waitcnt vmcnt(5)
	ds_write_b128 v98, v[106:109] offset:27648
	s_waitcnt vmcnt(4)
	ds_write_b128 v98, v[78:81] offset:32256
	s_waitcnt lgkmcnt(7)
	v_mfma_f32_16x16x32_bf16 v[50:53], v[196:199], v[228:231], v[50:53]
	v_mfma_f32_16x16x32_bf16 v[54:57], v[196:199], v[232:235], v[54:57]
	v_mfma_f32_16x16x32_bf16 v[18:21], v[196:199], v[236:239], v[18:21]
	v_mfma_f32_16x16x32_bf16 v[22:25], v[196:199], v[240:243], v[22:25]
	s_waitcnt vmcnt(3)
	ds_write_b128 v98, v[110:113] offset:55296
	s_waitcnt vmcnt(2)
	ds_write_b128 v98, v[82:85] offset:59904
	s_waitcnt lgkmcnt(8)
	v_mfma_f32_16x16x32_bf16 v[58:61], v[200:203], v[228:231], v[58:61]
	v_mfma_f32_16x16x32_bf16 v[62:65], v[200:203], v[232:235], v[62:65]
	v_mfma_f32_16x16x32_bf16 v[26:29], v[200:203], v[236:239], v[26:29]
	v_mfma_f32_16x16x32_bf16 v[30:33], v[200:203], v[240:243], v[30:33]
	s_waitcnt vmcnt(1)
	ds_write_b128 v98, v[114:117] offset:64512
	s_waitcnt vmcnt(0)
	ds_write_b128 v99, v[86:89] offset:32256
	s_waitcnt lgkmcnt(0)
	s_barrier
	ds_read_b128 v[212:215], v245 offset:55296
	ds_read_b128 v[196:199], v244 offset:18432
	ds_read_b128 v[216:219], v245 offset:57600
	ds_read_b128 v[220:223], v245 offset:59904
	ds_read_b128 v[224:227], v245 offset:62208
	ds_read_b128 v[200:203], v244 offset:20736
	s_setprio 0
	v_mfma_f32_16x16x32_bf16 v[34:37], v[204:207], v[228:231], v[34:37]
	v_mfma_f32_16x16x32_bf16 v[38:41], v[204:207], v[232:235], v[38:41]
	v_mfma_f32_16x16x32_bf16 v[2:5], v[204:207], v[236:239], v[2:5]
	v_mfma_f32_16x16x32_bf16 v[6:9], v[204:207], v[240:243], v[6:9]
	ds_read_b128 v[204:207], v244 offset:23040
	v_mfma_f32_16x16x32_bf16 v[42:45], v[208:211], v[228:231], v[42:45]
	v_mfma_f32_16x16x32_bf16 v[46:49], v[208:211], v[232:235], v[46:49]
	v_mfma_f32_16x16x32_bf16 v[10:13], v[208:211], v[236:239], v[10:13]
	v_mfma_f32_16x16x32_bf16 v[14:17], v[208:211], v[240:243], v[14:17]
	ds_read_b128 v[208:211], v244 offset:25344
	s_waitcnt lgkmcnt(6)
	v_mfma_f32_16x16x32_bf16 v[50:53], v[196:199], v[212:215], v[50:53]
	ds_read_b128 v[228:231], v245 offset:55360
	s_waitcnt lgkmcnt(6)
	v_mfma_f32_16x16x32_bf16 v[54:57], v[196:199], v[216:219], v[54:57]
	ds_read_b128 v[232:235], v245 offset:57664
	s_waitcnt lgkmcnt(6)
	v_mfma_f32_16x16x32_bf16 v[18:21], v[196:199], v[220:223], v[18:21]
	ds_read_b128 v[236:239], v245 offset:59968
	s_waitcnt lgkmcnt(6)
	v_mfma_f32_16x16x32_bf16 v[22:25], v[196:199], v[224:227], v[22:25]
	ds_read_b128 v[240:243], v245 offset:62272
	ds_read_b128 v[196:199], v244 offset:18496
	s_waitcnt lgkmcnt(7)
	v_mfma_f32_16x16x32_bf16 v[58:61], v[200:203], v[212:215], v[58:61]
	v_mfma_f32_16x16x32_bf16 v[62:65], v[200:203], v[216:219], v[62:65]
	v_mfma_f32_16x16x32_bf16 v[26:29], v[200:203], v[220:223], v[26:29]
	v_mfma_f32_16x16x32_bf16 v[30:33], v[200:203], v[224:227], v[30:33]
	ds_read_b128 v[200:203], v244 offset:20800
	s_waitcnt lgkmcnt(7)
	v_mfma_f32_16x16x32_bf16 v[34:37], v[204:207], v[212:215], v[34:37]
	v_mfma_f32_16x16x32_bf16 v[38:41], v[204:207], v[216:219], v[38:41]
	v_mfma_f32_16x16x32_bf16 v[2:5], v[204:207], v[220:223], v[2:5]
	v_mfma_f32_16x16x32_bf16 v[6:9], v[204:207], v[224:227], v[6:9]
	ds_read_b128 v[204:207], v244 offset:23104
	s_waitcnt lgkmcnt(7)
	v_mfma_f32_16x16x32_bf16 v[42:45], v[208:211], v[212:215], v[42:45]
	v_mfma_f32_16x16x32_bf16 v[46:49], v[208:211], v[216:219], v[46:49]
	v_mfma_f32_16x16x32_bf16 v[10:13], v[208:211], v[220:223], v[10:13]
	v_mfma_f32_16x16x32_bf16 v[14:17], v[208:211], v[224:227], v[14:17]
	ds_read_b128 v[208:211], v244 offset:25408
	s_waitcnt lgkmcnt(3)
	v_mfma_f32_16x16x32_bf16 v[50:53], v[196:199], v[228:231], v[50:53]
	v_mfma_f32_16x16x32_bf16 v[54:57], v[196:199], v[232:235], v[54:57]
	v_mfma_f32_16x16x32_bf16 v[18:21], v[196:199], v[236:239], v[18:21]
	v_mfma_f32_16x16x32_bf16 v[22:25], v[196:199], v[240:243], v[22:25]
	s_waitcnt lgkmcnt(2)
	v_mfma_f32_16x16x32_bf16 v[58:61], v[200:203], v[228:231], v[58:61]
	v_mfma_f32_16x16x32_bf16 v[62:65], v[200:203], v[232:235], v[62:65]
	v_mfma_f32_16x16x32_bf16 v[26:29], v[200:203], v[236:239], v[26:29]
	v_mfma_f32_16x16x32_bf16 v[30:33], v[200:203], v[240:243], v[30:33]
	s_lshr_b32 s14, s2, 3
	s_bfe_u32 s13, s2, 0x10002
	s_cmp_lt_i32 s14, 1
	s_mov_b64 s[2:3], -1
	s_waitcnt lgkmcnt(0)
	s_barrier
	v_mfma_f32_16x16x32_bf16 v[34:37], v[204:207], v[228:231], v[34:37]
	v_mfma_f32_16x16x32_bf16 v[38:41], v[204:207], v[232:235], v[38:41]
	v_mfma_f32_16x16x32_bf16 v[2:5], v[204:207], v[236:239], v[2:5]
	v_mfma_f32_16x16x32_bf16 v[6:9], v[204:207], v[240:243], v[6:9]
	v_mfma_f32_16x16x32_bf16 v[42:45], v[208:211], v[228:231], v[42:45]
	v_mfma_f32_16x16x32_bf16 v[46:49], v[208:211], v[232:235], v[46:49]
	v_mfma_f32_16x16x32_bf16 v[10:13], v[208:211], v[236:239], v[10:13]
	v_mfma_f32_16x16x32_bf16 v[14:17], v[208:211], v[240:243], v[14:17]
	s_nop 7
	v_permlane16_swap_b32_e32 v50, v54
	v_permlane16_swap_b32_e32 v51, v55
	v_permlane16_swap_b32_e32 v52, v56
	v_permlane16_swap_b32_e32 v53, v57
	v_permlane16_swap_b32_e32 v58, v62
	v_permlane16_swap_b32_e32 v59, v63
	v_permlane16_swap_b32_e32 v60, v64
	v_permlane16_swap_b32_e32 v61, v65
	v_permlane16_swap_b32_e32 v18, v22
	v_permlane16_swap_b32_e32 v19, v23
	v_permlane16_swap_b32_e32 v20, v24
	v_permlane16_swap_b32_e32 v21, v25
	v_permlane16_swap_b32_e32 v26, v30
	v_permlane16_swap_b32_e32 v27, v31
	v_permlane16_swap_b32_e32 v28, v32
	v_permlane16_swap_b32_e32 v29, v33
	v_permlane16_swap_b32_e32 v34, v38
	v_permlane16_swap_b32_e32 v35, v39
	v_permlane16_swap_b32_e32 v36, v40
	v_permlane16_swap_b32_e32 v37, v41
	v_permlane16_swap_b32_e32 v42, v46
	v_permlane16_swap_b32_e32 v43, v47
	v_permlane16_swap_b32_e32 v44, v48
	v_permlane16_swap_b32_e32 v45, v49
	v_permlane16_swap_b32_e32 v2, v6
	v_permlane16_swap_b32_e32 v3, v7
	v_permlane16_swap_b32_e32 v4, v8
	v_permlane16_swap_b32_e32 v5, v9
	v_permlane16_swap_b32_e32 v10, v14
	v_permlane16_swap_b32_e32 v11, v15
	v_permlane16_swap_b32_e32 v12, v16
	v_permlane16_swap_b32_e32 v13, v17
	v_permlane32_swap_b32_e32 v50, v54
	v_permlane32_swap_b32_e32 v51, v55
	v_permlane32_swap_b32_e32 v52, v56
	v_permlane32_swap_b32_e32 v53, v57
	v_permlane32_swap_b32_e32 v58, v62
	v_permlane32_swap_b32_e32 v59, v63
	v_permlane32_swap_b32_e32 v60, v64
	v_permlane32_swap_b32_e32 v61, v65
	v_permlane32_swap_b32_e32 v18, v22
	v_permlane32_swap_b32_e32 v19, v23
	v_permlane32_swap_b32_e32 v20, v24
	v_permlane32_swap_b32_e32 v21, v25
	v_permlane32_swap_b32_e32 v26, v30
	v_permlane32_swap_b32_e32 v27, v31
	v_permlane32_swap_b32_e32 v28, v32
	v_permlane32_swap_b32_e32 v29, v33
	v_permlane32_swap_b32_e32 v34, v38
	v_permlane32_swap_b32_e32 v35, v39
	v_permlane32_swap_b32_e32 v36, v40
	v_permlane32_swap_b32_e32 v37, v41
	v_permlane32_swap_b32_e32 v42, v46
	v_permlane32_swap_b32_e32 v43, v47
	v_permlane32_swap_b32_e32 v44, v48
	v_permlane32_swap_b32_e32 v45, v49
	v_permlane32_swap_b32_e32 v2, v6
	v_permlane32_swap_b32_e32 v3, v7
	v_permlane32_swap_b32_e32 v4, v8
	v_permlane32_swap_b32_e32 v5, v9
	v_permlane32_swap_b32_e32 v10, v14
	v_permlane32_swap_b32_e32 v11, v15
	v_permlane32_swap_b32_e32 v12, v16
	v_permlane32_swap_b32_e32 v13, v17
	s_cbranch_scc1 .LBB0_755
	s_and_b32 s2, 0xffff, s14
	s_cmp_lg_u32 s2, 1
	s_mov_b64 s[2:3], -1
	s_cbranch_scc0 .LBB0_752
	s_cmp_eq_u32 s13, 0
	s_cselect_b32 s12, 3, 10
	s_mov_b64 s[2:3], 0

.LBB0_828:
	s_lshr_b32 s8, s0, 2
	s_lshl_b32 s0, s0, 7
	s_and_b32 s7, s0, 0x180
	v_or_b32_e32 v2, s7, v93
	v_lshlrev_b32_e32 v74, 10, v2
	s_add_i32 s8, s8, s4
	v_lshl_add_u64 v[66:67], v[76:77], 0, v[74:75]
	v_add_lshl_u32 v74, s7, v94, 10
	s_lshl_b32 s0, s8, 7
	v_lshl_add_u64 v[68:69], v[76:77], 0, v[74:75]
	v_add_lshl_u32 v74, s7, v95, 10
	v_lshl_add_u64 v[70:71], v[76:77], 0, v[74:75]
	v_add_lshl_u32 v74, s7, v96, 10
	v_or_b32_e32 v2, s0, v93
	v_lshl_add_u64 v[72:73], v[76:77], 0, v[74:75]
	v_lshlrev_b32_e32 v74, 10, v2
	v_lshl_add_u64 v[84:85], v[78:79], 0, v[74:75]
	v_add_lshl_u32 v74, s0, v94, 10
	v_lshl_add_u64 v[86:87], v[78:79], 0, v[74:75]
	v_add_lshl_u32 v74, s0, v95, 10
	v_lshl_add_u64 v[88:89], v[78:79], 0, v[74:75]
	v_add_lshl_u32 v74, s0, v96, 10
	v_lshl_add_u64 v[90:91], v[78:79], 0, v[74:75]
	global_load_dwordx4 v[2:5], v[66:67], off
	global_load_dwordx4 v[6:9], v[68:69], off
	global_load_dwordx4 v[10:13], v[70:71], off
	global_load_dwordx4 v[14:17], v[72:73], off
	global_load_dwordx4 v[18:21], v[84:85], off
	global_load_dwordx4 v[22:25], v[86:87], off
	global_load_dwordx4 v[26:29], v[88:89], off
	global_load_dwordx4 v[30:33], v[90:91], off
	global_load_dwordx4 v[102:105], v[66:67], off offset:128
	global_load_dwordx4 v[106:109], v[68:69], off offset:128
	global_load_dwordx4 v[110:113], v[70:71], off offset:128
	global_load_dwordx4 v[114:117], v[72:73], off offset:128
	global_load_dwordx4 v[118:121], v[84:85], off offset:128
	global_load_dwordx4 v[122:125], v[86:87], off offset:128
	global_load_dwordx4 v[126:129], v[88:89], off offset:128
	global_load_dwordx4 v[136:139], v[90:91], off offset:128
	s_waitcnt vmcnt(15)
	ds_write_b128 v100, v[2:5]
	s_waitcnt vmcnt(14)
	ds_write_b128 v100, v[6:9] offset:4608
	s_waitcnt vmcnt(13)
	ds_write_b128 v100, v[10:13] offset:9216
	s_waitcnt vmcnt(12)
	ds_write_b128 v100, v[14:17] offset:13824
	s_waitcnt vmcnt(11)
	ds_write_b128 v100, v[18:21] offset:36864
	s_waitcnt vmcnt(10)
	ds_write_b128 v100, v[22:25] offset:41472
	s_waitcnt vmcnt(9)
	ds_write_b128 v100, v[26:29] offset:46080
	s_waitcnt vmcnt(8)
	ds_write_b128 v100, v[30:33] offset:50688
	s_waitcnt lgkmcnt(0)
	s_barrier
	global_load_dwordx4 v[140:143], v[66:67], off offset:256
	global_load_dwordx4 v[144:147], v[68:69], off offset:256
	global_load_dwordx4 v[148:151], v[70:71], off offset:256
	global_load_dwordx4 v[152:155], v[72:73], off offset:256
	global_load_dwordx4 v[156:159], v[84:85], off offset:256
	global_load_dwordx4 v[160:163], v[86:87], off offset:256
	global_load_dwordx4 v[164:167], v[88:89], off offset:256
	global_load_dwordx4 v[168:171], v[90:91], off offset:256
	v_and_b32_e32 v246, 15, v1
	v_add_u32_e32 v246, 4, v246
	v_bfe_u32 v246, v246, 3, 1
	v_bfe_u32 v249, v1, 4, 2
	v_xor_b32_e32 v246, v246, v249
	v_bfe_u32 v249, v1, 5, 1
	v_sub_u32_e32 v246, v246, v249
	v_lshlrev_b32_e32 v246, 4, v246
	v_bfe_u32 v249, v1, 4, 1
	v_mul_u32_u24_e32 v249, 0x900, v249
	v_sub_u32_e32 v246, v246, v249
	v_add_u32_e32 v244, v246, v98
	v_add_u32_e32 v245, v246, v99
	ds_read_b128 v[212:215], v245 offset:36864
	ds_read_b128 v[196:199], v244
	ds_read_b128 v[216:219], v245 offset:39168
	ds_read_b128 v[220:223], v245 offset:41472
	ds_read_b128 v[224:227], v245 offset:43776
	ds_read_b128 v[200:203], v244 offset:2304
	ds_read_b128 v[204:207], v244 offset:4608
	ds_read_b128 v[208:211], v244 offset:6912
	s_waitcnt lgkmcnt(6)
	v_mfma_f32_16x16x32_bf16 v[50:53], v[196:199], v[212:215], 0
	ds_read_b128 v[228:231], v245 offset:36928
	s_waitcnt lgkmcnt(6)
	v_mfma_f32_16x16x32_bf16 v[54:57], v[196:199], v[216:219], 0
	ds_read_b128 v[232:235], v245 offset:39232
	s_waitcnt lgkmcnt(6)
	v_mfma_f32_16x16x32_bf16 v[18:21], v[196:199], v[220:223], 0
	ds_read_b128 v[236:239], v245 offset:41536
	s_waitcnt lgkmcnt(6)
	v_mfma_f32_16x16x32_bf16 v[22:25], v[196:199], v[224:227], 0
	ds_read_b128 v[240:243], v245 offset:43840
	ds_read_b128 v[196:199], v244 offset:64
	s_waitcnt lgkmcnt(7)
	v_mfma_f32_16x16x32_bf16 v[58:61], v[200:203], v[212:215], 0
	v_mfma_f32_16x16x32_bf16 v[62:65], v[200:203], v[216:219], 0
	v_mfma_f32_16x16x32_bf16 v[26:29], v[200:203], v[220:223], 0
	v_mfma_f32_16x16x32_bf16 v[30:33], v[200:203], v[224:227], 0
	ds_read_b128 v[200:203], v244 offset:2368
	s_waitcnt lgkmcnt(7)
	v_mfma_f32_16x16x32_bf16 v[34:37], v[204:207], v[212:215], 0
	v_mfma_f32_16x16x32_bf16 v[38:41], v[204:207], v[216:219], 0
	v_mfma_f32_16x16x32_bf16 v[2:5], v[204:207], v[220:223], 0
	v_mfma_f32_16x16x32_bf16 v[6:9], v[204:207], v[224:227], 0
	ds_read_b128 v[204:207], v244 offset:4672
	s_setprio 1
	s_waitcnt vmcnt(15)
	ds_write_b128 v100, v[102:105] offset:18432
	s_waitcnt vmcnt(14)
	ds_write_b128 v100, v[106:109] offset:23040
	s_waitcnt lgkmcnt(9)
	v_mfma_f32_16x16x32_bf16 v[42:45], v[208:211], v[212:215], 0
	v_mfma_f32_16x16x32_bf16 v[46:49], v[208:211], v[216:219], 0
	v_mfma_f32_16x16x32_bf16 v[10:13], v[208:211], v[220:223], 0
	v_mfma_f32_16x16x32_bf16 v[14:17], v[208:211], v[224:227], 0
	ds_read_b128 v[208:211], v244 offset:6976
	s_waitcnt vmcnt(13)
	ds_write_b128 v100, v[110:113] offset:27648
	s_waitcnt vmcnt(12)
	ds_write_b128 v100, v[114:117] offset:32256
	s_waitcnt lgkmcnt(7)
	v_mfma_f32_16x16x32_bf16 v[50:53], v[196:199], v[228:231], v[50:53]
	v_mfma_f32_16x16x32_bf16 v[54:57], v[196:199], v[232:235], v[54:57]
	v_mfma_f32_16x16x32_bf16 v[18:21], v[196:199], v[236:239], v[18:21]
	v_mfma_f32_16x16x32_bf16 v[22:25], v[196:199], v[240:243], v[22:25]
	s_waitcnt vmcnt(11)
	ds_write_b128 v100, v[118:121] offset:55296
	s_waitcnt vmcnt(10)
	ds_write_b128 v100, v[122:125] offset:59904
	s_waitcnt lgkmcnt(8)
	v_mfma_f32_16x16x32_bf16 v[58:61], v[200:203], v[228:231], v[58:61]
	v_mfma_f32_16x16x32_bf16 v[62:65], v[200:203], v[232:235], v[62:65]
	v_mfma_f32_16x16x32_bf16 v[26:29], v[200:203], v[236:239], v[26:29]
	v_mfma_f32_16x16x32_bf16 v[30:33], v[200:203], v[240:243], v[30:33]
	s_waitcnt vmcnt(9)
	ds_write_b128 v100, v[126:129] offset:64512
	s_waitcnt vmcnt(8)
	ds_write_b128 v101, v[136:139] offset:32256
	s_waitcnt lgkmcnt(0)
	s_barrier
	ds_read_b128 v[212:215], v245 offset:55296
	ds_read_b128 v[196:199], v244 offset:18432
	ds_read_b128 v[216:219], v245 offset:57600
	ds_read_b128 v[220:223], v245 offset:59904
	ds_read_b128 v[224:227], v245 offset:62208
	ds_read_b128 v[200:203], v244 offset:20736
	s_setprio 0
	v_mfma_f32_16x16x32_bf16 v[34:37], v[204:207], v[228:231], v[34:37]
	v_mfma_f32_16x16x32_bf16 v[38:41], v[204:207], v[232:235], v[38:41]
	v_mfma_f32_16x16x32_bf16 v[2:5], v[204:207], v[236:239], v[2:5]
	v_mfma_f32_16x16x32_bf16 v[6:9], v[204:207], v[240:243], v[6:9]
	ds_read_b128 v[204:207], v244 offset:23040
	v_mfma_f32_16x16x32_bf16 v[42:45], v[208:211], v[228:231], v[42:45]
	v_mfma_f32_16x16x32_bf16 v[46:49], v[208:211], v[232:235], v[46:49]
	v_mfma_f32_16x16x32_bf16 v[10:13], v[208:211], v[236:239], v[10:13]
	v_mfma_f32_16x16x32_bf16 v[14:17], v[208:211], v[240:243], v[14:17]
	ds_read_b128 v[208:211], v244 offset:25344
	global_load_dwordx4 v[102:105], v[66:67], off offset:384
	global_load_dwordx4 v[106:109], v[68:69], off offset:384
	global_load_dwordx4 v[110:113], v[70:71], off offset:384
	global_load_dwordx4 v[114:117], v[72:73], off offset:384
	global_load_dwordx4 v[118:121], v[84:85], off offset:384
	global_load_dwordx4 v[122:125], v[86:87], off offset:384
	global_load_dwordx4 v[126:129], v[88:89], off offset:384
	global_load_dwordx4 v[136:139], v[90:91], off offset:384
	s_waitcnt lgkmcnt(6)
	v_mfma_f32_16x16x32_bf16 v[50:53], v[196:199], v[212:215], v[50:53]
	ds_read_b128 v[228:231], v245 offset:55360
	s_waitcnt lgkmcnt(6)
	v_mfma_f32_16x16x32_bf16 v[54:57], v[196:199], v[216:219], v[54:57]
	ds_read_b128 v[232:235], v245 offset:57664
	s_waitcnt lgkmcnt(6)
	v_mfma_f32_16x16x32_bf16 v[18:21], v[196:199], v[220:223], v[18:21]
	ds_read_b128 v[236:239], v245 offset:59968
	s_waitcnt lgkmcnt(6)
	v_mfma_f32_16x16x32_bf16 v[22:25], v[196:199], v[224:227], v[22:25]
	ds_read_b128 v[240:243], v245 offset:62272
	ds_read_b128 v[196:199], v244 offset:18496
	s_waitcnt lgkmcnt(7)
	v_mfma_f32_16x16x32_bf16 v[58:61], v[200:203], v[212:215], v[58:61]
	v_mfma_f32_16x16x32_bf16 v[62:65], v[200:203], v[216:219], v[62:65]
	v_mfma_f32_16x16x32_bf16 v[26:29], v[200:203], v[220:223], v[26:29]
	v_mfma_f32_16x16x32_bf16 v[30:33], v[200:203], v[224:227], v[30:33]
	ds_read_b128 v[200:203], v244 offset:20800
	s_waitcnt lgkmcnt(7)
	v_mfma_f32_16x16x32_bf16 v[34:37], v[204:207], v[212:215], v[34:37]
	v_mfma_f32_16x16x32_bf16 v[38:41], v[204:207], v[216:219], v[38:41]
	v_mfma_f32_16x16x32_bf16 v[2:5], v[204:207], v[220:223], v[2:5]
	v_mfma_f32_16x16x32_bf16 v[6:9], v[204:207], v[224:227], v[6:9]
	ds_read_b128 v[204:207], v244 offset:23104
	s_setprio 1
	s_waitcnt vmcnt(15)
	ds_write_b128 v100, v[140:143]
	s_waitcnt vmcnt(14)
	ds_write_b128 v100, v[144:147] offset:4608
	s_waitcnt lgkmcnt(9)
	v_mfma_f32_16x16x32_bf16 v[42:45], v[208:211], v[212:215], v[42:45]
	v_mfma_f32_16x16x32_bf16 v[46:49], v[208:211], v[216:219], v[46:49]
	v_mfma_f32_16x16x32_bf16 v[10:13], v[208:211], v[220:223], v[10:13]
	v_mfma_f32_16x16x32_bf16 v[14:17], v[208:211], v[224:227], v[14:17]
	ds_read_b128 v[208:211], v244 offset:25408
	s_waitcnt vmcnt(13)
	ds_write_b128 v100, v[148:151] offset:9216
	s_waitcnt vmcnt(12)
	ds_write_b128 v100, v[152:155] offset:13824
	s_waitcnt lgkmcnt(7)
	v_mfma_f32_16x16x32_bf16 v[50:53], v[196:199], v[228:231], v[50:53]
	v_mfma_f32_16x16x32_bf16 v[54:57], v[196:199], v[232:235], v[54:57]
	v_mfma_f32_16x16x32_bf16 v[18:21], v[196:199], v[236:239], v[18:21]
	v_mfma_f32_16x16x32_bf16 v[22:25], v[196:199], v[240:243], v[22:25]
	s_waitcnt vmcnt(11)
	ds_write_b128 v100, v[156:159] offset:36864
	s_waitcnt vmcnt(10)
	ds_write_b128 v100, v[160:163] offset:41472
	s_waitcnt lgkmcnt(8)
	v_mfma_f32_16x16x32_bf16 v[58:61], v[200:203], v[228:231], v[58:61]
	v_mfma_f32_16x16x32_bf16 v[62:65], v[200:203], v[232:235], v[62:65]
	v_mfma_f32_16x16x32_bf16 v[26:29], v[200:203], v[236:239], v[26:29]
	v_mfma_f32_16x16x32_bf16 v[30:33], v[200:203], v[240:243], v[30:33]
	s_waitcnt vmcnt(9)
	ds_write_b128 v100, v[164:167] offset:46080
	s_waitcnt vmcnt(8)
	ds_write_b128 v100, v[168:171] offset:50688
	s_waitcnt lgkmcnt(0)
	s_barrier
	ds_read_b128 v[212:215], v245 offset:36864
	ds_read_b128 v[196:199], v244
	ds_read_b128 v[216:219], v245 offset:39168
	ds_read_b128 v[220:223], v245 offset:41472
	ds_read_b128 v[224:227], v245 offset:43776
	ds_read_b128 v[200:203], v244 offset:2304
	s_setprio 0
	v_mfma_f32_16x16x32_bf16 v[34:37], v[204:207], v[228:231], v[34:37]
	v_mfma_f32_16x16x32_bf16 v[38:41], v[204:207], v[232:235], v[38:41]
	v_mfma_f32_16x16x32_bf16 v[2:5], v[204:207], v[236:239], v[2:5]
	v_mfma_f32_16x16x32_bf16 v[6:9], v[204:207], v[240:243], v[6:9]
	ds_read_b128 v[204:207], v244 offset:4608
	v_mfma_f32_16x16x32_bf16 v[42:45], v[208:211], v[228:231], v[42:45]
	v_mfma_f32_16x16x32_bf16 v[46:49], v[208:211], v[232:235], v[46:49]
	v_mfma_f32_16x16x32_bf16 v[10:13], v[208:211], v[236:239], v[10:13]
	v_mfma_f32_16x16x32_bf16 v[14:17], v[208:211], v[240:243], v[14:17]
	ds_read_b128 v[208:211], v244 offset:6912
	global_load_dwordx4 v[140:143], v[66:67], off offset:512
	global_load_dwordx4 v[144:147], v[68:69], off offset:512
	global_load_dwordx4 v[148:151], v[70:71], off offset:512
	global_load_dwordx4 v[152:155], v[72:73], off offset:512
	global_load_dwordx4 v[156:159], v[84:85], off offset:512
	global_load_dwordx4 v[160:163], v[86:87], off offset:512
	global_load_dwordx4 v[164:167], v[88:89], off offset:512
	global_load_dwordx4 v[168:171], v[90:91], off offset:512
	s_waitcnt lgkmcnt(6)
	v_mfma_f32_16x16x32_bf16 v[50:53], v[196:199], v[212:215], v[50:53]
	ds_read_b128 v[228:231], v245 offset:36928
	s_waitcnt lgkmcnt(6)
	v_mfma_f32_16x16x32_bf16 v[54:57], v[196:199], v[216:219], v[54:57]
	ds_read_b128 v[232:235], v245 offset:39232
	s_waitcnt lgkmcnt(6)
	v_mfma_f32_16x16x32_bf16 v[18:21], v[196:199], v[220:223], v[18:21]
	ds_read_b128 v[236:239], v245 offset:41536
	s_waitcnt lgkmcnt(6)
	v_mfma_f32_16x16x32_bf16 v[22:25], v[196:199], v[224:227], v[22:25]
	ds_read_b128 v[240:243], v245 offset:43840
	ds_read_b128 v[196:199], v244 offset:64
	s_waitcnt lgkmcnt(7)
	v_mfma_f32_16x16x32_bf16 v[58:61], v[200:203], v[212:215], v[58:61]
	v_mfma_f32_16x16x32_bf16 v[62:65], v[200:203], v[216:219], v[62:65]
	v_mfma_f32_16x16x32_bf16 v[26:29], v[200:203], v[220:223], v[26:29]
	v_mfma_f32_16x16x32_bf16 v[30:33], v[200:203], v[224:227], v[30:33]
	ds_read_b128 v[200:203], v244 offset:2368
	s_waitcnt lgkmcnt(7)
	v_mfma_f32_16x16x32_bf16 v[34:37], v[204:207], v[212:215], v[34:37]
	v_mfma_f32_16x16x32_bf16 v[38:41], v[204:207], v[216:219], v[38:41]
	v_mfma_f32_16x16x32_bf16 v[2:5], v[204:207], v[220:223], v[2:5]
	v_mfma_f32_16x16x32_bf16 v[6:9], v[204:207], v[224:227], v[6:9]
	ds_read_b128 v[204:207], v244 offset:4672
	s_setprio 1
	s_waitcnt vmcnt(15)
	ds_write_b128 v100, v[102:105] offset:18432
	s_waitcnt vmcnt(14)
	ds_write_b128 v100, v[106:109] offset:23040
	s_waitcnt lgkmcnt(9)
	v_mfma_f32_16x16x32_bf16 v[42:45], v[208:211], v[212:215], v[42:45]
	v_mfma_f32_16x16x32_bf16 v[46:49], v[208:211], v[216:219], v[46:49]
	v_mfma_f32_16x16x32_bf16 v[10:13], v[208:211], v[220:223], v[10:13]
	v_mfma_f32_16x16x32_bf16 v[14:17], v[208:211], v[224:227], v[14:17]
	ds_read_b128 v[208:211], v244 offset:6976
	s_waitcnt vmcnt(13)
	ds_write_b128 v100, v[110:113] offset:27648
	s_waitcnt vmcnt(12)
	ds_write_b128 v100, v[114:117] offset:32256
	s_waitcnt lgkmcnt(7)
	v_mfma_f32_16x16x32_bf16 v[50:53], v[196:199], v[228:231], v[50:53]
	v_mfma_f32_16x16x32_bf16 v[54:57], v[196:199], v[232:235], v[54:57]
	v_mfma_f32_16x16x32_bf16 v[18:21], v[196:199], v[236:239], v[18:21]
	v_mfma_f32_16x16x32_bf16 v[22:25], v[196:199], v[240:243], v[22:25]
	s_waitcnt vmcnt(11)
	ds_write_b128 v100, v[118:121] offset:55296
	s_waitcnt vmcnt(10)
	ds_write_b128 v100, v[122:125] offset:59904
	s_waitcnt lgkmcnt(8)
	v_mfma_f32_16x16x32_bf16 v[58:61], v[200:203], v[228:231], v[58:61]
	v_mfma_f32_16x16x32_bf16 v[62:65], v[200:203], v[232:235], v[62:65]
	v_mfma_f32_16x16x32_bf16 v[26:29], v[200:203], v[236:239], v[26:29]
	v_mfma_f32_16x16x32_bf16 v[30:33], v[200:203], v[240:243], v[30:33]
	s_waitcnt vmcnt(9)
	ds_write_b128 v100, v[126:129] offset:64512
	s_waitcnt vmcnt(8)
	ds_write_b128 v101, v[136:139] offset:32256
	s_waitcnt lgkmcnt(0)
	s_barrier
	ds_read_b128 v[212:215], v245 offset:55296
	ds_read_b128 v[196:199], v244 offset:18432
	ds_read_b128 v[216:219], v245 offset:57600
	ds_read_b128 v[220:223], v245 offset:59904
	ds_read_b128 v[224:227], v245 offset:62208
	ds_read_b128 v[200:203], v244 offset:20736
	s_setprio 0
	v_mfma_f32_16x16x32_bf16 v[34:37], v[204:207], v[228:231], v[34:37]
	v_mfma_f32_16x16x32_bf16 v[38:41], v[204:207], v[232:235], v[38:41]
	v_mfma_f32_16x16x32_bf16 v[2:5], v[204:207], v[236:239], v[2:5]
	v_mfma_f32_16x16x32_bf16 v[6:9], v[204:207], v[240:243], v[6:9]
	ds_read_b128 v[204:207], v244 offset:23040
	v_mfma_f32_16x16x32_bf16 v[42:45], v[208:211], v[228:231], v[42:45]
	v_mfma_f32_16x16x32_bf16 v[46:49], v[208:211], v[232:235], v[46:49]
	v_mfma_f32_16x16x32_bf16 v[10:13], v[208:211], v[236:239], v[10:13]
	v_mfma_f32_16x16x32_bf16 v[14:17], v[208:211], v[240:243], v[14:17]
	ds_read_b128 v[208:211], v244 offset:25344
	global_load_dwordx4 v[102:105], v[66:67], off offset:640
	global_load_dwordx4 v[106:109], v[68:69], off offset:640
	global_load_dwordx4 v[110:113], v[70:71], off offset:640
	global_load_dwordx4 v[114:117], v[72:73], off offset:640
	global_load_dwordx4 v[118:121], v[84:85], off offset:640
	global_load_dwordx4 v[122:125], v[86:87], off offset:640
	global_load_dwordx4 v[126:129], v[88:89], off offset:640
	global_load_dwordx4 v[136:139], v[90:91], off offset:640
	s_waitcnt lgkmcnt(6)
	v_mfma_f32_16x16x32_bf16 v[50:53], v[196:199], v[212:215], v[50:53]
	ds_read_b128 v[228:231], v245 offset:55360
	s_waitcnt lgkmcnt(6)
	v_mfma_f32_16x16x32_bf16 v[54:57], v[196:199], v[216:219], v[54:57]
	ds_read_b128 v[232:235], v245 offset:57664
	s_waitcnt lgkmcnt(6)
	v_mfma_f32_16x16x32_bf16 v[18:21], v[196:199], v[220:223], v[18:21]
	ds_read_b128 v[236:239], v245 offset:59968
	s_waitcnt lgkmcnt(6)
	v_mfma_f32_16x16x32_bf16 v[22:25], v[196:199], v[224:227], v[22:25]
	ds_read_b128 v[240:243], v245 offset:62272
	ds_read_b128 v[196:199], v244 offset:18496
	s_waitcnt lgkmcnt(7)
	v_mfma_f32_16x16x32_bf16 v[58:61], v[200:203], v[212:215], v[58:61]
	v_mfma_f32_16x16x32_bf16 v[62:65], v[200:203], v[216:219], v[62:65]
	v_mfma_f32_16x16x32_bf16 v[26:29], v[200:203], v[220:223], v[26:29]
	v_mfma_f32_16x16x32_bf16 v[30:33], v[200:203], v[224:227], v[30:33]
	ds_read_b128 v[200:203], v244 offset:20800
	s_waitcnt lgkmcnt(7)
	v_mfma_f32_16x16x32_bf16 v[34:37], v[204:207], v[212:215], v[34:37]
	v_mfma_f32_16x16x32_bf16 v[38:41], v[204:207], v[216:219], v[38:41]
	v_mfma_f32_16x16x32_bf16 v[2:5], v[204:207], v[220:223], v[2:5]
	v_mfma_f32_16x16x32_bf16 v[6:9], v[204:207], v[224:227], v[6:9]
	ds_read_b128 v[204:207], v244 offset:23104
	s_setprio 1
	s_waitcnt vmcnt(15)
	ds_write_b128 v100, v[140:143]
	s_waitcnt vmcnt(14)
	ds_write_b128 v100, v[144:147] offset:4608
	s_waitcnt lgkmcnt(9)
	v_mfma_f32_16x16x32_bf16 v[42:45], v[208:211], v[212:215], v[42:45]
	v_mfma_f32_16x16x32_bf16 v[46:49], v[208:211], v[216:219], v[46:49]
	v_mfma_f32_16x16x32_bf16 v[10:13], v[208:211], v[220:223], v[10:13]
	v_mfma_f32_16x16x32_bf16 v[14:17], v[208:211], v[224:227], v[14:17]
	ds_read_b128 v[208:211], v244 offset:25408
	s_waitcnt vmcnt(13)
	ds_write_b128 v100, v[148:151] offset:9216
	s_waitcnt vmcnt(12)
	ds_write_b128 v100, v[152:155] offset:13824
	s_waitcnt lgkmcnt(7)
	v_mfma_f32_16x16x32_bf16 v[50:53], v[196:199], v[228:231], v[50:53]
	v_mfma_f32_16x16x32_bf16 v[54:57], v[196:199], v[232:235], v[54:57]
	v_mfma_f32_16x16x32_bf16 v[18:21], v[196:199], v[236:239], v[18:21]
	v_mfma_f32_16x16x32_bf16 v[22:25], v[196:199], v[240:243], v[22:25]
	s_waitcnt vmcnt(11)
	ds_write_b128 v100, v[156:159] offset:36864
	s_waitcnt vmcnt(10)
	ds_write_b128 v100, v[160:163] offset:41472
	s_waitcnt lgkmcnt(8)
	v_mfma_f32_16x16x32_bf16 v[58:61], v[200:203], v[228:231], v[58:61]
	v_mfma_f32_16x16x32_bf16 v[62:65], v[200:203], v[232:235], v[62:65]
	v_mfma_f32_16x16x32_bf16 v[26:29], v[200:203], v[236:239], v[26:29]
	v_mfma_f32_16x16x32_bf16 v[30:33], v[200:203], v[240:243], v[30:33]
	s_waitcnt vmcnt(9)
	ds_write_b128 v100, v[164:167] offset:46080
	s_waitcnt vmcnt(8)
	ds_write_b128 v100, v[168:171] offset:50688
	s_waitcnt lgkmcnt(0)
	s_barrier
	ds_read_b128 v[212:215], v245 offset:36864
	ds_read_b128 v[196:199], v244
	ds_read_b128 v[216:219], v245 offset:39168
	ds_read_b128 v[220:223], v245 offset:41472
	ds_read_b128 v[224:227], v245 offset:43776
	ds_read_b128 v[200:203], v244 offset:2304
	s_setprio 0
	v_mfma_f32_16x16x32_bf16 v[34:37], v[204:207], v[228:231], v[34:37]
	v_mfma_f32_16x16x32_bf16 v[38:41], v[204:207], v[232:235], v[38:41]
	v_mfma_f32_16x16x32_bf16 v[2:5], v[204:207], v[236:239], v[2:5]
	v_mfma_f32_16x16x32_bf16 v[6:9], v[204:207], v[240:243], v[6:9]
	ds_read_b128 v[204:207], v244 offset:4608
	v_mfma_f32_16x16x32_bf16 v[42:45], v[208:211], v[228:231], v[42:45]
	v_mfma_f32_16x16x32_bf16 v[46:49], v[208:211], v[232:235], v[46:49]
	v_mfma_f32_16x16x32_bf16 v[10:13], v[208:211], v[236:239], v[10:13]
	v_mfma_f32_16x16x32_bf16 v[14:17], v[208:211], v[240:243], v[14:17]
	ds_read_b128 v[208:211], v244 offset:6912
	global_load_dwordx4 v[140:143], v[66:67], off offset:768
	global_load_dwordx4 v[144:147], v[68:69], off offset:768
	global_load_dwordx4 v[148:151], v[70:71], off offset:768
	global_load_dwordx4 v[152:155], v[72:73], off offset:768
	global_load_dwordx4 v[156:159], v[84:85], off offset:768
	global_load_dwordx4 v[160:163], v[86:87], off offset:768
	global_load_dwordx4 v[164:167], v[88:89], off offset:768
	global_load_dwordx4 v[168:171], v[90:91], off offset:768
	s_waitcnt lgkmcnt(6)
	v_mfma_f32_16x16x32_bf16 v[50:53], v[196:199], v[212:215], v[50:53]
	ds_read_b128 v[228:231], v245 offset:36928
	s_waitcnt lgkmcnt(6)
	v_mfma_f32_16x16x32_bf16 v[54:57], v[196:199], v[216:219], v[54:57]
	ds_read_b128 v[232:235], v245 offset:39232
	s_waitcnt lgkmcnt(6)
	v_mfma_f32_16x16x32_bf16 v[18:21], v[196:199], v[220:223], v[18:21]
	ds_read_b128 v[236:239], v245 offset:41536
	s_waitcnt lgkmcnt(6)
	v_mfma_f32_16x16x32_bf16 v[22:25], v[196:199], v[224:227], v[22:25]
	ds_read_b128 v[240:243], v245 offset:43840
	ds_read_b128 v[196:199], v244 offset:64
	s_waitcnt lgkmcnt(7)
	v_mfma_f32_16x16x32_bf16 v[58:61], v[200:203], v[212:215], v[58:61]
	v_mfma_f32_16x16x32_bf16 v[62:65], v[200:203], v[216:219], v[62:65]
	v_mfma_f32_16x16x32_bf16 v[26:29], v[200:203], v[220:223], v[26:29]
	v_mfma_f32_16x16x32_bf16 v[30:33], v[200:203], v[224:227], v[30:33]
	ds_read_b128 v[200:203], v244 offset:2368
	s_waitcnt lgkmcnt(7)
	v_mfma_f32_16x16x32_bf16 v[34:37], v[204:207], v[212:215], v[34:37]
	v_mfma_f32_16x16x32_bf16 v[38:41], v[204:207], v[216:219], v[38:41]
	v_mfma_f32_16x16x32_bf16 v[2:5], v[204:207], v[220:223], v[2:5]
	v_mfma_f32_16x16x32_bf16 v[6:9], v[204:207], v[224:227], v[6:9]
	ds_read_b128 v[204:207], v244 offset:4672
	s_setprio 1
	s_waitcnt vmcnt(15)
	ds_write_b128 v100, v[102:105] offset:18432
	s_waitcnt vmcnt(14)
	ds_write_b128 v100, v[106:109] offset:23040
	s_waitcnt lgkmcnt(9)
	v_mfma_f32_16x16x32_bf16 v[42:45], v[208:211], v[212:215], v[42:45]
	v_mfma_f32_16x16x32_bf16 v[46:49], v[208:211], v[216:219], v[46:49]
	v_mfma_f32_16x16x32_bf16 v[10:13], v[208:211], v[220:223], v[10:13]
	v_mfma_f32_16x16x32_bf16 v[14:17], v[208:211], v[224:227], v[14:17]
	ds_read_b128 v[208:211], v244 offset:6976
	s_waitcnt vmcnt(13)
	ds_write_b128 v100, v[110:113] offset:27648
	s_waitcnt vmcnt(12)
	ds_write_b128 v100, v[114:117] offset:32256
	s_waitcnt lgkmcnt(7)
	v_mfma_f32_16x16x32_bf16 v[50:53], v[196:199], v[228:231], v[50:53]
	v_mfma_f32_16x16x32_bf16 v[54:57], v[196:199], v[232:235], v[54:57]
	v_mfma_f32_16x16x32_bf16 v[18:21], v[196:199], v[236:239], v[18:21]
	v_mfma_f32_16x16x32_bf16 v[22:25], v[196:199], v[240:243], v[22:25]
	s_waitcnt vmcnt(11)
	ds_write_b128 v100, v[118:121] offset:55296
	s_waitcnt vmcnt(10)
	ds_write_b128 v100, v[122:125] offset:59904
	s_waitcnt lgkmcnt(8)
	v_mfma_f32_16x16x32_bf16 v[58:61], v[200:203], v[228:231], v[58:61]
	v_mfma_f32_16x16x32_bf16 v[62:65], v[200:203], v[232:235], v[62:65]
	v_mfma_f32_16x16x32_bf16 v[26:29], v[200:203], v[236:239], v[26:29]
	v_mfma_f32_16x16x32_bf16 v[30:33], v[200:203], v[240:243], v[30:33]
	s_waitcnt vmcnt(9)
	ds_write_b128 v100, v[126:129] offset:64512
	s_waitcnt vmcnt(8)
	ds_write_b128 v101, v[136:139] offset:32256
	s_waitcnt lgkmcnt(0)
	s_barrier
	ds_read_b128 v[212:215], v245 offset:55296
	ds_read_b128 v[196:199], v244 offset:18432
	ds_read_b128 v[216:219], v245 offset:57600
	ds_read_b128 v[220:223], v245 offset:59904
	ds_read_b128 v[224:227], v245 offset:62208
	ds_read_b128 v[200:203], v244 offset:20736
	s_setprio 0
	v_mfma_f32_16x16x32_bf16 v[34:37], v[204:207], v[228:231], v[34:37]
	v_mfma_f32_16x16x32_bf16 v[38:41], v[204:207], v[232:235], v[38:41]
	v_mfma_f32_16x16x32_bf16 v[2:5], v[204:207], v[236:239], v[2:5]
	v_mfma_f32_16x16x32_bf16 v[6:9], v[204:207], v[240:243], v[6:9]
	ds_read_b128 v[204:207], v244 offset:23040
	v_mfma_f32_16x16x32_bf16 v[42:45], v[208:211], v[228:231], v[42:45]
	v_mfma_f32_16x16x32_bf16 v[46:49], v[208:211], v[232:235], v[46:49]
	v_mfma_f32_16x16x32_bf16 v[10:13], v[208:211], v[236:239], v[10:13]
	v_mfma_f32_16x16x32_bf16 v[14:17], v[208:211], v[240:243], v[14:17]
	ds_read_b128 v[208:211], v244 offset:25344
	global_load_dwordx4 v[102:105], v[66:67], off offset:896
	s_nop 0
	global_load_dwordx4 v[66:69], v[68:69], off offset:896
	s_nop 0
	global_load_dwordx4 v[106:109], v[70:71], off offset:896
	s_nop 0
	global_load_dwordx4 v[70:73], v[72:73], off offset:896
	s_nop 0
	global_load_dwordx4 v[110:113], v[84:85], off offset:896
	s_nop 0
	global_load_dwordx4 v[84:87], v[86:87], off offset:896
	s_nop 0
	global_load_dwordx4 v[114:117], v[88:89], off offset:896
	s_nop 0
	global_load_dwordx4 v[88:91], v[90:91], off offset:896
	s_waitcnt lgkmcnt(6)
	v_mfma_f32_16x16x32_bf16 v[50:53], v[196:199], v[212:215], v[50:53]
	ds_read_b128 v[228:231], v245 offset:55360
	s_waitcnt lgkmcnt(6)
	v_mfma_f32_16x16x32_bf16 v[54:57], v[196:199], v[216:219], v[54:57]
	ds_read_b128 v[232:235], v245 offset:57664
	s_waitcnt lgkmcnt(6)
	v_mfma_f32_16x16x32_bf16 v[18:21], v[196:199], v[220:223], v[18:21]
	ds_read_b128 v[236:239], v245 offset:59968
	s_waitcnt lgkmcnt(6)
	v_mfma_f32_16x16x32_bf16 v[22:25], v[196:199], v[224:227], v[22:25]
	ds_read_b128 v[240:243], v245 offset:62272
	ds_read_b128 v[196:199], v244 offset:18496
	s_waitcnt lgkmcnt(7)
	v_mfma_f32_16x16x32_bf16 v[58:61], v[200:203], v[212:215], v[58:61]
	v_mfma_f32_16x16x32_bf16 v[62:65], v[200:203], v[216:219], v[62:65]
	v_mfma_f32_16x16x32_bf16 v[26:29], v[200:203], v[220:223], v[26:29]
	v_mfma_f32_16x16x32_bf16 v[30:33], v[200:203], v[224:227], v[30:33]
	ds_read_b128 v[200:203], v244 offset:20800
	s_waitcnt lgkmcnt(7)
	v_mfma_f32_16x16x32_bf16 v[34:37], v[204:207], v[212:215], v[34:37]
	v_mfma_f32_16x16x32_bf16 v[38:41], v[204:207], v[216:219], v[38:41]
	v_mfma_f32_16x16x32_bf16 v[2:5], v[204:207], v[220:223], v[2:5]
	v_mfma_f32_16x16x32_bf16 v[6:9], v[204:207], v[224:227], v[6:9]
	ds_read_b128 v[204:207], v244 offset:23104
	s_setprio 1
	s_waitcnt vmcnt(15)
	ds_write_b128 v100, v[140:143]
	s_waitcnt vmcnt(14)
	ds_write_b128 v100, v[144:147] offset:4608
	s_waitcnt lgkmcnt(9)
	v_mfma_f32_16x16x32_bf16 v[42:45], v[208:211], v[212:215], v[42:45]
	v_mfma_f32_16x16x32_bf16 v[46:49], v[208:211], v[216:219], v[46:49]
	v_mfma_f32_16x16x32_bf16 v[10:13], v[208:211], v[220:223], v[10:13]
	v_mfma_f32_16x16x32_bf16 v[14:17], v[208:211], v[224:227], v[14:17]
	ds_read_b128 v[208:211], v244 offset:25408
	s_waitcnt vmcnt(13)
	ds_write_b128 v100, v[148:151] offset:9216
	s_waitcnt vmcnt(12)
	ds_write_b128 v100, v[152:155] offset:13824
	s_waitcnt lgkmcnt(7)
	v_mfma_f32_16x16x32_bf16 v[50:53], v[196:199], v[228:231], v[50:53]
	v_mfma_f32_16x16x32_bf16 v[54:57], v[196:199], v[232:235], v[54:57]
	v_mfma_f32_16x16x32_bf16 v[18:21], v[196:199], v[236:239], v[18:21]
	v_mfma_f32_16x16x32_bf16 v[22:25], v[196:199], v[240:243], v[22:25]
	s_waitcnt vmcnt(11)
	ds_write_b128 v100, v[156:159] offset:36864
	s_waitcnt vmcnt(10)
	ds_write_b128 v100, v[160:163] offset:41472
	s_waitcnt lgkmcnt(8)
	v_mfma_f32_16x16x32_bf16 v[58:61], v[200:203], v[228:231], v[58:61]
	v_mfma_f32_16x16x32_bf16 v[62:65], v[200:203], v[232:235], v[62:65]
	v_mfma_f32_16x16x32_bf16 v[26:29], v[200:203], v[236:239], v[26:29]
	v_mfma_f32_16x16x32_bf16 v[30:33], v[200:203], v[240:243], v[30:33]
	s_waitcnt vmcnt(9)
	ds_write_b128 v100, v[164:167] offset:46080
	s_waitcnt vmcnt(8)
	ds_write_b128 v100, v[168:171] offset:50688
	s_waitcnt lgkmcnt(0)
	s_barrier
	ds_read_b128 v[212:215], v245 offset:36864
	ds_read_b128 v[196:199], v244
	ds_read_b128 v[216:219], v245 offset:39168
	ds_read_b128 v[220:223], v245 offset:41472
	ds_read_b128 v[224:227], v245 offset:43776
	ds_read_b128 v[200:203], v244 offset:2304
	s_setprio 0
	v_mfma_f32_16x16x32_bf16 v[34:37], v[204:207], v[228:231], v[34:37]
	v_mfma_f32_16x16x32_bf16 v[38:41], v[204:207], v[232:235], v[38:41]
	v_mfma_f32_16x16x32_bf16 v[2:5], v[204:207], v[236:239], v[2:5]
	v_mfma_f32_16x16x32_bf16 v[6:9], v[204:207], v[240:243], v[6:9]
	ds_read_b128 v[204:207], v244 offset:4608
	v_mfma_f32_16x16x32_bf16 v[42:45], v[208:211], v[228:231], v[42:45]
	v_mfma_f32_16x16x32_bf16 v[46:49], v[208:211], v[232:235], v[46:49]
	v_mfma_f32_16x16x32_bf16 v[10:13], v[208:211], v[236:239], v[10:13]
	v_mfma_f32_16x16x32_bf16 v[14:17], v[208:211], v[240:243], v[14:17]
	ds_read_b128 v[208:211], v244 offset:6912
	s_waitcnt lgkmcnt(6)
	v_mfma_f32_16x16x32_bf16 v[50:53], v[196:199], v[212:215], v[50:53]
	ds_read_b128 v[228:231], v245 offset:36928
	s_waitcnt lgkmcnt(6)
	v_mfma_f32_16x16x32_bf16 v[54:57], v[196:199], v[216:219], v[54:57]
	ds_read_b128 v[232:235], v245 offset:39232
	s_waitcnt lgkmcnt(6)
	v_mfma_f32_16x16x32_bf16 v[18:21], v[196:199], v[220:223], v[18:21]
	ds_read_b128 v[236:239], v245 offset:41536
	s_waitcnt lgkmcnt(6)
	v_mfma_f32_16x16x32_bf16 v[22:25], v[196:199], v[224:227], v[22:25]
	ds_read_b128 v[240:243], v245 offset:43840
	ds_read_b128 v[196:199], v244 offset:64
	s_waitcnt lgkmcnt(7)
	v_mfma_f32_16x16x32_bf16 v[58:61], v[200:203], v[212:215], v[58:61]
	v_mfma_f32_16x16x32_bf16 v[62:65], v[200:203], v[216:219], v[62:65]
	v_mfma_f32_16x16x32_bf16 v[26:29], v[200:203], v[220:223], v[26:29]
	v_mfma_f32_16x16x32_bf16 v[30:33], v[200:203], v[224:227], v[30:33]
	ds_read_b128 v[200:203], v244 offset:2368
	s_waitcnt lgkmcnt(7)
	v_mfma_f32_16x16x32_bf16 v[34:37], v[204:207], v[212:215], v[34:37]
	v_mfma_f32_16x16x32_bf16 v[38:41], v[204:207], v[216:219], v[38:41]
	v_mfma_f32_16x16x32_bf16 v[2:5], v[204:207], v[220:223], v[2:5]
	v_mfma_f32_16x16x32_bf16 v[6:9], v[204:207], v[224:227], v[6:9]
	ds_read_b128 v[204:207], v244 offset:4672
	s_setprio 1
	s_waitcnt vmcnt(7)
	ds_write_b128 v100, v[102:105] offset:18432
	s_waitcnt vmcnt(6)
	ds_write_b128 v100, v[66:69] offset:23040
	s_waitcnt lgkmcnt(9)
	v_mfma_f32_16x16x32_bf16 v[42:45], v[208:211], v[212:215], v[42:45]
	v_mfma_f32_16x16x32_bf16 v[46:49], v[208:211], v[216:219], v[46:49]
	v_mfma_f32_16x16x32_bf16 v[10:13], v[208:211], v[220:223], v[10:13]
	v_mfma_f32_16x16x32_bf16 v[14:17], v[208:211], v[224:227], v[14:17]
	ds_read_b128 v[208:211], v244 offset:6976
	s_waitcnt vmcnt(5)
	ds_write_b128 v100, v[106:109] offset:27648
	s_waitcnt vmcnt(4)
	ds_write_b128 v100, v[70:73] offset:32256
	s_waitcnt lgkmcnt(7)
	v_mfma_f32_16x16x32_bf16 v[50:53], v[196:199], v[228:231], v[50:53]
	v_mfma_f32_16x16x32_bf16 v[54:57], v[196:199], v[232:235], v[54:57]
	v_mfma_f32_16x16x32_bf16 v[18:21], v[196:199], v[236:239], v[18:21]
	v_mfma_f32_16x16x32_bf16 v[22:25], v[196:199], v[240:243], v[22:25]
	s_waitcnt vmcnt(3)
	ds_write_b128 v100, v[110:113] offset:55296
	s_waitcnt vmcnt(2)
	ds_write_b128 v100, v[84:87] offset:59904
	s_waitcnt lgkmcnt(8)
	v_mfma_f32_16x16x32_bf16 v[58:61], v[200:203], v[228:231], v[58:61]
	v_mfma_f32_16x16x32_bf16 v[62:65], v[200:203], v[232:235], v[62:65]
	v_mfma_f32_16x16x32_bf16 v[26:29], v[200:203], v[236:239], v[26:29]
	v_mfma_f32_16x16x32_bf16 v[30:33], v[200:203], v[240:243], v[30:33]
	s_waitcnt vmcnt(1)
	ds_write_b128 v100, v[114:117] offset:64512
	s_waitcnt vmcnt(0)
	ds_write_b128 v101, v[88:91] offset:32256
	s_waitcnt lgkmcnt(0)
	s_barrier
	ds_read_b128 v[212:215], v245 offset:55296
	ds_read_b128 v[196:199], v244 offset:18432
	ds_read_b128 v[216:219], v245 offset:57600
	ds_read_b128 v[220:223], v245 offset:59904
	ds_read_b128 v[224:227], v245 offset:62208
	ds_read_b128 v[200:203], v244 offset:20736
	s_setprio 0
	v_mfma_f32_16x16x32_bf16 v[34:37], v[204:207], v[228:231], v[34:37]
	v_mfma_f32_16x16x32_bf16 v[38:41], v[204:207], v[232:235], v[38:41]
	v_mfma_f32_16x16x32_bf16 v[2:5], v[204:207], v[236:239], v[2:5]
	v_mfma_f32_16x16x32_bf16 v[6:9], v[204:207], v[240:243], v[6:9]
	ds_read_b128 v[204:207], v244 offset:23040
	v_mfma_f32_16x16x32_bf16 v[42:45], v[208:211], v[228:231], v[42:45]
	v_mfma_f32_16x16x32_bf16 v[46:49], v[208:211], v[232:235], v[46:49]
	v_mfma_f32_16x16x32_bf16 v[10:13], v[208:211], v[236:239], v[10:13]
	v_mfma_f32_16x16x32_bf16 v[14:17], v[208:211], v[240:243], v[14:17]
	ds_read_b128 v[208:211], v244 offset:25344
	s_waitcnt lgkmcnt(6)
	v_mfma_f32_16x16x32_bf16 v[50:53], v[196:199], v[212:215], v[50:53]
	ds_read_b128 v[228:231], v245 offset:55360
	s_waitcnt lgkmcnt(6)
	v_mfma_f32_16x16x32_bf16 v[54:57], v[196:199], v[216:219], v[54:57]
	ds_read_b128 v[232:235], v245 offset:57664
	s_waitcnt lgkmcnt(6)
	v_mfma_f32_16x16x32_bf16 v[18:21], v[196:199], v[220:223], v[18:21]
	ds_read_b128 v[236:239], v245 offset:59968
	s_waitcnt lgkmcnt(6)
	v_mfma_f32_16x16x32_bf16 v[22:25], v[196:199], v[224:227], v[22:25]
	ds_read_b128 v[240:243], v245 offset:62272
	ds_read_b128 v[196:199], v244 offset:18496
	s_waitcnt lgkmcnt(7)
	v_mfma_f32_16x16x32_bf16 v[58:61], v[200:203], v[212:215], v[58:61]
	v_mfma_f32_16x16x32_bf16 v[62:65], v[200:203], v[216:219], v[62:65]
	v_mfma_f32_16x16x32_bf16 v[26:29], v[200:203], v[220:223], v[26:29]
	v_mfma_f32_16x16x32_bf16 v[30:33], v[200:203], v[224:227], v[30:33]
	ds_read_b128 v[200:203], v244 offset:20800
	s_waitcnt lgkmcnt(7)
	v_mfma_f32_16x16x32_bf16 v[34:37], v[204:207], v[212:215], v[34:37]
	v_mfma_f32_16x16x32_bf16 v[38:41], v[204:207], v[216:219], v[38:41]
	v_mfma_f32_16x16x32_bf16 v[2:5], v[204:207], v[220:223], v[2:5]
	v_mfma_f32_16x16x32_bf16 v[6:9], v[204:207], v[224:227], v[6:9]
	ds_read_b128 v[204:207], v244 offset:23104
	s_waitcnt lgkmcnt(7)
	v_mfma_f32_16x16x32_bf16 v[42:45], v[208:211], v[212:215], v[42:45]
	v_mfma_f32_16x16x32_bf16 v[46:49], v[208:211], v[216:219], v[46:49]
	v_mfma_f32_16x16x32_bf16 v[10:13], v[208:211], v[220:223], v[10:13]
	v_mfma_f32_16x16x32_bf16 v[14:17], v[208:211], v[224:227], v[14:17]
	ds_read_b128 v[208:211], v244 offset:25408
	s_waitcnt lgkmcnt(3)
	v_mfma_f32_16x16x32_bf16 v[50:53], v[196:199], v[228:231], v[50:53]
	v_mfma_f32_16x16x32_bf16 v[54:57], v[196:199], v[232:235], v[54:57]
	v_mfma_f32_16x16x32_bf16 v[18:21], v[196:199], v[236:239], v[18:21]
	v_mfma_f32_16x16x32_bf16 v[22:25], v[196:199], v[240:243], v[22:25]
	s_waitcnt lgkmcnt(2)
	v_mfma_f32_16x16x32_bf16 v[58:61], v[200:203], v[228:231], v[58:61]
	v_mfma_f32_16x16x32_bf16 v[62:65], v[200:203], v[232:235], v[62:65]
	v_mfma_f32_16x16x32_bf16 v[26:29], v[200:203], v[236:239], v[26:29]
	v_mfma_f32_16x16x32_bf16 v[30:33], v[200:203], v[240:243], v[30:33]
	s_add_i32 s6, s6, 1
	s_add_i32 s5, s5, s3
	v_or_b32_e32 v70, s0, v92
	s_lshl_b32 s0, s7, 1
	v_lshl_add_u64 v[110:111], v[80:81], 0, s[0:1]
	v_lshlrev_b32_e32 v74, 10, v70
	v_lshl_add_u64 v[112:113], v[110:111], 0, v[74:75]
	s_waitcnt lgkmcnt(0)
	s_barrier
	v_mfma_f32_16x16x32_bf16 v[34:37], v[204:207], v[228:231], v[34:37]
	v_mfma_f32_16x16x32_bf16 v[38:41], v[204:207], v[232:235], v[38:41]
	v_mfma_f32_16x16x32_bf16 v[2:5], v[204:207], v[236:239], v[2:5]
	v_mfma_f32_16x16x32_bf16 v[6:9], v[204:207], v[240:243], v[6:9]
	v_mfma_f32_16x16x32_bf16 v[42:45], v[208:211], v[228:231], v[42:45]
	v_mfma_f32_16x16x32_bf16 v[46:49], v[208:211], v[232:235], v[46:49]
	v_mfma_f32_16x16x32_bf16 v[10:13], v[208:211], v[236:239], v[10:13]
	v_mfma_f32_16x16x32_bf16 v[14:17], v[208:211], v[240:243], v[14:17]
	s_nop 7
	v_permlane16_swap_b32_e32 v50, v54
	v_permlane16_swap_b32_e32 v51, v55
	v_permlane16_swap_b32_e32 v52, v56
	v_permlane16_swap_b32_e32 v53, v57
	v_permlane16_swap_b32_e32 v58, v62
	v_permlane16_swap_b32_e32 v59, v63
	v_permlane16_swap_b32_e32 v60, v64
	v_permlane16_swap_b32_e32 v61, v65
	v_permlane16_swap_b32_e32 v18, v22
	v_permlane16_swap_b32_e32 v19, v23
	v_permlane16_swap_b32_e32 v20, v24
	v_permlane16_swap_b32_e32 v21, v25
	v_permlane16_swap_b32_e32 v26, v30
	v_permlane16_swap_b32_e32 v27, v31
	v_permlane16_swap_b32_e32 v28, v32
	v_permlane16_swap_b32_e32 v29, v33
	v_permlane16_swap_b32_e32 v34, v38
	v_permlane16_swap_b32_e32 v35, v39
	v_permlane16_swap_b32_e32 v36, v40
	v_permlane16_swap_b32_e32 v37, v41
	v_permlane16_swap_b32_e32 v42, v46
	v_permlane16_swap_b32_e32 v43, v47
	v_permlane16_swap_b32_e32 v44, v48
	v_permlane16_swap_b32_e32 v45, v49
	v_permlane16_swap_b32_e32 v2, v6
	v_permlane16_swap_b32_e32 v3, v7
	v_permlane16_swap_b32_e32 v4, v8
	v_permlane16_swap_b32_e32 v5, v9
	v_permlane16_swap_b32_e32 v10, v14
	v_permlane16_swap_b32_e32 v11, v15
	v_permlane16_swap_b32_e32 v12, v16
	v_permlane16_swap_b32_e32 v13, v17
	v_permlane32_swap_b32_e32 v50, v54
	v_permlane32_swap_b32_e32 v51, v55
	v_permlane32_swap_b32_e32 v52, v56
	v_permlane32_swap_b32_e32 v53, v57
	v_permlane32_swap_b32_e32 v58, v62
	v_permlane32_swap_b32_e32 v59, v63
	v_permlane32_swap_b32_e32 v60, v64
	v_permlane32_swap_b32_e32 v61, v65
	v_permlane32_swap_b32_e32 v18, v22
	v_permlane32_swap_b32_e32 v19, v23
	v_permlane32_swap_b32_e32 v20, v24
	v_permlane32_swap_b32_e32 v21, v25
	v_permlane32_swap_b32_e32 v26, v30
	v_permlane32_swap_b32_e32 v27, v31
	v_permlane32_swap_b32_e32 v28, v32
	v_permlane32_swap_b32_e32 v29, v33
	v_permlane32_swap_b32_e32 v34, v38
	v_permlane32_swap_b32_e32 v35, v39
	v_permlane32_swap_b32_e32 v36, v40
	v_permlane32_swap_b32_e32 v37, v41
	v_permlane32_swap_b32_e32 v42, v46
	v_permlane32_swap_b32_e32 v43, v47
	v_permlane32_swap_b32_e32 v44, v48
	v_permlane32_swap_b32_e32 v45, v49
	v_permlane32_swap_b32_e32 v2, v6
	v_permlane32_swap_b32_e32 v3, v7
	v_permlane32_swap_b32_e32 v4, v8
	v_permlane32_swap_b32_e32 v5, v9
	v_permlane32_swap_b32_e32 v10, v14
	v_permlane32_swap_b32_e32 v11, v15
	v_permlane32_swap_b32_e32 v12, v16
	v_permlane32_swap_b32_e32 v13, v17
	global_load_dwordx4 v[106:109], v[112:113], off
	s_mul_i32 s0, s6, s3
	s_add_i32 s0, s0, s2
	s_cmp_lt_u32 s5, 48
	global_load_dwordx4 v[88:91], v[112:113], off offset:32
	global_load_dwordx4 v[70:73], v[112:113], off offset:64
	s_waitcnt vmcnt(2)
	v_mov_b32_e32 v86, v108
	global_load_dwordx4 v[66:69], v[112:113], off offset:96
	v_permlane32_swap_b32_e32 v106, v86
	v_mov_b32_e32 v102, v109
	s_nop 1
	v_permlane32_swap_b32_e32 v107, v102
	s_waitcnt vmcnt(2)
	v_mov_b32_e32 v108, v90
	v_mov_b32_e32 v109, v91
	s_nop 0
	v_permlane32_swap_b32_e32 v88, v108
	v_permlane32_swap_b32_e32 v89, v109
	s_waitcnt vmcnt(1)
	v_mov_b32_e32 v112, v72
	v_mov_b32_e32 v113, v73
	v_lshlrev_b32_e32 v72, 16, v106
	v_and_b32_e32 v73, 0xffff0000, v106
	v_pk_mul_f32 v[72:73], v[50:51], v[72:73]
	v_lshlrev_b32_e32 v50, 16, v107
	v_and_b32_e32 v51, 0xffff0000, v107
	v_pk_mul_f32 v[84:85], v[52:53], v[50:51]
	v_lshlrev_b32_e32 v50, 16, v86
	v_and_b32_e32 v51, 0xffff0000, v86
	v_pk_mul_f32 v[86:87], v[54:55], v[50:51]
	v_lshlrev_b32_e32 v54, 16, v102
	v_and_b32_e32 v55, 0xffff0000, v102
	v_pk_mul_f32 v[102:103], v[56:57], v[54:55]
	v_cvt_pk_bf16_f32 v55, v84, v85
	v_cvt_pk_bf16_f32 v56, v86, v87
	v_cvt_pk_bf16_f32 v57, v102, v103
	v_cvt_pk_bf16_f32 v54, v72, v73
	v_add_lshl_u32 v72, s7, v97, 1
	v_mov_b32_e32 v73, v75
	v_permlane32_swap_b32_e32 v54, v56
	v_permlane32_swap_b32_e32 v55, v57
	v_lshlrev_b32_e32 v106, 16, v88
	v_and_b32_e32 v107, 0xffff0000, v88
	v_lshlrev_b32_e32 v88, 16, v89
	v_and_b32_e32 v89, 0xffff0000, v89
	v_pk_mul_f32 v[60:61], v[60:61], v[88:89]
	v_lshlrev_b32_e32 v88, 16, v108
	v_and_b32_e32 v89, 0xffff0000, v108
	v_pk_mul_f32 v[62:63], v[62:63], v[88:89]
	v_lshlrev_b32_e32 v88, 16, v109
	v_and_b32_e32 v89, 0xffff0000, v109
	v_pk_mul_f32 v[58:59], v[58:59], v[106:107]
	v_pk_mul_f32 v[64:65], v[64:65], v[88:89]
	v_cvt_pk_bf16_f32 v58, v58, v59
	v_cvt_pk_bf16_f32 v59, v60, v61
	v_cvt_pk_bf16_f32 v60, v62, v63
	v_cvt_pk_bf16_f32 v61, v64, v65
	v_permlane32_swap_b32_e32 v70, v112
	v_permlane32_swap_b32_e32 v58, v60
	v_permlane32_swap_b32_e32 v59, v61
	v_permlane32_swap_b32_e32 v71, v113
	s_waitcnt vmcnt(0)
	v_mov_b32_e32 v114, v68
	v_mov_b32_e32 v115, v69
	v_lshl_add_u64 v[68:69], v[82:83], 0, v[74:75]
	v_or_b32_e32 v74, 0x8000, v74
	v_lshl_add_u64 v[90:91], v[110:111], 0, v[74:75]
	global_load_dwordx4 v[50:53], v[90:91], off
	global_load_dwordx4 v[84:87], v[90:91], off offset:32
	global_load_dwordx4 v[102:105], v[90:91], off offset:64
	v_lshl_add_u64 v[68:69], v[68:69], 0, v[72:73]
	global_store_dwordx4 v[68:69], v[54:57], off
	global_load_dwordx4 v[54:57], v[90:91], off offset:96
	v_permlane32_swap_b32_e32 v66, v114
	global_store_dwordx4 v[68:69], v[58:61], off offset:32
	v_permlane32_swap_b32_e32 v67, v115
	s_nop 0
	v_lshlrev_b32_e32 v58, 16, v70
	v_and_b32_e32 v59, 0xffff0000, v70
	v_pk_mul_f32 v[34:35], v[34:35], v[58:59]
	v_lshlrev_b32_e32 v58, 16, v71
	v_and_b32_e32 v59, 0xffff0000, v71
	v_pk_mul_f32 v[36:37], v[36:37], v[58:59]
	v_lshlrev_b32_e32 v58, 16, v112
	v_and_b32_e32 v59, 0xffff0000, v112
	v_pk_mul_f32 v[38:39], v[38:39], v[58:59]
	v_lshlrev_b32_e32 v58, 16, v113
	v_and_b32_e32 v59, 0xffff0000, v113
	v_pk_mul_f32 v[40:41], v[40:41], v[58:59]
	v_cvt_pk_bf16_f32 v34, v34, v35
	v_cvt_pk_bf16_f32 v35, v36, v37
	v_cvt_pk_bf16_f32 v36, v38, v39
	v_cvt_pk_bf16_f32 v37, v40, v41
	s_nop 0
	v_permlane32_swap_b32_e32 v34, v36
	v_permlane32_swap_b32_e32 v35, v37
	global_store_dwordx4 v[68:69], v[34:37], off offset:64
	v_lshlrev_b32_e32 v38, 16, v114
	v_and_b32_e32 v39, 0xffff0000, v114
	v_lshlrev_b32_e32 v34, 16, v66
	v_and_b32_e32 v35, 0xffff0000, v66
	v_lshlrev_b32_e32 v36, 16, v67
	v_and_b32_e32 v37, 0xffff0000, v67
	v_lshlrev_b32_e32 v40, 16, v115
	v_and_b32_e32 v41, 0xffff0000, v115
	v_pk_mul_f32 v[34:35], v[42:43], v[34:35]
	v_pk_mul_f32 v[36:37], v[44:45], v[36:37]
	v_pk_mul_f32 v[38:39], v[46:47], v[38:39]
	v_pk_mul_f32 v[40:41], v[48:49], v[40:41]
	v_cvt_pk_bf16_f32 v34, v34, v35
	v_cvt_pk_bf16_f32 v35, v36, v37
	v_cvt_pk_bf16_f32 v36, v38, v39
	v_cvt_pk_bf16_f32 v37, v40, v41
	s_nop 0
	v_permlane32_swap_b32_e32 v34, v36
	v_permlane32_swap_b32_e32 v35, v37
	global_store_dwordx4 v[68:69], v[34:37], off offset:96
	s_waitcnt vmcnt(7)
	v_mov_b32_e32 v38, v52
	s_nop 1
	v_permlane32_swap_b32_e32 v50, v38
	v_mov_b32_e32 v39, v53
	s_nop 1
	v_permlane32_swap_b32_e32 v51, v39
	v_lshlrev_b32_e32 v36, 16, v50
	v_and_b32_e32 v37, 0xffff0000, v50
	v_pk_mul_f32 v[18:19], v[18:19], v[36:37]
	v_lshlrev_b32_e32 v36, 16, v51
	v_and_b32_e32 v37, 0xffff0000, v51
	v_pk_mul_f32 v[20:21], v[20:21], v[36:37]
	v_lshlrev_b32_e32 v36, 16, v38
	v_and_b32_e32 v37, 0xffff0000, v38
	v_pk_mul_f32 v[22:23], v[22:23], v[36:37]
	v_lshlrev_b32_e32 v36, 16, v39
	v_and_b32_e32 v37, 0xffff0000, v39
	v_pk_mul_f32 v[24:25], v[24:25], v[36:37]
	s_waitcnt vmcnt(6)
	v_mov_b32_e32 v40, v86
	v_lshl_add_u64 v[34:35], v[82:83], 0, v[74:75]
	v_cvt_pk_bf16_f32 v18, v18, v19
	v_cvt_pk_bf16_f32 v19, v20, v21
	v_cvt_pk_bf16_f32 v20, v22, v23
	v_cvt_pk_bf16_f32 v21, v24, v25
	v_permlane32_swap_b32_e32 v84, v40
	v_mov_b32_e32 v41, v87
	v_permlane32_swap_b32_e32 v18, v20
	v_permlane32_swap_b32_e32 v19, v21
	v_lshl_add_u64 v[22:23], v[34:35], 0, v[72:73]
	v_permlane32_swap_b32_e32 v85, v41
	global_store_dwordx4 v[22:23], v[18:21], off
	v_lshlrev_b32_e32 v24, 16, v40
	v_and_b32_e32 v25, 0xffff0000, v40
	v_lshlrev_b32_e32 v18, 16, v84
	v_and_b32_e32 v19, 0xffff0000, v84
	v_pk_mul_f32 v[18:19], v[26:27], v[18:19]
	v_lshlrev_b32_e32 v20, 16, v85
	v_and_b32_e32 v21, 0xffff0000, v85
	v_lshlrev_b32_e32 v26, 16, v41
	v_and_b32_e32 v27, 0xffff0000, v41
	v_pk_mul_f32 v[20:21], v[28:29], v[20:21]
	v_pk_mul_f32 v[24:25], v[30:31], v[24:25]
	v_pk_mul_f32 v[26:27], v[32:33], v[26:27]
	s_waitcnt vmcnt(6)
	v_mov_b32_e32 v42, v104
	v_cvt_pk_bf16_f32 v18, v18, v19
	v_cvt_pk_bf16_f32 v19, v20, v21
	v_cvt_pk_bf16_f32 v20, v24, v25
	v_cvt_pk_bf16_f32 v21, v26, v27
	v_permlane32_swap_b32_e32 v102, v42
	v_mov_b32_e32 v43, v105
	v_permlane32_swap_b32_e32 v18, v20
	v_permlane32_swap_b32_e32 v19, v21
	v_permlane32_swap_b32_e32 v103, v43
	global_store_dwordx4 v[22:23], v[18:21], off offset:32
	s_waitcnt vmcnt(5)
	v_mov_b32_e32 v44, v56
	v_mov_b32_e32 v45, v57
	v_lshlrev_b32_e32 v18, 16, v102
	v_and_b32_e32 v19, 0xffff0000, v102
	v_pk_mul_f32 v[2:3], v[2:3], v[18:19]
	v_lshlrev_b32_e32 v18, 16, v103
	v_and_b32_e32 v19, 0xffff0000, v103
	v_pk_mul_f32 v[4:5], v[4:5], v[18:19]
	v_lshlrev_b32_e32 v18, 16, v42
	v_and_b32_e32 v19, 0xffff0000, v42
	v_pk_mul_f32 v[6:7], v[6:7], v[18:19]
	v_lshlrev_b32_e32 v18, 16, v43
	v_and_b32_e32 v19, 0xffff0000, v43
	v_pk_mul_f32 v[8:9], v[8:9], v[18:19]
	v_cvt_pk_bf16_f32 v2, v2, v3
	v_cvt_pk_bf16_f32 v3, v4, v5
	v_cvt_pk_bf16_f32 v4, v6, v7
	v_cvt_pk_bf16_f32 v5, v8, v9
	v_permlane32_swap_b32_e32 v54, v44
	v_permlane32_swap_b32_e32 v55, v45
	v_permlane32_swap_b32_e32 v2, v4
	v_permlane32_swap_b32_e32 v3, v5
	global_store_dwordx4 v[22:23], v[2:5], off offset:64
	v_lshlrev_b32_e32 v6, 16, v44
	v_and_b32_e32 v7, 0xffff0000, v44
	v_lshlrev_b32_e32 v2, 16, v54
	v_and_b32_e32 v3, 0xffff0000, v54
	v_lshlrev_b32_e32 v4, 16, v55
	v_and_b32_e32 v5, 0xffff0000, v55
	v_lshlrev_b32_e32 v8, 16, v45
	v_and_b32_e32 v9, 0xffff0000, v45
	v_pk_mul_f32 v[2:3], v[10:11], v[2:3]
	v_pk_mul_f32 v[4:5], v[12:13], v[4:5]
	v_pk_mul_f32 v[6:7], v[14:15], v[6:7]
	v_pk_mul_f32 v[8:9], v[16:17], v[8:9]
	v_cvt_pk_bf16_f32 v2, v2, v3
	v_cvt_pk_bf16_f32 v3, v4, v5
	v_cvt_pk_bf16_f32 v4, v6, v7
	v_cvt_pk_bf16_f32 v5, v8, v9
	s_nop 0
	v_permlane32_swap_b32_e32 v2, v4
	v_permlane32_swap_b32_e32 v3, v5
	global_store_dwordx4 v[22:23], v[2:5], off offset:96
	s_cbranch_scc1 .LBB0_828

.LBB0_979:
	s_lshr_b32 s0, s2, 2
	s_and_b32 s2, s2, 3
	s_or_b32 s2, s2, s8
	s_lshl_b32 s2, s2, 7
	v_or_b32_e32 v2, s2, v89
	v_lshlrev_b32_e32 v66, 11, v2
	s_add_i32 s0, s0, s9
	v_lshl_add_u64 v[72:73], v[68:69], 0, v[66:67]
	v_add_lshl_u32 v66, s2, v90, 11
	s_lshl_b32 s3, s0, 7
	v_lshl_add_u64 v[74:75], v[68:69], 0, v[66:67]
	v_add_lshl_u32 v66, s2, v91, 11
	v_lshl_add_u64 v[76:77], v[68:69], 0, v[66:67]
	v_add_lshl_u32 v66, s2, v92, 11
	v_or_b32_e32 v2, s3, v89
	v_lshl_add_u64 v[78:79], v[68:69], 0, v[66:67]
	v_lshlrev_b32_e32 v66, 11, v2
	v_lshl_add_u64 v[80:81], v[70:71], 0, v[66:67]
	v_add_lshl_u32 v66, s3, v90, 11
	v_lshl_add_u64 v[82:83], v[70:71], 0, v[66:67]
	v_add_lshl_u32 v66, s3, v91, 11
	v_lshl_add_u64 v[84:85], v[70:71], 0, v[66:67]
	v_add_lshl_u32 v66, s3, v92, 11
	v_lshl_add_u64 v[86:87], v[70:71], 0, v[66:67]
	global_load_dwordx4 v[2:5], v[72:73], off
	global_load_dwordx4 v[6:9], v[74:75], off
	global_load_dwordx4 v[10:13], v[76:77], off
	global_load_dwordx4 v[14:17], v[78:79], off
	global_load_dwordx4 v[18:21], v[80:81], off
	global_load_dwordx4 v[22:25], v[82:83], off
	global_load_dwordx4 v[26:29], v[84:85], off
	global_load_dwordx4 v[30:33], v[86:87], off
	global_load_dwordx4 v[98:101], v[72:73], off offset:128
	global_load_dwordx4 v[102:105], v[74:75], off offset:128
	global_load_dwordx4 v[106:109], v[76:77], off offset:128
	global_load_dwordx4 v[110:113], v[78:79], off offset:128
	global_load_dwordx4 v[114:117], v[80:81], off offset:128
	global_load_dwordx4 v[118:121], v[82:83], off offset:128
	global_load_dwordx4 v[122:125], v[84:85], off offset:128
	global_load_dwordx4 v[126:129], v[86:87], off offset:128
	s_waitcnt vmcnt(15)
	ds_write_b128 v95, v[2:5]
	s_waitcnt vmcnt(14)
	ds_write_b128 v95, v[6:9] offset:4608
	s_waitcnt vmcnt(13)
	ds_write_b128 v95, v[10:13] offset:9216
	s_waitcnt vmcnt(12)
	ds_write_b128 v95, v[14:17] offset:13824
	s_waitcnt vmcnt(11)
	ds_write_b128 v95, v[18:21] offset:36864
	s_waitcnt vmcnt(10)
	ds_write_b128 v95, v[22:25] offset:41472
	s_waitcnt vmcnt(9)
	ds_write_b128 v95, v[26:29] offset:46080
	s_waitcnt vmcnt(8)
	ds_write_b128 v95, v[30:33] offset:50688
	s_waitcnt lgkmcnt(0)
	s_barrier
	global_load_dwordx4 v[136:139], v[72:73], off offset:256
	global_load_dwordx4 v[140:143], v[74:75], off offset:256
	global_load_dwordx4 v[144:147], v[76:77], off offset:256
	global_load_dwordx4 v[148:151], v[78:79], off offset:256
	global_load_dwordx4 v[152:155], v[80:81], off offset:256
	global_load_dwordx4 v[156:159], v[82:83], off offset:256
	global_load_dwordx4 v[160:163], v[84:85], off offset:256
	global_load_dwordx4 v[164:167], v[86:87], off offset:256
	v_and_b32_e32 v246, 15, v1
	v_add_u32_e32 v246, 4, v246
	v_bfe_u32 v246, v246, 3, 1
	v_bfe_u32 v249, v1, 4, 2
	v_xor_b32_e32 v246, v246, v249
	v_bfe_u32 v249, v1, 5, 1
	v_sub_u32_e32 v246, v246, v249
	v_lshlrev_b32_e32 v246, 4, v246
	v_bfe_u32 v249, v1, 4, 1
	v_mul_u32_u24_e32 v249, 0x900, v249
	v_sub_u32_e32 v246, v246, v249
	v_add_u32_e32 v244, v246, v93
	v_add_u32_e32 v245, v246, v94
	ds_read_b128 v[212:215], v245 offset:36864
	ds_read_b128 v[196:199], v244
	ds_read_b128 v[216:219], v245 offset:39168
	ds_read_b128 v[220:223], v245 offset:41472
	ds_read_b128 v[224:227], v245 offset:43776
	ds_read_b128 v[200:203], v244 offset:2304
	ds_read_b128 v[204:207], v244 offset:4608
	ds_read_b128 v[208:211], v244 offset:6912
	s_waitcnt lgkmcnt(6)
	v_mfma_f32_16x16x32_bf16 v[34:37], v[196:199], v[212:215], 0
	ds_read_b128 v[228:231], v245 offset:36928
	s_waitcnt lgkmcnt(6)
	v_mfma_f32_16x16x32_bf16 v[38:41], v[196:199], v[216:219], 0
	ds_read_b128 v[232:235], v245 offset:39232
	s_waitcnt lgkmcnt(6)
	v_mfma_f32_16x16x32_bf16 v[2:5], v[196:199], v[220:223], 0
	ds_read_b128 v[236:239], v245 offset:41536
	s_waitcnt lgkmcnt(6)
	v_mfma_f32_16x16x32_bf16 v[6:9], v[196:199], v[224:227], 0
	ds_read_b128 v[240:243], v245 offset:43840
	ds_read_b128 v[196:199], v244 offset:64
	s_waitcnt lgkmcnt(7)
	v_mfma_f32_16x16x32_bf16 v[42:45], v[200:203], v[212:215], 0
	v_mfma_f32_16x16x32_bf16 v[46:49], v[200:203], v[216:219], 0
	v_mfma_f32_16x16x32_bf16 v[10:13], v[200:203], v[220:223], 0
	v_mfma_f32_16x16x32_bf16 v[14:17], v[200:203], v[224:227], 0
	ds_read_b128 v[200:203], v244 offset:2368
	s_waitcnt lgkmcnt(7)
	v_mfma_f32_16x16x32_bf16 v[50:53], v[204:207], v[212:215], 0
	v_mfma_f32_16x16x32_bf16 v[54:57], v[204:207], v[216:219], 0
	v_mfma_f32_16x16x32_bf16 v[18:21], v[204:207], v[220:223], 0
	v_mfma_f32_16x16x32_bf16 v[22:25], v[204:207], v[224:227], 0
	ds_read_b128 v[204:207], v244 offset:4672
	s_setprio 1
	s_waitcnt vmcnt(15)
	ds_write_b128 v95, v[98:101] offset:18432
	s_waitcnt vmcnt(14)
	ds_write_b128 v95, v[102:105] offset:23040
	s_waitcnt lgkmcnt(9)
	v_mfma_f32_16x16x32_bf16 v[58:61], v[208:211], v[212:215], 0
	v_mfma_f32_16x16x32_bf16 v[62:65], v[208:211], v[216:219], 0
	v_mfma_f32_16x16x32_bf16 v[26:29], v[208:211], v[220:223], 0
	v_mfma_f32_16x16x32_bf16 v[30:33], v[208:211], v[224:227], 0
	ds_read_b128 v[208:211], v244 offset:6976
	s_waitcnt vmcnt(13)
	ds_write_b128 v95, v[106:109] offset:27648
	s_waitcnt vmcnt(12)
	ds_write_b128 v95, v[110:113] offset:32256
	s_waitcnt lgkmcnt(7)
	v_mfma_f32_16x16x32_bf16 v[34:37], v[196:199], v[228:231], v[34:37]
	v_mfma_f32_16x16x32_bf16 v[38:41], v[196:199], v[232:235], v[38:41]
	v_mfma_f32_16x16x32_bf16 v[2:5], v[196:199], v[236:239], v[2:5]
	v_mfma_f32_16x16x32_bf16 v[6:9], v[196:199], v[240:243], v[6:9]
	s_waitcnt vmcnt(11)
	ds_write_b128 v95, v[114:117] offset:55296
	s_waitcnt vmcnt(10)
	ds_write_b128 v95, v[118:121] offset:59904
	s_waitcnt lgkmcnt(8)
	v_mfma_f32_16x16x32_bf16 v[42:45], v[200:203], v[228:231], v[42:45]
	v_mfma_f32_16x16x32_bf16 v[46:49], v[200:203], v[232:235], v[46:49]
	v_mfma_f32_16x16x32_bf16 v[10:13], v[200:203], v[236:239], v[10:13]
	v_mfma_f32_16x16x32_bf16 v[14:17], v[200:203], v[240:243], v[14:17]
	s_waitcnt vmcnt(9)
	ds_write_b128 v95, v[122:125] offset:64512
	s_waitcnt vmcnt(8)
	ds_write_b128 v96, v[126:129] offset:32256
	s_waitcnt lgkmcnt(0)
	s_barrier
	ds_read_b128 v[212:215], v245 offset:55296
	ds_read_b128 v[196:199], v244 offset:18432
	ds_read_b128 v[216:219], v245 offset:57600
	ds_read_b128 v[220:223], v245 offset:59904
	ds_read_b128 v[224:227], v245 offset:62208
	ds_read_b128 v[200:203], v244 offset:20736
	s_setprio 0
	v_mfma_f32_16x16x32_bf16 v[50:53], v[204:207], v[228:231], v[50:53]
	v_mfma_f32_16x16x32_bf16 v[54:57], v[204:207], v[232:235], v[54:57]
	v_mfma_f32_16x16x32_bf16 v[18:21], v[204:207], v[236:239], v[18:21]
	v_mfma_f32_16x16x32_bf16 v[22:25], v[204:207], v[240:243], v[22:25]
	ds_read_b128 v[204:207], v244 offset:23040
	v_mfma_f32_16x16x32_bf16 v[58:61], v[208:211], v[228:231], v[58:61]
	v_mfma_f32_16x16x32_bf16 v[62:65], v[208:211], v[232:235], v[62:65]
	v_mfma_f32_16x16x32_bf16 v[26:29], v[208:211], v[236:239], v[26:29]
	v_mfma_f32_16x16x32_bf16 v[30:33], v[208:211], v[240:243], v[30:33]
	ds_read_b128 v[208:211], v244 offset:25344
	global_load_dwordx4 v[98:101], v[72:73], off offset:384
	global_load_dwordx4 v[102:105], v[74:75], off offset:384
	global_load_dwordx4 v[106:109], v[76:77], off offset:384
	global_load_dwordx4 v[110:113], v[78:79], off offset:384
	global_load_dwordx4 v[114:117], v[80:81], off offset:384
	global_load_dwordx4 v[118:121], v[82:83], off offset:384
	global_load_dwordx4 v[122:125], v[84:85], off offset:384
	global_load_dwordx4 v[126:129], v[86:87], off offset:384
	s_waitcnt lgkmcnt(6)
	v_mfma_f32_16x16x32_bf16 v[34:37], v[196:199], v[212:215], v[34:37]
	ds_read_b128 v[228:231], v245 offset:55360
	s_waitcnt lgkmcnt(6)
	v_mfma_f32_16x16x32_bf16 v[38:41], v[196:199], v[216:219], v[38:41]
	ds_read_b128 v[232:235], v245 offset:57664
	s_waitcnt lgkmcnt(6)
	v_mfma_f32_16x16x32_bf16 v[2:5], v[196:199], v[220:223], v[2:5]
	ds_read_b128 v[236:239], v245 offset:59968
	s_waitcnt lgkmcnt(6)
	v_mfma_f32_16x16x32_bf16 v[6:9], v[196:199], v[224:227], v[6:9]
	ds_read_b128 v[240:243], v245 offset:62272
	ds_read_b128 v[196:199], v244 offset:18496
	s_waitcnt lgkmcnt(7)
	v_mfma_f32_16x16x32_bf16 v[42:45], v[200:203], v[212:215], v[42:45]
	v_mfma_f32_16x16x32_bf16 v[46:49], v[200:203], v[216:219], v[46:49]
	v_mfma_f32_16x16x32_bf16 v[10:13], v[200:203], v[220:223], v[10:13]
	v_mfma_f32_16x16x32_bf16 v[14:17], v[200:203], v[224:227], v[14:17]
	ds_read_b128 v[200:203], v244 offset:20800
	s_waitcnt lgkmcnt(7)
	v_mfma_f32_16x16x32_bf16 v[50:53], v[204:207], v[212:215], v[50:53]
	v_mfma_f32_16x16x32_bf16 v[54:57], v[204:207], v[216:219], v[54:57]
	v_mfma_f32_16x16x32_bf16 v[18:21], v[204:207], v[220:223], v[18:21]
	v_mfma_f32_16x16x32_bf16 v[22:25], v[204:207], v[224:227], v[22:25]
	ds_read_b128 v[204:207], v244 offset:23104
	s_setprio 1
	s_waitcnt vmcnt(15)
	ds_write_b128 v95, v[136:139]
	s_waitcnt vmcnt(14)
	ds_write_b128 v95, v[140:143] offset:4608
	s_waitcnt lgkmcnt(9)
	v_mfma_f32_16x16x32_bf16 v[58:61], v[208:211], v[212:215], v[58:61]
	v_mfma_f32_16x16x32_bf16 v[62:65], v[208:211], v[216:219], v[62:65]
	v_mfma_f32_16x16x32_bf16 v[26:29], v[208:211], v[220:223], v[26:29]
	v_mfma_f32_16x16x32_bf16 v[30:33], v[208:211], v[224:227], v[30:33]
	ds_read_b128 v[208:211], v244 offset:25408
	s_waitcnt vmcnt(13)
	ds_write_b128 v95, v[144:147] offset:9216
	s_waitcnt vmcnt(12)
	ds_write_b128 v95, v[148:151] offset:13824
	s_waitcnt lgkmcnt(7)
	v_mfma_f32_16x16x32_bf16 v[34:37], v[196:199], v[228:231], v[34:37]
	v_mfma_f32_16x16x32_bf16 v[38:41], v[196:199], v[232:235], v[38:41]
	v_mfma_f32_16x16x32_bf16 v[2:5], v[196:199], v[236:239], v[2:5]
	v_mfma_f32_16x16x32_bf16 v[6:9], v[196:199], v[240:243], v[6:9]
	s_waitcnt vmcnt(11)
	ds_write_b128 v95, v[152:155] offset:36864
	s_waitcnt vmcnt(10)
	ds_write_b128 v95, v[156:159] offset:41472
	s_waitcnt lgkmcnt(8)
	v_mfma_f32_16x16x32_bf16 v[42:45], v[200:203], v[228:231], v[42:45]
	v_mfma_f32_16x16x32_bf16 v[46:49], v[200:203], v[232:235], v[46:49]
	v_mfma_f32_16x16x32_bf16 v[10:13], v[200:203], v[236:239], v[10:13]
	v_mfma_f32_16x16x32_bf16 v[14:17], v[200:203], v[240:243], v[14:17]
	s_waitcnt vmcnt(9)
	ds_write_b128 v95, v[160:163] offset:46080
	s_waitcnt vmcnt(8)
	ds_write_b128 v95, v[164:167] offset:50688
	s_waitcnt lgkmcnt(0)
	s_barrier
	ds_read_b128 v[212:215], v245 offset:36864
	ds_read_b128 v[196:199], v244
	ds_read_b128 v[216:219], v245 offset:39168
	ds_read_b128 v[220:223], v245 offset:41472
	ds_read_b128 v[224:227], v245 offset:43776
	ds_read_b128 v[200:203], v244 offset:2304
	s_setprio 0
	v_mfma_f32_16x16x32_bf16 v[50:53], v[204:207], v[228:231], v[50:53]
	v_mfma_f32_16x16x32_bf16 v[54:57], v[204:207], v[232:235], v[54:57]
	v_mfma_f32_16x16x32_bf16 v[18:21], v[204:207], v[236:239], v[18:21]
	v_mfma_f32_16x16x32_bf16 v[22:25], v[204:207], v[240:243], v[22:25]
	ds_read_b128 v[204:207], v244 offset:4608
	v_mfma_f32_16x16x32_bf16 v[58:61], v[208:211], v[228:231], v[58:61]
	v_mfma_f32_16x16x32_bf16 v[62:65], v[208:211], v[232:235], v[62:65]
	v_mfma_f32_16x16x32_bf16 v[26:29], v[208:211], v[236:239], v[26:29]
	v_mfma_f32_16x16x32_bf16 v[30:33], v[208:211], v[240:243], v[30:33]
	ds_read_b128 v[208:211], v244 offset:6912
	global_load_dwordx4 v[136:139], v[72:73], off offset:512
	global_load_dwordx4 v[140:143], v[74:75], off offset:512
	global_load_dwordx4 v[144:147], v[76:77], off offset:512
	global_load_dwordx4 v[148:151], v[78:79], off offset:512
	global_load_dwordx4 v[152:155], v[80:81], off offset:512
	global_load_dwordx4 v[156:159], v[82:83], off offset:512
	global_load_dwordx4 v[160:163], v[84:85], off offset:512
	global_load_dwordx4 v[164:167], v[86:87], off offset:512
	s_waitcnt lgkmcnt(6)
	v_mfma_f32_16x16x32_bf16 v[34:37], v[196:199], v[212:215], v[34:37]
	ds_read_b128 v[228:231], v245 offset:36928
	s_waitcnt lgkmcnt(6)
	v_mfma_f32_16x16x32_bf16 v[38:41], v[196:199], v[216:219], v[38:41]
	ds_read_b128 v[232:235], v245 offset:39232
	s_waitcnt lgkmcnt(6)
	v_mfma_f32_16x16x32_bf16 v[2:5], v[196:199], v[220:223], v[2:5]
	ds_read_b128 v[236:239], v245 offset:41536
	s_waitcnt lgkmcnt(6)
	v_mfma_f32_16x16x32_bf16 v[6:9], v[196:199], v[224:227], v[6:9]
	ds_read_b128 v[240:243], v245 offset:43840
	ds_read_b128 v[196:199], v244 offset:64
	s_waitcnt lgkmcnt(7)
	v_mfma_f32_16x16x32_bf16 v[42:45], v[200:203], v[212:215], v[42:45]
	v_mfma_f32_16x16x32_bf16 v[46:49], v[200:203], v[216:219], v[46:49]
	v_mfma_f32_16x16x32_bf16 v[10:13], v[200:203], v[220:223], v[10:13]
	v_mfma_f32_16x16x32_bf16 v[14:17], v[200:203], v[224:227], v[14:17]
	ds_read_b128 v[200:203], v244 offset:2368
	s_waitcnt lgkmcnt(7)
	v_mfma_f32_16x16x32_bf16 v[50:53], v[204:207], v[212:215], v[50:53]
	v_mfma_f32_16x16x32_bf16 v[54:57], v[204:207], v[216:219], v[54:57]
	v_mfma_f32_16x16x32_bf16 v[18:21], v[204:207], v[220:223], v[18:21]
	v_mfma_f32_16x16x32_bf16 v[22:25], v[204:207], v[224:227], v[22:25]
	ds_read_b128 v[204:207], v244 offset:4672
	s_setprio 1
	s_waitcnt vmcnt(15)
	ds_write_b128 v95, v[98:101] offset:18432
	s_waitcnt vmcnt(14)
	ds_write_b128 v95, v[102:105] offset:23040
	s_waitcnt lgkmcnt(9)
	v_mfma_f32_16x16x32_bf16 v[58:61], v[208:211], v[212:215], v[58:61]
	v_mfma_f32_16x16x32_bf16 v[62:65], v[208:211], v[216:219], v[62:65]
	v_mfma_f32_16x16x32_bf16 v[26:29], v[208:211], v[220:223], v[26:29]
	v_mfma_f32_16x16x32_bf16 v[30:33], v[208:211], v[224:227], v[30:33]
	ds_read_b128 v[208:211], v244 offset:6976
	s_waitcnt vmcnt(13)
	ds_write_b128 v95, v[106:109] offset:27648
	s_waitcnt vmcnt(12)
	ds_write_b128 v95, v[110:113] offset:32256
	s_waitcnt lgkmcnt(7)
	v_mfma_f32_16x16x32_bf16 v[34:37], v[196:199], v[228:231], v[34:37]
	v_mfma_f32_16x16x32_bf16 v[38:41], v[196:199], v[232:235], v[38:41]
	v_mfma_f32_16x16x32_bf16 v[2:5], v[196:199], v[236:239], v[2:5]
	v_mfma_f32_16x16x32_bf16 v[6:9], v[196:199], v[240:243], v[6:9]
	s_waitcnt vmcnt(11)
	ds_write_b128 v95, v[114:117] offset:55296
	s_waitcnt vmcnt(10)
	ds_write_b128 v95, v[118:121] offset:59904
	s_waitcnt lgkmcnt(8)
	v_mfma_f32_16x16x32_bf16 v[42:45], v[200:203], v[228:231], v[42:45]
	v_mfma_f32_16x16x32_bf16 v[46:49], v[200:203], v[232:235], v[46:49]
	v_mfma_f32_16x16x32_bf16 v[10:13], v[200:203], v[236:239], v[10:13]
	v_mfma_f32_16x16x32_bf16 v[14:17], v[200:203], v[240:243], v[14:17]
	s_waitcnt vmcnt(9)
	ds_write_b128 v95, v[122:125] offset:64512
	s_waitcnt vmcnt(8)
	ds_write_b128 v96, v[126:129] offset:32256
	s_waitcnt lgkmcnt(0)
	s_barrier
	ds_read_b128 v[212:215], v245 offset:55296
	ds_read_b128 v[196:199], v244 offset:18432
	ds_read_b128 v[216:219], v245 offset:57600
	ds_read_b128 v[220:223], v245 offset:59904
	ds_read_b128 v[224:227], v245 offset:62208
	ds_read_b128 v[200:203], v244 offset:20736
	s_setprio 0
	v_mfma_f32_16x16x32_bf16 v[50:53], v[204:207], v[228:231], v[50:53]
	v_mfma_f32_16x16x32_bf16 v[54:57], v[204:207], v[232:235], v[54:57]
	v_mfma_f32_16x16x32_bf16 v[18:21], v[204:207], v[236:239], v[18:21]
	v_mfma_f32_16x16x32_bf16 v[22:25], v[204:207], v[240:243], v[22:25]
	ds_read_b128 v[204:207], v244 offset:23040
	v_mfma_f32_16x16x32_bf16 v[58:61], v[208:211], v[228:231], v[58:61]
	v_mfma_f32_16x16x32_bf16 v[62:65], v[208:211], v[232:235], v[62:65]
	v_mfma_f32_16x16x32_bf16 v[26:29], v[208:211], v[236:239], v[26:29]
	v_mfma_f32_16x16x32_bf16 v[30:33], v[208:211], v[240:243], v[30:33]
	ds_read_b128 v[208:211], v244 offset:25344
	global_load_dwordx4 v[98:101], v[72:73], off offset:640
	global_load_dwordx4 v[102:105], v[74:75], off offset:640
	global_load_dwordx4 v[106:109], v[76:77], off offset:640
	global_load_dwordx4 v[110:113], v[78:79], off offset:640
	global_load_dwordx4 v[114:117], v[80:81], off offset:640
	global_load_dwordx4 v[118:121], v[82:83], off offset:640
	global_load_dwordx4 v[122:125], v[84:85], off offset:640
	global_load_dwordx4 v[126:129], v[86:87], off offset:640
	s_waitcnt lgkmcnt(6)
	v_mfma_f32_16x16x32_bf16 v[34:37], v[196:199], v[212:215], v[34:37]
	ds_read_b128 v[228:231], v245 offset:55360
	s_waitcnt lgkmcnt(6)
	v_mfma_f32_16x16x32_bf16 v[38:41], v[196:199], v[216:219], v[38:41]
	ds_read_b128 v[232:235], v245 offset:57664
	s_waitcnt lgkmcnt(6)
	v_mfma_f32_16x16x32_bf16 v[2:5], v[196:199], v[220:223], v[2:5]
	ds_read_b128 v[236:239], v245 offset:59968
	s_waitcnt lgkmcnt(6)
	v_mfma_f32_16x16x32_bf16 v[6:9], v[196:199], v[224:227], v[6:9]
	ds_read_b128 v[240:243], v245 offset:62272
	ds_read_b128 v[196:199], v244 offset:18496
	s_waitcnt lgkmcnt(7)
	v_mfma_f32_16x16x32_bf16 v[42:45], v[200:203], v[212:215], v[42:45]
	v_mfma_f32_16x16x32_bf16 v[46:49], v[200:203], v[216:219], v[46:49]
	v_mfma_f32_16x16x32_bf16 v[10:13], v[200:203], v[220:223], v[10:13]
	v_mfma_f32_16x16x32_bf16 v[14:17], v[200:203], v[224:227], v[14:17]
	ds_read_b128 v[200:203], v244 offset:20800
	s_waitcnt lgkmcnt(7)
	v_mfma_f32_16x16x32_bf16 v[50:53], v[204:207], v[212:215], v[50:53]
	v_mfma_f32_16x16x32_bf16 v[54:57], v[204:207], v[216:219], v[54:57]
	v_mfma_f32_16x16x32_bf16 v[18:21], v[204:207], v[220:223], v[18:21]
	v_mfma_f32_16x16x32_bf16 v[22:25], v[204:207], v[224:227], v[22:25]
	ds_read_b128 v[204:207], v244 offset:23104
	s_setprio 1
	s_waitcnt vmcnt(15)
	ds_write_b128 v95, v[136:139]
	s_waitcnt vmcnt(14)
	ds_write_b128 v95, v[140:143] offset:4608
	s_waitcnt lgkmcnt(9)
	v_mfma_f32_16x16x32_bf16 v[58:61], v[208:211], v[212:215], v[58:61]
	v_mfma_f32_16x16x32_bf16 v[62:65], v[208:211], v[216:219], v[62:65]
	v_mfma_f32_16x16x32_bf16 v[26:29], v[208:211], v[220:223], v[26:29]
	v_mfma_f32_16x16x32_bf16 v[30:33], v[208:211], v[224:227], v[30:33]
	ds_read_b128 v[208:211], v244 offset:25408
	s_waitcnt vmcnt(13)
	ds_write_b128 v95, v[144:147] offset:9216
	s_waitcnt vmcnt(12)
	ds_write_b128 v95, v[148:151] offset:13824
	s_waitcnt lgkmcnt(7)
	v_mfma_f32_16x16x32_bf16 v[34:37], v[196:199], v[228:231], v[34:37]
	v_mfma_f32_16x16x32_bf16 v[38:41], v[196:199], v[232:235], v[38:41]
	v_mfma_f32_16x16x32_bf16 v[2:5], v[196:199], v[236:239], v[2:5]
	v_mfma_f32_16x16x32_bf16 v[6:9], v[196:199], v[240:243], v[6:9]
	s_waitcnt vmcnt(11)
	ds_write_b128 v95, v[152:155] offset:36864
	s_waitcnt vmcnt(10)
	ds_write_b128 v95, v[156:159] offset:41472
	s_waitcnt lgkmcnt(8)
	v_mfma_f32_16x16x32_bf16 v[42:45], v[200:203], v[228:231], v[42:45]
	v_mfma_f32_16x16x32_bf16 v[46:49], v[200:203], v[232:235], v[46:49]
	v_mfma_f32_16x16x32_bf16 v[10:13], v[200:203], v[236:239], v[10:13]
	v_mfma_f32_16x16x32_bf16 v[14:17], v[200:203], v[240:243], v[14:17]
	s_waitcnt vmcnt(9)
	ds_write_b128 v95, v[160:163] offset:46080
	s_waitcnt vmcnt(8)
	ds_write_b128 v95, v[164:167] offset:50688
	s_waitcnt lgkmcnt(0)
	s_barrier
	ds_read_b128 v[212:215], v245 offset:36864
	ds_read_b128 v[196:199], v244
	ds_read_b128 v[216:219], v245 offset:39168
	ds_read_b128 v[220:223], v245 offset:41472
	ds_read_b128 v[224:227], v245 offset:43776
	ds_read_b128 v[200:203], v244 offset:2304
	s_setprio 0
	v_mfma_f32_16x16x32_bf16 v[50:53], v[204:207], v[228:231], v[50:53]
	v_mfma_f32_16x16x32_bf16 v[54:57], v[204:207], v[232:235], v[54:57]
	v_mfma_f32_16x16x32_bf16 v[18:21], v[204:207], v[236:239], v[18:21]
	v_mfma_f32_16x16x32_bf16 v[22:25], v[204:207], v[240:243], v[22:25]
	ds_read_b128 v[204:207], v244 offset:4608
	v_mfma_f32_16x16x32_bf16 v[58:61], v[208:211], v[228:231], v[58:61]
	v_mfma_f32_16x16x32_bf16 v[62:65], v[208:211], v[232:235], v[62:65]
	v_mfma_f32_16x16x32_bf16 v[26:29], v[208:211], v[236:239], v[26:29]
	v_mfma_f32_16x16x32_bf16 v[30:33], v[208:211], v[240:243], v[30:33]
	ds_read_b128 v[208:211], v244 offset:6912
	global_load_dwordx4 v[136:139], v[72:73], off offset:768
	global_load_dwordx4 v[140:143], v[74:75], off offset:768
	global_load_dwordx4 v[144:147], v[76:77], off offset:768
	global_load_dwordx4 v[148:151], v[78:79], off offset:768
	global_load_dwordx4 v[152:155], v[80:81], off offset:768
	global_load_dwordx4 v[156:159], v[82:83], off offset:768
	global_load_dwordx4 v[160:163], v[84:85], off offset:768
	global_load_dwordx4 v[164:167], v[86:87], off offset:768
	s_waitcnt lgkmcnt(6)
	v_mfma_f32_16x16x32_bf16 v[34:37], v[196:199], v[212:215], v[34:37]
	ds_read_b128 v[228:231], v245 offset:36928
	s_waitcnt lgkmcnt(6)
	v_mfma_f32_16x16x32_bf16 v[38:41], v[196:199], v[216:219], v[38:41]
	ds_read_b128 v[232:235], v245 offset:39232
	s_waitcnt lgkmcnt(6)
	v_mfma_f32_16x16x32_bf16 v[2:5], v[196:199], v[220:223], v[2:5]
	ds_read_b128 v[236:239], v245 offset:41536
	s_waitcnt lgkmcnt(6)
	v_mfma_f32_16x16x32_bf16 v[6:9], v[196:199], v[224:227], v[6:9]
	ds_read_b128 v[240:243], v245 offset:43840
	ds_read_b128 v[196:199], v244 offset:64
	s_waitcnt lgkmcnt(7)
	v_mfma_f32_16x16x32_bf16 v[42:45], v[200:203], v[212:215], v[42:45]
	v_mfma_f32_16x16x32_bf16 v[46:49], v[200:203], v[216:219], v[46:49]
	v_mfma_f32_16x16x32_bf16 v[10:13], v[200:203], v[220:223], v[10:13]
	v_mfma_f32_16x16x32_bf16 v[14:17], v[200:203], v[224:227], v[14:17]
	ds_read_b128 v[200:203], v244 offset:2368
	s_waitcnt lgkmcnt(7)
	v_mfma_f32_16x16x32_bf16 v[50:53], v[204:207], v[212:215], v[50:53]
	v_mfma_f32_16x16x32_bf16 v[54:57], v[204:207], v[216:219], v[54:57]
	v_mfma_f32_16x16x32_bf16 v[18:21], v[204:207], v[220:223], v[18:21]
	v_mfma_f32_16x16x32_bf16 v[22:25], v[204:207], v[224:227], v[22:25]
	ds_read_b128 v[204:207], v244 offset:4672
	s_setprio 1
	s_waitcnt vmcnt(15)
	ds_write_b128 v95, v[98:101] offset:18432
	s_waitcnt vmcnt(14)
	ds_write_b128 v95, v[102:105] offset:23040
	s_waitcnt lgkmcnt(9)
	v_mfma_f32_16x16x32_bf16 v[58:61], v[208:211], v[212:215], v[58:61]
	v_mfma_f32_16x16x32_bf16 v[62:65], v[208:211], v[216:219], v[62:65]
	v_mfma_f32_16x16x32_bf16 v[26:29], v[208:211], v[220:223], v[26:29]
	v_mfma_f32_16x16x32_bf16 v[30:33], v[208:211], v[224:227], v[30:33]
	ds_read_b128 v[208:211], v244 offset:6976
	s_waitcnt vmcnt(13)
	ds_write_b128 v95, v[106:109] offset:27648
	s_waitcnt vmcnt(12)
	ds_write_b128 v95, v[110:113] offset:32256
	s_waitcnt lgkmcnt(7)
	v_mfma_f32_16x16x32_bf16 v[34:37], v[196:199], v[228:231], v[34:37]
	v_mfma_f32_16x16x32_bf16 v[38:41], v[196:199], v[232:235], v[38:41]
	v_mfma_f32_16x16x32_bf16 v[2:5], v[196:199], v[236:239], v[2:5]
	v_mfma_f32_16x16x32_bf16 v[6:9], v[196:199], v[240:243], v[6:9]
	s_waitcnt vmcnt(11)
	ds_write_b128 v95, v[114:117] offset:55296
	s_waitcnt vmcnt(10)
	ds_write_b128 v95, v[118:121] offset:59904
	s_waitcnt lgkmcnt(8)
	v_mfma_f32_16x16x32_bf16 v[42:45], v[200:203], v[228:231], v[42:45]
	v_mfma_f32_16x16x32_bf16 v[46:49], v[200:203], v[232:235], v[46:49]
	v_mfma_f32_16x16x32_bf16 v[10:13], v[200:203], v[236:239], v[10:13]
	v_mfma_f32_16x16x32_bf16 v[14:17], v[200:203], v[240:243], v[14:17]
	s_waitcnt vmcnt(9)
	ds_write_b128 v95, v[122:125] offset:64512
	s_waitcnt vmcnt(8)
	ds_write_b128 v96, v[126:129] offset:32256
	s_waitcnt lgkmcnt(0)
	s_barrier
	ds_read_b128 v[212:215], v245 offset:55296
	ds_read_b128 v[196:199], v244 offset:18432
	ds_read_b128 v[216:219], v245 offset:57600
	ds_read_b128 v[220:223], v245 offset:59904
	ds_read_b128 v[224:227], v245 offset:62208
	ds_read_b128 v[200:203], v244 offset:20736
	s_setprio 0
	v_mfma_f32_16x16x32_bf16 v[50:53], v[204:207], v[228:231], v[50:53]
	v_mfma_f32_16x16x32_bf16 v[54:57], v[204:207], v[232:235], v[54:57]
	v_mfma_f32_16x16x32_bf16 v[18:21], v[204:207], v[236:239], v[18:21]
	v_mfma_f32_16x16x32_bf16 v[22:25], v[204:207], v[240:243], v[22:25]
	ds_read_b128 v[204:207], v244 offset:23040
	v_mfma_f32_16x16x32_bf16 v[58:61], v[208:211], v[228:231], v[58:61]
	v_mfma_f32_16x16x32_bf16 v[62:65], v[208:211], v[232:235], v[62:65]
	v_mfma_f32_16x16x32_bf16 v[26:29], v[208:211], v[236:239], v[26:29]
	v_mfma_f32_16x16x32_bf16 v[30:33], v[208:211], v[240:243], v[30:33]
	ds_read_b128 v[208:211], v244 offset:25344
	global_load_dwordx4 v[98:101], v[72:73], off offset:896
	global_load_dwordx4 v[102:105], v[74:75], off offset:896
	global_load_dwordx4 v[106:109], v[76:77], off offset:896
	global_load_dwordx4 v[110:113], v[78:79], off offset:896
	global_load_dwordx4 v[114:117], v[80:81], off offset:896
	global_load_dwordx4 v[118:121], v[82:83], off offset:896
	global_load_dwordx4 v[122:125], v[84:85], off offset:896
	global_load_dwordx4 v[126:129], v[86:87], off offset:896
	s_waitcnt lgkmcnt(6)
	v_mfma_f32_16x16x32_bf16 v[34:37], v[196:199], v[212:215], v[34:37]
	ds_read_b128 v[228:231], v245 offset:55360
	s_waitcnt lgkmcnt(6)
	v_mfma_f32_16x16x32_bf16 v[38:41], v[196:199], v[216:219], v[38:41]
	ds_read_b128 v[232:235], v245 offset:57664
	s_waitcnt lgkmcnt(6)
	v_mfma_f32_16x16x32_bf16 v[2:5], v[196:199], v[220:223], v[2:5]
	ds_read_b128 v[236:239], v245 offset:59968
	s_waitcnt lgkmcnt(6)
	v_mfma_f32_16x16x32_bf16 v[6:9], v[196:199], v[224:227], v[6:9]
	ds_read_b128 v[240:243], v245 offset:62272
	ds_read_b128 v[196:199], v244 offset:18496
	s_waitcnt lgkmcnt(7)
	v_mfma_f32_16x16x32_bf16 v[42:45], v[200:203], v[212:215], v[42:45]
	v_mfma_f32_16x16x32_bf16 v[46:49], v[200:203], v[216:219], v[46:49]
	v_mfma_f32_16x16x32_bf16 v[10:13], v[200:203], v[220:223], v[10:13]
	v_mfma_f32_16x16x32_bf16 v[14:17], v[200:203], v[224:227], v[14:17]
	ds_read_b128 v[200:203], v244 offset:20800
	s_waitcnt lgkmcnt(7)
	v_mfma_f32_16x16x32_bf16 v[50:53], v[204:207], v[212:215], v[50:53]
	v_mfma_f32_16x16x32_bf16 v[54:57], v[204:207], v[216:219], v[54:57]
	v_mfma_f32_16x16x32_bf16 v[18:21], v[204:207], v[220:223], v[18:21]
	v_mfma_f32_16x16x32_bf16 v[22:25], v[204:207], v[224:227], v[22:25]
	ds_read_b128 v[204:207], v244 offset:23104
	s_setprio 1
	s_waitcnt vmcnt(15)
	ds_write_b128 v95, v[136:139]
	s_waitcnt vmcnt(14)
	ds_write_b128 v95, v[140:143] offset:4608
	s_waitcnt lgkmcnt(9)
	v_mfma_f32_16x16x32_bf16 v[58:61], v[208:211], v[212:215], v[58:61]
	v_mfma_f32_16x16x32_bf16 v[62:65], v[208:211], v[216:219], v[62:65]
	v_mfma_f32_16x16x32_bf16 v[26:29], v[208:211], v[220:223], v[26:29]
	v_mfma_f32_16x16x32_bf16 v[30:33], v[208:211], v[224:227], v[30:33]
	ds_read_b128 v[208:211], v244 offset:25408
	s_waitcnt vmcnt(13)
	ds_write_b128 v95, v[144:147] offset:9216
	s_waitcnt vmcnt(12)
	ds_write_b128 v95, v[148:151] offset:13824
	s_waitcnt lgkmcnt(7)
	v_mfma_f32_16x16x32_bf16 v[34:37], v[196:199], v[228:231], v[34:37]
	v_mfma_f32_16x16x32_bf16 v[38:41], v[196:199], v[232:235], v[38:41]
	v_mfma_f32_16x16x32_bf16 v[2:5], v[196:199], v[236:239], v[2:5]
	v_mfma_f32_16x16x32_bf16 v[6:9], v[196:199], v[240:243], v[6:9]
	s_waitcnt vmcnt(11)
	ds_write_b128 v95, v[152:155] offset:36864
	s_waitcnt vmcnt(10)
	ds_write_b128 v95, v[156:159] offset:41472
	s_waitcnt lgkmcnt(8)
	v_mfma_f32_16x16x32_bf16 v[42:45], v[200:203], v[228:231], v[42:45]
	v_mfma_f32_16x16x32_bf16 v[46:49], v[200:203], v[232:235], v[46:49]
	v_mfma_f32_16x16x32_bf16 v[10:13], v[200:203], v[236:239], v[10:13]
	v_mfma_f32_16x16x32_bf16 v[14:17], v[200:203], v[240:243], v[14:17]
	s_waitcnt vmcnt(9)
	ds_write_b128 v95, v[160:163] offset:46080
	s_waitcnt vmcnt(8)
	ds_write_b128 v95, v[164:167] offset:50688
	s_waitcnt lgkmcnt(0)
	s_barrier
	ds_read_b128 v[212:215], v245 offset:36864
	ds_read_b128 v[196:199], v244
	ds_read_b128 v[216:219], v245 offset:39168
	ds_read_b128 v[220:223], v245 offset:41472
	ds_read_b128 v[224:227], v245 offset:43776
	ds_read_b128 v[200:203], v244 offset:2304
	s_setprio 0
	v_mfma_f32_16x16x32_bf16 v[50:53], v[204:207], v[228:231], v[50:53]
	v_mfma_f32_16x16x32_bf16 v[54:57], v[204:207], v[232:235], v[54:57]
	v_mfma_f32_16x16x32_bf16 v[18:21], v[204:207], v[236:239], v[18:21]
	v_mfma_f32_16x16x32_bf16 v[22:25], v[204:207], v[240:243], v[22:25]
	ds_read_b128 v[204:207], v244 offset:4608
	v_mfma_f32_16x16x32_bf16 v[58:61], v[208:211], v[228:231], v[58:61]
	v_mfma_f32_16x16x32_bf16 v[62:65], v[208:211], v[232:235], v[62:65]
	v_mfma_f32_16x16x32_bf16 v[26:29], v[208:211], v[236:239], v[26:29]
	v_mfma_f32_16x16x32_bf16 v[30:33], v[208:211], v[240:243], v[30:33]
	ds_read_b128 v[208:211], v244 offset:6912
	global_load_dwordx4 v[136:139], v[72:73], off offset:1024
	global_load_dwordx4 v[140:143], v[74:75], off offset:1024
	global_load_dwordx4 v[144:147], v[76:77], off offset:1024
	global_load_dwordx4 v[148:151], v[78:79], off offset:1024
	global_load_dwordx4 v[152:155], v[80:81], off offset:1024
	global_load_dwordx4 v[156:159], v[82:83], off offset:1024
	global_load_dwordx4 v[160:163], v[84:85], off offset:1024
	global_load_dwordx4 v[164:167], v[86:87], off offset:1024
	s_waitcnt lgkmcnt(6)
	v_mfma_f32_16x16x32_bf16 v[34:37], v[196:199], v[212:215], v[34:37]
	ds_read_b128 v[228:231], v245 offset:36928
	s_waitcnt lgkmcnt(6)
	v_mfma_f32_16x16x32_bf16 v[38:41], v[196:199], v[216:219], v[38:41]
	ds_read_b128 v[232:235], v245 offset:39232
	s_waitcnt lgkmcnt(6)
	v_mfma_f32_16x16x32_bf16 v[2:5], v[196:199], v[220:223], v[2:5]
	ds_read_b128 v[236:239], v245 offset:41536
	s_waitcnt lgkmcnt(6)
	v_mfma_f32_16x16x32_bf16 v[6:9], v[196:199], v[224:227], v[6:9]
	ds_read_b128 v[240:243], v245 offset:43840
	ds_read_b128 v[196:199], v244 offset:64
	s_waitcnt lgkmcnt(7)
	v_mfma_f32_16x16x32_bf16 v[42:45], v[200:203], v[212:215], v[42:45]
	v_mfma_f32_16x16x32_bf16 v[46:49], v[200:203], v[216:219], v[46:49]
	v_mfma_f32_16x16x32_bf16 v[10:13], v[200:203], v[220:223], v[10:13]
	v_mfma_f32_16x16x32_bf16 v[14:17], v[200:203], v[224:227], v[14:17]
	ds_read_b128 v[200:203], v244 offset:2368
	s_waitcnt lgkmcnt(7)
	v_mfma_f32_16x16x32_bf16 v[50:53], v[204:207], v[212:215], v[50:53]
	v_mfma_f32_16x16x32_bf16 v[54:57], v[204:207], v[216:219], v[54:57]
	v_mfma_f32_16x16x32_bf16 v[18:21], v[204:207], v[220:223], v[18:21]
	v_mfma_f32_16x16x32_bf16 v[22:25], v[204:207], v[224:227], v[22:25]
	ds_read_b128 v[204:207], v244 offset:4672
	s_setprio 1
	s_waitcnt vmcnt(15)
	ds_write_b128 v95, v[98:101] offset:18432
	s_waitcnt vmcnt(14)
	ds_write_b128 v95, v[102:105] offset:23040
	s_waitcnt lgkmcnt(9)
	v_mfma_f32_16x16x32_bf16 v[58:61], v[208:211], v[212:215], v[58:61]
	v_mfma_f32_16x16x32_bf16 v[62:65], v[208:211], v[216:219], v[62:65]
	v_mfma_f32_16x16x32_bf16 v[26:29], v[208:211], v[220:223], v[26:29]
	v_mfma_f32_16x16x32_bf16 v[30:33], v[208:211], v[224:227], v[30:33]
	ds_read_b128 v[208:211], v244 offset:6976
	s_waitcnt vmcnt(13)
	ds_write_b128 v95, v[106:109] offset:27648
	s_waitcnt vmcnt(12)
	ds_write_b128 v95, v[110:113] offset:32256
	s_waitcnt lgkmcnt(7)
	v_mfma_f32_16x16x32_bf16 v[34:37], v[196:199], v[228:231], v[34:37]
	v_mfma_f32_16x16x32_bf16 v[38:41], v[196:199], v[232:235], v[38:41]
	v_mfma_f32_16x16x32_bf16 v[2:5], v[196:199], v[236:239], v[2:5]
	v_mfma_f32_16x16x32_bf16 v[6:9], v[196:199], v[240:243], v[6:9]
	s_waitcnt vmcnt(11)
	ds_write_b128 v95, v[114:117] offset:55296
	s_waitcnt vmcnt(10)
	ds_write_b128 v95, v[118:121] offset:59904
	s_waitcnt lgkmcnt(8)
	v_mfma_f32_16x16x32_bf16 v[42:45], v[200:203], v[228:231], v[42:45]
	v_mfma_f32_16x16x32_bf16 v[46:49], v[200:203], v[232:235], v[46:49]
	v_mfma_f32_16x16x32_bf16 v[10:13], v[200:203], v[236:239], v[10:13]
	v_mfma_f32_16x16x32_bf16 v[14:17], v[200:203], v[240:243], v[14:17]
	s_waitcnt vmcnt(9)
	ds_write_b128 v95, v[122:125] offset:64512
	s_waitcnt vmcnt(8)
	ds_write_b128 v96, v[126:129] offset:32256
	s_waitcnt lgkmcnt(0)
	s_barrier
	ds_read_b128 v[212:215], v245 offset:55296
	ds_read_b128 v[196:199], v244 offset:18432
	ds_read_b128 v[216:219], v245 offset:57600
	ds_read_b128 v[220:223], v245 offset:59904
	ds_read_b128 v[224:227], v245 offset:62208
	ds_read_b128 v[200:203], v244 offset:20736
	s_setprio 0
	v_mfma_f32_16x16x32_bf16 v[50:53], v[204:207], v[228:231], v[50:53]
	v_mfma_f32_16x16x32_bf16 v[54:57], v[204:207], v[232:235], v[54:57]
	v_mfma_f32_16x16x32_bf16 v[18:21], v[204:207], v[236:239], v[18:21]
	v_mfma_f32_16x16x32_bf16 v[22:25], v[204:207], v[240:243], v[22:25]
	ds_read_b128 v[204:207], v244 offset:23040
	v_mfma_f32_16x16x32_bf16 v[58:61], v[208:211], v[228:231], v[58:61]
	v_mfma_f32_16x16x32_bf16 v[62:65], v[208:211], v[232:235], v[62:65]
	v_mfma_f32_16x16x32_bf16 v[26:29], v[208:211], v[236:239], v[26:29]
	v_mfma_f32_16x16x32_bf16 v[30:33], v[208:211], v[240:243], v[30:33]
	ds_read_b128 v[208:211], v244 offset:25344
	global_load_dwordx4 v[98:101], v[72:73], off offset:1152
	global_load_dwordx4 v[102:105], v[74:75], off offset:1152
	global_load_dwordx4 v[106:109], v[76:77], off offset:1152
	global_load_dwordx4 v[110:113], v[78:79], off offset:1152
	global_load_dwordx4 v[114:117], v[80:81], off offset:1152
	global_load_dwordx4 v[118:121], v[82:83], off offset:1152
	global_load_dwordx4 v[122:125], v[84:85], off offset:1152
	global_load_dwordx4 v[126:129], v[86:87], off offset:1152
	s_waitcnt lgkmcnt(6)
	v_mfma_f32_16x16x32_bf16 v[34:37], v[196:199], v[212:215], v[34:37]
	ds_read_b128 v[228:231], v245 offset:55360
	s_waitcnt lgkmcnt(6)
	v_mfma_f32_16x16x32_bf16 v[38:41], v[196:199], v[216:219], v[38:41]
	ds_read_b128 v[232:235], v245 offset:57664
	s_waitcnt lgkmcnt(6)
	v_mfma_f32_16x16x32_bf16 v[2:5], v[196:199], v[220:223], v[2:5]
	ds_read_b128 v[236:239], v245 offset:59968
	s_waitcnt lgkmcnt(6)
	v_mfma_f32_16x16x32_bf16 v[6:9], v[196:199], v[224:227], v[6:9]
	ds_read_b128 v[240:243], v245 offset:62272
	ds_read_b128 v[196:199], v244 offset:18496
	s_waitcnt lgkmcnt(7)
	v_mfma_f32_16x16x32_bf16 v[42:45], v[200:203], v[212:215], v[42:45]
	v_mfma_f32_16x16x32_bf16 v[46:49], v[200:203], v[216:219], v[46:49]
	v_mfma_f32_16x16x32_bf16 v[10:13], v[200:203], v[220:223], v[10:13]
	v_mfma_f32_16x16x32_bf16 v[14:17], v[200:203], v[224:227], v[14:17]
	ds_read_b128 v[200:203], v244 offset:20800
	s_waitcnt lgkmcnt(7)
	v_mfma_f32_16x16x32_bf16 v[50:53], v[204:207], v[212:215], v[50:53]
	v_mfma_f32_16x16x32_bf16 v[54:57], v[204:207], v[216:219], v[54:57]
	v_mfma_f32_16x16x32_bf16 v[18:21], v[204:207], v[220:223], v[18:21]
	v_mfma_f32_16x16x32_bf16 v[22:25], v[204:207], v[224:227], v[22:25]
	ds_read_b128 v[204:207], v244 offset:23104
	s_setprio 1
	s_waitcnt vmcnt(15)
	ds_write_b128 v95, v[136:139]
	s_waitcnt vmcnt(14)
	ds_write_b128 v95, v[140:143] offset:4608
	s_waitcnt lgkmcnt(9)
	v_mfma_f32_16x16x32_bf16 v[58:61], v[208:211], v[212:215], v[58:61]
	v_mfma_f32_16x16x32_bf16 v[62:65], v[208:211], v[216:219], v[62:65]
	v_mfma_f32_16x16x32_bf16 v[26:29], v[208:211], v[220:223], v[26:29]
	v_mfma_f32_16x16x32_bf16 v[30:33], v[208:211], v[224:227], v[30:33]
	ds_read_b128 v[208:211], v244 offset:25408
	s_waitcnt vmcnt(13)
	ds_write_b128 v95, v[144:147] offset:9216
	s_waitcnt vmcnt(12)
	ds_write_b128 v95, v[148:151] offset:13824
	s_waitcnt lgkmcnt(7)
	v_mfma_f32_16x16x32_bf16 v[34:37], v[196:199], v[228:231], v[34:37]
	v_mfma_f32_16x16x32_bf16 v[38:41], v[196:199], v[232:235], v[38:41]
	v_mfma_f32_16x16x32_bf16 v[2:5], v[196:199], v[236:239], v[2:5]
	v_mfma_f32_16x16x32_bf16 v[6:9], v[196:199], v[240:243], v[6:9]
	s_waitcnt vmcnt(11)
	ds_write_b128 v95, v[152:155] offset:36864
	s_waitcnt vmcnt(10)
	ds_write_b128 v95, v[156:159] offset:41472
	s_waitcnt lgkmcnt(8)
	v_mfma_f32_16x16x32_bf16 v[42:45], v[200:203], v[228:231], v[42:45]
	v_mfma_f32_16x16x32_bf16 v[46:49], v[200:203], v[232:235], v[46:49]
	v_mfma_f32_16x16x32_bf16 v[10:13], v[200:203], v[236:239], v[10:13]
	v_mfma_f32_16x16x32_bf16 v[14:17], v[200:203], v[240:243], v[14:17]
	s_waitcnt vmcnt(9)
	ds_write_b128 v95, v[160:163] offset:46080
	s_waitcnt vmcnt(8)
	ds_write_b128 v95, v[164:167] offset:50688
	s_waitcnt lgkmcnt(0)
	s_barrier
	ds_read_b128 v[212:215], v245 offset:36864
	ds_read_b128 v[196:199], v244
	ds_read_b128 v[216:219], v245 offset:39168
	ds_read_b128 v[220:223], v245 offset:41472
	ds_read_b128 v[224:227], v245 offset:43776
	ds_read_b128 v[200:203], v244 offset:2304
	s_setprio 0
	v_mfma_f32_16x16x32_bf16 v[50:53], v[204:207], v[228:231], v[50:53]
	v_mfma_f32_16x16x32_bf16 v[54:57], v[204:207], v[232:235], v[54:57]
	v_mfma_f32_16x16x32_bf16 v[18:21], v[204:207], v[236:239], v[18:21]
	v_mfma_f32_16x16x32_bf16 v[22:25], v[204:207], v[240:243], v[22:25]
	ds_read_b128 v[204:207], v244 offset:4608
	v_mfma_f32_16x16x32_bf16 v[58:61], v[208:211], v[228:231], v[58:61]
	v_mfma_f32_16x16x32_bf16 v[62:65], v[208:211], v[232:235], v[62:65]
	v_mfma_f32_16x16x32_bf16 v[26:29], v[208:211], v[236:239], v[26:29]
	v_mfma_f32_16x16x32_bf16 v[30:33], v[208:211], v[240:243], v[30:33]
	ds_read_b128 v[208:211], v244 offset:6912
	global_load_dwordx4 v[136:139], v[72:73], off offset:1280
	global_load_dwordx4 v[140:143], v[74:75], off offset:1280
	global_load_dwordx4 v[144:147], v[76:77], off offset:1280
	global_load_dwordx4 v[148:151], v[78:79], off offset:1280
	global_load_dwordx4 v[152:155], v[80:81], off offset:1280
	global_load_dwordx4 v[156:159], v[82:83], off offset:1280
	global_load_dwordx4 v[160:163], v[84:85], off offset:1280
	global_load_dwordx4 v[164:167], v[86:87], off offset:1280
	s_waitcnt lgkmcnt(6)
	v_mfma_f32_16x16x32_bf16 v[34:37], v[196:199], v[212:215], v[34:37]
	ds_read_b128 v[228:231], v245 offset:36928
	s_waitcnt lgkmcnt(6)
	v_mfma_f32_16x16x32_bf16 v[38:41], v[196:199], v[216:219], v[38:41]
	ds_read_b128 v[232:235], v245 offset:39232
	s_waitcnt lgkmcnt(6)
	v_mfma_f32_16x16x32_bf16 v[2:5], v[196:199], v[220:223], v[2:5]
	ds_read_b128 v[236:239], v245 offset:41536
	s_waitcnt lgkmcnt(6)
	v_mfma_f32_16x16x32_bf16 v[6:9], v[196:199], v[224:227], v[6:9]
	ds_read_b128 v[240:243], v245 offset:43840
	ds_read_b128 v[196:199], v244 offset:64
	s_waitcnt lgkmcnt(7)
	v_mfma_f32_16x16x32_bf16 v[42:45], v[200:203], v[212:215], v[42:45]
	v_mfma_f32_16x16x32_bf16 v[46:49], v[200:203], v[216:219], v[46:49]
	v_mfma_f32_16x16x32_bf16 v[10:13], v[200:203], v[220:223], v[10:13]
	v_mfma_f32_16x16x32_bf16 v[14:17], v[200:203], v[224:227], v[14:17]
	ds_read_b128 v[200:203], v244 offset:2368
	s_waitcnt lgkmcnt(7)
	v_mfma_f32_16x16x32_bf16 v[50:53], v[204:207], v[212:215], v[50:53]
	v_mfma_f32_16x16x32_bf16 v[54:57], v[204:207], v[216:219], v[54:57]
	v_mfma_f32_16x16x32_bf16 v[18:21], v[204:207], v[220:223], v[18:21]
	v_mfma_f32_16x16x32_bf16 v[22:25], v[204:207], v[224:227], v[22:25]
	ds_read_b128 v[204:207], v244 offset:4672
	s_setprio 1
	s_waitcnt vmcnt(15)
	ds_write_b128 v95, v[98:101] offset:18432
	s_waitcnt vmcnt(14)
	ds_write_b128 v95, v[102:105] offset:23040
	s_waitcnt lgkmcnt(9)
	v_mfma_f32_16x16x32_bf16 v[58:61], v[208:211], v[212:215], v[58:61]
	v_mfma_f32_16x16x32_bf16 v[62:65], v[208:211], v[216:219], v[62:65]
	v_mfma_f32_16x16x32_bf16 v[26:29], v[208:211], v[220:223], v[26:29]
	v_mfma_f32_16x16x32_bf16 v[30:33], v[208:211], v[224:227], v[30:33]
	ds_read_b128 v[208:211], v244 offset:6976
	s_waitcnt vmcnt(13)
	ds_write_b128 v95, v[106:109] offset:27648
	s_waitcnt vmcnt(12)
	ds_write_b128 v95, v[110:113] offset:32256
	s_waitcnt lgkmcnt(7)
	v_mfma_f32_16x16x32_bf16 v[34:37], v[196:199], v[228:231], v[34:37]
	v_mfma_f32_16x16x32_bf16 v[38:41], v[196:199], v[232:235], v[38:41]
	v_mfma_f32_16x16x32_bf16 v[2:5], v[196:199], v[236:239], v[2:5]
	v_mfma_f32_16x16x32_bf16 v[6:9], v[196:199], v[240:243], v[6:9]
	s_waitcnt vmcnt(11)
	ds_write_b128 v95, v[114:117] offset:55296
	s_waitcnt vmcnt(10)
	ds_write_b128 v95, v[118:121] offset:59904
	s_waitcnt lgkmcnt(8)
	v_mfma_f32_16x16x32_bf16 v[42:45], v[200:203], v[228:231], v[42:45]
	v_mfma_f32_16x16x32_bf16 v[46:49], v[200:203], v[232:235], v[46:49]
	v_mfma_f32_16x16x32_bf16 v[10:13], v[200:203], v[236:239], v[10:13]
	v_mfma_f32_16x16x32_bf16 v[14:17], v[200:203], v[240:243], v[14:17]
	s_waitcnt vmcnt(9)
	ds_write_b128 v95, v[122:125] offset:64512
	s_waitcnt vmcnt(8)
	ds_write_b128 v96, v[126:129] offset:32256
	s_waitcnt lgkmcnt(0)
	s_barrier
	ds_read_b128 v[212:215], v245 offset:55296
	ds_read_b128 v[196:199], v244 offset:18432
	ds_read_b128 v[216:219], v245 offset:57600
	ds_read_b128 v[220:223], v245 offset:59904
	ds_read_b128 v[224:227], v245 offset:62208
	ds_read_b128 v[200:203], v244 offset:20736
	s_setprio 0
	v_mfma_f32_16x16x32_bf16 v[50:53], v[204:207], v[228:231], v[50:53]
	v_mfma_f32_16x16x32_bf16 v[54:57], v[204:207], v[232:235], v[54:57]
	v_mfma_f32_16x16x32_bf16 v[18:21], v[204:207], v[236:239], v[18:21]
	v_mfma_f32_16x16x32_bf16 v[22:25], v[204:207], v[240:243], v[22:25]
	ds_read_b128 v[204:207], v244 offset:23040
	v_mfma_f32_16x16x32_bf16 v[58:61], v[208:211], v[228:231], v[58:61]
	v_mfma_f32_16x16x32_bf16 v[62:65], v[208:211], v[232:235], v[62:65]
	v_mfma_f32_16x16x32_bf16 v[26:29], v[208:211], v[236:239], v[26:29]
	v_mfma_f32_16x16x32_bf16 v[30:33], v[208:211], v[240:243], v[30:33]
	ds_read_b128 v[208:211], v244 offset:25344
	global_load_dwordx4 v[98:101], v[72:73], off offset:1408
	global_load_dwordx4 v[102:105], v[74:75], off offset:1408
	global_load_dwordx4 v[106:109], v[76:77], off offset:1408
	global_load_dwordx4 v[110:113], v[78:79], off offset:1408
	global_load_dwordx4 v[114:117], v[80:81], off offset:1408
	global_load_dwordx4 v[118:121], v[82:83], off offset:1408
	global_load_dwordx4 v[122:125], v[84:85], off offset:1408
	global_load_dwordx4 v[126:129], v[86:87], off offset:1408
	s_waitcnt lgkmcnt(6)
	v_mfma_f32_16x16x32_bf16 v[34:37], v[196:199], v[212:215], v[34:37]
	ds_read_b128 v[228:231], v245 offset:55360
	s_waitcnt lgkmcnt(6)
	v_mfma_f32_16x16x32_bf16 v[38:41], v[196:199], v[216:219], v[38:41]
	ds_read_b128 v[232:235], v245 offset:57664
	s_waitcnt lgkmcnt(6)
	v_mfma_f32_16x16x32_bf16 v[2:5], v[196:199], v[220:223], v[2:5]
	ds_read_b128 v[236:239], v245 offset:59968
	s_waitcnt lgkmcnt(6)
	v_mfma_f32_16x16x32_bf16 v[6:9], v[196:199], v[224:227], v[6:9]
	ds_read_b128 v[240:243], v245 offset:62272
	ds_read_b128 v[196:199], v244 offset:18496
	s_waitcnt lgkmcnt(7)
	v_mfma_f32_16x16x32_bf16 v[42:45], v[200:203], v[212:215], v[42:45]
	v_mfma_f32_16x16x32_bf16 v[46:49], v[200:203], v[216:219], v[46:49]
	v_mfma_f32_16x16x32_bf16 v[10:13], v[200:203], v[220:223], v[10:13]
	v_mfma_f32_16x16x32_bf16 v[14:17], v[200:203], v[224:227], v[14:17]
	ds_read_b128 v[200:203], v244 offset:20800
	s_waitcnt lgkmcnt(7)
	v_mfma_f32_16x16x32_bf16 v[50:53], v[204:207], v[212:215], v[50:53]
	v_mfma_f32_16x16x32_bf16 v[54:57], v[204:207], v[216:219], v[54:57]
	v_mfma_f32_16x16x32_bf16 v[18:21], v[204:207], v[220:223], v[18:21]
	v_mfma_f32_16x16x32_bf16 v[22:25], v[204:207], v[224:227], v[22:25]
	ds_read_b128 v[204:207], v244 offset:23104
	s_setprio 1
	s_waitcnt vmcnt(15)
	ds_write_b128 v95, v[136:139]
	s_waitcnt vmcnt(14)
	ds_write_b128 v95, v[140:143] offset:4608
	s_waitcnt lgkmcnt(9)
	v_mfma_f32_16x16x32_bf16 v[58:61], v[208:211], v[212:215], v[58:61]
	v_mfma_f32_16x16x32_bf16 v[62:65], v[208:211], v[216:219], v[62:65]
	v_mfma_f32_16x16x32_bf16 v[26:29], v[208:211], v[220:223], v[26:29]
	v_mfma_f32_16x16x32_bf16 v[30:33], v[208:211], v[224:227], v[30:33]
	ds_read_b128 v[208:211], v244 offset:25408
	s_waitcnt vmcnt(13)
	ds_write_b128 v95, v[144:147] offset:9216
	s_waitcnt vmcnt(12)
	ds_write_b128 v95, v[148:151] offset:13824
	s_waitcnt lgkmcnt(7)
	v_mfma_f32_16x16x32_bf16 v[34:37], v[196:199], v[228:231], v[34:37]
	v_mfma_f32_16x16x32_bf16 v[38:41], v[196:199], v[232:235], v[38:41]
	v_mfma_f32_16x16x32_bf16 v[2:5], v[196:199], v[236:239], v[2:5]
	v_mfma_f32_16x16x32_bf16 v[6:9], v[196:199], v[240:243], v[6:9]
	s_waitcnt vmcnt(11)
	ds_write_b128 v95, v[152:155] offset:36864
	s_waitcnt vmcnt(10)
	ds_write_b128 v95, v[156:159] offset:41472
	s_waitcnt lgkmcnt(8)
	v_mfma_f32_16x16x32_bf16 v[42:45], v[200:203], v[228:231], v[42:45]
	v_mfma_f32_16x16x32_bf16 v[46:49], v[200:203], v[232:235], v[46:49]
	v_mfma_f32_16x16x32_bf16 v[10:13], v[200:203], v[236:239], v[10:13]
	v_mfma_f32_16x16x32_bf16 v[14:17], v[200:203], v[240:243], v[14:17]
	s_waitcnt vmcnt(9)
	ds_write_b128 v95, v[160:163] offset:46080
	s_waitcnt vmcnt(8)
	ds_write_b128 v95, v[164:167] offset:50688
	s_waitcnt lgkmcnt(0)
	s_barrier
	ds_read_b128 v[212:215], v245 offset:36864
	ds_read_b128 v[196:199], v244
	ds_read_b128 v[216:219], v245 offset:39168
	ds_read_b128 v[220:223], v245 offset:41472
	ds_read_b128 v[224:227], v245 offset:43776
	ds_read_b128 v[200:203], v244 offset:2304
	s_setprio 0
	v_mfma_f32_16x16x32_bf16 v[50:53], v[204:207], v[228:231], v[50:53]
	v_mfma_f32_16x16x32_bf16 v[54:57], v[204:207], v[232:235], v[54:57]
	v_mfma_f32_16x16x32_bf16 v[18:21], v[204:207], v[236:239], v[18:21]
	v_mfma_f32_16x16x32_bf16 v[22:25], v[204:207], v[240:243], v[22:25]
	ds_read_b128 v[204:207], v244 offset:4608
	v_mfma_f32_16x16x32_bf16 v[58:61], v[208:211], v[228:231], v[58:61]
	v_mfma_f32_16x16x32_bf16 v[62:65], v[208:211], v[232:235], v[62:65]
	v_mfma_f32_16x16x32_bf16 v[26:29], v[208:211], v[236:239], v[26:29]
	v_mfma_f32_16x16x32_bf16 v[30:33], v[208:211], v[240:243], v[30:33]
	ds_read_b128 v[208:211], v244 offset:6912
	global_load_dwordx4 v[136:139], v[72:73], off offset:1536
	global_load_dwordx4 v[140:143], v[74:75], off offset:1536
	global_load_dwordx4 v[144:147], v[76:77], off offset:1536
	global_load_dwordx4 v[148:151], v[78:79], off offset:1536
	global_load_dwordx4 v[152:155], v[80:81], off offset:1536
	global_load_dwordx4 v[156:159], v[82:83], off offset:1536
	global_load_dwordx4 v[160:163], v[84:85], off offset:1536
	global_load_dwordx4 v[164:167], v[86:87], off offset:1536
	s_waitcnt lgkmcnt(6)
	v_mfma_f32_16x16x32_bf16 v[34:37], v[196:199], v[212:215], v[34:37]
	ds_read_b128 v[228:231], v245 offset:36928
	s_waitcnt lgkmcnt(6)
	v_mfma_f32_16x16x32_bf16 v[38:41], v[196:199], v[216:219], v[38:41]
	ds_read_b128 v[232:235], v245 offset:39232
	s_waitcnt lgkmcnt(6)
	v_mfma_f32_16x16x32_bf16 v[2:5], v[196:199], v[220:223], v[2:5]
	ds_read_b128 v[236:239], v245 offset:41536
	s_waitcnt lgkmcnt(6)
	v_mfma_f32_16x16x32_bf16 v[6:9], v[196:199], v[224:227], v[6:9]
	ds_read_b128 v[240:243], v245 offset:43840
	ds_read_b128 v[196:199], v244 offset:64
	s_waitcnt lgkmcnt(7)
	v_mfma_f32_16x16x32_bf16 v[42:45], v[200:203], v[212:215], v[42:45]
	v_mfma_f32_16x16x32_bf16 v[46:49], v[200:203], v[216:219], v[46:49]
	v_mfma_f32_16x16x32_bf16 v[10:13], v[200:203], v[220:223], v[10:13]
	v_mfma_f32_16x16x32_bf16 v[14:17], v[200:203], v[224:227], v[14:17]
	ds_read_b128 v[200:203], v244 offset:2368
	s_waitcnt lgkmcnt(7)
	v_mfma_f32_16x16x32_bf16 v[50:53], v[204:207], v[212:215], v[50:53]
	v_mfma_f32_16x16x32_bf16 v[54:57], v[204:207], v[216:219], v[54:57]
	v_mfma_f32_16x16x32_bf16 v[18:21], v[204:207], v[220:223], v[18:21]
	v_mfma_f32_16x16x32_bf16 v[22:25], v[204:207], v[224:227], v[22:25]
	ds_read_b128 v[204:207], v244 offset:4672
	s_setprio 1
	s_waitcnt vmcnt(15)
	ds_write_b128 v95, v[98:101] offset:18432
	s_waitcnt vmcnt(14)
	ds_write_b128 v95, v[102:105] offset:23040
	s_waitcnt lgkmcnt(9)
	v_mfma_f32_16x16x32_bf16 v[58:61], v[208:211], v[212:215], v[58:61]
	v_mfma_f32_16x16x32_bf16 v[62:65], v[208:211], v[216:219], v[62:65]
	v_mfma_f32_16x16x32_bf16 v[26:29], v[208:211], v[220:223], v[26:29]
	v_mfma_f32_16x16x32_bf16 v[30:33], v[208:211], v[224:227], v[30:33]
	ds_read_b128 v[208:211], v244 offset:6976
	s_waitcnt vmcnt(13)
	ds_write_b128 v95, v[106:109] offset:27648
	s_waitcnt vmcnt(12)
	ds_write_b128 v95, v[110:113] offset:32256
	s_waitcnt lgkmcnt(7)
	v_mfma_f32_16x16x32_bf16 v[34:37], v[196:199], v[228:231], v[34:37]
	v_mfma_f32_16x16x32_bf16 v[38:41], v[196:199], v[232:235], v[38:41]
	v_mfma_f32_16x16x32_bf16 v[2:5], v[196:199], v[236:239], v[2:5]
	v_mfma_f32_16x16x32_bf16 v[6:9], v[196:199], v[240:243], v[6:9]
	s_waitcnt vmcnt(11)
	ds_write_b128 v95, v[114:117] offset:55296
	s_waitcnt vmcnt(10)
	ds_write_b128 v95, v[118:121] offset:59904
	s_waitcnt lgkmcnt(8)
	v_mfma_f32_16x16x32_bf16 v[42:45], v[200:203], v[228:231], v[42:45]
	v_mfma_f32_16x16x32_bf16 v[46:49], v[200:203], v[232:235], v[46:49]
	v_mfma_f32_16x16x32_bf16 v[10:13], v[200:203], v[236:239], v[10:13]
	v_mfma_f32_16x16x32_bf16 v[14:17], v[200:203], v[240:243], v[14:17]
	s_waitcnt vmcnt(9)
	ds_write_b128 v95, v[122:125] offset:64512
	s_waitcnt vmcnt(8)
	ds_write_b128 v96, v[126:129] offset:32256
	s_waitcnt lgkmcnt(0)
	s_barrier
	ds_read_b128 v[212:215], v245 offset:55296
	ds_read_b128 v[196:199], v244 offset:18432
	ds_read_b128 v[216:219], v245 offset:57600
	ds_read_b128 v[220:223], v245 offset:59904
	ds_read_b128 v[224:227], v245 offset:62208
	ds_read_b128 v[200:203], v244 offset:20736
	s_setprio 0
	v_mfma_f32_16x16x32_bf16 v[50:53], v[204:207], v[228:231], v[50:53]
	v_mfma_f32_16x16x32_bf16 v[54:57], v[204:207], v[232:235], v[54:57]
	v_mfma_f32_16x16x32_bf16 v[18:21], v[204:207], v[236:239], v[18:21]
	v_mfma_f32_16x16x32_bf16 v[22:25], v[204:207], v[240:243], v[22:25]
	ds_read_b128 v[204:207], v244 offset:23040
	v_mfma_f32_16x16x32_bf16 v[58:61], v[208:211], v[228:231], v[58:61]
	v_mfma_f32_16x16x32_bf16 v[62:65], v[208:211], v[232:235], v[62:65]
	v_mfma_f32_16x16x32_bf16 v[26:29], v[208:211], v[236:239], v[26:29]
	v_mfma_f32_16x16x32_bf16 v[30:33], v[208:211], v[240:243], v[30:33]
	ds_read_b128 v[208:211], v244 offset:25344
	global_load_dwordx4 v[98:101], v[72:73], off offset:1664
	global_load_dwordx4 v[102:105], v[74:75], off offset:1664
	global_load_dwordx4 v[106:109], v[76:77], off offset:1664
	global_load_dwordx4 v[110:113], v[78:79], off offset:1664
	global_load_dwordx4 v[114:117], v[80:81], off offset:1664
	global_load_dwordx4 v[118:121], v[82:83], off offset:1664
	global_load_dwordx4 v[122:125], v[84:85], off offset:1664
	global_load_dwordx4 v[126:129], v[86:87], off offset:1664
	s_waitcnt lgkmcnt(6)
	v_mfma_f32_16x16x32_bf16 v[34:37], v[196:199], v[212:215], v[34:37]
	ds_read_b128 v[228:231], v245 offset:55360
	s_waitcnt lgkmcnt(6)
	v_mfma_f32_16x16x32_bf16 v[38:41], v[196:199], v[216:219], v[38:41]
	ds_read_b128 v[232:235], v245 offset:57664
	s_waitcnt lgkmcnt(6)
	v_mfma_f32_16x16x32_bf16 v[2:5], v[196:199], v[220:223], v[2:5]
	ds_read_b128 v[236:239], v245 offset:59968
	s_waitcnt lgkmcnt(6)
	v_mfma_f32_16x16x32_bf16 v[6:9], v[196:199], v[224:227], v[6:9]
	ds_read_b128 v[240:243], v245 offset:62272
	ds_read_b128 v[196:199], v244 offset:18496
	s_waitcnt lgkmcnt(7)
	v_mfma_f32_16x16x32_bf16 v[42:45], v[200:203], v[212:215], v[42:45]
	v_mfma_f32_16x16x32_bf16 v[46:49], v[200:203], v[216:219], v[46:49]
	v_mfma_f32_16x16x32_bf16 v[10:13], v[200:203], v[220:223], v[10:13]
	v_mfma_f32_16x16x32_bf16 v[14:17], v[200:203], v[224:227], v[14:17]
	ds_read_b128 v[200:203], v244 offset:20800
	s_waitcnt lgkmcnt(7)
	v_mfma_f32_16x16x32_bf16 v[50:53], v[204:207], v[212:215], v[50:53]
	v_mfma_f32_16x16x32_bf16 v[54:57], v[204:207], v[216:219], v[54:57]
	v_mfma_f32_16x16x32_bf16 v[18:21], v[204:207], v[220:223], v[18:21]
	v_mfma_f32_16x16x32_bf16 v[22:25], v[204:207], v[224:227], v[22:25]
	ds_read_b128 v[204:207], v244 offset:23104
	s_setprio 1
	s_waitcnt vmcnt(15)
	ds_write_b128 v95, v[136:139]
	s_waitcnt vmcnt(14)
	ds_write_b128 v95, v[140:143] offset:4608
	s_waitcnt lgkmcnt(9)
	v_mfma_f32_16x16x32_bf16 v[58:61], v[208:211], v[212:215], v[58:61]
	v_mfma_f32_16x16x32_bf16 v[62:65], v[208:211], v[216:219], v[62:65]
	v_mfma_f32_16x16x32_bf16 v[26:29], v[208:211], v[220:223], v[26:29]
	v_mfma_f32_16x16x32_bf16 v[30:33], v[208:211], v[224:227], v[30:33]
	ds_read_b128 v[208:211], v244 offset:25408
	s_waitcnt vmcnt(13)
	ds_write_b128 v95, v[144:147] offset:9216
	s_waitcnt vmcnt(12)
	ds_write_b128 v95, v[148:151] offset:13824
	s_waitcnt lgkmcnt(7)
	v_mfma_f32_16x16x32_bf16 v[34:37], v[196:199], v[228:231], v[34:37]
	v_mfma_f32_16x16x32_bf16 v[38:41], v[196:199], v[232:235], v[38:41]
	v_mfma_f32_16x16x32_bf16 v[2:5], v[196:199], v[236:239], v[2:5]
	v_mfma_f32_16x16x32_bf16 v[6:9], v[196:199], v[240:243], v[6:9]
	s_waitcnt vmcnt(11)
	ds_write_b128 v95, v[152:155] offset:36864
	s_waitcnt vmcnt(10)
	ds_write_b128 v95, v[156:159] offset:41472
	s_waitcnt lgkmcnt(8)
	v_mfma_f32_16x16x32_bf16 v[42:45], v[200:203], v[228:231], v[42:45]
	v_mfma_f32_16x16x32_bf16 v[46:49], v[200:203], v[232:235], v[46:49]
	v_mfma_f32_16x16x32_bf16 v[10:13], v[200:203], v[236:239], v[10:13]
	v_mfma_f32_16x16x32_bf16 v[14:17], v[200:203], v[240:243], v[14:17]
	s_waitcnt vmcnt(9)
	ds_write_b128 v95, v[160:163] offset:46080
	s_waitcnt vmcnt(8)
	ds_write_b128 v95, v[164:167] offset:50688
	s_waitcnt lgkmcnt(0)
	s_barrier
	ds_read_b128 v[212:215], v245 offset:36864
	ds_read_b128 v[196:199], v244
	ds_read_b128 v[216:219], v245 offset:39168
	ds_read_b128 v[220:223], v245 offset:41472
	ds_read_b128 v[224:227], v245 offset:43776
	ds_read_b128 v[200:203], v244 offset:2304
	s_setprio 0
	v_mfma_f32_16x16x32_bf16 v[50:53], v[204:207], v[228:231], v[50:53]
	v_mfma_f32_16x16x32_bf16 v[54:57], v[204:207], v[232:235], v[54:57]
	v_mfma_f32_16x16x32_bf16 v[18:21], v[204:207], v[236:239], v[18:21]
	v_mfma_f32_16x16x32_bf16 v[22:25], v[204:207], v[240:243], v[22:25]
	ds_read_b128 v[204:207], v244 offset:4608
	v_mfma_f32_16x16x32_bf16 v[58:61], v[208:211], v[228:231], v[58:61]
	v_mfma_f32_16x16x32_bf16 v[62:65], v[208:211], v[232:235], v[62:65]
	v_mfma_f32_16x16x32_bf16 v[26:29], v[208:211], v[236:239], v[26:29]
	v_mfma_f32_16x16x32_bf16 v[30:33], v[208:211], v[240:243], v[30:33]
	ds_read_b128 v[208:211], v244 offset:6912
	global_load_dwordx4 v[136:139], v[72:73], off offset:1792
	global_load_dwordx4 v[140:143], v[74:75], off offset:1792
	global_load_dwordx4 v[144:147], v[76:77], off offset:1792
	global_load_dwordx4 v[148:151], v[78:79], off offset:1792
	global_load_dwordx4 v[152:155], v[80:81], off offset:1792
	global_load_dwordx4 v[156:159], v[82:83], off offset:1792
	global_load_dwordx4 v[160:163], v[84:85], off offset:1792
	global_load_dwordx4 v[164:167], v[86:87], off offset:1792
	s_waitcnt lgkmcnt(6)
	v_mfma_f32_16x16x32_bf16 v[34:37], v[196:199], v[212:215], v[34:37]
	ds_read_b128 v[228:231], v245 offset:36928
	s_waitcnt lgkmcnt(6)
	v_mfma_f32_16x16x32_bf16 v[38:41], v[196:199], v[216:219], v[38:41]
	ds_read_b128 v[232:235], v245 offset:39232
	s_waitcnt lgkmcnt(6)
	v_mfma_f32_16x16x32_bf16 v[2:5], v[196:199], v[220:223], v[2:5]
	ds_read_b128 v[236:239], v245 offset:41536
	s_waitcnt lgkmcnt(6)
	v_mfma_f32_16x16x32_bf16 v[6:9], v[196:199], v[224:227], v[6:9]
	ds_read_b128 v[240:243], v245 offset:43840
	ds_read_b128 v[196:199], v244 offset:64
	s_waitcnt lgkmcnt(7)
	v_mfma_f32_16x16x32_bf16 v[42:45], v[200:203], v[212:215], v[42:45]
	v_mfma_f32_16x16x32_bf16 v[46:49], v[200:203], v[216:219], v[46:49]
	v_mfma_f32_16x16x32_bf16 v[10:13], v[200:203], v[220:223], v[10:13]
	v_mfma_f32_16x16x32_bf16 v[14:17], v[200:203], v[224:227], v[14:17]
	ds_read_b128 v[200:203], v244 offset:2368
	s_waitcnt lgkmcnt(7)
	v_mfma_f32_16x16x32_bf16 v[50:53], v[204:207], v[212:215], v[50:53]
	v_mfma_f32_16x16x32_bf16 v[54:57], v[204:207], v[216:219], v[54:57]
	v_mfma_f32_16x16x32_bf16 v[18:21], v[204:207], v[220:223], v[18:21]
	v_mfma_f32_16x16x32_bf16 v[22:25], v[204:207], v[224:227], v[22:25]
	ds_read_b128 v[204:207], v244 offset:4672
	s_setprio 1
	s_waitcnt vmcnt(15)
	ds_write_b128 v95, v[98:101] offset:18432
	s_waitcnt vmcnt(14)
	ds_write_b128 v95, v[102:105] offset:23040
	s_waitcnt lgkmcnt(9)
	v_mfma_f32_16x16x32_bf16 v[58:61], v[208:211], v[212:215], v[58:61]
	v_mfma_f32_16x16x32_bf16 v[62:65], v[208:211], v[216:219], v[62:65]
	v_mfma_f32_16x16x32_bf16 v[26:29], v[208:211], v[220:223], v[26:29]
	v_mfma_f32_16x16x32_bf16 v[30:33], v[208:211], v[224:227], v[30:33]
	ds_read_b128 v[208:211], v244 offset:6976
	s_waitcnt vmcnt(13)
	ds_write_b128 v95, v[106:109] offset:27648
	s_waitcnt vmcnt(12)
	ds_write_b128 v95, v[110:113] offset:32256
	s_waitcnt lgkmcnt(7)
	v_mfma_f32_16x16x32_bf16 v[34:37], v[196:199], v[228:231], v[34:37]
	v_mfma_f32_16x16x32_bf16 v[38:41], v[196:199], v[232:235], v[38:41]
	v_mfma_f32_16x16x32_bf16 v[2:5], v[196:199], v[236:239], v[2:5]
	v_mfma_f32_16x16x32_bf16 v[6:9], v[196:199], v[240:243], v[6:9]
	s_waitcnt vmcnt(11)
	ds_write_b128 v95, v[114:117] offset:55296
	s_waitcnt vmcnt(10)
	ds_write_b128 v95, v[118:121] offset:59904
	s_waitcnt lgkmcnt(8)
	v_mfma_f32_16x16x32_bf16 v[42:45], v[200:203], v[228:231], v[42:45]
	v_mfma_f32_16x16x32_bf16 v[46:49], v[200:203], v[232:235], v[46:49]
	v_mfma_f32_16x16x32_bf16 v[10:13], v[200:203], v[236:239], v[10:13]
	v_mfma_f32_16x16x32_bf16 v[14:17], v[200:203], v[240:243], v[14:17]
	s_waitcnt vmcnt(9)
	ds_write_b128 v95, v[122:125] offset:64512
	s_waitcnt vmcnt(8)
	ds_write_b128 v96, v[126:129] offset:32256
	s_waitcnt lgkmcnt(0)
	s_barrier
	ds_read_b128 v[212:215], v245 offset:55296
	ds_read_b128 v[196:199], v244 offset:18432
	ds_read_b128 v[216:219], v245 offset:57600
	ds_read_b128 v[220:223], v245 offset:59904
	ds_read_b128 v[224:227], v245 offset:62208
	ds_read_b128 v[200:203], v244 offset:20736
	s_setprio 0
	v_mfma_f32_16x16x32_bf16 v[50:53], v[204:207], v[228:231], v[50:53]
	v_mfma_f32_16x16x32_bf16 v[54:57], v[204:207], v[232:235], v[54:57]
	v_mfma_f32_16x16x32_bf16 v[18:21], v[204:207], v[236:239], v[18:21]
	v_mfma_f32_16x16x32_bf16 v[22:25], v[204:207], v[240:243], v[22:25]
	ds_read_b128 v[204:207], v244 offset:23040
	v_mfma_f32_16x16x32_bf16 v[58:61], v[208:211], v[228:231], v[58:61]
	v_mfma_f32_16x16x32_bf16 v[62:65], v[208:211], v[232:235], v[62:65]
	v_mfma_f32_16x16x32_bf16 v[26:29], v[208:211], v[236:239], v[26:29]
	v_mfma_f32_16x16x32_bf16 v[30:33], v[208:211], v[240:243], v[30:33]
	ds_read_b128 v[208:211], v244 offset:25344
	global_load_dwordx4 v[98:101], v[72:73], off offset:1920
	s_nop 0
	global_load_dwordx4 v[72:75], v[74:75], off offset:1920
	s_nop 0
	global_load_dwordx4 v[102:105], v[76:77], off offset:1920
	s_nop 0
	global_load_dwordx4 v[76:79], v[78:79], off offset:1920
	s_nop 0
	global_load_dwordx4 v[106:109], v[80:81], off offset:1920
	s_nop 0
	global_load_dwordx4 v[80:83], v[82:83], off offset:1920
	s_nop 0
	global_load_dwordx4 v[110:113], v[84:85], off offset:1920
	s_nop 0
	global_load_dwordx4 v[84:87], v[86:87], off offset:1920
	s_waitcnt lgkmcnt(6)
	v_mfma_f32_16x16x32_bf16 v[34:37], v[196:199], v[212:215], v[34:37]
	ds_read_b128 v[228:231], v245 offset:55360
	s_waitcnt lgkmcnt(6)
	v_mfma_f32_16x16x32_bf16 v[38:41], v[196:199], v[216:219], v[38:41]
	ds_read_b128 v[232:235], v245 offset:57664
	s_waitcnt lgkmcnt(6)
	v_mfma_f32_16x16x32_bf16 v[2:5], v[196:199], v[220:223], v[2:5]
	ds_read_b128 v[236:239], v245 offset:59968
	s_waitcnt lgkmcnt(6)
	v_mfma_f32_16x16x32_bf16 v[6:9], v[196:199], v[224:227], v[6:9]
	ds_read_b128 v[240:243], v245 offset:62272
	ds_read_b128 v[196:199], v244 offset:18496
	s_waitcnt lgkmcnt(7)
	v_mfma_f32_16x16x32_bf16 v[42:45], v[200:203], v[212:215], v[42:45]
	v_mfma_f32_16x16x32_bf16 v[46:49], v[200:203], v[216:219], v[46:49]
	v_mfma_f32_16x16x32_bf16 v[10:13], v[200:203], v[220:223], v[10:13]
	v_mfma_f32_16x16x32_bf16 v[14:17], v[200:203], v[224:227], v[14:17]
	ds_read_b128 v[200:203], v244 offset:20800
	s_waitcnt lgkmcnt(7)
	v_mfma_f32_16x16x32_bf16 v[50:53], v[204:207], v[212:215], v[50:53]
	v_mfma_f32_16x16x32_bf16 v[54:57], v[204:207], v[216:219], v[54:57]
	v_mfma_f32_16x16x32_bf16 v[18:21], v[204:207], v[220:223], v[18:21]
	v_mfma_f32_16x16x32_bf16 v[22:25], v[204:207], v[224:227], v[22:25]
	ds_read_b128 v[204:207], v244 offset:23104
	s_setprio 1
	s_waitcnt vmcnt(15)
	ds_write_b128 v95, v[136:139]
	s_waitcnt vmcnt(14)
	ds_write_b128 v95, v[140:143] offset:4608
	s_waitcnt lgkmcnt(9)
	v_mfma_f32_16x16x32_bf16 v[58:61], v[208:211], v[212:215], v[58:61]
	v_mfma_f32_16x16x32_bf16 v[62:65], v[208:211], v[216:219], v[62:65]
	v_mfma_f32_16x16x32_bf16 v[26:29], v[208:211], v[220:223], v[26:29]
	v_mfma_f32_16x16x32_bf16 v[30:33], v[208:211], v[224:227], v[30:33]
	ds_read_b128 v[208:211], v244 offset:25408
	s_waitcnt vmcnt(13)
	ds_write_b128 v95, v[144:147] offset:9216
	s_waitcnt vmcnt(12)
	ds_write_b128 v95, v[148:151] offset:13824
	s_waitcnt lgkmcnt(7)
	v_mfma_f32_16x16x32_bf16 v[34:37], v[196:199], v[228:231], v[34:37]
	v_mfma_f32_16x16x32_bf16 v[38:41], v[196:199], v[232:235], v[38:41]
	v_mfma_f32_16x16x32_bf16 v[2:5], v[196:199], v[236:239], v[2:5]
	v_mfma_f32_16x16x32_bf16 v[6:9], v[196:199], v[240:243], v[6:9]
	s_waitcnt vmcnt(11)
	ds_write_b128 v95, v[152:155] offset:36864
	s_waitcnt vmcnt(10)
	ds_write_b128 v95, v[156:159] offset:41472
	s_waitcnt lgkmcnt(8)
	v_mfma_f32_16x16x32_bf16 v[42:45], v[200:203], v[228:231], v[42:45]
	v_mfma_f32_16x16x32_bf16 v[46:49], v[200:203], v[232:235], v[46:49]
	v_mfma_f32_16x16x32_bf16 v[10:13], v[200:203], v[236:239], v[10:13]
	v_mfma_f32_16x16x32_bf16 v[14:17], v[200:203], v[240:243], v[14:17]
	s_waitcnt vmcnt(9)
	ds_write_b128 v95, v[160:163] offset:46080
	s_waitcnt vmcnt(8)
	ds_write_b128 v95, v[164:167] offset:50688
	s_waitcnt lgkmcnt(0)
	s_barrier
	ds_read_b128 v[212:215], v245 offset:36864
	ds_read_b128 v[196:199], v244
	ds_read_b128 v[216:219], v245 offset:39168
	ds_read_b128 v[220:223], v245 offset:41472
	ds_read_b128 v[224:227], v245 offset:43776
	ds_read_b128 v[200:203], v244 offset:2304
	s_setprio 0
	v_mfma_f32_16x16x32_bf16 v[50:53], v[204:207], v[228:231], v[50:53]
	v_mfma_f32_16x16x32_bf16 v[54:57], v[204:207], v[232:235], v[54:57]
	v_mfma_f32_16x16x32_bf16 v[18:21], v[204:207], v[236:239], v[18:21]
	v_mfma_f32_16x16x32_bf16 v[22:25], v[204:207], v[240:243], v[22:25]
	ds_read_b128 v[204:207], v244 offset:4608
	v_mfma_f32_16x16x32_bf16 v[58:61], v[208:211], v[228:231], v[58:61]
	v_mfma_f32_16x16x32_bf16 v[62:65], v[208:211], v[232:235], v[62:65]
	v_mfma_f32_16x16x32_bf16 v[26:29], v[208:211], v[236:239], v[26:29]
	v_mfma_f32_16x16x32_bf16 v[30:33], v[208:211], v[240:243], v[30:33]
	ds_read_b128 v[208:211], v244 offset:6912
	s_waitcnt lgkmcnt(6)
	v_mfma_f32_16x16x32_bf16 v[34:37], v[196:199], v[212:215], v[34:37]
	ds_read_b128 v[228:231], v245 offset:36928
	s_waitcnt lgkmcnt(6)
	v_mfma_f32_16x16x32_bf16 v[38:41], v[196:199], v[216:219], v[38:41]
	ds_read_b128 v[232:235], v245 offset:39232
	s_waitcnt lgkmcnt(6)
	v_mfma_f32_16x16x32_bf16 v[2:5], v[196:199], v[220:223], v[2:5]
	ds_read_b128 v[236:239], v245 offset:41536
	s_waitcnt lgkmcnt(6)
	v_mfma_f32_16x16x32_bf16 v[6:9], v[196:199], v[224:227], v[6:9]
	ds_read_b128 v[240:243], v245 offset:43840
	ds_read_b128 v[196:199], v244 offset:64
	s_waitcnt lgkmcnt(7)
	v_mfma_f32_16x16x32_bf16 v[42:45], v[200:203], v[212:215], v[42:45]
	v_mfma_f32_16x16x32_bf16 v[46:49], v[200:203], v[216:219], v[46:49]
	v_mfma_f32_16x16x32_bf16 v[10:13], v[200:203], v[220:223], v[10:13]
	v_mfma_f32_16x16x32_bf16 v[14:17], v[200:203], v[224:227], v[14:17]
	ds_read_b128 v[200:203], v244 offset:2368
	s_waitcnt lgkmcnt(7)
	v_mfma_f32_16x16x32_bf16 v[50:53], v[204:207], v[212:215], v[50:53]
	v_mfma_f32_16x16x32_bf16 v[54:57], v[204:207], v[216:219], v[54:57]
	v_mfma_f32_16x16x32_bf16 v[18:21], v[204:207], v[220:223], v[18:21]
	v_mfma_f32_16x16x32_bf16 v[22:25], v[204:207], v[224:227], v[22:25]
	ds_read_b128 v[204:207], v244 offset:4672
	s_setprio 1
	s_waitcnt vmcnt(7)
	ds_write_b128 v95, v[98:101] offset:18432
	s_waitcnt vmcnt(6)
	ds_write_b128 v95, v[72:75] offset:23040
	s_waitcnt lgkmcnt(9)
	v_mfma_f32_16x16x32_bf16 v[58:61], v[208:211], v[212:215], v[58:61]
	v_mfma_f32_16x16x32_bf16 v[62:65], v[208:211], v[216:219], v[62:65]
	v_mfma_f32_16x16x32_bf16 v[26:29], v[208:211], v[220:223], v[26:29]
	v_mfma_f32_16x16x32_bf16 v[30:33], v[208:211], v[224:227], v[30:33]
	ds_read_b128 v[208:211], v244 offset:6976
	s_waitcnt vmcnt(5)
	ds_write_b128 v95, v[102:105] offset:27648
	s_waitcnt vmcnt(4)
	ds_write_b128 v95, v[76:79] offset:32256
	s_waitcnt lgkmcnt(7)
	v_mfma_f32_16x16x32_bf16 v[34:37], v[196:199], v[228:231], v[34:37]
	v_mfma_f32_16x16x32_bf16 v[38:41], v[196:199], v[232:235], v[38:41]
	v_mfma_f32_16x16x32_bf16 v[2:5], v[196:199], v[236:239], v[2:5]
	v_mfma_f32_16x16x32_bf16 v[6:9], v[196:199], v[240:243], v[6:9]
	s_waitcnt vmcnt(3)
	ds_write_b128 v95, v[106:109] offset:55296
	s_waitcnt vmcnt(2)
	ds_write_b128 v95, v[80:83] offset:59904
	s_waitcnt lgkmcnt(8)
	v_mfma_f32_16x16x32_bf16 v[42:45], v[200:203], v[228:231], v[42:45]
	v_mfma_f32_16x16x32_bf16 v[46:49], v[200:203], v[232:235], v[46:49]
	v_mfma_f32_16x16x32_bf16 v[10:13], v[200:203], v[236:239], v[10:13]
	v_mfma_f32_16x16x32_bf16 v[14:17], v[200:203], v[240:243], v[14:17]
	s_waitcnt vmcnt(1)
	ds_write_b128 v95, v[110:113] offset:64512
	s_waitcnt vmcnt(0)
	ds_write_b128 v96, v[84:87] offset:32256
	s_waitcnt lgkmcnt(0)
	s_barrier
	ds_read_b128 v[212:215], v245 offset:55296
	ds_read_b128 v[196:199], v244 offset:18432
	ds_read_b128 v[216:219], v245 offset:57600
	ds_read_b128 v[220:223], v245 offset:59904
	ds_read_b128 v[224:227], v245 offset:62208
	ds_read_b128 v[200:203], v244 offset:20736
	s_setprio 0
	v_mfma_f32_16x16x32_bf16 v[50:53], v[204:207], v[228:231], v[50:53]
	v_mfma_f32_16x16x32_bf16 v[54:57], v[204:207], v[232:235], v[54:57]
	v_mfma_f32_16x16x32_bf16 v[18:21], v[204:207], v[236:239], v[18:21]
	v_mfma_f32_16x16x32_bf16 v[22:25], v[204:207], v[240:243], v[22:25]
	ds_read_b128 v[204:207], v244 offset:23040
	v_mfma_f32_16x16x32_bf16 v[58:61], v[208:211], v[228:231], v[58:61]
	v_mfma_f32_16x16x32_bf16 v[62:65], v[208:211], v[232:235], v[62:65]
	v_mfma_f32_16x16x32_bf16 v[26:29], v[208:211], v[236:239], v[26:29]
	v_mfma_f32_16x16x32_bf16 v[30:33], v[208:211], v[240:243], v[30:33]
	ds_read_b128 v[208:211], v244 offset:25344
	s_waitcnt lgkmcnt(6)
	v_mfma_f32_16x16x32_bf16 v[34:37], v[196:199], v[212:215], v[34:37]
	ds_read_b128 v[228:231], v245 offset:55360
	s_waitcnt lgkmcnt(6)
	v_mfma_f32_16x16x32_bf16 v[38:41], v[196:199], v[216:219], v[38:41]
	ds_read_b128 v[232:235], v245 offset:57664
	s_waitcnt lgkmcnt(6)
	v_mfma_f32_16x16x32_bf16 v[2:5], v[196:199], v[220:223], v[2:5]
	ds_read_b128 v[236:239], v245 offset:59968
	s_waitcnt lgkmcnt(6)
	v_mfma_f32_16x16x32_bf16 v[6:9], v[196:199], v[224:227], v[6:9]
	ds_read_b128 v[240:243], v245 offset:62272
	ds_read_b128 v[196:199], v244 offset:18496
	s_waitcnt lgkmcnt(7)
	v_mfma_f32_16x16x32_bf16 v[42:45], v[200:203], v[212:215], v[42:45]
	v_mfma_f32_16x16x32_bf16 v[46:49], v[200:203], v[216:219], v[46:49]
	v_mfma_f32_16x16x32_bf16 v[10:13], v[200:203], v[220:223], v[10:13]
	v_mfma_f32_16x16x32_bf16 v[14:17], v[200:203], v[224:227], v[14:17]
	ds_read_b128 v[200:203], v244 offset:20800
	s_waitcnt lgkmcnt(7)
	v_mfma_f32_16x16x32_bf16 v[50:53], v[204:207], v[212:215], v[50:53]
	v_mfma_f32_16x16x32_bf16 v[54:57], v[204:207], v[216:219], v[54:57]
	v_mfma_f32_16x16x32_bf16 v[18:21], v[204:207], v[220:223], v[18:21]
	v_mfma_f32_16x16x32_bf16 v[22:25], v[204:207], v[224:227], v[22:25]
	ds_read_b128 v[204:207], v244 offset:23104
	s_waitcnt lgkmcnt(7)
	v_mfma_f32_16x16x32_bf16 v[58:61], v[208:211], v[212:215], v[58:61]
	v_mfma_f32_16x16x32_bf16 v[62:65], v[208:211], v[216:219], v[62:65]
	v_mfma_f32_16x16x32_bf16 v[26:29], v[208:211], v[220:223], v[26:29]
	v_mfma_f32_16x16x32_bf16 v[30:33], v[208:211], v[224:227], v[30:33]
	ds_read_b128 v[208:211], v244 offset:25408
	s_waitcnt lgkmcnt(3)
	v_mfma_f32_16x16x32_bf16 v[34:37], v[196:199], v[228:231], v[34:37]
	v_mfma_f32_16x16x32_bf16 v[38:41], v[196:199], v[232:235], v[38:41]
	v_mfma_f32_16x16x32_bf16 v[2:5], v[196:199], v[236:239], v[2:5]
	v_mfma_f32_16x16x32_bf16 v[6:9], v[196:199], v[240:243], v[6:9]
	s_waitcnt lgkmcnt(2)
	v_mfma_f32_16x16x32_bf16 v[42:45], v[200:203], v[228:231], v[42:45]
	v_mfma_f32_16x16x32_bf16 v[46:49], v[200:203], v[232:235], v[46:49]
	v_mfma_f32_16x16x32_bf16 v[10:13], v[200:203], v[236:239], v[10:13]
	v_mfma_f32_16x16x32_bf16 v[14:17], v[200:203], v[240:243], v[14:17]
	v_or_b32_e32 v66, s3, v88
	s_addk_i32 s3, 0xf000
	s_lshr_b32 s3, s3, 12
	s_cmp_lt_u32 s0, 32
	s_cselect_b64 vcc, -1, 0
	s_and_b64 s[4:5], vcc, exec
	s_mul_i32 s0, s3, 0xc00
	s_cselect_b32 s5, s17, s19
	s_cselect_b32 s4, s16, s18
	s_addk_i32 s0, 0xc00
	s_and_b64 s[12:13], vcc, exec
	s_cselect_b32 s0, 0, s0
	v_add_u32_e32 v72, 0xfffff000, v66
	v_cndmask_b32_e32 v72, v72, v66, vcc
	v_mov_b32_e32 v73, v67
	v_lshlrev_b64 v[72:73], 12, v[72:73]
	v_lshl_add_u64 v[78:79], s[4:5], 0, v[72:73]
	v_add_lshl_u32 v72, s2, v97, 2
	s_lshl_b64 s[2:3], s[0:1], 2
	s_add_u32 s0, s82, s2
	s_addc_u32 s3, s83, s3
	v_mov_b32_e32 v73, v67
	s_add_u32 s2, s0, 0xe958000
	v_lshl_add_u64 v[148:149], v[78:79], 0, v[72:73]
	s_addc_u32 s3, s3, 0
	v_or_b32_e32 v156, 0xe0, v72
	v_or_b32_e32 v157, 32, v72
	v_or_b32_e32 v158, 64, v72
	v_or_b32_e32 v159, 0x60, v72
	v_or_b32_e32 v160, 0x80, v72
	v_or_b32_e32 v161, 0xa0, v72
	v_or_b32_e32 v162, 0xc0, v72
	s_waitcnt lgkmcnt(0)
	s_barrier
	v_mfma_f32_16x16x32_bf16 v[50:53], v[204:207], v[228:231], v[50:53]
	v_mfma_f32_16x16x32_bf16 v[54:57], v[204:207], v[232:235], v[54:57]
	v_mfma_f32_16x16x32_bf16 v[18:21], v[204:207], v[236:239], v[18:21]
	v_mfma_f32_16x16x32_bf16 v[22:25], v[204:207], v[240:243], v[22:25]
	v_mfma_f32_16x16x32_bf16 v[58:61], v[208:211], v[228:231], v[58:61]
	v_mfma_f32_16x16x32_bf16 v[62:65], v[208:211], v[232:235], v[62:65]
	v_mfma_f32_16x16x32_bf16 v[26:29], v[208:211], v[236:239], v[26:29]
	v_mfma_f32_16x16x32_bf16 v[30:33], v[208:211], v[240:243], v[30:33]
	s_nop 7
	v_permlane16_swap_b32_e32 v34, v38
	v_permlane16_swap_b32_e32 v35, v39
	v_permlane16_swap_b32_e32 v36, v40
	v_permlane16_swap_b32_e32 v37, v41
	v_permlane16_swap_b32_e32 v42, v46
	v_permlane16_swap_b32_e32 v43, v47
	v_permlane16_swap_b32_e32 v44, v48
	v_permlane16_swap_b32_e32 v45, v49
	v_permlane16_swap_b32_e32 v2, v6
	v_permlane16_swap_b32_e32 v3, v7
	v_permlane16_swap_b32_e32 v4, v8
	v_permlane16_swap_b32_e32 v5, v9
	v_permlane16_swap_b32_e32 v10, v14
	v_permlane16_swap_b32_e32 v11, v15
	v_permlane16_swap_b32_e32 v12, v16
	v_permlane16_swap_b32_e32 v13, v17
	v_permlane16_swap_b32_e32 v50, v54
	v_permlane16_swap_b32_e32 v51, v55
	v_permlane16_swap_b32_e32 v52, v56
	v_permlane16_swap_b32_e32 v53, v57
	v_permlane16_swap_b32_e32 v58, v62
	v_permlane16_swap_b32_e32 v59, v63
	v_permlane16_swap_b32_e32 v60, v64
	v_permlane16_swap_b32_e32 v61, v65
	v_permlane16_swap_b32_e32 v18, v22
	v_permlane16_swap_b32_e32 v19, v23
	v_permlane16_swap_b32_e32 v20, v24
	v_permlane16_swap_b32_e32 v21, v25
	v_permlane16_swap_b32_e32 v26, v30
	v_permlane16_swap_b32_e32 v27, v31
	v_permlane16_swap_b32_e32 v28, v32
	v_permlane16_swap_b32_e32 v29, v33
	v_permlane32_swap_b32_e32 v34, v38
	v_permlane32_swap_b32_e32 v35, v39
	v_permlane32_swap_b32_e32 v36, v40
	v_permlane32_swap_b32_e32 v37, v41
	v_permlane32_swap_b32_e32 v42, v46
	v_permlane32_swap_b32_e32 v43, v47
	v_permlane32_swap_b32_e32 v44, v48
	v_permlane32_swap_b32_e32 v45, v49
	v_permlane32_swap_b32_e32 v2, v6
	v_permlane32_swap_b32_e32 v3, v7
	v_permlane32_swap_b32_e32 v4, v8
	v_permlane32_swap_b32_e32 v5, v9
	v_permlane32_swap_b32_e32 v10, v14
	v_permlane32_swap_b32_e32 v11, v15
	v_permlane32_swap_b32_e32 v12, v16
	v_permlane32_swap_b32_e32 v13, v17
	v_permlane32_swap_b32_e32 v50, v54
	v_permlane32_swap_b32_e32 v51, v55
	v_permlane32_swap_b32_e32 v52, v56
	v_permlane32_swap_b32_e32 v53, v57
	v_permlane32_swap_b32_e32 v58, v62
	v_permlane32_swap_b32_e32 v59, v63
	v_permlane32_swap_b32_e32 v60, v64
	v_permlane32_swap_b32_e32 v61, v65
	v_permlane32_swap_b32_e32 v18, v22
	v_permlane32_swap_b32_e32 v19, v23
	v_permlane32_swap_b32_e32 v20, v24
	v_permlane32_swap_b32_e32 v21, v25
	v_permlane32_swap_b32_e32 v26, v30
	v_permlane32_swap_b32_e32 v27, v31
	v_permlane32_swap_b32_e32 v28, v32
	v_permlane32_swap_b32_e32 v29, v33
	global_load_dwordx4 v[102:105], v[148:149], off offset:224
	s_add_i32 s11, s11, 1
	s_mul_i32 s0, s11, s7
	s_add_i32 s10, s10, s7
	global_load_dwordx4 v[84:87], v156, s[2:3]
	global_load_dwordx4 v[78:81], v[148:149], off offset:192
	v_lshlrev_b64 v[82:83], 12, v[66:67]
	v_lshl_add_u64 v[82:83], s[80:81], 0, v[82:83]
	v_lshl_add_u64 v[82:83], v[82:83], 0, v[72:73]
	s_waitcnt vmcnt(1)
	v_pk_fma_f32 v[64:65], v[64:65], v[86:87], v[104:105]
	global_load_dwordx4 v[74:77], v162, s[2:3]
	global_load_dwordx4 v[98:101], v[148:149], off offset:160
	global_load_dwordx4 v[106:109], v161, s[2:3]
	global_load_dwordx4 v[110:113], v[148:149], off offset:128
	global_load_dwordx4 v[114:117], v160, s[2:3]
	global_load_dwordx4 v[118:121], v[148:149], off offset:96
	global_load_dwordx4 v[122:125], v159, s[2:3]
	global_load_dwordx4 v[126:129], v[148:149], off offset:64
	global_load_dwordx4 v[136:139], v158, s[2:3]
	global_load_dwordx4 v[140:143], v[148:149], off offset:32
	global_load_dwordx4 v[144:147], v157, s[2:3]
	v_or_b32_e32 v86, 32, v66
	global_load_dwordx4 v[148:151], v[148:149], off
	v_pk_fma_f32 v[62:63], v[62:63], v[84:85], v[102:103]
	global_load_dwordx4 v[152:155], v72, s[2:3]
	v_mov_b32_e32 v87, v67
	global_store_dwordx4 v[82:83], v[62:65], off offset:224
	s_waitcnt vmcnt(13)
	v_pk_fma_f32 v[58:59], v[58:59], v[74:75], v[78:79]
	v_pk_fma_f32 v[60:61], v[60:61], v[76:77], v[80:81]
	s_waitcnt vmcnt(11)
	v_pk_fma_f32 v[54:55], v[54:55], v[106:107], v[98:99]
	v_pk_fma_f32 v[56:57], v[56:57], v[108:109], v[100:101]
	s_waitcnt vmcnt(9)
	v_pk_fma_f32 v[50:51], v[50:51], v[114:115], v[110:111]
	v_pk_fma_f32 v[52:53], v[52:53], v[116:117], v[112:113]
	s_waitcnt vmcnt(7)
	v_pk_fma_f32 v[46:47], v[46:47], v[122:123], v[118:119]
	v_pk_fma_f32 v[48:49], v[48:49], v[124:125], v[120:121]
	s_waitcnt vmcnt(5)
	v_pk_fma_f32 v[42:43], v[42:43], v[136:137], v[126:127]
	v_pk_fma_f32 v[44:45], v[44:45], v[138:139], v[128:129]
	s_waitcnt vmcnt(3)
	v_pk_fma_f32 v[38:39], v[38:39], v[144:145], v[140:141]
	v_pk_fma_f32 v[40:41], v[40:41], v[146:147], v[142:143]
	global_store_dwordx4 v[82:83], v[38:41], off offset:32
	global_store_dwordx4 v[82:83], v[42:45], off offset:64
	s_waitcnt vmcnt(3)
	v_pk_fma_f32 v[34:35], v[34:35], v[152:153], v[148:149]
	v_pk_fma_f32 v[36:37], v[36:37], v[154:155], v[150:151]
	global_store_dwordx4 v[82:83], v[34:37], off
	global_store_dwordx4 v[82:83], v[46:49], off offset:96
	global_store_dwordx4 v[82:83], v[50:53], off offset:128
	v_add_u32_e32 v34, 0xfffff020, v66
	v_cndmask_b32_e32 v66, v34, v86, vcc
	v_lshlrev_b64 v[34:35], 12, v[66:67]
	v_lshl_add_u64 v[34:35], s[4:5], 0, v[34:35]
	global_store_dwordx4 v[82:83], v[54:57], off offset:160
	global_store_dwordx4 v[82:83], v[58:61], off offset:192
	v_lshl_add_u64 v[118:119], v[34:35], 0, v[72:73]
	global_load_dwordx4 v[34:37], v[118:119], off offset:224
	global_load_dwordx4 v[38:41], v156, s[2:3]
	global_load_dwordx4 v[42:45], v[118:119], off offset:192
	global_load_dwordx4 v[46:49], v162, s[2:3]
	global_load_dwordx4 v[50:53], v[118:119], off offset:160
	global_load_dwordx4 v[54:57], v161, s[2:3]
	global_load_dwordx4 v[58:61], v[118:119], off offset:128
	global_load_dwordx4 v[62:65], v160, s[2:3]
	global_load_dwordx4 v[74:77], v[118:119], off offset:96
	global_load_dwordx4 v[78:81], v159, s[2:3]
	global_load_dwordx4 v[82:85], v[118:119], off offset:64
	global_load_dwordx4 v[98:101], v158, s[2:3]
	global_load_dwordx4 v[102:105], v[118:119], off offset:32
	global_load_dwordx4 v[106:109], v157, s[2:3]
	global_load_dwordx4 v[110:113], v[118:119], off
	global_load_dwordx4 v[114:117], v72, s[2:3]
	v_lshlrev_b64 v[86:87], 12, v[86:87]
	v_lshl_add_u64 v[86:87], s[80:81], 0, v[86:87]
	s_add_i32 s2, s0, s6
	v_lshl_add_u64 v[72:73], v[86:87], 0, v[72:73]
	s_cmpk_lt_u32 s10, 0x60
	s_waitcnt vmcnt(14)
	v_pk_fma_f32 v[30:31], v[30:31], v[38:39], v[34:35]
	v_pk_fma_f32 v[32:33], v[32:33], v[40:41], v[36:37]
	s_waitcnt vmcnt(12)
	v_pk_fma_f32 v[26:27], v[26:27], v[46:47], v[42:43]
	v_pk_fma_f32 v[28:29], v[28:29], v[48:49], v[44:45]
	s_waitcnt vmcnt(10)
	v_pk_fma_f32 v[22:23], v[22:23], v[54:55], v[50:51]
	v_pk_fma_f32 v[24:25], v[24:25], v[56:57], v[52:53]
	s_waitcnt vmcnt(8)
	v_pk_fma_f32 v[18:19], v[18:19], v[62:63], v[58:59]
	v_pk_fma_f32 v[20:21], v[20:21], v[64:65], v[60:61]
	s_waitcnt vmcnt(6)
	v_pk_fma_f32 v[14:15], v[14:15], v[78:79], v[74:75]
	v_pk_fma_f32 v[16:17], v[16:17], v[80:81], v[76:77]
	s_waitcnt vmcnt(4)
	v_pk_fma_f32 v[10:11], v[10:11], v[98:99], v[82:83]
	v_pk_fma_f32 v[12:13], v[12:13], v[100:101], v[84:85]
	s_waitcnt vmcnt(2)
	v_pk_fma_f32 v[6:7], v[6:7], v[106:107], v[102:103]
	v_pk_fma_f32 v[8:9], v[8:9], v[108:109], v[104:105]
	s_waitcnt vmcnt(0)
	v_pk_fma_f32 v[2:3], v[2:3], v[114:115], v[110:111]
	v_pk_fma_f32 v[4:5], v[4:5], v[116:117], v[112:113]
	global_store_dwordx4 v[72:73], v[2:5], off
	global_store_dwordx4 v[72:73], v[6:9], off offset:32
	global_store_dwordx4 v[72:73], v[10:13], off offset:64
	global_store_dwordx4 v[72:73], v[14:17], off offset:96
	global_store_dwordx4 v[72:73], v[18:21], off offset:128
	global_store_dwordx4 v[72:73], v[22:25], off offset:160
	global_store_dwordx4 v[72:73], v[26:29], off offset:192
	global_store_dwordx4 v[72:73], v[30:33], off offset:224
	s_cbranch_scc1 .LBB0_979

.LBB0_1149:
	v_ashrrev_i32_e32 v3, 31, v2
	v_lshlrev_b64 v[2:3], 11, v[2:3]
	v_lshl_add_u64 v[70:71], v[86:87], 0, v[2:3]
	v_or_b32_e32 v2, s56, v154
	v_ashrrev_i32_e32 v3, 31, v2
	v_lshlrev_b64 v[2:3], 11, v[2:3]
	v_lshl_add_u64 v[72:73], v[84:85], 0, v[2:3]
	v_add_u32_e32 v2, s56, v155
	v_ashrrev_i32_e32 v3, 31, v2
	v_lshlrev_b64 v[2:3], 11, v[2:3]
	v_lshl_add_u64 v[74:75], v[84:85], 0, v[2:3]
	v_add_u32_e32 v2, s56, v156
	v_ashrrev_i32_e32 v3, 31, v2
	v_lshlrev_b64 v[2:3], 11, v[2:3]
	v_lshl_add_u64 v[76:77], v[84:85], 0, v[2:3]
	v_add_u32_e32 v2, s56, v157
	v_ashrrev_i32_e32 v3, 31, v2
	v_ashrrev_i32_e32 v9, 31, v8
	v_ashrrev_i32_e32 v5, 31, v4
	v_lshlrev_b64 v[2:3], 11, v[2:3]
	v_ashrrev_i32_e32 v7, 31, v6
	v_lshlrev_b64 v[8:9], 11, v[8:9]
	v_lshlrev_b64 v[4:5], 11, v[4:5]
	v_lshl_add_u64 v[78:79], v[84:85], 0, v[2:3]
	v_lshlrev_b64 v[2:3], 11, v[6:7]
	v_lshl_add_u64 v[66:67], v[86:87], 0, v[8:9]
	v_lshl_add_u64 v[68:69], v[86:87], 0, v[4:5]
	v_lshl_add_u64 v[80:81], v[86:87], 0, v[2:3]
	global_load_dwordx4 v[2:5], v[70:71], off
	global_load_dwordx4 v[6:9], v[68:69], off
	global_load_dwordx4 v[10:13], v[66:67], off
	global_load_dwordx4 v[14:17], v[80:81], off
	global_load_dwordx4 v[18:21], v[72:73], off
	global_load_dwordx4 v[22:25], v[74:75], off
	global_load_dwordx4 v[26:29], v[76:77], off
	global_load_dwordx4 v[30:33], v[78:79], off
	global_load_dwordx4 v[122:125], v[70:71], off offset:128
	global_load_dwordx4 v[126:129], v[68:69], off offset:128
	global_load_dwordx4 v[136:139], v[66:67], off offset:128
	global_load_dwordx4 v[140:143], v[80:81], off offset:128
	global_load_dwordx4 v[144:147], v[72:73], off offset:128
	global_load_dwordx4 v[148:151], v[74:75], off offset:128
	global_load_dwordx4 v[172:175], v[76:77], off offset:128
	global_load_dwordx4 v[176:179], v[78:79], off offset:128
	s_waitcnt vmcnt(15)
	ds_write_b128 v164, v[2:5] offset:36864
	s_waitcnt vmcnt(14)
	ds_write_b128 v164, v[6:9] offset:41472
	s_waitcnt vmcnt(13)
	ds_write_b128 v164, v[10:13] offset:46080
	s_waitcnt vmcnt(12)
	ds_write_b128 v164, v[14:17] offset:50688
	s_waitcnt vmcnt(11)
	ds_write_b128 v164, v[18:21]
	s_waitcnt vmcnt(10)
	ds_write_b128 v164, v[22:25] offset:4608
	s_waitcnt vmcnt(9)
	ds_write_b128 v164, v[26:29] offset:9216
	s_waitcnt vmcnt(8)
	ds_write_b128 v164, v[30:33] offset:13824
	s_waitcnt lgkmcnt(0)
	s_barrier
	global_load_dwordx4 v[180:183], v[74:75], off offset:256
	global_load_dwordx4 v[188:191], v[76:77], off offset:256
	global_load_dwordx4 v[192:195], v[72:73], off offset:256
	global_load_dwordx4 v[196:199], v[70:71], off offset:256
	global_load_dwordx4 v[200:203], v[68:69], off offset:256
	global_load_dwordx4 v[204:207], v[66:67], off offset:256
	global_load_dwordx4 v[208:211], v[78:79], off offset:256
	global_load_dwordx4 v[212:215], v[80:81], off offset:256
	v_and_b32_e32 v246, 15, v1
	v_add_u32_e32 v246, 4, v246
	v_bfe_u32 v246, v246, 3, 1
	v_bfe_u32 v249, v1, 4, 2
	v_xor_b32_e32 v246, v246, v249
	v_bfe_u32 v249, v1, 5, 1
	v_sub_u32_e32 v246, v246, v249
	v_lshlrev_b32_e32 v246, 4, v246
	v_bfe_u32 v249, v1, 4, 1
	v_mul_u32_u24_e32 v249, 0x900, v249
	v_sub_u32_e32 v246, v246, v249
	v_add_u32_e32 v244, v246, v161
	v_add_u32_e32 v245, v246, v163
	ds_read_b128 v[232:235], v245 offset:36864
	ds_read_b128 v[216:219], v244
	ds_read_b128 v[236:239], v245 offset:39168
	ds_read_b128 v[240:243], v245 offset:41472
	ds_read_b128 v[252:255], v245 offset:43776
	ds_read_b128 v[220:223], v244 offset:2304
	ds_read_b128 v[224:227], v244 offset:4608
	ds_read_b128 v[228:231], v244 offset:6912
	s_waitcnt lgkmcnt(6)
	v_mfma_f32_16x16x32_bf16 v[50:53], v[216:219], v[232:235], 0
	s_waitcnt lgkmcnt(5)
	v_mfma_f32_16x16x32_bf16 v[54:57], v[216:219], v[236:239], 0
	s_waitcnt lgkmcnt(4)
	v_mfma_f32_16x16x32_bf16 v[34:37], v[216:219], v[240:243], 0
	s_waitcnt lgkmcnt(3)
	v_mfma_f32_16x16x32_bf16 v[38:41], v[216:219], v[252:255], 0
	ds_read_b128 v[216:219], v244 offset:64
	s_waitcnt lgkmcnt(3)
	v_mfma_f32_16x16x32_bf16 v[58:61], v[220:223], v[232:235], 0
	v_mfma_f32_16x16x32_bf16 v[62:65], v[220:223], v[236:239], 0
	v_mfma_f32_16x16x32_bf16 v[42:45], v[220:223], v[240:243], 0
	v_mfma_f32_16x16x32_bf16 v[46:49], v[220:223], v[252:255], 0
	ds_read_b128 v[220:223], v244 offset:2368
	s_setprio 1
	s_waitcnt vmcnt(11)
	ds_write_b128 v164, v[144:147] offset:18432
	s_waitcnt vmcnt(10)
	ds_write_b128 v164, v[148:151] offset:23040
	s_waitcnt lgkmcnt(5)
	v_mfma_f32_16x16x32_bf16 v[18:21], v[224:227], v[232:235], 0
	v_mfma_f32_16x16x32_bf16 v[22:25], v[224:227], v[236:239], 0
	v_mfma_f32_16x16x32_bf16 v[2:5], v[224:227], v[240:243], 0
	v_mfma_f32_16x16x32_bf16 v[6:9], v[224:227], v[252:255], 0
	ds_read_b128 v[224:227], v244 offset:4672
	s_waitcnt vmcnt(9)
	ds_write_b128 v164, v[172:175] offset:27648
	s_waitcnt vmcnt(8)
	ds_write_b128 v164, v[176:179] offset:32256
	s_waitcnt lgkmcnt(7)
	v_mfma_f32_16x16x32_bf16 v[26:29], v[228:231], v[232:235], 0
	ds_read_b128 v[232:235], v245 offset:36928
	v_mfma_f32_16x16x32_bf16 v[30:33], v[228:231], v[236:239], 0
	ds_read_b128 v[236:239], v245 offset:39232
	v_mfma_f32_16x16x32_bf16 v[10:13], v[228:231], v[240:243], 0
	ds_read_b128 v[240:243], v245 offset:41536
	v_mfma_f32_16x16x32_bf16 v[14:17], v[228:231], v[252:255], 0
	ds_read_b128 v[252:255], v245 offset:43840
	ds_read_b128 v[228:231], v244 offset:6976
	s_waitcnt lgkmcnt(4)
	v_mfma_f32_16x16x32_bf16 v[50:53], v[216:219], v[232:235], v[50:53]
	s_waitcnt lgkmcnt(3)
	v_mfma_f32_16x16x32_bf16 v[54:57], v[216:219], v[236:239], v[54:57]
	s_waitcnt lgkmcnt(2)
	v_mfma_f32_16x16x32_bf16 v[34:37], v[216:219], v[240:243], v[34:37]
	s_waitcnt lgkmcnt(1)
	v_mfma_f32_16x16x32_bf16 v[38:41], v[216:219], v[252:255], v[38:41]
	ds_write_b128 v164, v[122:125] offset:55296
	ds_write_b128 v164, v[126:129] offset:59904
	v_mfma_f32_16x16x32_bf16 v[58:61], v[220:223], v[232:235], v[58:61]
	v_mfma_f32_16x16x32_bf16 v[62:65], v[220:223], v[236:239], v[62:65]
	v_mfma_f32_16x16x32_bf16 v[42:45], v[220:223], v[240:243], v[42:45]
	v_mfma_f32_16x16x32_bf16 v[46:49], v[220:223], v[252:255], v[46:49]
	ds_write_b128 v164, v[136:139] offset:64512
	ds_write_b128 v165, v[140:143] offset:32256
	v_mfma_f32_16x16x32_bf16 v[18:21], v[224:227], v[232:235], v[18:21]
	v_mfma_f32_16x16x32_bf16 v[22:25], v[224:227], v[236:239], v[22:25]
	v_mfma_f32_16x16x32_bf16 v[2:5], v[224:227], v[240:243], v[2:5]
	v_mfma_f32_16x16x32_bf16 v[6:9], v[224:227], v[252:255], v[6:9]
	s_waitcnt lgkmcnt(4)
	v_mfma_f32_16x16x32_bf16 v[26:29], v[228:231], v[232:235], v[26:29]
	v_mfma_f32_16x16x32_bf16 v[30:33], v[228:231], v[236:239], v[30:33]
	v_mfma_f32_16x16x32_bf16 v[10:13], v[228:231], v[240:243], v[10:13]
	v_mfma_f32_16x16x32_bf16 v[14:17], v[228:231], v[252:255], v[14:17]
	s_waitcnt lgkmcnt(0)
	s_barrier
	global_load_dwordx4 v[122:125], v[72:73], off offset:384
	global_load_dwordx4 v[126:129], v[74:75], off offset:384
	global_load_dwordx4 v[136:139], v[76:77], off offset:384
	global_load_dwordx4 v[140:143], v[78:79], off offset:384
	global_load_dwordx4 v[144:147], v[70:71], off offset:384
	global_load_dwordx4 v[148:151], v[68:69], off offset:384
	global_load_dwordx4 v[172:175], v[66:67], off offset:384
	global_load_dwordx4 v[176:179], v[80:81], off offset:384
	ds_read_b128 v[232:235], v245 offset:55296
	ds_read_b128 v[216:219], v244 offset:18432
	ds_read_b128 v[236:239], v245 offset:57600
	ds_read_b128 v[240:243], v245 offset:59904
	ds_read_b128 v[252:255], v245 offset:62208
	ds_read_b128 v[220:223], v244 offset:20736
	ds_read_b128 v[224:227], v244 offset:23040
	ds_read_b128 v[228:231], v244 offset:25344
	s_setprio 0
	s_waitcnt lgkmcnt(6)
	v_mfma_f32_16x16x32_bf16 v[50:53], v[216:219], v[232:235], v[50:53]
	s_waitcnt lgkmcnt(5)
	v_mfma_f32_16x16x32_bf16 v[54:57], v[216:219], v[236:239], v[54:57]
	s_waitcnt lgkmcnt(4)
	v_mfma_f32_16x16x32_bf16 v[34:37], v[216:219], v[240:243], v[34:37]
	s_waitcnt lgkmcnt(3)
	v_mfma_f32_16x16x32_bf16 v[38:41], v[216:219], v[252:255], v[38:41]
	ds_read_b128 v[216:219], v244 offset:18496
	s_waitcnt lgkmcnt(3)
	v_mfma_f32_16x16x32_bf16 v[58:61], v[220:223], v[232:235], v[58:61]
	v_mfma_f32_16x16x32_bf16 v[62:65], v[220:223], v[236:239], v[62:65]
	v_mfma_f32_16x16x32_bf16 v[42:45], v[220:223], v[240:243], v[42:45]
	v_mfma_f32_16x16x32_bf16 v[46:49], v[220:223], v[252:255], v[46:49]
	ds_read_b128 v[220:223], v244 offset:20800
	s_setprio 1
	s_waitcnt vmcnt(13)
	ds_write_b128 v164, v[192:195]
	ds_write_b128 v164, v[180:183] offset:4608
	s_waitcnt lgkmcnt(5)
	v_mfma_f32_16x16x32_bf16 v[18:21], v[224:227], v[232:235], v[18:21]
	v_mfma_f32_16x16x32_bf16 v[22:25], v[224:227], v[236:239], v[22:25]
	v_mfma_f32_16x16x32_bf16 v[2:5], v[224:227], v[240:243], v[2:5]
	v_mfma_f32_16x16x32_bf16 v[6:9], v[224:227], v[252:255], v[6:9]
	ds_read_b128 v[224:227], v244 offset:23104
	ds_write_b128 v164, v[188:191] offset:9216
	s_waitcnt vmcnt(9)
	ds_write_b128 v164, v[208:211] offset:13824
	s_waitcnt lgkmcnt(7)
	v_mfma_f32_16x16x32_bf16 v[26:29], v[228:231], v[232:235], v[26:29]
	ds_read_b128 v[232:235], v245 offset:55360
	v_mfma_f32_16x16x32_bf16 v[30:33], v[228:231], v[236:239], v[30:33]
	ds_read_b128 v[236:239], v245 offset:57664
	v_mfma_f32_16x16x32_bf16 v[10:13], v[228:231], v[240:243], v[10:13]
	ds_read_b128 v[240:243], v245 offset:59968
	v_mfma_f32_16x16x32_bf16 v[14:17], v[228:231], v[252:255], v[14:17]
	ds_read_b128 v[252:255], v245 offset:62272
	ds_read_b128 v[228:231], v244 offset:25408
	s_waitcnt lgkmcnt(4)
	v_mfma_f32_16x16x32_bf16 v[50:53], v[216:219], v[232:235], v[50:53]
	s_waitcnt lgkmcnt(3)
	v_mfma_f32_16x16x32_bf16 v[54:57], v[216:219], v[236:239], v[54:57]
	s_waitcnt lgkmcnt(2)
	v_mfma_f32_16x16x32_bf16 v[34:37], v[216:219], v[240:243], v[34:37]
	s_waitcnt lgkmcnt(1)
	v_mfma_f32_16x16x32_bf16 v[38:41], v[216:219], v[252:255], v[38:41]
	ds_write_b128 v164, v[196:199] offset:36864
	ds_write_b128 v164, v[200:203] offset:41472
	v_mfma_f32_16x16x32_bf16 v[58:61], v[220:223], v[232:235], v[58:61]
	v_mfma_f32_16x16x32_bf16 v[62:65], v[220:223], v[236:239], v[62:65]
	v_mfma_f32_16x16x32_bf16 v[42:45], v[220:223], v[240:243], v[42:45]
	v_mfma_f32_16x16x32_bf16 v[46:49], v[220:223], v[252:255], v[46:49]
	ds_write_b128 v164, v[204:207] offset:46080
	s_waitcnt vmcnt(8)
	ds_write_b128 v164, v[212:215] offset:50688
	v_mfma_f32_16x16x32_bf16 v[18:21], v[224:227], v[232:235], v[18:21]
	v_mfma_f32_16x16x32_bf16 v[22:25], v[224:227], v[236:239], v[22:25]
	v_mfma_f32_16x16x32_bf16 v[2:5], v[224:227], v[240:243], v[2:5]
	v_mfma_f32_16x16x32_bf16 v[6:9], v[224:227], v[252:255], v[6:9]
	s_waitcnt lgkmcnt(4)
	v_mfma_f32_16x16x32_bf16 v[26:29], v[228:231], v[232:235], v[26:29]
	v_mfma_f32_16x16x32_bf16 v[30:33], v[228:231], v[236:239], v[30:33]
	v_mfma_f32_16x16x32_bf16 v[10:13], v[228:231], v[240:243], v[10:13]
	v_mfma_f32_16x16x32_bf16 v[14:17], v[228:231], v[252:255], v[14:17]
	s_waitcnt lgkmcnt(0)
	s_barrier
	global_load_dwordx4 v[180:183], v[72:73], off offset:512
	global_load_dwordx4 v[188:191], v[74:75], off offset:512
	global_load_dwordx4 v[192:195], v[76:77], off offset:512
	global_load_dwordx4 v[196:199], v[78:79], off offset:512
	global_load_dwordx4 v[200:203], v[70:71], off offset:512
	global_load_dwordx4 v[204:207], v[68:69], off offset:512
	global_load_dwordx4 v[208:211], v[66:67], off offset:512
	global_load_dwordx4 v[212:215], v[80:81], off offset:512
	ds_read_b128 v[232:235], v245 offset:36864
	ds_read_b128 v[216:219], v244
	ds_read_b128 v[236:239], v245 offset:39168
	ds_read_b128 v[240:243], v245 offset:41472
	ds_read_b128 v[252:255], v245 offset:43776
	ds_read_b128 v[220:223], v244 offset:2304
	ds_read_b128 v[224:227], v244 offset:4608
	ds_read_b128 v[228:231], v244 offset:6912
	s_setprio 0
	s_waitcnt lgkmcnt(6)
	v_mfma_f32_16x16x32_bf16 v[50:53], v[216:219], v[232:235], v[50:53]
	s_waitcnt lgkmcnt(5)
	v_mfma_f32_16x16x32_bf16 v[54:57], v[216:219], v[236:239], v[54:57]
	s_waitcnt lgkmcnt(4)
	v_mfma_f32_16x16x32_bf16 v[34:37], v[216:219], v[240:243], v[34:37]
	s_waitcnt lgkmcnt(3)
	v_mfma_f32_16x16x32_bf16 v[38:41], v[216:219], v[252:255], v[38:41]
	ds_read_b128 v[216:219], v244 offset:64
	s_waitcnt lgkmcnt(3)
	v_mfma_f32_16x16x32_bf16 v[58:61], v[220:223], v[232:235], v[58:61]
	v_mfma_f32_16x16x32_bf16 v[62:65], v[220:223], v[236:239], v[62:65]
	v_mfma_f32_16x16x32_bf16 v[42:45], v[220:223], v[240:243], v[42:45]
	v_mfma_f32_16x16x32_bf16 v[46:49], v[220:223], v[252:255], v[46:49]
	ds_read_b128 v[220:223], v244 offset:2368
	s_setprio 1
	s_waitcnt vmcnt(15)
	ds_write_b128 v164, v[122:125] offset:18432
	s_waitcnt vmcnt(14)
	ds_write_b128 v164, v[126:129] offset:23040
	s_waitcnt lgkmcnt(5)
	v_mfma_f32_16x16x32_bf16 v[18:21], v[224:227], v[232:235], v[18:21]
	v_mfma_f32_16x16x32_bf16 v[22:25], v[224:227], v[236:239], v[22:25]
	v_mfma_f32_16x16x32_bf16 v[2:5], v[224:227], v[240:243], v[2:5]
	v_mfma_f32_16x16x32_bf16 v[6:9], v[224:227], v[252:255], v[6:9]
	ds_read_b128 v[224:227], v244 offset:4672
	s_waitcnt vmcnt(13)
	ds_write_b128 v164, v[136:139] offset:27648
	s_waitcnt vmcnt(12)
	ds_write_b128 v164, v[140:143] offset:32256
	s_waitcnt lgkmcnt(7)
	v_mfma_f32_16x16x32_bf16 v[26:29], v[228:231], v[232:235], v[26:29]
	ds_read_b128 v[232:235], v245 offset:36928
	v_mfma_f32_16x16x32_bf16 v[30:33], v[228:231], v[236:239], v[30:33]
	ds_read_b128 v[236:239], v245 offset:39232
	v_mfma_f32_16x16x32_bf16 v[10:13], v[228:231], v[240:243], v[10:13]
	ds_read_b128 v[240:243], v245 offset:41536
	v_mfma_f32_16x16x32_bf16 v[14:17], v[228:231], v[252:255], v[14:17]
	ds_read_b128 v[252:255], v245 offset:43840
	ds_read_b128 v[228:231], v244 offset:6976
	s_waitcnt lgkmcnt(4)
	v_mfma_f32_16x16x32_bf16 v[50:53], v[216:219], v[232:235], v[50:53]
	s_waitcnt lgkmcnt(3)
	v_mfma_f32_16x16x32_bf16 v[54:57], v[216:219], v[236:239], v[54:57]
	s_waitcnt lgkmcnt(2)
	v_mfma_f32_16x16x32_bf16 v[34:37], v[216:219], v[240:243], v[34:37]
	s_waitcnt lgkmcnt(1)
	v_mfma_f32_16x16x32_bf16 v[38:41], v[216:219], v[252:255], v[38:41]
	s_waitcnt vmcnt(11)
	ds_write_b128 v164, v[144:147] offset:55296
	s_waitcnt vmcnt(10)
	ds_write_b128 v164, v[148:151] offset:59904
	v_mfma_f32_16x16x32_bf16 v[58:61], v[220:223], v[232:235], v[58:61]
	v_mfma_f32_16x16x32_bf16 v[62:65], v[220:223], v[236:239], v[62:65]
	v_mfma_f32_16x16x32_bf16 v[42:45], v[220:223], v[240:243], v[42:45]
	v_mfma_f32_16x16x32_bf16 v[46:49], v[220:223], v[252:255], v[46:49]
	s_waitcnt vmcnt(9)
	ds_write_b128 v164, v[172:175] offset:64512
	s_waitcnt vmcnt(8)
	ds_write_b128 v165, v[176:179] offset:32256
	v_mfma_f32_16x16x32_bf16 v[18:21], v[224:227], v[232:235], v[18:21]
	v_mfma_f32_16x16x32_bf16 v[22:25], v[224:227], v[236:239], v[22:25]
	v_mfma_f32_16x16x32_bf16 v[2:5], v[224:227], v[240:243], v[2:5]
	v_mfma_f32_16x16x32_bf16 v[6:9], v[224:227], v[252:255], v[6:9]
	s_waitcnt lgkmcnt(4)
	v_mfma_f32_16x16x32_bf16 v[26:29], v[228:231], v[232:235], v[26:29]
	v_mfma_f32_16x16x32_bf16 v[30:33], v[228:231], v[236:239], v[30:33]
	v_mfma_f32_16x16x32_bf16 v[10:13], v[228:231], v[240:243], v[10:13]
	v_mfma_f32_16x16x32_bf16 v[14:17], v[228:231], v[252:255], v[14:17]
	s_waitcnt lgkmcnt(0)
	s_barrier
	global_load_dwordx4 v[122:125], v[72:73], off offset:640
	global_load_dwordx4 v[126:129], v[74:75], off offset:640
	global_load_dwordx4 v[136:139], v[76:77], off offset:640
	global_load_dwordx4 v[140:143], v[78:79], off offset:640
	global_load_dwordx4 v[144:147], v[70:71], off offset:640
	global_load_dwordx4 v[148:151], v[68:69], off offset:640
	global_load_dwordx4 v[172:175], v[66:67], off offset:640
	global_load_dwordx4 v[176:179], v[80:81], off offset:640
	ds_read_b128 v[232:235], v245 offset:55296
	ds_read_b128 v[216:219], v244 offset:18432
	ds_read_b128 v[236:239], v245 offset:57600
	ds_read_b128 v[240:243], v245 offset:59904
	ds_read_b128 v[252:255], v245 offset:62208
	ds_read_b128 v[220:223], v244 offset:20736
	ds_read_b128 v[224:227], v244 offset:23040
	ds_read_b128 v[228:231], v244 offset:25344
	s_setprio 0
	s_waitcnt lgkmcnt(6)
	v_mfma_f32_16x16x32_bf16 v[50:53], v[216:219], v[232:235], v[50:53]
	s_waitcnt lgkmcnt(5)
	v_mfma_f32_16x16x32_bf16 v[54:57], v[216:219], v[236:239], v[54:57]
	s_waitcnt lgkmcnt(4)
	v_mfma_f32_16x16x32_bf16 v[34:37], v[216:219], v[240:243], v[34:37]
	s_waitcnt lgkmcnt(3)
	v_mfma_f32_16x16x32_bf16 v[38:41], v[216:219], v[252:255], v[38:41]
	ds_read_b128 v[216:219], v244 offset:18496
	s_waitcnt lgkmcnt(3)
	v_mfma_f32_16x16x32_bf16 v[58:61], v[220:223], v[232:235], v[58:61]
	v_mfma_f32_16x16x32_bf16 v[62:65], v[220:223], v[236:239], v[62:65]
	v_mfma_f32_16x16x32_bf16 v[42:45], v[220:223], v[240:243], v[42:45]
	v_mfma_f32_16x16x32_bf16 v[46:49], v[220:223], v[252:255], v[46:49]
	ds_read_b128 v[220:223], v244 offset:20800
	s_setprio 1
	s_waitcnt vmcnt(15)
	ds_write_b128 v164, v[180:183]
	s_waitcnt vmcnt(14)
	ds_write_b128 v164, v[188:191] offset:4608
	s_waitcnt lgkmcnt(5)
	v_mfma_f32_16x16x32_bf16 v[18:21], v[224:227], v[232:235], v[18:21]
	v_mfma_f32_16x16x32_bf16 v[22:25], v[224:227], v[236:239], v[22:25]
	v_mfma_f32_16x16x32_bf16 v[2:5], v[224:227], v[240:243], v[2:5]
	v_mfma_f32_16x16x32_bf16 v[6:9], v[224:227], v[252:255], v[6:9]
	ds_read_b128 v[224:227], v244 offset:23104
	s_waitcnt vmcnt(13)
	ds_write_b128 v164, v[192:195] offset:9216
	s_waitcnt vmcnt(12)
	ds_write_b128 v164, v[196:199] offset:13824
	s_waitcnt lgkmcnt(7)
	v_mfma_f32_16x16x32_bf16 v[26:29], v[228:231], v[232:235], v[26:29]
	ds_read_b128 v[232:235], v245 offset:55360
	v_mfma_f32_16x16x32_bf16 v[30:33], v[228:231], v[236:239], v[30:33]
	ds_read_b128 v[236:239], v245 offset:57664
	v_mfma_f32_16x16x32_bf16 v[10:13], v[228:231], v[240:243], v[10:13]
	ds_read_b128 v[240:243], v245 offset:59968
	v_mfma_f32_16x16x32_bf16 v[14:17], v[228:231], v[252:255], v[14:17]
	ds_read_b128 v[252:255], v245 offset:62272
	ds_read_b128 v[228:231], v244 offset:25408
	s_waitcnt lgkmcnt(4)
	v_mfma_f32_16x16x32_bf16 v[50:53], v[216:219], v[232:235], v[50:53]
	s_waitcnt lgkmcnt(3)
	v_mfma_f32_16x16x32_bf16 v[54:57], v[216:219], v[236:239], v[54:57]
	s_waitcnt lgkmcnt(2)
	v_mfma_f32_16x16x32_bf16 v[34:37], v[216:219], v[240:243], v[34:37]
	s_waitcnt lgkmcnt(1)
	v_mfma_f32_16x16x32_bf16 v[38:41], v[216:219], v[252:255], v[38:41]
	s_waitcnt vmcnt(11)
	ds_write_b128 v164, v[200:203] offset:36864
	s_waitcnt vmcnt(10)
	ds_write_b128 v164, v[204:207] offset:41472
	v_mfma_f32_16x16x32_bf16 v[58:61], v[220:223], v[232:235], v[58:61]
	v_mfma_f32_16x16x32_bf16 v[62:65], v[220:223], v[236:239], v[62:65]
	v_mfma_f32_16x16x32_bf16 v[42:45], v[220:223], v[240:243], v[42:45]
	v_mfma_f32_16x16x32_bf16 v[46:49], v[220:223], v[252:255], v[46:49]
	s_waitcnt vmcnt(9)
	ds_write_b128 v164, v[208:211] offset:46080
	s_waitcnt vmcnt(8)
	ds_write_b128 v164, v[212:215] offset:50688
	v_mfma_f32_16x16x32_bf16 v[18:21], v[224:227], v[232:235], v[18:21]
	v_mfma_f32_16x16x32_bf16 v[22:25], v[224:227], v[236:239], v[22:25]
	v_mfma_f32_16x16x32_bf16 v[2:5], v[224:227], v[240:243], v[2:5]
	v_mfma_f32_16x16x32_bf16 v[6:9], v[224:227], v[252:255], v[6:9]
	s_waitcnt lgkmcnt(4)
	v_mfma_f32_16x16x32_bf16 v[26:29], v[228:231], v[232:235], v[26:29]
	v_mfma_f32_16x16x32_bf16 v[30:33], v[228:231], v[236:239], v[30:33]
	v_mfma_f32_16x16x32_bf16 v[10:13], v[228:231], v[240:243], v[10:13]
	v_mfma_f32_16x16x32_bf16 v[14:17], v[228:231], v[252:255], v[14:17]
	s_waitcnt lgkmcnt(0)
	s_barrier
	global_load_dwordx4 v[180:183], v[72:73], off offset:768
	global_load_dwordx4 v[188:191], v[74:75], off offset:768
	global_load_dwordx4 v[192:195], v[76:77], off offset:768
	global_load_dwordx4 v[196:199], v[78:79], off offset:768
	global_load_dwordx4 v[200:203], v[70:71], off offset:768
	global_load_dwordx4 v[204:207], v[68:69], off offset:768
	global_load_dwordx4 v[208:211], v[66:67], off offset:768
	global_load_dwordx4 v[212:215], v[80:81], off offset:768
	ds_read_b128 v[232:235], v245 offset:36864
	ds_read_b128 v[216:219], v244
	ds_read_b128 v[236:239], v245 offset:39168
	ds_read_b128 v[240:243], v245 offset:41472
	ds_read_b128 v[252:255], v245 offset:43776
	ds_read_b128 v[220:223], v244 offset:2304
	ds_read_b128 v[224:227], v244 offset:4608
	ds_read_b128 v[228:231], v244 offset:6912
	s_setprio 0
	s_waitcnt lgkmcnt(6)
	v_mfma_f32_16x16x32_bf16 v[50:53], v[216:219], v[232:235], v[50:53]
	s_waitcnt lgkmcnt(5)
	v_mfma_f32_16x16x32_bf16 v[54:57], v[216:219], v[236:239], v[54:57]
	s_waitcnt lgkmcnt(4)
	v_mfma_f32_16x16x32_bf16 v[34:37], v[216:219], v[240:243], v[34:37]
	s_waitcnt lgkmcnt(3)
	v_mfma_f32_16x16x32_bf16 v[38:41], v[216:219], v[252:255], v[38:41]
	ds_read_b128 v[216:219], v244 offset:64
	s_waitcnt lgkmcnt(3)
	v_mfma_f32_16x16x32_bf16 v[58:61], v[220:223], v[232:235], v[58:61]
	v_mfma_f32_16x16x32_bf16 v[62:65], v[220:223], v[236:239], v[62:65]
	v_mfma_f32_16x16x32_bf16 v[42:45], v[220:223], v[240:243], v[42:45]
	v_mfma_f32_16x16x32_bf16 v[46:49], v[220:223], v[252:255], v[46:49]
	ds_read_b128 v[220:223], v244 offset:2368
	s_setprio 1
	s_waitcnt vmcnt(15)
	ds_write_b128 v164, v[122:125] offset:18432
	s_waitcnt vmcnt(14)
	ds_write_b128 v164, v[126:129] offset:23040
	s_waitcnt lgkmcnt(5)
	v_mfma_f32_16x16x32_bf16 v[18:21], v[224:227], v[232:235], v[18:21]
	v_mfma_f32_16x16x32_bf16 v[22:25], v[224:227], v[236:239], v[22:25]
	v_mfma_f32_16x16x32_bf16 v[2:5], v[224:227], v[240:243], v[2:5]
	v_mfma_f32_16x16x32_bf16 v[6:9], v[224:227], v[252:255], v[6:9]
	ds_read_b128 v[224:227], v244 offset:4672
	s_waitcnt vmcnt(13)
	ds_write_b128 v164, v[136:139] offset:27648
	s_waitcnt vmcnt(12)
	ds_write_b128 v164, v[140:143] offset:32256
	s_waitcnt lgkmcnt(7)
	v_mfma_f32_16x16x32_bf16 v[26:29], v[228:231], v[232:235], v[26:29]
	ds_read_b128 v[232:235], v245 offset:36928
	v_mfma_f32_16x16x32_bf16 v[30:33], v[228:231], v[236:239], v[30:33]
	ds_read_b128 v[236:239], v245 offset:39232
	v_mfma_f32_16x16x32_bf16 v[10:13], v[228:231], v[240:243], v[10:13]
	ds_read_b128 v[240:243], v245 offset:41536
	v_mfma_f32_16x16x32_bf16 v[14:17], v[228:231], v[252:255], v[14:17]
	ds_read_b128 v[252:255], v245 offset:43840
	ds_read_b128 v[228:231], v244 offset:6976
	s_waitcnt lgkmcnt(4)
	v_mfma_f32_16x16x32_bf16 v[50:53], v[216:219], v[232:235], v[50:53]
	s_waitcnt lgkmcnt(3)
	v_mfma_f32_16x16x32_bf16 v[54:57], v[216:219], v[236:239], v[54:57]
	s_waitcnt lgkmcnt(2)
	v_mfma_f32_16x16x32_bf16 v[34:37], v[216:219], v[240:243], v[34:37]
	s_waitcnt lgkmcnt(1)
	v_mfma_f32_16x16x32_bf16 v[38:41], v[216:219], v[252:255], v[38:41]
	s_waitcnt vmcnt(11)
	ds_write_b128 v164, v[144:147] offset:55296
	s_waitcnt vmcnt(10)
	ds_write_b128 v164, v[148:151] offset:59904
	v_mfma_f32_16x16x32_bf16 v[58:61], v[220:223], v[232:235], v[58:61]
	v_mfma_f32_16x16x32_bf16 v[62:65], v[220:223], v[236:239], v[62:65]
	v_mfma_f32_16x16x32_bf16 v[42:45], v[220:223], v[240:243], v[42:45]
	v_mfma_f32_16x16x32_bf16 v[46:49], v[220:223], v[252:255], v[46:49]
	s_waitcnt vmcnt(9)
	ds_write_b128 v164, v[172:175] offset:64512
	s_waitcnt vmcnt(8)
	ds_write_b128 v165, v[176:179] offset:32256
	v_mfma_f32_16x16x32_bf16 v[18:21], v[224:227], v[232:235], v[18:21]
	v_mfma_f32_16x16x32_bf16 v[22:25], v[224:227], v[236:239], v[22:25]
	v_mfma_f32_16x16x32_bf16 v[2:5], v[224:227], v[240:243], v[2:5]
	v_mfma_f32_16x16x32_bf16 v[6:9], v[224:227], v[252:255], v[6:9]
	s_waitcnt lgkmcnt(4)
	v_mfma_f32_16x16x32_bf16 v[26:29], v[228:231], v[232:235], v[26:29]
	v_mfma_f32_16x16x32_bf16 v[30:33], v[228:231], v[236:239], v[30:33]
	v_mfma_f32_16x16x32_bf16 v[10:13], v[228:231], v[240:243], v[10:13]
	v_mfma_f32_16x16x32_bf16 v[14:17], v[228:231], v[252:255], v[14:17]
	s_waitcnt lgkmcnt(0)
	s_barrier
	global_load_dwordx4 v[122:125], v[72:73], off offset:896
	global_load_dwordx4 v[126:129], v[74:75], off offset:896
	global_load_dwordx4 v[136:139], v[76:77], off offset:896
	global_load_dwordx4 v[140:143], v[78:79], off offset:896
	global_load_dwordx4 v[144:147], v[70:71], off offset:896
	global_load_dwordx4 v[148:151], v[68:69], off offset:896
	global_load_dwordx4 v[172:175], v[66:67], off offset:896
	global_load_dwordx4 v[176:179], v[80:81], off offset:896
	ds_read_b128 v[232:235], v245 offset:55296
	ds_read_b128 v[216:219], v244 offset:18432
	ds_read_b128 v[236:239], v245 offset:57600
	ds_read_b128 v[240:243], v245 offset:59904
	ds_read_b128 v[252:255], v245 offset:62208
	ds_read_b128 v[220:223], v244 offset:20736
	ds_read_b128 v[224:227], v244 offset:23040
	ds_read_b128 v[228:231], v244 offset:25344
	s_setprio 0
	s_waitcnt lgkmcnt(6)
	v_mfma_f32_16x16x32_bf16 v[50:53], v[216:219], v[232:235], v[50:53]
	s_waitcnt lgkmcnt(5)
	v_mfma_f32_16x16x32_bf16 v[54:57], v[216:219], v[236:239], v[54:57]
	s_waitcnt lgkmcnt(4)
	v_mfma_f32_16x16x32_bf16 v[34:37], v[216:219], v[240:243], v[34:37]
	s_waitcnt lgkmcnt(3)
	v_mfma_f32_16x16x32_bf16 v[38:41], v[216:219], v[252:255], v[38:41]
	ds_read_b128 v[216:219], v244 offset:18496
	s_waitcnt lgkmcnt(3)
	v_mfma_f32_16x16x32_bf16 v[58:61], v[220:223], v[232:235], v[58:61]
	v_mfma_f32_16x16x32_bf16 v[62:65], v[220:223], v[236:239], v[62:65]
	v_mfma_f32_16x16x32_bf16 v[42:45], v[220:223], v[240:243], v[42:45]
	v_mfma_f32_16x16x32_bf16 v[46:49], v[220:223], v[252:255], v[46:49]
	ds_read_b128 v[220:223], v244 offset:20800
	s_setprio 1
	s_waitcnt vmcnt(15)
	ds_write_b128 v164, v[180:183]
	s_waitcnt vmcnt(14)
	ds_write_b128 v164, v[188:191] offset:4608
	s_waitcnt lgkmcnt(5)
	v_mfma_f32_16x16x32_bf16 v[18:21], v[224:227], v[232:235], v[18:21]
	v_mfma_f32_16x16x32_bf16 v[22:25], v[224:227], v[236:239], v[22:25]
	v_mfma_f32_16x16x32_bf16 v[2:5], v[224:227], v[240:243], v[2:5]
	v_mfma_f32_16x16x32_bf16 v[6:9], v[224:227], v[252:255], v[6:9]
	ds_read_b128 v[224:227], v244 offset:23104
	s_waitcnt vmcnt(13)
	ds_write_b128 v164, v[192:195] offset:9216
	s_waitcnt vmcnt(12)
	ds_write_b128 v164, v[196:199] offset:13824
	s_waitcnt lgkmcnt(7)
	v_mfma_f32_16x16x32_bf16 v[26:29], v[228:231], v[232:235], v[26:29]
	ds_read_b128 v[232:235], v245 offset:55360
	v_mfma_f32_16x16x32_bf16 v[30:33], v[228:231], v[236:239], v[30:33]
	ds_read_b128 v[236:239], v245 offset:57664
	v_mfma_f32_16x16x32_bf16 v[10:13], v[228:231], v[240:243], v[10:13]
	ds_read_b128 v[240:243], v245 offset:59968
	v_mfma_f32_16x16x32_bf16 v[14:17], v[228:231], v[252:255], v[14:17]
	ds_read_b128 v[252:255], v245 offset:62272
	ds_read_b128 v[228:231], v244 offset:25408
	s_waitcnt lgkmcnt(4)
	v_mfma_f32_16x16x32_bf16 v[50:53], v[216:219], v[232:235], v[50:53]
	s_waitcnt lgkmcnt(3)
	v_mfma_f32_16x16x32_bf16 v[54:57], v[216:219], v[236:239], v[54:57]
	s_waitcnt lgkmcnt(2)
	v_mfma_f32_16x16x32_bf16 v[34:37], v[216:219], v[240:243], v[34:37]
	s_waitcnt lgkmcnt(1)
	v_mfma_f32_16x16x32_bf16 v[38:41], v[216:219], v[252:255], v[38:41]
	s_waitcnt vmcnt(11)
	ds_write_b128 v164, v[200:203] offset:36864
	s_waitcnt vmcnt(10)
	ds_write_b128 v164, v[204:207] offset:41472
	v_mfma_f32_16x16x32_bf16 v[58:61], v[220:223], v[232:235], v[58:61]
	v_mfma_f32_16x16x32_bf16 v[62:65], v[220:223], v[236:239], v[62:65]
	v_mfma_f32_16x16x32_bf16 v[42:45], v[220:223], v[240:243], v[42:45]
	v_mfma_f32_16x16x32_bf16 v[46:49], v[220:223], v[252:255], v[46:49]
	s_waitcnt vmcnt(9)
	ds_write_b128 v164, v[208:211] offset:46080
	s_waitcnt vmcnt(8)
	ds_write_b128 v164, v[212:215] offset:50688
	v_mfma_f32_16x16x32_bf16 v[18:21], v[224:227], v[232:235], v[18:21]
	v_mfma_f32_16x16x32_bf16 v[22:25], v[224:227], v[236:239], v[22:25]
	v_mfma_f32_16x16x32_bf16 v[2:5], v[224:227], v[240:243], v[2:5]
	v_mfma_f32_16x16x32_bf16 v[6:9], v[224:227], v[252:255], v[6:9]
	s_waitcnt lgkmcnt(4)
	v_mfma_f32_16x16x32_bf16 v[26:29], v[228:231], v[232:235], v[26:29]
	v_mfma_f32_16x16x32_bf16 v[30:33], v[228:231], v[236:239], v[30:33]
	v_mfma_f32_16x16x32_bf16 v[10:13], v[228:231], v[240:243], v[10:13]
	v_mfma_f32_16x16x32_bf16 v[14:17], v[228:231], v[252:255], v[14:17]
	s_waitcnt lgkmcnt(0)
	s_barrier
	global_load_dwordx4 v[180:183], v[72:73], off offset:1024
	global_load_dwordx4 v[188:191], v[74:75], off offset:1024
	global_load_dwordx4 v[192:195], v[76:77], off offset:1024
	global_load_dwordx4 v[196:199], v[78:79], off offset:1024
	global_load_dwordx4 v[200:203], v[70:71], off offset:1024
	global_load_dwordx4 v[204:207], v[68:69], off offset:1024
	global_load_dwordx4 v[208:211], v[66:67], off offset:1024
	global_load_dwordx4 v[212:215], v[80:81], off offset:1024
	ds_read_b128 v[232:235], v245 offset:36864
	ds_read_b128 v[216:219], v244
	ds_read_b128 v[236:239], v245 offset:39168
	ds_read_b128 v[240:243], v245 offset:41472
	ds_read_b128 v[252:255], v245 offset:43776
	ds_read_b128 v[220:223], v244 offset:2304
	ds_read_b128 v[224:227], v244 offset:4608
	ds_read_b128 v[228:231], v244 offset:6912
	s_setprio 0
	s_waitcnt lgkmcnt(6)
	v_mfma_f32_16x16x32_bf16 v[50:53], v[216:219], v[232:235], v[50:53]
	s_waitcnt lgkmcnt(5)
	v_mfma_f32_16x16x32_bf16 v[54:57], v[216:219], v[236:239], v[54:57]
	s_waitcnt lgkmcnt(4)
	v_mfma_f32_16x16x32_bf16 v[34:37], v[216:219], v[240:243], v[34:37]
	s_waitcnt lgkmcnt(3)
	v_mfma_f32_16x16x32_bf16 v[38:41], v[216:219], v[252:255], v[38:41]
	ds_read_b128 v[216:219], v244 offset:64
	s_waitcnt lgkmcnt(3)
	v_mfma_f32_16x16x32_bf16 v[58:61], v[220:223], v[232:235], v[58:61]
	v_mfma_f32_16x16x32_bf16 v[62:65], v[220:223], v[236:239], v[62:65]
	v_mfma_f32_16x16x32_bf16 v[42:45], v[220:223], v[240:243], v[42:45]
	v_mfma_f32_16x16x32_bf16 v[46:49], v[220:223], v[252:255], v[46:49]
	ds_read_b128 v[220:223], v244 offset:2368
	s_setprio 1
	s_waitcnt vmcnt(15)
	ds_write_b128 v164, v[122:125] offset:18432
	s_waitcnt vmcnt(14)
	ds_write_b128 v164, v[126:129] offset:23040
	s_waitcnt lgkmcnt(5)
	v_mfma_f32_16x16x32_bf16 v[18:21], v[224:227], v[232:235], v[18:21]
	v_mfma_f32_16x16x32_bf16 v[22:25], v[224:227], v[236:239], v[22:25]
	v_mfma_f32_16x16x32_bf16 v[2:5], v[224:227], v[240:243], v[2:5]
	v_mfma_f32_16x16x32_bf16 v[6:9], v[224:227], v[252:255], v[6:9]
	ds_read_b128 v[224:227], v244 offset:4672
	s_waitcnt vmcnt(13)
	ds_write_b128 v164, v[136:139] offset:27648
	s_waitcnt vmcnt(12)
	ds_write_b128 v164, v[140:143] offset:32256
	s_waitcnt lgkmcnt(7)
	v_mfma_f32_16x16x32_bf16 v[26:29], v[228:231], v[232:235], v[26:29]
	ds_read_b128 v[232:235], v245 offset:36928
	v_mfma_f32_16x16x32_bf16 v[30:33], v[228:231], v[236:239], v[30:33]
	ds_read_b128 v[236:239], v245 offset:39232
	v_mfma_f32_16x16x32_bf16 v[10:13], v[228:231], v[240:243], v[10:13]
	ds_read_b128 v[240:243], v245 offset:41536
	v_mfma_f32_16x16x32_bf16 v[14:17], v[228:231], v[252:255], v[14:17]
	ds_read_b128 v[252:255], v245 offset:43840
	ds_read_b128 v[228:231], v244 offset:6976
	s_waitcnt lgkmcnt(4)
	v_mfma_f32_16x16x32_bf16 v[50:53], v[216:219], v[232:235], v[50:53]
	s_waitcnt lgkmcnt(3)
	v_mfma_f32_16x16x32_bf16 v[54:57], v[216:219], v[236:239], v[54:57]
	s_waitcnt lgkmcnt(2)
	v_mfma_f32_16x16x32_bf16 v[34:37], v[216:219], v[240:243], v[34:37]
	s_waitcnt lgkmcnt(1)
	v_mfma_f32_16x16x32_bf16 v[38:41], v[216:219], v[252:255], v[38:41]
	s_waitcnt vmcnt(11)
	ds_write_b128 v164, v[144:147] offset:55296
	s_waitcnt vmcnt(10)
	ds_write_b128 v164, v[148:151] offset:59904
	v_mfma_f32_16x16x32_bf16 v[58:61], v[220:223], v[232:235], v[58:61]
	v_mfma_f32_16x16x32_bf16 v[62:65], v[220:223], v[236:239], v[62:65]
	v_mfma_f32_16x16x32_bf16 v[42:45], v[220:223], v[240:243], v[42:45]
	v_mfma_f32_16x16x32_bf16 v[46:49], v[220:223], v[252:255], v[46:49]
	s_waitcnt vmcnt(9)
	ds_write_b128 v164, v[172:175] offset:64512
	s_waitcnt vmcnt(8)
	ds_write_b128 v165, v[176:179] offset:32256
	v_mfma_f32_16x16x32_bf16 v[18:21], v[224:227], v[232:235], v[18:21]
	v_mfma_f32_16x16x32_bf16 v[22:25], v[224:227], v[236:239], v[22:25]
	v_mfma_f32_16x16x32_bf16 v[2:5], v[224:227], v[240:243], v[2:5]
	v_mfma_f32_16x16x32_bf16 v[6:9], v[224:227], v[252:255], v[6:9]
	s_waitcnt lgkmcnt(4)
	v_mfma_f32_16x16x32_bf16 v[26:29], v[228:231], v[232:235], v[26:29]
	v_mfma_f32_16x16x32_bf16 v[30:33], v[228:231], v[236:239], v[30:33]
	v_mfma_f32_16x16x32_bf16 v[10:13], v[228:231], v[240:243], v[10:13]
	v_mfma_f32_16x16x32_bf16 v[14:17], v[228:231], v[252:255], v[14:17]
	s_waitcnt lgkmcnt(0)
	s_barrier
	global_load_dwordx4 v[122:125], v[72:73], off offset:1152
	global_load_dwordx4 v[126:129], v[74:75], off offset:1152
	global_load_dwordx4 v[136:139], v[76:77], off offset:1152
	global_load_dwordx4 v[140:143], v[78:79], off offset:1152
	global_load_dwordx4 v[144:147], v[70:71], off offset:1152
	global_load_dwordx4 v[148:151], v[68:69], off offset:1152
	global_load_dwordx4 v[172:175], v[66:67], off offset:1152
	global_load_dwordx4 v[176:179], v[80:81], off offset:1152
	ds_read_b128 v[232:235], v245 offset:55296
	ds_read_b128 v[216:219], v244 offset:18432
	ds_read_b128 v[236:239], v245 offset:57600
	ds_read_b128 v[240:243], v245 offset:59904
	ds_read_b128 v[252:255], v245 offset:62208
	ds_read_b128 v[220:223], v244 offset:20736
	ds_read_b128 v[224:227], v244 offset:23040
	ds_read_b128 v[228:231], v244 offset:25344
	s_setprio 0
	s_waitcnt lgkmcnt(6)
	v_mfma_f32_16x16x32_bf16 v[50:53], v[216:219], v[232:235], v[50:53]
	s_waitcnt lgkmcnt(5)
	v_mfma_f32_16x16x32_bf16 v[54:57], v[216:219], v[236:239], v[54:57]
	s_waitcnt lgkmcnt(4)
	v_mfma_f32_16x16x32_bf16 v[34:37], v[216:219], v[240:243], v[34:37]
	s_waitcnt lgkmcnt(3)
	v_mfma_f32_16x16x32_bf16 v[38:41], v[216:219], v[252:255], v[38:41]
	ds_read_b128 v[216:219], v244 offset:18496
	s_waitcnt lgkmcnt(3)
	v_mfma_f32_16x16x32_bf16 v[58:61], v[220:223], v[232:235], v[58:61]
	v_mfma_f32_16x16x32_bf16 v[62:65], v[220:223], v[236:239], v[62:65]
	v_mfma_f32_16x16x32_bf16 v[42:45], v[220:223], v[240:243], v[42:45]
	v_mfma_f32_16x16x32_bf16 v[46:49], v[220:223], v[252:255], v[46:49]
	ds_read_b128 v[220:223], v244 offset:20800
	s_setprio 1
	s_waitcnt vmcnt(15)
	ds_write_b128 v164, v[180:183]
	s_waitcnt vmcnt(14)
	ds_write_b128 v164, v[188:191] offset:4608
	s_waitcnt lgkmcnt(5)
	v_mfma_f32_16x16x32_bf16 v[18:21], v[224:227], v[232:235], v[18:21]
	v_mfma_f32_16x16x32_bf16 v[22:25], v[224:227], v[236:239], v[22:25]
	v_mfma_f32_16x16x32_bf16 v[2:5], v[224:227], v[240:243], v[2:5]
	v_mfma_f32_16x16x32_bf16 v[6:9], v[224:227], v[252:255], v[6:9]
	ds_read_b128 v[224:227], v244 offset:23104
	s_waitcnt vmcnt(13)
	ds_write_b128 v164, v[192:195] offset:9216
	s_waitcnt vmcnt(12)
	ds_write_b128 v164, v[196:199] offset:13824
	s_waitcnt lgkmcnt(7)
	v_mfma_f32_16x16x32_bf16 v[26:29], v[228:231], v[232:235], v[26:29]
	ds_read_b128 v[232:235], v245 offset:55360
	v_mfma_f32_16x16x32_bf16 v[30:33], v[228:231], v[236:239], v[30:33]
	ds_read_b128 v[236:239], v245 offset:57664
	v_mfma_f32_16x16x32_bf16 v[10:13], v[228:231], v[240:243], v[10:13]
	ds_read_b128 v[240:243], v245 offset:59968
	v_mfma_f32_16x16x32_bf16 v[14:17], v[228:231], v[252:255], v[14:17]
	ds_read_b128 v[252:255], v245 offset:62272
	ds_read_b128 v[228:231], v244 offset:25408
	s_waitcnt lgkmcnt(4)
	v_mfma_f32_16x16x32_bf16 v[50:53], v[216:219], v[232:235], v[50:53]
	s_waitcnt lgkmcnt(3)
	v_mfma_f32_16x16x32_bf16 v[54:57], v[216:219], v[236:239], v[54:57]
	s_waitcnt lgkmcnt(2)
	v_mfma_f32_16x16x32_bf16 v[34:37], v[216:219], v[240:243], v[34:37]
	s_waitcnt lgkmcnt(1)
	v_mfma_f32_16x16x32_bf16 v[38:41], v[216:219], v[252:255], v[38:41]
	s_waitcnt vmcnt(11)
	ds_write_b128 v164, v[200:203] offset:36864
	s_waitcnt vmcnt(10)
	ds_write_b128 v164, v[204:207] offset:41472
	v_mfma_f32_16x16x32_bf16 v[58:61], v[220:223], v[232:235], v[58:61]
	v_mfma_f32_16x16x32_bf16 v[62:65], v[220:223], v[236:239], v[62:65]
	v_mfma_f32_16x16x32_bf16 v[42:45], v[220:223], v[240:243], v[42:45]
	v_mfma_f32_16x16x32_bf16 v[46:49], v[220:223], v[252:255], v[46:49]
	s_waitcnt vmcnt(9)
	ds_write_b128 v164, v[208:211] offset:46080
	s_waitcnt vmcnt(8)
	ds_write_b128 v164, v[212:215] offset:50688
	v_mfma_f32_16x16x32_bf16 v[18:21], v[224:227], v[232:235], v[18:21]
	v_mfma_f32_16x16x32_bf16 v[22:25], v[224:227], v[236:239], v[22:25]
	v_mfma_f32_16x16x32_bf16 v[2:5], v[224:227], v[240:243], v[2:5]
	v_mfma_f32_16x16x32_bf16 v[6:9], v[224:227], v[252:255], v[6:9]
	s_waitcnt lgkmcnt(4)
	v_mfma_f32_16x16x32_bf16 v[26:29], v[228:231], v[232:235], v[26:29]
	v_mfma_f32_16x16x32_bf16 v[30:33], v[228:231], v[236:239], v[30:33]
	v_mfma_f32_16x16x32_bf16 v[10:13], v[228:231], v[240:243], v[10:13]
	v_mfma_f32_16x16x32_bf16 v[14:17], v[228:231], v[252:255], v[14:17]
	s_waitcnt lgkmcnt(0)
	s_barrier
	global_load_dwordx4 v[180:183], v[72:73], off offset:1280
	global_load_dwordx4 v[188:191], v[74:75], off offset:1280
	global_load_dwordx4 v[192:195], v[76:77], off offset:1280
	global_load_dwordx4 v[196:199], v[78:79], off offset:1280
	global_load_dwordx4 v[200:203], v[70:71], off offset:1280
	global_load_dwordx4 v[204:207], v[68:69], off offset:1280
	global_load_dwordx4 v[208:211], v[66:67], off offset:1280
	global_load_dwordx4 v[212:215], v[80:81], off offset:1280
	ds_read_b128 v[232:235], v245 offset:36864
	ds_read_b128 v[216:219], v244
	ds_read_b128 v[236:239], v245 offset:39168
	ds_read_b128 v[240:243], v245 offset:41472
	ds_read_b128 v[252:255], v245 offset:43776
	ds_read_b128 v[220:223], v244 offset:2304
	ds_read_b128 v[224:227], v244 offset:4608
	ds_read_b128 v[228:231], v244 offset:6912
	s_setprio 0
	s_waitcnt lgkmcnt(6)
	v_mfma_f32_16x16x32_bf16 v[50:53], v[216:219], v[232:235], v[50:53]
	s_waitcnt lgkmcnt(5)
	v_mfma_f32_16x16x32_bf16 v[54:57], v[216:219], v[236:239], v[54:57]
	s_waitcnt lgkmcnt(4)
	v_mfma_f32_16x16x32_bf16 v[34:37], v[216:219], v[240:243], v[34:37]
	s_waitcnt lgkmcnt(3)
	v_mfma_f32_16x16x32_bf16 v[38:41], v[216:219], v[252:255], v[38:41]
	ds_read_b128 v[216:219], v244 offset:64
	s_waitcnt lgkmcnt(3)
	v_mfma_f32_16x16x32_bf16 v[58:61], v[220:223], v[232:235], v[58:61]
	v_mfma_f32_16x16x32_bf16 v[62:65], v[220:223], v[236:239], v[62:65]
	v_mfma_f32_16x16x32_bf16 v[42:45], v[220:223], v[240:243], v[42:45]
	v_mfma_f32_16x16x32_bf16 v[46:49], v[220:223], v[252:255], v[46:49]
	ds_read_b128 v[220:223], v244 offset:2368
	s_setprio 1
	s_waitcnt vmcnt(15)
	ds_write_b128 v164, v[122:125] offset:18432
	s_waitcnt vmcnt(14)
	ds_write_b128 v164, v[126:129] offset:23040
	s_waitcnt lgkmcnt(5)
	v_mfma_f32_16x16x32_bf16 v[18:21], v[224:227], v[232:235], v[18:21]
	v_mfma_f32_16x16x32_bf16 v[22:25], v[224:227], v[236:239], v[22:25]
	v_mfma_f32_16x16x32_bf16 v[2:5], v[224:227], v[240:243], v[2:5]
	v_mfma_f32_16x16x32_bf16 v[6:9], v[224:227], v[252:255], v[6:9]
	ds_read_b128 v[224:227], v244 offset:4672
	s_waitcnt vmcnt(13)
	ds_write_b128 v164, v[136:139] offset:27648
	s_waitcnt vmcnt(12)
	ds_write_b128 v164, v[140:143] offset:32256
	s_waitcnt lgkmcnt(7)
	v_mfma_f32_16x16x32_bf16 v[26:29], v[228:231], v[232:235], v[26:29]
	ds_read_b128 v[232:235], v245 offset:36928
	v_mfma_f32_16x16x32_bf16 v[30:33], v[228:231], v[236:239], v[30:33]
	ds_read_b128 v[236:239], v245 offset:39232
	v_mfma_f32_16x16x32_bf16 v[10:13], v[228:231], v[240:243], v[10:13]
	ds_read_b128 v[240:243], v245 offset:41536
	v_mfma_f32_16x16x32_bf16 v[14:17], v[228:231], v[252:255], v[14:17]
	ds_read_b128 v[252:255], v245 offset:43840
	ds_read_b128 v[228:231], v244 offset:6976
	s_waitcnt lgkmcnt(4)
	v_mfma_f32_16x16x32_bf16 v[50:53], v[216:219], v[232:235], v[50:53]
	s_waitcnt lgkmcnt(3)
	v_mfma_f32_16x16x32_bf16 v[54:57], v[216:219], v[236:239], v[54:57]
	s_waitcnt lgkmcnt(2)
	v_mfma_f32_16x16x32_bf16 v[34:37], v[216:219], v[240:243], v[34:37]
	s_waitcnt lgkmcnt(1)
	v_mfma_f32_16x16x32_bf16 v[38:41], v[216:219], v[252:255], v[38:41]
	s_waitcnt vmcnt(11)
	ds_write_b128 v164, v[144:147] offset:55296
	s_waitcnt vmcnt(10)
	ds_write_b128 v164, v[148:151] offset:59904
	v_mfma_f32_16x16x32_bf16 v[58:61], v[220:223], v[232:235], v[58:61]
	v_mfma_f32_16x16x32_bf16 v[62:65], v[220:223], v[236:239], v[62:65]
	v_mfma_f32_16x16x32_bf16 v[42:45], v[220:223], v[240:243], v[42:45]
	v_mfma_f32_16x16x32_bf16 v[46:49], v[220:223], v[252:255], v[46:49]
	s_waitcnt vmcnt(9)
	ds_write_b128 v164, v[172:175] offset:64512
	s_waitcnt vmcnt(8)
	ds_write_b128 v165, v[176:179] offset:32256
	v_mfma_f32_16x16x32_bf16 v[18:21], v[224:227], v[232:235], v[18:21]
	v_mfma_f32_16x16x32_bf16 v[22:25], v[224:227], v[236:239], v[22:25]
	v_mfma_f32_16x16x32_bf16 v[2:5], v[224:227], v[240:243], v[2:5]
	v_mfma_f32_16x16x32_bf16 v[6:9], v[224:227], v[252:255], v[6:9]
	s_waitcnt lgkmcnt(4)
	v_mfma_f32_16x16x32_bf16 v[26:29], v[228:231], v[232:235], v[26:29]
	v_mfma_f32_16x16x32_bf16 v[30:33], v[228:231], v[236:239], v[30:33]
	v_mfma_f32_16x16x32_bf16 v[10:13], v[228:231], v[240:243], v[10:13]
	v_mfma_f32_16x16x32_bf16 v[14:17], v[228:231], v[252:255], v[14:17]
	s_waitcnt lgkmcnt(0)
	s_barrier
	global_load_dwordx4 v[122:125], v[72:73], off offset:1408
	global_load_dwordx4 v[126:129], v[74:75], off offset:1408
	global_load_dwordx4 v[136:139], v[76:77], off offset:1408
	global_load_dwordx4 v[140:143], v[78:79], off offset:1408
	global_load_dwordx4 v[144:147], v[70:71], off offset:1408
	global_load_dwordx4 v[148:151], v[68:69], off offset:1408
	global_load_dwordx4 v[172:175], v[66:67], off offset:1408
	global_load_dwordx4 v[176:179], v[80:81], off offset:1408
	ds_read_b128 v[232:235], v245 offset:55296
	ds_read_b128 v[216:219], v244 offset:18432
	ds_read_b128 v[236:239], v245 offset:57600
	ds_read_b128 v[240:243], v245 offset:59904
	ds_read_b128 v[252:255], v245 offset:62208
	ds_read_b128 v[220:223], v244 offset:20736
	ds_read_b128 v[224:227], v244 offset:23040
	ds_read_b128 v[228:231], v244 offset:25344
	s_setprio 0
	s_waitcnt lgkmcnt(6)
	v_mfma_f32_16x16x32_bf16 v[50:53], v[216:219], v[232:235], v[50:53]
	s_waitcnt lgkmcnt(5)
	v_mfma_f32_16x16x32_bf16 v[54:57], v[216:219], v[236:239], v[54:57]
	s_waitcnt lgkmcnt(4)
	v_mfma_f32_16x16x32_bf16 v[34:37], v[216:219], v[240:243], v[34:37]
	s_waitcnt lgkmcnt(3)
	v_mfma_f32_16x16x32_bf16 v[38:41], v[216:219], v[252:255], v[38:41]
	ds_read_b128 v[216:219], v244 offset:18496
	s_waitcnt lgkmcnt(3)
	v_mfma_f32_16x16x32_bf16 v[58:61], v[220:223], v[232:235], v[58:61]
	v_mfma_f32_16x16x32_bf16 v[62:65], v[220:223], v[236:239], v[62:65]
	v_mfma_f32_16x16x32_bf16 v[42:45], v[220:223], v[240:243], v[42:45]
	v_mfma_f32_16x16x32_bf16 v[46:49], v[220:223], v[252:255], v[46:49]
	ds_read_b128 v[220:223], v244 offset:20800
	s_setprio 1
	s_waitcnt vmcnt(15)
	ds_write_b128 v164, v[180:183]
	s_waitcnt vmcnt(14)
	ds_write_b128 v164, v[188:191] offset:4608
	s_waitcnt lgkmcnt(5)
	v_mfma_f32_16x16x32_bf16 v[18:21], v[224:227], v[232:235], v[18:21]
	v_mfma_f32_16x16x32_bf16 v[22:25], v[224:227], v[236:239], v[22:25]
	v_mfma_f32_16x16x32_bf16 v[2:5], v[224:227], v[240:243], v[2:5]
	v_mfma_f32_16x16x32_bf16 v[6:9], v[224:227], v[252:255], v[6:9]
	ds_read_b128 v[224:227], v244 offset:23104
	s_waitcnt vmcnt(13)
	ds_write_b128 v164, v[192:195] offset:9216
	s_waitcnt vmcnt(12)
	ds_write_b128 v164, v[196:199] offset:13824
	s_waitcnt lgkmcnt(7)
	v_mfma_f32_16x16x32_bf16 v[26:29], v[228:231], v[232:235], v[26:29]
	ds_read_b128 v[232:235], v245 offset:55360
	v_mfma_f32_16x16x32_bf16 v[30:33], v[228:231], v[236:239], v[30:33]
	ds_read_b128 v[236:239], v245 offset:57664
	v_mfma_f32_16x16x32_bf16 v[10:13], v[228:231], v[240:243], v[10:13]
	ds_read_b128 v[240:243], v245 offset:59968
	v_mfma_f32_16x16x32_bf16 v[14:17], v[228:231], v[252:255], v[14:17]
	ds_read_b128 v[252:255], v245 offset:62272
	ds_read_b128 v[228:231], v244 offset:25408
	s_waitcnt lgkmcnt(4)
	v_mfma_f32_16x16x32_bf16 v[50:53], v[216:219], v[232:235], v[50:53]
	s_waitcnt lgkmcnt(3)
	v_mfma_f32_16x16x32_bf16 v[54:57], v[216:219], v[236:239], v[54:57]
	s_waitcnt lgkmcnt(2)
	v_mfma_f32_16x16x32_bf16 v[34:37], v[216:219], v[240:243], v[34:37]
	s_waitcnt lgkmcnt(1)
	v_mfma_f32_16x16x32_bf16 v[38:41], v[216:219], v[252:255], v[38:41]
	s_waitcnt vmcnt(11)
	ds_write_b128 v164, v[200:203] offset:36864
	s_waitcnt vmcnt(10)
	ds_write_b128 v164, v[204:207] offset:41472
	v_mfma_f32_16x16x32_bf16 v[58:61], v[220:223], v[232:235], v[58:61]
	v_mfma_f32_16x16x32_bf16 v[62:65], v[220:223], v[236:239], v[62:65]
	v_mfma_f32_16x16x32_bf16 v[42:45], v[220:223], v[240:243], v[42:45]
	v_mfma_f32_16x16x32_bf16 v[46:49], v[220:223], v[252:255], v[46:49]
	s_waitcnt vmcnt(9)
	ds_write_b128 v164, v[208:211] offset:46080
	s_waitcnt vmcnt(8)
	ds_write_b128 v164, v[212:215] offset:50688
	v_mfma_f32_16x16x32_bf16 v[18:21], v[224:227], v[232:235], v[18:21]
	v_mfma_f32_16x16x32_bf16 v[22:25], v[224:227], v[236:239], v[22:25]
	v_mfma_f32_16x16x32_bf16 v[2:5], v[224:227], v[240:243], v[2:5]
	v_mfma_f32_16x16x32_bf16 v[6:9], v[224:227], v[252:255], v[6:9]
	s_waitcnt lgkmcnt(4)
	v_mfma_f32_16x16x32_bf16 v[26:29], v[228:231], v[232:235], v[26:29]
	v_mfma_f32_16x16x32_bf16 v[30:33], v[228:231], v[236:239], v[30:33]
	v_mfma_f32_16x16x32_bf16 v[10:13], v[228:231], v[240:243], v[10:13]
	v_mfma_f32_16x16x32_bf16 v[14:17], v[228:231], v[252:255], v[14:17]
	s_waitcnt lgkmcnt(0)
	s_barrier
	global_load_dwordx4 v[180:183], v[72:73], off offset:1536
	global_load_dwordx4 v[188:191], v[74:75], off offset:1536
	global_load_dwordx4 v[192:195], v[76:77], off offset:1536
	global_load_dwordx4 v[196:199], v[78:79], off offset:1536
	global_load_dwordx4 v[200:203], v[70:71], off offset:1536
	global_load_dwordx4 v[204:207], v[68:69], off offset:1536
	global_load_dwordx4 v[208:211], v[66:67], off offset:1536
	global_load_dwordx4 v[212:215], v[80:81], off offset:1536
	ds_read_b128 v[232:235], v245 offset:36864
	ds_read_b128 v[216:219], v244
	ds_read_b128 v[236:239], v245 offset:39168
	ds_read_b128 v[240:243], v245 offset:41472
	ds_read_b128 v[252:255], v245 offset:43776
	ds_read_b128 v[220:223], v244 offset:2304
	ds_read_b128 v[224:227], v244 offset:4608
	ds_read_b128 v[228:231], v244 offset:6912
	s_setprio 0
	s_waitcnt lgkmcnt(6)
	v_mfma_f32_16x16x32_bf16 v[50:53], v[216:219], v[232:235], v[50:53]
	s_waitcnt lgkmcnt(5)
	v_mfma_f32_16x16x32_bf16 v[54:57], v[216:219], v[236:239], v[54:57]
	s_waitcnt lgkmcnt(4)
	v_mfma_f32_16x16x32_bf16 v[34:37], v[216:219], v[240:243], v[34:37]
	s_waitcnt lgkmcnt(3)
	v_mfma_f32_16x16x32_bf16 v[38:41], v[216:219], v[252:255], v[38:41]
	ds_read_b128 v[216:219], v244 offset:64
	s_waitcnt lgkmcnt(3)
	v_mfma_f32_16x16x32_bf16 v[58:61], v[220:223], v[232:235], v[58:61]
	v_mfma_f32_16x16x32_bf16 v[62:65], v[220:223], v[236:239], v[62:65]
	v_mfma_f32_16x16x32_bf16 v[42:45], v[220:223], v[240:243], v[42:45]
	v_mfma_f32_16x16x32_bf16 v[46:49], v[220:223], v[252:255], v[46:49]
	ds_read_b128 v[220:223], v244 offset:2368
	s_setprio 1
	s_waitcnt vmcnt(15)
	ds_write_b128 v164, v[122:125] offset:18432
	s_waitcnt vmcnt(14)
	ds_write_b128 v164, v[126:129] offset:23040
	s_waitcnt lgkmcnt(5)
	v_mfma_f32_16x16x32_bf16 v[18:21], v[224:227], v[232:235], v[18:21]
	v_mfma_f32_16x16x32_bf16 v[22:25], v[224:227], v[236:239], v[22:25]
	v_mfma_f32_16x16x32_bf16 v[2:5], v[224:227], v[240:243], v[2:5]
	v_mfma_f32_16x16x32_bf16 v[6:9], v[224:227], v[252:255], v[6:9]
	ds_read_b128 v[224:227], v244 offset:4672
	s_waitcnt vmcnt(13)
	ds_write_b128 v164, v[136:139] offset:27648
	s_waitcnt vmcnt(12)
	ds_write_b128 v164, v[140:143] offset:32256
	s_waitcnt lgkmcnt(7)
	v_mfma_f32_16x16x32_bf16 v[26:29], v[228:231], v[232:235], v[26:29]
	ds_read_b128 v[232:235], v245 offset:36928
	v_mfma_f32_16x16x32_bf16 v[30:33], v[228:231], v[236:239], v[30:33]
	ds_read_b128 v[236:239], v245 offset:39232
	v_mfma_f32_16x16x32_bf16 v[10:13], v[228:231], v[240:243], v[10:13]
	ds_read_b128 v[240:243], v245 offset:41536
	v_mfma_f32_16x16x32_bf16 v[14:17], v[228:231], v[252:255], v[14:17]
	ds_read_b128 v[252:255], v245 offset:43840
	ds_read_b128 v[228:231], v244 offset:6976
	s_waitcnt lgkmcnt(4)
	v_mfma_f32_16x16x32_bf16 v[50:53], v[216:219], v[232:235], v[50:53]
	s_waitcnt lgkmcnt(3)
	v_mfma_f32_16x16x32_bf16 v[54:57], v[216:219], v[236:239], v[54:57]
	s_waitcnt lgkmcnt(2)
	v_mfma_f32_16x16x32_bf16 v[34:37], v[216:219], v[240:243], v[34:37]
	s_waitcnt lgkmcnt(1)
	v_mfma_f32_16x16x32_bf16 v[38:41], v[216:219], v[252:255], v[38:41]
	s_waitcnt vmcnt(11)
	ds_write_b128 v164, v[144:147] offset:55296
	s_waitcnt vmcnt(10)
	ds_write_b128 v164, v[148:151] offset:59904
	v_mfma_f32_16x16x32_bf16 v[58:61], v[220:223], v[232:235], v[58:61]
	v_mfma_f32_16x16x32_bf16 v[62:65], v[220:223], v[236:239], v[62:65]
	v_mfma_f32_16x16x32_bf16 v[42:45], v[220:223], v[240:243], v[42:45]
	v_mfma_f32_16x16x32_bf16 v[46:49], v[220:223], v[252:255], v[46:49]
	s_waitcnt vmcnt(9)
	ds_write_b128 v164, v[172:175] offset:64512
	s_waitcnt vmcnt(8)
	ds_write_b128 v165, v[176:179] offset:32256
	v_mfma_f32_16x16x32_bf16 v[18:21], v[224:227], v[232:235], v[18:21]
	v_mfma_f32_16x16x32_bf16 v[22:25], v[224:227], v[236:239], v[22:25]
	v_mfma_f32_16x16x32_bf16 v[2:5], v[224:227], v[240:243], v[2:5]
	v_mfma_f32_16x16x32_bf16 v[6:9], v[224:227], v[252:255], v[6:9]
	s_waitcnt lgkmcnt(4)
	v_mfma_f32_16x16x32_bf16 v[26:29], v[228:231], v[232:235], v[26:29]
	v_mfma_f32_16x16x32_bf16 v[30:33], v[228:231], v[236:239], v[30:33]
	v_mfma_f32_16x16x32_bf16 v[10:13], v[228:231], v[240:243], v[10:13]
	v_mfma_f32_16x16x32_bf16 v[14:17], v[228:231], v[252:255], v[14:17]
	s_waitcnt lgkmcnt(0)
	s_barrier
	global_load_dwordx4 v[122:125], v[72:73], off offset:1664
	global_load_dwordx4 v[126:129], v[74:75], off offset:1664
	global_load_dwordx4 v[136:139], v[76:77], off offset:1664
	global_load_dwordx4 v[140:143], v[78:79], off offset:1664
	global_load_dwordx4 v[144:147], v[70:71], off offset:1664
	global_load_dwordx4 v[148:151], v[68:69], off offset:1664
	global_load_dwordx4 v[172:175], v[66:67], off offset:1664
	global_load_dwordx4 v[176:179], v[80:81], off offset:1664
	ds_read_b128 v[232:235], v245 offset:55296
	ds_read_b128 v[216:219], v244 offset:18432
	ds_read_b128 v[236:239], v245 offset:57600
	ds_read_b128 v[240:243], v245 offset:59904
	ds_read_b128 v[252:255], v245 offset:62208
	ds_read_b128 v[220:223], v244 offset:20736
	ds_read_b128 v[224:227], v244 offset:23040
	ds_read_b128 v[228:231], v244 offset:25344
	s_setprio 0
	s_waitcnt lgkmcnt(6)
	v_mfma_f32_16x16x32_bf16 v[50:53], v[216:219], v[232:235], v[50:53]
	s_waitcnt lgkmcnt(5)
	v_mfma_f32_16x16x32_bf16 v[54:57], v[216:219], v[236:239], v[54:57]
	s_waitcnt lgkmcnt(4)
	v_mfma_f32_16x16x32_bf16 v[34:37], v[216:219], v[240:243], v[34:37]
	s_waitcnt lgkmcnt(3)
	v_mfma_f32_16x16x32_bf16 v[38:41], v[216:219], v[252:255], v[38:41]
	ds_read_b128 v[216:219], v244 offset:18496
	s_waitcnt lgkmcnt(3)
	v_mfma_f32_16x16x32_bf16 v[58:61], v[220:223], v[232:235], v[58:61]
	v_mfma_f32_16x16x32_bf16 v[62:65], v[220:223], v[236:239], v[62:65]
	v_mfma_f32_16x16x32_bf16 v[42:45], v[220:223], v[240:243], v[42:45]
	v_mfma_f32_16x16x32_bf16 v[46:49], v[220:223], v[252:255], v[46:49]
	ds_read_b128 v[220:223], v244 offset:20800
	s_setprio 1
	s_waitcnt vmcnt(15)
	ds_write_b128 v164, v[180:183]
	s_waitcnt vmcnt(14)
	ds_write_b128 v164, v[188:191] offset:4608
	s_waitcnt lgkmcnt(5)
	v_mfma_f32_16x16x32_bf16 v[18:21], v[224:227], v[232:235], v[18:21]
	v_mfma_f32_16x16x32_bf16 v[22:25], v[224:227], v[236:239], v[22:25]
	v_mfma_f32_16x16x32_bf16 v[2:5], v[224:227], v[240:243], v[2:5]
	v_mfma_f32_16x16x32_bf16 v[6:9], v[224:227], v[252:255], v[6:9]
	ds_read_b128 v[224:227], v244 offset:23104
	s_waitcnt vmcnt(13)
	ds_write_b128 v164, v[192:195] offset:9216
	s_waitcnt vmcnt(12)
	ds_write_b128 v164, v[196:199] offset:13824
	s_waitcnt lgkmcnt(7)
	v_mfma_f32_16x16x32_bf16 v[26:29], v[228:231], v[232:235], v[26:29]
	ds_read_b128 v[232:235], v245 offset:55360
	v_mfma_f32_16x16x32_bf16 v[30:33], v[228:231], v[236:239], v[30:33]
	ds_read_b128 v[236:239], v245 offset:57664
	v_mfma_f32_16x16x32_bf16 v[10:13], v[228:231], v[240:243], v[10:13]
	ds_read_b128 v[240:243], v245 offset:59968
	v_mfma_f32_16x16x32_bf16 v[14:17], v[228:231], v[252:255], v[14:17]
	ds_read_b128 v[252:255], v245 offset:62272
	ds_read_b128 v[228:231], v244 offset:25408
	s_waitcnt lgkmcnt(4)
	v_mfma_f32_16x16x32_bf16 v[50:53], v[216:219], v[232:235], v[50:53]
	s_waitcnt lgkmcnt(3)
	v_mfma_f32_16x16x32_bf16 v[54:57], v[216:219], v[236:239], v[54:57]
	s_waitcnt lgkmcnt(2)
	v_mfma_f32_16x16x32_bf16 v[34:37], v[216:219], v[240:243], v[34:37]
	s_waitcnt lgkmcnt(1)
	v_mfma_f32_16x16x32_bf16 v[38:41], v[216:219], v[252:255], v[38:41]
	s_waitcnt vmcnt(11)
	ds_write_b128 v164, v[200:203] offset:36864
	s_waitcnt vmcnt(10)
	ds_write_b128 v164, v[204:207] offset:41472
	v_mfma_f32_16x16x32_bf16 v[58:61], v[220:223], v[232:235], v[58:61]
	v_mfma_f32_16x16x32_bf16 v[62:65], v[220:223], v[236:239], v[62:65]
	v_mfma_f32_16x16x32_bf16 v[42:45], v[220:223], v[240:243], v[42:45]
	v_mfma_f32_16x16x32_bf16 v[46:49], v[220:223], v[252:255], v[46:49]
	s_waitcnt vmcnt(9)
	ds_write_b128 v164, v[208:211] offset:46080
	s_waitcnt vmcnt(8)
	ds_write_b128 v164, v[212:215] offset:50688
	v_mfma_f32_16x16x32_bf16 v[18:21], v[224:227], v[232:235], v[18:21]
	v_mfma_f32_16x16x32_bf16 v[22:25], v[224:227], v[236:239], v[22:25]
	v_mfma_f32_16x16x32_bf16 v[2:5], v[224:227], v[240:243], v[2:5]
	v_mfma_f32_16x16x32_bf16 v[6:9], v[224:227], v[252:255], v[6:9]
	s_waitcnt lgkmcnt(4)
	v_mfma_f32_16x16x32_bf16 v[26:29], v[228:231], v[232:235], v[26:29]
	v_mfma_f32_16x16x32_bf16 v[30:33], v[228:231], v[236:239], v[30:33]
	v_mfma_f32_16x16x32_bf16 v[10:13], v[228:231], v[240:243], v[10:13]
	v_mfma_f32_16x16x32_bf16 v[14:17], v[228:231], v[252:255], v[14:17]
	s_waitcnt lgkmcnt(0)
	s_barrier
	global_load_dwordx4 v[180:183], v[72:73], off offset:1792
	global_load_dwordx4 v[188:191], v[74:75], off offset:1792
	global_load_dwordx4 v[192:195], v[76:77], off offset:1792
	global_load_dwordx4 v[196:199], v[78:79], off offset:1792
	global_load_dwordx4 v[200:203], v[70:71], off offset:1792
	global_load_dwordx4 v[204:207], v[68:69], off offset:1792
	global_load_dwordx4 v[208:211], v[66:67], off offset:1792
	global_load_dwordx4 v[212:215], v[80:81], off offset:1792
	ds_read_b128 v[232:235], v245 offset:36864
	ds_read_b128 v[216:219], v244
	ds_read_b128 v[236:239], v245 offset:39168
	ds_read_b128 v[240:243], v245 offset:41472
	ds_read_b128 v[252:255], v245 offset:43776
	ds_read_b128 v[220:223], v244 offset:2304
	ds_read_b128 v[224:227], v244 offset:4608
	ds_read_b128 v[228:231], v244 offset:6912
	s_setprio 0
	s_waitcnt lgkmcnt(6)
	v_mfma_f32_16x16x32_bf16 v[50:53], v[216:219], v[232:235], v[50:53]
	s_waitcnt lgkmcnt(5)
	v_mfma_f32_16x16x32_bf16 v[54:57], v[216:219], v[236:239], v[54:57]
	s_waitcnt lgkmcnt(4)
	v_mfma_f32_16x16x32_bf16 v[34:37], v[216:219], v[240:243], v[34:37]
	s_waitcnt lgkmcnt(3)
	v_mfma_f32_16x16x32_bf16 v[38:41], v[216:219], v[252:255], v[38:41]
	ds_read_b128 v[216:219], v244 offset:64
	s_waitcnt lgkmcnt(3)
	v_mfma_f32_16x16x32_bf16 v[58:61], v[220:223], v[232:235], v[58:61]
	v_mfma_f32_16x16x32_bf16 v[62:65], v[220:223], v[236:239], v[62:65]
	v_mfma_f32_16x16x32_bf16 v[42:45], v[220:223], v[240:243], v[42:45]
	v_mfma_f32_16x16x32_bf16 v[46:49], v[220:223], v[252:255], v[46:49]
	ds_read_b128 v[220:223], v244 offset:2368
	s_setprio 1
	s_waitcnt vmcnt(15)
	ds_write_b128 v164, v[122:125] offset:18432
	s_waitcnt vmcnt(14)
	ds_write_b128 v164, v[126:129] offset:23040
	s_waitcnt lgkmcnt(5)
	v_mfma_f32_16x16x32_bf16 v[18:21], v[224:227], v[232:235], v[18:21]
	v_mfma_f32_16x16x32_bf16 v[22:25], v[224:227], v[236:239], v[22:25]
	v_mfma_f32_16x16x32_bf16 v[2:5], v[224:227], v[240:243], v[2:5]
	v_mfma_f32_16x16x32_bf16 v[6:9], v[224:227], v[252:255], v[6:9]
	ds_read_b128 v[224:227], v244 offset:4672
	s_waitcnt vmcnt(13)
	ds_write_b128 v164, v[136:139] offset:27648
	s_waitcnt vmcnt(12)
	ds_write_b128 v164, v[140:143] offset:32256
	s_waitcnt lgkmcnt(7)
	v_mfma_f32_16x16x32_bf16 v[26:29], v[228:231], v[232:235], v[26:29]
	ds_read_b128 v[232:235], v245 offset:36928
	v_mfma_f32_16x16x32_bf16 v[30:33], v[228:231], v[236:239], v[30:33]
	ds_read_b128 v[236:239], v245 offset:39232
	v_mfma_f32_16x16x32_bf16 v[10:13], v[228:231], v[240:243], v[10:13]
	ds_read_b128 v[240:243], v245 offset:41536
	v_mfma_f32_16x16x32_bf16 v[14:17], v[228:231], v[252:255], v[14:17]
	ds_read_b128 v[252:255], v245 offset:43840
	ds_read_b128 v[228:231], v244 offset:6976
	s_waitcnt lgkmcnt(4)
	v_mfma_f32_16x16x32_bf16 v[50:53], v[216:219], v[232:235], v[50:53]
	s_waitcnt lgkmcnt(3)
	v_mfma_f32_16x16x32_bf16 v[54:57], v[216:219], v[236:239], v[54:57]
	s_waitcnt lgkmcnt(2)
	v_mfma_f32_16x16x32_bf16 v[34:37], v[216:219], v[240:243], v[34:37]
	s_waitcnt lgkmcnt(1)
	v_mfma_f32_16x16x32_bf16 v[38:41], v[216:219], v[252:255], v[38:41]
	s_waitcnt vmcnt(11)
	ds_write_b128 v164, v[144:147] offset:55296
	s_waitcnt vmcnt(10)
	ds_write_b128 v164, v[148:151] offset:59904
	v_mfma_f32_16x16x32_bf16 v[58:61], v[220:223], v[232:235], v[58:61]
	v_mfma_f32_16x16x32_bf16 v[62:65], v[220:223], v[236:239], v[62:65]
	v_mfma_f32_16x16x32_bf16 v[42:45], v[220:223], v[240:243], v[42:45]
	v_mfma_f32_16x16x32_bf16 v[46:49], v[220:223], v[252:255], v[46:49]
	s_waitcnt vmcnt(9)
	ds_write_b128 v164, v[172:175] offset:64512
	s_waitcnt vmcnt(8)
	ds_write_b128 v165, v[176:179] offset:32256
	v_mfma_f32_16x16x32_bf16 v[18:21], v[224:227], v[232:235], v[18:21]
	v_mfma_f32_16x16x32_bf16 v[22:25], v[224:227], v[236:239], v[22:25]
	v_mfma_f32_16x16x32_bf16 v[2:5], v[224:227], v[240:243], v[2:5]
	v_mfma_f32_16x16x32_bf16 v[6:9], v[224:227], v[252:255], v[6:9]
	s_waitcnt lgkmcnt(4)
	v_mfma_f32_16x16x32_bf16 v[26:29], v[228:231], v[232:235], v[26:29]
	v_mfma_f32_16x16x32_bf16 v[30:33], v[228:231], v[236:239], v[30:33]
	v_mfma_f32_16x16x32_bf16 v[10:13], v[228:231], v[240:243], v[10:13]
	v_mfma_f32_16x16x32_bf16 v[14:17], v[228:231], v[252:255], v[14:17]
	s_waitcnt lgkmcnt(0)
	s_barrier
	global_load_dwordx4 v[122:125], v[72:73], off offset:1920
	s_nop 0
	global_load_dwordx4 v[72:75], v[74:75], off offset:1920
	s_nop 0
	global_load_dwordx4 v[126:129], v[76:77], off offset:1920
	s_nop 0
	global_load_dwordx4 v[76:79], v[78:79], off offset:1920
	s_nop 0
	global_load_dwordx4 v[136:139], v[70:71], off offset:1920
	s_nop 0
	global_load_dwordx4 v[68:71], v[68:69], off offset:1920
	s_nop 0
	global_load_dwordx4 v[140:143], v[66:67], off offset:1920
	global_load_dwordx4 v[144:147], v[80:81], off offset:1920
	ds_read_b128 v[232:235], v245 offset:55296
	ds_read_b128 v[216:219], v244 offset:18432
	ds_read_b128 v[236:239], v245 offset:57600
	ds_read_b128 v[240:243], v245 offset:59904
	ds_read_b128 v[252:255], v245 offset:62208
	ds_read_b128 v[220:223], v244 offset:20736
	ds_read_b128 v[224:227], v244 offset:23040
	ds_read_b128 v[228:231], v244 offset:25344
	s_setprio 0
	s_waitcnt lgkmcnt(6)
	v_mfma_f32_16x16x32_bf16 v[50:53], v[216:219], v[232:235], v[50:53]
	s_waitcnt lgkmcnt(5)
	v_mfma_f32_16x16x32_bf16 v[54:57], v[216:219], v[236:239], v[54:57]
	s_waitcnt lgkmcnt(4)
	v_mfma_f32_16x16x32_bf16 v[34:37], v[216:219], v[240:243], v[34:37]
	s_waitcnt lgkmcnt(3)
	v_mfma_f32_16x16x32_bf16 v[38:41], v[216:219], v[252:255], v[38:41]
	ds_read_b128 v[216:219], v244 offset:18496
	s_waitcnt lgkmcnt(3)
	v_mfma_f32_16x16x32_bf16 v[58:61], v[220:223], v[232:235], v[58:61]
	v_mfma_f32_16x16x32_bf16 v[62:65], v[220:223], v[236:239], v[62:65]
	v_mfma_f32_16x16x32_bf16 v[42:45], v[220:223], v[240:243], v[42:45]
	v_mfma_f32_16x16x32_bf16 v[46:49], v[220:223], v[252:255], v[46:49]
	ds_read_b128 v[220:223], v244 offset:20800
	s_setprio 1
	s_waitcnt vmcnt(15)
	ds_write_b128 v164, v[180:183]
	s_waitcnt vmcnt(14)
	ds_write_b128 v164, v[188:191] offset:4608
	s_waitcnt lgkmcnt(5)
	v_mfma_f32_16x16x32_bf16 v[18:21], v[224:227], v[232:235], v[18:21]
	v_mfma_f32_16x16x32_bf16 v[22:25], v[224:227], v[236:239], v[22:25]
	v_mfma_f32_16x16x32_bf16 v[2:5], v[224:227], v[240:243], v[2:5]
	v_mfma_f32_16x16x32_bf16 v[6:9], v[224:227], v[252:255], v[6:9]
	ds_read_b128 v[224:227], v244 offset:23104
	s_waitcnt vmcnt(13)
	ds_write_b128 v164, v[192:195] offset:9216
	s_waitcnt vmcnt(12)
	ds_write_b128 v164, v[196:199] offset:13824
	s_waitcnt lgkmcnt(7)
	v_mfma_f32_16x16x32_bf16 v[26:29], v[228:231], v[232:235], v[26:29]
	ds_read_b128 v[232:235], v245 offset:55360
	v_mfma_f32_16x16x32_bf16 v[30:33], v[228:231], v[236:239], v[30:33]
	ds_read_b128 v[236:239], v245 offset:57664
	v_mfma_f32_16x16x32_bf16 v[10:13], v[228:231], v[240:243], v[10:13]
	ds_read_b128 v[240:243], v245 offset:59968
	v_mfma_f32_16x16x32_bf16 v[14:17], v[228:231], v[252:255], v[14:17]
	ds_read_b128 v[252:255], v245 offset:62272
	ds_read_b128 v[228:231], v244 offset:25408
	s_waitcnt lgkmcnt(4)
	v_mfma_f32_16x16x32_bf16 v[50:53], v[216:219], v[232:235], v[50:53]
	s_waitcnt lgkmcnt(3)
	v_mfma_f32_16x16x32_bf16 v[54:57], v[216:219], v[236:239], v[54:57]
	s_waitcnt lgkmcnt(2)
	v_mfma_f32_16x16x32_bf16 v[34:37], v[216:219], v[240:243], v[34:37]
	s_waitcnt lgkmcnt(1)
	v_mfma_f32_16x16x32_bf16 v[38:41], v[216:219], v[252:255], v[38:41]
	s_waitcnt vmcnt(11)
	ds_write_b128 v164, v[200:203] offset:36864
	s_waitcnt vmcnt(10)
	ds_write_b128 v164, v[204:207] offset:41472
	v_mfma_f32_16x16x32_bf16 v[58:61], v[220:223], v[232:235], v[58:61]
	v_mfma_f32_16x16x32_bf16 v[62:65], v[220:223], v[236:239], v[62:65]
	v_mfma_f32_16x16x32_bf16 v[42:45], v[220:223], v[240:243], v[42:45]
	v_mfma_f32_16x16x32_bf16 v[46:49], v[220:223], v[252:255], v[46:49]
	s_waitcnt vmcnt(9)
	ds_write_b128 v164, v[208:211] offset:46080
	s_waitcnt vmcnt(8)
	ds_write_b128 v164, v[212:215] offset:50688
	v_mfma_f32_16x16x32_bf16 v[18:21], v[224:227], v[232:235], v[18:21]
	v_mfma_f32_16x16x32_bf16 v[22:25], v[224:227], v[236:239], v[22:25]
	v_mfma_f32_16x16x32_bf16 v[2:5], v[224:227], v[240:243], v[2:5]
	v_mfma_f32_16x16x32_bf16 v[6:9], v[224:227], v[252:255], v[6:9]
	s_waitcnt lgkmcnt(4)
	v_mfma_f32_16x16x32_bf16 v[26:29], v[228:231], v[232:235], v[26:29]
	v_mfma_f32_16x16x32_bf16 v[30:33], v[228:231], v[236:239], v[30:33]
	v_mfma_f32_16x16x32_bf16 v[10:13], v[228:231], v[240:243], v[10:13]
	v_mfma_f32_16x16x32_bf16 v[14:17], v[228:231], v[252:255], v[14:17]
	s_waitcnt lgkmcnt(0)
	s_barrier
	ds_read_b128 v[232:235], v245 offset:36864
	ds_read_b128 v[216:219], v244
	ds_read_b128 v[236:239], v245 offset:39168
	ds_read_b128 v[240:243], v245 offset:41472
	ds_read_b128 v[252:255], v245 offset:43776
	ds_read_b128 v[220:223], v244 offset:2304
	ds_read_b128 v[224:227], v244 offset:4608
	ds_read_b128 v[228:231], v244 offset:6912
	s_setprio 0
	s_waitcnt lgkmcnt(6)
	v_mfma_f32_16x16x32_bf16 v[50:53], v[216:219], v[232:235], v[50:53]
	s_waitcnt lgkmcnt(5)
	v_mfma_f32_16x16x32_bf16 v[54:57], v[216:219], v[236:239], v[54:57]
	s_waitcnt lgkmcnt(4)
	v_mfma_f32_16x16x32_bf16 v[34:37], v[216:219], v[240:243], v[34:37]
	s_waitcnt lgkmcnt(3)
	v_mfma_f32_16x16x32_bf16 v[38:41], v[216:219], v[252:255], v[38:41]
	ds_read_b128 v[216:219], v244 offset:64
	s_waitcnt lgkmcnt(3)
	v_mfma_f32_16x16x32_bf16 v[58:61], v[220:223], v[232:235], v[58:61]
	v_mfma_f32_16x16x32_bf16 v[62:65], v[220:223], v[236:239], v[62:65]
	v_mfma_f32_16x16x32_bf16 v[42:45], v[220:223], v[240:243], v[42:45]
	v_mfma_f32_16x16x32_bf16 v[46:49], v[220:223], v[252:255], v[46:49]
	ds_read_b128 v[220:223], v244 offset:2368
	s_setprio 1
	s_waitcnt vmcnt(7)
	ds_write_b128 v164, v[122:125] offset:18432
	s_waitcnt vmcnt(6)
	ds_write_b128 v164, v[72:75] offset:23040
	s_waitcnt lgkmcnt(5)
	v_mfma_f32_16x16x32_bf16 v[18:21], v[224:227], v[232:235], v[18:21]
	v_mfma_f32_16x16x32_bf16 v[22:25], v[224:227], v[236:239], v[22:25]
	v_mfma_f32_16x16x32_bf16 v[2:5], v[224:227], v[240:243], v[2:5]
	v_mfma_f32_16x16x32_bf16 v[6:9], v[224:227], v[252:255], v[6:9]
	ds_read_b128 v[224:227], v244 offset:4672
	s_waitcnt vmcnt(5)
	ds_write_b128 v164, v[126:129] offset:27648
	s_waitcnt vmcnt(4)
	ds_write_b128 v164, v[76:79] offset:32256
	s_waitcnt lgkmcnt(7)
	v_mfma_f32_16x16x32_bf16 v[26:29], v[228:231], v[232:235], v[26:29]
	ds_read_b128 v[232:235], v245 offset:36928
	v_mfma_f32_16x16x32_bf16 v[30:33], v[228:231], v[236:239], v[30:33]
	ds_read_b128 v[236:239], v245 offset:39232
	v_mfma_f32_16x16x32_bf16 v[10:13], v[228:231], v[240:243], v[10:13]
	ds_read_b128 v[240:243], v245 offset:41536
	v_mfma_f32_16x16x32_bf16 v[14:17], v[228:231], v[252:255], v[14:17]
	ds_read_b128 v[252:255], v245 offset:43840
	ds_read_b128 v[228:231], v244 offset:6976
	s_waitcnt lgkmcnt(4)
	v_mfma_f32_16x16x32_bf16 v[50:53], v[216:219], v[232:235], v[50:53]
	s_waitcnt lgkmcnt(3)
	v_mfma_f32_16x16x32_bf16 v[54:57], v[216:219], v[236:239], v[54:57]
	s_waitcnt lgkmcnt(2)
	v_mfma_f32_16x16x32_bf16 v[34:37], v[216:219], v[240:243], v[34:37]
	s_waitcnt lgkmcnt(1)
	v_mfma_f32_16x16x32_bf16 v[38:41], v[216:219], v[252:255], v[38:41]
	s_waitcnt vmcnt(3)
	ds_write_b128 v164, v[136:139] offset:55296
	s_waitcnt vmcnt(2)
	ds_write_b128 v164, v[68:71] offset:59904
	v_mfma_f32_16x16x32_bf16 v[58:61], v[220:223], v[232:235], v[58:61]
	v_mfma_f32_16x16x32_bf16 v[62:65], v[220:223], v[236:239], v[62:65]
	v_mfma_f32_16x16x32_bf16 v[42:45], v[220:223], v[240:243], v[42:45]
	v_mfma_f32_16x16x32_bf16 v[46:49], v[220:223], v[252:255], v[46:49]
	s_waitcnt vmcnt(1)
	ds_write_b128 v164, v[140:143] offset:64512
	s_waitcnt vmcnt(0)
	ds_write_b128 v165, v[144:147] offset:32256
	v_mfma_f32_16x16x32_bf16 v[18:21], v[224:227], v[232:235], v[18:21]
	v_mfma_f32_16x16x32_bf16 v[22:25], v[224:227], v[236:239], v[22:25]
	v_mfma_f32_16x16x32_bf16 v[2:5], v[224:227], v[240:243], v[2:5]
	v_mfma_f32_16x16x32_bf16 v[6:9], v[224:227], v[252:255], v[6:9]
	s_waitcnt lgkmcnt(4)
	v_mfma_f32_16x16x32_bf16 v[26:29], v[228:231], v[232:235], v[26:29]
	v_mfma_f32_16x16x32_bf16 v[30:33], v[228:231], v[236:239], v[30:33]
	v_mfma_f32_16x16x32_bf16 v[10:13], v[228:231], v[240:243], v[10:13]
	v_mfma_f32_16x16x32_bf16 v[14:17], v[228:231], v[252:255], v[14:17]
	s_waitcnt lgkmcnt(0)
	s_barrier
	ds_read_b128 v[232:235], v245 offset:55296
	ds_read_b128 v[216:219], v244 offset:18432
	ds_read_b128 v[236:239], v245 offset:57600
	ds_read_b128 v[240:243], v245 offset:59904
	ds_read_b128 v[252:255], v245 offset:62208
	ds_read_b128 v[220:223], v244 offset:20736
	ds_read_b128 v[224:227], v244 offset:23040
	ds_read_b128 v[228:231], v244 offset:25344
	s_setprio 0
	s_waitcnt lgkmcnt(6)
	v_mfma_f32_16x16x32_bf16 v[50:53], v[216:219], v[232:235], v[50:53]
	s_waitcnt lgkmcnt(5)
	v_mfma_f32_16x16x32_bf16 v[54:57], v[216:219], v[236:239], v[54:57]
	s_waitcnt lgkmcnt(4)
	v_mfma_f32_16x16x32_bf16 v[34:37], v[216:219], v[240:243], v[34:37]
	s_waitcnt lgkmcnt(3)
	v_mfma_f32_16x16x32_bf16 v[38:41], v[216:219], v[252:255], v[38:41]
	ds_read_b128 v[216:219], v244 offset:18496
	s_waitcnt lgkmcnt(3)
	v_mfma_f32_16x16x32_bf16 v[58:61], v[220:223], v[232:235], v[58:61]
	v_mfma_f32_16x16x32_bf16 v[62:65], v[220:223], v[236:239], v[62:65]
	v_mfma_f32_16x16x32_bf16 v[42:45], v[220:223], v[240:243], v[42:45]
	v_mfma_f32_16x16x32_bf16 v[46:49], v[220:223], v[252:255], v[46:49]
	ds_read_b128 v[220:223], v244 offset:20800
	s_waitcnt lgkmcnt(3)
	v_mfma_f32_16x16x32_bf16 v[18:21], v[224:227], v[232:235], v[18:21]
	v_mfma_f32_16x16x32_bf16 v[22:25], v[224:227], v[236:239], v[22:25]
	v_mfma_f32_16x16x32_bf16 v[2:5], v[224:227], v[240:243], v[2:5]
	v_mfma_f32_16x16x32_bf16 v[6:9], v[224:227], v[252:255], v[6:9]
	ds_read_b128 v[224:227], v244 offset:23104
	s_waitcnt lgkmcnt(3)
	v_mfma_f32_16x16x32_bf16 v[26:29], v[228:231], v[232:235], v[26:29]
	ds_read_b128 v[232:235], v245 offset:55360
	v_mfma_f32_16x16x32_bf16 v[30:33], v[228:231], v[236:239], v[30:33]
	ds_read_b128 v[236:239], v245 offset:57664
	v_mfma_f32_16x16x32_bf16 v[10:13], v[228:231], v[240:243], v[10:13]
	ds_read_b128 v[240:243], v245 offset:59968
	v_mfma_f32_16x16x32_bf16 v[14:17], v[228:231], v[252:255], v[14:17]
	ds_read_b128 v[252:255], v245 offset:62272
	ds_read_b128 v[228:231], v244 offset:25408
	s_waitcnt lgkmcnt(4)
	v_mfma_f32_16x16x32_bf16 v[50:53], v[216:219], v[232:235], v[50:53]
	s_waitcnt lgkmcnt(3)
	v_mfma_f32_16x16x32_bf16 v[54:57], v[216:219], v[236:239], v[54:57]
	s_waitcnt lgkmcnt(2)
	v_mfma_f32_16x16x32_bf16 v[34:37], v[216:219], v[240:243], v[34:37]
	s_waitcnt lgkmcnt(1)
	v_mfma_f32_16x16x32_bf16 v[38:41], v[216:219], v[252:255], v[38:41]
	v_mfma_f32_16x16x32_bf16 v[58:61], v[220:223], v[232:235], v[58:61]
	v_mfma_f32_16x16x32_bf16 v[62:65], v[220:223], v[236:239], v[62:65]
	v_mfma_f32_16x16x32_bf16 v[42:45], v[220:223], v[240:243], v[42:45]
	v_mfma_f32_16x16x32_bf16 v[46:49], v[220:223], v[252:255], v[46:49]
	v_mfma_f32_16x16x32_bf16 v[18:21], v[224:227], v[232:235], v[18:21]
	v_mfma_f32_16x16x32_bf16 v[22:25], v[224:227], v[236:239], v[22:25]
	v_mfma_f32_16x16x32_bf16 v[2:5], v[224:227], v[240:243], v[2:5]
	v_mfma_f32_16x16x32_bf16 v[6:9], v[224:227], v[252:255], v[6:9]
	s_waitcnt lgkmcnt(0)
	v_mfma_f32_16x16x32_bf16 v[26:29], v[228:231], v[232:235], v[26:29]
	v_mfma_f32_16x16x32_bf16 v[30:33], v[228:231], v[236:239], v[30:33]
	v_mfma_f32_16x16x32_bf16 v[10:13], v[228:231], v[240:243], v[10:13]
	v_mfma_f32_16x16x32_bf16 v[14:17], v[228:231], v[252:255], v[14:17]
	s_mov_b64 s[2:3], 0
	s_waitcnt lgkmcnt(0)
	s_barrier
	s_nop 7
	v_permlane16_swap_b32_e32 v50, v54
	v_permlane16_swap_b32_e32 v51, v55
	v_permlane16_swap_b32_e32 v52, v56
	v_permlane16_swap_b32_e32 v53, v57
	v_permlane16_swap_b32_e32 v58, v62
	v_permlane16_swap_b32_e32 v59, v63
	v_permlane16_swap_b32_e32 v60, v64
	v_permlane16_swap_b32_e32 v61, v65
	v_permlane16_swap_b32_e32 v34, v38
	v_permlane16_swap_b32_e32 v35, v39
	v_permlane16_swap_b32_e32 v36, v40
	v_permlane16_swap_b32_e32 v37, v41
	v_permlane16_swap_b32_e32 v42, v46
	v_permlane16_swap_b32_e32 v43, v47
	v_permlane16_swap_b32_e32 v44, v48
	v_permlane16_swap_b32_e32 v45, v49
	v_permlane16_swap_b32_e32 v18, v22
	v_permlane16_swap_b32_e32 v19, v23
	v_permlane16_swap_b32_e32 v20, v24
	v_permlane16_swap_b32_e32 v21, v25
	v_permlane16_swap_b32_e32 v26, v30
	v_permlane16_swap_b32_e32 v27, v31
	v_permlane16_swap_b32_e32 v28, v32
	v_permlane16_swap_b32_e32 v29, v33
	v_permlane16_swap_b32_e32 v2, v6
	v_permlane16_swap_b32_e32 v3, v7
	v_permlane16_swap_b32_e32 v4, v8
	v_permlane16_swap_b32_e32 v5, v9
	v_permlane16_swap_b32_e32 v10, v14
	v_permlane16_swap_b32_e32 v11, v15
	v_permlane16_swap_b32_e32 v12, v16
	v_permlane16_swap_b32_e32 v13, v17
	v_permlane32_swap_b32_e32 v50, v54
	v_permlane32_swap_b32_e32 v51, v55
	v_permlane32_swap_b32_e32 v52, v56
	v_permlane32_swap_b32_e32 v53, v57
	v_permlane32_swap_b32_e32 v58, v62
	v_permlane32_swap_b32_e32 v59, v63
	v_permlane32_swap_b32_e32 v60, v64
	v_permlane32_swap_b32_e32 v61, v65
	v_permlane32_swap_b32_e32 v34, v38
	v_permlane32_swap_b32_e32 v35, v39
	v_permlane32_swap_b32_e32 v36, v40
	v_permlane32_swap_b32_e32 v37, v41
	v_permlane32_swap_b32_e32 v42, v46
	v_permlane32_swap_b32_e32 v43, v47
	v_permlane32_swap_b32_e32 v44, v48
	v_permlane32_swap_b32_e32 v45, v49
	v_permlane32_swap_b32_e32 v18, v22
	v_permlane32_swap_b32_e32 v19, v23
	v_permlane32_swap_b32_e32 v20, v24
	v_permlane32_swap_b32_e32 v21, v25
	v_permlane32_swap_b32_e32 v26, v30
	v_permlane32_swap_b32_e32 v27, v31
	v_permlane32_swap_b32_e32 v28, v32
	v_permlane32_swap_b32_e32 v29, v33
	v_permlane32_swap_b32_e32 v2, v6
	v_permlane32_swap_b32_e32 v3, v7
	v_permlane32_swap_b32_e32 v4, v8
	v_permlane32_swap_b32_e32 v5, v9
	v_permlane32_swap_b32_e32 v10, v14
	v_permlane32_swap_b32_e32 v11, v15
	v_permlane32_swap_b32_e32 v12, v16
	v_permlane32_swap_b32_e32 v13, v17

.LBB0_1167:
	v_ashrrev_i32_e32 v3, 31, v2
	v_lshlrev_b64 v[2:3], 11, v[2:3]
	v_ashrrev_i32_e32 v9, 31, v8
	v_lshl_add_u64 v[70:71], v[86:87], 0, v[2:3]
	v_lshlrev_b64 v[2:3], 11, v[8:9]
	v_lshl_add_u64 v[72:73], v[86:87], 0, v[2:3]
	v_or_b32_e32 v2, s56, v154
	v_ashrrev_i32_e32 v3, 31, v2
	v_lshlrev_b64 v[2:3], 11, v[2:3]
	v_lshl_add_u64 v[74:75], v[84:85], 0, v[2:3]
	v_add_u32_e32 v2, s56, v155
	v_ashrrev_i32_e32 v3, 31, v2
	v_lshlrev_b64 v[2:3], 11, v[2:3]
	v_lshl_add_u64 v[76:77], v[84:85], 0, v[2:3]
	v_add_u32_e32 v2, s56, v156
	v_ashrrev_i32_e32 v3, 31, v2
	v_lshlrev_b64 v[2:3], 11, v[2:3]
	v_lshl_add_u64 v[78:79], v[84:85], 0, v[2:3]
	v_add_u32_e32 v2, s56, v157
	v_ashrrev_i32_e32 v7, 31, v6
	v_ashrrev_i32_e32 v5, 31, v4
	v_ashrrev_i32_e32 v3, 31, v2
	v_lshlrev_b64 v[6:7], 11, v[6:7]
	v_lshlrev_b64 v[4:5], 11, v[4:5]
	v_lshlrev_b64 v[2:3], 11, v[2:3]
	v_lshl_add_u64 v[66:67], v[86:87], 0, v[6:7]
	v_lshl_add_u64 v[68:69], v[86:87], 0, v[4:5]
	v_lshl_add_u64 v[80:81], v[84:85], 0, v[2:3]
	global_load_dwordx4 v[2:5], v[70:71], off
	global_load_dwordx4 v[6:9], v[68:69], off
	global_load_dwordx4 v[10:13], v[66:67], off
	global_load_dwordx4 v[14:17], v[72:73], off
	global_load_dwordx4 v[18:21], v[74:75], off
	global_load_dwordx4 v[22:25], v[76:77], off
	global_load_dwordx4 v[26:29], v[78:79], off
	global_load_dwordx4 v[30:33], v[80:81], off
	global_load_dwordx4 v[122:125], v[70:71], off offset:128
	global_load_dwordx4 v[126:129], v[68:69], off offset:128
	global_load_dwordx4 v[136:139], v[66:67], off offset:128
	global_load_dwordx4 v[140:143], v[72:73], off offset:128
	global_load_dwordx4 v[144:147], v[74:75], off offset:128
	global_load_dwordx4 v[148:151], v[76:77], off offset:128
	global_load_dwordx4 v[172:175], v[78:79], off offset:128
	global_load_dwordx4 v[176:179], v[80:81], off offset:128
	s_waitcnt vmcnt(15)
	ds_write_b128 v164, v[2:5]
	s_waitcnt vmcnt(14)
	ds_write_b128 v164, v[6:9] offset:4608
	s_waitcnt vmcnt(13)
	ds_write_b128 v164, v[10:13] offset:9216
	s_waitcnt vmcnt(12)
	ds_write_b128 v164, v[14:17] offset:13824
	s_waitcnt vmcnt(11)
	ds_write_b128 v164, v[18:21] offset:36864
	s_waitcnt vmcnt(10)
	ds_write_b128 v164, v[22:25] offset:41472
	s_waitcnt vmcnt(9)
	ds_write_b128 v164, v[26:29] offset:46080
	s_waitcnt vmcnt(8)
	ds_write_b128 v164, v[30:33] offset:50688
	s_waitcnt lgkmcnt(0)
	s_barrier
	global_load_dwordx4 v[180:183], v[68:69], off offset:256
	global_load_dwordx4 v[188:191], v[66:67], off offset:256
	global_load_dwordx4 v[192:195], v[70:71], off offset:256
	global_load_dwordx4 v[196:199], v[72:73], off offset:256
	global_load_dwordx4 v[200:203], v[74:75], off offset:256
	global_load_dwordx4 v[204:207], v[76:77], off offset:256
	global_load_dwordx4 v[208:211], v[78:79], off offset:256
	global_load_dwordx4 v[212:215], v[80:81], off offset:256
	v_and_b32_e32 v246, 15, v1
	v_add_u32_e32 v246, 4, v246
	v_bfe_u32 v246, v246, 3, 1
	v_bfe_u32 v249, v1, 4, 2
	v_xor_b32_e32 v246, v246, v249
	v_bfe_u32 v249, v1, 5, 1
	v_sub_u32_e32 v246, v246, v249
	v_lshlrev_b32_e32 v246, 4, v246
	v_bfe_u32 v249, v1, 4, 1
	v_mul_u32_u24_e32 v249, 0x900, v249
	v_sub_u32_e32 v246, v246, v249
	v_add_u32_e32 v244, v246, v161
	v_add_u32_e32 v245, v246, v163
	ds_read_b128 v[232:235], v245 offset:36864
	ds_read_b128 v[216:219], v244
	ds_read_b128 v[236:239], v245 offset:39168
	ds_read_b128 v[240:243], v245 offset:41472
	ds_read_b128 v[252:255], v245 offset:43776
	ds_read_b128 v[220:223], v244 offset:2304
	ds_read_b128 v[224:227], v244 offset:4608
	ds_read_b128 v[228:231], v244 offset:6912
	s_waitcnt lgkmcnt(6)
	v_mfma_f32_16x16x32_bf16 v[50:53], v[216:219], v[232:235], 0
	s_waitcnt lgkmcnt(5)
	v_mfma_f32_16x16x32_bf16 v[54:57], v[216:219], v[236:239], 0
	s_waitcnt lgkmcnt(4)
	v_mfma_f32_16x16x32_bf16 v[34:37], v[216:219], v[240:243], 0
	s_waitcnt lgkmcnt(3)
	v_mfma_f32_16x16x32_bf16 v[38:41], v[216:219], v[252:255], 0
	ds_read_b128 v[216:219], v244 offset:64
	s_waitcnt lgkmcnt(3)
	v_mfma_f32_16x16x32_bf16 v[58:61], v[220:223], v[232:235], 0
	v_mfma_f32_16x16x32_bf16 v[62:65], v[220:223], v[236:239], 0
	v_mfma_f32_16x16x32_bf16 v[42:45], v[220:223], v[240:243], 0
	v_mfma_f32_16x16x32_bf16 v[46:49], v[220:223], v[252:255], 0
	ds_read_b128 v[220:223], v244 offset:2368
	s_setprio 1
	s_waitcnt vmcnt(15)
	ds_write_b128 v164, v[122:125] offset:18432
	s_waitcnt vmcnt(14)
	ds_write_b128 v164, v[126:129] offset:23040
	s_waitcnt lgkmcnt(5)
	v_mfma_f32_16x16x32_bf16 v[18:21], v[224:227], v[232:235], 0
	v_mfma_f32_16x16x32_bf16 v[22:25], v[224:227], v[236:239], 0
	v_mfma_f32_16x16x32_bf16 v[2:5], v[224:227], v[240:243], 0
	v_mfma_f32_16x16x32_bf16 v[6:9], v[224:227], v[252:255], 0
	ds_read_b128 v[224:227], v244 offset:4672
	s_waitcnt vmcnt(13)
	ds_write_b128 v164, v[136:139] offset:27648
	s_waitcnt vmcnt(12)
	ds_write_b128 v164, v[140:143] offset:32256
	s_waitcnt lgkmcnt(7)
	v_mfma_f32_16x16x32_bf16 v[26:29], v[228:231], v[232:235], 0
	ds_read_b128 v[232:235], v245 offset:36928
	v_mfma_f32_16x16x32_bf16 v[30:33], v[228:231], v[236:239], 0
	ds_read_b128 v[236:239], v245 offset:39232
	v_mfma_f32_16x16x32_bf16 v[10:13], v[228:231], v[240:243], 0
	ds_read_b128 v[240:243], v245 offset:41536
	v_mfma_f32_16x16x32_bf16 v[14:17], v[228:231], v[252:255], 0
	ds_read_b128 v[252:255], v245 offset:43840
	ds_read_b128 v[228:231], v244 offset:6976
	s_waitcnt lgkmcnt(4)
	v_mfma_f32_16x16x32_bf16 v[50:53], v[216:219], v[232:235], v[50:53]
	s_waitcnt lgkmcnt(3)
	v_mfma_f32_16x16x32_bf16 v[54:57], v[216:219], v[236:239], v[54:57]
	s_waitcnt lgkmcnt(2)
	v_mfma_f32_16x16x32_bf16 v[34:37], v[216:219], v[240:243], v[34:37]
	s_waitcnt lgkmcnt(1)
	v_mfma_f32_16x16x32_bf16 v[38:41], v[216:219], v[252:255], v[38:41]
	s_waitcnt vmcnt(11)
	ds_write_b128 v164, v[144:147] offset:55296
	s_waitcnt vmcnt(10)
	ds_write_b128 v164, v[148:151] offset:59904
	v_mfma_f32_16x16x32_bf16 v[58:61], v[220:223], v[232:235], v[58:61]
	v_mfma_f32_16x16x32_bf16 v[62:65], v[220:223], v[236:239], v[62:65]
	v_mfma_f32_16x16x32_bf16 v[42:45], v[220:223], v[240:243], v[42:45]
	v_mfma_f32_16x16x32_bf16 v[46:49], v[220:223], v[252:255], v[46:49]
	s_waitcnt vmcnt(9)
	ds_write_b128 v164, v[172:175] offset:64512
	s_waitcnt vmcnt(8)
	ds_write_b128 v165, v[176:179] offset:32256
	v_mfma_f32_16x16x32_bf16 v[18:21], v[224:227], v[232:235], v[18:21]
	v_mfma_f32_16x16x32_bf16 v[22:25], v[224:227], v[236:239], v[22:25]
	v_mfma_f32_16x16x32_bf16 v[2:5], v[224:227], v[240:243], v[2:5]
	v_mfma_f32_16x16x32_bf16 v[6:9], v[224:227], v[252:255], v[6:9]
	s_waitcnt lgkmcnt(4)
	v_mfma_f32_16x16x32_bf16 v[26:29], v[228:231], v[232:235], v[26:29]
	v_mfma_f32_16x16x32_bf16 v[30:33], v[228:231], v[236:239], v[30:33]
	v_mfma_f32_16x16x32_bf16 v[10:13], v[228:231], v[240:243], v[10:13]
	v_mfma_f32_16x16x32_bf16 v[14:17], v[228:231], v[252:255], v[14:17]
	s_waitcnt lgkmcnt(0)
	s_barrier
	global_load_dwordx4 v[122:125], v[70:71], off offset:384
	global_load_dwordx4 v[126:129], v[68:69], off offset:384
	global_load_dwordx4 v[136:139], v[66:67], off offset:384
	global_load_dwordx4 v[140:143], v[72:73], off offset:384
	global_load_dwordx4 v[144:147], v[74:75], off offset:384
	global_load_dwordx4 v[148:151], v[76:77], off offset:384
	global_load_dwordx4 v[172:175], v[78:79], off offset:384
	global_load_dwordx4 v[176:179], v[80:81], off offset:384
	ds_read_b128 v[232:235], v245 offset:55296
	ds_read_b128 v[216:219], v244 offset:18432
	ds_read_b128 v[236:239], v245 offset:57600
	ds_read_b128 v[240:243], v245 offset:59904
	ds_read_b128 v[252:255], v245 offset:62208
	ds_read_b128 v[220:223], v244 offset:20736
	ds_read_b128 v[224:227], v244 offset:23040
	ds_read_b128 v[228:231], v244 offset:25344
	s_setprio 0
	s_waitcnt lgkmcnt(6)
	v_mfma_f32_16x16x32_bf16 v[50:53], v[216:219], v[232:235], v[50:53]
	s_waitcnt lgkmcnt(5)
	v_mfma_f32_16x16x32_bf16 v[54:57], v[216:219], v[236:239], v[54:57]
	s_waitcnt lgkmcnt(4)
	v_mfma_f32_16x16x32_bf16 v[34:37], v[216:219], v[240:243], v[34:37]
	s_waitcnt lgkmcnt(3)
	v_mfma_f32_16x16x32_bf16 v[38:41], v[216:219], v[252:255], v[38:41]
	ds_read_b128 v[216:219], v244 offset:18496
	s_waitcnt lgkmcnt(3)
	v_mfma_f32_16x16x32_bf16 v[58:61], v[220:223], v[232:235], v[58:61]
	v_mfma_f32_16x16x32_bf16 v[62:65], v[220:223], v[236:239], v[62:65]
	v_mfma_f32_16x16x32_bf16 v[42:45], v[220:223], v[240:243], v[42:45]
	v_mfma_f32_16x16x32_bf16 v[46:49], v[220:223], v[252:255], v[46:49]
	ds_read_b128 v[220:223], v244 offset:20800
	s_setprio 1
	s_waitcnt vmcnt(13)
	ds_write_b128 v164, v[192:195]
	ds_write_b128 v164, v[180:183] offset:4608
	s_waitcnt lgkmcnt(5)
	v_mfma_f32_16x16x32_bf16 v[18:21], v[224:227], v[232:235], v[18:21]
	v_mfma_f32_16x16x32_bf16 v[22:25], v[224:227], v[236:239], v[22:25]
	v_mfma_f32_16x16x32_bf16 v[2:5], v[224:227], v[240:243], v[2:5]
	v_mfma_f32_16x16x32_bf16 v[6:9], v[224:227], v[252:255], v[6:9]
	ds_read_b128 v[224:227], v244 offset:23104
	ds_write_b128 v164, v[188:191] offset:9216
	s_waitcnt vmcnt(12)
	ds_write_b128 v164, v[196:199] offset:13824
	s_waitcnt lgkmcnt(7)
	v_mfma_f32_16x16x32_bf16 v[26:29], v[228:231], v[232:235], v[26:29]
	ds_read_b128 v[232:235], v245 offset:55360
	v_mfma_f32_16x16x32_bf16 v[30:33], v[228:231], v[236:239], v[30:33]
	ds_read_b128 v[236:239], v245 offset:57664
	v_mfma_f32_16x16x32_bf16 v[10:13], v[228:231], v[240:243], v[10:13]
	ds_read_b128 v[240:243], v245 offset:59968
	v_mfma_f32_16x16x32_bf16 v[14:17], v[228:231], v[252:255], v[14:17]
	ds_read_b128 v[252:255], v245 offset:62272
	ds_read_b128 v[228:231], v244 offset:25408
	s_waitcnt lgkmcnt(4)
	v_mfma_f32_16x16x32_bf16 v[50:53], v[216:219], v[232:235], v[50:53]
	s_waitcnt lgkmcnt(3)
	v_mfma_f32_16x16x32_bf16 v[54:57], v[216:219], v[236:239], v[54:57]
	s_waitcnt lgkmcnt(2)
	v_mfma_f32_16x16x32_bf16 v[34:37], v[216:219], v[240:243], v[34:37]
	s_waitcnt lgkmcnt(1)
	v_mfma_f32_16x16x32_bf16 v[38:41], v[216:219], v[252:255], v[38:41]
	s_waitcnt vmcnt(11)
	ds_write_b128 v164, v[200:203] offset:36864
	s_waitcnt vmcnt(10)
	ds_write_b128 v164, v[204:207] offset:41472
	v_mfma_f32_16x16x32_bf16 v[58:61], v[220:223], v[232:235], v[58:61]
	v_mfma_f32_16x16x32_bf16 v[62:65], v[220:223], v[236:239], v[62:65]
	v_mfma_f32_16x16x32_bf16 v[42:45], v[220:223], v[240:243], v[42:45]
	v_mfma_f32_16x16x32_bf16 v[46:49], v[220:223], v[252:255], v[46:49]
	s_waitcnt vmcnt(9)
	ds_write_b128 v164, v[208:211] offset:46080
	s_waitcnt vmcnt(8)
	ds_write_b128 v164, v[212:215] offset:50688
	v_mfma_f32_16x16x32_bf16 v[18:21], v[224:227], v[232:235], v[18:21]
	v_mfma_f32_16x16x32_bf16 v[22:25], v[224:227], v[236:239], v[22:25]
	v_mfma_f32_16x16x32_bf16 v[2:5], v[224:227], v[240:243], v[2:5]
	v_mfma_f32_16x16x32_bf16 v[6:9], v[224:227], v[252:255], v[6:9]
	s_waitcnt lgkmcnt(4)
	v_mfma_f32_16x16x32_bf16 v[26:29], v[228:231], v[232:235], v[26:29]
	v_mfma_f32_16x16x32_bf16 v[30:33], v[228:231], v[236:239], v[30:33]
	v_mfma_f32_16x16x32_bf16 v[10:13], v[228:231], v[240:243], v[10:13]
	v_mfma_f32_16x16x32_bf16 v[14:17], v[228:231], v[252:255], v[14:17]
	s_waitcnt lgkmcnt(0)
	s_barrier
	global_load_dwordx4 v[180:183], v[70:71], off offset:512
	global_load_dwordx4 v[188:191], v[68:69], off offset:512
	global_load_dwordx4 v[192:195], v[66:67], off offset:512
	global_load_dwordx4 v[196:199], v[72:73], off offset:512
	global_load_dwordx4 v[200:203], v[74:75], off offset:512
	global_load_dwordx4 v[204:207], v[76:77], off offset:512
	global_load_dwordx4 v[208:211], v[78:79], off offset:512
	global_load_dwordx4 v[212:215], v[80:81], off offset:512
	ds_read_b128 v[232:235], v245 offset:36864
	ds_read_b128 v[216:219], v244
	ds_read_b128 v[236:239], v245 offset:39168
	ds_read_b128 v[240:243], v245 offset:41472
	ds_read_b128 v[252:255], v245 offset:43776
	ds_read_b128 v[220:223], v244 offset:2304
	ds_read_b128 v[224:227], v244 offset:4608
	ds_read_b128 v[228:231], v244 offset:6912
	s_setprio 0
	s_waitcnt lgkmcnt(6)
	v_mfma_f32_16x16x32_bf16 v[50:53], v[216:219], v[232:235], v[50:53]
	s_waitcnt lgkmcnt(5)
	v_mfma_f32_16x16x32_bf16 v[54:57], v[216:219], v[236:239], v[54:57]
	s_waitcnt lgkmcnt(4)
	v_mfma_f32_16x16x32_bf16 v[34:37], v[216:219], v[240:243], v[34:37]
	s_waitcnt lgkmcnt(3)
	v_mfma_f32_16x16x32_bf16 v[38:41], v[216:219], v[252:255], v[38:41]
	ds_read_b128 v[216:219], v244 offset:64
	s_waitcnt lgkmcnt(3)
	v_mfma_f32_16x16x32_bf16 v[58:61], v[220:223], v[232:235], v[58:61]
	v_mfma_f32_16x16x32_bf16 v[62:65], v[220:223], v[236:239], v[62:65]
	v_mfma_f32_16x16x32_bf16 v[42:45], v[220:223], v[240:243], v[42:45]
	v_mfma_f32_16x16x32_bf16 v[46:49], v[220:223], v[252:255], v[46:49]
	ds_read_b128 v[220:223], v244 offset:2368
	s_setprio 1
	s_waitcnt vmcnt(15)
	ds_write_b128 v164, v[122:125] offset:18432
	s_waitcnt vmcnt(14)
	ds_write_b128 v164, v[126:129] offset:23040
	s_waitcnt lgkmcnt(5)
	v_mfma_f32_16x16x32_bf16 v[18:21], v[224:227], v[232:235], v[18:21]
	v_mfma_f32_16x16x32_bf16 v[22:25], v[224:227], v[236:239], v[22:25]
	v_mfma_f32_16x16x32_bf16 v[2:5], v[224:227], v[240:243], v[2:5]
	v_mfma_f32_16x16x32_bf16 v[6:9], v[224:227], v[252:255], v[6:9]
	ds_read_b128 v[224:227], v244 offset:4672
	s_waitcnt vmcnt(13)
	ds_write_b128 v164, v[136:139] offset:27648
	s_waitcnt vmcnt(12)
	ds_write_b128 v164, v[140:143] offset:32256
	s_waitcnt lgkmcnt(7)
	v_mfma_f32_16x16x32_bf16 v[26:29], v[228:231], v[232:235], v[26:29]
	ds_read_b128 v[232:235], v245 offset:36928
	v_mfma_f32_16x16x32_bf16 v[30:33], v[228:231], v[236:239], v[30:33]
	ds_read_b128 v[236:239], v245 offset:39232
	v_mfma_f32_16x16x32_bf16 v[10:13], v[228:231], v[240:243], v[10:13]
	ds_read_b128 v[240:243], v245 offset:41536
	v_mfma_f32_16x16x32_bf16 v[14:17], v[228:231], v[252:255], v[14:17]
	ds_read_b128 v[252:255], v245 offset:43840
	ds_read_b128 v[228:231], v244 offset:6976
	s_waitcnt lgkmcnt(4)
	v_mfma_f32_16x16x32_bf16 v[50:53], v[216:219], v[232:235], v[50:53]
	s_waitcnt lgkmcnt(3)
	v_mfma_f32_16x16x32_bf16 v[54:57], v[216:219], v[236:239], v[54:57]
	s_waitcnt lgkmcnt(2)
	v_mfma_f32_16x16x32_bf16 v[34:37], v[216:219], v[240:243], v[34:37]
	s_waitcnt lgkmcnt(1)
	v_mfma_f32_16x16x32_bf16 v[38:41], v[216:219], v[252:255], v[38:41]
	s_waitcnt vmcnt(11)
	ds_write_b128 v164, v[144:147] offset:55296
	s_waitcnt vmcnt(10)
	ds_write_b128 v164, v[148:151] offset:59904
	v_mfma_f32_16x16x32_bf16 v[58:61], v[220:223], v[232:235], v[58:61]
	v_mfma_f32_16x16x32_bf16 v[62:65], v[220:223], v[236:239], v[62:65]
	v_mfma_f32_16x16x32_bf16 v[42:45], v[220:223], v[240:243], v[42:45]
	v_mfma_f32_16x16x32_bf16 v[46:49], v[220:223], v[252:255], v[46:49]
	s_waitcnt vmcnt(9)
	ds_write_b128 v164, v[172:175] offset:64512
	s_waitcnt vmcnt(8)
	ds_write_b128 v165, v[176:179] offset:32256
	v_mfma_f32_16x16x32_bf16 v[18:21], v[224:227], v[232:235], v[18:21]
	v_mfma_f32_16x16x32_bf16 v[22:25], v[224:227], v[236:239], v[22:25]
	v_mfma_f32_16x16x32_bf16 v[2:5], v[224:227], v[240:243], v[2:5]
	v_mfma_f32_16x16x32_bf16 v[6:9], v[224:227], v[252:255], v[6:9]
	s_waitcnt lgkmcnt(4)
	v_mfma_f32_16x16x32_bf16 v[26:29], v[228:231], v[232:235], v[26:29]
	v_mfma_f32_16x16x32_bf16 v[30:33], v[228:231], v[236:239], v[30:33]
	v_mfma_f32_16x16x32_bf16 v[10:13], v[228:231], v[240:243], v[10:13]
	v_mfma_f32_16x16x32_bf16 v[14:17], v[228:231], v[252:255], v[14:17]
	s_waitcnt lgkmcnt(0)
	s_barrier
	global_load_dwordx4 v[122:125], v[70:71], off offset:640
	global_load_dwordx4 v[126:129], v[68:69], off offset:640
	global_load_dwordx4 v[136:139], v[66:67], off offset:640
	global_load_dwordx4 v[140:143], v[72:73], off offset:640
	global_load_dwordx4 v[144:147], v[74:75], off offset:640
	global_load_dwordx4 v[148:151], v[76:77], off offset:640
	global_load_dwordx4 v[172:175], v[78:79], off offset:640
	global_load_dwordx4 v[176:179], v[80:81], off offset:640
	ds_read_b128 v[232:235], v245 offset:55296
	ds_read_b128 v[216:219], v244 offset:18432
	ds_read_b128 v[236:239], v245 offset:57600
	ds_read_b128 v[240:243], v245 offset:59904
	ds_read_b128 v[252:255], v245 offset:62208
	ds_read_b128 v[220:223], v244 offset:20736
	ds_read_b128 v[224:227], v244 offset:23040
	ds_read_b128 v[228:231], v244 offset:25344
	s_setprio 0
	s_waitcnt lgkmcnt(6)
	v_mfma_f32_16x16x32_bf16 v[50:53], v[216:219], v[232:235], v[50:53]
	s_waitcnt lgkmcnt(5)
	v_mfma_f32_16x16x32_bf16 v[54:57], v[216:219], v[236:239], v[54:57]
	s_waitcnt lgkmcnt(4)
	v_mfma_f32_16x16x32_bf16 v[34:37], v[216:219], v[240:243], v[34:37]
	s_waitcnt lgkmcnt(3)
	v_mfma_f32_16x16x32_bf16 v[38:41], v[216:219], v[252:255], v[38:41]
	ds_read_b128 v[216:219], v244 offset:18496
	s_waitcnt lgkmcnt(3)
	v_mfma_f32_16x16x32_bf16 v[58:61], v[220:223], v[232:235], v[58:61]
	v_mfma_f32_16x16x32_bf16 v[62:65], v[220:223], v[236:239], v[62:65]
	v_mfma_f32_16x16x32_bf16 v[42:45], v[220:223], v[240:243], v[42:45]
	v_mfma_f32_16x16x32_bf16 v[46:49], v[220:223], v[252:255], v[46:49]
	ds_read_b128 v[220:223], v244 offset:20800
	s_setprio 1
	s_waitcnt vmcnt(15)
	ds_write_b128 v164, v[180:183]
	s_waitcnt vmcnt(14)
	ds_write_b128 v164, v[188:191] offset:4608
	s_waitcnt lgkmcnt(5)
	v_mfma_f32_16x16x32_bf16 v[18:21], v[224:227], v[232:235], v[18:21]
	v_mfma_f32_16x16x32_bf16 v[22:25], v[224:227], v[236:239], v[22:25]
	v_mfma_f32_16x16x32_bf16 v[2:5], v[224:227], v[240:243], v[2:5]
	v_mfma_f32_16x16x32_bf16 v[6:9], v[224:227], v[252:255], v[6:9]
	ds_read_b128 v[224:227], v244 offset:23104
	s_waitcnt vmcnt(13)
	ds_write_b128 v164, v[192:195] offset:9216
	s_waitcnt vmcnt(12)
	ds_write_b128 v164, v[196:199] offset:13824
	s_waitcnt lgkmcnt(7)
	v_mfma_f32_16x16x32_bf16 v[26:29], v[228:231], v[232:235], v[26:29]
	ds_read_b128 v[232:235], v245 offset:55360
	v_mfma_f32_16x16x32_bf16 v[30:33], v[228:231], v[236:239], v[30:33]
	ds_read_b128 v[236:239], v245 offset:57664
	v_mfma_f32_16x16x32_bf16 v[10:13], v[228:231], v[240:243], v[10:13]
	ds_read_b128 v[240:243], v245 offset:59968
	v_mfma_f32_16x16x32_bf16 v[14:17], v[228:231], v[252:255], v[14:17]
	ds_read_b128 v[252:255], v245 offset:62272
	ds_read_b128 v[228:231], v244 offset:25408
	s_waitcnt lgkmcnt(4)
	v_mfma_f32_16x16x32_bf16 v[50:53], v[216:219], v[232:235], v[50:53]
	s_waitcnt lgkmcnt(3)
	v_mfma_f32_16x16x32_bf16 v[54:57], v[216:219], v[236:239], v[54:57]
	s_waitcnt lgkmcnt(2)
	v_mfma_f32_16x16x32_bf16 v[34:37], v[216:219], v[240:243], v[34:37]
	s_waitcnt lgkmcnt(1)
	v_mfma_f32_16x16x32_bf16 v[38:41], v[216:219], v[252:255], v[38:41]
	s_waitcnt vmcnt(11)
	ds_write_b128 v164, v[200:203] offset:36864
	s_waitcnt vmcnt(10)
	ds_write_b128 v164, v[204:207] offset:41472
	v_mfma_f32_16x16x32_bf16 v[58:61], v[220:223], v[232:235], v[58:61]
	v_mfma_f32_16x16x32_bf16 v[62:65], v[220:223], v[236:239], v[62:65]
	v_mfma_f32_16x16x32_bf16 v[42:45], v[220:223], v[240:243], v[42:45]
	v_mfma_f32_16x16x32_bf16 v[46:49], v[220:223], v[252:255], v[46:49]
	s_waitcnt vmcnt(9)
	ds_write_b128 v164, v[208:211] offset:46080
	s_waitcnt vmcnt(8)
	ds_write_b128 v164, v[212:215] offset:50688
	v_mfma_f32_16x16x32_bf16 v[18:21], v[224:227], v[232:235], v[18:21]
	v_mfma_f32_16x16x32_bf16 v[22:25], v[224:227], v[236:239], v[22:25]
	v_mfma_f32_16x16x32_bf16 v[2:5], v[224:227], v[240:243], v[2:5]
	v_mfma_f32_16x16x32_bf16 v[6:9], v[224:227], v[252:255], v[6:9]
	s_waitcnt lgkmcnt(4)
	v_mfma_f32_16x16x32_bf16 v[26:29], v[228:231], v[232:235], v[26:29]
	v_mfma_f32_16x16x32_bf16 v[30:33], v[228:231], v[236:239], v[30:33]
	v_mfma_f32_16x16x32_bf16 v[10:13], v[228:231], v[240:243], v[10:13]
	v_mfma_f32_16x16x32_bf16 v[14:17], v[228:231], v[252:255], v[14:17]
	s_waitcnt lgkmcnt(0)
	s_barrier
	global_load_dwordx4 v[180:183], v[70:71], off offset:768
	global_load_dwordx4 v[188:191], v[68:69], off offset:768
	global_load_dwordx4 v[192:195], v[66:67], off offset:768
	global_load_dwordx4 v[196:199], v[72:73], off offset:768
	global_load_dwordx4 v[200:203], v[74:75], off offset:768
	global_load_dwordx4 v[204:207], v[76:77], off offset:768
	global_load_dwordx4 v[208:211], v[78:79], off offset:768
	global_load_dwordx4 v[212:215], v[80:81], off offset:768
	ds_read_b128 v[232:235], v245 offset:36864
	ds_read_b128 v[216:219], v244
	ds_read_b128 v[236:239], v245 offset:39168
	ds_read_b128 v[240:243], v245 offset:41472
	ds_read_b128 v[252:255], v245 offset:43776
	ds_read_b128 v[220:223], v244 offset:2304
	ds_read_b128 v[224:227], v244 offset:4608
	ds_read_b128 v[228:231], v244 offset:6912
	s_setprio 0
	s_waitcnt lgkmcnt(6)
	v_mfma_f32_16x16x32_bf16 v[50:53], v[216:219], v[232:235], v[50:53]
	s_waitcnt lgkmcnt(5)
	v_mfma_f32_16x16x32_bf16 v[54:57], v[216:219], v[236:239], v[54:57]
	s_waitcnt lgkmcnt(4)
	v_mfma_f32_16x16x32_bf16 v[34:37], v[216:219], v[240:243], v[34:37]
	s_waitcnt lgkmcnt(3)
	v_mfma_f32_16x16x32_bf16 v[38:41], v[216:219], v[252:255], v[38:41]
	ds_read_b128 v[216:219], v244 offset:64
	s_waitcnt lgkmcnt(3)
	v_mfma_f32_16x16x32_bf16 v[58:61], v[220:223], v[232:235], v[58:61]
	v_mfma_f32_16x16x32_bf16 v[62:65], v[220:223], v[236:239], v[62:65]
	v_mfma_f32_16x16x32_bf16 v[42:45], v[220:223], v[240:243], v[42:45]
	v_mfma_f32_16x16x32_bf16 v[46:49], v[220:223], v[252:255], v[46:49]
	ds_read_b128 v[220:223], v244 offset:2368
	s_setprio 1
	s_waitcnt vmcnt(15)
	ds_write_b128 v164, v[122:125] offset:18432
	s_waitcnt vmcnt(14)
	ds_write_b128 v164, v[126:129] offset:23040
	s_waitcnt lgkmcnt(5)
	v_mfma_f32_16x16x32_bf16 v[18:21], v[224:227], v[232:235], v[18:21]
	v_mfma_f32_16x16x32_bf16 v[22:25], v[224:227], v[236:239], v[22:25]
	v_mfma_f32_16x16x32_bf16 v[2:5], v[224:227], v[240:243], v[2:5]
	v_mfma_f32_16x16x32_bf16 v[6:9], v[224:227], v[252:255], v[6:9]
	ds_read_b128 v[224:227], v244 offset:4672
	s_waitcnt vmcnt(13)
	ds_write_b128 v164, v[136:139] offset:27648
	s_waitcnt vmcnt(12)
	ds_write_b128 v164, v[140:143] offset:32256
	s_waitcnt lgkmcnt(7)
	v_mfma_f32_16x16x32_bf16 v[26:29], v[228:231], v[232:235], v[26:29]
	ds_read_b128 v[232:235], v245 offset:36928
	v_mfma_f32_16x16x32_bf16 v[30:33], v[228:231], v[236:239], v[30:33]
	ds_read_b128 v[236:239], v245 offset:39232
	v_mfma_f32_16x16x32_bf16 v[10:13], v[228:231], v[240:243], v[10:13]
	ds_read_b128 v[240:243], v245 offset:41536
	v_mfma_f32_16x16x32_bf16 v[14:17], v[228:231], v[252:255], v[14:17]
	ds_read_b128 v[252:255], v245 offset:43840
	ds_read_b128 v[228:231], v244 offset:6976
	s_waitcnt lgkmcnt(4)
	v_mfma_f32_16x16x32_bf16 v[50:53], v[216:219], v[232:235], v[50:53]
	s_waitcnt lgkmcnt(3)
	v_mfma_f32_16x16x32_bf16 v[54:57], v[216:219], v[236:239], v[54:57]
	s_waitcnt lgkmcnt(2)
	v_mfma_f32_16x16x32_bf16 v[34:37], v[216:219], v[240:243], v[34:37]
	s_waitcnt lgkmcnt(1)
	v_mfma_f32_16x16x32_bf16 v[38:41], v[216:219], v[252:255], v[38:41]
	s_waitcnt vmcnt(11)
	ds_write_b128 v164, v[144:147] offset:55296
	s_waitcnt vmcnt(10)
	ds_write_b128 v164, v[148:151] offset:59904
	v_mfma_f32_16x16x32_bf16 v[58:61], v[220:223], v[232:235], v[58:61]
	v_mfma_f32_16x16x32_bf16 v[62:65], v[220:223], v[236:239], v[62:65]
	v_mfma_f32_16x16x32_bf16 v[42:45], v[220:223], v[240:243], v[42:45]
	v_mfma_f32_16x16x32_bf16 v[46:49], v[220:223], v[252:255], v[46:49]
	s_waitcnt vmcnt(9)
	ds_write_b128 v164, v[172:175] offset:64512
	s_waitcnt vmcnt(8)
	ds_write_b128 v165, v[176:179] offset:32256
	v_mfma_f32_16x16x32_bf16 v[18:21], v[224:227], v[232:235], v[18:21]
	v_mfma_f32_16x16x32_bf16 v[22:25], v[224:227], v[236:239], v[22:25]
	v_mfma_f32_16x16x32_bf16 v[2:5], v[224:227], v[240:243], v[2:5]
	v_mfma_f32_16x16x32_bf16 v[6:9], v[224:227], v[252:255], v[6:9]
	s_waitcnt lgkmcnt(4)
	v_mfma_f32_16x16x32_bf16 v[26:29], v[228:231], v[232:235], v[26:29]
	v_mfma_f32_16x16x32_bf16 v[30:33], v[228:231], v[236:239], v[30:33]
	v_mfma_f32_16x16x32_bf16 v[10:13], v[228:231], v[240:243], v[10:13]
	v_mfma_f32_16x16x32_bf16 v[14:17], v[228:231], v[252:255], v[14:17]
	s_waitcnt lgkmcnt(0)
	s_barrier
	global_load_dwordx4 v[122:125], v[70:71], off offset:896
	global_load_dwordx4 v[126:129], v[68:69], off offset:896
	global_load_dwordx4 v[136:139], v[66:67], off offset:896
	global_load_dwordx4 v[140:143], v[72:73], off offset:896
	global_load_dwordx4 v[144:147], v[74:75], off offset:896
	global_load_dwordx4 v[148:151], v[76:77], off offset:896
	global_load_dwordx4 v[172:175], v[78:79], off offset:896
	global_load_dwordx4 v[176:179], v[80:81], off offset:896
	ds_read_b128 v[232:235], v245 offset:55296
	ds_read_b128 v[216:219], v244 offset:18432
	ds_read_b128 v[236:239], v245 offset:57600
	ds_read_b128 v[240:243], v245 offset:59904
	ds_read_b128 v[252:255], v245 offset:62208
	ds_read_b128 v[220:223], v244 offset:20736
	ds_read_b128 v[224:227], v244 offset:23040
	ds_read_b128 v[228:231], v244 offset:25344
	s_setprio 0
	s_waitcnt lgkmcnt(6)
	v_mfma_f32_16x16x32_bf16 v[50:53], v[216:219], v[232:235], v[50:53]
	s_waitcnt lgkmcnt(5)
	v_mfma_f32_16x16x32_bf16 v[54:57], v[216:219], v[236:239], v[54:57]
	s_waitcnt lgkmcnt(4)
	v_mfma_f32_16x16x32_bf16 v[34:37], v[216:219], v[240:243], v[34:37]
	s_waitcnt lgkmcnt(3)
	v_mfma_f32_16x16x32_bf16 v[38:41], v[216:219], v[252:255], v[38:41]
	ds_read_b128 v[216:219], v244 offset:18496
	s_waitcnt lgkmcnt(3)
	v_mfma_f32_16x16x32_bf16 v[58:61], v[220:223], v[232:235], v[58:61]
	v_mfma_f32_16x16x32_bf16 v[62:65], v[220:223], v[236:239], v[62:65]
	v_mfma_f32_16x16x32_bf16 v[42:45], v[220:223], v[240:243], v[42:45]
	v_mfma_f32_16x16x32_bf16 v[46:49], v[220:223], v[252:255], v[46:49]
	ds_read_b128 v[220:223], v244 offset:20800
	s_setprio 1
	s_waitcnt vmcnt(15)
	ds_write_b128 v164, v[180:183]
	s_waitcnt vmcnt(14)
	ds_write_b128 v164, v[188:191] offset:4608
	s_waitcnt lgkmcnt(5)
	v_mfma_f32_16x16x32_bf16 v[18:21], v[224:227], v[232:235], v[18:21]
	v_mfma_f32_16x16x32_bf16 v[22:25], v[224:227], v[236:239], v[22:25]
	v_mfma_f32_16x16x32_bf16 v[2:5], v[224:227], v[240:243], v[2:5]
	v_mfma_f32_16x16x32_bf16 v[6:9], v[224:227], v[252:255], v[6:9]
	ds_read_b128 v[224:227], v244 offset:23104
	s_waitcnt vmcnt(13)
	ds_write_b128 v164, v[192:195] offset:9216
	s_waitcnt vmcnt(12)
	ds_write_b128 v164, v[196:199] offset:13824
	s_waitcnt lgkmcnt(7)
	v_mfma_f32_16x16x32_bf16 v[26:29], v[228:231], v[232:235], v[26:29]
	ds_read_b128 v[232:235], v245 offset:55360
	v_mfma_f32_16x16x32_bf16 v[30:33], v[228:231], v[236:239], v[30:33]
	ds_read_b128 v[236:239], v245 offset:57664
	v_mfma_f32_16x16x32_bf16 v[10:13], v[228:231], v[240:243], v[10:13]
	ds_read_b128 v[240:243], v245 offset:59968
	v_mfma_f32_16x16x32_bf16 v[14:17], v[228:231], v[252:255], v[14:17]
	ds_read_b128 v[252:255], v245 offset:62272
	ds_read_b128 v[228:231], v244 offset:25408
	s_waitcnt lgkmcnt(4)
	v_mfma_f32_16x16x32_bf16 v[50:53], v[216:219], v[232:235], v[50:53]
	s_waitcnt lgkmcnt(3)
	v_mfma_f32_16x16x32_bf16 v[54:57], v[216:219], v[236:239], v[54:57]
	s_waitcnt lgkmcnt(2)
	v_mfma_f32_16x16x32_bf16 v[34:37], v[216:219], v[240:243], v[34:37]
	s_waitcnt lgkmcnt(1)
	v_mfma_f32_16x16x32_bf16 v[38:41], v[216:219], v[252:255], v[38:41]
	s_waitcnt vmcnt(11)
	ds_write_b128 v164, v[200:203] offset:36864
	s_waitcnt vmcnt(10)
	ds_write_b128 v164, v[204:207] offset:41472
	v_mfma_f32_16x16x32_bf16 v[58:61], v[220:223], v[232:235], v[58:61]
	v_mfma_f32_16x16x32_bf16 v[62:65], v[220:223], v[236:239], v[62:65]
	v_mfma_f32_16x16x32_bf16 v[42:45], v[220:223], v[240:243], v[42:45]
	v_mfma_f32_16x16x32_bf16 v[46:49], v[220:223], v[252:255], v[46:49]
	s_waitcnt vmcnt(9)
	ds_write_b128 v164, v[208:211] offset:46080
	s_waitcnt vmcnt(8)
	ds_write_b128 v164, v[212:215] offset:50688
	v_mfma_f32_16x16x32_bf16 v[18:21], v[224:227], v[232:235], v[18:21]
	v_mfma_f32_16x16x32_bf16 v[22:25], v[224:227], v[236:239], v[22:25]
	v_mfma_f32_16x16x32_bf16 v[2:5], v[224:227], v[240:243], v[2:5]
	v_mfma_f32_16x16x32_bf16 v[6:9], v[224:227], v[252:255], v[6:9]
	s_waitcnt lgkmcnt(4)
	v_mfma_f32_16x16x32_bf16 v[26:29], v[228:231], v[232:235], v[26:29]
	v_mfma_f32_16x16x32_bf16 v[30:33], v[228:231], v[236:239], v[30:33]
	v_mfma_f32_16x16x32_bf16 v[10:13], v[228:231], v[240:243], v[10:13]
	v_mfma_f32_16x16x32_bf16 v[14:17], v[228:231], v[252:255], v[14:17]
	s_waitcnt lgkmcnt(0)
	s_barrier
	global_load_dwordx4 v[180:183], v[70:71], off offset:1024
	global_load_dwordx4 v[188:191], v[68:69], off offset:1024
	global_load_dwordx4 v[192:195], v[66:67], off offset:1024
	global_load_dwordx4 v[196:199], v[72:73], off offset:1024
	global_load_dwordx4 v[200:203], v[74:75], off offset:1024
	global_load_dwordx4 v[204:207], v[76:77], off offset:1024
	global_load_dwordx4 v[208:211], v[78:79], off offset:1024
	global_load_dwordx4 v[212:215], v[80:81], off offset:1024
	ds_read_b128 v[232:235], v245 offset:36864
	ds_read_b128 v[216:219], v244
	ds_read_b128 v[236:239], v245 offset:39168
	ds_read_b128 v[240:243], v245 offset:41472
	ds_read_b128 v[252:255], v245 offset:43776
	ds_read_b128 v[220:223], v244 offset:2304
	ds_read_b128 v[224:227], v244 offset:4608
	ds_read_b128 v[228:231], v244 offset:6912
	s_setprio 0
	s_waitcnt lgkmcnt(6)
	v_mfma_f32_16x16x32_bf16 v[50:53], v[216:219], v[232:235], v[50:53]
	s_waitcnt lgkmcnt(5)
	v_mfma_f32_16x16x32_bf16 v[54:57], v[216:219], v[236:239], v[54:57]
	s_waitcnt lgkmcnt(4)
	v_mfma_f32_16x16x32_bf16 v[34:37], v[216:219], v[240:243], v[34:37]
	s_waitcnt lgkmcnt(3)
	v_mfma_f32_16x16x32_bf16 v[38:41], v[216:219], v[252:255], v[38:41]
	ds_read_b128 v[216:219], v244 offset:64
	s_waitcnt lgkmcnt(3)
	v_mfma_f32_16x16x32_bf16 v[58:61], v[220:223], v[232:235], v[58:61]
	v_mfma_f32_16x16x32_bf16 v[62:65], v[220:223], v[236:239], v[62:65]
	v_mfma_f32_16x16x32_bf16 v[42:45], v[220:223], v[240:243], v[42:45]
	v_mfma_f32_16x16x32_bf16 v[46:49], v[220:223], v[252:255], v[46:49]
	ds_read_b128 v[220:223], v244 offset:2368
	s_setprio 1
	s_waitcnt vmcnt(15)
	ds_write_b128 v164, v[122:125] offset:18432
	s_waitcnt vmcnt(14)
	ds_write_b128 v164, v[126:129] offset:23040
	s_waitcnt lgkmcnt(5)
	v_mfma_f32_16x16x32_bf16 v[18:21], v[224:227], v[232:235], v[18:21]
	v_mfma_f32_16x16x32_bf16 v[22:25], v[224:227], v[236:239], v[22:25]
	v_mfma_f32_16x16x32_bf16 v[2:5], v[224:227], v[240:243], v[2:5]
	v_mfma_f32_16x16x32_bf16 v[6:9], v[224:227], v[252:255], v[6:9]
	ds_read_b128 v[224:227], v244 offset:4672
	s_waitcnt vmcnt(13)
	ds_write_b128 v164, v[136:139] offset:27648
	s_waitcnt vmcnt(12)
	ds_write_b128 v164, v[140:143] offset:32256
	s_waitcnt lgkmcnt(7)
	v_mfma_f32_16x16x32_bf16 v[26:29], v[228:231], v[232:235], v[26:29]
	ds_read_b128 v[232:235], v245 offset:36928
	v_mfma_f32_16x16x32_bf16 v[30:33], v[228:231], v[236:239], v[30:33]
	ds_read_b128 v[236:239], v245 offset:39232
	v_mfma_f32_16x16x32_bf16 v[10:13], v[228:231], v[240:243], v[10:13]
	ds_read_b128 v[240:243], v245 offset:41536
	v_mfma_f32_16x16x32_bf16 v[14:17], v[228:231], v[252:255], v[14:17]
	ds_read_b128 v[252:255], v245 offset:43840
	ds_read_b128 v[228:231], v244 offset:6976
	s_waitcnt lgkmcnt(4)
	v_mfma_f32_16x16x32_bf16 v[50:53], v[216:219], v[232:235], v[50:53]
	s_waitcnt lgkmcnt(3)
	v_mfma_f32_16x16x32_bf16 v[54:57], v[216:219], v[236:239], v[54:57]
	s_waitcnt lgkmcnt(2)
	v_mfma_f32_16x16x32_bf16 v[34:37], v[216:219], v[240:243], v[34:37]
	s_waitcnt lgkmcnt(1)
	v_mfma_f32_16x16x32_bf16 v[38:41], v[216:219], v[252:255], v[38:41]
	s_waitcnt vmcnt(11)
	ds_write_b128 v164, v[144:147] offset:55296
	s_waitcnt vmcnt(10)
	ds_write_b128 v164, v[148:151] offset:59904
	v_mfma_f32_16x16x32_bf16 v[58:61], v[220:223], v[232:235], v[58:61]
	v_mfma_f32_16x16x32_bf16 v[62:65], v[220:223], v[236:239], v[62:65]
	v_mfma_f32_16x16x32_bf16 v[42:45], v[220:223], v[240:243], v[42:45]
	v_mfma_f32_16x16x32_bf16 v[46:49], v[220:223], v[252:255], v[46:49]
	s_waitcnt vmcnt(9)
	ds_write_b128 v164, v[172:175] offset:64512
	s_waitcnt vmcnt(8)
	ds_write_b128 v165, v[176:179] offset:32256
	v_mfma_f32_16x16x32_bf16 v[18:21], v[224:227], v[232:235], v[18:21]
	v_mfma_f32_16x16x32_bf16 v[22:25], v[224:227], v[236:239], v[22:25]
	v_mfma_f32_16x16x32_bf16 v[2:5], v[224:227], v[240:243], v[2:5]
	v_mfma_f32_16x16x32_bf16 v[6:9], v[224:227], v[252:255], v[6:9]
	s_waitcnt lgkmcnt(4)
	v_mfma_f32_16x16x32_bf16 v[26:29], v[228:231], v[232:235], v[26:29]
	v_mfma_f32_16x16x32_bf16 v[30:33], v[228:231], v[236:239], v[30:33]
	v_mfma_f32_16x16x32_bf16 v[10:13], v[228:231], v[240:243], v[10:13]
	v_mfma_f32_16x16x32_bf16 v[14:17], v[228:231], v[252:255], v[14:17]
	s_waitcnt lgkmcnt(0)
	s_barrier
	global_load_dwordx4 v[122:125], v[70:71], off offset:1152
	global_load_dwordx4 v[126:129], v[68:69], off offset:1152
	global_load_dwordx4 v[136:139], v[66:67], off offset:1152
	global_load_dwordx4 v[140:143], v[72:73], off offset:1152
	global_load_dwordx4 v[144:147], v[74:75], off offset:1152
	global_load_dwordx4 v[148:151], v[76:77], off offset:1152
	global_load_dwordx4 v[172:175], v[78:79], off offset:1152
	global_load_dwordx4 v[176:179], v[80:81], off offset:1152
	ds_read_b128 v[232:235], v245 offset:55296
	ds_read_b128 v[216:219], v244 offset:18432
	ds_read_b128 v[236:239], v245 offset:57600
	ds_read_b128 v[240:243], v245 offset:59904
	ds_read_b128 v[252:255], v245 offset:62208
	ds_read_b128 v[220:223], v244 offset:20736
	ds_read_b128 v[224:227], v244 offset:23040
	ds_read_b128 v[228:231], v244 offset:25344
	s_setprio 0
	s_waitcnt lgkmcnt(6)
	v_mfma_f32_16x16x32_bf16 v[50:53], v[216:219], v[232:235], v[50:53]
	s_waitcnt lgkmcnt(5)
	v_mfma_f32_16x16x32_bf16 v[54:57], v[216:219], v[236:239], v[54:57]
	s_waitcnt lgkmcnt(4)
	v_mfma_f32_16x16x32_bf16 v[34:37], v[216:219], v[240:243], v[34:37]
	s_waitcnt lgkmcnt(3)
	v_mfma_f32_16x16x32_bf16 v[38:41], v[216:219], v[252:255], v[38:41]
	ds_read_b128 v[216:219], v244 offset:18496
	s_waitcnt lgkmcnt(3)
	v_mfma_f32_16x16x32_bf16 v[58:61], v[220:223], v[232:235], v[58:61]
	v_mfma_f32_16x16x32_bf16 v[62:65], v[220:223], v[236:239], v[62:65]
	v_mfma_f32_16x16x32_bf16 v[42:45], v[220:223], v[240:243], v[42:45]
	v_mfma_f32_16x16x32_bf16 v[46:49], v[220:223], v[252:255], v[46:49]
	ds_read_b128 v[220:223], v244 offset:20800
	s_setprio 1
	s_waitcnt vmcnt(15)
	ds_write_b128 v164, v[180:183]
	s_waitcnt vmcnt(14)
	ds_write_b128 v164, v[188:191] offset:4608
	s_waitcnt lgkmcnt(5)
	v_mfma_f32_16x16x32_bf16 v[18:21], v[224:227], v[232:235], v[18:21]
	v_mfma_f32_16x16x32_bf16 v[22:25], v[224:227], v[236:239], v[22:25]
	v_mfma_f32_16x16x32_bf16 v[2:5], v[224:227], v[240:243], v[2:5]
	v_mfma_f32_16x16x32_bf16 v[6:9], v[224:227], v[252:255], v[6:9]
	ds_read_b128 v[224:227], v244 offset:23104
	s_waitcnt vmcnt(13)
	ds_write_b128 v164, v[192:195] offset:9216
	s_waitcnt vmcnt(12)
	ds_write_b128 v164, v[196:199] offset:13824
	s_waitcnt lgkmcnt(7)
	v_mfma_f32_16x16x32_bf16 v[26:29], v[228:231], v[232:235], v[26:29]
	ds_read_b128 v[232:235], v245 offset:55360
	v_mfma_f32_16x16x32_bf16 v[30:33], v[228:231], v[236:239], v[30:33]
	ds_read_b128 v[236:239], v245 offset:57664
	v_mfma_f32_16x16x32_bf16 v[10:13], v[228:231], v[240:243], v[10:13]
	ds_read_b128 v[240:243], v245 offset:59968
	v_mfma_f32_16x16x32_bf16 v[14:17], v[228:231], v[252:255], v[14:17]
	ds_read_b128 v[252:255], v245 offset:62272
	ds_read_b128 v[228:231], v244 offset:25408
	s_waitcnt lgkmcnt(4)
	v_mfma_f32_16x16x32_bf16 v[50:53], v[216:219], v[232:235], v[50:53]
	s_waitcnt lgkmcnt(3)
	v_mfma_f32_16x16x32_bf16 v[54:57], v[216:219], v[236:239], v[54:57]
	s_waitcnt lgkmcnt(2)
	v_mfma_f32_16x16x32_bf16 v[34:37], v[216:219], v[240:243], v[34:37]
	s_waitcnt lgkmcnt(1)
	v_mfma_f32_16x16x32_bf16 v[38:41], v[216:219], v[252:255], v[38:41]
	s_waitcnt vmcnt(11)
	ds_write_b128 v164, v[200:203] offset:36864
	s_waitcnt vmcnt(10)
	ds_write_b128 v164, v[204:207] offset:41472
	v_mfma_f32_16x16x32_bf16 v[58:61], v[220:223], v[232:235], v[58:61]
	v_mfma_f32_16x16x32_bf16 v[62:65], v[220:223], v[236:239], v[62:65]
	v_mfma_f32_16x16x32_bf16 v[42:45], v[220:223], v[240:243], v[42:45]
	v_mfma_f32_16x16x32_bf16 v[46:49], v[220:223], v[252:255], v[46:49]
	s_waitcnt vmcnt(9)
	ds_write_b128 v164, v[208:211] offset:46080
	s_waitcnt vmcnt(8)
	ds_write_b128 v164, v[212:215] offset:50688
	v_mfma_f32_16x16x32_bf16 v[18:21], v[224:227], v[232:235], v[18:21]
	v_mfma_f32_16x16x32_bf16 v[22:25], v[224:227], v[236:239], v[22:25]
	v_mfma_f32_16x16x32_bf16 v[2:5], v[224:227], v[240:243], v[2:5]
	v_mfma_f32_16x16x32_bf16 v[6:9], v[224:227], v[252:255], v[6:9]
	s_waitcnt lgkmcnt(4)
	v_mfma_f32_16x16x32_bf16 v[26:29], v[228:231], v[232:235], v[26:29]
	v_mfma_f32_16x16x32_bf16 v[30:33], v[228:231], v[236:239], v[30:33]
	v_mfma_f32_16x16x32_bf16 v[10:13], v[228:231], v[240:243], v[10:13]
	v_mfma_f32_16x16x32_bf16 v[14:17], v[228:231], v[252:255], v[14:17]
	s_waitcnt lgkmcnt(0)
	s_barrier
	global_load_dwordx4 v[180:183], v[70:71], off offset:1280
	global_load_dwordx4 v[188:191], v[68:69], off offset:1280
	global_load_dwordx4 v[192:195], v[66:67], off offset:1280
	global_load_dwordx4 v[196:199], v[72:73], off offset:1280
	global_load_dwordx4 v[200:203], v[74:75], off offset:1280
	global_load_dwordx4 v[204:207], v[76:77], off offset:1280
	global_load_dwordx4 v[208:211], v[78:79], off offset:1280
	global_load_dwordx4 v[212:215], v[80:81], off offset:1280
	ds_read_b128 v[232:235], v245 offset:36864
	ds_read_b128 v[216:219], v244
	ds_read_b128 v[236:239], v245 offset:39168
	ds_read_b128 v[240:243], v245 offset:41472
	ds_read_b128 v[252:255], v245 offset:43776
	ds_read_b128 v[220:223], v244 offset:2304
	ds_read_b128 v[224:227], v244 offset:4608
	ds_read_b128 v[228:231], v244 offset:6912
	s_setprio 0
	s_waitcnt lgkmcnt(6)
	v_mfma_f32_16x16x32_bf16 v[50:53], v[216:219], v[232:235], v[50:53]
	s_waitcnt lgkmcnt(5)
	v_mfma_f32_16x16x32_bf16 v[54:57], v[216:219], v[236:239], v[54:57]
	s_waitcnt lgkmcnt(4)
	v_mfma_f32_16x16x32_bf16 v[34:37], v[216:219], v[240:243], v[34:37]
	s_waitcnt lgkmcnt(3)
	v_mfma_f32_16x16x32_bf16 v[38:41], v[216:219], v[252:255], v[38:41]
	ds_read_b128 v[216:219], v244 offset:64
	s_waitcnt lgkmcnt(3)
	v_mfma_f32_16x16x32_bf16 v[58:61], v[220:223], v[232:235], v[58:61]
	v_mfma_f32_16x16x32_bf16 v[62:65], v[220:223], v[236:239], v[62:65]
	v_mfma_f32_16x16x32_bf16 v[42:45], v[220:223], v[240:243], v[42:45]
	v_mfma_f32_16x16x32_bf16 v[46:49], v[220:223], v[252:255], v[46:49]
	ds_read_b128 v[220:223], v244 offset:2368
	s_setprio 1
	s_waitcnt vmcnt(15)
	ds_write_b128 v164, v[122:125] offset:18432
	s_waitcnt vmcnt(14)
	ds_write_b128 v164, v[126:129] offset:23040
	s_waitcnt lgkmcnt(5)
	v_mfma_f32_16x16x32_bf16 v[18:21], v[224:227], v[232:235], v[18:21]
	v_mfma_f32_16x16x32_bf16 v[22:25], v[224:227], v[236:239], v[22:25]
	v_mfma_f32_16x16x32_bf16 v[2:5], v[224:227], v[240:243], v[2:5]
	v_mfma_f32_16x16x32_bf16 v[6:9], v[224:227], v[252:255], v[6:9]
	ds_read_b128 v[224:227], v244 offset:4672
	s_waitcnt vmcnt(13)
	ds_write_b128 v164, v[136:139] offset:27648
	s_waitcnt vmcnt(12)
	ds_write_b128 v164, v[140:143] offset:32256
	s_waitcnt lgkmcnt(7)
	v_mfma_f32_16x16x32_bf16 v[26:29], v[228:231], v[232:235], v[26:29]
	ds_read_b128 v[232:235], v245 offset:36928
	v_mfma_f32_16x16x32_bf16 v[30:33], v[228:231], v[236:239], v[30:33]
	ds_read_b128 v[236:239], v245 offset:39232
	v_mfma_f32_16x16x32_bf16 v[10:13], v[228:231], v[240:243], v[10:13]
	ds_read_b128 v[240:243], v245 offset:41536
	v_mfma_f32_16x16x32_bf16 v[14:17], v[228:231], v[252:255], v[14:17]
	ds_read_b128 v[252:255], v245 offset:43840
	ds_read_b128 v[228:231], v244 offset:6976
	s_waitcnt lgkmcnt(4)
	v_mfma_f32_16x16x32_bf16 v[50:53], v[216:219], v[232:235], v[50:53]
	s_waitcnt lgkmcnt(3)
	v_mfma_f32_16x16x32_bf16 v[54:57], v[216:219], v[236:239], v[54:57]
	s_waitcnt lgkmcnt(2)
	v_mfma_f32_16x16x32_bf16 v[34:37], v[216:219], v[240:243], v[34:37]
	s_waitcnt lgkmcnt(1)
	v_mfma_f32_16x16x32_bf16 v[38:41], v[216:219], v[252:255], v[38:41]
	s_waitcnt vmcnt(11)
	ds_write_b128 v164, v[144:147] offset:55296
	s_waitcnt vmcnt(10)
	ds_write_b128 v164, v[148:151] offset:59904
	v_mfma_f32_16x16x32_bf16 v[58:61], v[220:223], v[232:235], v[58:61]
	v_mfma_f32_16x16x32_bf16 v[62:65], v[220:223], v[236:239], v[62:65]
	v_mfma_f32_16x16x32_bf16 v[42:45], v[220:223], v[240:243], v[42:45]
	v_mfma_f32_16x16x32_bf16 v[46:49], v[220:223], v[252:255], v[46:49]
	s_waitcnt vmcnt(9)
	ds_write_b128 v164, v[172:175] offset:64512
	s_waitcnt vmcnt(8)
	ds_write_b128 v165, v[176:179] offset:32256
	v_mfma_f32_16x16x32_bf16 v[18:21], v[224:227], v[232:235], v[18:21]
	v_mfma_f32_16x16x32_bf16 v[22:25], v[224:227], v[236:239], v[22:25]
	v_mfma_f32_16x16x32_bf16 v[2:5], v[224:227], v[240:243], v[2:5]
	v_mfma_f32_16x16x32_bf16 v[6:9], v[224:227], v[252:255], v[6:9]
	s_waitcnt lgkmcnt(4)
	v_mfma_f32_16x16x32_bf16 v[26:29], v[228:231], v[232:235], v[26:29]
	v_mfma_f32_16x16x32_bf16 v[30:33], v[228:231], v[236:239], v[30:33]
	v_mfma_f32_16x16x32_bf16 v[10:13], v[228:231], v[240:243], v[10:13]
	v_mfma_f32_16x16x32_bf16 v[14:17], v[228:231], v[252:255], v[14:17]
	s_waitcnt lgkmcnt(0)
	s_barrier
	global_load_dwordx4 v[122:125], v[70:71], off offset:1408
	global_load_dwordx4 v[126:129], v[68:69], off offset:1408
	global_load_dwordx4 v[136:139], v[66:67], off offset:1408
	global_load_dwordx4 v[140:143], v[72:73], off offset:1408
	global_load_dwordx4 v[144:147], v[74:75], off offset:1408
	global_load_dwordx4 v[148:151], v[76:77], off offset:1408
	global_load_dwordx4 v[172:175], v[78:79], off offset:1408
	global_load_dwordx4 v[176:179], v[80:81], off offset:1408
	ds_read_b128 v[232:235], v245 offset:55296
	ds_read_b128 v[216:219], v244 offset:18432
	ds_read_b128 v[236:239], v245 offset:57600
	ds_read_b128 v[240:243], v245 offset:59904
	ds_read_b128 v[252:255], v245 offset:62208
	ds_read_b128 v[220:223], v244 offset:20736
	ds_read_b128 v[224:227], v244 offset:23040
	ds_read_b128 v[228:231], v244 offset:25344
	s_setprio 0
	s_waitcnt lgkmcnt(6)
	v_mfma_f32_16x16x32_bf16 v[50:53], v[216:219], v[232:235], v[50:53]
	s_waitcnt lgkmcnt(5)
	v_mfma_f32_16x16x32_bf16 v[54:57], v[216:219], v[236:239], v[54:57]
	s_waitcnt lgkmcnt(4)
	v_mfma_f32_16x16x32_bf16 v[34:37], v[216:219], v[240:243], v[34:37]
	s_waitcnt lgkmcnt(3)
	v_mfma_f32_16x16x32_bf16 v[38:41], v[216:219], v[252:255], v[38:41]
	ds_read_b128 v[216:219], v244 offset:18496
	s_waitcnt lgkmcnt(3)
	v_mfma_f32_16x16x32_bf16 v[58:61], v[220:223], v[232:235], v[58:61]
	v_mfma_f32_16x16x32_bf16 v[62:65], v[220:223], v[236:239], v[62:65]
	v_mfma_f32_16x16x32_bf16 v[42:45], v[220:223], v[240:243], v[42:45]
	v_mfma_f32_16x16x32_bf16 v[46:49], v[220:223], v[252:255], v[46:49]
	ds_read_b128 v[220:223], v244 offset:20800
	s_setprio 1
	s_waitcnt vmcnt(15)
	ds_write_b128 v164, v[180:183]
	s_waitcnt vmcnt(14)
	ds_write_b128 v164, v[188:191] offset:4608
	s_waitcnt lgkmcnt(5)
	v_mfma_f32_16x16x32_bf16 v[18:21], v[224:227], v[232:235], v[18:21]
	v_mfma_f32_16x16x32_bf16 v[22:25], v[224:227], v[236:239], v[22:25]
	v_mfma_f32_16x16x32_bf16 v[2:5], v[224:227], v[240:243], v[2:5]
	v_mfma_f32_16x16x32_bf16 v[6:9], v[224:227], v[252:255], v[6:9]
	ds_read_b128 v[224:227], v244 offset:23104
	s_waitcnt vmcnt(13)
	ds_write_b128 v164, v[192:195] offset:9216
	s_waitcnt vmcnt(12)
	ds_write_b128 v164, v[196:199] offset:13824
	s_waitcnt lgkmcnt(7)
	v_mfma_f32_16x16x32_bf16 v[26:29], v[228:231], v[232:235], v[26:29]
	ds_read_b128 v[232:235], v245 offset:55360
	v_mfma_f32_16x16x32_bf16 v[30:33], v[228:231], v[236:239], v[30:33]
	ds_read_b128 v[236:239], v245 offset:57664
	v_mfma_f32_16x16x32_bf16 v[10:13], v[228:231], v[240:243], v[10:13]
	ds_read_b128 v[240:243], v245 offset:59968
	v_mfma_f32_16x16x32_bf16 v[14:17], v[228:231], v[252:255], v[14:17]
	ds_read_b128 v[252:255], v245 offset:62272
	ds_read_b128 v[228:231], v244 offset:25408
	s_waitcnt lgkmcnt(4)
	v_mfma_f32_16x16x32_bf16 v[50:53], v[216:219], v[232:235], v[50:53]
	s_waitcnt lgkmcnt(3)
	v_mfma_f32_16x16x32_bf16 v[54:57], v[216:219], v[236:239], v[54:57]
	s_waitcnt lgkmcnt(2)
	v_mfma_f32_16x16x32_bf16 v[34:37], v[216:219], v[240:243], v[34:37]
	s_waitcnt lgkmcnt(1)
	v_mfma_f32_16x16x32_bf16 v[38:41], v[216:219], v[252:255], v[38:41]
	s_waitcnt vmcnt(11)
	ds_write_b128 v164, v[200:203] offset:36864
	s_waitcnt vmcnt(10)
	ds_write_b128 v164, v[204:207] offset:41472
	v_mfma_f32_16x16x32_bf16 v[58:61], v[220:223], v[232:235], v[58:61]
	v_mfma_f32_16x16x32_bf16 v[62:65], v[220:223], v[236:239], v[62:65]
	v_mfma_f32_16x16x32_bf16 v[42:45], v[220:223], v[240:243], v[42:45]
	v_mfma_f32_16x16x32_bf16 v[46:49], v[220:223], v[252:255], v[46:49]
	s_waitcnt vmcnt(9)
	ds_write_b128 v164, v[208:211] offset:46080
	s_waitcnt vmcnt(8)
	ds_write_b128 v164, v[212:215] offset:50688
	v_mfma_f32_16x16x32_bf16 v[18:21], v[224:227], v[232:235], v[18:21]
	v_mfma_f32_16x16x32_bf16 v[22:25], v[224:227], v[236:239], v[22:25]
	v_mfma_f32_16x16x32_bf16 v[2:5], v[224:227], v[240:243], v[2:5]
	v_mfma_f32_16x16x32_bf16 v[6:9], v[224:227], v[252:255], v[6:9]
	s_waitcnt lgkmcnt(4)
	v_mfma_f32_16x16x32_bf16 v[26:29], v[228:231], v[232:235], v[26:29]
	v_mfma_f32_16x16x32_bf16 v[30:33], v[228:231], v[236:239], v[30:33]
	v_mfma_f32_16x16x32_bf16 v[10:13], v[228:231], v[240:243], v[10:13]
	v_mfma_f32_16x16x32_bf16 v[14:17], v[228:231], v[252:255], v[14:17]
	s_waitcnt lgkmcnt(0)
	s_barrier
	global_load_dwordx4 v[180:183], v[70:71], off offset:1536
	global_load_dwordx4 v[188:191], v[68:69], off offset:1536
	global_load_dwordx4 v[192:195], v[66:67], off offset:1536
	global_load_dwordx4 v[196:199], v[72:73], off offset:1536
	global_load_dwordx4 v[200:203], v[74:75], off offset:1536
	global_load_dwordx4 v[204:207], v[76:77], off offset:1536
	global_load_dwordx4 v[208:211], v[78:79], off offset:1536
	global_load_dwordx4 v[212:215], v[80:81], off offset:1536
	ds_read_b128 v[232:235], v245 offset:36864
	ds_read_b128 v[216:219], v244
	ds_read_b128 v[236:239], v245 offset:39168
	ds_read_b128 v[240:243], v245 offset:41472
	ds_read_b128 v[252:255], v245 offset:43776
	ds_read_b128 v[220:223], v244 offset:2304
	ds_read_b128 v[224:227], v244 offset:4608
	ds_read_b128 v[228:231], v244 offset:6912
	s_setprio 0
	s_waitcnt lgkmcnt(6)
	v_mfma_f32_16x16x32_bf16 v[50:53], v[216:219], v[232:235], v[50:53]
	s_waitcnt lgkmcnt(5)
	v_mfma_f32_16x16x32_bf16 v[54:57], v[216:219], v[236:239], v[54:57]
	s_waitcnt lgkmcnt(4)
	v_mfma_f32_16x16x32_bf16 v[34:37], v[216:219], v[240:243], v[34:37]
	s_waitcnt lgkmcnt(3)
	v_mfma_f32_16x16x32_bf16 v[38:41], v[216:219], v[252:255], v[38:41]
	ds_read_b128 v[216:219], v244 offset:64
	s_waitcnt lgkmcnt(3)
	v_mfma_f32_16x16x32_bf16 v[58:61], v[220:223], v[232:235], v[58:61]
	v_mfma_f32_16x16x32_bf16 v[62:65], v[220:223], v[236:239], v[62:65]
	v_mfma_f32_16x16x32_bf16 v[42:45], v[220:223], v[240:243], v[42:45]
	v_mfma_f32_16x16x32_bf16 v[46:49], v[220:223], v[252:255], v[46:49]
	ds_read_b128 v[220:223], v244 offset:2368
	s_setprio 1
	s_waitcnt vmcnt(15)
	ds_write_b128 v164, v[122:125] offset:18432
	s_waitcnt vmcnt(14)
	ds_write_b128 v164, v[126:129] offset:23040
	s_waitcnt lgkmcnt(5)
	v_mfma_f32_16x16x32_bf16 v[18:21], v[224:227], v[232:235], v[18:21]
	v_mfma_f32_16x16x32_bf16 v[22:25], v[224:227], v[236:239], v[22:25]
	v_mfma_f32_16x16x32_bf16 v[2:5], v[224:227], v[240:243], v[2:5]
	v_mfma_f32_16x16x32_bf16 v[6:9], v[224:227], v[252:255], v[6:9]
	ds_read_b128 v[224:227], v244 offset:4672
	s_waitcnt vmcnt(13)
	ds_write_b128 v164, v[136:139] offset:27648
	s_waitcnt vmcnt(12)
	ds_write_b128 v164, v[140:143] offset:32256
	s_waitcnt lgkmcnt(7)
	v_mfma_f32_16x16x32_bf16 v[26:29], v[228:231], v[232:235], v[26:29]
	ds_read_b128 v[232:235], v245 offset:36928
	v_mfma_f32_16x16x32_bf16 v[30:33], v[228:231], v[236:239], v[30:33]
	ds_read_b128 v[236:239], v245 offset:39232
	v_mfma_f32_16x16x32_bf16 v[10:13], v[228:231], v[240:243], v[10:13]
	ds_read_b128 v[240:243], v245 offset:41536
	v_mfma_f32_16x16x32_bf16 v[14:17], v[228:231], v[252:255], v[14:17]
	ds_read_b128 v[252:255], v245 offset:43840
	ds_read_b128 v[228:231], v244 offset:6976
	s_waitcnt lgkmcnt(4)
	v_mfma_f32_16x16x32_bf16 v[50:53], v[216:219], v[232:235], v[50:53]
	s_waitcnt lgkmcnt(3)
	v_mfma_f32_16x16x32_bf16 v[54:57], v[216:219], v[236:239], v[54:57]
	s_waitcnt lgkmcnt(2)
	v_mfma_f32_16x16x32_bf16 v[34:37], v[216:219], v[240:243], v[34:37]
	s_waitcnt lgkmcnt(1)
	v_mfma_f32_16x16x32_bf16 v[38:41], v[216:219], v[252:255], v[38:41]
	s_waitcnt vmcnt(11)
	ds_write_b128 v164, v[144:147] offset:55296
	s_waitcnt vmcnt(10)
	ds_write_b128 v164, v[148:151] offset:59904
	v_mfma_f32_16x16x32_bf16 v[58:61], v[220:223], v[232:235], v[58:61]
	v_mfma_f32_16x16x32_bf16 v[62:65], v[220:223], v[236:239], v[62:65]
	v_mfma_f32_16x16x32_bf16 v[42:45], v[220:223], v[240:243], v[42:45]
	v_mfma_f32_16x16x32_bf16 v[46:49], v[220:223], v[252:255], v[46:49]
	s_waitcnt vmcnt(9)
	ds_write_b128 v164, v[172:175] offset:64512
	s_waitcnt vmcnt(8)
	ds_write_b128 v165, v[176:179] offset:32256
	v_mfma_f32_16x16x32_bf16 v[18:21], v[224:227], v[232:235], v[18:21]
	v_mfma_f32_16x16x32_bf16 v[22:25], v[224:227], v[236:239], v[22:25]
	v_mfma_f32_16x16x32_bf16 v[2:5], v[224:227], v[240:243], v[2:5]
	v_mfma_f32_16x16x32_bf16 v[6:9], v[224:227], v[252:255], v[6:9]
	s_waitcnt lgkmcnt(4)
	v_mfma_f32_16x16x32_bf16 v[26:29], v[228:231], v[232:235], v[26:29]
	v_mfma_f32_16x16x32_bf16 v[30:33], v[228:231], v[236:239], v[30:33]
	v_mfma_f32_16x16x32_bf16 v[10:13], v[228:231], v[240:243], v[10:13]
	v_mfma_f32_16x16x32_bf16 v[14:17], v[228:231], v[252:255], v[14:17]
	s_waitcnt lgkmcnt(0)
	s_barrier
	global_load_dwordx4 v[122:125], v[70:71], off offset:1664
	global_load_dwordx4 v[126:129], v[68:69], off offset:1664
	global_load_dwordx4 v[136:139], v[66:67], off offset:1664
	global_load_dwordx4 v[140:143], v[72:73], off offset:1664
	global_load_dwordx4 v[144:147], v[74:75], off offset:1664
	global_load_dwordx4 v[148:151], v[76:77], off offset:1664
	global_load_dwordx4 v[172:175], v[78:79], off offset:1664
	global_load_dwordx4 v[176:179], v[80:81], off offset:1664
	ds_read_b128 v[232:235], v245 offset:55296
	ds_read_b128 v[216:219], v244 offset:18432
	ds_read_b128 v[236:239], v245 offset:57600
	ds_read_b128 v[240:243], v245 offset:59904
	ds_read_b128 v[252:255], v245 offset:62208
	ds_read_b128 v[220:223], v244 offset:20736
	ds_read_b128 v[224:227], v244 offset:23040
	ds_read_b128 v[228:231], v244 offset:25344
	s_setprio 0
	s_waitcnt lgkmcnt(6)
	v_mfma_f32_16x16x32_bf16 v[50:53], v[216:219], v[232:235], v[50:53]
	s_waitcnt lgkmcnt(5)
	v_mfma_f32_16x16x32_bf16 v[54:57], v[216:219], v[236:239], v[54:57]
	s_waitcnt lgkmcnt(4)
	v_mfma_f32_16x16x32_bf16 v[34:37], v[216:219], v[240:243], v[34:37]
	s_waitcnt lgkmcnt(3)
	v_mfma_f32_16x16x32_bf16 v[38:41], v[216:219], v[252:255], v[38:41]
	ds_read_b128 v[216:219], v244 offset:18496
	s_waitcnt lgkmcnt(3)
	v_mfma_f32_16x16x32_bf16 v[58:61], v[220:223], v[232:235], v[58:61]
	v_mfma_f32_16x16x32_bf16 v[62:65], v[220:223], v[236:239], v[62:65]
	v_mfma_f32_16x16x32_bf16 v[42:45], v[220:223], v[240:243], v[42:45]
	v_mfma_f32_16x16x32_bf16 v[46:49], v[220:223], v[252:255], v[46:49]
	ds_read_b128 v[220:223], v244 offset:20800
	s_setprio 1
	s_waitcnt vmcnt(15)
	ds_write_b128 v164, v[180:183]
	s_waitcnt vmcnt(14)
	ds_write_b128 v164, v[188:191] offset:4608
	s_waitcnt lgkmcnt(5)
	v_mfma_f32_16x16x32_bf16 v[18:21], v[224:227], v[232:235], v[18:21]
	v_mfma_f32_16x16x32_bf16 v[22:25], v[224:227], v[236:239], v[22:25]
	v_mfma_f32_16x16x32_bf16 v[2:5], v[224:227], v[240:243], v[2:5]
	v_mfma_f32_16x16x32_bf16 v[6:9], v[224:227], v[252:255], v[6:9]
	ds_read_b128 v[224:227], v244 offset:23104
	s_waitcnt vmcnt(13)
	ds_write_b128 v164, v[192:195] offset:9216
	s_waitcnt vmcnt(12)
	ds_write_b128 v164, v[196:199] offset:13824
	s_waitcnt lgkmcnt(7)
	v_mfma_f32_16x16x32_bf16 v[26:29], v[228:231], v[232:235], v[26:29]
	ds_read_b128 v[232:235], v245 offset:55360
	v_mfma_f32_16x16x32_bf16 v[30:33], v[228:231], v[236:239], v[30:33]
	ds_read_b128 v[236:239], v245 offset:57664
	v_mfma_f32_16x16x32_bf16 v[10:13], v[228:231], v[240:243], v[10:13]
	ds_read_b128 v[240:243], v245 offset:59968
	v_mfma_f32_16x16x32_bf16 v[14:17], v[228:231], v[252:255], v[14:17]
	ds_read_b128 v[252:255], v245 offset:62272
	ds_read_b128 v[228:231], v244 offset:25408
	s_waitcnt lgkmcnt(4)
	v_mfma_f32_16x16x32_bf16 v[50:53], v[216:219], v[232:235], v[50:53]
	s_waitcnt lgkmcnt(3)
	v_mfma_f32_16x16x32_bf16 v[54:57], v[216:219], v[236:239], v[54:57]
	s_waitcnt lgkmcnt(2)
	v_mfma_f32_16x16x32_bf16 v[34:37], v[216:219], v[240:243], v[34:37]
	s_waitcnt lgkmcnt(1)
	v_mfma_f32_16x16x32_bf16 v[38:41], v[216:219], v[252:255], v[38:41]
	s_waitcnt vmcnt(11)
	ds_write_b128 v164, v[200:203] offset:36864
	s_waitcnt vmcnt(10)
	ds_write_b128 v164, v[204:207] offset:41472
	v_mfma_f32_16x16x32_bf16 v[58:61], v[220:223], v[232:235], v[58:61]
	v_mfma_f32_16x16x32_bf16 v[62:65], v[220:223], v[236:239], v[62:65]
	v_mfma_f32_16x16x32_bf16 v[42:45], v[220:223], v[240:243], v[42:45]
	v_mfma_f32_16x16x32_bf16 v[46:49], v[220:223], v[252:255], v[46:49]
	s_waitcnt vmcnt(9)
	ds_write_b128 v164, v[208:211] offset:46080
	s_waitcnt vmcnt(8)
	ds_write_b128 v164, v[212:215] offset:50688
	v_mfma_f32_16x16x32_bf16 v[18:21], v[224:227], v[232:235], v[18:21]
	v_mfma_f32_16x16x32_bf16 v[22:25], v[224:227], v[236:239], v[22:25]
	v_mfma_f32_16x16x32_bf16 v[2:5], v[224:227], v[240:243], v[2:5]
	v_mfma_f32_16x16x32_bf16 v[6:9], v[224:227], v[252:255], v[6:9]
	s_waitcnt lgkmcnt(4)
	v_mfma_f32_16x16x32_bf16 v[26:29], v[228:231], v[232:235], v[26:29]
	v_mfma_f32_16x16x32_bf16 v[30:33], v[228:231], v[236:239], v[30:33]
	v_mfma_f32_16x16x32_bf16 v[10:13], v[228:231], v[240:243], v[10:13]
	v_mfma_f32_16x16x32_bf16 v[14:17], v[228:231], v[252:255], v[14:17]
	s_waitcnt lgkmcnt(0)
	s_barrier
	global_load_dwordx4 v[180:183], v[70:71], off offset:1792
	global_load_dwordx4 v[188:191], v[68:69], off offset:1792
	global_load_dwordx4 v[192:195], v[66:67], off offset:1792
	global_load_dwordx4 v[196:199], v[72:73], off offset:1792
	global_load_dwordx4 v[200:203], v[74:75], off offset:1792
	global_load_dwordx4 v[204:207], v[76:77], off offset:1792
	global_load_dwordx4 v[208:211], v[78:79], off offset:1792
	global_load_dwordx4 v[212:215], v[80:81], off offset:1792
	ds_read_b128 v[232:235], v245 offset:36864
	ds_read_b128 v[216:219], v244
	ds_read_b128 v[236:239], v245 offset:39168
	ds_read_b128 v[240:243], v245 offset:41472
	ds_read_b128 v[252:255], v245 offset:43776
	ds_read_b128 v[220:223], v244 offset:2304
	ds_read_b128 v[224:227], v244 offset:4608
	ds_read_b128 v[228:231], v244 offset:6912
	s_setprio 0
	s_waitcnt lgkmcnt(6)
	v_mfma_f32_16x16x32_bf16 v[50:53], v[216:219], v[232:235], v[50:53]
	s_waitcnt lgkmcnt(5)
	v_mfma_f32_16x16x32_bf16 v[54:57], v[216:219], v[236:239], v[54:57]
	s_waitcnt lgkmcnt(4)
	v_mfma_f32_16x16x32_bf16 v[34:37], v[216:219], v[240:243], v[34:37]
	s_waitcnt lgkmcnt(3)
	v_mfma_f32_16x16x32_bf16 v[38:41], v[216:219], v[252:255], v[38:41]
	ds_read_b128 v[216:219], v244 offset:64
	s_waitcnt lgkmcnt(3)
	v_mfma_f32_16x16x32_bf16 v[58:61], v[220:223], v[232:235], v[58:61]
	v_mfma_f32_16x16x32_bf16 v[62:65], v[220:223], v[236:239], v[62:65]
	v_mfma_f32_16x16x32_bf16 v[42:45], v[220:223], v[240:243], v[42:45]
	v_mfma_f32_16x16x32_bf16 v[46:49], v[220:223], v[252:255], v[46:49]
	ds_read_b128 v[220:223], v244 offset:2368
	s_setprio 1
	s_waitcnt vmcnt(15)
	ds_write_b128 v164, v[122:125] offset:18432
	s_waitcnt vmcnt(14)
	ds_write_b128 v164, v[126:129] offset:23040
	s_waitcnt lgkmcnt(5)
	v_mfma_f32_16x16x32_bf16 v[18:21], v[224:227], v[232:235], v[18:21]
	v_mfma_f32_16x16x32_bf16 v[22:25], v[224:227], v[236:239], v[22:25]
	v_mfma_f32_16x16x32_bf16 v[2:5], v[224:227], v[240:243], v[2:5]
	v_mfma_f32_16x16x32_bf16 v[6:9], v[224:227], v[252:255], v[6:9]
	ds_read_b128 v[224:227], v244 offset:4672
	s_waitcnt vmcnt(13)
	ds_write_b128 v164, v[136:139] offset:27648
	s_waitcnt vmcnt(12)
	ds_write_b128 v164, v[140:143] offset:32256
	s_waitcnt lgkmcnt(7)
	v_mfma_f32_16x16x32_bf16 v[26:29], v[228:231], v[232:235], v[26:29]
	ds_read_b128 v[232:235], v245 offset:36928
	v_mfma_f32_16x16x32_bf16 v[30:33], v[228:231], v[236:239], v[30:33]
	ds_read_b128 v[236:239], v245 offset:39232
	v_mfma_f32_16x16x32_bf16 v[10:13], v[228:231], v[240:243], v[10:13]
	ds_read_b128 v[240:243], v245 offset:41536
	v_mfma_f32_16x16x32_bf16 v[14:17], v[228:231], v[252:255], v[14:17]
	ds_read_b128 v[252:255], v245 offset:43840
	ds_read_b128 v[228:231], v244 offset:6976
	s_waitcnt lgkmcnt(4)
	v_mfma_f32_16x16x32_bf16 v[50:53], v[216:219], v[232:235], v[50:53]
	s_waitcnt lgkmcnt(3)
	v_mfma_f32_16x16x32_bf16 v[54:57], v[216:219], v[236:239], v[54:57]
	s_waitcnt lgkmcnt(2)
	v_mfma_f32_16x16x32_bf16 v[34:37], v[216:219], v[240:243], v[34:37]
	s_waitcnt lgkmcnt(1)
	v_mfma_f32_16x16x32_bf16 v[38:41], v[216:219], v[252:255], v[38:41]
	s_waitcnt vmcnt(11)
	ds_write_b128 v164, v[144:147] offset:55296
	s_waitcnt vmcnt(10)
	ds_write_b128 v164, v[148:151] offset:59904
	v_mfma_f32_16x16x32_bf16 v[58:61], v[220:223], v[232:235], v[58:61]
	v_mfma_f32_16x16x32_bf16 v[62:65], v[220:223], v[236:239], v[62:65]
	v_mfma_f32_16x16x32_bf16 v[42:45], v[220:223], v[240:243], v[42:45]
	v_mfma_f32_16x16x32_bf16 v[46:49], v[220:223], v[252:255], v[46:49]
	s_waitcnt vmcnt(9)
	ds_write_b128 v164, v[172:175] offset:64512
	s_waitcnt vmcnt(8)
	ds_write_b128 v165, v[176:179] offset:32256
	v_mfma_f32_16x16x32_bf16 v[18:21], v[224:227], v[232:235], v[18:21]
	v_mfma_f32_16x16x32_bf16 v[22:25], v[224:227], v[236:239], v[22:25]
	v_mfma_f32_16x16x32_bf16 v[2:5], v[224:227], v[240:243], v[2:5]
	v_mfma_f32_16x16x32_bf16 v[6:9], v[224:227], v[252:255], v[6:9]
	s_waitcnt lgkmcnt(4)
	v_mfma_f32_16x16x32_bf16 v[26:29], v[228:231], v[232:235], v[26:29]
	v_mfma_f32_16x16x32_bf16 v[30:33], v[228:231], v[236:239], v[30:33]
	v_mfma_f32_16x16x32_bf16 v[10:13], v[228:231], v[240:243], v[10:13]
	v_mfma_f32_16x16x32_bf16 v[14:17], v[228:231], v[252:255], v[14:17]
	s_waitcnt lgkmcnt(0)
	s_barrier
	global_load_dwordx4 v[122:125], v[70:71], off offset:1920
	s_nop 0
	global_load_dwordx4 v[68:71], v[68:69], off offset:1920
	s_nop 0
	global_load_dwordx4 v[126:129], v[66:67], off offset:1920
	global_load_dwordx4 v[136:139], v[72:73], off offset:1920
	s_nop 0
	global_load_dwordx4 v[72:75], v[74:75], off offset:1920
	s_nop 0
	global_load_dwordx4 v[140:143], v[76:77], off offset:1920
	s_nop 0
	global_load_dwordx4 v[76:79], v[78:79], off offset:1920
	s_nop 0
	global_load_dwordx4 v[144:147], v[80:81], off offset:1920
	ds_read_b128 v[232:235], v245 offset:55296
	ds_read_b128 v[216:219], v244 offset:18432
	ds_read_b128 v[236:239], v245 offset:57600
	ds_read_b128 v[240:243], v245 offset:59904
	ds_read_b128 v[252:255], v245 offset:62208
	ds_read_b128 v[220:223], v244 offset:20736
	ds_read_b128 v[224:227], v244 offset:23040
	ds_read_b128 v[228:231], v244 offset:25344
	s_setprio 0
	s_waitcnt lgkmcnt(6)
	v_mfma_f32_16x16x32_bf16 v[50:53], v[216:219], v[232:235], v[50:53]
	s_waitcnt lgkmcnt(5)
	v_mfma_f32_16x16x32_bf16 v[54:57], v[216:219], v[236:239], v[54:57]
	s_waitcnt lgkmcnt(4)
	v_mfma_f32_16x16x32_bf16 v[34:37], v[216:219], v[240:243], v[34:37]
	s_waitcnt lgkmcnt(3)
	v_mfma_f32_16x16x32_bf16 v[38:41], v[216:219], v[252:255], v[38:41]
	ds_read_b128 v[216:219], v244 offset:18496
	s_waitcnt lgkmcnt(3)
	v_mfma_f32_16x16x32_bf16 v[58:61], v[220:223], v[232:235], v[58:61]
	v_mfma_f32_16x16x32_bf16 v[62:65], v[220:223], v[236:239], v[62:65]
	v_mfma_f32_16x16x32_bf16 v[42:45], v[220:223], v[240:243], v[42:45]
	v_mfma_f32_16x16x32_bf16 v[46:49], v[220:223], v[252:255], v[46:49]
	ds_read_b128 v[220:223], v244 offset:20800
	s_setprio 1
	s_waitcnt vmcnt(15)
	ds_write_b128 v164, v[180:183]
	s_waitcnt vmcnt(14)
	ds_write_b128 v164, v[188:191] offset:4608
	s_waitcnt lgkmcnt(5)
	v_mfma_f32_16x16x32_bf16 v[18:21], v[224:227], v[232:235], v[18:21]
	v_mfma_f32_16x16x32_bf16 v[22:25], v[224:227], v[236:239], v[22:25]
	v_mfma_f32_16x16x32_bf16 v[2:5], v[224:227], v[240:243], v[2:5]
	v_mfma_f32_16x16x32_bf16 v[6:9], v[224:227], v[252:255], v[6:9]
	ds_read_b128 v[224:227], v244 offset:23104
	s_waitcnt vmcnt(13)
	ds_write_b128 v164, v[192:195] offset:9216
	s_waitcnt vmcnt(12)
	ds_write_b128 v164, v[196:199] offset:13824
	s_waitcnt lgkmcnt(7)
	v_mfma_f32_16x16x32_bf16 v[26:29], v[228:231], v[232:235], v[26:29]
	ds_read_b128 v[232:235], v245 offset:55360
	v_mfma_f32_16x16x32_bf16 v[30:33], v[228:231], v[236:239], v[30:33]
	ds_read_b128 v[236:239], v245 offset:57664
	v_mfma_f32_16x16x32_bf16 v[10:13], v[228:231], v[240:243], v[10:13]
	ds_read_b128 v[240:243], v245 offset:59968
	v_mfma_f32_16x16x32_bf16 v[14:17], v[228:231], v[252:255], v[14:17]
	ds_read_b128 v[252:255], v245 offset:62272
	ds_read_b128 v[228:231], v244 offset:25408
	s_waitcnt lgkmcnt(4)
	v_mfma_f32_16x16x32_bf16 v[50:53], v[216:219], v[232:235], v[50:53]
	s_waitcnt lgkmcnt(3)
	v_mfma_f32_16x16x32_bf16 v[54:57], v[216:219], v[236:239], v[54:57]
	s_waitcnt lgkmcnt(2)
	v_mfma_f32_16x16x32_bf16 v[34:37], v[216:219], v[240:243], v[34:37]
	s_waitcnt lgkmcnt(1)
	v_mfma_f32_16x16x32_bf16 v[38:41], v[216:219], v[252:255], v[38:41]
	s_waitcnt vmcnt(11)
	ds_write_b128 v164, v[200:203] offset:36864
	s_waitcnt vmcnt(10)
	ds_write_b128 v164, v[204:207] offset:41472
	v_mfma_f32_16x16x32_bf16 v[58:61], v[220:223], v[232:235], v[58:61]
	v_mfma_f32_16x16x32_bf16 v[62:65], v[220:223], v[236:239], v[62:65]
	v_mfma_f32_16x16x32_bf16 v[42:45], v[220:223], v[240:243], v[42:45]
	v_mfma_f32_16x16x32_bf16 v[46:49], v[220:223], v[252:255], v[46:49]
	s_waitcnt vmcnt(9)
	ds_write_b128 v164, v[208:211] offset:46080
	s_waitcnt vmcnt(8)
	ds_write_b128 v164, v[212:215] offset:50688
	v_mfma_f32_16x16x32_bf16 v[18:21], v[224:227], v[232:235], v[18:21]
	v_mfma_f32_16x16x32_bf16 v[22:25], v[224:227], v[236:239], v[22:25]
	v_mfma_f32_16x16x32_bf16 v[2:5], v[224:227], v[240:243], v[2:5]
	v_mfma_f32_16x16x32_bf16 v[6:9], v[224:227], v[252:255], v[6:9]
	s_waitcnt lgkmcnt(4)
	v_mfma_f32_16x16x32_bf16 v[26:29], v[228:231], v[232:235], v[26:29]
	v_mfma_f32_16x16x32_bf16 v[30:33], v[228:231], v[236:239], v[30:33]
	v_mfma_f32_16x16x32_bf16 v[10:13], v[228:231], v[240:243], v[10:13]
	v_mfma_f32_16x16x32_bf16 v[14:17], v[228:231], v[252:255], v[14:17]
	s_waitcnt lgkmcnt(0)
	s_barrier
	ds_read_b128 v[232:235], v245 offset:36864
	ds_read_b128 v[216:219], v244
	ds_read_b128 v[236:239], v245 offset:39168
	ds_read_b128 v[240:243], v245 offset:41472
	ds_read_b128 v[252:255], v245 offset:43776
	ds_read_b128 v[220:223], v244 offset:2304
	ds_read_b128 v[224:227], v244 offset:4608
	ds_read_b128 v[228:231], v244 offset:6912
	s_setprio 0
	s_waitcnt lgkmcnt(6)
	v_mfma_f32_16x16x32_bf16 v[50:53], v[216:219], v[232:235], v[50:53]
	s_waitcnt lgkmcnt(5)
	v_mfma_f32_16x16x32_bf16 v[54:57], v[216:219], v[236:239], v[54:57]
	s_waitcnt lgkmcnt(4)
	v_mfma_f32_16x16x32_bf16 v[34:37], v[216:219], v[240:243], v[34:37]
	s_waitcnt lgkmcnt(3)
	v_mfma_f32_16x16x32_bf16 v[38:41], v[216:219], v[252:255], v[38:41]
	ds_read_b128 v[216:219], v244 offset:64
	s_waitcnt lgkmcnt(3)
	v_mfma_f32_16x16x32_bf16 v[58:61], v[220:223], v[232:235], v[58:61]
	v_mfma_f32_16x16x32_bf16 v[62:65], v[220:223], v[236:239], v[62:65]
	v_mfma_f32_16x16x32_bf16 v[42:45], v[220:223], v[240:243], v[42:45]
	v_mfma_f32_16x16x32_bf16 v[46:49], v[220:223], v[252:255], v[46:49]
	ds_read_b128 v[220:223], v244 offset:2368
	s_setprio 1
	s_waitcnt vmcnt(7)
	ds_write_b128 v164, v[122:125] offset:18432
	s_waitcnt vmcnt(6)
	ds_write_b128 v164, v[68:71] offset:23040
	s_waitcnt lgkmcnt(5)
	v_mfma_f32_16x16x32_bf16 v[18:21], v[224:227], v[232:235], v[18:21]
	v_mfma_f32_16x16x32_bf16 v[22:25], v[224:227], v[236:239], v[22:25]
	v_mfma_f32_16x16x32_bf16 v[2:5], v[224:227], v[240:243], v[2:5]
	v_mfma_f32_16x16x32_bf16 v[6:9], v[224:227], v[252:255], v[6:9]
	ds_read_b128 v[224:227], v244 offset:4672
	s_waitcnt vmcnt(5)
	ds_write_b128 v164, v[126:129] offset:27648
	s_waitcnt vmcnt(4)
	ds_write_b128 v164, v[136:139] offset:32256
	s_waitcnt lgkmcnt(7)
	v_mfma_f32_16x16x32_bf16 v[26:29], v[228:231], v[232:235], v[26:29]
	ds_read_b128 v[232:235], v245 offset:36928
	v_mfma_f32_16x16x32_bf16 v[30:33], v[228:231], v[236:239], v[30:33]
	ds_read_b128 v[236:239], v245 offset:39232
	v_mfma_f32_16x16x32_bf16 v[10:13], v[228:231], v[240:243], v[10:13]
	ds_read_b128 v[240:243], v245 offset:41536
	v_mfma_f32_16x16x32_bf16 v[14:17], v[228:231], v[252:255], v[14:17]
	ds_read_b128 v[252:255], v245 offset:43840
	ds_read_b128 v[228:231], v244 offset:6976
	s_waitcnt lgkmcnt(4)
	v_mfma_f32_16x16x32_bf16 v[50:53], v[216:219], v[232:235], v[50:53]
	s_waitcnt lgkmcnt(3)
	v_mfma_f32_16x16x32_bf16 v[54:57], v[216:219], v[236:239], v[54:57]
	s_waitcnt lgkmcnt(2)
	v_mfma_f32_16x16x32_bf16 v[34:37], v[216:219], v[240:243], v[34:37]
	s_waitcnt lgkmcnt(1)
	v_mfma_f32_16x16x32_bf16 v[38:41], v[216:219], v[252:255], v[38:41]
	s_waitcnt vmcnt(3)
	ds_write_b128 v164, v[72:75] offset:55296
	s_waitcnt vmcnt(2)
	ds_write_b128 v164, v[140:143] offset:59904
	v_mfma_f32_16x16x32_bf16 v[58:61], v[220:223], v[232:235], v[58:61]
	v_mfma_f32_16x16x32_bf16 v[62:65], v[220:223], v[236:239], v[62:65]
	v_mfma_f32_16x16x32_bf16 v[42:45], v[220:223], v[240:243], v[42:45]
	v_mfma_f32_16x16x32_bf16 v[46:49], v[220:223], v[252:255], v[46:49]
	s_waitcnt vmcnt(1)
	ds_write_b128 v164, v[76:79] offset:64512
	s_waitcnt vmcnt(0)
	ds_write_b128 v165, v[144:147] offset:32256
	v_mfma_f32_16x16x32_bf16 v[18:21], v[224:227], v[232:235], v[18:21]
	v_mfma_f32_16x16x32_bf16 v[22:25], v[224:227], v[236:239], v[22:25]
	v_mfma_f32_16x16x32_bf16 v[2:5], v[224:227], v[240:243], v[2:5]
	v_mfma_f32_16x16x32_bf16 v[6:9], v[224:227], v[252:255], v[6:9]
	s_waitcnt lgkmcnt(4)
	v_mfma_f32_16x16x32_bf16 v[26:29], v[228:231], v[232:235], v[26:29]
	v_mfma_f32_16x16x32_bf16 v[30:33], v[228:231], v[236:239], v[30:33]
	v_mfma_f32_16x16x32_bf16 v[10:13], v[228:231], v[240:243], v[10:13]
	v_mfma_f32_16x16x32_bf16 v[14:17], v[228:231], v[252:255], v[14:17]
	s_waitcnt lgkmcnt(0)
	s_barrier
	ds_read_b128 v[232:235], v245 offset:55296
	ds_read_b128 v[216:219], v244 offset:18432
	ds_read_b128 v[236:239], v245 offset:57600
	ds_read_b128 v[240:243], v245 offset:59904
	ds_read_b128 v[252:255], v245 offset:62208
	ds_read_b128 v[220:223], v244 offset:20736
	ds_read_b128 v[224:227], v244 offset:23040
	ds_read_b128 v[228:231], v244 offset:25344
	s_setprio 0
	s_waitcnt lgkmcnt(6)
	v_mfma_f32_16x16x32_bf16 v[50:53], v[216:219], v[232:235], v[50:53]
	s_waitcnt lgkmcnt(5)
	v_mfma_f32_16x16x32_bf16 v[54:57], v[216:219], v[236:239], v[54:57]
	s_waitcnt lgkmcnt(4)
	v_mfma_f32_16x16x32_bf16 v[34:37], v[216:219], v[240:243], v[34:37]
	s_waitcnt lgkmcnt(3)
	v_mfma_f32_16x16x32_bf16 v[38:41], v[216:219], v[252:255], v[38:41]
	ds_read_b128 v[216:219], v244 offset:18496
	s_waitcnt lgkmcnt(3)
	v_mfma_f32_16x16x32_bf16 v[58:61], v[220:223], v[232:235], v[58:61]
	v_mfma_f32_16x16x32_bf16 v[62:65], v[220:223], v[236:239], v[62:65]
	v_mfma_f32_16x16x32_bf16 v[42:45], v[220:223], v[240:243], v[42:45]
	v_mfma_f32_16x16x32_bf16 v[46:49], v[220:223], v[252:255], v[46:49]
	ds_read_b128 v[220:223], v244 offset:20800
	s_waitcnt lgkmcnt(3)
	v_mfma_f32_16x16x32_bf16 v[18:21], v[224:227], v[232:235], v[18:21]
	v_mfma_f32_16x16x32_bf16 v[22:25], v[224:227], v[236:239], v[22:25]
	v_mfma_f32_16x16x32_bf16 v[2:5], v[224:227], v[240:243], v[2:5]
	v_mfma_f32_16x16x32_bf16 v[6:9], v[224:227], v[252:255], v[6:9]
	ds_read_b128 v[224:227], v244 offset:23104
	s_waitcnt lgkmcnt(3)
	v_mfma_f32_16x16x32_bf16 v[26:29], v[228:231], v[232:235], v[26:29]
	ds_read_b128 v[232:235], v245 offset:55360
	v_mfma_f32_16x16x32_bf16 v[30:33], v[228:231], v[236:239], v[30:33]
	ds_read_b128 v[236:239], v245 offset:57664
	v_mfma_f32_16x16x32_bf16 v[10:13], v[228:231], v[240:243], v[10:13]
	ds_read_b128 v[240:243], v245 offset:59968
	v_mfma_f32_16x16x32_bf16 v[14:17], v[228:231], v[252:255], v[14:17]
	ds_read_b128 v[252:255], v245 offset:62272
	ds_read_b128 v[228:231], v244 offset:25408
	s_waitcnt lgkmcnt(4)
	v_mfma_f32_16x16x32_bf16 v[50:53], v[216:219], v[232:235], v[50:53]
	s_waitcnt lgkmcnt(3)
	v_mfma_f32_16x16x32_bf16 v[54:57], v[216:219], v[236:239], v[54:57]
	s_waitcnt lgkmcnt(2)
	v_mfma_f32_16x16x32_bf16 v[34:37], v[216:219], v[240:243], v[34:37]
	s_waitcnt lgkmcnt(1)
	v_mfma_f32_16x16x32_bf16 v[38:41], v[216:219], v[252:255], v[38:41]
	v_mfma_f32_16x16x32_bf16 v[58:61], v[220:223], v[232:235], v[58:61]
	v_mfma_f32_16x16x32_bf16 v[62:65], v[220:223], v[236:239], v[62:65]
	v_mfma_f32_16x16x32_bf16 v[42:45], v[220:223], v[240:243], v[42:45]
	v_mfma_f32_16x16x32_bf16 v[46:49], v[220:223], v[252:255], v[46:49]
	v_mfma_f32_16x16x32_bf16 v[18:21], v[224:227], v[232:235], v[18:21]
	v_mfma_f32_16x16x32_bf16 v[22:25], v[224:227], v[236:239], v[22:25]
	v_mfma_f32_16x16x32_bf16 v[2:5], v[224:227], v[240:243], v[2:5]
	v_mfma_f32_16x16x32_bf16 v[6:9], v[224:227], v[252:255], v[6:9]
	s_waitcnt lgkmcnt(0)
	v_mfma_f32_16x16x32_bf16 v[26:29], v[228:231], v[232:235], v[26:29]
	v_mfma_f32_16x16x32_bf16 v[30:33], v[228:231], v[236:239], v[30:33]
	v_mfma_f32_16x16x32_bf16 v[10:13], v[228:231], v[240:243], v[10:13]
	v_mfma_f32_16x16x32_bf16 v[14:17], v[228:231], v[252:255], v[14:17]
	s_waitcnt lgkmcnt(0)
	s_barrier
	s_nop 7
	v_permlane16_swap_b32_e32 v50, v54
	v_permlane16_swap_b32_e32 v51, v55
	v_permlane16_swap_b32_e32 v52, v56
	v_permlane16_swap_b32_e32 v53, v57
	v_permlane16_swap_b32_e32 v58, v62
	v_permlane16_swap_b32_e32 v59, v63
	v_permlane16_swap_b32_e32 v60, v64
	v_permlane16_swap_b32_e32 v61, v65
	v_permlane16_swap_b32_e32 v34, v38
	v_permlane16_swap_b32_e32 v35, v39
	v_permlane16_swap_b32_e32 v36, v40
	v_permlane16_swap_b32_e32 v37, v41
	v_permlane16_swap_b32_e32 v42, v46
	v_permlane16_swap_b32_e32 v43, v47
	v_permlane16_swap_b32_e32 v44, v48
	v_permlane16_swap_b32_e32 v45, v49
	v_permlane16_swap_b32_e32 v18, v22
	v_permlane16_swap_b32_e32 v19, v23
	v_permlane16_swap_b32_e32 v20, v24
	v_permlane16_swap_b32_e32 v21, v25
	v_permlane16_swap_b32_e32 v26, v30
	v_permlane16_swap_b32_e32 v27, v31
	v_permlane16_swap_b32_e32 v28, v32
	v_permlane16_swap_b32_e32 v29, v33
	v_permlane16_swap_b32_e32 v2, v6
	v_permlane16_swap_b32_e32 v3, v7
	v_permlane16_swap_b32_e32 v4, v8
	v_permlane16_swap_b32_e32 v5, v9
	v_permlane16_swap_b32_e32 v10, v14
	v_permlane16_swap_b32_e32 v11, v15
	v_permlane16_swap_b32_e32 v12, v16
	v_permlane16_swap_b32_e32 v13, v17
	v_permlane32_swap_b32_e32 v50, v54
	v_permlane32_swap_b32_e32 v51, v55
	v_permlane32_swap_b32_e32 v52, v56
	v_permlane32_swap_b32_e32 v53, v57
	v_permlane32_swap_b32_e32 v58, v62
	v_permlane32_swap_b32_e32 v59, v63
	v_permlane32_swap_b32_e32 v60, v64
	v_permlane32_swap_b32_e32 v61, v65
	v_permlane32_swap_b32_e32 v34, v38
	v_permlane32_swap_b32_e32 v35, v39
	v_permlane32_swap_b32_e32 v36, v40
	v_permlane32_swap_b32_e32 v37, v41
	v_permlane32_swap_b32_e32 v42, v46
	v_permlane32_swap_b32_e32 v43, v47
	v_permlane32_swap_b32_e32 v44, v48
	v_permlane32_swap_b32_e32 v45, v49
	v_permlane32_swap_b32_e32 v18, v22
	v_permlane32_swap_b32_e32 v19, v23
	v_permlane32_swap_b32_e32 v20, v24
	v_permlane32_swap_b32_e32 v21, v25
	v_permlane32_swap_b32_e32 v26, v30
	v_permlane32_swap_b32_e32 v27, v31
	v_permlane32_swap_b32_e32 v28, v32
	v_permlane32_swap_b32_e32 v29, v33
	v_permlane32_swap_b32_e32 v2, v6
	v_permlane32_swap_b32_e32 v3, v7
	v_permlane32_swap_b32_e32 v4, v8
	v_permlane32_swap_b32_e32 v5, v9
	v_permlane32_swap_b32_e32 v10, v14
	v_permlane32_swap_b32_e32 v11, v15
	v_permlane32_swap_b32_e32 v12, v16
	v_permlane32_swap_b32_e32 v13, v17

.LBB0_1641:
	s_and_b32 s3, s2, 0xffff
	s_mul_i32 s3, s3, 0xaaab
	s_lshr_b32 s3, s3, 18
	s_mul_i32 s10, s3, 6
	s_sub_i32 s2, s2, s10
	s_and_b32 s2, s2, 0xffff
	s_add_i32 s2, s6, s2
	s_lshl_b32 s10, s2, 7
	v_or_b32_e32 v2, s10, v91
	v_lshlrev_b32_e32 v66, 11, v2
	v_lshl_add_u64 v[74:75], v[68:69], 0, v[66:67]
	v_add_lshl_u32 v66, s10, v92, 11
	s_add_i32 s3, s8, s3
	v_lshl_add_u64 v[76:77], v[68:69], 0, v[66:67]
	v_add_lshl_u32 v66, s10, v93, 11
	s_lshl_b32 s11, s3, 7
	v_lshl_add_u64 v[78:79], v[68:69], 0, v[66:67]
	v_add_lshl_u32 v66, s10, v94, 11
	v_lshl_add_u64 v[80:81], v[68:69], 0, v[66:67]
	v_or_b32_e32 v66, s11, v91
	v_lshlrev_b64 v[2:3], 11, v[66:67]
	v_add_u32_e32 v66, s11, v92
	v_lshl_add_u64 v[82:83], v[70:71], 0, v[2:3]
	v_lshlrev_b64 v[2:3], 11, v[66:67]
	v_add_u32_e32 v66, s11, v93
	v_lshl_add_u64 v[84:85], v[70:71], 0, v[2:3]
	v_lshlrev_b64 v[2:3], 11, v[66:67]
	v_add_u32_e32 v66, s11, v94
	v_lshl_add_u64 v[86:87], v[70:71], 0, v[2:3]
	v_lshlrev_b64 v[2:3], 11, v[66:67]
	v_lshl_add_u64 v[88:89], v[70:71], 0, v[2:3]
	global_load_dwordx4 v[2:5], v[74:75], off
	global_load_dwordx4 v[6:9], v[76:77], off
	global_load_dwordx4 v[10:13], v[78:79], off
	global_load_dwordx4 v[14:17], v[80:81], off
	global_load_dwordx4 v[18:21], v[82:83], off
	global_load_dwordx4 v[22:25], v[84:85], off
	global_load_dwordx4 v[26:29], v[86:87], off
	global_load_dwordx4 v[30:33], v[88:89], off
	global_load_dwordx4 v[102:105], v[74:75], off offset:128
	global_load_dwordx4 v[106:109], v[76:77], off offset:128
	global_load_dwordx4 v[110:113], v[78:79], off offset:128
	global_load_dwordx4 v[114:117], v[80:81], off offset:128
	global_load_dwordx4 v[118:121], v[82:83], off offset:128
	global_load_dwordx4 v[122:125], v[84:85], off offset:128
	global_load_dwordx4 v[126:129], v[86:87], off offset:128
	global_load_dwordx4 v[132:135], v[88:89], off offset:128
	s_waitcnt vmcnt(15)
	ds_write_b128 v98, v[2:5]
	s_waitcnt vmcnt(14)
	ds_write_b128 v98, v[6:9] offset:4608
	s_waitcnt vmcnt(13)
	ds_write_b128 v98, v[10:13] offset:9216
	s_waitcnt vmcnt(12)
	ds_write_b128 v98, v[14:17] offset:13824
	s_waitcnt vmcnt(11)
	ds_write_b128 v98, v[18:21] offset:36864
	s_waitcnt vmcnt(10)
	ds_write_b128 v98, v[22:25] offset:41472
	s_waitcnt vmcnt(9)
	ds_write_b128 v98, v[26:29] offset:46080
	s_waitcnt vmcnt(8)
	ds_write_b128 v98, v[30:33] offset:50688
	s_waitcnt lgkmcnt(0)
	s_barrier
	global_load_dwordx4 v[136:139], v[74:75], off offset:256
	global_load_dwordx4 v[140:143], v[76:77], off offset:256
	global_load_dwordx4 v[144:147], v[78:79], off offset:256
	global_load_dwordx4 v[148:151], v[80:81], off offset:256
	global_load_dwordx4 v[152:155], v[82:83], off offset:256
	global_load_dwordx4 v[156:159], v[84:85], off offset:256
	global_load_dwordx4 v[160:163], v[86:87], off offset:256
	global_load_dwordx4 v[164:167], v[88:89], off offset:256
	v_and_b32_e32 v246, 15, v1
	v_add_u32_e32 v246, 4, v246
	v_bfe_u32 v246, v246, 3, 1
	v_bfe_u32 v249, v1, 4, 2
	v_xor_b32_e32 v246, v246, v249
	v_bfe_u32 v249, v1, 5, 1
	v_sub_u32_e32 v246, v246, v249
	v_lshlrev_b32_e32 v246, 4, v246
	v_bfe_u32 v249, v1, 4, 1
	v_mul_u32_u24_e32 v249, 0x900, v249
	v_sub_u32_e32 v246, v246, v249
	v_add_u32_e32 v244, v246, v96
	v_add_u32_e32 v245, v246, v97
	ds_read_b128 v[212:215], v245 offset:36864
	ds_read_b128 v[196:199], v244
	ds_read_b128 v[216:219], v245 offset:39168
	ds_read_b128 v[220:223], v245 offset:41472
	ds_read_b128 v[224:227], v245 offset:43776
	ds_read_b128 v[200:203], v244 offset:2304
	ds_read_b128 v[204:207], v244 offset:4608
	ds_read_b128 v[208:211], v244 offset:6912
	s_waitcnt lgkmcnt(6)
	v_mfma_f32_16x16x32_bf16 v[50:53], v[196:199], v[212:215], 0
	ds_read_b128 v[228:231], v245 offset:36928
	s_waitcnt lgkmcnt(6)
	v_mfma_f32_16x16x32_bf16 v[54:57], v[196:199], v[216:219], 0
	ds_read_b128 v[232:235], v245 offset:39232
	s_waitcnt lgkmcnt(6)
	v_mfma_f32_16x16x32_bf16 v[18:21], v[196:199], v[220:223], 0
	ds_read_b128 v[236:239], v245 offset:41536
	s_waitcnt lgkmcnt(6)
	v_mfma_f32_16x16x32_bf16 v[22:25], v[196:199], v[224:227], 0
	ds_read_b128 v[240:243], v245 offset:43840
	ds_read_b128 v[196:199], v244 offset:64
	s_waitcnt lgkmcnt(7)
	v_mfma_f32_16x16x32_bf16 v[58:61], v[200:203], v[212:215], 0
	v_mfma_f32_16x16x32_bf16 v[62:65], v[200:203], v[216:219], 0
	v_mfma_f32_16x16x32_bf16 v[26:29], v[200:203], v[220:223], 0
	v_mfma_f32_16x16x32_bf16 v[30:33], v[200:203], v[224:227], 0
	ds_read_b128 v[200:203], v244 offset:2368
	s_waitcnt lgkmcnt(7)
	v_mfma_f32_16x16x32_bf16 v[34:37], v[204:207], v[212:215], 0
	v_mfma_f32_16x16x32_bf16 v[38:41], v[204:207], v[216:219], 0
	v_mfma_f32_16x16x32_bf16 v[2:5], v[204:207], v[220:223], 0
	v_mfma_f32_16x16x32_bf16 v[6:9], v[204:207], v[224:227], 0
	ds_read_b128 v[204:207], v244 offset:4672
	s_setprio 1
	s_waitcnt vmcnt(15)
	ds_write_b128 v98, v[102:105] offset:18432
	s_waitcnt vmcnt(14)
	ds_write_b128 v98, v[106:109] offset:23040
	s_waitcnt lgkmcnt(9)
	v_mfma_f32_16x16x32_bf16 v[42:45], v[208:211], v[212:215], 0
	v_mfma_f32_16x16x32_bf16 v[46:49], v[208:211], v[216:219], 0
	v_mfma_f32_16x16x32_bf16 v[10:13], v[208:211], v[220:223], 0
	v_mfma_f32_16x16x32_bf16 v[14:17], v[208:211], v[224:227], 0
	ds_read_b128 v[208:211], v244 offset:6976
	s_waitcnt vmcnt(13)
	ds_write_b128 v98, v[110:113] offset:27648
	s_waitcnt vmcnt(12)
	ds_write_b128 v98, v[114:117] offset:32256
	s_waitcnt lgkmcnt(7)
	v_mfma_f32_16x16x32_bf16 v[50:53], v[196:199], v[228:231], v[50:53]
	v_mfma_f32_16x16x32_bf16 v[54:57], v[196:199], v[232:235], v[54:57]
	v_mfma_f32_16x16x32_bf16 v[18:21], v[196:199], v[236:239], v[18:21]
	v_mfma_f32_16x16x32_bf16 v[22:25], v[196:199], v[240:243], v[22:25]
	s_waitcnt vmcnt(11)
	ds_write_b128 v98, v[118:121] offset:55296
	s_waitcnt vmcnt(10)
	ds_write_b128 v98, v[122:125] offset:59904
	s_waitcnt lgkmcnt(8)
	v_mfma_f32_16x16x32_bf16 v[58:61], v[200:203], v[228:231], v[58:61]
	v_mfma_f32_16x16x32_bf16 v[62:65], v[200:203], v[232:235], v[62:65]
	v_mfma_f32_16x16x32_bf16 v[26:29], v[200:203], v[236:239], v[26:29]
	v_mfma_f32_16x16x32_bf16 v[30:33], v[200:203], v[240:243], v[30:33]
	s_waitcnt vmcnt(9)
	ds_write_b128 v98, v[126:129] offset:64512
	s_waitcnt vmcnt(8)
	ds_write_b128 v99, v[132:135] offset:32256
	s_waitcnt lgkmcnt(0)
	s_barrier
	ds_read_b128 v[212:215], v245 offset:55296
	ds_read_b128 v[196:199], v244 offset:18432
	ds_read_b128 v[216:219], v245 offset:57600
	ds_read_b128 v[220:223], v245 offset:59904
	ds_read_b128 v[224:227], v245 offset:62208
	ds_read_b128 v[200:203], v244 offset:20736
	s_setprio 0
	v_mfma_f32_16x16x32_bf16 v[34:37], v[204:207], v[228:231], v[34:37]
	v_mfma_f32_16x16x32_bf16 v[38:41], v[204:207], v[232:235], v[38:41]
	v_mfma_f32_16x16x32_bf16 v[2:5], v[204:207], v[236:239], v[2:5]
	v_mfma_f32_16x16x32_bf16 v[6:9], v[204:207], v[240:243], v[6:9]
	ds_read_b128 v[204:207], v244 offset:23040
	v_mfma_f32_16x16x32_bf16 v[42:45], v[208:211], v[228:231], v[42:45]
	v_mfma_f32_16x16x32_bf16 v[46:49], v[208:211], v[232:235], v[46:49]
	v_mfma_f32_16x16x32_bf16 v[10:13], v[208:211], v[236:239], v[10:13]
	v_mfma_f32_16x16x32_bf16 v[14:17], v[208:211], v[240:243], v[14:17]
	ds_read_b128 v[208:211], v244 offset:25344
	global_load_dwordx4 v[102:105], v[74:75], off offset:384
	global_load_dwordx4 v[106:109], v[76:77], off offset:384
	global_load_dwordx4 v[110:113], v[78:79], off offset:384
	global_load_dwordx4 v[114:117], v[80:81], off offset:384
	global_load_dwordx4 v[118:121], v[82:83], off offset:384
	global_load_dwordx4 v[122:125], v[84:85], off offset:384
	global_load_dwordx4 v[126:129], v[86:87], off offset:384
	global_load_dwordx4 v[132:135], v[88:89], off offset:384
	s_waitcnt lgkmcnt(6)
	v_mfma_f32_16x16x32_bf16 v[50:53], v[196:199], v[212:215], v[50:53]
	ds_read_b128 v[228:231], v245 offset:55360
	s_waitcnt lgkmcnt(6)
	v_mfma_f32_16x16x32_bf16 v[54:57], v[196:199], v[216:219], v[54:57]
	ds_read_b128 v[232:235], v245 offset:57664
	s_waitcnt lgkmcnt(6)
	v_mfma_f32_16x16x32_bf16 v[18:21], v[196:199], v[220:223], v[18:21]
	ds_read_b128 v[236:239], v245 offset:59968
	s_waitcnt lgkmcnt(6)
	v_mfma_f32_16x16x32_bf16 v[22:25], v[196:199], v[224:227], v[22:25]
	ds_read_b128 v[240:243], v245 offset:62272
	ds_read_b128 v[196:199], v244 offset:18496
	s_waitcnt lgkmcnt(7)
	v_mfma_f32_16x16x32_bf16 v[58:61], v[200:203], v[212:215], v[58:61]
	v_mfma_f32_16x16x32_bf16 v[62:65], v[200:203], v[216:219], v[62:65]
	v_mfma_f32_16x16x32_bf16 v[26:29], v[200:203], v[220:223], v[26:29]
	v_mfma_f32_16x16x32_bf16 v[30:33], v[200:203], v[224:227], v[30:33]
	ds_read_b128 v[200:203], v244 offset:20800
	s_waitcnt lgkmcnt(7)
	v_mfma_f32_16x16x32_bf16 v[34:37], v[204:207], v[212:215], v[34:37]
	v_mfma_f32_16x16x32_bf16 v[38:41], v[204:207], v[216:219], v[38:41]
	v_mfma_f32_16x16x32_bf16 v[2:5], v[204:207], v[220:223], v[2:5]
	v_mfma_f32_16x16x32_bf16 v[6:9], v[204:207], v[224:227], v[6:9]
	ds_read_b128 v[204:207], v244 offset:23104
	s_setprio 1
	s_waitcnt vmcnt(15)
	ds_write_b128 v98, v[136:139]
	s_waitcnt vmcnt(14)
	ds_write_b128 v98, v[140:143] offset:4608
	s_waitcnt lgkmcnt(9)
	v_mfma_f32_16x16x32_bf16 v[42:45], v[208:211], v[212:215], v[42:45]
	v_mfma_f32_16x16x32_bf16 v[46:49], v[208:211], v[216:219], v[46:49]
	v_mfma_f32_16x16x32_bf16 v[10:13], v[208:211], v[220:223], v[10:13]
	v_mfma_f32_16x16x32_bf16 v[14:17], v[208:211], v[224:227], v[14:17]
	ds_read_b128 v[208:211], v244 offset:25408
	s_waitcnt vmcnt(13)
	ds_write_b128 v98, v[144:147] offset:9216
	s_waitcnt vmcnt(12)
	ds_write_b128 v98, v[148:151] offset:13824
	s_waitcnt lgkmcnt(7)
	v_mfma_f32_16x16x32_bf16 v[50:53], v[196:199], v[228:231], v[50:53]
	v_mfma_f32_16x16x32_bf16 v[54:57], v[196:199], v[232:235], v[54:57]
	v_mfma_f32_16x16x32_bf16 v[18:21], v[196:199], v[236:239], v[18:21]
	v_mfma_f32_16x16x32_bf16 v[22:25], v[196:199], v[240:243], v[22:25]
	s_waitcnt vmcnt(11)
	ds_write_b128 v98, v[152:155] offset:36864
	s_waitcnt vmcnt(10)
	ds_write_b128 v98, v[156:159] offset:41472
	s_waitcnt lgkmcnt(8)
	v_mfma_f32_16x16x32_bf16 v[58:61], v[200:203], v[228:231], v[58:61]
	v_mfma_f32_16x16x32_bf16 v[62:65], v[200:203], v[232:235], v[62:65]
	v_mfma_f32_16x16x32_bf16 v[26:29], v[200:203], v[236:239], v[26:29]
	v_mfma_f32_16x16x32_bf16 v[30:33], v[200:203], v[240:243], v[30:33]
	s_waitcnt vmcnt(9)
	ds_write_b128 v98, v[160:163] offset:46080
	s_waitcnt vmcnt(8)
	ds_write_b128 v98, v[164:167] offset:50688
	s_waitcnt lgkmcnt(0)
	s_barrier
	ds_read_b128 v[212:215], v245 offset:36864
	ds_read_b128 v[196:199], v244
	ds_read_b128 v[216:219], v245 offset:39168
	ds_read_b128 v[220:223], v245 offset:41472
	ds_read_b128 v[224:227], v245 offset:43776
	ds_read_b128 v[200:203], v244 offset:2304
	s_setprio 0
	v_mfma_f32_16x16x32_bf16 v[34:37], v[204:207], v[228:231], v[34:37]
	v_mfma_f32_16x16x32_bf16 v[38:41], v[204:207], v[232:235], v[38:41]
	v_mfma_f32_16x16x32_bf16 v[2:5], v[204:207], v[236:239], v[2:5]
	v_mfma_f32_16x16x32_bf16 v[6:9], v[204:207], v[240:243], v[6:9]
	ds_read_b128 v[204:207], v244 offset:4608
	v_mfma_f32_16x16x32_bf16 v[42:45], v[208:211], v[228:231], v[42:45]
	v_mfma_f32_16x16x32_bf16 v[46:49], v[208:211], v[232:235], v[46:49]
	v_mfma_f32_16x16x32_bf16 v[10:13], v[208:211], v[236:239], v[10:13]
	v_mfma_f32_16x16x32_bf16 v[14:17], v[208:211], v[240:243], v[14:17]
	ds_read_b128 v[208:211], v244 offset:6912
	global_load_dwordx4 v[136:139], v[74:75], off offset:512
	global_load_dwordx4 v[140:143], v[76:77], off offset:512
	global_load_dwordx4 v[144:147], v[78:79], off offset:512
	global_load_dwordx4 v[148:151], v[80:81], off offset:512
	global_load_dwordx4 v[152:155], v[82:83], off offset:512
	global_load_dwordx4 v[156:159], v[84:85], off offset:512
	global_load_dwordx4 v[160:163], v[86:87], off offset:512
	global_load_dwordx4 v[164:167], v[88:89], off offset:512
	s_waitcnt lgkmcnt(6)
	v_mfma_f32_16x16x32_bf16 v[50:53], v[196:199], v[212:215], v[50:53]
	ds_read_b128 v[228:231], v245 offset:36928
	s_waitcnt lgkmcnt(6)
	v_mfma_f32_16x16x32_bf16 v[54:57], v[196:199], v[216:219], v[54:57]
	ds_read_b128 v[232:235], v245 offset:39232
	s_waitcnt lgkmcnt(6)
	v_mfma_f32_16x16x32_bf16 v[18:21], v[196:199], v[220:223], v[18:21]
	ds_read_b128 v[236:239], v245 offset:41536
	s_waitcnt lgkmcnt(6)
	v_mfma_f32_16x16x32_bf16 v[22:25], v[196:199], v[224:227], v[22:25]
	ds_read_b128 v[240:243], v245 offset:43840
	ds_read_b128 v[196:199], v244 offset:64
	s_waitcnt lgkmcnt(7)
	v_mfma_f32_16x16x32_bf16 v[58:61], v[200:203], v[212:215], v[58:61]
	v_mfma_f32_16x16x32_bf16 v[62:65], v[200:203], v[216:219], v[62:65]
	v_mfma_f32_16x16x32_bf16 v[26:29], v[200:203], v[220:223], v[26:29]
	v_mfma_f32_16x16x32_bf16 v[30:33], v[200:203], v[224:227], v[30:33]
	ds_read_b128 v[200:203], v244 offset:2368
	s_waitcnt lgkmcnt(7)
	v_mfma_f32_16x16x32_bf16 v[34:37], v[204:207], v[212:215], v[34:37]
	v_mfma_f32_16x16x32_bf16 v[38:41], v[204:207], v[216:219], v[38:41]
	v_mfma_f32_16x16x32_bf16 v[2:5], v[204:207], v[220:223], v[2:5]
	v_mfma_f32_16x16x32_bf16 v[6:9], v[204:207], v[224:227], v[6:9]
	ds_read_b128 v[204:207], v244 offset:4672
	s_setprio 1
	s_waitcnt vmcnt(15)
	ds_write_b128 v98, v[102:105] offset:18432
	s_waitcnt vmcnt(14)
	ds_write_b128 v98, v[106:109] offset:23040
	s_waitcnt lgkmcnt(9)
	v_mfma_f32_16x16x32_bf16 v[42:45], v[208:211], v[212:215], v[42:45]
	v_mfma_f32_16x16x32_bf16 v[46:49], v[208:211], v[216:219], v[46:49]
	v_mfma_f32_16x16x32_bf16 v[10:13], v[208:211], v[220:223], v[10:13]
	v_mfma_f32_16x16x32_bf16 v[14:17], v[208:211], v[224:227], v[14:17]
	ds_read_b128 v[208:211], v244 offset:6976
	s_waitcnt vmcnt(13)
	ds_write_b128 v98, v[110:113] offset:27648
	s_waitcnt vmcnt(12)
	ds_write_b128 v98, v[114:117] offset:32256
	s_waitcnt lgkmcnt(7)
	v_mfma_f32_16x16x32_bf16 v[50:53], v[196:199], v[228:231], v[50:53]
	v_mfma_f32_16x16x32_bf16 v[54:57], v[196:199], v[232:235], v[54:57]
	v_mfma_f32_16x16x32_bf16 v[18:21], v[196:199], v[236:239], v[18:21]
	v_mfma_f32_16x16x32_bf16 v[22:25], v[196:199], v[240:243], v[22:25]
	s_waitcnt vmcnt(11)
	ds_write_b128 v98, v[118:121] offset:55296
	s_waitcnt vmcnt(10)
	ds_write_b128 v98, v[122:125] offset:59904
	s_waitcnt lgkmcnt(8)
	v_mfma_f32_16x16x32_bf16 v[58:61], v[200:203], v[228:231], v[58:61]
	v_mfma_f32_16x16x32_bf16 v[62:65], v[200:203], v[232:235], v[62:65]
	v_mfma_f32_16x16x32_bf16 v[26:29], v[200:203], v[236:239], v[26:29]
	v_mfma_f32_16x16x32_bf16 v[30:33], v[200:203], v[240:243], v[30:33]
	s_waitcnt vmcnt(9)
	ds_write_b128 v98, v[126:129] offset:64512
	s_waitcnt vmcnt(8)
	ds_write_b128 v99, v[132:135] offset:32256
	s_waitcnt lgkmcnt(0)
	s_barrier
	ds_read_b128 v[212:215], v245 offset:55296
	ds_read_b128 v[196:199], v244 offset:18432
	ds_read_b128 v[216:219], v245 offset:57600
	ds_read_b128 v[220:223], v245 offset:59904
	ds_read_b128 v[224:227], v245 offset:62208
	ds_read_b128 v[200:203], v244 offset:20736
	s_setprio 0
	v_mfma_f32_16x16x32_bf16 v[34:37], v[204:207], v[228:231], v[34:37]
	v_mfma_f32_16x16x32_bf16 v[38:41], v[204:207], v[232:235], v[38:41]
	v_mfma_f32_16x16x32_bf16 v[2:5], v[204:207], v[236:239], v[2:5]
	v_mfma_f32_16x16x32_bf16 v[6:9], v[204:207], v[240:243], v[6:9]
	ds_read_b128 v[204:207], v244 offset:23040
	v_mfma_f32_16x16x32_bf16 v[42:45], v[208:211], v[228:231], v[42:45]
	v_mfma_f32_16x16x32_bf16 v[46:49], v[208:211], v[232:235], v[46:49]
	v_mfma_f32_16x16x32_bf16 v[10:13], v[208:211], v[236:239], v[10:13]
	v_mfma_f32_16x16x32_bf16 v[14:17], v[208:211], v[240:243], v[14:17]
	ds_read_b128 v[208:211], v244 offset:25344
	global_load_dwordx4 v[102:105], v[74:75], off offset:640
	global_load_dwordx4 v[106:109], v[76:77], off offset:640
	global_load_dwordx4 v[110:113], v[78:79], off offset:640
	global_load_dwordx4 v[114:117], v[80:81], off offset:640
	global_load_dwordx4 v[118:121], v[82:83], off offset:640
	global_load_dwordx4 v[122:125], v[84:85], off offset:640
	global_load_dwordx4 v[126:129], v[86:87], off offset:640
	global_load_dwordx4 v[132:135], v[88:89], off offset:640
	s_waitcnt lgkmcnt(6)
	v_mfma_f32_16x16x32_bf16 v[50:53], v[196:199], v[212:215], v[50:53]
	ds_read_b128 v[228:231], v245 offset:55360
	s_waitcnt lgkmcnt(6)
	v_mfma_f32_16x16x32_bf16 v[54:57], v[196:199], v[216:219], v[54:57]
	ds_read_b128 v[232:235], v245 offset:57664
	s_waitcnt lgkmcnt(6)
	v_mfma_f32_16x16x32_bf16 v[18:21], v[196:199], v[220:223], v[18:21]
	ds_read_b128 v[236:239], v245 offset:59968
	s_waitcnt lgkmcnt(6)
	v_mfma_f32_16x16x32_bf16 v[22:25], v[196:199], v[224:227], v[22:25]
	ds_read_b128 v[240:243], v245 offset:62272
	ds_read_b128 v[196:199], v244 offset:18496
	s_waitcnt lgkmcnt(7)
	v_mfma_f32_16x16x32_bf16 v[58:61], v[200:203], v[212:215], v[58:61]
	v_mfma_f32_16x16x32_bf16 v[62:65], v[200:203], v[216:219], v[62:65]
	v_mfma_f32_16x16x32_bf16 v[26:29], v[200:203], v[220:223], v[26:29]
	v_mfma_f32_16x16x32_bf16 v[30:33], v[200:203], v[224:227], v[30:33]
	ds_read_b128 v[200:203], v244 offset:20800
	s_waitcnt lgkmcnt(7)
	v_mfma_f32_16x16x32_bf16 v[34:37], v[204:207], v[212:215], v[34:37]
	v_mfma_f32_16x16x32_bf16 v[38:41], v[204:207], v[216:219], v[38:41]
	v_mfma_f32_16x16x32_bf16 v[2:5], v[204:207], v[220:223], v[2:5]
	v_mfma_f32_16x16x32_bf16 v[6:9], v[204:207], v[224:227], v[6:9]
	ds_read_b128 v[204:207], v244 offset:23104
	s_setprio 1
	s_waitcnt vmcnt(15)
	ds_write_b128 v98, v[136:139]
	s_waitcnt vmcnt(14)
	ds_write_b128 v98, v[140:143] offset:4608
	s_waitcnt lgkmcnt(9)
	v_mfma_f32_16x16x32_bf16 v[42:45], v[208:211], v[212:215], v[42:45]
	v_mfma_f32_16x16x32_bf16 v[46:49], v[208:211], v[216:219], v[46:49]
	v_mfma_f32_16x16x32_bf16 v[10:13], v[208:211], v[220:223], v[10:13]
	v_mfma_f32_16x16x32_bf16 v[14:17], v[208:211], v[224:227], v[14:17]
	ds_read_b128 v[208:211], v244 offset:25408
	s_waitcnt vmcnt(13)
	ds_write_b128 v98, v[144:147] offset:9216
	s_waitcnt vmcnt(12)
	ds_write_b128 v98, v[148:151] offset:13824
	s_waitcnt lgkmcnt(7)
	v_mfma_f32_16x16x32_bf16 v[50:53], v[196:199], v[228:231], v[50:53]
	v_mfma_f32_16x16x32_bf16 v[54:57], v[196:199], v[232:235], v[54:57]
	v_mfma_f32_16x16x32_bf16 v[18:21], v[196:199], v[236:239], v[18:21]
	v_mfma_f32_16x16x32_bf16 v[22:25], v[196:199], v[240:243], v[22:25]
	s_waitcnt vmcnt(11)
	ds_write_b128 v98, v[152:155] offset:36864
	s_waitcnt vmcnt(10)
	ds_write_b128 v98, v[156:159] offset:41472
	s_waitcnt lgkmcnt(8)
	v_mfma_f32_16x16x32_bf16 v[58:61], v[200:203], v[228:231], v[58:61]
	v_mfma_f32_16x16x32_bf16 v[62:65], v[200:203], v[232:235], v[62:65]
	v_mfma_f32_16x16x32_bf16 v[26:29], v[200:203], v[236:239], v[26:29]
	v_mfma_f32_16x16x32_bf16 v[30:33], v[200:203], v[240:243], v[30:33]
	s_waitcnt vmcnt(9)
	ds_write_b128 v98, v[160:163] offset:46080
	s_waitcnt vmcnt(8)
	ds_write_b128 v98, v[164:167] offset:50688
	s_waitcnt lgkmcnt(0)
	s_barrier
	ds_read_b128 v[212:215], v245 offset:36864
	ds_read_b128 v[196:199], v244
	ds_read_b128 v[216:219], v245 offset:39168
	ds_read_b128 v[220:223], v245 offset:41472
	ds_read_b128 v[224:227], v245 offset:43776
	ds_read_b128 v[200:203], v244 offset:2304
	s_setprio 0
	v_mfma_f32_16x16x32_bf16 v[34:37], v[204:207], v[228:231], v[34:37]
	v_mfma_f32_16x16x32_bf16 v[38:41], v[204:207], v[232:235], v[38:41]
	v_mfma_f32_16x16x32_bf16 v[2:5], v[204:207], v[236:239], v[2:5]
	v_mfma_f32_16x16x32_bf16 v[6:9], v[204:207], v[240:243], v[6:9]
	ds_read_b128 v[204:207], v244 offset:4608
	v_mfma_f32_16x16x32_bf16 v[42:45], v[208:211], v[228:231], v[42:45]
	v_mfma_f32_16x16x32_bf16 v[46:49], v[208:211], v[232:235], v[46:49]
	v_mfma_f32_16x16x32_bf16 v[10:13], v[208:211], v[236:239], v[10:13]
	v_mfma_f32_16x16x32_bf16 v[14:17], v[208:211], v[240:243], v[14:17]
	ds_read_b128 v[208:211], v244 offset:6912
	global_load_dwordx4 v[136:139], v[74:75], off offset:768
	global_load_dwordx4 v[140:143], v[76:77], off offset:768
	global_load_dwordx4 v[144:147], v[78:79], off offset:768
	global_load_dwordx4 v[148:151], v[80:81], off offset:768
	global_load_dwordx4 v[152:155], v[82:83], off offset:768
	global_load_dwordx4 v[156:159], v[84:85], off offset:768
	global_load_dwordx4 v[160:163], v[86:87], off offset:768
	global_load_dwordx4 v[164:167], v[88:89], off offset:768
	s_waitcnt lgkmcnt(6)
	v_mfma_f32_16x16x32_bf16 v[50:53], v[196:199], v[212:215], v[50:53]
	ds_read_b128 v[228:231], v245 offset:36928
	s_waitcnt lgkmcnt(6)
	v_mfma_f32_16x16x32_bf16 v[54:57], v[196:199], v[216:219], v[54:57]
	ds_read_b128 v[232:235], v245 offset:39232
	s_waitcnt lgkmcnt(6)
	v_mfma_f32_16x16x32_bf16 v[18:21], v[196:199], v[220:223], v[18:21]
	ds_read_b128 v[236:239], v245 offset:41536
	s_waitcnt lgkmcnt(6)
	v_mfma_f32_16x16x32_bf16 v[22:25], v[196:199], v[224:227], v[22:25]
	ds_read_b128 v[240:243], v245 offset:43840
	ds_read_b128 v[196:199], v244 offset:64
	s_waitcnt lgkmcnt(7)
	v_mfma_f32_16x16x32_bf16 v[58:61], v[200:203], v[212:215], v[58:61]
	v_mfma_f32_16x16x32_bf16 v[62:65], v[200:203], v[216:219], v[62:65]
	v_mfma_f32_16x16x32_bf16 v[26:29], v[200:203], v[220:223], v[26:29]
	v_mfma_f32_16x16x32_bf16 v[30:33], v[200:203], v[224:227], v[30:33]
	ds_read_b128 v[200:203], v244 offset:2368
	s_waitcnt lgkmcnt(7)
	v_mfma_f32_16x16x32_bf16 v[34:37], v[204:207], v[212:215], v[34:37]
	v_mfma_f32_16x16x32_bf16 v[38:41], v[204:207], v[216:219], v[38:41]
	v_mfma_f32_16x16x32_bf16 v[2:5], v[204:207], v[220:223], v[2:5]
	v_mfma_f32_16x16x32_bf16 v[6:9], v[204:207], v[224:227], v[6:9]
	ds_read_b128 v[204:207], v244 offset:4672
	s_setprio 1
	s_waitcnt vmcnt(15)
	ds_write_b128 v98, v[102:105] offset:18432
	s_waitcnt vmcnt(14)
	ds_write_b128 v98, v[106:109] offset:23040
	s_waitcnt lgkmcnt(9)
	v_mfma_f32_16x16x32_bf16 v[42:45], v[208:211], v[212:215], v[42:45]
	v_mfma_f32_16x16x32_bf16 v[46:49], v[208:211], v[216:219], v[46:49]
	v_mfma_f32_16x16x32_bf16 v[10:13], v[208:211], v[220:223], v[10:13]
	v_mfma_f32_16x16x32_bf16 v[14:17], v[208:211], v[224:227], v[14:17]
	ds_read_b128 v[208:211], v244 offset:6976
	s_waitcnt vmcnt(13)
	ds_write_b128 v98, v[110:113] offset:27648
	s_waitcnt vmcnt(12)
	ds_write_b128 v98, v[114:117] offset:32256
	s_waitcnt lgkmcnt(7)
	v_mfma_f32_16x16x32_bf16 v[50:53], v[196:199], v[228:231], v[50:53]
	v_mfma_f32_16x16x32_bf16 v[54:57], v[196:199], v[232:235], v[54:57]
	v_mfma_f32_16x16x32_bf16 v[18:21], v[196:199], v[236:239], v[18:21]
	v_mfma_f32_16x16x32_bf16 v[22:25], v[196:199], v[240:243], v[22:25]
	s_waitcnt vmcnt(11)
	ds_write_b128 v98, v[118:121] offset:55296
	s_waitcnt vmcnt(10)
	ds_write_b128 v98, v[122:125] offset:59904
	s_waitcnt lgkmcnt(8)
	v_mfma_f32_16x16x32_bf16 v[58:61], v[200:203], v[228:231], v[58:61]
	v_mfma_f32_16x16x32_bf16 v[62:65], v[200:203], v[232:235], v[62:65]
	v_mfma_f32_16x16x32_bf16 v[26:29], v[200:203], v[236:239], v[26:29]
	v_mfma_f32_16x16x32_bf16 v[30:33], v[200:203], v[240:243], v[30:33]
	s_waitcnt vmcnt(9)
	ds_write_b128 v98, v[126:129] offset:64512
	s_waitcnt vmcnt(8)
	ds_write_b128 v99, v[132:135] offset:32256
	s_waitcnt lgkmcnt(0)
	s_barrier
	ds_read_b128 v[212:215], v245 offset:55296
	ds_read_b128 v[196:199], v244 offset:18432
	ds_read_b128 v[216:219], v245 offset:57600
	ds_read_b128 v[220:223], v245 offset:59904
	ds_read_b128 v[224:227], v245 offset:62208
	ds_read_b128 v[200:203], v244 offset:20736
	s_setprio 0
	v_mfma_f32_16x16x32_bf16 v[34:37], v[204:207], v[228:231], v[34:37]
	v_mfma_f32_16x16x32_bf16 v[38:41], v[204:207], v[232:235], v[38:41]
	v_mfma_f32_16x16x32_bf16 v[2:5], v[204:207], v[236:239], v[2:5]
	v_mfma_f32_16x16x32_bf16 v[6:9], v[204:207], v[240:243], v[6:9]
	ds_read_b128 v[204:207], v244 offset:23040
	v_mfma_f32_16x16x32_bf16 v[42:45], v[208:211], v[228:231], v[42:45]
	v_mfma_f32_16x16x32_bf16 v[46:49], v[208:211], v[232:235], v[46:49]
	v_mfma_f32_16x16x32_bf16 v[10:13], v[208:211], v[236:239], v[10:13]
	v_mfma_f32_16x16x32_bf16 v[14:17], v[208:211], v[240:243], v[14:17]
	ds_read_b128 v[208:211], v244 offset:25344
	global_load_dwordx4 v[102:105], v[74:75], off offset:896
	global_load_dwordx4 v[106:109], v[76:77], off offset:896
	global_load_dwordx4 v[110:113], v[78:79], off offset:896
	global_load_dwordx4 v[114:117], v[80:81], off offset:896
	global_load_dwordx4 v[118:121], v[82:83], off offset:896
	global_load_dwordx4 v[122:125], v[84:85], off offset:896
	global_load_dwordx4 v[126:129], v[86:87], off offset:896
	global_load_dwordx4 v[132:135], v[88:89], off offset:896
	s_waitcnt lgkmcnt(6)
	v_mfma_f32_16x16x32_bf16 v[50:53], v[196:199], v[212:215], v[50:53]
	ds_read_b128 v[228:231], v245 offset:55360
	s_waitcnt lgkmcnt(6)
	v_mfma_f32_16x16x32_bf16 v[54:57], v[196:199], v[216:219], v[54:57]
	ds_read_b128 v[232:235], v245 offset:57664
	s_waitcnt lgkmcnt(6)
	v_mfma_f32_16x16x32_bf16 v[18:21], v[196:199], v[220:223], v[18:21]
	ds_read_b128 v[236:239], v245 offset:59968
	s_waitcnt lgkmcnt(6)
	v_mfma_f32_16x16x32_bf16 v[22:25], v[196:199], v[224:227], v[22:25]
	ds_read_b128 v[240:243], v245 offset:62272
	ds_read_b128 v[196:199], v244 offset:18496
	s_waitcnt lgkmcnt(7)
	v_mfma_f32_16x16x32_bf16 v[58:61], v[200:203], v[212:215], v[58:61]
	v_mfma_f32_16x16x32_bf16 v[62:65], v[200:203], v[216:219], v[62:65]
	v_mfma_f32_16x16x32_bf16 v[26:29], v[200:203], v[220:223], v[26:29]
	v_mfma_f32_16x16x32_bf16 v[30:33], v[200:203], v[224:227], v[30:33]
	ds_read_b128 v[200:203], v244 offset:20800
	s_waitcnt lgkmcnt(7)
	v_mfma_f32_16x16x32_bf16 v[34:37], v[204:207], v[212:215], v[34:37]
	v_mfma_f32_16x16x32_bf16 v[38:41], v[204:207], v[216:219], v[38:41]
	v_mfma_f32_16x16x32_bf16 v[2:5], v[204:207], v[220:223], v[2:5]
	v_mfma_f32_16x16x32_bf16 v[6:9], v[204:207], v[224:227], v[6:9]
	ds_read_b128 v[204:207], v244 offset:23104
	s_setprio 1
	s_waitcnt vmcnt(15)
	ds_write_b128 v98, v[136:139]
	s_waitcnt vmcnt(14)
	ds_write_b128 v98, v[140:143] offset:4608
	s_waitcnt lgkmcnt(9)
	v_mfma_f32_16x16x32_bf16 v[42:45], v[208:211], v[212:215], v[42:45]
	v_mfma_f32_16x16x32_bf16 v[46:49], v[208:211], v[216:219], v[46:49]
	v_mfma_f32_16x16x32_bf16 v[10:13], v[208:211], v[220:223], v[10:13]
	v_mfma_f32_16x16x32_bf16 v[14:17], v[208:211], v[224:227], v[14:17]
	ds_read_b128 v[208:211], v244 offset:25408
	s_waitcnt vmcnt(13)
	ds_write_b128 v98, v[144:147] offset:9216
	s_waitcnt vmcnt(12)
	ds_write_b128 v98, v[148:151] offset:13824
	s_waitcnt lgkmcnt(7)
	v_mfma_f32_16x16x32_bf16 v[50:53], v[196:199], v[228:231], v[50:53]
	v_mfma_f32_16x16x32_bf16 v[54:57], v[196:199], v[232:235], v[54:57]
	v_mfma_f32_16x16x32_bf16 v[18:21], v[196:199], v[236:239], v[18:21]
	v_mfma_f32_16x16x32_bf16 v[22:25], v[196:199], v[240:243], v[22:25]
	s_waitcnt vmcnt(11)
	ds_write_b128 v98, v[152:155] offset:36864
	s_waitcnt vmcnt(10)
	ds_write_b128 v98, v[156:159] offset:41472
	s_waitcnt lgkmcnt(8)
	v_mfma_f32_16x16x32_bf16 v[58:61], v[200:203], v[228:231], v[58:61]
	v_mfma_f32_16x16x32_bf16 v[62:65], v[200:203], v[232:235], v[62:65]
	v_mfma_f32_16x16x32_bf16 v[26:29], v[200:203], v[236:239], v[26:29]
	v_mfma_f32_16x16x32_bf16 v[30:33], v[200:203], v[240:243], v[30:33]
	s_waitcnt vmcnt(9)
	ds_write_b128 v98, v[160:163] offset:46080
	s_waitcnt vmcnt(8)
	ds_write_b128 v98, v[164:167] offset:50688
	s_waitcnt lgkmcnt(0)
	s_barrier
	ds_read_b128 v[212:215], v245 offset:36864
	ds_read_b128 v[196:199], v244
	ds_read_b128 v[216:219], v245 offset:39168
	ds_read_b128 v[220:223], v245 offset:41472
	ds_read_b128 v[224:227], v245 offset:43776
	ds_read_b128 v[200:203], v244 offset:2304
	s_setprio 0
	v_mfma_f32_16x16x32_bf16 v[34:37], v[204:207], v[228:231], v[34:37]
	v_mfma_f32_16x16x32_bf16 v[38:41], v[204:207], v[232:235], v[38:41]
	v_mfma_f32_16x16x32_bf16 v[2:5], v[204:207], v[236:239], v[2:5]
	v_mfma_f32_16x16x32_bf16 v[6:9], v[204:207], v[240:243], v[6:9]
	ds_read_b128 v[204:207], v244 offset:4608
	v_mfma_f32_16x16x32_bf16 v[42:45], v[208:211], v[228:231], v[42:45]
	v_mfma_f32_16x16x32_bf16 v[46:49], v[208:211], v[232:235], v[46:49]
	v_mfma_f32_16x16x32_bf16 v[10:13], v[208:211], v[236:239], v[10:13]
	v_mfma_f32_16x16x32_bf16 v[14:17], v[208:211], v[240:243], v[14:17]
	ds_read_b128 v[208:211], v244 offset:6912
	global_load_dwordx4 v[136:139], v[74:75], off offset:1024
	global_load_dwordx4 v[140:143], v[76:77], off offset:1024
	global_load_dwordx4 v[144:147], v[78:79], off offset:1024
	global_load_dwordx4 v[148:151], v[80:81], off offset:1024
	global_load_dwordx4 v[152:155], v[82:83], off offset:1024
	global_load_dwordx4 v[156:159], v[84:85], off offset:1024
	global_load_dwordx4 v[160:163], v[86:87], off offset:1024
	global_load_dwordx4 v[164:167], v[88:89], off offset:1024
	s_waitcnt lgkmcnt(6)
	v_mfma_f32_16x16x32_bf16 v[50:53], v[196:199], v[212:215], v[50:53]
	ds_read_b128 v[228:231], v245 offset:36928
	s_waitcnt lgkmcnt(6)
	v_mfma_f32_16x16x32_bf16 v[54:57], v[196:199], v[216:219], v[54:57]
	ds_read_b128 v[232:235], v245 offset:39232
	s_waitcnt lgkmcnt(6)
	v_mfma_f32_16x16x32_bf16 v[18:21], v[196:199], v[220:223], v[18:21]
	ds_read_b128 v[236:239], v245 offset:41536
	s_waitcnt lgkmcnt(6)
	v_mfma_f32_16x16x32_bf16 v[22:25], v[196:199], v[224:227], v[22:25]
	ds_read_b128 v[240:243], v245 offset:43840
	ds_read_b128 v[196:199], v244 offset:64
	s_waitcnt lgkmcnt(7)
	v_mfma_f32_16x16x32_bf16 v[58:61], v[200:203], v[212:215], v[58:61]
	v_mfma_f32_16x16x32_bf16 v[62:65], v[200:203], v[216:219], v[62:65]
	v_mfma_f32_16x16x32_bf16 v[26:29], v[200:203], v[220:223], v[26:29]
	v_mfma_f32_16x16x32_bf16 v[30:33], v[200:203], v[224:227], v[30:33]
	ds_read_b128 v[200:203], v244 offset:2368
	s_waitcnt lgkmcnt(7)
	v_mfma_f32_16x16x32_bf16 v[34:37], v[204:207], v[212:215], v[34:37]
	v_mfma_f32_16x16x32_bf16 v[38:41], v[204:207], v[216:219], v[38:41]
	v_mfma_f32_16x16x32_bf16 v[2:5], v[204:207], v[220:223], v[2:5]
	v_mfma_f32_16x16x32_bf16 v[6:9], v[204:207], v[224:227], v[6:9]
	ds_read_b128 v[204:207], v244 offset:4672
	s_setprio 1
	s_waitcnt vmcnt(15)
	ds_write_b128 v98, v[102:105] offset:18432
	s_waitcnt vmcnt(14)
	ds_write_b128 v98, v[106:109] offset:23040
	s_waitcnt lgkmcnt(9)
	v_mfma_f32_16x16x32_bf16 v[42:45], v[208:211], v[212:215], v[42:45]
	v_mfma_f32_16x16x32_bf16 v[46:49], v[208:211], v[216:219], v[46:49]
	v_mfma_f32_16x16x32_bf16 v[10:13], v[208:211], v[220:223], v[10:13]
	v_mfma_f32_16x16x32_bf16 v[14:17], v[208:211], v[224:227], v[14:17]
	ds_read_b128 v[208:211], v244 offset:6976
	s_waitcnt vmcnt(13)
	ds_write_b128 v98, v[110:113] offset:27648
	s_waitcnt vmcnt(12)
	ds_write_b128 v98, v[114:117] offset:32256
	s_waitcnt lgkmcnt(7)
	v_mfma_f32_16x16x32_bf16 v[50:53], v[196:199], v[228:231], v[50:53]
	v_mfma_f32_16x16x32_bf16 v[54:57], v[196:199], v[232:235], v[54:57]
	v_mfma_f32_16x16x32_bf16 v[18:21], v[196:199], v[236:239], v[18:21]
	v_mfma_f32_16x16x32_bf16 v[22:25], v[196:199], v[240:243], v[22:25]
	s_waitcnt vmcnt(11)
	ds_write_b128 v98, v[118:121] offset:55296
	s_waitcnt vmcnt(10)
	ds_write_b128 v98, v[122:125] offset:59904
	s_waitcnt lgkmcnt(8)
	v_mfma_f32_16x16x32_bf16 v[58:61], v[200:203], v[228:231], v[58:61]
	v_mfma_f32_16x16x32_bf16 v[62:65], v[200:203], v[232:235], v[62:65]
	v_mfma_f32_16x16x32_bf16 v[26:29], v[200:203], v[236:239], v[26:29]
	v_mfma_f32_16x16x32_bf16 v[30:33], v[200:203], v[240:243], v[30:33]
	s_waitcnt vmcnt(9)
	ds_write_b128 v98, v[126:129] offset:64512
	s_waitcnt vmcnt(8)
	ds_write_b128 v99, v[132:135] offset:32256
	s_waitcnt lgkmcnt(0)
	s_barrier
	ds_read_b128 v[212:215], v245 offset:55296
	ds_read_b128 v[196:199], v244 offset:18432
	ds_read_b128 v[216:219], v245 offset:57600
	ds_read_b128 v[220:223], v245 offset:59904
	ds_read_b128 v[224:227], v245 offset:62208
	ds_read_b128 v[200:203], v244 offset:20736
	s_setprio 0
	v_mfma_f32_16x16x32_bf16 v[34:37], v[204:207], v[228:231], v[34:37]
	v_mfma_f32_16x16x32_bf16 v[38:41], v[204:207], v[232:235], v[38:41]
	v_mfma_f32_16x16x32_bf16 v[2:5], v[204:207], v[236:239], v[2:5]
	v_mfma_f32_16x16x32_bf16 v[6:9], v[204:207], v[240:243], v[6:9]
	ds_read_b128 v[204:207], v244 offset:23040
	v_mfma_f32_16x16x32_bf16 v[42:45], v[208:211], v[228:231], v[42:45]
	v_mfma_f32_16x16x32_bf16 v[46:49], v[208:211], v[232:235], v[46:49]
	v_mfma_f32_16x16x32_bf16 v[10:13], v[208:211], v[236:239], v[10:13]
	v_mfma_f32_16x16x32_bf16 v[14:17], v[208:211], v[240:243], v[14:17]
	ds_read_b128 v[208:211], v244 offset:25344
	global_load_dwordx4 v[102:105], v[74:75], off offset:1152
	global_load_dwordx4 v[106:109], v[76:77], off offset:1152
	global_load_dwordx4 v[110:113], v[78:79], off offset:1152
	global_load_dwordx4 v[114:117], v[80:81], off offset:1152
	global_load_dwordx4 v[118:121], v[82:83], off offset:1152
	global_load_dwordx4 v[122:125], v[84:85], off offset:1152
	global_load_dwordx4 v[126:129], v[86:87], off offset:1152
	global_load_dwordx4 v[132:135], v[88:89], off offset:1152
	s_waitcnt lgkmcnt(6)
	v_mfma_f32_16x16x32_bf16 v[50:53], v[196:199], v[212:215], v[50:53]
	ds_read_b128 v[228:231], v245 offset:55360
	s_waitcnt lgkmcnt(6)
	v_mfma_f32_16x16x32_bf16 v[54:57], v[196:199], v[216:219], v[54:57]
	ds_read_b128 v[232:235], v245 offset:57664
	s_waitcnt lgkmcnt(6)
	v_mfma_f32_16x16x32_bf16 v[18:21], v[196:199], v[220:223], v[18:21]
	ds_read_b128 v[236:239], v245 offset:59968
	s_waitcnt lgkmcnt(6)
	v_mfma_f32_16x16x32_bf16 v[22:25], v[196:199], v[224:227], v[22:25]
	ds_read_b128 v[240:243], v245 offset:62272
	ds_read_b128 v[196:199], v244 offset:18496
	s_waitcnt lgkmcnt(7)
	v_mfma_f32_16x16x32_bf16 v[58:61], v[200:203], v[212:215], v[58:61]
	v_mfma_f32_16x16x32_bf16 v[62:65], v[200:203], v[216:219], v[62:65]
	v_mfma_f32_16x16x32_bf16 v[26:29], v[200:203], v[220:223], v[26:29]
	v_mfma_f32_16x16x32_bf16 v[30:33], v[200:203], v[224:227], v[30:33]
	ds_read_b128 v[200:203], v244 offset:20800
	s_waitcnt lgkmcnt(7)
	v_mfma_f32_16x16x32_bf16 v[34:37], v[204:207], v[212:215], v[34:37]
	v_mfma_f32_16x16x32_bf16 v[38:41], v[204:207], v[216:219], v[38:41]
	v_mfma_f32_16x16x32_bf16 v[2:5], v[204:207], v[220:223], v[2:5]
	v_mfma_f32_16x16x32_bf16 v[6:9], v[204:207], v[224:227], v[6:9]
	ds_read_b128 v[204:207], v244 offset:23104
	s_setprio 1
	s_waitcnt vmcnt(15)
	ds_write_b128 v98, v[136:139]
	s_waitcnt vmcnt(14)
	ds_write_b128 v98, v[140:143] offset:4608
	s_waitcnt lgkmcnt(9)
	v_mfma_f32_16x16x32_bf16 v[42:45], v[208:211], v[212:215], v[42:45]
	v_mfma_f32_16x16x32_bf16 v[46:49], v[208:211], v[216:219], v[46:49]
	v_mfma_f32_16x16x32_bf16 v[10:13], v[208:211], v[220:223], v[10:13]
	v_mfma_f32_16x16x32_bf16 v[14:17], v[208:211], v[224:227], v[14:17]
	ds_read_b128 v[208:211], v244 offset:25408
	s_waitcnt vmcnt(13)
	ds_write_b128 v98, v[144:147] offset:9216
	s_waitcnt vmcnt(12)
	ds_write_b128 v98, v[148:151] offset:13824
	s_waitcnt lgkmcnt(7)
	v_mfma_f32_16x16x32_bf16 v[50:53], v[196:199], v[228:231], v[50:53]
	v_mfma_f32_16x16x32_bf16 v[54:57], v[196:199], v[232:235], v[54:57]
	v_mfma_f32_16x16x32_bf16 v[18:21], v[196:199], v[236:239], v[18:21]
	v_mfma_f32_16x16x32_bf16 v[22:25], v[196:199], v[240:243], v[22:25]
	s_waitcnt vmcnt(11)
	ds_write_b128 v98, v[152:155] offset:36864
	s_waitcnt vmcnt(10)
	ds_write_b128 v98, v[156:159] offset:41472
	s_waitcnt lgkmcnt(8)
	v_mfma_f32_16x16x32_bf16 v[58:61], v[200:203], v[228:231], v[58:61]
	v_mfma_f32_16x16x32_bf16 v[62:65], v[200:203], v[232:235], v[62:65]
	v_mfma_f32_16x16x32_bf16 v[26:29], v[200:203], v[236:239], v[26:29]
	v_mfma_f32_16x16x32_bf16 v[30:33], v[200:203], v[240:243], v[30:33]
	s_waitcnt vmcnt(9)
	ds_write_b128 v98, v[160:163] offset:46080
	s_waitcnt vmcnt(8)
	ds_write_b128 v98, v[164:167] offset:50688
	s_waitcnt lgkmcnt(0)
	s_barrier
	ds_read_b128 v[212:215], v245 offset:36864
	ds_read_b128 v[196:199], v244
	ds_read_b128 v[216:219], v245 offset:39168
	ds_read_b128 v[220:223], v245 offset:41472
	ds_read_b128 v[224:227], v245 offset:43776
	ds_read_b128 v[200:203], v244 offset:2304
	s_setprio 0
	v_mfma_f32_16x16x32_bf16 v[34:37], v[204:207], v[228:231], v[34:37]
	v_mfma_f32_16x16x32_bf16 v[38:41], v[204:207], v[232:235], v[38:41]
	v_mfma_f32_16x16x32_bf16 v[2:5], v[204:207], v[236:239], v[2:5]
	v_mfma_f32_16x16x32_bf16 v[6:9], v[204:207], v[240:243], v[6:9]
	ds_read_b128 v[204:207], v244 offset:4608
	v_mfma_f32_16x16x32_bf16 v[42:45], v[208:211], v[228:231], v[42:45]
	v_mfma_f32_16x16x32_bf16 v[46:49], v[208:211], v[232:235], v[46:49]
	v_mfma_f32_16x16x32_bf16 v[10:13], v[208:211], v[236:239], v[10:13]
	v_mfma_f32_16x16x32_bf16 v[14:17], v[208:211], v[240:243], v[14:17]
	ds_read_b128 v[208:211], v244 offset:6912
	global_load_dwordx4 v[136:139], v[74:75], off offset:1280
	global_load_dwordx4 v[140:143], v[76:77], off offset:1280
	global_load_dwordx4 v[144:147], v[78:79], off offset:1280
	global_load_dwordx4 v[148:151], v[80:81], off offset:1280
	global_load_dwordx4 v[152:155], v[82:83], off offset:1280
	global_load_dwordx4 v[156:159], v[84:85], off offset:1280
	global_load_dwordx4 v[160:163], v[86:87], off offset:1280
	global_load_dwordx4 v[164:167], v[88:89], off offset:1280
	s_waitcnt lgkmcnt(6)
	v_mfma_f32_16x16x32_bf16 v[50:53], v[196:199], v[212:215], v[50:53]
	ds_read_b128 v[228:231], v245 offset:36928
	s_waitcnt lgkmcnt(6)
	v_mfma_f32_16x16x32_bf16 v[54:57], v[196:199], v[216:219], v[54:57]
	ds_read_b128 v[232:235], v245 offset:39232
	s_waitcnt lgkmcnt(6)
	v_mfma_f32_16x16x32_bf16 v[18:21], v[196:199], v[220:223], v[18:21]
	ds_read_b128 v[236:239], v245 offset:41536
	s_waitcnt lgkmcnt(6)
	v_mfma_f32_16x16x32_bf16 v[22:25], v[196:199], v[224:227], v[22:25]
	ds_read_b128 v[240:243], v245 offset:43840
	ds_read_b128 v[196:199], v244 offset:64
	s_waitcnt lgkmcnt(7)
	v_mfma_f32_16x16x32_bf16 v[58:61], v[200:203], v[212:215], v[58:61]
	v_mfma_f32_16x16x32_bf16 v[62:65], v[200:203], v[216:219], v[62:65]
	v_mfma_f32_16x16x32_bf16 v[26:29], v[200:203], v[220:223], v[26:29]
	v_mfma_f32_16x16x32_bf16 v[30:33], v[200:203], v[224:227], v[30:33]
	ds_read_b128 v[200:203], v244 offset:2368
	s_waitcnt lgkmcnt(7)
	v_mfma_f32_16x16x32_bf16 v[34:37], v[204:207], v[212:215], v[34:37]
	v_mfma_f32_16x16x32_bf16 v[38:41], v[204:207], v[216:219], v[38:41]
	v_mfma_f32_16x16x32_bf16 v[2:5], v[204:207], v[220:223], v[2:5]
	v_mfma_f32_16x16x32_bf16 v[6:9], v[204:207], v[224:227], v[6:9]
	ds_read_b128 v[204:207], v244 offset:4672
	s_setprio 1
	s_waitcnt vmcnt(15)
	ds_write_b128 v98, v[102:105] offset:18432
	s_waitcnt vmcnt(14)
	ds_write_b128 v98, v[106:109] offset:23040
	s_waitcnt lgkmcnt(9)
	v_mfma_f32_16x16x32_bf16 v[42:45], v[208:211], v[212:215], v[42:45]
	v_mfma_f32_16x16x32_bf16 v[46:49], v[208:211], v[216:219], v[46:49]
	v_mfma_f32_16x16x32_bf16 v[10:13], v[208:211], v[220:223], v[10:13]
	v_mfma_f32_16x16x32_bf16 v[14:17], v[208:211], v[224:227], v[14:17]
	ds_read_b128 v[208:211], v244 offset:6976
	s_waitcnt vmcnt(13)
	ds_write_b128 v98, v[110:113] offset:27648
	s_waitcnt vmcnt(12)
	ds_write_b128 v98, v[114:117] offset:32256
	s_waitcnt lgkmcnt(7)
	v_mfma_f32_16x16x32_bf16 v[50:53], v[196:199], v[228:231], v[50:53]
	v_mfma_f32_16x16x32_bf16 v[54:57], v[196:199], v[232:235], v[54:57]
	v_mfma_f32_16x16x32_bf16 v[18:21], v[196:199], v[236:239], v[18:21]
	v_mfma_f32_16x16x32_bf16 v[22:25], v[196:199], v[240:243], v[22:25]
	s_waitcnt vmcnt(11)
	ds_write_b128 v98, v[118:121] offset:55296
	s_waitcnt vmcnt(10)
	ds_write_b128 v98, v[122:125] offset:59904
	s_waitcnt lgkmcnt(8)
	v_mfma_f32_16x16x32_bf16 v[58:61], v[200:203], v[228:231], v[58:61]
	v_mfma_f32_16x16x32_bf16 v[62:65], v[200:203], v[232:235], v[62:65]
	v_mfma_f32_16x16x32_bf16 v[26:29], v[200:203], v[236:239], v[26:29]
	v_mfma_f32_16x16x32_bf16 v[30:33], v[200:203], v[240:243], v[30:33]
	s_waitcnt vmcnt(9)
	ds_write_b128 v98, v[126:129] offset:64512
	s_waitcnt vmcnt(8)
	ds_write_b128 v99, v[132:135] offset:32256
	s_waitcnt lgkmcnt(0)
	s_barrier
	ds_read_b128 v[212:215], v245 offset:55296
	ds_read_b128 v[196:199], v244 offset:18432
	ds_read_b128 v[216:219], v245 offset:57600
	ds_read_b128 v[220:223], v245 offset:59904
	ds_read_b128 v[224:227], v245 offset:62208
	ds_read_b128 v[200:203], v244 offset:20736
	s_setprio 0
	v_mfma_f32_16x16x32_bf16 v[34:37], v[204:207], v[228:231], v[34:37]
	v_mfma_f32_16x16x32_bf16 v[38:41], v[204:207], v[232:235], v[38:41]
	v_mfma_f32_16x16x32_bf16 v[2:5], v[204:207], v[236:239], v[2:5]
	v_mfma_f32_16x16x32_bf16 v[6:9], v[204:207], v[240:243], v[6:9]
	ds_read_b128 v[204:207], v244 offset:23040
	v_mfma_f32_16x16x32_bf16 v[42:45], v[208:211], v[228:231], v[42:45]
	v_mfma_f32_16x16x32_bf16 v[46:49], v[208:211], v[232:235], v[46:49]
	v_mfma_f32_16x16x32_bf16 v[10:13], v[208:211], v[236:239], v[10:13]
	v_mfma_f32_16x16x32_bf16 v[14:17], v[208:211], v[240:243], v[14:17]
	ds_read_b128 v[208:211], v244 offset:25344
	global_load_dwordx4 v[102:105], v[74:75], off offset:1408
	global_load_dwordx4 v[106:109], v[76:77], off offset:1408
	global_load_dwordx4 v[110:113], v[78:79], off offset:1408
	global_load_dwordx4 v[114:117], v[80:81], off offset:1408
	global_load_dwordx4 v[118:121], v[82:83], off offset:1408
	global_load_dwordx4 v[122:125], v[84:85], off offset:1408
	global_load_dwordx4 v[126:129], v[86:87], off offset:1408
	global_load_dwordx4 v[132:135], v[88:89], off offset:1408
	s_waitcnt lgkmcnt(6)
	v_mfma_f32_16x16x32_bf16 v[50:53], v[196:199], v[212:215], v[50:53]
	ds_read_b128 v[228:231], v245 offset:55360
	s_waitcnt lgkmcnt(6)
	v_mfma_f32_16x16x32_bf16 v[54:57], v[196:199], v[216:219], v[54:57]
	ds_read_b128 v[232:235], v245 offset:57664
	s_waitcnt lgkmcnt(6)
	v_mfma_f32_16x16x32_bf16 v[18:21], v[196:199], v[220:223], v[18:21]
	ds_read_b128 v[236:239], v245 offset:59968
	s_waitcnt lgkmcnt(6)
	v_mfma_f32_16x16x32_bf16 v[22:25], v[196:199], v[224:227], v[22:25]
	ds_read_b128 v[240:243], v245 offset:62272
	ds_read_b128 v[196:199], v244 offset:18496
	s_waitcnt lgkmcnt(7)
	v_mfma_f32_16x16x32_bf16 v[58:61], v[200:203], v[212:215], v[58:61]
	v_mfma_f32_16x16x32_bf16 v[62:65], v[200:203], v[216:219], v[62:65]
	v_mfma_f32_16x16x32_bf16 v[26:29], v[200:203], v[220:223], v[26:29]
	v_mfma_f32_16x16x32_bf16 v[30:33], v[200:203], v[224:227], v[30:33]
	ds_read_b128 v[200:203], v244 offset:20800
	s_waitcnt lgkmcnt(7)
	v_mfma_f32_16x16x32_bf16 v[34:37], v[204:207], v[212:215], v[34:37]
	v_mfma_f32_16x16x32_bf16 v[38:41], v[204:207], v[216:219], v[38:41]
	v_mfma_f32_16x16x32_bf16 v[2:5], v[204:207], v[220:223], v[2:5]
	v_mfma_f32_16x16x32_bf16 v[6:9], v[204:207], v[224:227], v[6:9]
	ds_read_b128 v[204:207], v244 offset:23104
	s_setprio 1
	s_waitcnt vmcnt(15)
	ds_write_b128 v98, v[136:139]
	s_waitcnt vmcnt(14)
	ds_write_b128 v98, v[140:143] offset:4608
	s_waitcnt lgkmcnt(9)
	v_mfma_f32_16x16x32_bf16 v[42:45], v[208:211], v[212:215], v[42:45]
	v_mfma_f32_16x16x32_bf16 v[46:49], v[208:211], v[216:219], v[46:49]
	v_mfma_f32_16x16x32_bf16 v[10:13], v[208:211], v[220:223], v[10:13]
	v_mfma_f32_16x16x32_bf16 v[14:17], v[208:211], v[224:227], v[14:17]
	ds_read_b128 v[208:211], v244 offset:25408
	s_waitcnt vmcnt(13)
	ds_write_b128 v98, v[144:147] offset:9216
	s_waitcnt vmcnt(12)
	ds_write_b128 v98, v[148:151] offset:13824
	s_waitcnt lgkmcnt(7)
	v_mfma_f32_16x16x32_bf16 v[50:53], v[196:199], v[228:231], v[50:53]
	v_mfma_f32_16x16x32_bf16 v[54:57], v[196:199], v[232:235], v[54:57]
	v_mfma_f32_16x16x32_bf16 v[18:21], v[196:199], v[236:239], v[18:21]
	v_mfma_f32_16x16x32_bf16 v[22:25], v[196:199], v[240:243], v[22:25]
	s_waitcnt vmcnt(11)
	ds_write_b128 v98, v[152:155] offset:36864
	s_waitcnt vmcnt(10)
	ds_write_b128 v98, v[156:159] offset:41472
	s_waitcnt lgkmcnt(8)
	v_mfma_f32_16x16x32_bf16 v[58:61], v[200:203], v[228:231], v[58:61]
	v_mfma_f32_16x16x32_bf16 v[62:65], v[200:203], v[232:235], v[62:65]
	v_mfma_f32_16x16x32_bf16 v[26:29], v[200:203], v[236:239], v[26:29]
	v_mfma_f32_16x16x32_bf16 v[30:33], v[200:203], v[240:243], v[30:33]
	s_waitcnt vmcnt(9)
	ds_write_b128 v98, v[160:163] offset:46080
	s_waitcnt vmcnt(8)
	ds_write_b128 v98, v[164:167] offset:50688
	s_waitcnt lgkmcnt(0)
	s_barrier
	ds_read_b128 v[212:215], v245 offset:36864
	ds_read_b128 v[196:199], v244
	ds_read_b128 v[216:219], v245 offset:39168
	ds_read_b128 v[220:223], v245 offset:41472
	ds_read_b128 v[224:227], v245 offset:43776
	ds_read_b128 v[200:203], v244 offset:2304
	s_setprio 0
	v_mfma_f32_16x16x32_bf16 v[34:37], v[204:207], v[228:231], v[34:37]
	v_mfma_f32_16x16x32_bf16 v[38:41], v[204:207], v[232:235], v[38:41]
	v_mfma_f32_16x16x32_bf16 v[2:5], v[204:207], v[236:239], v[2:5]
	v_mfma_f32_16x16x32_bf16 v[6:9], v[204:207], v[240:243], v[6:9]
	ds_read_b128 v[204:207], v244 offset:4608
	v_mfma_f32_16x16x32_bf16 v[42:45], v[208:211], v[228:231], v[42:45]
	v_mfma_f32_16x16x32_bf16 v[46:49], v[208:211], v[232:235], v[46:49]
	v_mfma_f32_16x16x32_bf16 v[10:13], v[208:211], v[236:239], v[10:13]
	v_mfma_f32_16x16x32_bf16 v[14:17], v[208:211], v[240:243], v[14:17]
	ds_read_b128 v[208:211], v244 offset:6912
	global_load_dwordx4 v[136:139], v[74:75], off offset:1536
	global_load_dwordx4 v[140:143], v[76:77], off offset:1536
	global_load_dwordx4 v[144:147], v[78:79], off offset:1536
	global_load_dwordx4 v[148:151], v[80:81], off offset:1536
	global_load_dwordx4 v[152:155], v[82:83], off offset:1536
	global_load_dwordx4 v[156:159], v[84:85], off offset:1536
	global_load_dwordx4 v[160:163], v[86:87], off offset:1536
	global_load_dwordx4 v[164:167], v[88:89], off offset:1536
	s_waitcnt lgkmcnt(6)
	v_mfma_f32_16x16x32_bf16 v[50:53], v[196:199], v[212:215], v[50:53]
	ds_read_b128 v[228:231], v245 offset:36928
	s_waitcnt lgkmcnt(6)
	v_mfma_f32_16x16x32_bf16 v[54:57], v[196:199], v[216:219], v[54:57]
	ds_read_b128 v[232:235], v245 offset:39232
	s_waitcnt lgkmcnt(6)
	v_mfma_f32_16x16x32_bf16 v[18:21], v[196:199], v[220:223], v[18:21]
	ds_read_b128 v[236:239], v245 offset:41536
	s_waitcnt lgkmcnt(6)
	v_mfma_f32_16x16x32_bf16 v[22:25], v[196:199], v[224:227], v[22:25]
	ds_read_b128 v[240:243], v245 offset:43840
	ds_read_b128 v[196:199], v244 offset:64
	s_waitcnt lgkmcnt(7)
	v_mfma_f32_16x16x32_bf16 v[58:61], v[200:203], v[212:215], v[58:61]
	v_mfma_f32_16x16x32_bf16 v[62:65], v[200:203], v[216:219], v[62:65]
	v_mfma_f32_16x16x32_bf16 v[26:29], v[200:203], v[220:223], v[26:29]
	v_mfma_f32_16x16x32_bf16 v[30:33], v[200:203], v[224:227], v[30:33]
	ds_read_b128 v[200:203], v244 offset:2368
	s_waitcnt lgkmcnt(7)
	v_mfma_f32_16x16x32_bf16 v[34:37], v[204:207], v[212:215], v[34:37]
	v_mfma_f32_16x16x32_bf16 v[38:41], v[204:207], v[216:219], v[38:41]
	v_mfma_f32_16x16x32_bf16 v[2:5], v[204:207], v[220:223], v[2:5]
	v_mfma_f32_16x16x32_bf16 v[6:9], v[204:207], v[224:227], v[6:9]
	ds_read_b128 v[204:207], v244 offset:4672
	s_setprio 1
	s_waitcnt vmcnt(15)
	ds_write_b128 v98, v[102:105] offset:18432
	s_waitcnt vmcnt(14)
	ds_write_b128 v98, v[106:109] offset:23040
	s_waitcnt lgkmcnt(9)
	v_mfma_f32_16x16x32_bf16 v[42:45], v[208:211], v[212:215], v[42:45]
	v_mfma_f32_16x16x32_bf16 v[46:49], v[208:211], v[216:219], v[46:49]
	v_mfma_f32_16x16x32_bf16 v[10:13], v[208:211], v[220:223], v[10:13]
	v_mfma_f32_16x16x32_bf16 v[14:17], v[208:211], v[224:227], v[14:17]
	ds_read_b128 v[208:211], v244 offset:6976
	s_waitcnt vmcnt(13)
	ds_write_b128 v98, v[110:113] offset:27648
	s_waitcnt vmcnt(12)
	ds_write_b128 v98, v[114:117] offset:32256
	s_waitcnt lgkmcnt(7)
	v_mfma_f32_16x16x32_bf16 v[50:53], v[196:199], v[228:231], v[50:53]
	v_mfma_f32_16x16x32_bf16 v[54:57], v[196:199], v[232:235], v[54:57]
	v_mfma_f32_16x16x32_bf16 v[18:21], v[196:199], v[236:239], v[18:21]
	v_mfma_f32_16x16x32_bf16 v[22:25], v[196:199], v[240:243], v[22:25]
	s_waitcnt vmcnt(11)
	ds_write_b128 v98, v[118:121] offset:55296
	s_waitcnt vmcnt(10)
	ds_write_b128 v98, v[122:125] offset:59904
	s_waitcnt lgkmcnt(8)
	v_mfma_f32_16x16x32_bf16 v[58:61], v[200:203], v[228:231], v[58:61]
	v_mfma_f32_16x16x32_bf16 v[62:65], v[200:203], v[232:235], v[62:65]
	v_mfma_f32_16x16x32_bf16 v[26:29], v[200:203], v[236:239], v[26:29]
	v_mfma_f32_16x16x32_bf16 v[30:33], v[200:203], v[240:243], v[30:33]
	s_waitcnt vmcnt(9)
	ds_write_b128 v98, v[126:129] offset:64512
	s_waitcnt vmcnt(8)
	ds_write_b128 v99, v[132:135] offset:32256
	s_waitcnt lgkmcnt(0)
	s_barrier
	ds_read_b128 v[212:215], v245 offset:55296
	ds_read_b128 v[196:199], v244 offset:18432
	ds_read_b128 v[216:219], v245 offset:57600
	ds_read_b128 v[220:223], v245 offset:59904
	ds_read_b128 v[224:227], v245 offset:62208
	ds_read_b128 v[200:203], v244 offset:20736
	s_setprio 0
	v_mfma_f32_16x16x32_bf16 v[34:37], v[204:207], v[228:231], v[34:37]
	v_mfma_f32_16x16x32_bf16 v[38:41], v[204:207], v[232:235], v[38:41]
	v_mfma_f32_16x16x32_bf16 v[2:5], v[204:207], v[236:239], v[2:5]
	v_mfma_f32_16x16x32_bf16 v[6:9], v[204:207], v[240:243], v[6:9]
	ds_read_b128 v[204:207], v244 offset:23040
	v_mfma_f32_16x16x32_bf16 v[42:45], v[208:211], v[228:231], v[42:45]
	v_mfma_f32_16x16x32_bf16 v[46:49], v[208:211], v[232:235], v[46:49]
	v_mfma_f32_16x16x32_bf16 v[10:13], v[208:211], v[236:239], v[10:13]
	v_mfma_f32_16x16x32_bf16 v[14:17], v[208:211], v[240:243], v[14:17]
	ds_read_b128 v[208:211], v244 offset:25344
	global_load_dwordx4 v[102:105], v[74:75], off offset:1664
	global_load_dwordx4 v[106:109], v[76:77], off offset:1664
	global_load_dwordx4 v[110:113], v[78:79], off offset:1664
	global_load_dwordx4 v[114:117], v[80:81], off offset:1664
	global_load_dwordx4 v[118:121], v[82:83], off offset:1664
	global_load_dwordx4 v[122:125], v[84:85], off offset:1664
	global_load_dwordx4 v[126:129], v[86:87], off offset:1664
	global_load_dwordx4 v[132:135], v[88:89], off offset:1664
	s_waitcnt lgkmcnt(6)
	v_mfma_f32_16x16x32_bf16 v[50:53], v[196:199], v[212:215], v[50:53]
	ds_read_b128 v[228:231], v245 offset:55360
	s_waitcnt lgkmcnt(6)
	v_mfma_f32_16x16x32_bf16 v[54:57], v[196:199], v[216:219], v[54:57]
	ds_read_b128 v[232:235], v245 offset:57664
	s_waitcnt lgkmcnt(6)
	v_mfma_f32_16x16x32_bf16 v[18:21], v[196:199], v[220:223], v[18:21]
	ds_read_b128 v[236:239], v245 offset:59968
	s_waitcnt lgkmcnt(6)
	v_mfma_f32_16x16x32_bf16 v[22:25], v[196:199], v[224:227], v[22:25]
	ds_read_b128 v[240:243], v245 offset:62272
	ds_read_b128 v[196:199], v244 offset:18496
	s_waitcnt lgkmcnt(7)
	v_mfma_f32_16x16x32_bf16 v[58:61], v[200:203], v[212:215], v[58:61]
	v_mfma_f32_16x16x32_bf16 v[62:65], v[200:203], v[216:219], v[62:65]
	v_mfma_f32_16x16x32_bf16 v[26:29], v[200:203], v[220:223], v[26:29]
	v_mfma_f32_16x16x32_bf16 v[30:33], v[200:203], v[224:227], v[30:33]
	ds_read_b128 v[200:203], v244 offset:20800
	s_waitcnt lgkmcnt(7)
	v_mfma_f32_16x16x32_bf16 v[34:37], v[204:207], v[212:215], v[34:37]
	v_mfma_f32_16x16x32_bf16 v[38:41], v[204:207], v[216:219], v[38:41]
	v_mfma_f32_16x16x32_bf16 v[2:5], v[204:207], v[220:223], v[2:5]
	v_mfma_f32_16x16x32_bf16 v[6:9], v[204:207], v[224:227], v[6:9]
	ds_read_b128 v[204:207], v244 offset:23104
	s_setprio 1
	s_waitcnt vmcnt(15)
	ds_write_b128 v98, v[136:139]
	s_waitcnt vmcnt(14)
	ds_write_b128 v98, v[140:143] offset:4608
	s_waitcnt lgkmcnt(9)
	v_mfma_f32_16x16x32_bf16 v[42:45], v[208:211], v[212:215], v[42:45]
	v_mfma_f32_16x16x32_bf16 v[46:49], v[208:211], v[216:219], v[46:49]
	v_mfma_f32_16x16x32_bf16 v[10:13], v[208:211], v[220:223], v[10:13]
	v_mfma_f32_16x16x32_bf16 v[14:17], v[208:211], v[224:227], v[14:17]
	ds_read_b128 v[208:211], v244 offset:25408
	s_waitcnt vmcnt(13)
	ds_write_b128 v98, v[144:147] offset:9216
	s_waitcnt vmcnt(12)
	ds_write_b128 v98, v[148:151] offset:13824
	s_waitcnt lgkmcnt(7)
	v_mfma_f32_16x16x32_bf16 v[50:53], v[196:199], v[228:231], v[50:53]
	v_mfma_f32_16x16x32_bf16 v[54:57], v[196:199], v[232:235], v[54:57]
	v_mfma_f32_16x16x32_bf16 v[18:21], v[196:199], v[236:239], v[18:21]
	v_mfma_f32_16x16x32_bf16 v[22:25], v[196:199], v[240:243], v[22:25]
	s_waitcnt vmcnt(11)
	ds_write_b128 v98, v[152:155] offset:36864
	s_waitcnt vmcnt(10)
	ds_write_b128 v98, v[156:159] offset:41472
	s_waitcnt lgkmcnt(8)
	v_mfma_f32_16x16x32_bf16 v[58:61], v[200:203], v[228:231], v[58:61]
	v_mfma_f32_16x16x32_bf16 v[62:65], v[200:203], v[232:235], v[62:65]
	v_mfma_f32_16x16x32_bf16 v[26:29], v[200:203], v[236:239], v[26:29]
	v_mfma_f32_16x16x32_bf16 v[30:33], v[200:203], v[240:243], v[30:33]
	s_waitcnt vmcnt(9)
	ds_write_b128 v98, v[160:163] offset:46080
	s_waitcnt vmcnt(8)
	ds_write_b128 v98, v[164:167] offset:50688
	s_waitcnt lgkmcnt(0)
	s_barrier
	ds_read_b128 v[212:215], v245 offset:36864
	ds_read_b128 v[196:199], v244
	ds_read_b128 v[216:219], v245 offset:39168
	ds_read_b128 v[220:223], v245 offset:41472
	ds_read_b128 v[224:227], v245 offset:43776
	ds_read_b128 v[200:203], v244 offset:2304
	s_setprio 0
	v_mfma_f32_16x16x32_bf16 v[34:37], v[204:207], v[228:231], v[34:37]
	v_mfma_f32_16x16x32_bf16 v[38:41], v[204:207], v[232:235], v[38:41]
	v_mfma_f32_16x16x32_bf16 v[2:5], v[204:207], v[236:239], v[2:5]
	v_mfma_f32_16x16x32_bf16 v[6:9], v[204:207], v[240:243], v[6:9]
	ds_read_b128 v[204:207], v244 offset:4608
	v_mfma_f32_16x16x32_bf16 v[42:45], v[208:211], v[228:231], v[42:45]
	v_mfma_f32_16x16x32_bf16 v[46:49], v[208:211], v[232:235], v[46:49]
	v_mfma_f32_16x16x32_bf16 v[10:13], v[208:211], v[236:239], v[10:13]
	v_mfma_f32_16x16x32_bf16 v[14:17], v[208:211], v[240:243], v[14:17]
	ds_read_b128 v[208:211], v244 offset:6912
	global_load_dwordx4 v[136:139], v[74:75], off offset:1792
	global_load_dwordx4 v[140:143], v[76:77], off offset:1792
	global_load_dwordx4 v[144:147], v[78:79], off offset:1792
	global_load_dwordx4 v[148:151], v[80:81], off offset:1792
	global_load_dwordx4 v[152:155], v[82:83], off offset:1792
	global_load_dwordx4 v[156:159], v[84:85], off offset:1792
	global_load_dwordx4 v[160:163], v[86:87], off offset:1792
	global_load_dwordx4 v[164:167], v[88:89], off offset:1792
	s_waitcnt lgkmcnt(6)
	v_mfma_f32_16x16x32_bf16 v[50:53], v[196:199], v[212:215], v[50:53]
	ds_read_b128 v[228:231], v245 offset:36928
	s_waitcnt lgkmcnt(6)
	v_mfma_f32_16x16x32_bf16 v[54:57], v[196:199], v[216:219], v[54:57]
	ds_read_b128 v[232:235], v245 offset:39232
	s_waitcnt lgkmcnt(6)
	v_mfma_f32_16x16x32_bf16 v[18:21], v[196:199], v[220:223], v[18:21]
	ds_read_b128 v[236:239], v245 offset:41536
	s_waitcnt lgkmcnt(6)
	v_mfma_f32_16x16x32_bf16 v[22:25], v[196:199], v[224:227], v[22:25]
	ds_read_b128 v[240:243], v245 offset:43840
	ds_read_b128 v[196:199], v244 offset:64
	s_waitcnt lgkmcnt(7)
	v_mfma_f32_16x16x32_bf16 v[58:61], v[200:203], v[212:215], v[58:61]
	v_mfma_f32_16x16x32_bf16 v[62:65], v[200:203], v[216:219], v[62:65]
	v_mfma_f32_16x16x32_bf16 v[26:29], v[200:203], v[220:223], v[26:29]
	v_mfma_f32_16x16x32_bf16 v[30:33], v[200:203], v[224:227], v[30:33]
	ds_read_b128 v[200:203], v244 offset:2368
	s_waitcnt lgkmcnt(7)
	v_mfma_f32_16x16x32_bf16 v[34:37], v[204:207], v[212:215], v[34:37]
	v_mfma_f32_16x16x32_bf16 v[38:41], v[204:207], v[216:219], v[38:41]
	v_mfma_f32_16x16x32_bf16 v[2:5], v[204:207], v[220:223], v[2:5]
	v_mfma_f32_16x16x32_bf16 v[6:9], v[204:207], v[224:227], v[6:9]
	ds_read_b128 v[204:207], v244 offset:4672
	s_setprio 1
	s_waitcnt vmcnt(15)
	ds_write_b128 v98, v[102:105] offset:18432
	s_waitcnt vmcnt(14)
	ds_write_b128 v98, v[106:109] offset:23040
	s_waitcnt lgkmcnt(9)
	v_mfma_f32_16x16x32_bf16 v[42:45], v[208:211], v[212:215], v[42:45]
	v_mfma_f32_16x16x32_bf16 v[46:49], v[208:211], v[216:219], v[46:49]
	v_mfma_f32_16x16x32_bf16 v[10:13], v[208:211], v[220:223], v[10:13]
	v_mfma_f32_16x16x32_bf16 v[14:17], v[208:211], v[224:227], v[14:17]
	ds_read_b128 v[208:211], v244 offset:6976
	s_waitcnt vmcnt(13)
	ds_write_b128 v98, v[110:113] offset:27648
	s_waitcnt vmcnt(12)
	ds_write_b128 v98, v[114:117] offset:32256
	s_waitcnt lgkmcnt(7)
	v_mfma_f32_16x16x32_bf16 v[50:53], v[196:199], v[228:231], v[50:53]
	v_mfma_f32_16x16x32_bf16 v[54:57], v[196:199], v[232:235], v[54:57]
	v_mfma_f32_16x16x32_bf16 v[18:21], v[196:199], v[236:239], v[18:21]
	v_mfma_f32_16x16x32_bf16 v[22:25], v[196:199], v[240:243], v[22:25]
	s_waitcnt vmcnt(11)
	ds_write_b128 v98, v[118:121] offset:55296
	s_waitcnt vmcnt(10)
	ds_write_b128 v98, v[122:125] offset:59904
	s_waitcnt lgkmcnt(8)
	v_mfma_f32_16x16x32_bf16 v[58:61], v[200:203], v[228:231], v[58:61]
	v_mfma_f32_16x16x32_bf16 v[62:65], v[200:203], v[232:235], v[62:65]
	v_mfma_f32_16x16x32_bf16 v[26:29], v[200:203], v[236:239], v[26:29]
	v_mfma_f32_16x16x32_bf16 v[30:33], v[200:203], v[240:243], v[30:33]
	s_waitcnt vmcnt(9)
	ds_write_b128 v98, v[126:129] offset:64512
	s_waitcnt vmcnt(8)
	ds_write_b128 v99, v[132:135] offset:32256
	s_waitcnt lgkmcnt(0)
	s_barrier
	ds_read_b128 v[212:215], v245 offset:55296
	ds_read_b128 v[196:199], v244 offset:18432
	ds_read_b128 v[216:219], v245 offset:57600
	ds_read_b128 v[220:223], v245 offset:59904
	ds_read_b128 v[224:227], v245 offset:62208
	ds_read_b128 v[200:203], v244 offset:20736
	s_setprio 0
	v_mfma_f32_16x16x32_bf16 v[34:37], v[204:207], v[228:231], v[34:37]
	v_mfma_f32_16x16x32_bf16 v[38:41], v[204:207], v[232:235], v[38:41]
	v_mfma_f32_16x16x32_bf16 v[2:5], v[204:207], v[236:239], v[2:5]
	v_mfma_f32_16x16x32_bf16 v[6:9], v[204:207], v[240:243], v[6:9]
	ds_read_b128 v[204:207], v244 offset:23040
	v_mfma_f32_16x16x32_bf16 v[42:45], v[208:211], v[228:231], v[42:45]
	v_mfma_f32_16x16x32_bf16 v[46:49], v[208:211], v[232:235], v[46:49]
	v_mfma_f32_16x16x32_bf16 v[10:13], v[208:211], v[236:239], v[10:13]
	v_mfma_f32_16x16x32_bf16 v[14:17], v[208:211], v[240:243], v[14:17]
	ds_read_b128 v[208:211], v244 offset:25344
	global_load_dwordx4 v[102:105], v[74:75], off offset:1920
	s_nop 0
	global_load_dwordx4 v[74:77], v[76:77], off offset:1920
	s_nop 0
	global_load_dwordx4 v[106:109], v[78:79], off offset:1920
	s_nop 0
	global_load_dwordx4 v[78:81], v[80:81], off offset:1920
	s_nop 0
	global_load_dwordx4 v[110:113], v[82:83], off offset:1920
	s_nop 0
	global_load_dwordx4 v[82:85], v[84:85], off offset:1920
	s_nop 0
	global_load_dwordx4 v[114:117], v[86:87], off offset:1920
	s_nop 0
	global_load_dwordx4 v[86:89], v[88:89], off offset:1920
	s_waitcnt lgkmcnt(6)
	v_mfma_f32_16x16x32_bf16 v[50:53], v[196:199], v[212:215], v[50:53]
	ds_read_b128 v[228:231], v245 offset:55360
	s_waitcnt lgkmcnt(6)
	v_mfma_f32_16x16x32_bf16 v[54:57], v[196:199], v[216:219], v[54:57]
	ds_read_b128 v[232:235], v245 offset:57664
	s_waitcnt lgkmcnt(6)
	v_mfma_f32_16x16x32_bf16 v[18:21], v[196:199], v[220:223], v[18:21]
	ds_read_b128 v[236:239], v245 offset:59968
	s_waitcnt lgkmcnt(6)
	v_mfma_f32_16x16x32_bf16 v[22:25], v[196:199], v[224:227], v[22:25]
	ds_read_b128 v[240:243], v245 offset:62272
	ds_read_b128 v[196:199], v244 offset:18496
	s_waitcnt lgkmcnt(7)
	v_mfma_f32_16x16x32_bf16 v[58:61], v[200:203], v[212:215], v[58:61]
	v_mfma_f32_16x16x32_bf16 v[62:65], v[200:203], v[216:219], v[62:65]
	v_mfma_f32_16x16x32_bf16 v[26:29], v[200:203], v[220:223], v[26:29]
	v_mfma_f32_16x16x32_bf16 v[30:33], v[200:203], v[224:227], v[30:33]
	ds_read_b128 v[200:203], v244 offset:20800
	s_waitcnt lgkmcnt(7)
	v_mfma_f32_16x16x32_bf16 v[34:37], v[204:207], v[212:215], v[34:37]
	v_mfma_f32_16x16x32_bf16 v[38:41], v[204:207], v[216:219], v[38:41]
	v_mfma_f32_16x16x32_bf16 v[2:5], v[204:207], v[220:223], v[2:5]
	v_mfma_f32_16x16x32_bf16 v[6:9], v[204:207], v[224:227], v[6:9]
	ds_read_b128 v[204:207], v244 offset:23104
	s_setprio 1
	s_waitcnt vmcnt(15)
	ds_write_b128 v98, v[136:139]
	s_waitcnt vmcnt(14)
	ds_write_b128 v98, v[140:143] offset:4608
	s_waitcnt lgkmcnt(9)
	v_mfma_f32_16x16x32_bf16 v[42:45], v[208:211], v[212:215], v[42:45]
	v_mfma_f32_16x16x32_bf16 v[46:49], v[208:211], v[216:219], v[46:49]
	v_mfma_f32_16x16x32_bf16 v[10:13], v[208:211], v[220:223], v[10:13]
	v_mfma_f32_16x16x32_bf16 v[14:17], v[208:211], v[224:227], v[14:17]
	ds_read_b128 v[208:211], v244 offset:25408
	s_waitcnt vmcnt(13)
	ds_write_b128 v98, v[144:147] offset:9216
	s_waitcnt vmcnt(12)
	ds_write_b128 v98, v[148:151] offset:13824
	s_waitcnt lgkmcnt(7)
	v_mfma_f32_16x16x32_bf16 v[50:53], v[196:199], v[228:231], v[50:53]
	v_mfma_f32_16x16x32_bf16 v[54:57], v[196:199], v[232:235], v[54:57]
	v_mfma_f32_16x16x32_bf16 v[18:21], v[196:199], v[236:239], v[18:21]
	v_mfma_f32_16x16x32_bf16 v[22:25], v[196:199], v[240:243], v[22:25]
	s_waitcnt vmcnt(11)
	ds_write_b128 v98, v[152:155] offset:36864
	s_waitcnt vmcnt(10)
	ds_write_b128 v98, v[156:159] offset:41472
	s_waitcnt lgkmcnt(8)
	v_mfma_f32_16x16x32_bf16 v[58:61], v[200:203], v[228:231], v[58:61]
	v_mfma_f32_16x16x32_bf16 v[62:65], v[200:203], v[232:235], v[62:65]
	v_mfma_f32_16x16x32_bf16 v[26:29], v[200:203], v[236:239], v[26:29]
	v_mfma_f32_16x16x32_bf16 v[30:33], v[200:203], v[240:243], v[30:33]
	s_waitcnt vmcnt(9)
	ds_write_b128 v98, v[160:163] offset:46080
	s_waitcnt vmcnt(8)
	ds_write_b128 v98, v[164:167] offset:50688
	s_waitcnt lgkmcnt(0)
	s_barrier
	ds_read_b128 v[212:215], v245 offset:36864
	ds_read_b128 v[196:199], v244
	ds_read_b128 v[216:219], v245 offset:39168
	ds_read_b128 v[220:223], v245 offset:41472
	ds_read_b128 v[224:227], v245 offset:43776
	ds_read_b128 v[200:203], v244 offset:2304
	s_setprio 0
	v_mfma_f32_16x16x32_bf16 v[34:37], v[204:207], v[228:231], v[34:37]
	v_mfma_f32_16x16x32_bf16 v[38:41], v[204:207], v[232:235], v[38:41]
	v_mfma_f32_16x16x32_bf16 v[2:5], v[204:207], v[236:239], v[2:5]
	v_mfma_f32_16x16x32_bf16 v[6:9], v[204:207], v[240:243], v[6:9]
	ds_read_b128 v[204:207], v244 offset:4608
	v_mfma_f32_16x16x32_bf16 v[42:45], v[208:211], v[228:231], v[42:45]
	v_mfma_f32_16x16x32_bf16 v[46:49], v[208:211], v[232:235], v[46:49]
	v_mfma_f32_16x16x32_bf16 v[10:13], v[208:211], v[236:239], v[10:13]
	v_mfma_f32_16x16x32_bf16 v[14:17], v[208:211], v[240:243], v[14:17]
	ds_read_b128 v[208:211], v244 offset:6912
	s_waitcnt lgkmcnt(6)
	v_mfma_f32_16x16x32_bf16 v[50:53], v[196:199], v[212:215], v[50:53]
	ds_read_b128 v[228:231], v245 offset:36928
	s_waitcnt lgkmcnt(6)
	v_mfma_f32_16x16x32_bf16 v[54:57], v[196:199], v[216:219], v[54:57]
	ds_read_b128 v[232:235], v245 offset:39232
	s_waitcnt lgkmcnt(6)
	v_mfma_f32_16x16x32_bf16 v[18:21], v[196:199], v[220:223], v[18:21]
	ds_read_b128 v[236:239], v245 offset:41536
	s_waitcnt lgkmcnt(6)
	v_mfma_f32_16x16x32_bf16 v[22:25], v[196:199], v[224:227], v[22:25]
	ds_read_b128 v[240:243], v245 offset:43840
	ds_read_b128 v[196:199], v244 offset:64
	s_waitcnt lgkmcnt(7)
	v_mfma_f32_16x16x32_bf16 v[58:61], v[200:203], v[212:215], v[58:61]
	v_mfma_f32_16x16x32_bf16 v[62:65], v[200:203], v[216:219], v[62:65]
	v_mfma_f32_16x16x32_bf16 v[26:29], v[200:203], v[220:223], v[26:29]
	v_mfma_f32_16x16x32_bf16 v[30:33], v[200:203], v[224:227], v[30:33]
	ds_read_b128 v[200:203], v244 offset:2368
	s_waitcnt lgkmcnt(7)
	v_mfma_f32_16x16x32_bf16 v[34:37], v[204:207], v[212:215], v[34:37]
	v_mfma_f32_16x16x32_bf16 v[38:41], v[204:207], v[216:219], v[38:41]
	v_mfma_f32_16x16x32_bf16 v[2:5], v[204:207], v[220:223], v[2:5]
	v_mfma_f32_16x16x32_bf16 v[6:9], v[204:207], v[224:227], v[6:9]
	ds_read_b128 v[204:207], v244 offset:4672
	s_setprio 1
	s_waitcnt vmcnt(7)
	ds_write_b128 v98, v[102:105] offset:18432
	s_waitcnt vmcnt(6)
	ds_write_b128 v98, v[74:77] offset:23040
	s_waitcnt lgkmcnt(9)
	v_mfma_f32_16x16x32_bf16 v[42:45], v[208:211], v[212:215], v[42:45]
	v_mfma_f32_16x16x32_bf16 v[46:49], v[208:211], v[216:219], v[46:49]
	v_mfma_f32_16x16x32_bf16 v[10:13], v[208:211], v[220:223], v[10:13]
	v_mfma_f32_16x16x32_bf16 v[14:17], v[208:211], v[224:227], v[14:17]
	ds_read_b128 v[208:211], v244 offset:6976
	s_waitcnt vmcnt(5)
	ds_write_b128 v98, v[106:109] offset:27648
	s_waitcnt vmcnt(4)
	ds_write_b128 v98, v[78:81] offset:32256
	s_waitcnt lgkmcnt(7)
	v_mfma_f32_16x16x32_bf16 v[50:53], v[196:199], v[228:231], v[50:53]
	v_mfma_f32_16x16x32_bf16 v[54:57], v[196:199], v[232:235], v[54:57]
	v_mfma_f32_16x16x32_bf16 v[18:21], v[196:199], v[236:239], v[18:21]
	v_mfma_f32_16x16x32_bf16 v[22:25], v[196:199], v[240:243], v[22:25]
	s_waitcnt vmcnt(3)
	ds_write_b128 v98, v[110:113] offset:55296
	s_waitcnt vmcnt(2)
	ds_write_b128 v98, v[82:85] offset:59904
	s_waitcnt lgkmcnt(8)
	v_mfma_f32_16x16x32_bf16 v[58:61], v[200:203], v[228:231], v[58:61]
	v_mfma_f32_16x16x32_bf16 v[62:65], v[200:203], v[232:235], v[62:65]
	v_mfma_f32_16x16x32_bf16 v[26:29], v[200:203], v[236:239], v[26:29]
	v_mfma_f32_16x16x32_bf16 v[30:33], v[200:203], v[240:243], v[30:33]
	s_waitcnt vmcnt(1)
	ds_write_b128 v98, v[114:117] offset:64512
	s_waitcnt vmcnt(0)
	ds_write_b128 v99, v[86:89] offset:32256
	s_waitcnt lgkmcnt(0)
	s_barrier
	ds_read_b128 v[212:215], v245 offset:55296
	ds_read_b128 v[196:199], v244 offset:18432
	ds_read_b128 v[216:219], v245 offset:57600
	ds_read_b128 v[220:223], v245 offset:59904
	ds_read_b128 v[224:227], v245 offset:62208
	ds_read_b128 v[200:203], v244 offset:20736
	s_setprio 0
	v_mfma_f32_16x16x32_bf16 v[34:37], v[204:207], v[228:231], v[34:37]
	v_mfma_f32_16x16x32_bf16 v[38:41], v[204:207], v[232:235], v[38:41]
	v_mfma_f32_16x16x32_bf16 v[2:5], v[204:207], v[236:239], v[2:5]
	v_mfma_f32_16x16x32_bf16 v[6:9], v[204:207], v[240:243], v[6:9]
	ds_read_b128 v[204:207], v244 offset:23040
	v_mfma_f32_16x16x32_bf16 v[42:45], v[208:211], v[228:231], v[42:45]
	v_mfma_f32_16x16x32_bf16 v[46:49], v[208:211], v[232:235], v[46:49]
	v_mfma_f32_16x16x32_bf16 v[10:13], v[208:211], v[236:239], v[10:13]
	v_mfma_f32_16x16x32_bf16 v[14:17], v[208:211], v[240:243], v[14:17]
	ds_read_b128 v[208:211], v244 offset:25344
	s_waitcnt lgkmcnt(6)
	v_mfma_f32_16x16x32_bf16 v[50:53], v[196:199], v[212:215], v[50:53]
	ds_read_b128 v[228:231], v245 offset:55360
	s_waitcnt lgkmcnt(6)
	v_mfma_f32_16x16x32_bf16 v[54:57], v[196:199], v[216:219], v[54:57]
	ds_read_b128 v[232:235], v245 offset:57664
	s_waitcnt lgkmcnt(6)
	v_mfma_f32_16x16x32_bf16 v[18:21], v[196:199], v[220:223], v[18:21]
	ds_read_b128 v[236:239], v245 offset:59968
	s_waitcnt lgkmcnt(6)
	v_mfma_f32_16x16x32_bf16 v[22:25], v[196:199], v[224:227], v[22:25]
	ds_read_b128 v[240:243], v245 offset:62272
	ds_read_b128 v[196:199], v244 offset:18496
	s_waitcnt lgkmcnt(7)
	v_mfma_f32_16x16x32_bf16 v[58:61], v[200:203], v[212:215], v[58:61]
	v_mfma_f32_16x16x32_bf16 v[62:65], v[200:203], v[216:219], v[62:65]
	v_mfma_f32_16x16x32_bf16 v[26:29], v[200:203], v[220:223], v[26:29]
	v_mfma_f32_16x16x32_bf16 v[30:33], v[200:203], v[224:227], v[30:33]
	ds_read_b128 v[200:203], v244 offset:20800
	s_waitcnt lgkmcnt(7)
	v_mfma_f32_16x16x32_bf16 v[34:37], v[204:207], v[212:215], v[34:37]
	v_mfma_f32_16x16x32_bf16 v[38:41], v[204:207], v[216:219], v[38:41]
	v_mfma_f32_16x16x32_bf16 v[2:5], v[204:207], v[220:223], v[2:5]
	v_mfma_f32_16x16x32_bf16 v[6:9], v[204:207], v[224:227], v[6:9]
	ds_read_b128 v[204:207], v244 offset:23104
	s_waitcnt lgkmcnt(7)
	v_mfma_f32_16x16x32_bf16 v[42:45], v[208:211], v[212:215], v[42:45]
	v_mfma_f32_16x16x32_bf16 v[46:49], v[208:211], v[216:219], v[46:49]
	v_mfma_f32_16x16x32_bf16 v[10:13], v[208:211], v[220:223], v[10:13]
	v_mfma_f32_16x16x32_bf16 v[14:17], v[208:211], v[224:227], v[14:17]
	ds_read_b128 v[208:211], v244 offset:25408
	s_waitcnt lgkmcnt(3)
	v_mfma_f32_16x16x32_bf16 v[50:53], v[196:199], v[228:231], v[50:53]
	v_mfma_f32_16x16x32_bf16 v[54:57], v[196:199], v[232:235], v[54:57]
	v_mfma_f32_16x16x32_bf16 v[18:21], v[196:199], v[236:239], v[18:21]
	v_mfma_f32_16x16x32_bf16 v[22:25], v[196:199], v[240:243], v[22:25]
	s_waitcnt lgkmcnt(2)
	v_mfma_f32_16x16x32_bf16 v[58:61], v[200:203], v[228:231], v[58:61]
	v_mfma_f32_16x16x32_bf16 v[62:65], v[200:203], v[232:235], v[62:65]
	v_mfma_f32_16x16x32_bf16 v[26:29], v[200:203], v[236:239], v[26:29]
	v_mfma_f32_16x16x32_bf16 v[30:33], v[200:203], v[240:243], v[30:33]
	s_lshr_b32 s14, s2, 3
	s_bfe_u32 s13, s2, 0x10002
	s_cmp_lt_i32 s14, 1
	s_mov_b64 s[2:3], -1
	s_waitcnt lgkmcnt(0)
	s_barrier
	v_mfma_f32_16x16x32_bf16 v[34:37], v[204:207], v[228:231], v[34:37]
	v_mfma_f32_16x16x32_bf16 v[38:41], v[204:207], v[232:235], v[38:41]
	v_mfma_f32_16x16x32_bf16 v[2:5], v[204:207], v[236:239], v[2:5]
	v_mfma_f32_16x16x32_bf16 v[6:9], v[204:207], v[240:243], v[6:9]
	v_mfma_f32_16x16x32_bf16 v[42:45], v[208:211], v[228:231], v[42:45]
	v_mfma_f32_16x16x32_bf16 v[46:49], v[208:211], v[232:235], v[46:49]
	v_mfma_f32_16x16x32_bf16 v[10:13], v[208:211], v[236:239], v[10:13]
	v_mfma_f32_16x16x32_bf16 v[14:17], v[208:211], v[240:243], v[14:17]
	s_nop 7
	v_permlane16_swap_b32_e32 v50, v54
	v_permlane16_swap_b32_e32 v51, v55
	v_permlane16_swap_b32_e32 v52, v56
	v_permlane16_swap_b32_e32 v53, v57
	v_permlane16_swap_b32_e32 v58, v62
	v_permlane16_swap_b32_e32 v59, v63
	v_permlane16_swap_b32_e32 v60, v64
	v_permlane16_swap_b32_e32 v61, v65
	v_permlane16_swap_b32_e32 v18, v22
	v_permlane16_swap_b32_e32 v19, v23
	v_permlane16_swap_b32_e32 v20, v24
	v_permlane16_swap_b32_e32 v21, v25
	v_permlane16_swap_b32_e32 v26, v30
	v_permlane16_swap_b32_e32 v27, v31
	v_permlane16_swap_b32_e32 v28, v32
	v_permlane16_swap_b32_e32 v29, v33
	v_permlane16_swap_b32_e32 v34, v38
	v_permlane16_swap_b32_e32 v35, v39
	v_permlane16_swap_b32_e32 v36, v40
	v_permlane16_swap_b32_e32 v37, v41
	v_permlane16_swap_b32_e32 v42, v46
	v_permlane16_swap_b32_e32 v43, v47
	v_permlane16_swap_b32_e32 v44, v48
	v_permlane16_swap_b32_e32 v45, v49
	v_permlane16_swap_b32_e32 v2, v6
	v_permlane16_swap_b32_e32 v3, v7
	v_permlane16_swap_b32_e32 v4, v8
	v_permlane16_swap_b32_e32 v5, v9
	v_permlane16_swap_b32_e32 v10, v14
	v_permlane16_swap_b32_e32 v11, v15
	v_permlane16_swap_b32_e32 v12, v16
	v_permlane16_swap_b32_e32 v13, v17
	v_permlane32_swap_b32_e32 v50, v54
	v_permlane32_swap_b32_e32 v51, v55
	v_permlane32_swap_b32_e32 v52, v56
	v_permlane32_swap_b32_e32 v53, v57
	v_permlane32_swap_b32_e32 v58, v62
	v_permlane32_swap_b32_e32 v59, v63
	v_permlane32_swap_b32_e32 v60, v64
	v_permlane32_swap_b32_e32 v61, v65
	v_permlane32_swap_b32_e32 v18, v22
	v_permlane32_swap_b32_e32 v19, v23
	v_permlane32_swap_b32_e32 v20, v24
	v_permlane32_swap_b32_e32 v21, v25
	v_permlane32_swap_b32_e32 v26, v30
	v_permlane32_swap_b32_e32 v27, v31
	v_permlane32_swap_b32_e32 v28, v32
	v_permlane32_swap_b32_e32 v29, v33
	v_permlane32_swap_b32_e32 v34, v38
	v_permlane32_swap_b32_e32 v35, v39
	v_permlane32_swap_b32_e32 v36, v40
	v_permlane32_swap_b32_e32 v37, v41
	v_permlane32_swap_b32_e32 v42, v46
	v_permlane32_swap_b32_e32 v43, v47
	v_permlane32_swap_b32_e32 v44, v48
	v_permlane32_swap_b32_e32 v45, v49
	v_permlane32_swap_b32_e32 v2, v6
	v_permlane32_swap_b32_e32 v3, v7
	v_permlane32_swap_b32_e32 v4, v8
	v_permlane32_swap_b32_e32 v5, v9
	v_permlane32_swap_b32_e32 v10, v14
	v_permlane32_swap_b32_e32 v11, v15
	v_permlane32_swap_b32_e32 v12, v16
	v_permlane32_swap_b32_e32 v13, v17
	s_cbranch_scc1 .LBB0_1647
	s_and_b32 s2, 0xffff, s14
	s_cmp_lg_u32 s2, 1
	s_mov_b64 s[2:3], -1
	s_cbranch_scc0 .LBB0_1644
	s_cmp_eq_u32 s13, 0
	s_cselect_b32 s12, 3, 10
	s_mov_b64 s[2:3], 0

.LBB0_1720:
	s_lshr_b32 s8, s0, 2
	s_lshl_b32 s0, s0, 7
	s_and_b32 s7, s0, 0x180
	v_or_b32_e32 v2, s7, v93
	v_lshlrev_b32_e32 v74, 10, v2
	s_add_i32 s8, s8, s4
	v_lshl_add_u64 v[66:67], v[76:77], 0, v[74:75]
	v_add_lshl_u32 v74, s7, v94, 10
	s_lshl_b32 s0, s8, 7
	v_lshl_add_u64 v[68:69], v[76:77], 0, v[74:75]
	v_add_lshl_u32 v74, s7, v95, 10
	v_lshl_add_u64 v[70:71], v[76:77], 0, v[74:75]
	v_add_lshl_u32 v74, s7, v96, 10
	v_or_b32_e32 v2, s0, v93
	v_lshl_add_u64 v[72:73], v[76:77], 0, v[74:75]
	v_lshlrev_b32_e32 v74, 10, v2
	v_lshl_add_u64 v[84:85], v[78:79], 0, v[74:75]
	v_add_lshl_u32 v74, s0, v94, 10
	v_lshl_add_u64 v[86:87], v[78:79], 0, v[74:75]
	v_add_lshl_u32 v74, s0, v95, 10
	v_lshl_add_u64 v[88:89], v[78:79], 0, v[74:75]
	v_add_lshl_u32 v74, s0, v96, 10
	v_lshl_add_u64 v[90:91], v[78:79], 0, v[74:75]
	global_load_dwordx4 v[2:5], v[66:67], off
	global_load_dwordx4 v[6:9], v[68:69], off
	global_load_dwordx4 v[10:13], v[70:71], off
	global_load_dwordx4 v[14:17], v[72:73], off
	global_load_dwordx4 v[18:21], v[84:85], off
	global_load_dwordx4 v[22:25], v[86:87], off
	global_load_dwordx4 v[26:29], v[88:89], off
	global_load_dwordx4 v[30:33], v[90:91], off
	global_load_dwordx4 v[102:105], v[66:67], off offset:128
	global_load_dwordx4 v[106:109], v[68:69], off offset:128
	global_load_dwordx4 v[110:113], v[70:71], off offset:128
	global_load_dwordx4 v[114:117], v[72:73], off offset:128
	global_load_dwordx4 v[118:121], v[84:85], off offset:128
	global_load_dwordx4 v[122:125], v[86:87], off offset:128
	global_load_dwordx4 v[126:129], v[88:89], off offset:128
	global_load_dwordx4 v[132:135], v[90:91], off offset:128
	s_waitcnt vmcnt(15)
	ds_write_b128 v100, v[2:5]
	s_waitcnt vmcnt(14)
	ds_write_b128 v100, v[6:9] offset:4608
	s_waitcnt vmcnt(13)
	ds_write_b128 v100, v[10:13] offset:9216
	s_waitcnt vmcnt(12)
	ds_write_b128 v100, v[14:17] offset:13824
	s_waitcnt vmcnt(11)
	ds_write_b128 v100, v[18:21] offset:36864
	s_waitcnt vmcnt(10)
	ds_write_b128 v100, v[22:25] offset:41472
	s_waitcnt vmcnt(9)
	ds_write_b128 v100, v[26:29] offset:46080
	s_waitcnt vmcnt(8)
	ds_write_b128 v100, v[30:33] offset:50688
	s_waitcnt lgkmcnt(0)
	s_barrier
	global_load_dwordx4 v[136:139], v[66:67], off offset:256
	global_load_dwordx4 v[140:143], v[68:69], off offset:256
	global_load_dwordx4 v[144:147], v[70:71], off offset:256
	global_load_dwordx4 v[148:151], v[72:73], off offset:256
	global_load_dwordx4 v[152:155], v[84:85], off offset:256
	global_load_dwordx4 v[156:159], v[86:87], off offset:256
	global_load_dwordx4 v[160:163], v[88:89], off offset:256
	global_load_dwordx4 v[164:167], v[90:91], off offset:256
	v_and_b32_e32 v246, 15, v1
	v_add_u32_e32 v246, 4, v246
	v_bfe_u32 v246, v246, 3, 1
	v_bfe_u32 v249, v1, 4, 2
	v_xor_b32_e32 v246, v246, v249
	v_bfe_u32 v249, v1, 5, 1
	v_sub_u32_e32 v246, v246, v249
	v_lshlrev_b32_e32 v246, 4, v246
	v_bfe_u32 v249, v1, 4, 1
	v_mul_u32_u24_e32 v249, 0x900, v249
	v_sub_u32_e32 v246, v246, v249
	v_add_u32_e32 v244, v246, v98
	v_add_u32_e32 v245, v246, v99
	ds_read_b128 v[212:215], v245 offset:36864
	ds_read_b128 v[196:199], v244
	ds_read_b128 v[216:219], v245 offset:39168
	ds_read_b128 v[220:223], v245 offset:41472
	ds_read_b128 v[224:227], v245 offset:43776
	ds_read_b128 v[200:203], v244 offset:2304
	ds_read_b128 v[204:207], v244 offset:4608
	ds_read_b128 v[208:211], v244 offset:6912
	s_waitcnt lgkmcnt(6)
	v_mfma_f32_16x16x32_bf16 v[50:53], v[196:199], v[212:215], 0
	ds_read_b128 v[228:231], v245 offset:36928
	s_waitcnt lgkmcnt(6)
	v_mfma_f32_16x16x32_bf16 v[54:57], v[196:199], v[216:219], 0
	ds_read_b128 v[232:235], v245 offset:39232
	s_waitcnt lgkmcnt(6)
	v_mfma_f32_16x16x32_bf16 v[18:21], v[196:199], v[220:223], 0
	ds_read_b128 v[236:239], v245 offset:41536
	s_waitcnt lgkmcnt(6)
	v_mfma_f32_16x16x32_bf16 v[22:25], v[196:199], v[224:227], 0
	ds_read_b128 v[240:243], v245 offset:43840
	ds_read_b128 v[196:199], v244 offset:64
	s_waitcnt lgkmcnt(7)
	v_mfma_f32_16x16x32_bf16 v[58:61], v[200:203], v[212:215], 0
	v_mfma_f32_16x16x32_bf16 v[62:65], v[200:203], v[216:219], 0
	v_mfma_f32_16x16x32_bf16 v[26:29], v[200:203], v[220:223], 0
	v_mfma_f32_16x16x32_bf16 v[30:33], v[200:203], v[224:227], 0
	ds_read_b128 v[200:203], v244 offset:2368
	s_waitcnt lgkmcnt(7)
	v_mfma_f32_16x16x32_bf16 v[34:37], v[204:207], v[212:215], 0
	v_mfma_f32_16x16x32_bf16 v[38:41], v[204:207], v[216:219], 0
	v_mfma_f32_16x16x32_bf16 v[2:5], v[204:207], v[220:223], 0
	v_mfma_f32_16x16x32_bf16 v[6:9], v[204:207], v[224:227], 0
	ds_read_b128 v[204:207], v244 offset:4672
	s_setprio 1
	s_waitcnt vmcnt(15)
	ds_write_b128 v100, v[102:105] offset:18432
	s_waitcnt vmcnt(14)
	ds_write_b128 v100, v[106:109] offset:23040
	s_waitcnt lgkmcnt(9)
	v_mfma_f32_16x16x32_bf16 v[42:45], v[208:211], v[212:215], 0
	v_mfma_f32_16x16x32_bf16 v[46:49], v[208:211], v[216:219], 0
	v_mfma_f32_16x16x32_bf16 v[10:13], v[208:211], v[220:223], 0
	v_mfma_f32_16x16x32_bf16 v[14:17], v[208:211], v[224:227], 0
	ds_read_b128 v[208:211], v244 offset:6976
	s_waitcnt vmcnt(13)
	ds_write_b128 v100, v[110:113] offset:27648
	s_waitcnt vmcnt(12)
	ds_write_b128 v100, v[114:117] offset:32256
	s_waitcnt lgkmcnt(7)
	v_mfma_f32_16x16x32_bf16 v[50:53], v[196:199], v[228:231], v[50:53]
	v_mfma_f32_16x16x32_bf16 v[54:57], v[196:199], v[232:235], v[54:57]
	v_mfma_f32_16x16x32_bf16 v[18:21], v[196:199], v[236:239], v[18:21]
	v_mfma_f32_16x16x32_bf16 v[22:25], v[196:199], v[240:243], v[22:25]
	s_waitcnt vmcnt(11)
	ds_write_b128 v100, v[118:121] offset:55296
	s_waitcnt vmcnt(10)
	ds_write_b128 v100, v[122:125] offset:59904
	s_waitcnt lgkmcnt(8)
	v_mfma_f32_16x16x32_bf16 v[58:61], v[200:203], v[228:231], v[58:61]
	v_mfma_f32_16x16x32_bf16 v[62:65], v[200:203], v[232:235], v[62:65]
	v_mfma_f32_16x16x32_bf16 v[26:29], v[200:203], v[236:239], v[26:29]
	v_mfma_f32_16x16x32_bf16 v[30:33], v[200:203], v[240:243], v[30:33]
	s_waitcnt vmcnt(9)
	ds_write_b128 v100, v[126:129] offset:64512
	s_waitcnt vmcnt(8)
	ds_write_b128 v101, v[132:135] offset:32256
	s_waitcnt lgkmcnt(0)
	s_barrier
	ds_read_b128 v[212:215], v245 offset:55296
	ds_read_b128 v[196:199], v244 offset:18432
	ds_read_b128 v[216:219], v245 offset:57600
	ds_read_b128 v[220:223], v245 offset:59904
	ds_read_b128 v[224:227], v245 offset:62208
	ds_read_b128 v[200:203], v244 offset:20736
	s_setprio 0
	v_mfma_f32_16x16x32_bf16 v[34:37], v[204:207], v[228:231], v[34:37]
	v_mfma_f32_16x16x32_bf16 v[38:41], v[204:207], v[232:235], v[38:41]
	v_mfma_f32_16x16x32_bf16 v[2:5], v[204:207], v[236:239], v[2:5]
	v_mfma_f32_16x16x32_bf16 v[6:9], v[204:207], v[240:243], v[6:9]
	ds_read_b128 v[204:207], v244 offset:23040
	v_mfma_f32_16x16x32_bf16 v[42:45], v[208:211], v[228:231], v[42:45]
	v_mfma_f32_16x16x32_bf16 v[46:49], v[208:211], v[232:235], v[46:49]
	v_mfma_f32_16x16x32_bf16 v[10:13], v[208:211], v[236:239], v[10:13]
	v_mfma_f32_16x16x32_bf16 v[14:17], v[208:211], v[240:243], v[14:17]
	ds_read_b128 v[208:211], v244 offset:25344
	global_load_dwordx4 v[102:105], v[66:67], off offset:384
	global_load_dwordx4 v[106:109], v[68:69], off offset:384
	global_load_dwordx4 v[110:113], v[70:71], off offset:384
	global_load_dwordx4 v[114:117], v[72:73], off offset:384
	global_load_dwordx4 v[118:121], v[84:85], off offset:384
	global_load_dwordx4 v[122:125], v[86:87], off offset:384
	global_load_dwordx4 v[126:129], v[88:89], off offset:384
	global_load_dwordx4 v[132:135], v[90:91], off offset:384
	s_waitcnt lgkmcnt(6)
	v_mfma_f32_16x16x32_bf16 v[50:53], v[196:199], v[212:215], v[50:53]
	ds_read_b128 v[228:231], v245 offset:55360
	s_waitcnt lgkmcnt(6)
	v_mfma_f32_16x16x32_bf16 v[54:57], v[196:199], v[216:219], v[54:57]
	ds_read_b128 v[232:235], v245 offset:57664
	s_waitcnt lgkmcnt(6)
	v_mfma_f32_16x16x32_bf16 v[18:21], v[196:199], v[220:223], v[18:21]
	ds_read_b128 v[236:239], v245 offset:59968
	s_waitcnt lgkmcnt(6)
	v_mfma_f32_16x16x32_bf16 v[22:25], v[196:199], v[224:227], v[22:25]
	ds_read_b128 v[240:243], v245 offset:62272
	ds_read_b128 v[196:199], v244 offset:18496
	s_waitcnt lgkmcnt(7)
	v_mfma_f32_16x16x32_bf16 v[58:61], v[200:203], v[212:215], v[58:61]
	v_mfma_f32_16x16x32_bf16 v[62:65], v[200:203], v[216:219], v[62:65]
	v_mfma_f32_16x16x32_bf16 v[26:29], v[200:203], v[220:223], v[26:29]
	v_mfma_f32_16x16x32_bf16 v[30:33], v[200:203], v[224:227], v[30:33]
	ds_read_b128 v[200:203], v244 offset:20800
	s_waitcnt lgkmcnt(7)
	v_mfma_f32_16x16x32_bf16 v[34:37], v[204:207], v[212:215], v[34:37]
	v_mfma_f32_16x16x32_bf16 v[38:41], v[204:207], v[216:219], v[38:41]
	v_mfma_f32_16x16x32_bf16 v[2:5], v[204:207], v[220:223], v[2:5]
	v_mfma_f32_16x16x32_bf16 v[6:9], v[204:207], v[224:227], v[6:9]
	ds_read_b128 v[204:207], v244 offset:23104
	s_setprio 1
	s_waitcnt vmcnt(15)
	ds_write_b128 v100, v[136:139]
	s_waitcnt vmcnt(14)
	ds_write_b128 v100, v[140:143] offset:4608
	s_waitcnt lgkmcnt(9)
	v_mfma_f32_16x16x32_bf16 v[42:45], v[208:211], v[212:215], v[42:45]
	v_mfma_f32_16x16x32_bf16 v[46:49], v[208:211], v[216:219], v[46:49]
	v_mfma_f32_16x16x32_bf16 v[10:13], v[208:211], v[220:223], v[10:13]
	v_mfma_f32_16x16x32_bf16 v[14:17], v[208:211], v[224:227], v[14:17]
	ds_read_b128 v[208:211], v244 offset:25408
	s_waitcnt vmcnt(13)
	ds_write_b128 v100, v[144:147] offset:9216
	s_waitcnt vmcnt(12)
	ds_write_b128 v100, v[148:151] offset:13824
	s_waitcnt lgkmcnt(7)
	v_mfma_f32_16x16x32_bf16 v[50:53], v[196:199], v[228:231], v[50:53]
	v_mfma_f32_16x16x32_bf16 v[54:57], v[196:199], v[232:235], v[54:57]
	v_mfma_f32_16x16x32_bf16 v[18:21], v[196:199], v[236:239], v[18:21]
	v_mfma_f32_16x16x32_bf16 v[22:25], v[196:199], v[240:243], v[22:25]
	s_waitcnt vmcnt(11)
	ds_write_b128 v100, v[152:155] offset:36864
	s_waitcnt vmcnt(10)
	ds_write_b128 v100, v[156:159] offset:41472
	s_waitcnt lgkmcnt(8)
	v_mfma_f32_16x16x32_bf16 v[58:61], v[200:203], v[228:231], v[58:61]
	v_mfma_f32_16x16x32_bf16 v[62:65], v[200:203], v[232:235], v[62:65]
	v_mfma_f32_16x16x32_bf16 v[26:29], v[200:203], v[236:239], v[26:29]
	v_mfma_f32_16x16x32_bf16 v[30:33], v[200:203], v[240:243], v[30:33]
	s_waitcnt vmcnt(9)
	ds_write_b128 v100, v[160:163] offset:46080
	s_waitcnt vmcnt(8)
	ds_write_b128 v100, v[164:167] offset:50688
	s_waitcnt lgkmcnt(0)
	s_barrier
	ds_read_b128 v[212:215], v245 offset:36864
	ds_read_b128 v[196:199], v244
	ds_read_b128 v[216:219], v245 offset:39168
	ds_read_b128 v[220:223], v245 offset:41472
	ds_read_b128 v[224:227], v245 offset:43776
	ds_read_b128 v[200:203], v244 offset:2304
	s_setprio 0
	v_mfma_f32_16x16x32_bf16 v[34:37], v[204:207], v[228:231], v[34:37]
	v_mfma_f32_16x16x32_bf16 v[38:41], v[204:207], v[232:235], v[38:41]
	v_mfma_f32_16x16x32_bf16 v[2:5], v[204:207], v[236:239], v[2:5]
	v_mfma_f32_16x16x32_bf16 v[6:9], v[204:207], v[240:243], v[6:9]
	ds_read_b128 v[204:207], v244 offset:4608
	v_mfma_f32_16x16x32_bf16 v[42:45], v[208:211], v[228:231], v[42:45]
	v_mfma_f32_16x16x32_bf16 v[46:49], v[208:211], v[232:235], v[46:49]
	v_mfma_f32_16x16x32_bf16 v[10:13], v[208:211], v[236:239], v[10:13]
	v_mfma_f32_16x16x32_bf16 v[14:17], v[208:211], v[240:243], v[14:17]
	ds_read_b128 v[208:211], v244 offset:6912
	global_load_dwordx4 v[136:139], v[66:67], off offset:512
	global_load_dwordx4 v[140:143], v[68:69], off offset:512
	global_load_dwordx4 v[144:147], v[70:71], off offset:512
	global_load_dwordx4 v[148:151], v[72:73], off offset:512
	global_load_dwordx4 v[152:155], v[84:85], off offset:512
	global_load_dwordx4 v[156:159], v[86:87], off offset:512
	global_load_dwordx4 v[160:163], v[88:89], off offset:512
	global_load_dwordx4 v[164:167], v[90:91], off offset:512
	s_waitcnt lgkmcnt(6)
	v_mfma_f32_16x16x32_bf16 v[50:53], v[196:199], v[212:215], v[50:53]
	ds_read_b128 v[228:231], v245 offset:36928
	s_waitcnt lgkmcnt(6)
	v_mfma_f32_16x16x32_bf16 v[54:57], v[196:199], v[216:219], v[54:57]
	ds_read_b128 v[232:235], v245 offset:39232
	s_waitcnt lgkmcnt(6)
	v_mfma_f32_16x16x32_bf16 v[18:21], v[196:199], v[220:223], v[18:21]
	ds_read_b128 v[236:239], v245 offset:41536
	s_waitcnt lgkmcnt(6)
	v_mfma_f32_16x16x32_bf16 v[22:25], v[196:199], v[224:227], v[22:25]
	ds_read_b128 v[240:243], v245 offset:43840
	ds_read_b128 v[196:199], v244 offset:64
	s_waitcnt lgkmcnt(7)
	v_mfma_f32_16x16x32_bf16 v[58:61], v[200:203], v[212:215], v[58:61]
	v_mfma_f32_16x16x32_bf16 v[62:65], v[200:203], v[216:219], v[62:65]
	v_mfma_f32_16x16x32_bf16 v[26:29], v[200:203], v[220:223], v[26:29]
	v_mfma_f32_16x16x32_bf16 v[30:33], v[200:203], v[224:227], v[30:33]
	ds_read_b128 v[200:203], v244 offset:2368
	s_waitcnt lgkmcnt(7)
	v_mfma_f32_16x16x32_bf16 v[34:37], v[204:207], v[212:215], v[34:37]
	v_mfma_f32_16x16x32_bf16 v[38:41], v[204:207], v[216:219], v[38:41]
	v_mfma_f32_16x16x32_bf16 v[2:5], v[204:207], v[220:223], v[2:5]
	v_mfma_f32_16x16x32_bf16 v[6:9], v[204:207], v[224:227], v[6:9]
	ds_read_b128 v[204:207], v244 offset:4672
	s_setprio 1
	s_waitcnt vmcnt(15)
	ds_write_b128 v100, v[102:105] offset:18432
	s_waitcnt vmcnt(14)
	ds_write_b128 v100, v[106:109] offset:23040
	s_waitcnt lgkmcnt(9)
	v_mfma_f32_16x16x32_bf16 v[42:45], v[208:211], v[212:215], v[42:45]
	v_mfma_f32_16x16x32_bf16 v[46:49], v[208:211], v[216:219], v[46:49]
	v_mfma_f32_16x16x32_bf16 v[10:13], v[208:211], v[220:223], v[10:13]
	v_mfma_f32_16x16x32_bf16 v[14:17], v[208:211], v[224:227], v[14:17]
	ds_read_b128 v[208:211], v244 offset:6976
	s_waitcnt vmcnt(13)
	ds_write_b128 v100, v[110:113] offset:27648
	s_waitcnt vmcnt(12)
	ds_write_b128 v100, v[114:117] offset:32256
	s_waitcnt lgkmcnt(7)
	v_mfma_f32_16x16x32_bf16 v[50:53], v[196:199], v[228:231], v[50:53]
	v_mfma_f32_16x16x32_bf16 v[54:57], v[196:199], v[232:235], v[54:57]
	v_mfma_f32_16x16x32_bf16 v[18:21], v[196:199], v[236:239], v[18:21]
	v_mfma_f32_16x16x32_bf16 v[22:25], v[196:199], v[240:243], v[22:25]
	s_waitcnt vmcnt(11)
	ds_write_b128 v100, v[118:121] offset:55296
	s_waitcnt vmcnt(10)
	ds_write_b128 v100, v[122:125] offset:59904
	s_waitcnt lgkmcnt(8)
	v_mfma_f32_16x16x32_bf16 v[58:61], v[200:203], v[228:231], v[58:61]
	v_mfma_f32_16x16x32_bf16 v[62:65], v[200:203], v[232:235], v[62:65]
	v_mfma_f32_16x16x32_bf16 v[26:29], v[200:203], v[236:239], v[26:29]
	v_mfma_f32_16x16x32_bf16 v[30:33], v[200:203], v[240:243], v[30:33]
	s_waitcnt vmcnt(9)
	ds_write_b128 v100, v[126:129] offset:64512
	s_waitcnt vmcnt(8)
	ds_write_b128 v101, v[132:135] offset:32256
	s_waitcnt lgkmcnt(0)
	s_barrier
	ds_read_b128 v[212:215], v245 offset:55296
	ds_read_b128 v[196:199], v244 offset:18432
	ds_read_b128 v[216:219], v245 offset:57600
	ds_read_b128 v[220:223], v245 offset:59904
	ds_read_b128 v[224:227], v245 offset:62208
	ds_read_b128 v[200:203], v244 offset:20736
	s_setprio 0
	v_mfma_f32_16x16x32_bf16 v[34:37], v[204:207], v[228:231], v[34:37]
	v_mfma_f32_16x16x32_bf16 v[38:41], v[204:207], v[232:235], v[38:41]
	v_mfma_f32_16x16x32_bf16 v[2:5], v[204:207], v[236:239], v[2:5]
	v_mfma_f32_16x16x32_bf16 v[6:9], v[204:207], v[240:243], v[6:9]
	ds_read_b128 v[204:207], v244 offset:23040
	v_mfma_f32_16x16x32_bf16 v[42:45], v[208:211], v[228:231], v[42:45]
	v_mfma_f32_16x16x32_bf16 v[46:49], v[208:211], v[232:235], v[46:49]
	v_mfma_f32_16x16x32_bf16 v[10:13], v[208:211], v[236:239], v[10:13]
	v_mfma_f32_16x16x32_bf16 v[14:17], v[208:211], v[240:243], v[14:17]
	ds_read_b128 v[208:211], v244 offset:25344
	global_load_dwordx4 v[102:105], v[66:67], off offset:640
	global_load_dwordx4 v[106:109], v[68:69], off offset:640
	global_load_dwordx4 v[110:113], v[70:71], off offset:640
	global_load_dwordx4 v[114:117], v[72:73], off offset:640
	global_load_dwordx4 v[118:121], v[84:85], off offset:640
	global_load_dwordx4 v[122:125], v[86:87], off offset:640
	global_load_dwordx4 v[126:129], v[88:89], off offset:640
	global_load_dwordx4 v[132:135], v[90:91], off offset:640
	s_waitcnt lgkmcnt(6)
	v_mfma_f32_16x16x32_bf16 v[50:53], v[196:199], v[212:215], v[50:53]
	ds_read_b128 v[228:231], v245 offset:55360
	s_waitcnt lgkmcnt(6)
	v_mfma_f32_16x16x32_bf16 v[54:57], v[196:199], v[216:219], v[54:57]
	ds_read_b128 v[232:235], v245 offset:57664
	s_waitcnt lgkmcnt(6)
	v_mfma_f32_16x16x32_bf16 v[18:21], v[196:199], v[220:223], v[18:21]
	ds_read_b128 v[236:239], v245 offset:59968
	s_waitcnt lgkmcnt(6)
	v_mfma_f32_16x16x32_bf16 v[22:25], v[196:199], v[224:227], v[22:25]
	ds_read_b128 v[240:243], v245 offset:62272
	ds_read_b128 v[196:199], v244 offset:18496
	s_waitcnt lgkmcnt(7)
	v_mfma_f32_16x16x32_bf16 v[58:61], v[200:203], v[212:215], v[58:61]
	v_mfma_f32_16x16x32_bf16 v[62:65], v[200:203], v[216:219], v[62:65]
	v_mfma_f32_16x16x32_bf16 v[26:29], v[200:203], v[220:223], v[26:29]
	v_mfma_f32_16x16x32_bf16 v[30:33], v[200:203], v[224:227], v[30:33]
	ds_read_b128 v[200:203], v244 offset:20800
	s_waitcnt lgkmcnt(7)
	v_mfma_f32_16x16x32_bf16 v[34:37], v[204:207], v[212:215], v[34:37]
	v_mfma_f32_16x16x32_bf16 v[38:41], v[204:207], v[216:219], v[38:41]
	v_mfma_f32_16x16x32_bf16 v[2:5], v[204:207], v[220:223], v[2:5]
	v_mfma_f32_16x16x32_bf16 v[6:9], v[204:207], v[224:227], v[6:9]
	ds_read_b128 v[204:207], v244 offset:23104
	s_setprio 1
	s_waitcnt vmcnt(15)
	ds_write_b128 v100, v[136:139]
	s_waitcnt vmcnt(14)
	ds_write_b128 v100, v[140:143] offset:4608
	s_waitcnt lgkmcnt(9)
	v_mfma_f32_16x16x32_bf16 v[42:45], v[208:211], v[212:215], v[42:45]
	v_mfma_f32_16x16x32_bf16 v[46:49], v[208:211], v[216:219], v[46:49]
	v_mfma_f32_16x16x32_bf16 v[10:13], v[208:211], v[220:223], v[10:13]
	v_mfma_f32_16x16x32_bf16 v[14:17], v[208:211], v[224:227], v[14:17]
	ds_read_b128 v[208:211], v244 offset:25408
	s_waitcnt vmcnt(13)
	ds_write_b128 v100, v[144:147] offset:9216
	s_waitcnt vmcnt(12)
	ds_write_b128 v100, v[148:151] offset:13824
	s_waitcnt lgkmcnt(7)
	v_mfma_f32_16x16x32_bf16 v[50:53], v[196:199], v[228:231], v[50:53]
	v_mfma_f32_16x16x32_bf16 v[54:57], v[196:199], v[232:235], v[54:57]
	v_mfma_f32_16x16x32_bf16 v[18:21], v[196:199], v[236:239], v[18:21]
	v_mfma_f32_16x16x32_bf16 v[22:25], v[196:199], v[240:243], v[22:25]
	s_waitcnt vmcnt(11)
	ds_write_b128 v100, v[152:155] offset:36864
	s_waitcnt vmcnt(10)
	ds_write_b128 v100, v[156:159] offset:41472
	s_waitcnt lgkmcnt(8)
	v_mfma_f32_16x16x32_bf16 v[58:61], v[200:203], v[228:231], v[58:61]
	v_mfma_f32_16x16x32_bf16 v[62:65], v[200:203], v[232:235], v[62:65]
	v_mfma_f32_16x16x32_bf16 v[26:29], v[200:203], v[236:239], v[26:29]
	v_mfma_f32_16x16x32_bf16 v[30:33], v[200:203], v[240:243], v[30:33]
	s_waitcnt vmcnt(9)
	ds_write_b128 v100, v[160:163] offset:46080
	s_waitcnt vmcnt(8)
	ds_write_b128 v100, v[164:167] offset:50688
	s_waitcnt lgkmcnt(0)
	s_barrier
	ds_read_b128 v[212:215], v245 offset:36864
	ds_read_b128 v[196:199], v244
	ds_read_b128 v[216:219], v245 offset:39168
	ds_read_b128 v[220:223], v245 offset:41472
	ds_read_b128 v[224:227], v245 offset:43776
	ds_read_b128 v[200:203], v244 offset:2304
	s_setprio 0
	v_mfma_f32_16x16x32_bf16 v[34:37], v[204:207], v[228:231], v[34:37]
	v_mfma_f32_16x16x32_bf16 v[38:41], v[204:207], v[232:235], v[38:41]
	v_mfma_f32_16x16x32_bf16 v[2:5], v[204:207], v[236:239], v[2:5]
	v_mfma_f32_16x16x32_bf16 v[6:9], v[204:207], v[240:243], v[6:9]
	ds_read_b128 v[204:207], v244 offset:4608
	v_mfma_f32_16x16x32_bf16 v[42:45], v[208:211], v[228:231], v[42:45]
	v_mfma_f32_16x16x32_bf16 v[46:49], v[208:211], v[232:235], v[46:49]
	v_mfma_f32_16x16x32_bf16 v[10:13], v[208:211], v[236:239], v[10:13]
	v_mfma_f32_16x16x32_bf16 v[14:17], v[208:211], v[240:243], v[14:17]
	ds_read_b128 v[208:211], v244 offset:6912
	global_load_dwordx4 v[136:139], v[66:67], off offset:768
	global_load_dwordx4 v[140:143], v[68:69], off offset:768
	global_load_dwordx4 v[144:147], v[70:71], off offset:768
	global_load_dwordx4 v[148:151], v[72:73], off offset:768
	global_load_dwordx4 v[152:155], v[84:85], off offset:768
	global_load_dwordx4 v[156:159], v[86:87], off offset:768
	global_load_dwordx4 v[160:163], v[88:89], off offset:768
	global_load_dwordx4 v[164:167], v[90:91], off offset:768
	s_waitcnt lgkmcnt(6)
	v_mfma_f32_16x16x32_bf16 v[50:53], v[196:199], v[212:215], v[50:53]
	ds_read_b128 v[228:231], v245 offset:36928
	s_waitcnt lgkmcnt(6)
	v_mfma_f32_16x16x32_bf16 v[54:57], v[196:199], v[216:219], v[54:57]
	ds_read_b128 v[232:235], v245 offset:39232
	s_waitcnt lgkmcnt(6)
	v_mfma_f32_16x16x32_bf16 v[18:21], v[196:199], v[220:223], v[18:21]
	ds_read_b128 v[236:239], v245 offset:41536
	s_waitcnt lgkmcnt(6)
	v_mfma_f32_16x16x32_bf16 v[22:25], v[196:199], v[224:227], v[22:25]
	ds_read_b128 v[240:243], v245 offset:43840
	ds_read_b128 v[196:199], v244 offset:64
	s_waitcnt lgkmcnt(7)
	v_mfma_f32_16x16x32_bf16 v[58:61], v[200:203], v[212:215], v[58:61]
	v_mfma_f32_16x16x32_bf16 v[62:65], v[200:203], v[216:219], v[62:65]
	v_mfma_f32_16x16x32_bf16 v[26:29], v[200:203], v[220:223], v[26:29]
	v_mfma_f32_16x16x32_bf16 v[30:33], v[200:203], v[224:227], v[30:33]
	ds_read_b128 v[200:203], v244 offset:2368
	s_waitcnt lgkmcnt(7)
	v_mfma_f32_16x16x32_bf16 v[34:37], v[204:207], v[212:215], v[34:37]
	v_mfma_f32_16x16x32_bf16 v[38:41], v[204:207], v[216:219], v[38:41]
	v_mfma_f32_16x16x32_bf16 v[2:5], v[204:207], v[220:223], v[2:5]
	v_mfma_f32_16x16x32_bf16 v[6:9], v[204:207], v[224:227], v[6:9]
	ds_read_b128 v[204:207], v244 offset:4672
	s_setprio 1
	s_waitcnt vmcnt(15)
	ds_write_b128 v100, v[102:105] offset:18432
	s_waitcnt vmcnt(14)
	ds_write_b128 v100, v[106:109] offset:23040
	s_waitcnt lgkmcnt(9)
	v_mfma_f32_16x16x32_bf16 v[42:45], v[208:211], v[212:215], v[42:45]
	v_mfma_f32_16x16x32_bf16 v[46:49], v[208:211], v[216:219], v[46:49]
	v_mfma_f32_16x16x32_bf16 v[10:13], v[208:211], v[220:223], v[10:13]
	v_mfma_f32_16x16x32_bf16 v[14:17], v[208:211], v[224:227], v[14:17]
	ds_read_b128 v[208:211], v244 offset:6976
	s_waitcnt vmcnt(13)
	ds_write_b128 v100, v[110:113] offset:27648
	s_waitcnt vmcnt(12)
	ds_write_b128 v100, v[114:117] offset:32256
	s_waitcnt lgkmcnt(7)
	v_mfma_f32_16x16x32_bf16 v[50:53], v[196:199], v[228:231], v[50:53]
	v_mfma_f32_16x16x32_bf16 v[54:57], v[196:199], v[232:235], v[54:57]
	v_mfma_f32_16x16x32_bf16 v[18:21], v[196:199], v[236:239], v[18:21]
	v_mfma_f32_16x16x32_bf16 v[22:25], v[196:199], v[240:243], v[22:25]
	s_waitcnt vmcnt(11)
	ds_write_b128 v100, v[118:121] offset:55296
	s_waitcnt vmcnt(10)
	ds_write_b128 v100, v[122:125] offset:59904
	s_waitcnt lgkmcnt(8)
	v_mfma_f32_16x16x32_bf16 v[58:61], v[200:203], v[228:231], v[58:61]
	v_mfma_f32_16x16x32_bf16 v[62:65], v[200:203], v[232:235], v[62:65]
	v_mfma_f32_16x16x32_bf16 v[26:29], v[200:203], v[236:239], v[26:29]
	v_mfma_f32_16x16x32_bf16 v[30:33], v[200:203], v[240:243], v[30:33]
	s_waitcnt vmcnt(9)
	ds_write_b128 v100, v[126:129] offset:64512
	s_waitcnt vmcnt(8)
	ds_write_b128 v101, v[132:135] offset:32256
	s_waitcnt lgkmcnt(0)
	s_barrier
	ds_read_b128 v[212:215], v245 offset:55296
	ds_read_b128 v[196:199], v244 offset:18432
	ds_read_b128 v[216:219], v245 offset:57600
	ds_read_b128 v[220:223], v245 offset:59904
	ds_read_b128 v[224:227], v245 offset:62208
	ds_read_b128 v[200:203], v244 offset:20736
	s_setprio 0
	v_mfma_f32_16x16x32_bf16 v[34:37], v[204:207], v[228:231], v[34:37]
	v_mfma_f32_16x16x32_bf16 v[38:41], v[204:207], v[232:235], v[38:41]
	v_mfma_f32_16x16x32_bf16 v[2:5], v[204:207], v[236:239], v[2:5]
	v_mfma_f32_16x16x32_bf16 v[6:9], v[204:207], v[240:243], v[6:9]
	ds_read_b128 v[204:207], v244 offset:23040
	v_mfma_f32_16x16x32_bf16 v[42:45], v[208:211], v[228:231], v[42:45]
	v_mfma_f32_16x16x32_bf16 v[46:49], v[208:211], v[232:235], v[46:49]
	v_mfma_f32_16x16x32_bf16 v[10:13], v[208:211], v[236:239], v[10:13]
	v_mfma_f32_16x16x32_bf16 v[14:17], v[208:211], v[240:243], v[14:17]
	ds_read_b128 v[208:211], v244 offset:25344
	global_load_dwordx4 v[102:105], v[66:67], off offset:896
	s_nop 0
	global_load_dwordx4 v[66:69], v[68:69], off offset:896
	s_nop 0
	global_load_dwordx4 v[106:109], v[70:71], off offset:896
	s_nop 0
	global_load_dwordx4 v[70:73], v[72:73], off offset:896
	s_nop 0
	global_load_dwordx4 v[110:113], v[84:85], off offset:896
	s_nop 0
	global_load_dwordx4 v[84:87], v[86:87], off offset:896
	s_nop 0
	global_load_dwordx4 v[114:117], v[88:89], off offset:896
	s_nop 0
	global_load_dwordx4 v[88:91], v[90:91], off offset:896
	s_waitcnt lgkmcnt(6)
	v_mfma_f32_16x16x32_bf16 v[50:53], v[196:199], v[212:215], v[50:53]
	ds_read_b128 v[228:231], v245 offset:55360
	s_waitcnt lgkmcnt(6)
	v_mfma_f32_16x16x32_bf16 v[54:57], v[196:199], v[216:219], v[54:57]
	ds_read_b128 v[232:235], v245 offset:57664
	s_waitcnt lgkmcnt(6)
	v_mfma_f32_16x16x32_bf16 v[18:21], v[196:199], v[220:223], v[18:21]
	ds_read_b128 v[236:239], v245 offset:59968
	s_waitcnt lgkmcnt(6)
	v_mfma_f32_16x16x32_bf16 v[22:25], v[196:199], v[224:227], v[22:25]
	ds_read_b128 v[240:243], v245 offset:62272
	ds_read_b128 v[196:199], v244 offset:18496
	s_waitcnt lgkmcnt(7)
	v_mfma_f32_16x16x32_bf16 v[58:61], v[200:203], v[212:215], v[58:61]
	v_mfma_f32_16x16x32_bf16 v[62:65], v[200:203], v[216:219], v[62:65]
	v_mfma_f32_16x16x32_bf16 v[26:29], v[200:203], v[220:223], v[26:29]
	v_mfma_f32_16x16x32_bf16 v[30:33], v[200:203], v[224:227], v[30:33]
	ds_read_b128 v[200:203], v244 offset:20800
	s_waitcnt lgkmcnt(7)
	v_mfma_f32_16x16x32_bf16 v[34:37], v[204:207], v[212:215], v[34:37]
	v_mfma_f32_16x16x32_bf16 v[38:41], v[204:207], v[216:219], v[38:41]
	v_mfma_f32_16x16x32_bf16 v[2:5], v[204:207], v[220:223], v[2:5]
	v_mfma_f32_16x16x32_bf16 v[6:9], v[204:207], v[224:227], v[6:9]
	ds_read_b128 v[204:207], v244 offset:23104
	s_setprio 1
	s_waitcnt vmcnt(15)
	ds_write_b128 v100, v[136:139]
	s_waitcnt vmcnt(14)
	ds_write_b128 v100, v[140:143] offset:4608
	s_waitcnt lgkmcnt(9)
	v_mfma_f32_16x16x32_bf16 v[42:45], v[208:211], v[212:215], v[42:45]
	v_mfma_f32_16x16x32_bf16 v[46:49], v[208:211], v[216:219], v[46:49]
	v_mfma_f32_16x16x32_bf16 v[10:13], v[208:211], v[220:223], v[10:13]
	v_mfma_f32_16x16x32_bf16 v[14:17], v[208:211], v[224:227], v[14:17]
	ds_read_b128 v[208:211], v244 offset:25408
	s_waitcnt vmcnt(13)
	ds_write_b128 v100, v[144:147] offset:9216
	s_waitcnt vmcnt(12)
	ds_write_b128 v100, v[148:151] offset:13824
	s_waitcnt lgkmcnt(7)
	v_mfma_f32_16x16x32_bf16 v[50:53], v[196:199], v[228:231], v[50:53]
	v_mfma_f32_16x16x32_bf16 v[54:57], v[196:199], v[232:235], v[54:57]
	v_mfma_f32_16x16x32_bf16 v[18:21], v[196:199], v[236:239], v[18:21]
	v_mfma_f32_16x16x32_bf16 v[22:25], v[196:199], v[240:243], v[22:25]
	s_waitcnt vmcnt(11)
	ds_write_b128 v100, v[152:155] offset:36864
	s_waitcnt vmcnt(10)
	ds_write_b128 v100, v[156:159] offset:41472
	s_waitcnt lgkmcnt(8)
	v_mfma_f32_16x16x32_bf16 v[58:61], v[200:203], v[228:231], v[58:61]
	v_mfma_f32_16x16x32_bf16 v[62:65], v[200:203], v[232:235], v[62:65]
	v_mfma_f32_16x16x32_bf16 v[26:29], v[200:203], v[236:239], v[26:29]
	v_mfma_f32_16x16x32_bf16 v[30:33], v[200:203], v[240:243], v[30:33]
	s_waitcnt vmcnt(9)
	ds_write_b128 v100, v[160:163] offset:46080
	s_waitcnt vmcnt(8)
	ds_write_b128 v100, v[164:167] offset:50688
	s_waitcnt lgkmcnt(0)
	s_barrier
	ds_read_b128 v[212:215], v245 offset:36864
	ds_read_b128 v[196:199], v244
	ds_read_b128 v[216:219], v245 offset:39168
	ds_read_b128 v[220:223], v245 offset:41472
	ds_read_b128 v[224:227], v245 offset:43776
	ds_read_b128 v[200:203], v244 offset:2304
	s_setprio 0
	v_mfma_f32_16x16x32_bf16 v[34:37], v[204:207], v[228:231], v[34:37]
	v_mfma_f32_16x16x32_bf16 v[38:41], v[204:207], v[232:235], v[38:41]
	v_mfma_f32_16x16x32_bf16 v[2:5], v[204:207], v[236:239], v[2:5]
	v_mfma_f32_16x16x32_bf16 v[6:9], v[204:207], v[240:243], v[6:9]
	ds_read_b128 v[204:207], v244 offset:4608
	v_mfma_f32_16x16x32_bf16 v[42:45], v[208:211], v[228:231], v[42:45]
	v_mfma_f32_16x16x32_bf16 v[46:49], v[208:211], v[232:235], v[46:49]
	v_mfma_f32_16x16x32_bf16 v[10:13], v[208:211], v[236:239], v[10:13]
	v_mfma_f32_16x16x32_bf16 v[14:17], v[208:211], v[240:243], v[14:17]
	ds_read_b128 v[208:211], v244 offset:6912
	s_waitcnt lgkmcnt(6)
	v_mfma_f32_16x16x32_bf16 v[50:53], v[196:199], v[212:215], v[50:53]
	ds_read_b128 v[228:231], v245 offset:36928
	s_waitcnt lgkmcnt(6)
	v_mfma_f32_16x16x32_bf16 v[54:57], v[196:199], v[216:219], v[54:57]
	ds_read_b128 v[232:235], v245 offset:39232
	s_waitcnt lgkmcnt(6)
	v_mfma_f32_16x16x32_bf16 v[18:21], v[196:199], v[220:223], v[18:21]
	ds_read_b128 v[236:239], v245 offset:41536
	s_waitcnt lgkmcnt(6)
	v_mfma_f32_16x16x32_bf16 v[22:25], v[196:199], v[224:227], v[22:25]
	ds_read_b128 v[240:243], v245 offset:43840
	ds_read_b128 v[196:199], v244 offset:64
	s_waitcnt lgkmcnt(7)
	v_mfma_f32_16x16x32_bf16 v[58:61], v[200:203], v[212:215], v[58:61]
	v_mfma_f32_16x16x32_bf16 v[62:65], v[200:203], v[216:219], v[62:65]
	v_mfma_f32_16x16x32_bf16 v[26:29], v[200:203], v[220:223], v[26:29]
	v_mfma_f32_16x16x32_bf16 v[30:33], v[200:203], v[224:227], v[30:33]
	ds_read_b128 v[200:203], v244 offset:2368
	s_waitcnt lgkmcnt(7)
	v_mfma_f32_16x16x32_bf16 v[34:37], v[204:207], v[212:215], v[34:37]
	v_mfma_f32_16x16x32_bf16 v[38:41], v[204:207], v[216:219], v[38:41]
	v_mfma_f32_16x16x32_bf16 v[2:5], v[204:207], v[220:223], v[2:5]
	v_mfma_f32_16x16x32_bf16 v[6:9], v[204:207], v[224:227], v[6:9]
	ds_read_b128 v[204:207], v244 offset:4672
	s_setprio 1
	s_waitcnt vmcnt(7)
	ds_write_b128 v100, v[102:105] offset:18432
	s_waitcnt vmcnt(6)
	ds_write_b128 v100, v[66:69] offset:23040
	s_waitcnt lgkmcnt(9)
	v_mfma_f32_16x16x32_bf16 v[42:45], v[208:211], v[212:215], v[42:45]
	v_mfma_f32_16x16x32_bf16 v[46:49], v[208:211], v[216:219], v[46:49]
	v_mfma_f32_16x16x32_bf16 v[10:13], v[208:211], v[220:223], v[10:13]
	v_mfma_f32_16x16x32_bf16 v[14:17], v[208:211], v[224:227], v[14:17]
	ds_read_b128 v[208:211], v244 offset:6976
	s_waitcnt vmcnt(5)
	ds_write_b128 v100, v[106:109] offset:27648
	s_waitcnt vmcnt(4)
	ds_write_b128 v100, v[70:73] offset:32256
	s_waitcnt lgkmcnt(7)
	v_mfma_f32_16x16x32_bf16 v[50:53], v[196:199], v[228:231], v[50:53]
	v_mfma_f32_16x16x32_bf16 v[54:57], v[196:199], v[232:235], v[54:57]
	v_mfma_f32_16x16x32_bf16 v[18:21], v[196:199], v[236:239], v[18:21]
	v_mfma_f32_16x16x32_bf16 v[22:25], v[196:199], v[240:243], v[22:25]
	s_waitcnt vmcnt(3)
	ds_write_b128 v100, v[110:113] offset:55296
	s_waitcnt vmcnt(2)
	ds_write_b128 v100, v[84:87] offset:59904
	s_waitcnt lgkmcnt(8)
	v_mfma_f32_16x16x32_bf16 v[58:61], v[200:203], v[228:231], v[58:61]
	v_mfma_f32_16x16x32_bf16 v[62:65], v[200:203], v[232:235], v[62:65]
	v_mfma_f32_16x16x32_bf16 v[26:29], v[200:203], v[236:239], v[26:29]
	v_mfma_f32_16x16x32_bf16 v[30:33], v[200:203], v[240:243], v[30:33]
	s_waitcnt vmcnt(1)
	ds_write_b128 v100, v[114:117] offset:64512
	s_waitcnt vmcnt(0)
	ds_write_b128 v101, v[88:91] offset:32256
	s_waitcnt lgkmcnt(0)
	s_barrier
	ds_read_b128 v[212:215], v245 offset:55296
	ds_read_b128 v[196:199], v244 offset:18432
	ds_read_b128 v[216:219], v245 offset:57600
	ds_read_b128 v[220:223], v245 offset:59904
	ds_read_b128 v[224:227], v245 offset:62208
	ds_read_b128 v[200:203], v244 offset:20736
	s_setprio 0
	v_mfma_f32_16x16x32_bf16 v[34:37], v[204:207], v[228:231], v[34:37]
	v_mfma_f32_16x16x32_bf16 v[38:41], v[204:207], v[232:235], v[38:41]
	v_mfma_f32_16x16x32_bf16 v[2:5], v[204:207], v[236:239], v[2:5]
	v_mfma_f32_16x16x32_bf16 v[6:9], v[204:207], v[240:243], v[6:9]
	ds_read_b128 v[204:207], v244 offset:23040
	v_mfma_f32_16x16x32_bf16 v[42:45], v[208:211], v[228:231], v[42:45]
	v_mfma_f32_16x16x32_bf16 v[46:49], v[208:211], v[232:235], v[46:49]
	v_mfma_f32_16x16x32_bf16 v[10:13], v[208:211], v[236:239], v[10:13]
	v_mfma_f32_16x16x32_bf16 v[14:17], v[208:211], v[240:243], v[14:17]
	ds_read_b128 v[208:211], v244 offset:25344
	s_waitcnt lgkmcnt(6)
	v_mfma_f32_16x16x32_bf16 v[50:53], v[196:199], v[212:215], v[50:53]
	ds_read_b128 v[228:231], v245 offset:55360
	s_waitcnt lgkmcnt(6)
	v_mfma_f32_16x16x32_bf16 v[54:57], v[196:199], v[216:219], v[54:57]
	ds_read_b128 v[232:235], v245 offset:57664
	s_waitcnt lgkmcnt(6)
	v_mfma_f32_16x16x32_bf16 v[18:21], v[196:199], v[220:223], v[18:21]
	ds_read_b128 v[236:239], v245 offset:59968
	s_waitcnt lgkmcnt(6)
	v_mfma_f32_16x16x32_bf16 v[22:25], v[196:199], v[224:227], v[22:25]
	ds_read_b128 v[240:243], v245 offset:62272
	ds_read_b128 v[196:199], v244 offset:18496
	s_waitcnt lgkmcnt(7)
	v_mfma_f32_16x16x32_bf16 v[58:61], v[200:203], v[212:215], v[58:61]
	v_mfma_f32_16x16x32_bf16 v[62:65], v[200:203], v[216:219], v[62:65]
	v_mfma_f32_16x16x32_bf16 v[26:29], v[200:203], v[220:223], v[26:29]
	v_mfma_f32_16x16x32_bf16 v[30:33], v[200:203], v[224:227], v[30:33]
	ds_read_b128 v[200:203], v244 offset:20800
	s_waitcnt lgkmcnt(7)
	v_mfma_f32_16x16x32_bf16 v[34:37], v[204:207], v[212:215], v[34:37]
	v_mfma_f32_16x16x32_bf16 v[38:41], v[204:207], v[216:219], v[38:41]
	v_mfma_f32_16x16x32_bf16 v[2:5], v[204:207], v[220:223], v[2:5]
	v_mfma_f32_16x16x32_bf16 v[6:9], v[204:207], v[224:227], v[6:9]
	ds_read_b128 v[204:207], v244 offset:23104
	s_waitcnt lgkmcnt(7)
	v_mfma_f32_16x16x32_bf16 v[42:45], v[208:211], v[212:215], v[42:45]
	v_mfma_f32_16x16x32_bf16 v[46:49], v[208:211], v[216:219], v[46:49]
	v_mfma_f32_16x16x32_bf16 v[10:13], v[208:211], v[220:223], v[10:13]
	v_mfma_f32_16x16x32_bf16 v[14:17], v[208:211], v[224:227], v[14:17]
	ds_read_b128 v[208:211], v244 offset:25408
	s_waitcnt lgkmcnt(3)
	v_mfma_f32_16x16x32_bf16 v[50:53], v[196:199], v[228:231], v[50:53]
	v_mfma_f32_16x16x32_bf16 v[54:57], v[196:199], v[232:235], v[54:57]
	v_mfma_f32_16x16x32_bf16 v[18:21], v[196:199], v[236:239], v[18:21]
	v_mfma_f32_16x16x32_bf16 v[22:25], v[196:199], v[240:243], v[22:25]
	s_waitcnt lgkmcnt(2)
	v_mfma_f32_16x16x32_bf16 v[58:61], v[200:203], v[228:231], v[58:61]
	v_mfma_f32_16x16x32_bf16 v[62:65], v[200:203], v[232:235], v[62:65]
	v_mfma_f32_16x16x32_bf16 v[26:29], v[200:203], v[236:239], v[26:29]
	v_mfma_f32_16x16x32_bf16 v[30:33], v[200:203], v[240:243], v[30:33]
	s_add_i32 s6, s6, 1
	s_add_i32 s5, s5, s3
	v_or_b32_e32 v70, s0, v92
	s_lshl_b32 s0, s7, 1
	v_lshl_add_u64 v[110:111], v[80:81], 0, s[0:1]
	v_lshlrev_b32_e32 v74, 10, v70
	v_lshl_add_u64 v[112:113], v[110:111], 0, v[74:75]
	s_waitcnt lgkmcnt(0)
	s_barrier
	v_mfma_f32_16x16x32_bf16 v[34:37], v[204:207], v[228:231], v[34:37]
	v_mfma_f32_16x16x32_bf16 v[38:41], v[204:207], v[232:235], v[38:41]
	v_mfma_f32_16x16x32_bf16 v[2:5], v[204:207], v[236:239], v[2:5]
	v_mfma_f32_16x16x32_bf16 v[6:9], v[204:207], v[240:243], v[6:9]
	v_mfma_f32_16x16x32_bf16 v[42:45], v[208:211], v[228:231], v[42:45]
	v_mfma_f32_16x16x32_bf16 v[46:49], v[208:211], v[232:235], v[46:49]
	v_mfma_f32_16x16x32_bf16 v[10:13], v[208:211], v[236:239], v[10:13]
	v_mfma_f32_16x16x32_bf16 v[14:17], v[208:211], v[240:243], v[14:17]
	s_nop 7
	v_permlane16_swap_b32_e32 v50, v54
	v_permlane16_swap_b32_e32 v51, v55
	v_permlane16_swap_b32_e32 v52, v56
	v_permlane16_swap_b32_e32 v53, v57
	v_permlane16_swap_b32_e32 v58, v62
	v_permlane16_swap_b32_e32 v59, v63
	v_permlane16_swap_b32_e32 v60, v64
	v_permlane16_swap_b32_e32 v61, v65
	v_permlane16_swap_b32_e32 v18, v22
	v_permlane16_swap_b32_e32 v19, v23
	v_permlane16_swap_b32_e32 v20, v24
	v_permlane16_swap_b32_e32 v21, v25
	v_permlane16_swap_b32_e32 v26, v30
	v_permlane16_swap_b32_e32 v27, v31
	v_permlane16_swap_b32_e32 v28, v32
	v_permlane16_swap_b32_e32 v29, v33
	v_permlane16_swap_b32_e32 v34, v38
	v_permlane16_swap_b32_e32 v35, v39
	v_permlane16_swap_b32_e32 v36, v40
	v_permlane16_swap_b32_e32 v37, v41
	v_permlane16_swap_b32_e32 v42, v46
	v_permlane16_swap_b32_e32 v43, v47
	v_permlane16_swap_b32_e32 v44, v48
	v_permlane16_swap_b32_e32 v45, v49
	v_permlane16_swap_b32_e32 v2, v6
	v_permlane16_swap_b32_e32 v3, v7
	v_permlane16_swap_b32_e32 v4, v8
	v_permlane16_swap_b32_e32 v5, v9
	v_permlane16_swap_b32_e32 v10, v14
	v_permlane16_swap_b32_e32 v11, v15
	v_permlane16_swap_b32_e32 v12, v16
	v_permlane16_swap_b32_e32 v13, v17
	v_permlane32_swap_b32_e32 v50, v54
	v_permlane32_swap_b32_e32 v51, v55
	v_permlane32_swap_b32_e32 v52, v56
	v_permlane32_swap_b32_e32 v53, v57
	v_permlane32_swap_b32_e32 v58, v62
	v_permlane32_swap_b32_e32 v59, v63
	v_permlane32_swap_b32_e32 v60, v64
	v_permlane32_swap_b32_e32 v61, v65
	v_permlane32_swap_b32_e32 v18, v22
	v_permlane32_swap_b32_e32 v19, v23
	v_permlane32_swap_b32_e32 v20, v24
	v_permlane32_swap_b32_e32 v21, v25
	v_permlane32_swap_b32_e32 v26, v30
	v_permlane32_swap_b32_e32 v27, v31
	v_permlane32_swap_b32_e32 v28, v32
	v_permlane32_swap_b32_e32 v29, v33
	v_permlane32_swap_b32_e32 v34, v38
	v_permlane32_swap_b32_e32 v35, v39
	v_permlane32_swap_b32_e32 v36, v40
	v_permlane32_swap_b32_e32 v37, v41
	v_permlane32_swap_b32_e32 v42, v46
	v_permlane32_swap_b32_e32 v43, v47
	v_permlane32_swap_b32_e32 v44, v48
	v_permlane32_swap_b32_e32 v45, v49
	v_permlane32_swap_b32_e32 v2, v6
	v_permlane32_swap_b32_e32 v3, v7
	v_permlane32_swap_b32_e32 v4, v8
	v_permlane32_swap_b32_e32 v5, v9
	v_permlane32_swap_b32_e32 v10, v14
	v_permlane32_swap_b32_e32 v11, v15
	v_permlane32_swap_b32_e32 v12, v16
	v_permlane32_swap_b32_e32 v13, v17
	global_load_dwordx4 v[106:109], v[112:113], off
	s_mul_i32 s0, s6, s3
	s_add_i32 s0, s0, s2
	s_cmp_lt_u32 s5, 48
	global_load_dwordx4 v[88:91], v[112:113], off offset:32
	global_load_dwordx4 v[70:73], v[112:113], off offset:64
	s_waitcnt vmcnt(2)
	v_mov_b32_e32 v86, v108
	global_load_dwordx4 v[66:69], v[112:113], off offset:96
	v_permlane32_swap_b32_e32 v106, v86
	v_mov_b32_e32 v102, v109
	s_nop 1
	v_permlane32_swap_b32_e32 v107, v102
	s_waitcnt vmcnt(2)
	v_mov_b32_e32 v108, v90
	v_mov_b32_e32 v109, v91
	s_nop 0
	v_permlane32_swap_b32_e32 v88, v108
	v_permlane32_swap_b32_e32 v89, v109
	s_waitcnt vmcnt(1)
	v_mov_b32_e32 v112, v72
	v_mov_b32_e32 v113, v73
	v_lshlrev_b32_e32 v72, 16, v106
	v_and_b32_e32 v73, 0xffff0000, v106
	v_pk_mul_f32 v[72:73], v[50:51], v[72:73]
	v_lshlrev_b32_e32 v50, 16, v107
	v_and_b32_e32 v51, 0xffff0000, v107
	v_pk_mul_f32 v[84:85], v[52:53], v[50:51]
	v_lshlrev_b32_e32 v50, 16, v86
	v_and_b32_e32 v51, 0xffff0000, v86
	v_pk_mul_f32 v[86:87], v[54:55], v[50:51]
	v_lshlrev_b32_e32 v54, 16, v102
	v_and_b32_e32 v55, 0xffff0000, v102
	v_pk_mul_f32 v[102:103], v[56:57], v[54:55]
	v_cvt_pk_bf16_f32 v55, v84, v85
	v_cvt_pk_bf16_f32 v56, v86, v87
	v_cvt_pk_bf16_f32 v57, v102, v103
	v_cvt_pk_bf16_f32 v54, v72, v73
	v_add_lshl_u32 v72, s7, v97, 1
	v_mov_b32_e32 v73, v75
	v_permlane32_swap_b32_e32 v54, v56
	v_permlane32_swap_b32_e32 v55, v57
	v_lshlrev_b32_e32 v106, 16, v88
	v_and_b32_e32 v107, 0xffff0000, v88
	v_lshlrev_b32_e32 v88, 16, v89
	v_and_b32_e32 v89, 0xffff0000, v89
	v_pk_mul_f32 v[60:61], v[60:61], v[88:89]
	v_lshlrev_b32_e32 v88, 16, v108
	v_and_b32_e32 v89, 0xffff0000, v108
	v_pk_mul_f32 v[62:63], v[62:63], v[88:89]
	v_lshlrev_b32_e32 v88, 16, v109
	v_and_b32_e32 v89, 0xffff0000, v109
	v_pk_mul_f32 v[58:59], v[58:59], v[106:107]
	v_pk_mul_f32 v[64:65], v[64:65], v[88:89]
	v_cvt_pk_bf16_f32 v58, v58, v59
	v_cvt_pk_bf16_f32 v59, v60, v61
	v_cvt_pk_bf16_f32 v60, v62, v63
	v_cvt_pk_bf16_f32 v61, v64, v65
	v_permlane32_swap_b32_e32 v70, v112
	v_permlane32_swap_b32_e32 v58, v60
	v_permlane32_swap_b32_e32 v59, v61
	v_permlane32_swap_b32_e32 v71, v113
	s_waitcnt vmcnt(0)
	v_mov_b32_e32 v114, v68
	v_mov_b32_e32 v115, v69
	v_lshl_add_u64 v[68:69], v[82:83], 0, v[74:75]
	v_or_b32_e32 v74, 0x8000, v74
	v_lshl_add_u64 v[90:91], v[110:111], 0, v[74:75]
	global_load_dwordx4 v[50:53], v[90:91], off
	global_load_dwordx4 v[84:87], v[90:91], off offset:32
	global_load_dwordx4 v[102:105], v[90:91], off offset:64
	v_lshl_add_u64 v[68:69], v[68:69], 0, v[72:73]
	global_store_dwordx4 v[68:69], v[54:57], off
	global_load_dwordx4 v[54:57], v[90:91], off offset:96
	v_permlane32_swap_b32_e32 v66, v114
	global_store_dwordx4 v[68:69], v[58:61], off offset:32
	v_permlane32_swap_b32_e32 v67, v115
	s_nop 0
	v_lshlrev_b32_e32 v58, 16, v70
	v_and_b32_e32 v59, 0xffff0000, v70
	v_pk_mul_f32 v[34:35], v[34:35], v[58:59]
	v_lshlrev_b32_e32 v58, 16, v71
	v_and_b32_e32 v59, 0xffff0000, v71
	v_pk_mul_f32 v[36:37], v[36:37], v[58:59]
	v_lshlrev_b32_e32 v58, 16, v112
	v_and_b32_e32 v59, 0xffff0000, v112
	v_pk_mul_f32 v[38:39], v[38:39], v[58:59]
	v_lshlrev_b32_e32 v58, 16, v113
	v_and_b32_e32 v59, 0xffff0000, v113
	v_pk_mul_f32 v[40:41], v[40:41], v[58:59]
	v_cvt_pk_bf16_f32 v34, v34, v35
	v_cvt_pk_bf16_f32 v35, v36, v37
	v_cvt_pk_bf16_f32 v36, v38, v39
	v_cvt_pk_bf16_f32 v37, v40, v41
	s_nop 0
	v_permlane32_swap_b32_e32 v34, v36
	v_permlane32_swap_b32_e32 v35, v37
	global_store_dwordx4 v[68:69], v[34:37], off offset:64
	v_lshlrev_b32_e32 v38, 16, v114
	v_and_b32_e32 v39, 0xffff0000, v114
	v_lshlrev_b32_e32 v34, 16, v66
	v_and_b32_e32 v35, 0xffff0000, v66
	v_lshlrev_b32_e32 v36, 16, v67
	v_and_b32_e32 v37, 0xffff0000, v67
	v_lshlrev_b32_e32 v40, 16, v115
	v_and_b32_e32 v41, 0xffff0000, v115
	v_pk_mul_f32 v[34:35], v[42:43], v[34:35]
	v_pk_mul_f32 v[36:37], v[44:45], v[36:37]
	v_pk_mul_f32 v[38:39], v[46:47], v[38:39]
	v_pk_mul_f32 v[40:41], v[48:49], v[40:41]
	v_cvt_pk_bf16_f32 v34, v34, v35
	v_cvt_pk_bf16_f32 v35, v36, v37
	v_cvt_pk_bf16_f32 v36, v38, v39
	v_cvt_pk_bf16_f32 v37, v40, v41
	s_nop 0
	v_permlane32_swap_b32_e32 v34, v36
	v_permlane32_swap_b32_e32 v35, v37
	global_store_dwordx4 v[68:69], v[34:37], off offset:96
	s_waitcnt vmcnt(7)
	v_mov_b32_e32 v38, v52
	s_nop 1
	v_permlane32_swap_b32_e32 v50, v38
	v_mov_b32_e32 v39, v53
	s_nop 1
	v_permlane32_swap_b32_e32 v51, v39
	v_lshlrev_b32_e32 v36, 16, v50
	v_and_b32_e32 v37, 0xffff0000, v50
	v_pk_mul_f32 v[18:19], v[18:19], v[36:37]
	v_lshlrev_b32_e32 v36, 16, v51
	v_and_b32_e32 v37, 0xffff0000, v51
	v_pk_mul_f32 v[20:21], v[20:21], v[36:37]
	v_lshlrev_b32_e32 v36, 16, v38
	v_and_b32_e32 v37, 0xffff0000, v38
	v_pk_mul_f32 v[22:23], v[22:23], v[36:37]
	v_lshlrev_b32_e32 v36, 16, v39
	v_and_b32_e32 v37, 0xffff0000, v39
	v_pk_mul_f32 v[24:25], v[24:25], v[36:37]
	s_waitcnt vmcnt(6)
	v_mov_b32_e32 v40, v86
	v_lshl_add_u64 v[34:35], v[82:83], 0, v[74:75]
	v_cvt_pk_bf16_f32 v18, v18, v19
	v_cvt_pk_bf16_f32 v19, v20, v21
	v_cvt_pk_bf16_f32 v20, v22, v23
	v_cvt_pk_bf16_f32 v21, v24, v25
	v_permlane32_swap_b32_e32 v84, v40
	v_mov_b32_e32 v41, v87
	v_permlane32_swap_b32_e32 v18, v20
	v_permlane32_swap_b32_e32 v19, v21
	v_lshl_add_u64 v[22:23], v[34:35], 0, v[72:73]
	v_permlane32_swap_b32_e32 v85, v41
	global_store_dwordx4 v[22:23], v[18:21], off
	v_lshlrev_b32_e32 v24, 16, v40
	v_and_b32_e32 v25, 0xffff0000, v40
	v_lshlrev_b32_e32 v18, 16, v84
	v_and_b32_e32 v19, 0xffff0000, v84
	v_pk_mul_f32 v[18:19], v[26:27], v[18:19]
	v_lshlrev_b32_e32 v20, 16, v85
	v_and_b32_e32 v21, 0xffff0000, v85
	v_lshlrev_b32_e32 v26, 16, v41
	v_and_b32_e32 v27, 0xffff0000, v41
	v_pk_mul_f32 v[20:21], v[28:29], v[20:21]
	v_pk_mul_f32 v[24:25], v[30:31], v[24:25]
	v_pk_mul_f32 v[26:27], v[32:33], v[26:27]
	s_waitcnt vmcnt(6)
	v_mov_b32_e32 v42, v104
	v_cvt_pk_bf16_f32 v18, v18, v19
	v_cvt_pk_bf16_f32 v19, v20, v21
	v_cvt_pk_bf16_f32 v20, v24, v25
	v_cvt_pk_bf16_f32 v21, v26, v27
	v_permlane32_swap_b32_e32 v102, v42
	v_mov_b32_e32 v43, v105
	v_permlane32_swap_b32_e32 v18, v20
	v_permlane32_swap_b32_e32 v19, v21
	v_permlane32_swap_b32_e32 v103, v43
	global_store_dwordx4 v[22:23], v[18:21], off offset:32
	s_waitcnt vmcnt(5)
	v_mov_b32_e32 v44, v56
	v_mov_b32_e32 v45, v57
	v_lshlrev_b32_e32 v18, 16, v102
	v_and_b32_e32 v19, 0xffff0000, v102
	v_pk_mul_f32 v[2:3], v[2:3], v[18:19]
	v_lshlrev_b32_e32 v18, 16, v103
	v_and_b32_e32 v19, 0xffff0000, v103
	v_pk_mul_f32 v[4:5], v[4:5], v[18:19]
	v_lshlrev_b32_e32 v18, 16, v42
	v_and_b32_e32 v19, 0xffff0000, v42
	v_pk_mul_f32 v[6:7], v[6:7], v[18:19]
	v_lshlrev_b32_e32 v18, 16, v43
	v_and_b32_e32 v19, 0xffff0000, v43
	v_pk_mul_f32 v[8:9], v[8:9], v[18:19]
	v_cvt_pk_bf16_f32 v2, v2, v3
	v_cvt_pk_bf16_f32 v3, v4, v5
	v_cvt_pk_bf16_f32 v4, v6, v7
	v_cvt_pk_bf16_f32 v5, v8, v9
	v_permlane32_swap_b32_e32 v54, v44
	v_permlane32_swap_b32_e32 v55, v45
	v_permlane32_swap_b32_e32 v2, v4
	v_permlane32_swap_b32_e32 v3, v5
	global_store_dwordx4 v[22:23], v[2:5], off offset:64
	v_lshlrev_b32_e32 v6, 16, v44
	v_and_b32_e32 v7, 0xffff0000, v44
	v_lshlrev_b32_e32 v2, 16, v54
	v_and_b32_e32 v3, 0xffff0000, v54
	v_lshlrev_b32_e32 v4, 16, v55
	v_and_b32_e32 v5, 0xffff0000, v55
	v_lshlrev_b32_e32 v8, 16, v45
	v_and_b32_e32 v9, 0xffff0000, v45
	v_pk_mul_f32 v[2:3], v[10:11], v[2:3]
	v_pk_mul_f32 v[4:5], v[12:13], v[4:5]
	v_pk_mul_f32 v[6:7], v[14:15], v[6:7]
	v_pk_mul_f32 v[8:9], v[16:17], v[8:9]
	v_cvt_pk_bf16_f32 v2, v2, v3
	v_cvt_pk_bf16_f32 v3, v4, v5
	v_cvt_pk_bf16_f32 v4, v6, v7
	v_cvt_pk_bf16_f32 v5, v8, v9
	s_nop 0
	v_permlane32_swap_b32_e32 v2, v4
	v_permlane32_swap_b32_e32 v3, v5
	global_store_dwordx4 v[22:23], v[2:5], off offset:96
	s_cbranch_scc1 .LBB0_1720

.LBB0_1871:
	s_lshr_b32 s0, s4, 2
	s_and_b32 s4, s4, 3
	s_or_b32 s4, s4, s8
	s_lshl_b32 s4, s4, 7
	v_or_b32_e32 v2, s4, v89
	v_lshlrev_b32_e32 v66, 11, v2
	s_add_i32 s0, s0, s9
	v_lshl_add_u64 v[72:73], v[68:69], 0, v[66:67]
	v_add_lshl_u32 v66, s4, v90, 11
	s_lshl_b32 s5, s0, 7
	v_lshl_add_u64 v[74:75], v[68:69], 0, v[66:67]
	v_add_lshl_u32 v66, s4, v91, 11
	v_lshl_add_u64 v[76:77], v[68:69], 0, v[66:67]
	v_add_lshl_u32 v66, s4, v92, 11
	v_or_b32_e32 v2, s5, v89
	v_lshl_add_u64 v[78:79], v[68:69], 0, v[66:67]
	v_lshlrev_b32_e32 v66, 11, v2
	v_lshl_add_u64 v[80:81], v[70:71], 0, v[66:67]
	v_add_lshl_u32 v66, s5, v90, 11
	v_lshl_add_u64 v[82:83], v[70:71], 0, v[66:67]
	v_add_lshl_u32 v66, s5, v91, 11
	v_lshl_add_u64 v[84:85], v[70:71], 0, v[66:67]
	v_add_lshl_u32 v66, s5, v92, 11
	v_lshl_add_u64 v[86:87], v[70:71], 0, v[66:67]
	global_load_dwordx4 v[2:5], v[72:73], off
	global_load_dwordx4 v[6:9], v[74:75], off
	global_load_dwordx4 v[10:13], v[76:77], off
	global_load_dwordx4 v[14:17], v[78:79], off
	global_load_dwordx4 v[18:21], v[80:81], off
	global_load_dwordx4 v[22:25], v[82:83], off
	global_load_dwordx4 v[26:29], v[84:85], off
	global_load_dwordx4 v[30:33], v[86:87], off
	global_load_dwordx4 v[98:101], v[72:73], off offset:128
	global_load_dwordx4 v[102:105], v[74:75], off offset:128
	global_load_dwordx4 v[106:109], v[76:77], off offset:128
	global_load_dwordx4 v[110:113], v[78:79], off offset:128
	global_load_dwordx4 v[114:117], v[80:81], off offset:128
	global_load_dwordx4 v[118:121], v[82:83], off offset:128
	global_load_dwordx4 v[122:125], v[84:85], off offset:128
	global_load_dwordx4 v[126:129], v[86:87], off offset:128
	s_waitcnt vmcnt(15)
	ds_write_b128 v95, v[2:5]
	s_waitcnt vmcnt(14)
	ds_write_b128 v95, v[6:9] offset:4608
	s_waitcnt vmcnt(13)
	ds_write_b128 v95, v[10:13] offset:9216
	s_waitcnt vmcnt(12)
	ds_write_b128 v95, v[14:17] offset:13824
	s_waitcnt vmcnt(11)
	ds_write_b128 v95, v[18:21] offset:36864
	s_waitcnt vmcnt(10)
	ds_write_b128 v95, v[22:25] offset:41472
	s_waitcnt vmcnt(9)
	ds_write_b128 v95, v[26:29] offset:46080
	s_waitcnt vmcnt(8)
	ds_write_b128 v95, v[30:33] offset:50688
	s_waitcnt lgkmcnt(0)
	s_barrier
	global_load_dwordx4 v[132:135], v[72:73], off offset:256
	global_load_dwordx4 v[136:139], v[74:75], off offset:256
	global_load_dwordx4 v[140:143], v[76:77], off offset:256
	global_load_dwordx4 v[144:147], v[78:79], off offset:256
	global_load_dwordx4 v[148:151], v[80:81], off offset:256
	global_load_dwordx4 v[152:155], v[82:83], off offset:256
	global_load_dwordx4 v[156:159], v[84:85], off offset:256
	global_load_dwordx4 v[160:163], v[86:87], off offset:256
	v_and_b32_e32 v246, 15, v1
	v_add_u32_e32 v246, 4, v246
	v_bfe_u32 v246, v246, 3, 1
	v_bfe_u32 v249, v1, 4, 2
	v_xor_b32_e32 v246, v246, v249
	v_bfe_u32 v249, v1, 5, 1
	v_sub_u32_e32 v246, v246, v249
	v_lshlrev_b32_e32 v246, 4, v246
	v_bfe_u32 v249, v1, 4, 1
	v_mul_u32_u24_e32 v249, 0x900, v249
	v_sub_u32_e32 v246, v246, v249
	v_add_u32_e32 v244, v246, v93
	v_add_u32_e32 v245, v246, v94
	ds_read_b128 v[212:215], v245 offset:36864
	ds_read_b128 v[196:199], v244
	ds_read_b128 v[216:219], v245 offset:39168
	ds_read_b128 v[220:223], v245 offset:41472
	ds_read_b128 v[224:227], v245 offset:43776
	ds_read_b128 v[200:203], v244 offset:2304
	ds_read_b128 v[204:207], v244 offset:4608
	ds_read_b128 v[208:211], v244 offset:6912
	s_waitcnt lgkmcnt(6)
	v_mfma_f32_16x16x32_bf16 v[34:37], v[196:199], v[212:215], 0
	ds_read_b128 v[228:231], v245 offset:36928
	s_waitcnt lgkmcnt(6)
	v_mfma_f32_16x16x32_bf16 v[38:41], v[196:199], v[216:219], 0
	ds_read_b128 v[232:235], v245 offset:39232
	s_waitcnt lgkmcnt(6)
	v_mfma_f32_16x16x32_bf16 v[2:5], v[196:199], v[220:223], 0
	ds_read_b128 v[236:239], v245 offset:41536
	s_waitcnt lgkmcnt(6)
	v_mfma_f32_16x16x32_bf16 v[6:9], v[196:199], v[224:227], 0
	ds_read_b128 v[240:243], v245 offset:43840
	ds_read_b128 v[196:199], v244 offset:64
	s_waitcnt lgkmcnt(7)
	v_mfma_f32_16x16x32_bf16 v[42:45], v[200:203], v[212:215], 0
	v_mfma_f32_16x16x32_bf16 v[46:49], v[200:203], v[216:219], 0
	v_mfma_f32_16x16x32_bf16 v[10:13], v[200:203], v[220:223], 0
	v_mfma_f32_16x16x32_bf16 v[14:17], v[200:203], v[224:227], 0
	ds_read_b128 v[200:203], v244 offset:2368
	s_waitcnt lgkmcnt(7)
	v_mfma_f32_16x16x32_bf16 v[50:53], v[204:207], v[212:215], 0
	v_mfma_f32_16x16x32_bf16 v[54:57], v[204:207], v[216:219], 0
	v_mfma_f32_16x16x32_bf16 v[18:21], v[204:207], v[220:223], 0
	v_mfma_f32_16x16x32_bf16 v[22:25], v[204:207], v[224:227], 0
	ds_read_b128 v[204:207], v244 offset:4672
	s_setprio 1
	s_waitcnt vmcnt(15)
	ds_write_b128 v95, v[98:101] offset:18432
	s_waitcnt vmcnt(14)
	ds_write_b128 v95, v[102:105] offset:23040
	s_waitcnt lgkmcnt(9)
	v_mfma_f32_16x16x32_bf16 v[58:61], v[208:211], v[212:215], 0
	v_mfma_f32_16x16x32_bf16 v[62:65], v[208:211], v[216:219], 0
	v_mfma_f32_16x16x32_bf16 v[26:29], v[208:211], v[220:223], 0
	v_mfma_f32_16x16x32_bf16 v[30:33], v[208:211], v[224:227], 0
	ds_read_b128 v[208:211], v244 offset:6976
	s_waitcnt vmcnt(13)
	ds_write_b128 v95, v[106:109] offset:27648
	s_waitcnt vmcnt(12)
	ds_write_b128 v95, v[110:113] offset:32256
	s_waitcnt lgkmcnt(7)
	v_mfma_f32_16x16x32_bf16 v[34:37], v[196:199], v[228:231], v[34:37]
	v_mfma_f32_16x16x32_bf16 v[38:41], v[196:199], v[232:235], v[38:41]
	v_mfma_f32_16x16x32_bf16 v[2:5], v[196:199], v[236:239], v[2:5]
	v_mfma_f32_16x16x32_bf16 v[6:9], v[196:199], v[240:243], v[6:9]
	s_waitcnt vmcnt(11)
	ds_write_b128 v95, v[114:117] offset:55296
	s_waitcnt vmcnt(10)
	ds_write_b128 v95, v[118:121] offset:59904
	s_waitcnt lgkmcnt(8)
	v_mfma_f32_16x16x32_bf16 v[42:45], v[200:203], v[228:231], v[42:45]
	v_mfma_f32_16x16x32_bf16 v[46:49], v[200:203], v[232:235], v[46:49]
	v_mfma_f32_16x16x32_bf16 v[10:13], v[200:203], v[236:239], v[10:13]
	v_mfma_f32_16x16x32_bf16 v[14:17], v[200:203], v[240:243], v[14:17]
	s_waitcnt vmcnt(9)
	ds_write_b128 v95, v[122:125] offset:64512
	s_waitcnt vmcnt(8)
	ds_write_b128 v96, v[126:129] offset:32256
	s_waitcnt lgkmcnt(0)
	s_barrier
	ds_read_b128 v[212:215], v245 offset:55296
	ds_read_b128 v[196:199], v244 offset:18432
	ds_read_b128 v[216:219], v245 offset:57600
	ds_read_b128 v[220:223], v245 offset:59904
	ds_read_b128 v[224:227], v245 offset:62208
	ds_read_b128 v[200:203], v244 offset:20736
	s_setprio 0
	v_mfma_f32_16x16x32_bf16 v[50:53], v[204:207], v[228:231], v[50:53]
	v_mfma_f32_16x16x32_bf16 v[54:57], v[204:207], v[232:235], v[54:57]
	v_mfma_f32_16x16x32_bf16 v[18:21], v[204:207], v[236:239], v[18:21]
	v_mfma_f32_16x16x32_bf16 v[22:25], v[204:207], v[240:243], v[22:25]
	ds_read_b128 v[204:207], v244 offset:23040
	v_mfma_f32_16x16x32_bf16 v[58:61], v[208:211], v[228:231], v[58:61]
	v_mfma_f32_16x16x32_bf16 v[62:65], v[208:211], v[232:235], v[62:65]
	v_mfma_f32_16x16x32_bf16 v[26:29], v[208:211], v[236:239], v[26:29]
	v_mfma_f32_16x16x32_bf16 v[30:33], v[208:211], v[240:243], v[30:33]
	ds_read_b128 v[208:211], v244 offset:25344
	global_load_dwordx4 v[98:101], v[72:73], off offset:384
	global_load_dwordx4 v[102:105], v[74:75], off offset:384
	global_load_dwordx4 v[106:109], v[76:77], off offset:384
	global_load_dwordx4 v[110:113], v[78:79], off offset:384
	global_load_dwordx4 v[114:117], v[80:81], off offset:384
	global_load_dwordx4 v[118:121], v[82:83], off offset:384
	global_load_dwordx4 v[122:125], v[84:85], off offset:384
	global_load_dwordx4 v[126:129], v[86:87], off offset:384
	s_waitcnt lgkmcnt(6)
	v_mfma_f32_16x16x32_bf16 v[34:37], v[196:199], v[212:215], v[34:37]
	ds_read_b128 v[228:231], v245 offset:55360
	s_waitcnt lgkmcnt(6)
	v_mfma_f32_16x16x32_bf16 v[38:41], v[196:199], v[216:219], v[38:41]
	ds_read_b128 v[232:235], v245 offset:57664
	s_waitcnt lgkmcnt(6)
	v_mfma_f32_16x16x32_bf16 v[2:5], v[196:199], v[220:223], v[2:5]
	ds_read_b128 v[236:239], v245 offset:59968
	s_waitcnt lgkmcnt(6)
	v_mfma_f32_16x16x32_bf16 v[6:9], v[196:199], v[224:227], v[6:9]
	ds_read_b128 v[240:243], v245 offset:62272
	ds_read_b128 v[196:199], v244 offset:18496
	s_waitcnt lgkmcnt(7)
	v_mfma_f32_16x16x32_bf16 v[42:45], v[200:203], v[212:215], v[42:45]
	v_mfma_f32_16x16x32_bf16 v[46:49], v[200:203], v[216:219], v[46:49]
	v_mfma_f32_16x16x32_bf16 v[10:13], v[200:203], v[220:223], v[10:13]
	v_mfma_f32_16x16x32_bf16 v[14:17], v[200:203], v[224:227], v[14:17]
	ds_read_b128 v[200:203], v244 offset:20800
	s_waitcnt lgkmcnt(7)
	v_mfma_f32_16x16x32_bf16 v[50:53], v[204:207], v[212:215], v[50:53]
	v_mfma_f32_16x16x32_bf16 v[54:57], v[204:207], v[216:219], v[54:57]
	v_mfma_f32_16x16x32_bf16 v[18:21], v[204:207], v[220:223], v[18:21]
	v_mfma_f32_16x16x32_bf16 v[22:25], v[204:207], v[224:227], v[22:25]
	ds_read_b128 v[204:207], v244 offset:23104
	s_setprio 1
	s_waitcnt vmcnt(15)
	ds_write_b128 v95, v[132:135]
	s_waitcnt vmcnt(14)
	ds_write_b128 v95, v[136:139] offset:4608
	s_waitcnt lgkmcnt(9)
	v_mfma_f32_16x16x32_bf16 v[58:61], v[208:211], v[212:215], v[58:61]
	v_mfma_f32_16x16x32_bf16 v[62:65], v[208:211], v[216:219], v[62:65]
	v_mfma_f32_16x16x32_bf16 v[26:29], v[208:211], v[220:223], v[26:29]
	v_mfma_f32_16x16x32_bf16 v[30:33], v[208:211], v[224:227], v[30:33]
	ds_read_b128 v[208:211], v244 offset:25408
	s_waitcnt vmcnt(13)
	ds_write_b128 v95, v[140:143] offset:9216
	s_waitcnt vmcnt(12)
	ds_write_b128 v95, v[144:147] offset:13824
	s_waitcnt lgkmcnt(7)
	v_mfma_f32_16x16x32_bf16 v[34:37], v[196:199], v[228:231], v[34:37]
	v_mfma_f32_16x16x32_bf16 v[38:41], v[196:199], v[232:235], v[38:41]
	v_mfma_f32_16x16x32_bf16 v[2:5], v[196:199], v[236:239], v[2:5]
	v_mfma_f32_16x16x32_bf16 v[6:9], v[196:199], v[240:243], v[6:9]
	s_waitcnt vmcnt(11)
	ds_write_b128 v95, v[148:151] offset:36864
	s_waitcnt vmcnt(10)
	ds_write_b128 v95, v[152:155] offset:41472
	s_waitcnt lgkmcnt(8)
	v_mfma_f32_16x16x32_bf16 v[42:45], v[200:203], v[228:231], v[42:45]
	v_mfma_f32_16x16x32_bf16 v[46:49], v[200:203], v[232:235], v[46:49]
	v_mfma_f32_16x16x32_bf16 v[10:13], v[200:203], v[236:239], v[10:13]
	v_mfma_f32_16x16x32_bf16 v[14:17], v[200:203], v[240:243], v[14:17]
	s_waitcnt vmcnt(9)
	ds_write_b128 v95, v[156:159] offset:46080
	s_waitcnt vmcnt(8)
	ds_write_b128 v95, v[160:163] offset:50688
	s_waitcnt lgkmcnt(0)
	s_barrier
	ds_read_b128 v[212:215], v245 offset:36864
	ds_read_b128 v[196:199], v244
	ds_read_b128 v[216:219], v245 offset:39168
	ds_read_b128 v[220:223], v245 offset:41472
	ds_read_b128 v[224:227], v245 offset:43776
	ds_read_b128 v[200:203], v244 offset:2304
	s_setprio 0
	v_mfma_f32_16x16x32_bf16 v[50:53], v[204:207], v[228:231], v[50:53]
	v_mfma_f32_16x16x32_bf16 v[54:57], v[204:207], v[232:235], v[54:57]
	v_mfma_f32_16x16x32_bf16 v[18:21], v[204:207], v[236:239], v[18:21]
	v_mfma_f32_16x16x32_bf16 v[22:25], v[204:207], v[240:243], v[22:25]
	ds_read_b128 v[204:207], v244 offset:4608
	v_mfma_f32_16x16x32_bf16 v[58:61], v[208:211], v[228:231], v[58:61]
	v_mfma_f32_16x16x32_bf16 v[62:65], v[208:211], v[232:235], v[62:65]
	v_mfma_f32_16x16x32_bf16 v[26:29], v[208:211], v[236:239], v[26:29]
	v_mfma_f32_16x16x32_bf16 v[30:33], v[208:211], v[240:243], v[30:33]
	ds_read_b128 v[208:211], v244 offset:6912
	global_load_dwordx4 v[132:135], v[72:73], off offset:512
	global_load_dwordx4 v[136:139], v[74:75], off offset:512
	global_load_dwordx4 v[140:143], v[76:77], off offset:512
	global_load_dwordx4 v[144:147], v[78:79], off offset:512
	global_load_dwordx4 v[148:151], v[80:81], off offset:512
	global_load_dwordx4 v[152:155], v[82:83], off offset:512
	global_load_dwordx4 v[156:159], v[84:85], off offset:512
	global_load_dwordx4 v[160:163], v[86:87], off offset:512
	s_waitcnt lgkmcnt(6)
	v_mfma_f32_16x16x32_bf16 v[34:37], v[196:199], v[212:215], v[34:37]
	ds_read_b128 v[228:231], v245 offset:36928
	s_waitcnt lgkmcnt(6)
	v_mfma_f32_16x16x32_bf16 v[38:41], v[196:199], v[216:219], v[38:41]
	ds_read_b128 v[232:235], v245 offset:39232
	s_waitcnt lgkmcnt(6)
	v_mfma_f32_16x16x32_bf16 v[2:5], v[196:199], v[220:223], v[2:5]
	ds_read_b128 v[236:239], v245 offset:41536
	s_waitcnt lgkmcnt(6)
	v_mfma_f32_16x16x32_bf16 v[6:9], v[196:199], v[224:227], v[6:9]
	ds_read_b128 v[240:243], v245 offset:43840
	ds_read_b128 v[196:199], v244 offset:64
	s_waitcnt lgkmcnt(7)
	v_mfma_f32_16x16x32_bf16 v[42:45], v[200:203], v[212:215], v[42:45]
	v_mfma_f32_16x16x32_bf16 v[46:49], v[200:203], v[216:219], v[46:49]
	v_mfma_f32_16x16x32_bf16 v[10:13], v[200:203], v[220:223], v[10:13]
	v_mfma_f32_16x16x32_bf16 v[14:17], v[200:203], v[224:227], v[14:17]
	ds_read_b128 v[200:203], v244 offset:2368
	s_waitcnt lgkmcnt(7)
	v_mfma_f32_16x16x32_bf16 v[50:53], v[204:207], v[212:215], v[50:53]
	v_mfma_f32_16x16x32_bf16 v[54:57], v[204:207], v[216:219], v[54:57]
	v_mfma_f32_16x16x32_bf16 v[18:21], v[204:207], v[220:223], v[18:21]
	v_mfma_f32_16x16x32_bf16 v[22:25], v[204:207], v[224:227], v[22:25]
	ds_read_b128 v[204:207], v244 offset:4672
	s_setprio 1
	s_waitcnt vmcnt(15)
	ds_write_b128 v95, v[98:101] offset:18432
	s_waitcnt vmcnt(14)
	ds_write_b128 v95, v[102:105] offset:23040
	s_waitcnt lgkmcnt(9)
	v_mfma_f32_16x16x32_bf16 v[58:61], v[208:211], v[212:215], v[58:61]
	v_mfma_f32_16x16x32_bf16 v[62:65], v[208:211], v[216:219], v[62:65]
	v_mfma_f32_16x16x32_bf16 v[26:29], v[208:211], v[220:223], v[26:29]
	v_mfma_f32_16x16x32_bf16 v[30:33], v[208:211], v[224:227], v[30:33]
	ds_read_b128 v[208:211], v244 offset:6976
	s_waitcnt vmcnt(13)
	ds_write_b128 v95, v[106:109] offset:27648
	s_waitcnt vmcnt(12)
	ds_write_b128 v95, v[110:113] offset:32256
	s_waitcnt lgkmcnt(7)
	v_mfma_f32_16x16x32_bf16 v[34:37], v[196:199], v[228:231], v[34:37]
	v_mfma_f32_16x16x32_bf16 v[38:41], v[196:199], v[232:235], v[38:41]
	v_mfma_f32_16x16x32_bf16 v[2:5], v[196:199], v[236:239], v[2:5]
	v_mfma_f32_16x16x32_bf16 v[6:9], v[196:199], v[240:243], v[6:9]
	s_waitcnt vmcnt(11)
	ds_write_b128 v95, v[114:117] offset:55296
	s_waitcnt vmcnt(10)
	ds_write_b128 v95, v[118:121] offset:59904
	s_waitcnt lgkmcnt(8)
	v_mfma_f32_16x16x32_bf16 v[42:45], v[200:203], v[228:231], v[42:45]
	v_mfma_f32_16x16x32_bf16 v[46:49], v[200:203], v[232:235], v[46:49]
	v_mfma_f32_16x16x32_bf16 v[10:13], v[200:203], v[236:239], v[10:13]
	v_mfma_f32_16x16x32_bf16 v[14:17], v[200:203], v[240:243], v[14:17]
	s_waitcnt vmcnt(9)
	ds_write_b128 v95, v[122:125] offset:64512
	s_waitcnt vmcnt(8)
	ds_write_b128 v96, v[126:129] offset:32256
	s_waitcnt lgkmcnt(0)
	s_barrier
	ds_read_b128 v[212:215], v245 offset:55296
	ds_read_b128 v[196:199], v244 offset:18432
	ds_read_b128 v[216:219], v245 offset:57600
	ds_read_b128 v[220:223], v245 offset:59904
	ds_read_b128 v[224:227], v245 offset:62208
	ds_read_b128 v[200:203], v244 offset:20736
	s_setprio 0
	v_mfma_f32_16x16x32_bf16 v[50:53], v[204:207], v[228:231], v[50:53]
	v_mfma_f32_16x16x32_bf16 v[54:57], v[204:207], v[232:235], v[54:57]
	v_mfma_f32_16x16x32_bf16 v[18:21], v[204:207], v[236:239], v[18:21]
	v_mfma_f32_16x16x32_bf16 v[22:25], v[204:207], v[240:243], v[22:25]
	ds_read_b128 v[204:207], v244 offset:23040
	v_mfma_f32_16x16x32_bf16 v[58:61], v[208:211], v[228:231], v[58:61]
	v_mfma_f32_16x16x32_bf16 v[62:65], v[208:211], v[232:235], v[62:65]
	v_mfma_f32_16x16x32_bf16 v[26:29], v[208:211], v[236:239], v[26:29]
	v_mfma_f32_16x16x32_bf16 v[30:33], v[208:211], v[240:243], v[30:33]
	ds_read_b128 v[208:211], v244 offset:25344
	global_load_dwordx4 v[98:101], v[72:73], off offset:640
	global_load_dwordx4 v[102:105], v[74:75], off offset:640
	global_load_dwordx4 v[106:109], v[76:77], off offset:640
	global_load_dwordx4 v[110:113], v[78:79], off offset:640
	global_load_dwordx4 v[114:117], v[80:81], off offset:640
	global_load_dwordx4 v[118:121], v[82:83], off offset:640
	global_load_dwordx4 v[122:125], v[84:85], off offset:640
	global_load_dwordx4 v[126:129], v[86:87], off offset:640
	s_waitcnt lgkmcnt(6)
	v_mfma_f32_16x16x32_bf16 v[34:37], v[196:199], v[212:215], v[34:37]
	ds_read_b128 v[228:231], v245 offset:55360
	s_waitcnt lgkmcnt(6)
	v_mfma_f32_16x16x32_bf16 v[38:41], v[196:199], v[216:219], v[38:41]
	ds_read_b128 v[232:235], v245 offset:57664
	s_waitcnt lgkmcnt(6)
	v_mfma_f32_16x16x32_bf16 v[2:5], v[196:199], v[220:223], v[2:5]
	ds_read_b128 v[236:239], v245 offset:59968
	s_waitcnt lgkmcnt(6)
	v_mfma_f32_16x16x32_bf16 v[6:9], v[196:199], v[224:227], v[6:9]
	ds_read_b128 v[240:243], v245 offset:62272
	ds_read_b128 v[196:199], v244 offset:18496
	s_waitcnt lgkmcnt(7)
	v_mfma_f32_16x16x32_bf16 v[42:45], v[200:203], v[212:215], v[42:45]
	v_mfma_f32_16x16x32_bf16 v[46:49], v[200:203], v[216:219], v[46:49]
	v_mfma_f32_16x16x32_bf16 v[10:13], v[200:203], v[220:223], v[10:13]
	v_mfma_f32_16x16x32_bf16 v[14:17], v[200:203], v[224:227], v[14:17]
	ds_read_b128 v[200:203], v244 offset:20800
	s_waitcnt lgkmcnt(7)
	v_mfma_f32_16x16x32_bf16 v[50:53], v[204:207], v[212:215], v[50:53]
	v_mfma_f32_16x16x32_bf16 v[54:57], v[204:207], v[216:219], v[54:57]
	v_mfma_f32_16x16x32_bf16 v[18:21], v[204:207], v[220:223], v[18:21]
	v_mfma_f32_16x16x32_bf16 v[22:25], v[204:207], v[224:227], v[22:25]
	ds_read_b128 v[204:207], v244 offset:23104
	s_setprio 1
	s_waitcnt vmcnt(15)
	ds_write_b128 v95, v[132:135]
	s_waitcnt vmcnt(14)
	ds_write_b128 v95, v[136:139] offset:4608
	s_waitcnt lgkmcnt(9)
	v_mfma_f32_16x16x32_bf16 v[58:61], v[208:211], v[212:215], v[58:61]
	v_mfma_f32_16x16x32_bf16 v[62:65], v[208:211], v[216:219], v[62:65]
	v_mfma_f32_16x16x32_bf16 v[26:29], v[208:211], v[220:223], v[26:29]
	v_mfma_f32_16x16x32_bf16 v[30:33], v[208:211], v[224:227], v[30:33]
	ds_read_b128 v[208:211], v244 offset:25408
	s_waitcnt vmcnt(13)
	ds_write_b128 v95, v[140:143] offset:9216
	s_waitcnt vmcnt(12)
	ds_write_b128 v95, v[144:147] offset:13824
	s_waitcnt lgkmcnt(7)
	v_mfma_f32_16x16x32_bf16 v[34:37], v[196:199], v[228:231], v[34:37]
	v_mfma_f32_16x16x32_bf16 v[38:41], v[196:199], v[232:235], v[38:41]
	v_mfma_f32_16x16x32_bf16 v[2:5], v[196:199], v[236:239], v[2:5]
	v_mfma_f32_16x16x32_bf16 v[6:9], v[196:199], v[240:243], v[6:9]
	s_waitcnt vmcnt(11)
	ds_write_b128 v95, v[148:151] offset:36864
	s_waitcnt vmcnt(10)
	ds_write_b128 v95, v[152:155] offset:41472
	s_waitcnt lgkmcnt(8)
	v_mfma_f32_16x16x32_bf16 v[42:45], v[200:203], v[228:231], v[42:45]
	v_mfma_f32_16x16x32_bf16 v[46:49], v[200:203], v[232:235], v[46:49]
	v_mfma_f32_16x16x32_bf16 v[10:13], v[200:203], v[236:239], v[10:13]
	v_mfma_f32_16x16x32_bf16 v[14:17], v[200:203], v[240:243], v[14:17]
	s_waitcnt vmcnt(9)
	ds_write_b128 v95, v[156:159] offset:46080
	s_waitcnt vmcnt(8)
	ds_write_b128 v95, v[160:163] offset:50688
	s_waitcnt lgkmcnt(0)
	s_barrier
	ds_read_b128 v[212:215], v245 offset:36864
	ds_read_b128 v[196:199], v244
	ds_read_b128 v[216:219], v245 offset:39168
	ds_read_b128 v[220:223], v245 offset:41472
	ds_read_b128 v[224:227], v245 offset:43776
	ds_read_b128 v[200:203], v244 offset:2304
	s_setprio 0
	v_mfma_f32_16x16x32_bf16 v[50:53], v[204:207], v[228:231], v[50:53]
	v_mfma_f32_16x16x32_bf16 v[54:57], v[204:207], v[232:235], v[54:57]
	v_mfma_f32_16x16x32_bf16 v[18:21], v[204:207], v[236:239], v[18:21]
	v_mfma_f32_16x16x32_bf16 v[22:25], v[204:207], v[240:243], v[22:25]
	ds_read_b128 v[204:207], v244 offset:4608
	v_mfma_f32_16x16x32_bf16 v[58:61], v[208:211], v[228:231], v[58:61]
	v_mfma_f32_16x16x32_bf16 v[62:65], v[208:211], v[232:235], v[62:65]
	v_mfma_f32_16x16x32_bf16 v[26:29], v[208:211], v[236:239], v[26:29]
	v_mfma_f32_16x16x32_bf16 v[30:33], v[208:211], v[240:243], v[30:33]
	ds_read_b128 v[208:211], v244 offset:6912
	global_load_dwordx4 v[132:135], v[72:73], off offset:768
	global_load_dwordx4 v[136:139], v[74:75], off offset:768
	global_load_dwordx4 v[140:143], v[76:77], off offset:768
	global_load_dwordx4 v[144:147], v[78:79], off offset:768
	global_load_dwordx4 v[148:151], v[80:81], off offset:768
	global_load_dwordx4 v[152:155], v[82:83], off offset:768
	global_load_dwordx4 v[156:159], v[84:85], off offset:768
	global_load_dwordx4 v[160:163], v[86:87], off offset:768
	s_waitcnt lgkmcnt(6)
	v_mfma_f32_16x16x32_bf16 v[34:37], v[196:199], v[212:215], v[34:37]
	ds_read_b128 v[228:231], v245 offset:36928
	s_waitcnt lgkmcnt(6)
	v_mfma_f32_16x16x32_bf16 v[38:41], v[196:199], v[216:219], v[38:41]
	ds_read_b128 v[232:235], v245 offset:39232
	s_waitcnt lgkmcnt(6)
	v_mfma_f32_16x16x32_bf16 v[2:5], v[196:199], v[220:223], v[2:5]
	ds_read_b128 v[236:239], v245 offset:41536
	s_waitcnt lgkmcnt(6)
	v_mfma_f32_16x16x32_bf16 v[6:9], v[196:199], v[224:227], v[6:9]
	ds_read_b128 v[240:243], v245 offset:43840
	ds_read_b128 v[196:199], v244 offset:64
	s_waitcnt lgkmcnt(7)
	v_mfma_f32_16x16x32_bf16 v[42:45], v[200:203], v[212:215], v[42:45]
	v_mfma_f32_16x16x32_bf16 v[46:49], v[200:203], v[216:219], v[46:49]
	v_mfma_f32_16x16x32_bf16 v[10:13], v[200:203], v[220:223], v[10:13]
	v_mfma_f32_16x16x32_bf16 v[14:17], v[200:203], v[224:227], v[14:17]
	ds_read_b128 v[200:203], v244 offset:2368
	s_waitcnt lgkmcnt(7)
	v_mfma_f32_16x16x32_bf16 v[50:53], v[204:207], v[212:215], v[50:53]
	v_mfma_f32_16x16x32_bf16 v[54:57], v[204:207], v[216:219], v[54:57]
	v_mfma_f32_16x16x32_bf16 v[18:21], v[204:207], v[220:223], v[18:21]
	v_mfma_f32_16x16x32_bf16 v[22:25], v[204:207], v[224:227], v[22:25]
	ds_read_b128 v[204:207], v244 offset:4672
	s_setprio 1
	s_waitcnt vmcnt(15)
	ds_write_b128 v95, v[98:101] offset:18432
	s_waitcnt vmcnt(14)
	ds_write_b128 v95, v[102:105] offset:23040
	s_waitcnt lgkmcnt(9)
	v_mfma_f32_16x16x32_bf16 v[58:61], v[208:211], v[212:215], v[58:61]
	v_mfma_f32_16x16x32_bf16 v[62:65], v[208:211], v[216:219], v[62:65]
	v_mfma_f32_16x16x32_bf16 v[26:29], v[208:211], v[220:223], v[26:29]
	v_mfma_f32_16x16x32_bf16 v[30:33], v[208:211], v[224:227], v[30:33]
	ds_read_b128 v[208:211], v244 offset:6976
	s_waitcnt vmcnt(13)
	ds_write_b128 v95, v[106:109] offset:27648
	s_waitcnt vmcnt(12)
	ds_write_b128 v95, v[110:113] offset:32256
	s_waitcnt lgkmcnt(7)
	v_mfma_f32_16x16x32_bf16 v[34:37], v[196:199], v[228:231], v[34:37]
	v_mfma_f32_16x16x32_bf16 v[38:41], v[196:199], v[232:235], v[38:41]
	v_mfma_f32_16x16x32_bf16 v[2:5], v[196:199], v[236:239], v[2:5]
	v_mfma_f32_16x16x32_bf16 v[6:9], v[196:199], v[240:243], v[6:9]
	s_waitcnt vmcnt(11)
	ds_write_b128 v95, v[114:117] offset:55296
	s_waitcnt vmcnt(10)
	ds_write_b128 v95, v[118:121] offset:59904
	s_waitcnt lgkmcnt(8)
	v_mfma_f32_16x16x32_bf16 v[42:45], v[200:203], v[228:231], v[42:45]
	v_mfma_f32_16x16x32_bf16 v[46:49], v[200:203], v[232:235], v[46:49]
	v_mfma_f32_16x16x32_bf16 v[10:13], v[200:203], v[236:239], v[10:13]
	v_mfma_f32_16x16x32_bf16 v[14:17], v[200:203], v[240:243], v[14:17]
	s_waitcnt vmcnt(9)
	ds_write_b128 v95, v[122:125] offset:64512
	s_waitcnt vmcnt(8)
	ds_write_b128 v96, v[126:129] offset:32256
	s_waitcnt lgkmcnt(0)
	s_barrier
	ds_read_b128 v[212:215], v245 offset:55296
	ds_read_b128 v[196:199], v244 offset:18432
	ds_read_b128 v[216:219], v245 offset:57600
	ds_read_b128 v[220:223], v245 offset:59904
	ds_read_b128 v[224:227], v245 offset:62208
	ds_read_b128 v[200:203], v244 offset:20736
	s_setprio 0
	v_mfma_f32_16x16x32_bf16 v[50:53], v[204:207], v[228:231], v[50:53]
	v_mfma_f32_16x16x32_bf16 v[54:57], v[204:207], v[232:235], v[54:57]
	v_mfma_f32_16x16x32_bf16 v[18:21], v[204:207], v[236:239], v[18:21]
	v_mfma_f32_16x16x32_bf16 v[22:25], v[204:207], v[240:243], v[22:25]
	ds_read_b128 v[204:207], v244 offset:23040
	v_mfma_f32_16x16x32_bf16 v[58:61], v[208:211], v[228:231], v[58:61]
	v_mfma_f32_16x16x32_bf16 v[62:65], v[208:211], v[232:235], v[62:65]
	v_mfma_f32_16x16x32_bf16 v[26:29], v[208:211], v[236:239], v[26:29]
	v_mfma_f32_16x16x32_bf16 v[30:33], v[208:211], v[240:243], v[30:33]
	ds_read_b128 v[208:211], v244 offset:25344
	global_load_dwordx4 v[98:101], v[72:73], off offset:896
	global_load_dwordx4 v[102:105], v[74:75], off offset:896
	global_load_dwordx4 v[106:109], v[76:77], off offset:896
	global_load_dwordx4 v[110:113], v[78:79], off offset:896
	global_load_dwordx4 v[114:117], v[80:81], off offset:896
	global_load_dwordx4 v[118:121], v[82:83], off offset:896
	global_load_dwordx4 v[122:125], v[84:85], off offset:896
	global_load_dwordx4 v[126:129], v[86:87], off offset:896
	s_waitcnt lgkmcnt(6)
	v_mfma_f32_16x16x32_bf16 v[34:37], v[196:199], v[212:215], v[34:37]
	ds_read_b128 v[228:231], v245 offset:55360
	s_waitcnt lgkmcnt(6)
	v_mfma_f32_16x16x32_bf16 v[38:41], v[196:199], v[216:219], v[38:41]
	ds_read_b128 v[232:235], v245 offset:57664
	s_waitcnt lgkmcnt(6)
	v_mfma_f32_16x16x32_bf16 v[2:5], v[196:199], v[220:223], v[2:5]
	ds_read_b128 v[236:239], v245 offset:59968
	s_waitcnt lgkmcnt(6)
	v_mfma_f32_16x16x32_bf16 v[6:9], v[196:199], v[224:227], v[6:9]
	ds_read_b128 v[240:243], v245 offset:62272
	ds_read_b128 v[196:199], v244 offset:18496
	s_waitcnt lgkmcnt(7)
	v_mfma_f32_16x16x32_bf16 v[42:45], v[200:203], v[212:215], v[42:45]
	v_mfma_f32_16x16x32_bf16 v[46:49], v[200:203], v[216:219], v[46:49]
	v_mfma_f32_16x16x32_bf16 v[10:13], v[200:203], v[220:223], v[10:13]
	v_mfma_f32_16x16x32_bf16 v[14:17], v[200:203], v[224:227], v[14:17]
	ds_read_b128 v[200:203], v244 offset:20800
	s_waitcnt lgkmcnt(7)
	v_mfma_f32_16x16x32_bf16 v[50:53], v[204:207], v[212:215], v[50:53]
	v_mfma_f32_16x16x32_bf16 v[54:57], v[204:207], v[216:219], v[54:57]
	v_mfma_f32_16x16x32_bf16 v[18:21], v[204:207], v[220:223], v[18:21]
	v_mfma_f32_16x16x32_bf16 v[22:25], v[204:207], v[224:227], v[22:25]
	ds_read_b128 v[204:207], v244 offset:23104
	s_setprio 1
	s_waitcnt vmcnt(15)
	ds_write_b128 v95, v[132:135]
	s_waitcnt vmcnt(14)
	ds_write_b128 v95, v[136:139] offset:4608
	s_waitcnt lgkmcnt(9)
	v_mfma_f32_16x16x32_bf16 v[58:61], v[208:211], v[212:215], v[58:61]
	v_mfma_f32_16x16x32_bf16 v[62:65], v[208:211], v[216:219], v[62:65]
	v_mfma_f32_16x16x32_bf16 v[26:29], v[208:211], v[220:223], v[26:29]
	v_mfma_f32_16x16x32_bf16 v[30:33], v[208:211], v[224:227], v[30:33]
	ds_read_b128 v[208:211], v244 offset:25408
	s_waitcnt vmcnt(13)
	ds_write_b128 v95, v[140:143] offset:9216
	s_waitcnt vmcnt(12)
	ds_write_b128 v95, v[144:147] offset:13824
	s_waitcnt lgkmcnt(7)
	v_mfma_f32_16x16x32_bf16 v[34:37], v[196:199], v[228:231], v[34:37]
	v_mfma_f32_16x16x32_bf16 v[38:41], v[196:199], v[232:235], v[38:41]
	v_mfma_f32_16x16x32_bf16 v[2:5], v[196:199], v[236:239], v[2:5]
	v_mfma_f32_16x16x32_bf16 v[6:9], v[196:199], v[240:243], v[6:9]
	s_waitcnt vmcnt(11)
	ds_write_b128 v95, v[148:151] offset:36864
	s_waitcnt vmcnt(10)
	ds_write_b128 v95, v[152:155] offset:41472
	s_waitcnt lgkmcnt(8)
	v_mfma_f32_16x16x32_bf16 v[42:45], v[200:203], v[228:231], v[42:45]
	v_mfma_f32_16x16x32_bf16 v[46:49], v[200:203], v[232:235], v[46:49]
	v_mfma_f32_16x16x32_bf16 v[10:13], v[200:203], v[236:239], v[10:13]
	v_mfma_f32_16x16x32_bf16 v[14:17], v[200:203], v[240:243], v[14:17]
	s_waitcnt vmcnt(9)
	ds_write_b128 v95, v[156:159] offset:46080
	s_waitcnt vmcnt(8)
	ds_write_b128 v95, v[160:163] offset:50688
	s_waitcnt lgkmcnt(0)
	s_barrier
	ds_read_b128 v[212:215], v245 offset:36864
	ds_read_b128 v[196:199], v244
	ds_read_b128 v[216:219], v245 offset:39168
	ds_read_b128 v[220:223], v245 offset:41472
	ds_read_b128 v[224:227], v245 offset:43776
	ds_read_b128 v[200:203], v244 offset:2304
	s_setprio 0
	v_mfma_f32_16x16x32_bf16 v[50:53], v[204:207], v[228:231], v[50:53]
	v_mfma_f32_16x16x32_bf16 v[54:57], v[204:207], v[232:235], v[54:57]
	v_mfma_f32_16x16x32_bf16 v[18:21], v[204:207], v[236:239], v[18:21]
	v_mfma_f32_16x16x32_bf16 v[22:25], v[204:207], v[240:243], v[22:25]
	ds_read_b128 v[204:207], v244 offset:4608
	v_mfma_f32_16x16x32_bf16 v[58:61], v[208:211], v[228:231], v[58:61]
	v_mfma_f32_16x16x32_bf16 v[62:65], v[208:211], v[232:235], v[62:65]
	v_mfma_f32_16x16x32_bf16 v[26:29], v[208:211], v[236:239], v[26:29]
	v_mfma_f32_16x16x32_bf16 v[30:33], v[208:211], v[240:243], v[30:33]
	ds_read_b128 v[208:211], v244 offset:6912
	global_load_dwordx4 v[132:135], v[72:73], off offset:1024
	global_load_dwordx4 v[136:139], v[74:75], off offset:1024
	global_load_dwordx4 v[140:143], v[76:77], off offset:1024
	global_load_dwordx4 v[144:147], v[78:79], off offset:1024
	global_load_dwordx4 v[148:151], v[80:81], off offset:1024
	global_load_dwordx4 v[152:155], v[82:83], off offset:1024
	global_load_dwordx4 v[156:159], v[84:85], off offset:1024
	global_load_dwordx4 v[160:163], v[86:87], off offset:1024
	s_waitcnt lgkmcnt(6)
	v_mfma_f32_16x16x32_bf16 v[34:37], v[196:199], v[212:215], v[34:37]
	ds_read_b128 v[228:231], v245 offset:36928
	s_waitcnt lgkmcnt(6)
	v_mfma_f32_16x16x32_bf16 v[38:41], v[196:199], v[216:219], v[38:41]
	ds_read_b128 v[232:235], v245 offset:39232
	s_waitcnt lgkmcnt(6)
	v_mfma_f32_16x16x32_bf16 v[2:5], v[196:199], v[220:223], v[2:5]
	ds_read_b128 v[236:239], v245 offset:41536
	s_waitcnt lgkmcnt(6)
	v_mfma_f32_16x16x32_bf16 v[6:9], v[196:199], v[224:227], v[6:9]
	ds_read_b128 v[240:243], v245 offset:43840
	ds_read_b128 v[196:199], v244 offset:64
	s_waitcnt lgkmcnt(7)
	v_mfma_f32_16x16x32_bf16 v[42:45], v[200:203], v[212:215], v[42:45]
	v_mfma_f32_16x16x32_bf16 v[46:49], v[200:203], v[216:219], v[46:49]
	v_mfma_f32_16x16x32_bf16 v[10:13], v[200:203], v[220:223], v[10:13]
	v_mfma_f32_16x16x32_bf16 v[14:17], v[200:203], v[224:227], v[14:17]
	ds_read_b128 v[200:203], v244 offset:2368
	s_waitcnt lgkmcnt(7)
	v_mfma_f32_16x16x32_bf16 v[50:53], v[204:207], v[212:215], v[50:53]
	v_mfma_f32_16x16x32_bf16 v[54:57], v[204:207], v[216:219], v[54:57]
	v_mfma_f32_16x16x32_bf16 v[18:21], v[204:207], v[220:223], v[18:21]
	v_mfma_f32_16x16x32_bf16 v[22:25], v[204:207], v[224:227], v[22:25]
	ds_read_b128 v[204:207], v244 offset:4672
	s_setprio 1
	s_waitcnt vmcnt(15)
	ds_write_b128 v95, v[98:101] offset:18432
	s_waitcnt vmcnt(14)
	ds_write_b128 v95, v[102:105] offset:23040
	s_waitcnt lgkmcnt(9)
	v_mfma_f32_16x16x32_bf16 v[58:61], v[208:211], v[212:215], v[58:61]
	v_mfma_f32_16x16x32_bf16 v[62:65], v[208:211], v[216:219], v[62:65]
	v_mfma_f32_16x16x32_bf16 v[26:29], v[208:211], v[220:223], v[26:29]
	v_mfma_f32_16x16x32_bf16 v[30:33], v[208:211], v[224:227], v[30:33]
	ds_read_b128 v[208:211], v244 offset:6976
	s_waitcnt vmcnt(13)
	ds_write_b128 v95, v[106:109] offset:27648
	s_waitcnt vmcnt(12)
	ds_write_b128 v95, v[110:113] offset:32256
	s_waitcnt lgkmcnt(7)
	v_mfma_f32_16x16x32_bf16 v[34:37], v[196:199], v[228:231], v[34:37]
	v_mfma_f32_16x16x32_bf16 v[38:41], v[196:199], v[232:235], v[38:41]
	v_mfma_f32_16x16x32_bf16 v[2:5], v[196:199], v[236:239], v[2:5]
	v_mfma_f32_16x16x32_bf16 v[6:9], v[196:199], v[240:243], v[6:9]
	s_waitcnt vmcnt(11)
	ds_write_b128 v95, v[114:117] offset:55296
	s_waitcnt vmcnt(10)
	ds_write_b128 v95, v[118:121] offset:59904
	s_waitcnt lgkmcnt(8)
	v_mfma_f32_16x16x32_bf16 v[42:45], v[200:203], v[228:231], v[42:45]
	v_mfma_f32_16x16x32_bf16 v[46:49], v[200:203], v[232:235], v[46:49]
	v_mfma_f32_16x16x32_bf16 v[10:13], v[200:203], v[236:239], v[10:13]
	v_mfma_f32_16x16x32_bf16 v[14:17], v[200:203], v[240:243], v[14:17]
	s_waitcnt vmcnt(9)
	ds_write_b128 v95, v[122:125] offset:64512
	s_waitcnt vmcnt(8)
	ds_write_b128 v96, v[126:129] offset:32256
	s_waitcnt lgkmcnt(0)
	s_barrier
	ds_read_b128 v[212:215], v245 offset:55296
	ds_read_b128 v[196:199], v244 offset:18432
	ds_read_b128 v[216:219], v245 offset:57600
	ds_read_b128 v[220:223], v245 offset:59904
	ds_read_b128 v[224:227], v245 offset:62208
	ds_read_b128 v[200:203], v244 offset:20736
	s_setprio 0
	v_mfma_f32_16x16x32_bf16 v[50:53], v[204:207], v[228:231], v[50:53]
	v_mfma_f32_16x16x32_bf16 v[54:57], v[204:207], v[232:235], v[54:57]
	v_mfma_f32_16x16x32_bf16 v[18:21], v[204:207], v[236:239], v[18:21]
	v_mfma_f32_16x16x32_bf16 v[22:25], v[204:207], v[240:243], v[22:25]
	ds_read_b128 v[204:207], v244 offset:23040
	v_mfma_f32_16x16x32_bf16 v[58:61], v[208:211], v[228:231], v[58:61]
	v_mfma_f32_16x16x32_bf16 v[62:65], v[208:211], v[232:235], v[62:65]
	v_mfma_f32_16x16x32_bf16 v[26:29], v[208:211], v[236:239], v[26:29]
	v_mfma_f32_16x16x32_bf16 v[30:33], v[208:211], v[240:243], v[30:33]
	ds_read_b128 v[208:211], v244 offset:25344
	global_load_dwordx4 v[98:101], v[72:73], off offset:1152
	global_load_dwordx4 v[102:105], v[74:75], off offset:1152
	global_load_dwordx4 v[106:109], v[76:77], off offset:1152
	global_load_dwordx4 v[110:113], v[78:79], off offset:1152
	global_load_dwordx4 v[114:117], v[80:81], off offset:1152
	global_load_dwordx4 v[118:121], v[82:83], off offset:1152
	global_load_dwordx4 v[122:125], v[84:85], off offset:1152
	global_load_dwordx4 v[126:129], v[86:87], off offset:1152
	s_waitcnt lgkmcnt(6)
	v_mfma_f32_16x16x32_bf16 v[34:37], v[196:199], v[212:215], v[34:37]
	ds_read_b128 v[228:231], v245 offset:55360
	s_waitcnt lgkmcnt(6)
	v_mfma_f32_16x16x32_bf16 v[38:41], v[196:199], v[216:219], v[38:41]
	ds_read_b128 v[232:235], v245 offset:57664
	s_waitcnt lgkmcnt(6)
	v_mfma_f32_16x16x32_bf16 v[2:5], v[196:199], v[220:223], v[2:5]
	ds_read_b128 v[236:239], v245 offset:59968
	s_waitcnt lgkmcnt(6)
	v_mfma_f32_16x16x32_bf16 v[6:9], v[196:199], v[224:227], v[6:9]
	ds_read_b128 v[240:243], v245 offset:62272
	ds_read_b128 v[196:199], v244 offset:18496
	s_waitcnt lgkmcnt(7)
	v_mfma_f32_16x16x32_bf16 v[42:45], v[200:203], v[212:215], v[42:45]
	v_mfma_f32_16x16x32_bf16 v[46:49], v[200:203], v[216:219], v[46:49]
	v_mfma_f32_16x16x32_bf16 v[10:13], v[200:203], v[220:223], v[10:13]
	v_mfma_f32_16x16x32_bf16 v[14:17], v[200:203], v[224:227], v[14:17]
	ds_read_b128 v[200:203], v244 offset:20800
	s_waitcnt lgkmcnt(7)
	v_mfma_f32_16x16x32_bf16 v[50:53], v[204:207], v[212:215], v[50:53]
	v_mfma_f32_16x16x32_bf16 v[54:57], v[204:207], v[216:219], v[54:57]
	v_mfma_f32_16x16x32_bf16 v[18:21], v[204:207], v[220:223], v[18:21]
	v_mfma_f32_16x16x32_bf16 v[22:25], v[204:207], v[224:227], v[22:25]
	ds_read_b128 v[204:207], v244 offset:23104
	s_setprio 1
	s_waitcnt vmcnt(15)
	ds_write_b128 v95, v[132:135]
	s_waitcnt vmcnt(14)
	ds_write_b128 v95, v[136:139] offset:4608
	s_waitcnt lgkmcnt(9)
	v_mfma_f32_16x16x32_bf16 v[58:61], v[208:211], v[212:215], v[58:61]
	v_mfma_f32_16x16x32_bf16 v[62:65], v[208:211], v[216:219], v[62:65]
	v_mfma_f32_16x16x32_bf16 v[26:29], v[208:211], v[220:223], v[26:29]
	v_mfma_f32_16x16x32_bf16 v[30:33], v[208:211], v[224:227], v[30:33]
	ds_read_b128 v[208:211], v244 offset:25408
	s_waitcnt vmcnt(13)
	ds_write_b128 v95, v[140:143] offset:9216
	s_waitcnt vmcnt(12)
	ds_write_b128 v95, v[144:147] offset:13824
	s_waitcnt lgkmcnt(7)
	v_mfma_f32_16x16x32_bf16 v[34:37], v[196:199], v[228:231], v[34:37]
	v_mfma_f32_16x16x32_bf16 v[38:41], v[196:199], v[232:235], v[38:41]
	v_mfma_f32_16x16x32_bf16 v[2:5], v[196:199], v[236:239], v[2:5]
	v_mfma_f32_16x16x32_bf16 v[6:9], v[196:199], v[240:243], v[6:9]
	s_waitcnt vmcnt(11)
	ds_write_b128 v95, v[148:151] offset:36864
	s_waitcnt vmcnt(10)
	ds_write_b128 v95, v[152:155] offset:41472
	s_waitcnt lgkmcnt(8)
	v_mfma_f32_16x16x32_bf16 v[42:45], v[200:203], v[228:231], v[42:45]
	v_mfma_f32_16x16x32_bf16 v[46:49], v[200:203], v[232:235], v[46:49]
	v_mfma_f32_16x16x32_bf16 v[10:13], v[200:203], v[236:239], v[10:13]
	v_mfma_f32_16x16x32_bf16 v[14:17], v[200:203], v[240:243], v[14:17]
	s_waitcnt vmcnt(9)
	ds_write_b128 v95, v[156:159] offset:46080
	s_waitcnt vmcnt(8)
	ds_write_b128 v95, v[160:163] offset:50688
	s_waitcnt lgkmcnt(0)
	s_barrier
	ds_read_b128 v[212:215], v245 offset:36864
	ds_read_b128 v[196:199], v244
	ds_read_b128 v[216:219], v245 offset:39168
	ds_read_b128 v[220:223], v245 offset:41472
	ds_read_b128 v[224:227], v245 offset:43776
	ds_read_b128 v[200:203], v244 offset:2304
	s_setprio 0
	v_mfma_f32_16x16x32_bf16 v[50:53], v[204:207], v[228:231], v[50:53]
	v_mfma_f32_16x16x32_bf16 v[54:57], v[204:207], v[232:235], v[54:57]
	v_mfma_f32_16x16x32_bf16 v[18:21], v[204:207], v[236:239], v[18:21]
	v_mfma_f32_16x16x32_bf16 v[22:25], v[204:207], v[240:243], v[22:25]
	ds_read_b128 v[204:207], v244 offset:4608
	v_mfma_f32_16x16x32_bf16 v[58:61], v[208:211], v[228:231], v[58:61]
	v_mfma_f32_16x16x32_bf16 v[62:65], v[208:211], v[232:235], v[62:65]
	v_mfma_f32_16x16x32_bf16 v[26:29], v[208:211], v[236:239], v[26:29]
	v_mfma_f32_16x16x32_bf16 v[30:33], v[208:211], v[240:243], v[30:33]
	ds_read_b128 v[208:211], v244 offset:6912
	global_load_dwordx4 v[132:135], v[72:73], off offset:1280
	global_load_dwordx4 v[136:139], v[74:75], off offset:1280
	global_load_dwordx4 v[140:143], v[76:77], off offset:1280
	global_load_dwordx4 v[144:147], v[78:79], off offset:1280
	global_load_dwordx4 v[148:151], v[80:81], off offset:1280
	global_load_dwordx4 v[152:155], v[82:83], off offset:1280
	global_load_dwordx4 v[156:159], v[84:85], off offset:1280
	global_load_dwordx4 v[160:163], v[86:87], off offset:1280
	s_waitcnt lgkmcnt(6)
	v_mfma_f32_16x16x32_bf16 v[34:37], v[196:199], v[212:215], v[34:37]
	ds_read_b128 v[228:231], v245 offset:36928
	s_waitcnt lgkmcnt(6)
	v_mfma_f32_16x16x32_bf16 v[38:41], v[196:199], v[216:219], v[38:41]
	ds_read_b128 v[232:235], v245 offset:39232
	s_waitcnt lgkmcnt(6)
	v_mfma_f32_16x16x32_bf16 v[2:5], v[196:199], v[220:223], v[2:5]
	ds_read_b128 v[236:239], v245 offset:41536
	s_waitcnt lgkmcnt(6)
	v_mfma_f32_16x16x32_bf16 v[6:9], v[196:199], v[224:227], v[6:9]
	ds_read_b128 v[240:243], v245 offset:43840
	ds_read_b128 v[196:199], v244 offset:64
	s_waitcnt lgkmcnt(7)
	v_mfma_f32_16x16x32_bf16 v[42:45], v[200:203], v[212:215], v[42:45]
	v_mfma_f32_16x16x32_bf16 v[46:49], v[200:203], v[216:219], v[46:49]
	v_mfma_f32_16x16x32_bf16 v[10:13], v[200:203], v[220:223], v[10:13]
	v_mfma_f32_16x16x32_bf16 v[14:17], v[200:203], v[224:227], v[14:17]
	ds_read_b128 v[200:203], v244 offset:2368
	s_waitcnt lgkmcnt(7)
	v_mfma_f32_16x16x32_bf16 v[50:53], v[204:207], v[212:215], v[50:53]
	v_mfma_f32_16x16x32_bf16 v[54:57], v[204:207], v[216:219], v[54:57]
	v_mfma_f32_16x16x32_bf16 v[18:21], v[204:207], v[220:223], v[18:21]
	v_mfma_f32_16x16x32_bf16 v[22:25], v[204:207], v[224:227], v[22:25]
	ds_read_b128 v[204:207], v244 offset:4672
	s_setprio 1
	s_waitcnt vmcnt(15)
	ds_write_b128 v95, v[98:101] offset:18432
	s_waitcnt vmcnt(14)
	ds_write_b128 v95, v[102:105] offset:23040
	s_waitcnt lgkmcnt(9)
	v_mfma_f32_16x16x32_bf16 v[58:61], v[208:211], v[212:215], v[58:61]
	v_mfma_f32_16x16x32_bf16 v[62:65], v[208:211], v[216:219], v[62:65]
	v_mfma_f32_16x16x32_bf16 v[26:29], v[208:211], v[220:223], v[26:29]
	v_mfma_f32_16x16x32_bf16 v[30:33], v[208:211], v[224:227], v[30:33]
	ds_read_b128 v[208:211], v244 offset:6976
	s_waitcnt vmcnt(13)
	ds_write_b128 v95, v[106:109] offset:27648
	s_waitcnt vmcnt(12)
	ds_write_b128 v95, v[110:113] offset:32256
	s_waitcnt lgkmcnt(7)
	v_mfma_f32_16x16x32_bf16 v[34:37], v[196:199], v[228:231], v[34:37]
	v_mfma_f32_16x16x32_bf16 v[38:41], v[196:199], v[232:235], v[38:41]
	v_mfma_f32_16x16x32_bf16 v[2:5], v[196:199], v[236:239], v[2:5]
	v_mfma_f32_16x16x32_bf16 v[6:9], v[196:199], v[240:243], v[6:9]
	s_waitcnt vmcnt(11)
	ds_write_b128 v95, v[114:117] offset:55296
	s_waitcnt vmcnt(10)
	ds_write_b128 v95, v[118:121] offset:59904
	s_waitcnt lgkmcnt(8)
	v_mfma_f32_16x16x32_bf16 v[42:45], v[200:203], v[228:231], v[42:45]
	v_mfma_f32_16x16x32_bf16 v[46:49], v[200:203], v[232:235], v[46:49]
	v_mfma_f32_16x16x32_bf16 v[10:13], v[200:203], v[236:239], v[10:13]
	v_mfma_f32_16x16x32_bf16 v[14:17], v[200:203], v[240:243], v[14:17]
	s_waitcnt vmcnt(9)
	ds_write_b128 v95, v[122:125] offset:64512
	s_waitcnt vmcnt(8)
	ds_write_b128 v96, v[126:129] offset:32256
	s_waitcnt lgkmcnt(0)
	s_barrier
	ds_read_b128 v[212:215], v245 offset:55296
	ds_read_b128 v[196:199], v244 offset:18432
	ds_read_b128 v[216:219], v245 offset:57600
	ds_read_b128 v[220:223], v245 offset:59904
	ds_read_b128 v[224:227], v245 offset:62208
	ds_read_b128 v[200:203], v244 offset:20736
	s_setprio 0
	v_mfma_f32_16x16x32_bf16 v[50:53], v[204:207], v[228:231], v[50:53]
	v_mfma_f32_16x16x32_bf16 v[54:57], v[204:207], v[232:235], v[54:57]
	v_mfma_f32_16x16x32_bf16 v[18:21], v[204:207], v[236:239], v[18:21]
	v_mfma_f32_16x16x32_bf16 v[22:25], v[204:207], v[240:243], v[22:25]
	ds_read_b128 v[204:207], v244 offset:23040
	v_mfma_f32_16x16x32_bf16 v[58:61], v[208:211], v[228:231], v[58:61]
	v_mfma_f32_16x16x32_bf16 v[62:65], v[208:211], v[232:235], v[62:65]
	v_mfma_f32_16x16x32_bf16 v[26:29], v[208:211], v[236:239], v[26:29]
	v_mfma_f32_16x16x32_bf16 v[30:33], v[208:211], v[240:243], v[30:33]
	ds_read_b128 v[208:211], v244 offset:25344
	global_load_dwordx4 v[98:101], v[72:73], off offset:1408
	global_load_dwordx4 v[102:105], v[74:75], off offset:1408
	global_load_dwordx4 v[106:109], v[76:77], off offset:1408
	global_load_dwordx4 v[110:113], v[78:79], off offset:1408
	global_load_dwordx4 v[114:117], v[80:81], off offset:1408
	global_load_dwordx4 v[118:121], v[82:83], off offset:1408
	global_load_dwordx4 v[122:125], v[84:85], off offset:1408
	global_load_dwordx4 v[126:129], v[86:87], off offset:1408
	s_waitcnt lgkmcnt(6)
	v_mfma_f32_16x16x32_bf16 v[34:37], v[196:199], v[212:215], v[34:37]
	ds_read_b128 v[228:231], v245 offset:55360
	s_waitcnt lgkmcnt(6)
	v_mfma_f32_16x16x32_bf16 v[38:41], v[196:199], v[216:219], v[38:41]
	ds_read_b128 v[232:235], v245 offset:57664
	s_waitcnt lgkmcnt(6)
	v_mfma_f32_16x16x32_bf16 v[2:5], v[196:199], v[220:223], v[2:5]
	ds_read_b128 v[236:239], v245 offset:59968
	s_waitcnt lgkmcnt(6)
	v_mfma_f32_16x16x32_bf16 v[6:9], v[196:199], v[224:227], v[6:9]
	ds_read_b128 v[240:243], v245 offset:62272
	ds_read_b128 v[196:199], v244 offset:18496
	s_waitcnt lgkmcnt(7)
	v_mfma_f32_16x16x32_bf16 v[42:45], v[200:203], v[212:215], v[42:45]
	v_mfma_f32_16x16x32_bf16 v[46:49], v[200:203], v[216:219], v[46:49]
	v_mfma_f32_16x16x32_bf16 v[10:13], v[200:203], v[220:223], v[10:13]
	v_mfma_f32_16x16x32_bf16 v[14:17], v[200:203], v[224:227], v[14:17]
	ds_read_b128 v[200:203], v244 offset:20800
	s_waitcnt lgkmcnt(7)
	v_mfma_f32_16x16x32_bf16 v[50:53], v[204:207], v[212:215], v[50:53]
	v_mfma_f32_16x16x32_bf16 v[54:57], v[204:207], v[216:219], v[54:57]
	v_mfma_f32_16x16x32_bf16 v[18:21], v[204:207], v[220:223], v[18:21]
	v_mfma_f32_16x16x32_bf16 v[22:25], v[204:207], v[224:227], v[22:25]
	ds_read_b128 v[204:207], v244 offset:23104
	s_setprio 1
	s_waitcnt vmcnt(15)
	ds_write_b128 v95, v[132:135]
	s_waitcnt vmcnt(14)
	ds_write_b128 v95, v[136:139] offset:4608
	s_waitcnt lgkmcnt(9)
	v_mfma_f32_16x16x32_bf16 v[58:61], v[208:211], v[212:215], v[58:61]
	v_mfma_f32_16x16x32_bf16 v[62:65], v[208:211], v[216:219], v[62:65]
	v_mfma_f32_16x16x32_bf16 v[26:29], v[208:211], v[220:223], v[26:29]
	v_mfma_f32_16x16x32_bf16 v[30:33], v[208:211], v[224:227], v[30:33]
	ds_read_b128 v[208:211], v244 offset:25408
	s_waitcnt vmcnt(13)
	ds_write_b128 v95, v[140:143] offset:9216
	s_waitcnt vmcnt(12)
	ds_write_b128 v95, v[144:147] offset:13824
	s_waitcnt lgkmcnt(7)
	v_mfma_f32_16x16x32_bf16 v[34:37], v[196:199], v[228:231], v[34:37]
	v_mfma_f32_16x16x32_bf16 v[38:41], v[196:199], v[232:235], v[38:41]
	v_mfma_f32_16x16x32_bf16 v[2:5], v[196:199], v[236:239], v[2:5]
	v_mfma_f32_16x16x32_bf16 v[6:9], v[196:199], v[240:243], v[6:9]
	s_waitcnt vmcnt(11)
	ds_write_b128 v95, v[148:151] offset:36864
	s_waitcnt vmcnt(10)
	ds_write_b128 v95, v[152:155] offset:41472
	s_waitcnt lgkmcnt(8)
	v_mfma_f32_16x16x32_bf16 v[42:45], v[200:203], v[228:231], v[42:45]
	v_mfma_f32_16x16x32_bf16 v[46:49], v[200:203], v[232:235], v[46:49]
	v_mfma_f32_16x16x32_bf16 v[10:13], v[200:203], v[236:239], v[10:13]
	v_mfma_f32_16x16x32_bf16 v[14:17], v[200:203], v[240:243], v[14:17]
	s_waitcnt vmcnt(9)
	ds_write_b128 v95, v[156:159] offset:46080
	s_waitcnt vmcnt(8)
	ds_write_b128 v95, v[160:163] offset:50688
	s_waitcnt lgkmcnt(0)
	s_barrier
	ds_read_b128 v[212:215], v245 offset:36864
	ds_read_b128 v[196:199], v244
	ds_read_b128 v[216:219], v245 offset:39168
	ds_read_b128 v[220:223], v245 offset:41472
	ds_read_b128 v[224:227], v245 offset:43776
	ds_read_b128 v[200:203], v244 offset:2304
	s_setprio 0
	v_mfma_f32_16x16x32_bf16 v[50:53], v[204:207], v[228:231], v[50:53]
	v_mfma_f32_16x16x32_bf16 v[54:57], v[204:207], v[232:235], v[54:57]
	v_mfma_f32_16x16x32_bf16 v[18:21], v[204:207], v[236:239], v[18:21]
	v_mfma_f32_16x16x32_bf16 v[22:25], v[204:207], v[240:243], v[22:25]
	ds_read_b128 v[204:207], v244 offset:4608
	v_mfma_f32_16x16x32_bf16 v[58:61], v[208:211], v[228:231], v[58:61]
	v_mfma_f32_16x16x32_bf16 v[62:65], v[208:211], v[232:235], v[62:65]
	v_mfma_f32_16x16x32_bf16 v[26:29], v[208:211], v[236:239], v[26:29]
	v_mfma_f32_16x16x32_bf16 v[30:33], v[208:211], v[240:243], v[30:33]
	ds_read_b128 v[208:211], v244 offset:6912
	global_load_dwordx4 v[132:135], v[72:73], off offset:1536
	global_load_dwordx4 v[136:139], v[74:75], off offset:1536
	global_load_dwordx4 v[140:143], v[76:77], off offset:1536
	global_load_dwordx4 v[144:147], v[78:79], off offset:1536
	global_load_dwordx4 v[148:151], v[80:81], off offset:1536
	global_load_dwordx4 v[152:155], v[82:83], off offset:1536
	global_load_dwordx4 v[156:159], v[84:85], off offset:1536
	global_load_dwordx4 v[160:163], v[86:87], off offset:1536
	s_waitcnt lgkmcnt(6)
	v_mfma_f32_16x16x32_bf16 v[34:37], v[196:199], v[212:215], v[34:37]
	ds_read_b128 v[228:231], v245 offset:36928
	s_waitcnt lgkmcnt(6)
	v_mfma_f32_16x16x32_bf16 v[38:41], v[196:199], v[216:219], v[38:41]
	ds_read_b128 v[232:235], v245 offset:39232
	s_waitcnt lgkmcnt(6)
	v_mfma_f32_16x16x32_bf16 v[2:5], v[196:199], v[220:223], v[2:5]
	ds_read_b128 v[236:239], v245 offset:41536
	s_waitcnt lgkmcnt(6)
	v_mfma_f32_16x16x32_bf16 v[6:9], v[196:199], v[224:227], v[6:9]
	ds_read_b128 v[240:243], v245 offset:43840
	ds_read_b128 v[196:199], v244 offset:64
	s_waitcnt lgkmcnt(7)
	v_mfma_f32_16x16x32_bf16 v[42:45], v[200:203], v[212:215], v[42:45]
	v_mfma_f32_16x16x32_bf16 v[46:49], v[200:203], v[216:219], v[46:49]
	v_mfma_f32_16x16x32_bf16 v[10:13], v[200:203], v[220:223], v[10:13]
	v_mfma_f32_16x16x32_bf16 v[14:17], v[200:203], v[224:227], v[14:17]
	ds_read_b128 v[200:203], v244 offset:2368
	s_waitcnt lgkmcnt(7)
	v_mfma_f32_16x16x32_bf16 v[50:53], v[204:207], v[212:215], v[50:53]
	v_mfma_f32_16x16x32_bf16 v[54:57], v[204:207], v[216:219], v[54:57]
	v_mfma_f32_16x16x32_bf16 v[18:21], v[204:207], v[220:223], v[18:21]
	v_mfma_f32_16x16x32_bf16 v[22:25], v[204:207], v[224:227], v[22:25]
	ds_read_b128 v[204:207], v244 offset:4672
	s_setprio 1
	s_waitcnt vmcnt(15)
	ds_write_b128 v95, v[98:101] offset:18432
	s_waitcnt vmcnt(14)
	ds_write_b128 v95, v[102:105] offset:23040
	s_waitcnt lgkmcnt(9)
	v_mfma_f32_16x16x32_bf16 v[58:61], v[208:211], v[212:215], v[58:61]
	v_mfma_f32_16x16x32_bf16 v[62:65], v[208:211], v[216:219], v[62:65]
	v_mfma_f32_16x16x32_bf16 v[26:29], v[208:211], v[220:223], v[26:29]
	v_mfma_f32_16x16x32_bf16 v[30:33], v[208:211], v[224:227], v[30:33]
	ds_read_b128 v[208:211], v244 offset:6976
	s_waitcnt vmcnt(13)
	ds_write_b128 v95, v[106:109] offset:27648
	s_waitcnt vmcnt(12)
	ds_write_b128 v95, v[110:113] offset:32256
	s_waitcnt lgkmcnt(7)
	v_mfma_f32_16x16x32_bf16 v[34:37], v[196:199], v[228:231], v[34:37]
	v_mfma_f32_16x16x32_bf16 v[38:41], v[196:199], v[232:235], v[38:41]
	v_mfma_f32_16x16x32_bf16 v[2:5], v[196:199], v[236:239], v[2:5]
	v_mfma_f32_16x16x32_bf16 v[6:9], v[196:199], v[240:243], v[6:9]
	s_waitcnt vmcnt(11)
	ds_write_b128 v95, v[114:117] offset:55296
	s_waitcnt vmcnt(10)
	ds_write_b128 v95, v[118:121] offset:59904
	s_waitcnt lgkmcnt(8)
	v_mfma_f32_16x16x32_bf16 v[42:45], v[200:203], v[228:231], v[42:45]
	v_mfma_f32_16x16x32_bf16 v[46:49], v[200:203], v[232:235], v[46:49]
	v_mfma_f32_16x16x32_bf16 v[10:13], v[200:203], v[236:239], v[10:13]
	v_mfma_f32_16x16x32_bf16 v[14:17], v[200:203], v[240:243], v[14:17]
	s_waitcnt vmcnt(9)
	ds_write_b128 v95, v[122:125] offset:64512
	s_waitcnt vmcnt(8)
	ds_write_b128 v96, v[126:129] offset:32256
	s_waitcnt lgkmcnt(0)
	s_barrier
	ds_read_b128 v[212:215], v245 offset:55296
	ds_read_b128 v[196:199], v244 offset:18432
	ds_read_b128 v[216:219], v245 offset:57600
	ds_read_b128 v[220:223], v245 offset:59904
	ds_read_b128 v[224:227], v245 offset:62208
	ds_read_b128 v[200:203], v244 offset:20736
	s_setprio 0
	v_mfma_f32_16x16x32_bf16 v[50:53], v[204:207], v[228:231], v[50:53]
	v_mfma_f32_16x16x32_bf16 v[54:57], v[204:207], v[232:235], v[54:57]
	v_mfma_f32_16x16x32_bf16 v[18:21], v[204:207], v[236:239], v[18:21]
	v_mfma_f32_16x16x32_bf16 v[22:25], v[204:207], v[240:243], v[22:25]
	ds_read_b128 v[204:207], v244 offset:23040
	v_mfma_f32_16x16x32_bf16 v[58:61], v[208:211], v[228:231], v[58:61]
	v_mfma_f32_16x16x32_bf16 v[62:65], v[208:211], v[232:235], v[62:65]
	v_mfma_f32_16x16x32_bf16 v[26:29], v[208:211], v[236:239], v[26:29]
	v_mfma_f32_16x16x32_bf16 v[30:33], v[208:211], v[240:243], v[30:33]
	ds_read_b128 v[208:211], v244 offset:25344
	global_load_dwordx4 v[98:101], v[72:73], off offset:1664
	global_load_dwordx4 v[102:105], v[74:75], off offset:1664
	global_load_dwordx4 v[106:109], v[76:77], off offset:1664
	global_load_dwordx4 v[110:113], v[78:79], off offset:1664
	global_load_dwordx4 v[114:117], v[80:81], off offset:1664
	global_load_dwordx4 v[118:121], v[82:83], off offset:1664
	global_load_dwordx4 v[122:125], v[84:85], off offset:1664
	global_load_dwordx4 v[126:129], v[86:87], off offset:1664
	s_waitcnt lgkmcnt(6)
	v_mfma_f32_16x16x32_bf16 v[34:37], v[196:199], v[212:215], v[34:37]
	ds_read_b128 v[228:231], v245 offset:55360
	s_waitcnt lgkmcnt(6)
	v_mfma_f32_16x16x32_bf16 v[38:41], v[196:199], v[216:219], v[38:41]
	ds_read_b128 v[232:235], v245 offset:57664
	s_waitcnt lgkmcnt(6)
	v_mfma_f32_16x16x32_bf16 v[2:5], v[196:199], v[220:223], v[2:5]
	ds_read_b128 v[236:239], v245 offset:59968
	s_waitcnt lgkmcnt(6)
	v_mfma_f32_16x16x32_bf16 v[6:9], v[196:199], v[224:227], v[6:9]
	ds_read_b128 v[240:243], v245 offset:62272
	ds_read_b128 v[196:199], v244 offset:18496
	s_waitcnt lgkmcnt(7)
	v_mfma_f32_16x16x32_bf16 v[42:45], v[200:203], v[212:215], v[42:45]
	v_mfma_f32_16x16x32_bf16 v[46:49], v[200:203], v[216:219], v[46:49]
	v_mfma_f32_16x16x32_bf16 v[10:13], v[200:203], v[220:223], v[10:13]
	v_mfma_f32_16x16x32_bf16 v[14:17], v[200:203], v[224:227], v[14:17]
	ds_read_b128 v[200:203], v244 offset:20800
	s_waitcnt lgkmcnt(7)
	v_mfma_f32_16x16x32_bf16 v[50:53], v[204:207], v[212:215], v[50:53]
	v_mfma_f32_16x16x32_bf16 v[54:57], v[204:207], v[216:219], v[54:57]
	v_mfma_f32_16x16x32_bf16 v[18:21], v[204:207], v[220:223], v[18:21]
	v_mfma_f32_16x16x32_bf16 v[22:25], v[204:207], v[224:227], v[22:25]
	ds_read_b128 v[204:207], v244 offset:23104
	s_setprio 1
	s_waitcnt vmcnt(15)
	ds_write_b128 v95, v[132:135]
	s_waitcnt vmcnt(14)
	ds_write_b128 v95, v[136:139] offset:4608
	s_waitcnt lgkmcnt(9)
	v_mfma_f32_16x16x32_bf16 v[58:61], v[208:211], v[212:215], v[58:61]
	v_mfma_f32_16x16x32_bf16 v[62:65], v[208:211], v[216:219], v[62:65]
	v_mfma_f32_16x16x32_bf16 v[26:29], v[208:211], v[220:223], v[26:29]
	v_mfma_f32_16x16x32_bf16 v[30:33], v[208:211], v[224:227], v[30:33]
	ds_read_b128 v[208:211], v244 offset:25408
	s_waitcnt vmcnt(13)
	ds_write_b128 v95, v[140:143] offset:9216
	s_waitcnt vmcnt(12)
	ds_write_b128 v95, v[144:147] offset:13824
	s_waitcnt lgkmcnt(7)
	v_mfma_f32_16x16x32_bf16 v[34:37], v[196:199], v[228:231], v[34:37]
	v_mfma_f32_16x16x32_bf16 v[38:41], v[196:199], v[232:235], v[38:41]
	v_mfma_f32_16x16x32_bf16 v[2:5], v[196:199], v[236:239], v[2:5]
	v_mfma_f32_16x16x32_bf16 v[6:9], v[196:199], v[240:243], v[6:9]
	s_waitcnt vmcnt(11)
	ds_write_b128 v95, v[148:151] offset:36864
	s_waitcnt vmcnt(10)
	ds_write_b128 v95, v[152:155] offset:41472
	s_waitcnt lgkmcnt(8)
	v_mfma_f32_16x16x32_bf16 v[42:45], v[200:203], v[228:231], v[42:45]
	v_mfma_f32_16x16x32_bf16 v[46:49], v[200:203], v[232:235], v[46:49]
	v_mfma_f32_16x16x32_bf16 v[10:13], v[200:203], v[236:239], v[10:13]
	v_mfma_f32_16x16x32_bf16 v[14:17], v[200:203], v[240:243], v[14:17]
	s_waitcnt vmcnt(9)
	ds_write_b128 v95, v[156:159] offset:46080
	s_waitcnt vmcnt(8)
	ds_write_b128 v95, v[160:163] offset:50688
	s_waitcnt lgkmcnt(0)
	s_barrier
	ds_read_b128 v[212:215], v245 offset:36864
	ds_read_b128 v[196:199], v244
	ds_read_b128 v[216:219], v245 offset:39168
	ds_read_b128 v[220:223], v245 offset:41472
	ds_read_b128 v[224:227], v245 offset:43776
	ds_read_b128 v[200:203], v244 offset:2304
	s_setprio 0
	v_mfma_f32_16x16x32_bf16 v[50:53], v[204:207], v[228:231], v[50:53]
	v_mfma_f32_16x16x32_bf16 v[54:57], v[204:207], v[232:235], v[54:57]
	v_mfma_f32_16x16x32_bf16 v[18:21], v[204:207], v[236:239], v[18:21]
	v_mfma_f32_16x16x32_bf16 v[22:25], v[204:207], v[240:243], v[22:25]
	ds_read_b128 v[204:207], v244 offset:4608
	v_mfma_f32_16x16x32_bf16 v[58:61], v[208:211], v[228:231], v[58:61]
	v_mfma_f32_16x16x32_bf16 v[62:65], v[208:211], v[232:235], v[62:65]
	v_mfma_f32_16x16x32_bf16 v[26:29], v[208:211], v[236:239], v[26:29]
	v_mfma_f32_16x16x32_bf16 v[30:33], v[208:211], v[240:243], v[30:33]
	ds_read_b128 v[208:211], v244 offset:6912
	global_load_dwordx4 v[132:135], v[72:73], off offset:1792
	global_load_dwordx4 v[136:139], v[74:75], off offset:1792
	global_load_dwordx4 v[140:143], v[76:77], off offset:1792
	global_load_dwordx4 v[144:147], v[78:79], off offset:1792
	global_load_dwordx4 v[148:151], v[80:81], off offset:1792
	global_load_dwordx4 v[152:155], v[82:83], off offset:1792
	global_load_dwordx4 v[156:159], v[84:85], off offset:1792
	global_load_dwordx4 v[160:163], v[86:87], off offset:1792
	s_waitcnt lgkmcnt(6)
	v_mfma_f32_16x16x32_bf16 v[34:37], v[196:199], v[212:215], v[34:37]
	ds_read_b128 v[228:231], v245 offset:36928
	s_waitcnt lgkmcnt(6)
	v_mfma_f32_16x16x32_bf16 v[38:41], v[196:199], v[216:219], v[38:41]
	ds_read_b128 v[232:235], v245 offset:39232
	s_waitcnt lgkmcnt(6)
	v_mfma_f32_16x16x32_bf16 v[2:5], v[196:199], v[220:223], v[2:5]
	ds_read_b128 v[236:239], v245 offset:41536
	s_waitcnt lgkmcnt(6)
	v_mfma_f32_16x16x32_bf16 v[6:9], v[196:199], v[224:227], v[6:9]
	ds_read_b128 v[240:243], v245 offset:43840
	ds_read_b128 v[196:199], v244 offset:64
	s_waitcnt lgkmcnt(7)
	v_mfma_f32_16x16x32_bf16 v[42:45], v[200:203], v[212:215], v[42:45]
	v_mfma_f32_16x16x32_bf16 v[46:49], v[200:203], v[216:219], v[46:49]
	v_mfma_f32_16x16x32_bf16 v[10:13], v[200:203], v[220:223], v[10:13]
	v_mfma_f32_16x16x32_bf16 v[14:17], v[200:203], v[224:227], v[14:17]
	ds_read_b128 v[200:203], v244 offset:2368
	s_waitcnt lgkmcnt(7)
	v_mfma_f32_16x16x32_bf16 v[50:53], v[204:207], v[212:215], v[50:53]
	v_mfma_f32_16x16x32_bf16 v[54:57], v[204:207], v[216:219], v[54:57]
	v_mfma_f32_16x16x32_bf16 v[18:21], v[204:207], v[220:223], v[18:21]
	v_mfma_f32_16x16x32_bf16 v[22:25], v[204:207], v[224:227], v[22:25]
	ds_read_b128 v[204:207], v244 offset:4672
	s_setprio 1
	s_waitcnt vmcnt(15)
	ds_write_b128 v95, v[98:101] offset:18432
	s_waitcnt vmcnt(14)
	ds_write_b128 v95, v[102:105] offset:23040
	s_waitcnt lgkmcnt(9)
	v_mfma_f32_16x16x32_bf16 v[58:61], v[208:211], v[212:215], v[58:61]
	v_mfma_f32_16x16x32_bf16 v[62:65], v[208:211], v[216:219], v[62:65]
	v_mfma_f32_16x16x32_bf16 v[26:29], v[208:211], v[220:223], v[26:29]
	v_mfma_f32_16x16x32_bf16 v[30:33], v[208:211], v[224:227], v[30:33]
	ds_read_b128 v[208:211], v244 offset:6976
	s_waitcnt vmcnt(13)
	ds_write_b128 v95, v[106:109] offset:27648
	s_waitcnt vmcnt(12)
	ds_write_b128 v95, v[110:113] offset:32256
	s_waitcnt lgkmcnt(7)
	v_mfma_f32_16x16x32_bf16 v[34:37], v[196:199], v[228:231], v[34:37]
	v_mfma_f32_16x16x32_bf16 v[38:41], v[196:199], v[232:235], v[38:41]
	v_mfma_f32_16x16x32_bf16 v[2:5], v[196:199], v[236:239], v[2:5]
	v_mfma_f32_16x16x32_bf16 v[6:9], v[196:199], v[240:243], v[6:9]
	s_waitcnt vmcnt(11)
	ds_write_b128 v95, v[114:117] offset:55296
	s_waitcnt vmcnt(10)
	ds_write_b128 v95, v[118:121] offset:59904
	s_waitcnt lgkmcnt(8)
	v_mfma_f32_16x16x32_bf16 v[42:45], v[200:203], v[228:231], v[42:45]
	v_mfma_f32_16x16x32_bf16 v[46:49], v[200:203], v[232:235], v[46:49]
	v_mfma_f32_16x16x32_bf16 v[10:13], v[200:203], v[236:239], v[10:13]
	v_mfma_f32_16x16x32_bf16 v[14:17], v[200:203], v[240:243], v[14:17]
	s_waitcnt vmcnt(9)
	ds_write_b128 v95, v[122:125] offset:64512
	s_waitcnt vmcnt(8)
	ds_write_b128 v96, v[126:129] offset:32256
	s_waitcnt lgkmcnt(0)
	s_barrier
	ds_read_b128 v[212:215], v245 offset:55296
	ds_read_b128 v[196:199], v244 offset:18432
	ds_read_b128 v[216:219], v245 offset:57600
	ds_read_b128 v[220:223], v245 offset:59904
	ds_read_b128 v[224:227], v245 offset:62208
	ds_read_b128 v[200:203], v244 offset:20736
	s_setprio 0
	v_mfma_f32_16x16x32_bf16 v[50:53], v[204:207], v[228:231], v[50:53]
	v_mfma_f32_16x16x32_bf16 v[54:57], v[204:207], v[232:235], v[54:57]
	v_mfma_f32_16x16x32_bf16 v[18:21], v[204:207], v[236:239], v[18:21]
	v_mfma_f32_16x16x32_bf16 v[22:25], v[204:207], v[240:243], v[22:25]
	ds_read_b128 v[204:207], v244 offset:23040
	v_mfma_f32_16x16x32_bf16 v[58:61], v[208:211], v[228:231], v[58:61]
	v_mfma_f32_16x16x32_bf16 v[62:65], v[208:211], v[232:235], v[62:65]
	v_mfma_f32_16x16x32_bf16 v[26:29], v[208:211], v[236:239], v[26:29]
	v_mfma_f32_16x16x32_bf16 v[30:33], v[208:211], v[240:243], v[30:33]
	ds_read_b128 v[208:211], v244 offset:25344
	global_load_dwordx4 v[98:101], v[72:73], off offset:1920
	s_nop 0
	global_load_dwordx4 v[72:75], v[74:75], off offset:1920
	s_nop 0
	global_load_dwordx4 v[102:105], v[76:77], off offset:1920
	s_nop 0
	global_load_dwordx4 v[76:79], v[78:79], off offset:1920
	s_nop 0
	global_load_dwordx4 v[106:109], v[80:81], off offset:1920
	s_nop 0
	global_load_dwordx4 v[80:83], v[82:83], off offset:1920
	s_nop 0
	global_load_dwordx4 v[110:113], v[84:85], off offset:1920
	s_nop 0
	global_load_dwordx4 v[84:87], v[86:87], off offset:1920
	s_waitcnt lgkmcnt(6)
	v_mfma_f32_16x16x32_bf16 v[34:37], v[196:199], v[212:215], v[34:37]
	ds_read_b128 v[228:231], v245 offset:55360
	s_waitcnt lgkmcnt(6)
	v_mfma_f32_16x16x32_bf16 v[38:41], v[196:199], v[216:219], v[38:41]
	ds_read_b128 v[232:235], v245 offset:57664
	s_waitcnt lgkmcnt(6)
	v_mfma_f32_16x16x32_bf16 v[2:5], v[196:199], v[220:223], v[2:5]
	ds_read_b128 v[236:239], v245 offset:59968
	s_waitcnt lgkmcnt(6)
	v_mfma_f32_16x16x32_bf16 v[6:9], v[196:199], v[224:227], v[6:9]
	ds_read_b128 v[240:243], v245 offset:62272
	ds_read_b128 v[196:199], v244 offset:18496
	s_waitcnt lgkmcnt(7)
	v_mfma_f32_16x16x32_bf16 v[42:45], v[200:203], v[212:215], v[42:45]
	v_mfma_f32_16x16x32_bf16 v[46:49], v[200:203], v[216:219], v[46:49]
	v_mfma_f32_16x16x32_bf16 v[10:13], v[200:203], v[220:223], v[10:13]
	v_mfma_f32_16x16x32_bf16 v[14:17], v[200:203], v[224:227], v[14:17]
	ds_read_b128 v[200:203], v244 offset:20800
	s_waitcnt lgkmcnt(7)
	v_mfma_f32_16x16x32_bf16 v[50:53], v[204:207], v[212:215], v[50:53]
	v_mfma_f32_16x16x32_bf16 v[54:57], v[204:207], v[216:219], v[54:57]
	v_mfma_f32_16x16x32_bf16 v[18:21], v[204:207], v[220:223], v[18:21]
	v_mfma_f32_16x16x32_bf16 v[22:25], v[204:207], v[224:227], v[22:25]
	ds_read_b128 v[204:207], v244 offset:23104
	s_setprio 1
	s_waitcnt vmcnt(15)
	ds_write_b128 v95, v[132:135]
	s_waitcnt vmcnt(14)
	ds_write_b128 v95, v[136:139] offset:4608
	s_waitcnt lgkmcnt(9)
	v_mfma_f32_16x16x32_bf16 v[58:61], v[208:211], v[212:215], v[58:61]
	v_mfma_f32_16x16x32_bf16 v[62:65], v[208:211], v[216:219], v[62:65]
	v_mfma_f32_16x16x32_bf16 v[26:29], v[208:211], v[220:223], v[26:29]
	v_mfma_f32_16x16x32_bf16 v[30:33], v[208:211], v[224:227], v[30:33]
	ds_read_b128 v[208:211], v244 offset:25408
	s_waitcnt vmcnt(13)
	ds_write_b128 v95, v[140:143] offset:9216
	s_waitcnt vmcnt(12)
	ds_write_b128 v95, v[144:147] offset:13824
	s_waitcnt lgkmcnt(7)
	v_mfma_f32_16x16x32_bf16 v[34:37], v[196:199], v[228:231], v[34:37]
	v_mfma_f32_16x16x32_bf16 v[38:41], v[196:199], v[232:235], v[38:41]
	v_mfma_f32_16x16x32_bf16 v[2:5], v[196:199], v[236:239], v[2:5]
	v_mfma_f32_16x16x32_bf16 v[6:9], v[196:199], v[240:243], v[6:9]
	s_waitcnt vmcnt(11)
	ds_write_b128 v95, v[148:151] offset:36864
	s_waitcnt vmcnt(10)
	ds_write_b128 v95, v[152:155] offset:41472
	s_waitcnt lgkmcnt(8)
	v_mfma_f32_16x16x32_bf16 v[42:45], v[200:203], v[228:231], v[42:45]
	v_mfma_f32_16x16x32_bf16 v[46:49], v[200:203], v[232:235], v[46:49]
	v_mfma_f32_16x16x32_bf16 v[10:13], v[200:203], v[236:239], v[10:13]
	v_mfma_f32_16x16x32_bf16 v[14:17], v[200:203], v[240:243], v[14:17]
	s_waitcnt vmcnt(9)
	ds_write_b128 v95, v[156:159] offset:46080
	s_waitcnt vmcnt(8)
	ds_write_b128 v95, v[160:163] offset:50688
	s_waitcnt lgkmcnt(0)
	s_barrier
	ds_read_b128 v[212:215], v245 offset:36864
	ds_read_b128 v[196:199], v244
	ds_read_b128 v[216:219], v245 offset:39168
	ds_read_b128 v[220:223], v245 offset:41472
	ds_read_b128 v[224:227], v245 offset:43776
	ds_read_b128 v[200:203], v244 offset:2304
	s_setprio 0
	v_mfma_f32_16x16x32_bf16 v[50:53], v[204:207], v[228:231], v[50:53]
	v_mfma_f32_16x16x32_bf16 v[54:57], v[204:207], v[232:235], v[54:57]
	v_mfma_f32_16x16x32_bf16 v[18:21], v[204:207], v[236:239], v[18:21]
	v_mfma_f32_16x16x32_bf16 v[22:25], v[204:207], v[240:243], v[22:25]
	ds_read_b128 v[204:207], v244 offset:4608
	v_mfma_f32_16x16x32_bf16 v[58:61], v[208:211], v[228:231], v[58:61]
	v_mfma_f32_16x16x32_bf16 v[62:65], v[208:211], v[232:235], v[62:65]
	v_mfma_f32_16x16x32_bf16 v[26:29], v[208:211], v[236:239], v[26:29]
	v_mfma_f32_16x16x32_bf16 v[30:33], v[208:211], v[240:243], v[30:33]
	ds_read_b128 v[208:211], v244 offset:6912
	s_waitcnt lgkmcnt(6)
	v_mfma_f32_16x16x32_bf16 v[34:37], v[196:199], v[212:215], v[34:37]
	ds_read_b128 v[228:231], v245 offset:36928
	s_waitcnt lgkmcnt(6)
	v_mfma_f32_16x16x32_bf16 v[38:41], v[196:199], v[216:219], v[38:41]
	ds_read_b128 v[232:235], v245 offset:39232
	s_waitcnt lgkmcnt(6)
	v_mfma_f32_16x16x32_bf16 v[2:5], v[196:199], v[220:223], v[2:5]
	ds_read_b128 v[236:239], v245 offset:41536
	s_waitcnt lgkmcnt(6)
	v_mfma_f32_16x16x32_bf16 v[6:9], v[196:199], v[224:227], v[6:9]
	ds_read_b128 v[240:243], v245 offset:43840
	ds_read_b128 v[196:199], v244 offset:64
	s_waitcnt lgkmcnt(7)
	v_mfma_f32_16x16x32_bf16 v[42:45], v[200:203], v[212:215], v[42:45]
	v_mfma_f32_16x16x32_bf16 v[46:49], v[200:203], v[216:219], v[46:49]
	v_mfma_f32_16x16x32_bf16 v[10:13], v[200:203], v[220:223], v[10:13]
	v_mfma_f32_16x16x32_bf16 v[14:17], v[200:203], v[224:227], v[14:17]
	ds_read_b128 v[200:203], v244 offset:2368
	s_waitcnt lgkmcnt(7)
	v_mfma_f32_16x16x32_bf16 v[50:53], v[204:207], v[212:215], v[50:53]
	v_mfma_f32_16x16x32_bf16 v[54:57], v[204:207], v[216:219], v[54:57]
	v_mfma_f32_16x16x32_bf16 v[18:21], v[204:207], v[220:223], v[18:21]
	v_mfma_f32_16x16x32_bf16 v[22:25], v[204:207], v[224:227], v[22:25]
	ds_read_b128 v[204:207], v244 offset:4672
	s_setprio 1
	s_waitcnt vmcnt(7)
	ds_write_b128 v95, v[98:101] offset:18432
	s_waitcnt vmcnt(6)
	ds_write_b128 v95, v[72:75] offset:23040
	s_waitcnt lgkmcnt(9)
	v_mfma_f32_16x16x32_bf16 v[58:61], v[208:211], v[212:215], v[58:61]
	v_mfma_f32_16x16x32_bf16 v[62:65], v[208:211], v[216:219], v[62:65]
	v_mfma_f32_16x16x32_bf16 v[26:29], v[208:211], v[220:223], v[26:29]
	v_mfma_f32_16x16x32_bf16 v[30:33], v[208:211], v[224:227], v[30:33]
	ds_read_b128 v[208:211], v244 offset:6976
	s_waitcnt vmcnt(5)
	ds_write_b128 v95, v[102:105] offset:27648
	s_waitcnt vmcnt(4)
	ds_write_b128 v95, v[76:79] offset:32256
	s_waitcnt lgkmcnt(7)
	v_mfma_f32_16x16x32_bf16 v[34:37], v[196:199], v[228:231], v[34:37]
	v_mfma_f32_16x16x32_bf16 v[38:41], v[196:199], v[232:235], v[38:41]
	v_mfma_f32_16x16x32_bf16 v[2:5], v[196:199], v[236:239], v[2:5]
	v_mfma_f32_16x16x32_bf16 v[6:9], v[196:199], v[240:243], v[6:9]
	s_waitcnt vmcnt(3)
	ds_write_b128 v95, v[106:109] offset:55296
	s_waitcnt vmcnt(2)
	ds_write_b128 v95, v[80:83] offset:59904
	s_waitcnt lgkmcnt(8)
	v_mfma_f32_16x16x32_bf16 v[42:45], v[200:203], v[228:231], v[42:45]
	v_mfma_f32_16x16x32_bf16 v[46:49], v[200:203], v[232:235], v[46:49]
	v_mfma_f32_16x16x32_bf16 v[10:13], v[200:203], v[236:239], v[10:13]
	v_mfma_f32_16x16x32_bf16 v[14:17], v[200:203], v[240:243], v[14:17]
	s_waitcnt vmcnt(1)
	ds_write_b128 v95, v[110:113] offset:64512
	s_waitcnt vmcnt(0)
	ds_write_b128 v96, v[84:87] offset:32256
	s_waitcnt lgkmcnt(0)
	s_barrier
	ds_read_b128 v[212:215], v245 offset:55296
	ds_read_b128 v[196:199], v244 offset:18432
	ds_read_b128 v[216:219], v245 offset:57600
	ds_read_b128 v[220:223], v245 offset:59904
	ds_read_b128 v[224:227], v245 offset:62208
	ds_read_b128 v[200:203], v244 offset:20736
	s_setprio 0
	v_mfma_f32_16x16x32_bf16 v[50:53], v[204:207], v[228:231], v[50:53]
	v_mfma_f32_16x16x32_bf16 v[54:57], v[204:207], v[232:235], v[54:57]
	v_mfma_f32_16x16x32_bf16 v[18:21], v[204:207], v[236:239], v[18:21]
	v_mfma_f32_16x16x32_bf16 v[22:25], v[204:207], v[240:243], v[22:25]
	ds_read_b128 v[204:207], v244 offset:23040
	v_mfma_f32_16x16x32_bf16 v[58:61], v[208:211], v[228:231], v[58:61]
	v_mfma_f32_16x16x32_bf16 v[62:65], v[208:211], v[232:235], v[62:65]
	v_mfma_f32_16x16x32_bf16 v[26:29], v[208:211], v[236:239], v[26:29]
	v_mfma_f32_16x16x32_bf16 v[30:33], v[208:211], v[240:243], v[30:33]
	ds_read_b128 v[208:211], v244 offset:25344
	s_waitcnt lgkmcnt(6)
	v_mfma_f32_16x16x32_bf16 v[34:37], v[196:199], v[212:215], v[34:37]
	ds_read_b128 v[228:231], v245 offset:55360
	s_waitcnt lgkmcnt(6)
	v_mfma_f32_16x16x32_bf16 v[38:41], v[196:199], v[216:219], v[38:41]
	ds_read_b128 v[232:235], v245 offset:57664
	s_waitcnt lgkmcnt(6)
	v_mfma_f32_16x16x32_bf16 v[2:5], v[196:199], v[220:223], v[2:5]
	ds_read_b128 v[236:239], v245 offset:59968
	s_waitcnt lgkmcnt(6)
	v_mfma_f32_16x16x32_bf16 v[6:9], v[196:199], v[224:227], v[6:9]
	ds_read_b128 v[240:243], v245 offset:62272
	ds_read_b128 v[196:199], v244 offset:18496
	s_waitcnt lgkmcnt(7)
	v_mfma_f32_16x16x32_bf16 v[42:45], v[200:203], v[212:215], v[42:45]
	v_mfma_f32_16x16x32_bf16 v[46:49], v[200:203], v[216:219], v[46:49]
	v_mfma_f32_16x16x32_bf16 v[10:13], v[200:203], v[220:223], v[10:13]
	v_mfma_f32_16x16x32_bf16 v[14:17], v[200:203], v[224:227], v[14:17]
	ds_read_b128 v[200:203], v244 offset:20800
	s_waitcnt lgkmcnt(7)
	v_mfma_f32_16x16x32_bf16 v[50:53], v[204:207], v[212:215], v[50:53]
	v_mfma_f32_16x16x32_bf16 v[54:57], v[204:207], v[216:219], v[54:57]
	v_mfma_f32_16x16x32_bf16 v[18:21], v[204:207], v[220:223], v[18:21]
	v_mfma_f32_16x16x32_bf16 v[22:25], v[204:207], v[224:227], v[22:25]
	ds_read_b128 v[204:207], v244 offset:23104
	s_waitcnt lgkmcnt(7)
	v_mfma_f32_16x16x32_bf16 v[58:61], v[208:211], v[212:215], v[58:61]
	v_mfma_f32_16x16x32_bf16 v[62:65], v[208:211], v[216:219], v[62:65]
	v_mfma_f32_16x16x32_bf16 v[26:29], v[208:211], v[220:223], v[26:29]
	v_mfma_f32_16x16x32_bf16 v[30:33], v[208:211], v[224:227], v[30:33]
	ds_read_b128 v[208:211], v244 offset:25408
	s_waitcnt lgkmcnt(3)
	v_mfma_f32_16x16x32_bf16 v[34:37], v[196:199], v[228:231], v[34:37]
	v_mfma_f32_16x16x32_bf16 v[38:41], v[196:199], v[232:235], v[38:41]
	v_mfma_f32_16x16x32_bf16 v[2:5], v[196:199], v[236:239], v[2:5]
	v_mfma_f32_16x16x32_bf16 v[6:9], v[196:199], v[240:243], v[6:9]
	s_waitcnt lgkmcnt(2)
	v_mfma_f32_16x16x32_bf16 v[42:45], v[200:203], v[228:231], v[42:45]
	v_mfma_f32_16x16x32_bf16 v[46:49], v[200:203], v[232:235], v[46:49]
	v_mfma_f32_16x16x32_bf16 v[10:13], v[200:203], v[236:239], v[10:13]
	v_mfma_f32_16x16x32_bf16 v[14:17], v[200:203], v[240:243], v[14:17]
	v_or_b32_e32 v66, s5, v88
	s_addk_i32 s5, 0xf000
	s_lshr_b32 s5, s5, 12
	s_mulk_i32 s5, 0xc00
	s_addk_i32 s5, 0x3000
	s_cmp_gt_u32 s0, 31
	v_lshlrev_b32_e32 v66, 12, v66
	s_cselect_b32 s0, s5, 0x2400
	v_lshl_add_u64 v[148:149], s[80:81], 0, v[66:67]
	v_add_lshl_u32 v66, s4, v97, 2
	s_lshl_b64 s[4:5], s[0:1], 2
	s_add_u32 s0, s82, s4
	s_addc_u32 s5, s83, s5
	s_add_u32 s4, s0, 0xe958000
	v_lshl_add_u64 v[150:151], v[148:149], 0, v[66:67]
	s_addc_u32 s5, s5, 0
	v_or_b32_e32 v152, 0xe0, v66
	v_or_b32_e32 v154, 32, v66
	v_or_b32_e32 v156, 64, v66
	v_or_b32_e32 v158, 0x60, v66
	v_or_b32_e32 v160, 0x80, v66
	v_or_b32_e32 v162, 0xa0, v66
	v_or_b32_e32 v164, 0xc0, v66
	v_mov_b32_e32 v155, v67
	v_mov_b32_e32 v157, v67
	v_mov_b32_e32 v159, v67
	v_mov_b32_e32 v161, v67
	v_mov_b32_e32 v163, v67
	v_mov_b32_e32 v165, v67
	v_mov_b32_e32 v153, v67
	s_add_i32 s11, s11, 1
	s_mul_i32 s0, s11, s7
	s_add_i32 s10, s10, s7
	s_waitcnt lgkmcnt(0)
	s_barrier
	v_mfma_f32_16x16x32_bf16 v[50:53], v[204:207], v[228:231], v[50:53]
	v_mfma_f32_16x16x32_bf16 v[54:57], v[204:207], v[232:235], v[54:57]
	v_mfma_f32_16x16x32_bf16 v[18:21], v[204:207], v[236:239], v[18:21]
	v_mfma_f32_16x16x32_bf16 v[22:25], v[204:207], v[240:243], v[22:25]
	v_mfma_f32_16x16x32_bf16 v[58:61], v[208:211], v[228:231], v[58:61]
	v_mfma_f32_16x16x32_bf16 v[62:65], v[208:211], v[232:235], v[62:65]
	v_mfma_f32_16x16x32_bf16 v[26:29], v[208:211], v[236:239], v[26:29]
	v_mfma_f32_16x16x32_bf16 v[30:33], v[208:211], v[240:243], v[30:33]
	s_nop 7
	v_permlane16_swap_b32_e32 v34, v38
	v_permlane16_swap_b32_e32 v35, v39
	v_permlane16_swap_b32_e32 v36, v40
	v_permlane16_swap_b32_e32 v37, v41
	v_permlane16_swap_b32_e32 v42, v46
	v_permlane16_swap_b32_e32 v43, v47
	v_permlane16_swap_b32_e32 v44, v48
	v_permlane16_swap_b32_e32 v45, v49
	v_permlane16_swap_b32_e32 v2, v6
	v_permlane16_swap_b32_e32 v3, v7
	v_permlane16_swap_b32_e32 v4, v8
	v_permlane16_swap_b32_e32 v5, v9
	v_permlane16_swap_b32_e32 v10, v14
	v_permlane16_swap_b32_e32 v11, v15
	v_permlane16_swap_b32_e32 v12, v16
	v_permlane16_swap_b32_e32 v13, v17
	v_permlane16_swap_b32_e32 v50, v54
	v_permlane16_swap_b32_e32 v51, v55
	v_permlane16_swap_b32_e32 v52, v56
	v_permlane16_swap_b32_e32 v53, v57
	v_permlane16_swap_b32_e32 v58, v62
	v_permlane16_swap_b32_e32 v59, v63
	v_permlane16_swap_b32_e32 v60, v64
	v_permlane16_swap_b32_e32 v61, v65
	v_permlane16_swap_b32_e32 v18, v22
	v_permlane16_swap_b32_e32 v19, v23
	v_permlane16_swap_b32_e32 v20, v24
	v_permlane16_swap_b32_e32 v21, v25
	v_permlane16_swap_b32_e32 v26, v30
	v_permlane16_swap_b32_e32 v27, v31
	v_permlane16_swap_b32_e32 v28, v32
	v_permlane16_swap_b32_e32 v29, v33
	v_permlane32_swap_b32_e32 v34, v38
	v_permlane32_swap_b32_e32 v35, v39
	v_permlane32_swap_b32_e32 v36, v40
	v_permlane32_swap_b32_e32 v37, v41
	v_permlane32_swap_b32_e32 v42, v46
	v_permlane32_swap_b32_e32 v43, v47
	v_permlane32_swap_b32_e32 v44, v48
	v_permlane32_swap_b32_e32 v45, v49
	v_permlane32_swap_b32_e32 v2, v6
	v_permlane32_swap_b32_e32 v3, v7
	v_permlane32_swap_b32_e32 v4, v8
	v_permlane32_swap_b32_e32 v5, v9
	v_permlane32_swap_b32_e32 v10, v14
	v_permlane32_swap_b32_e32 v11, v15
	v_permlane32_swap_b32_e32 v12, v16
	v_permlane32_swap_b32_e32 v13, v17
	v_permlane32_swap_b32_e32 v50, v54
	v_permlane32_swap_b32_e32 v51, v55
	v_permlane32_swap_b32_e32 v52, v56
	v_permlane32_swap_b32_e32 v53, v57
	v_permlane32_swap_b32_e32 v58, v62
	v_permlane32_swap_b32_e32 v59, v63
	v_permlane32_swap_b32_e32 v60, v64
	v_permlane32_swap_b32_e32 v61, v65
	v_permlane32_swap_b32_e32 v18, v22
	v_permlane32_swap_b32_e32 v19, v23
	v_permlane32_swap_b32_e32 v20, v24
	v_permlane32_swap_b32_e32 v21, v25
	v_permlane32_swap_b32_e32 v26, v30
	v_permlane32_swap_b32_e32 v27, v31
	v_permlane32_swap_b32_e32 v28, v32
	v_permlane32_swap_b32_e32 v29, v33
	global_load_dwordx4 v[76:79], v[150:151], off offset:224
	global_load_dwordx4 v[84:87], v152, s[4:5]
	global_load_dwordx4 v[80:83], v[150:151], off offset:192
	s_waitcnt vmcnt(1)
	v_fma_f32 v62, v62, v84, v76
	v_fma_f32 v63, v63, v85, v77
	global_load_dwordx4 v[72:75], v164, s[4:5]
	global_load_dwordx4 v[98:101], v[150:151], off offset:160
	global_load_dwordx4 v[102:105], v162, s[4:5]
	global_load_dwordx4 v[106:109], v[150:151], off offset:128
	global_load_dwordx4 v[110:113], v160, s[4:5]
	global_load_dwordx4 v[114:117], v[150:151], off offset:96
	global_load_dwordx4 v[118:121], v158, s[4:5]
	global_load_dwordx4 v[122:125], v[150:151], off offset:64
	global_load_dwordx4 v[126:129], v156, s[4:5]
	global_load_dwordx4 v[132:135], v[150:151], off offset:32
	global_load_dwordx4 v[136:139], v154, s[4:5]
	global_load_dwordx4 v[140:143], v[150:151], off
	global_load_dwordx4 v[144:147], v66, s[4:5]
	v_pk_fma_f32 v[64:65], v[64:65], v[86:87], v[78:79]
	global_store_dwordx4 v[150:151], v[62:65], off offset:224
	s_waitcnt vmcnt(13)
	v_pk_fma_f32 v[58:59], v[58:59], v[72:73], v[80:81]
	v_pk_fma_f32 v[60:61], v[60:61], v[74:75], v[82:83]
	s_waitcnt vmcnt(11)
	v_pk_fma_f32 v[54:55], v[54:55], v[102:103], v[98:99]
	v_pk_fma_f32 v[56:57], v[56:57], v[104:105], v[100:101]
	s_waitcnt vmcnt(9)
	v_pk_fma_f32 v[50:51], v[50:51], v[110:111], v[106:107]
	v_pk_fma_f32 v[52:53], v[52:53], v[112:113], v[108:109]
	s_waitcnt vmcnt(7)
	v_pk_fma_f32 v[46:47], v[46:47], v[118:119], v[114:115]
	v_pk_fma_f32 v[48:49], v[48:49], v[120:121], v[116:117]
	s_waitcnt vmcnt(5)
	v_pk_fma_f32 v[42:43], v[42:43], v[126:127], v[122:123]
	v_pk_fma_f32 v[44:45], v[44:45], v[128:129], v[124:125]
	s_waitcnt vmcnt(3)
	v_pk_fma_f32 v[38:39], v[38:39], v[136:137], v[132:133]
	v_pk_fma_f32 v[40:41], v[40:41], v[138:139], v[134:135]
	s_waitcnt vmcnt(1)
	v_pk_fma_f32 v[34:35], v[34:35], v[144:145], v[140:141]
	v_pk_fma_f32 v[36:37], v[36:37], v[146:147], v[142:143]
	global_store_dwordx4 v[150:151], v[34:37], off
	global_store_dwordx4 v[150:151], v[38:41], off offset:32
	global_store_dwordx4 v[150:151], v[42:45], off offset:64
	v_lshl_add_u64 v[34:35], v[148:149], 0, s[2:3]
	global_store_dwordx4 v[150:151], v[46:49], off offset:96
	global_store_dwordx4 v[150:151], v[50:53], off offset:128
	global_store_dwordx4 v[150:151], v[54:57], off offset:160
	global_store_dwordx4 v[150:151], v[58:61], off offset:192
	v_lshl_add_u64 v[114:115], v[34:35], 0, v[66:67]
	v_lshl_add_u64 v[116:117], v[34:35], 0, v[154:155]
	v_lshl_add_u64 v[118:119], v[34:35], 0, v[156:157]
	v_lshl_add_u64 v[120:121], v[34:35], 0, v[158:159]
	v_lshl_add_u64 v[122:123], v[34:35], 0, v[160:161]
	v_lshl_add_u64 v[124:125], v[34:35], 0, v[162:163]
	v_lshl_add_u64 v[126:127], v[34:35], 0, v[164:165]
	v_lshl_add_u64 v[128:129], v[34:35], 0, v[152:153]
	global_load_dwordx4 v[34:37], v[128:129], off
	global_load_dwordx4 v[38:41], v152, s[4:5]
	global_load_dwordx4 v[42:45], v[126:127], off
	global_load_dwordx4 v[46:49], v164, s[4:5]
	global_load_dwordx4 v[50:53], v[124:125], off
	global_load_dwordx4 v[54:57], v162, s[4:5]
	global_load_dwordx4 v[58:61], v[122:123], off
	global_load_dwordx4 v[62:65], v160, s[4:5]
	global_load_dwordx4 v[72:75], v[120:121], off
	global_load_dwordx4 v[76:79], v158, s[4:5]
	global_load_dwordx4 v[80:83], v[118:119], off
	global_load_dwordx4 v[84:87], v156, s[4:5]
	global_load_dwordx4 v[98:101], v[116:117], off
	global_load_dwordx4 v[102:105], v154, s[4:5]
	global_load_dwordx4 v[106:109], v[114:115], off
	global_load_dwordx4 v[110:113], v66, s[4:5]
	s_add_i32 s4, s0, s6
	s_cmpk_lt_u32 s10, 0x60
	s_waitcnt vmcnt(14)
	v_pk_fma_f32 v[30:31], v[30:31], v[38:39], v[34:35]
	v_pk_fma_f32 v[32:33], v[32:33], v[40:41], v[36:37]
	s_waitcnt vmcnt(12)
	v_pk_fma_f32 v[26:27], v[26:27], v[46:47], v[42:43]
	v_pk_fma_f32 v[28:29], v[28:29], v[48:49], v[44:45]
	s_waitcnt vmcnt(10)
	v_pk_fma_f32 v[22:23], v[22:23], v[54:55], v[50:51]
	v_pk_fma_f32 v[24:25], v[24:25], v[56:57], v[52:53]
	s_waitcnt vmcnt(8)
	v_pk_fma_f32 v[18:19], v[18:19], v[62:63], v[58:59]
	v_pk_fma_f32 v[20:21], v[20:21], v[64:65], v[60:61]
	s_waitcnt vmcnt(6)
	v_pk_fma_f32 v[14:15], v[14:15], v[76:77], v[72:73]
	v_pk_fma_f32 v[16:17], v[16:17], v[78:79], v[74:75]
	s_waitcnt vmcnt(4)
	v_pk_fma_f32 v[10:11], v[10:11], v[84:85], v[80:81]
	v_pk_fma_f32 v[12:13], v[12:13], v[86:87], v[82:83]
	s_waitcnt vmcnt(2)
	v_pk_fma_f32 v[6:7], v[6:7], v[102:103], v[98:99]
	v_pk_fma_f32 v[8:9], v[8:9], v[104:105], v[100:101]
	s_waitcnt vmcnt(0)
	v_pk_fma_f32 v[2:3], v[2:3], v[110:111], v[106:107]
	v_pk_fma_f32 v[4:5], v[4:5], v[112:113], v[108:109]
	global_store_dwordx4 v[114:115], v[2:5], off
	global_store_dwordx4 v[116:117], v[6:9], off
	global_store_dwordx4 v[118:119], v[10:13], off
	global_store_dwordx4 v[120:121], v[14:17], off
	global_store_dwordx4 v[122:123], v[18:21], off
	global_store_dwordx4 v[124:125], v[22:25], off
	global_store_dwordx4 v[126:127], v[26:29], off
	global_store_dwordx4 v[128:129], v[30:33], off
	s_cbranch_scc1 .LBB0_1871
